# strategy: instruction selection - all 490 flat_store_* (global addresses) re-encoded as global_store_* so epilogue stores no longer hold lgkmcnt / go through the flat path
# baseline (speedup 1.0000x reference)
; #define LAS __attribute__((address_space(3)))
; __global__ void __launch_bounds__(512, 2) fwd_kernel(Params p) {
;     ...
;     const int wave_s = __builtin_amdgcn_readfirstlane((int)threadIdx.x >> 6);
;     int ph = 0;
;     { volatile LAS unsigned* st0 = (volatile LAS unsigned*)(lds + MISC_LDS) + 8; if (threadIdx.x < 2) st0[threadIdx.x] = 0u; }
;     __syncthreads();
;     const XcdBarrier xbar = xcd_barrier_post((unsigned*)(p.ws + OFF_BAR), (volatile LAS unsigned*)(lds + MISC_LDS) + 8);
;     if (p.ph_hi < 0) grid.sync();
;     ...
;     PH_BEGIN
;         if (blockIdx.x == 0 && tid < 16) CTL[tid] = 0u;
.LBB0_17:
	s_load_dwordx16 s[72:87], s[0:1], 0x40
	s_mov_b32 s4, 0
	v_mbcnt_lo_u32_b32 v67, -1, 0
	s_waitcnt lgkmcnt(0)
	v_writelane_b32 v252, s72, 16
	s_nop 1
	v_writelane_b32 v252, s73, 17
	v_writelane_b32 v252, s74, 18
	v_writelane_b32 v252, s75, 19
	v_writelane_b32 v252, s76, 20
	v_writelane_b32 v252, s77, 21
	v_writelane_b32 v252, s78, 22
	v_writelane_b32 v252, s79, 23
	v_writelane_b32 v252, s80, 24
	v_writelane_b32 v252, s81, 25
	v_writelane_b32 v252, s82, 26
	v_writelane_b32 v252, s83, 27
	v_writelane_b32 v252, s84, 28
	v_writelane_b32 v252, s85, 29
	v_writelane_b32 v252, s86, 30
	v_writelane_b32 v252, s87, 31
	s_load_dwordx16 s[72:87], s[0:1], 0x80
	s_lshr_b32 s0, s3, 6
	s_cmp_lt_i32 s18, 1
	s_waitcnt lgkmcnt(0)
	v_writelane_b32 v252, s72, 32
	s_nop 1
	v_writelane_b32 v252, s73, 33
	v_writelane_b32 v252, s74, 34
	v_writelane_b32 v252, s75, 35
	v_writelane_b32 v252, s76, 36
	v_writelane_b32 v252, s77, 37
	v_writelane_b32 v252, s78, 38
	v_writelane_b32 v252, s79, 39
	v_writelane_b32 v252, s80, 40
	v_writelane_b32 v252, s81, 41
	v_writelane_b32 v252, s82, 42
	v_writelane_b32 v252, s83, 43
	v_writelane_b32 v252, s84, 44
	v_writelane_b32 v252, s85, 45
	v_writelane_b32 v252, s86, 46
	v_writelane_b32 v252, s87, 47
	v_writelane_b32 v252, s0, 48
	s_cselect_b64 s[0:1], -1, 0
	s_cmp_gt_i32 s19, 0
	s_cselect_b64 s[8:9], -1, 0
	s_and_b64 s[0:1], s[0:1], s[8:9]
	s_mov_b32 s72, 1
	s_andn2_b64 vcc, exec, s[0:1]
	v_writelane_b32 v252, s2, 49
	s_cbranch_vccnz .LBB0_124
	v_readlane_b32 s0, v252, 48
	v_mbcnt_hi_u32_b32 v5, -1, v67
	s_cmp_eq_u32 s2, 0
	v_lshl_add_u32 v64, s0, 6, v5
	s_cselect_b64 s[0:1], -1, 0
	v_cmp_gt_i32_e32 vcc, 16, v64
	v_readfirstlane_b32 s3, v64
	s_mov_b64 s[8:9], s[16:17]
	s_and_b64 s[10:11], s[0:1], vcc
	s_and_saveexec_b64 s[0:1], s[10:11]
	s_cbranch_execz .LBB0_20
	v_ashrrev_i32_e32 v65, 31, v64
	v_lshl_add_u64 v[0:1], v[64:65], 2, s[8:9]
	v_add_co_u32_e32 v0, vcc, 0x9d80000, v0
	v_mov_b32_e32 v2, 0
	s_nop 0
	v_addc_co_u32_e32 v1, vcc, 0, v1, vcc
	global_store_dword v[0:1], v2, off

; #define LAS __attribute__((address_space(3)))
; __device__ __forceinline__ void transpose_item(const float* W, int K, int N, bf16_t* WT, int drow0, int k0, int n0, LAS float* scr, int lane) {
; #pragma unroll
;     for (int i = 0; i < 32; ++i) { const int kk = 2 * i + (lane >> 5); scr[kk * 33 + (lane & 31)] = __builtin_nontemporal_load(&W[(size_t)(k0 + kk) * N + n0 + (lane & 31)]); }
; __device__ __forceinline__ void convert_ffn(const float* Wg, const float* Wu, const float* Wd, bf16_t* GU, bf16_t* DN, LAS float* scr, int gw, int NGW, int lane) {
;     ...
;         else { const int r = it - 2 * I1, kb = r / (DM / 32), nb = r % (DM / 32); transpose_item(Wd, FF, DM, DN, nb * 32, kb * 64, nb * 32, scr, lane); }
.LBB0_25:
	s_and_b32 s10, s29, 0x7fffffc0
	s_add_i32 s20, s10, 0xffffd400
	s_and_b32 s30, s24, 0x7e0
	s_lshl_b32 s10, s30, 2
	v_or_b32_e32 v58, s20, v10
	v_mov_b32_e32 v59, v1
	v_or_b32_e32 v60, s20, v12
	v_mov_b32_e32 v61, v1
	v_or_b32_e32 v62, s20, v13
	v_mov_b32_e32 v63, v1
	v_or_b32_e32 v68, s20, v14
	v_mov_b32_e32 v69, v1
	v_or_b32_e32 v70, s20, v15
	v_mov_b32_e32 v71, v1
	v_or_b32_e32 v72, s20, v16
	v_mov_b32_e32 v73, v1
	v_or_b32_e32 v74, s20, v17
	v_mov_b32_e32 v75, v1
	v_or_b32_e32 v76, s20, v18
	v_mov_b32_e32 v77, v1
	v_lshl_add_u64 v[56:57], v[2:3], 0, s[10:11]
	v_lshlrev_b64 v[58:59], 13, v[58:59]
	v_lshlrev_b64 v[60:61], 13, v[60:61]
	v_lshlrev_b64 v[62:63], 13, v[62:63]
	v_lshlrev_b64 v[68:69], 13, v[68:69]
	v_lshlrev_b64 v[70:71], 13, v[70:71]
	v_lshlrev_b64 v[72:73], 13, v[72:73]
	v_lshlrev_b64 v[74:75], 13, v[74:75]
	v_lshlrev_b64 v[76:77], 13, v[76:77]
	v_lshl_add_u64 v[58:59], v[56:57], 0, v[58:59]
	v_lshl_add_u64 v[60:61], v[56:57], 0, v[60:61]
	v_lshl_add_u64 v[62:63], v[56:57], 0, v[62:63]
	v_lshl_add_u64 v[68:69], v[56:57], 0, v[68:69]
	v_lshl_add_u64 v[70:71], v[56:57], 0, v[70:71]
	v_lshl_add_u64 v[72:73], v[56:57], 0, v[72:73]
	v_lshl_add_u64 v[74:75], v[56:57], 0, v[74:75]
	v_lshl_add_u64 v[76:77], v[56:57], 0, v[76:77]
	global_load_dword v65, v[58:59], off nt
	global_load_dword v110, v[60:61], off nt
	global_load_dword v111, v[62:63], off nt
	global_load_dword v112, v[68:69], off nt
	global_load_dword v113, v[70:71], off nt
	global_load_dword v114, v[72:73], off nt
	global_load_dword v115, v[74:75], off nt
	global_load_dword v116, v[76:77], off nt
	v_mov_b32_e32 v59, v1
	v_mov_b32_e32 v61, v1
	v_mov_b32_e32 v63, v1
	v_mov_b32_e32 v69, v1
	v_mov_b32_e32 v71, v1
	v_mov_b32_e32 v73, v1
	v_mov_b32_e32 v75, v1
	v_mov_b32_e32 v77, v1
	v_mov_b32_e32 v79, v1
	v_or_b32_e32 v58, s20, v19
	v_or_b32_e32 v60, s20, v20
	v_or_b32_e32 v62, s20, v21
	v_or_b32_e32 v68, s20, v22
	v_or_b32_e32 v70, s20, v23
	v_or_b32_e32 v72, s20, v24
	v_or_b32_e32 v74, s20, v25
	v_or_b32_e32 v76, s20, v26
	v_or_b32_e32 v78, s20, v27
	v_or_b32_e32 v80, s20, v28
	v_mov_b32_e32 v81, v1
	v_or_b32_e32 v82, s20, v29
	v_mov_b32_e32 v83, v1
	v_or_b32_e32 v84, s20, v30
	v_mov_b32_e32 v85, v1
	v_or_b32_e32 v86, s20, v31
	v_mov_b32_e32 v87, v1
	v_or_b32_e32 v88, s20, v32
	v_mov_b32_e32 v89, v1
	v_or_b32_e32 v90, s20, v33
	v_mov_b32_e32 v91, v1
	v_or_b32_e32 v92, s20, v34
	v_mov_b32_e32 v93, v1
	v_or_b32_e32 v94, s20, v35
	v_mov_b32_e32 v95, v1
	v_or_b32_e32 v96, s20, v36
	v_mov_b32_e32 v97, v1
	v_or_b32_e32 v98, s20, v37
	v_mov_b32_e32 v99, v1
	v_or_b32_e32 v100, s20, v38
	v_mov_b32_e32 v101, v1
	v_or_b32_e32 v102, s20, v39
	v_mov_b32_e32 v103, v1
	v_or_b32_e32 v104, s20, v40
	v_mov_b32_e32 v105, v1
	v_or_b32_e32 v106, s20, v41
	v_mov_b32_e32 v107, v1
	v_or_b32_e32 v108, s20, v42
	v_mov_b32_e32 v109, v1
	v_lshlrev_b64 v[58:59], 13, v[58:59]
	v_lshlrev_b64 v[60:61], 13, v[60:61]
	v_lshlrev_b64 v[62:63], 13, v[62:63]
	v_lshlrev_b64 v[68:69], 13, v[68:69]
	v_lshlrev_b64 v[70:71], 13, v[70:71]
	v_lshlrev_b64 v[72:73], 13, v[72:73]
	v_lshlrev_b64 v[74:75], 13, v[74:75]
	v_lshlrev_b64 v[76:77], 13, v[76:77]
	v_lshlrev_b64 v[78:79], 13, v[78:79]
	v_lshlrev_b64 v[80:81], 13, v[80:81]
	v_lshlrev_b64 v[82:83], 13, v[82:83]
	v_lshlrev_b64 v[84:85], 13, v[84:85]
	v_lshlrev_b64 v[86:87], 13, v[86:87]
	v_lshlrev_b64 v[88:89], 13, v[88:89]
	v_lshlrev_b64 v[90:91], 13, v[90:91]
	v_lshlrev_b64 v[92:93], 13, v[92:93]
	v_lshlrev_b64 v[94:95], 13, v[94:95]
	v_lshlrev_b64 v[96:97], 13, v[96:97]
	v_lshlrev_b64 v[98:99], 13, v[98:99]
	v_lshlrev_b64 v[100:101], 13, v[100:101]
	v_lshlrev_b64 v[102:103], 13, v[102:103]
	v_lshlrev_b64 v[104:105], 13, v[104:105]
	v_lshlrev_b64 v[106:107], 13, v[106:107]
	v_lshlrev_b64 v[108:109], 13, v[108:109]
	v_lshl_add_u64 v[58:59], v[56:57], 0, v[58:59]
	v_lshl_add_u64 v[60:61], v[56:57], 0, v[60:61]
	v_lshl_add_u64 v[62:63], v[56:57], 0, v[62:63]
	v_lshl_add_u64 v[68:69], v[56:57], 0, v[68:69]
	v_lshl_add_u64 v[70:71], v[56:57], 0, v[70:71]
	v_lshl_add_u64 v[72:73], v[56:57], 0, v[72:73]
	v_lshl_add_u64 v[74:75], v[56:57], 0, v[74:75]
	v_lshl_add_u64 v[76:77], v[56:57], 0, v[76:77]
	v_lshl_add_u64 v[78:79], v[56:57], 0, v[78:79]
	v_lshl_add_u64 v[80:81], v[56:57], 0, v[80:81]
	v_lshl_add_u64 v[82:83], v[56:57], 0, v[82:83]
	v_lshl_add_u64 v[84:85], v[56:57], 0, v[84:85]
	v_lshl_add_u64 v[86:87], v[56:57], 0, v[86:87]
	v_lshl_add_u64 v[88:89], v[56:57], 0, v[88:89]
	v_lshl_add_u64 v[90:91], v[56:57], 0, v[90:91]
	v_lshl_add_u64 v[92:93], v[56:57], 0, v[92:93]
	v_lshl_add_u64 v[94:95], v[56:57], 0, v[94:95]
	v_lshl_add_u64 v[96:97], v[56:57], 0, v[96:97]
	v_lshl_add_u64 v[98:99], v[56:57], 0, v[98:99]
	v_lshl_add_u64 v[100:101], v[56:57], 0, v[100:101]
	v_lshl_add_u64 v[102:103], v[56:57], 0, v[102:103]
	v_lshl_add_u64 v[104:105], v[56:57], 0, v[104:105]
	v_lshl_add_u64 v[106:107], v[56:57], 0, v[106:107]
	v_lshl_add_u64 v[56:57], v[56:57], 0, v[108:109]
	global_load_dword v58, v[58:59], off nt
	s_nop 0
	global_load_dword v59, v[60:61], off nt
	s_nop 0
	global_load_dword v60, v[62:63], off nt
	global_load_dword v61, v[68:69], off nt
	s_nop 0
	global_load_dword v62, v[70:71], off nt
	global_load_dword v63, v[72:73], off nt
	global_load_dword v68, v[74:75], off nt
	global_load_dword v69, v[76:77], off nt
	s_nop 0
	global_load_dword v70, v[78:79], off nt
	global_load_dword v71, v[80:81], off nt
	global_load_dword v72, v[82:83], off nt
	global_load_dword v73, v[84:85], off nt
	global_load_dword v74, v[86:87], off nt
	global_load_dword v75, v[88:89], off nt
	global_load_dword v76, v[90:91], off nt
	global_load_dword v77, v[92:93], off nt
	global_load_dword v78, v[94:95], off nt
	global_load_dword v79, v[96:97], off nt
	global_load_dword v80, v[98:99], off nt
	global_load_dword v81, v[100:101], off nt
	global_load_dword v82, v[102:103], off nt
	global_load_dword v83, v[104:105], off nt
	global_load_dword v84, v[106:107], off nt
	s_nop 0
	global_load_dword v56, v[56:57], off nt
	s_waitcnt vmcnt(0)
; #define LAS __attribute__((address_space(3)))
; __device__ __forceinline__ unsigned pk2(float lo, float hi) { return f2bf(lo) | (f2bf(hi) << 16); }
; #define LDS_WAIT() asm volatile("s_waitcnt lgkmcnt(0)" ::: "memory")
; __device__ __forceinline__ void transpose_item(const float* W, int K, int N, bf16_t* WT, int drow0, int k0, int n0, LAS float* scr, int lane) {
;     ...
;     for (int i = 0; i < 32; ++i) { const int kk = 2 * i + (lane >> 5); scr[kk * 33 + (lane & 31)] = __builtin_nontemporal_load(&W[(size_t)(k0 + kk) * N + n0 + (lane & 31)]); }
;     LDS_WAIT();
;     const int c = lane & 7;
; #pragma unroll
;     for (int j = 0; j < 4; ++j) { const int n = (lane >> 3) + 8 * j; const LAS float* s = scr + (8 * c) * 33 + n;
;         u32x4 o; o.x = pk2(s[0 * 33], s[1 * 33]); o.y = pk2(s[2 * 33], s[3 * 33]); o.z = pk2(s[4 * 33], s[5 * 33]); o.w = pk2(s[6 * 33], s[7 * 33]);
;         *(u32x4*)(WT + (size_t)(drow0 + n) * K + k0 + 8 * c) = o; }
;     LDS_WAIT();
	ds_write2_b32 v47, v65, v110 offset1:66
	ds_write2_b32 v47, v111, v112 offset0:132 offset1:198
	ds_write2_b32 v50, v113, v114 offset0:8 offset1:74
	ds_write2_b32 v48, v115, v116 offset1:66
	ds_write2_b32 v48, v58, v59 offset0:132 offset1:198
	ds_write2_b32 v51, v60, v61 offset0:8 offset1:74
	ds_write2_b32 v49, v62, v63 offset1:66
	ds_write2_b32 v49, v68, v69 offset0:132 offset1:198
	ds_write2_b32 v52, v70, v71 offset0:8 offset1:74
	ds_write2_b32 v52, v72, v73 offset0:140 offset1:206
	ds_write2_b32 v53, v74, v75 offset0:16 offset1:82
	ds_write2_b32 v53, v76, v77 offset0:148 offset1:214
	ds_write2_b32 v54, v78, v79 offset0:24 offset1:90
	ds_write2_b32 v54, v80, v81 offset0:156 offset1:222
	ds_write2_b32 v55, v82, v83 offset0:32 offset1:98
	ds_write2_b32 v55, v84, v56 offset0:164 offset1:230
	s_waitcnt lgkmcnt(0)
	ds_read_b32 v56, v43
	ds_read_b32 v57, v43 offset:132
	ds_read_b32 v58, v43 offset:264
	ds_read_b32 v59, v43 offset:396
	ds_read_b32 v62, v43 offset:528
	ds_read_b32 v63, v43 offset:660
	ds_read_b32 v65, v43 offset:792
	ds_read_b32 v68, v43 offset:924
	s_waitcnt lgkmcnt(0)
	v_bfe_u32 v69, v56, 16, 1
	v_add3_u32 v56, v56, v69, s26
	v_bfe_u32 v69, v57, 16, 1
	v_lshrrev_b32_e32 v56, 16, v56
	v_add3_u32 v57, v57, v69, s26
	v_and_or_b32 v56, v57, s27, v56
	v_bfe_u32 v57, v58, 16, 1
	v_add3_u32 v57, v58, v57, s26
	v_bfe_u32 v58, v59, 16, 1
	v_lshrrev_b32_e32 v57, 16, v57
	v_add3_u32 v58, v59, v58, s26
	v_and_or_b32 v57, v58, s27, v57
	v_bfe_u32 v58, v62, 16, 1
	v_add3_u32 v58, v62, v58, s26
	v_bfe_u32 v59, v63, 16, 1
	v_lshrrev_b32_e32 v58, 16, v58
	v_add3_u32 v59, v63, v59, s26
	v_and_or_b32 v58, v59, s27, v58
	v_bfe_u32 v59, v65, 16, 1
	v_add3_u32 v59, v65, v59, s26
	v_bfe_u32 v62, v68, 16, 1
	v_lshrrev_b32_e32 v59, 16, v59
	v_add3_u32 v62, v68, v62, s26
	v_and_or_b32 v59, v62, s27, v59
	v_or_b32_e32 v62, s30, v11
	s_mov_b32 s21, s11
	v_mul_u32_u24_e32 v62, 0x1600, v62
	v_lshl_add_u64 v[60:61], s[20:21], 1, v[6:7]
	v_lshlrev_b32_e32 v62, 1, v62
	v_mov_b32_e32 v63, v1
	v_lshl_add_u64 v[62:63], v[60:61], 0, v[62:63]
	global_store_dwordx4 v[62:63], v[56:59], off
	ds_read_b32 v56, v43 offset:32
	ds_read_b32 v57, v43 offset:164
	ds_read_b32 v58, v43 offset:296
	ds_read_b32 v59, v43 offset:428
	ds_read_b32 v62, v43 offset:560
	ds_read_b32 v63, v43 offset:692
	ds_read_b32 v65, v43 offset:824
	ds_read_b32 v68, v43 offset:956
	s_waitcnt lgkmcnt(0)
	v_bfe_u32 v69, v56, 16, 1
	v_add3_u32 v56, v56, v69, s26
	v_bfe_u32 v69, v57, 16, 1
	v_lshrrev_b32_e32 v56, 16, v56
	v_add3_u32 v57, v57, v69, s26
	v_and_or_b32 v56, v57, s27, v56
	v_bfe_u32 v57, v58, 16, 1
	v_add3_u32 v57, v58, v57, s26
	v_bfe_u32 v58, v59, 16, 1
	v_lshrrev_b32_e32 v57, 16, v57
	v_add3_u32 v58, v59, v58, s26
	v_and_or_b32 v57, v58, s27, v57
	v_bfe_u32 v58, v62, 16, 1
	v_add3_u32 v58, v62, v58, s26
	v_bfe_u32 v59, v63, 16, 1
	v_lshrrev_b32_e32 v58, 16, v58
	v_add3_u32 v59, v63, v59, s26
	v_and_or_b32 v58, v59, s27, v58
	v_bfe_u32 v59, v65, 16, 1
	v_add3_u32 v59, v65, v59, s26
	v_bfe_u32 v62, v68, 16, 1
	v_lshrrev_b32_e32 v59, 16, v59
	v_add3_u32 v62, v68, v62, s26
	v_and_or_b32 v59, v62, s27, v59
	v_or_b32_e32 v62, s30, v44
	v_mul_u32_u24_e32 v62, 0x1600, v62
	v_lshlrev_b32_e32 v62, 1, v62
	v_mov_b32_e32 v63, v1
	v_lshl_add_u64 v[62:63], v[60:61], 0, v[62:63]
	global_store_dwordx4 v[62:63], v[56:59], off
	ds_read_b32 v56, v43 offset:64
	ds_read_b32 v57, v43 offset:196
	ds_read_b32 v58, v43 offset:328
	ds_read_b32 v59, v43 offset:460
	ds_read_b32 v62, v43 offset:592
	ds_read_b32 v63, v43 offset:724
	ds_read_b32 v65, v43 offset:856
	ds_read_b32 v68, v43 offset:988
	s_waitcnt lgkmcnt(0)
	v_bfe_u32 v69, v56, 16, 1
	v_add3_u32 v56, v56, v69, s26
	v_bfe_u32 v69, v57, 16, 1
	v_lshrrev_b32_e32 v56, 16, v56
	v_add3_u32 v57, v57, v69, s26
	v_and_or_b32 v56, v57, s27, v56
	v_bfe_u32 v57, v58, 16, 1
	v_add3_u32 v57, v58, v57, s26
	v_bfe_u32 v58, v59, 16, 1
	v_lshrrev_b32_e32 v57, 16, v57
	v_add3_u32 v58, v59, v58, s26
	v_and_or_b32 v57, v58, s27, v57
	v_bfe_u32 v58, v62, 16, 1
	v_add3_u32 v58, v62, v58, s26
	v_bfe_u32 v59, v63, 16, 1
	v_lshrrev_b32_e32 v58, 16, v58
	v_add3_u32 v59, v63, v59, s26
	v_and_or_b32 v58, v59, s27, v58
	v_bfe_u32 v59, v65, 16, 1
	v_add3_u32 v59, v65, v59, s26
	v_bfe_u32 v62, v68, 16, 1
	v_lshrrev_b32_e32 v59, 16, v59
	v_add3_u32 v62, v68, v62, s26
	v_and_or_b32 v59, v62, s27, v59
	v_or_b32_e32 v62, s30, v45
	v_mul_u32_u24_e32 v62, 0x1600, v62
	v_lshlrev_b32_e32 v62, 1, v62
	v_mov_b32_e32 v63, v1
	v_lshl_add_u64 v[62:63], v[60:61], 0, v[62:63]
	global_store_dwordx4 v[62:63], v[56:59], off
	ds_read_b32 v56, v43 offset:96
	ds_read_b32 v57, v43 offset:228
	ds_read_b32 v58, v43 offset:360
	ds_read_b32 v59, v43 offset:492
	ds_read_b32 v62, v43 offset:624
	ds_read_b32 v63, v43 offset:756
	ds_read_b32 v65, v43 offset:888
	ds_read_b32 v68, v43 offset:1020
	s_waitcnt lgkmcnt(0)
	v_bfe_u32 v69, v56, 16, 1
	v_add3_u32 v56, v56, v69, s26
	v_bfe_u32 v69, v57, 16, 1
	v_lshrrev_b32_e32 v56, 16, v56
	v_add3_u32 v57, v57, v69, s26
	v_and_or_b32 v56, v57, s27, v56
	v_bfe_u32 v57, v58, 16, 1
	v_add3_u32 v57, v58, v57, s26
	v_bfe_u32 v58, v59, 16, 1
	v_lshrrev_b32_e32 v57, 16, v57
	v_add3_u32 v58, v59, v58, s26
	v_and_or_b32 v57, v58, s27, v57
	v_bfe_u32 v58, v62, 16, 1
	v_add3_u32 v58, v62, v58, s26
	v_bfe_u32 v59, v63, 16, 1
	v_lshrrev_b32_e32 v58, 16, v58
	v_add3_u32 v59, v63, v59, s26
	v_and_or_b32 v58, v59, s27, v58
	v_bfe_u32 v59, v65, 16, 1
	v_add3_u32 v59, v65, v59, s26
	v_bfe_u32 v62, v68, 16, 1
	v_lshrrev_b32_e32 v59, 16, v59
	v_add3_u32 v62, v68, v62, s26
	v_and_or_b32 v59, v62, s27, v59
	v_or_b32_e32 v62, s30, v46
	v_mul_u32_u24_e32 v62, 0x1600, v62
	v_lshlrev_b32_e32 v62, 1, v62
	v_mov_b32_e32 v63, v1
	v_lshl_add_u64 v[60:61], v[60:61], 0, v[62:63]
	global_store_dwordx4 v[60:61], v[56:59], off
	s_waitcnt lgkmcnt(0)
	s_cbranch_execnz .LBB0_22
; #define LAS __attribute__((address_space(3)))
; __device__ __forceinline__ void transpose_item(const float* W, int K, int N, bf16_t* WT, int drow0, int k0, int n0, LAS float* scr, int lane) {
; #pragma unroll
;     for (int i = 0; i < 32; ++i) { const int kk = 2 * i + (lane >> 5); scr[kk * 33 + (lane & 31)] = __builtin_nontemporal_load(&W[(size_t)(k0 + kk) * N + n0 + (lane & 31)]); }
; __device__ __forceinline__ void convert_ffn(const float* Wg, const float* Wu, const float* Wd, bf16_t* GU, bf16_t* DN, LAS float* scr, int gw, int NGW, int lane) {
;     ...
;         if (it < 2 * I1) { const int up = it >= I1, r = it - up * I1, kb = r / (FF / 32), nb = r % (FF / 32), n0 = nb * 32;
;             transpose_item(up ? Wu : Wg, DM, FF, GU, 256 * (n0 >> 7) + up * 128 + (n0 & 127), kb * 64, n0, scr, lane); }
.LBB0_26:
	s_cmpk_gt_i32 s29, 0x15ff
	v_readlane_b32 s36, v252, 0
	s_cselect_b32 s10, 0xffffea00, 0
	v_readlane_b32 s44, v252, 8
	v_readlane_b32 s45, v252, 9
	v_readlane_b32 s46, v252, 10
	v_readlane_b32 s47, v252, 11
	s_cselect_b32 s21, s46, s44
	s_cselect_b32 s33, s47, s45
	s_cselect_b32 s20, 0x80, 0
	s_add_i32 s10, s10, s29
	s_mul_hi_i32 s30, s10, 0x2e8ba2e9
	s_lshr_b32 s31, s30, 31
	s_ashr_i32 s30, s30, 5
	s_add_i32 s31, s30, s31
	s_mul_i32 s30, s31, 0xb0
	s_sub_i32 s10, s10, s30
	s_lshl_b32 s30, s10, 5
	s_lshl_b32 s10, s10, 6
	s_and_b32 s10, s10, 0xffffff00
	s_or_b32 s10, s10, s20
	s_and_b32 s20, s30, 0x60
	s_or_b32 s10, s10, s20
	s_lshl_b32 s20, s31, 6
	s_ashr_i32 s31, s30, 31
	s_lshl_b64 s[30:31], s[30:31], 2
	s_add_u32 s30, s21, s30
	s_addc_u32 s31, s33, s31
	v_lshl_add_u64 v[56:57], s[30:31], 0, v[0:1]
	v_or_b32_e32 v65, s20, v14
	v_mad_i64_i32 v[68:69], s[30:31], v65, s28, v[56:57]
	v_or_b32_e32 v65, s20, v15
	v_mad_i64_i32 v[70:71], s[30:31], v65, s28, v[56:57]
	v_or_b32_e32 v65, s20, v16
	v_mad_i64_i32 v[72:73], s[30:31], v65, s28, v[56:57]
	v_or_b32_e32 v65, s20, v17
	v_or_b32_e32 v58, s20, v10
	v_or_b32_e32 v60, s20, v12
	v_or_b32_e32 v62, s20, v13
	v_mad_i64_i32 v[74:75], s[30:31], v65, s28, v[56:57]
	v_or_b32_e32 v65, s20, v18
	v_mad_i64_i32 v[58:59], s[30:31], v58, s28, v[56:57]
	v_mad_i64_i32 v[60:61], s[30:31], v60, s28, v[56:57]
	v_mad_i64_i32 v[62:63], s[30:31], v62, s28, v[56:57]
	v_mad_i64_i32 v[76:77], s[30:31], v65, s28, v[56:57]
	global_load_dword v65, v[58:59], off nt
	global_load_dword v78, v[60:61], off nt
	global_load_dword v79, v[62:63], off nt
	global_load_dword v80, v[68:69], off nt
	global_load_dword v81, v[70:71], off nt
	global_load_dword v82, v[72:73], off nt
	global_load_dword v83, v[74:75], off nt
	global_load_dword v84, v[76:77], off nt
	v_or_b32_e32 v58, s20, v19
	v_or_b32_e32 v60, s20, v20
	v_or_b32_e32 v62, s20, v21
	v_or_b32_e32 v68, s20, v22
	v_or_b32_e32 v70, s20, v23
	v_or_b32_e32 v72, s20, v24
	v_or_b32_e32 v74, s20, v25
	v_or_b32_e32 v76, s20, v26
	v_mad_i64_i32 v[58:59], s[30:31], v58, s28, v[56:57]
	v_mad_i64_i32 v[60:61], s[30:31], v60, s28, v[56:57]
	v_mad_i64_i32 v[62:63], s[30:31], v62, s28, v[56:57]
	v_mad_i64_i32 v[68:69], s[30:31], v68, s28, v[56:57]
	v_mad_i64_i32 v[70:71], s[30:31], v70, s28, v[56:57]
	v_mad_i64_i32 v[72:73], s[30:31], v72, s28, v[56:57]
	v_mad_i64_i32 v[74:75], s[30:31], v74, s28, v[56:57]
	v_mad_i64_i32 v[76:77], s[30:31], v76, s28, v[56:57]
	global_load_dword v85, v[58:59], off nt
	global_load_dword v86, v[60:61], off nt
	global_load_dword v87, v[62:63], off nt
	global_load_dword v88, v[68:69], off nt
	global_load_dword v89, v[70:71], off nt
	global_load_dword v90, v[72:73], off nt
	global_load_dword v91, v[74:75], off nt
	global_load_dword v92, v[76:77], off nt
	v_or_b32_e32 v58, s20, v27
	v_or_b32_e32 v60, s20, v28
	v_or_b32_e32 v62, s20, v29
	v_or_b32_e32 v68, s20, v30
	v_or_b32_e32 v70, s20, v31
	v_or_b32_e32 v72, s20, v32
	v_or_b32_e32 v74, s20, v33
	v_or_b32_e32 v76, s20, v34
	v_mad_i64_i32 v[58:59], s[30:31], v58, s28, v[56:57]
	v_mad_i64_i32 v[60:61], s[30:31], v60, s28, v[56:57]
	v_mad_i64_i32 v[62:63], s[30:31], v62, s28, v[56:57]
	v_mad_i64_i32 v[68:69], s[30:31], v68, s28, v[56:57]
	v_mad_i64_i32 v[70:71], s[30:31], v70, s28, v[56:57]
	v_mad_i64_i32 v[72:73], s[30:31], v72, s28, v[56:57]
	v_mad_i64_i32 v[74:75], s[30:31], v74, s28, v[56:57]
	v_mad_i64_i32 v[76:77], s[30:31], v76, s28, v[56:57]
	global_load_dword v93, v[58:59], off nt
	global_load_dword v94, v[60:61], off nt
	global_load_dword v95, v[62:63], off nt
	global_load_dword v96, v[68:69], off nt
	global_load_dword v97, v[70:71], off nt
	global_load_dword v98, v[72:73], off nt
	global_load_dword v99, v[74:75], off nt
	s_nop 0
	global_load_dword v76, v[76:77], off nt
	v_or_b32_e32 v58, s20, v35
	v_or_b32_e32 v60, s20, v36
	v_or_b32_e32 v62, s20, v37
	v_or_b32_e32 v68, s20, v38
	v_or_b32_e32 v70, s20, v39
	v_or_b32_e32 v72, s20, v40
	v_or_b32_e32 v74, s20, v41
	v_or_b32_e32 v77, s20, v42
	v_mad_i64_i32 v[58:59], s[30:31], v58, s28, v[56:57]
	v_mad_i64_i32 v[60:61], s[30:31], v60, s28, v[56:57]
	v_mad_i64_i32 v[62:63], s[30:31], v62, s28, v[56:57]
	v_mad_i64_i32 v[68:69], s[30:31], v68, s28, v[56:57]
	v_mad_i64_i32 v[70:71], s[30:31], v70, s28, v[56:57]
	v_mad_i64_i32 v[72:73], s[30:31], v72, s28, v[56:57]
	v_mad_i64_i32 v[74:75], s[30:31], v74, s28, v[56:57]
	v_mad_i64_i32 v[56:57], s[30:31], v77, s28, v[56:57]
	global_load_dword v58, v[58:59], off nt
	s_nop 0
	global_load_dword v59, v[60:61], off nt
	s_nop 0
	global_load_dword v60, v[62:63], off nt
	global_load_dword v61, v[68:69], off nt
	s_nop 0
	global_load_dword v62, v[70:71], off nt
	global_load_dword v63, v[72:73], off nt
	global_load_dword v68, v[74:75], off nt
	s_nop 0
	global_load_dword v56, v[56:57], off nt
	s_waitcnt vmcnt(0)
	ds_write2_b32 v47, v65, v78 offset1:66
	ds_write2_b32 v47, v79, v80 offset0:132 offset1:198
	ds_write2_b32 v50, v81, v82 offset0:8 offset1:74
	ds_write2_b32 v48, v83, v84 offset1:66
	ds_write2_b32 v48, v85, v86 offset0:132 offset1:198
	ds_write2_b32 v51, v87, v88 offset0:8 offset1:74
	ds_write2_b32 v49, v89, v90 offset1:66
	ds_write2_b32 v49, v91, v92 offset0:132 offset1:198
	ds_write2_b32 v52, v93, v94 offset0:8 offset1:74
	ds_write2_b32 v52, v95, v96 offset0:140 offset1:206
	ds_write2_b32 v53, v97, v98 offset0:16 offset1:82
	ds_write2_b32 v53, v99, v76 offset0:148 offset1:214
	ds_write2_b32 v54, v58, v59 offset0:24 offset1:90
	ds_write2_b32 v54, v60, v61 offset0:156 offset1:222
	ds_write2_b32 v55, v62, v63 offset0:32 offset1:98
	ds_write2_b32 v55, v68, v56 offset0:164 offset1:230
	s_waitcnt lgkmcnt(0)
; #define LAS __attribute__((address_space(3)))
; __device__ __forceinline__ unsigned pk2(float lo, float hi) { return f2bf(lo) | (f2bf(hi) << 16); }
; #define LDS_WAIT() asm volatile("s_waitcnt lgkmcnt(0)" ::: "memory")
; __device__ __forceinline__ void transpose_item(const float* W, int K, int N, bf16_t* WT, int drow0, int k0, int n0, LAS float* scr, int lane) {
;     ...
;     LDS_WAIT();
;     const int c = lane & 7;
; #pragma unroll
;     for (int j = 0; j < 4; ++j) { const int n = (lane >> 3) + 8 * j; const LAS float* s = scr + (8 * c) * 33 + n;
;         u32x4 o; o.x = pk2(s[0 * 33], s[1 * 33]); o.y = pk2(s[2 * 33], s[3 * 33]); o.z = pk2(s[4 * 33], s[5 * 33]); o.w = pk2(s[6 * 33], s[7 * 33]);
;         *(u32x4*)(WT + (size_t)(drow0 + n) * K + k0 + 8 * c) = o; }
;     LDS_WAIT();
	ds_read_b32 v56, v43
	ds_read_b32 v57, v43 offset:132
	ds_read_b32 v58, v43 offset:264
	ds_read_b32 v59, v43 offset:396
	ds_read_b32 v60, v43 offset:528
	ds_read_b32 v61, v43 offset:660
	ds_read_b32 v62, v43 offset:792
	ds_read_b32 v63, v43 offset:924
	s_waitcnt lgkmcnt(0)
	v_bfe_u32 v65, v56, 16, 1
	v_add3_u32 v56, v56, v65, s26
	v_bfe_u32 v65, v57, 16, 1
	v_add3_u32 v57, v57, v65, s26
	v_bfe_u32 v65, v58, 16, 1
	v_lshrrev_b32_e32 v56, 16, v56
	v_add3_u32 v58, v58, v65, s26
	v_bfe_u32 v65, v59, 16, 1
	v_add3_u32 v59, v59, v65, s26
	v_and_or_b32 v56, v57, s27, v56
	v_lshrrev_b32_e32 v57, 16, v58
	v_bfe_u32 v58, v60, 16, 1
	v_and_or_b32 v57, v59, s27, v57
	v_add3_u32 v58, v60, v58, s26
	v_bfe_u32 v59, v61, 16, 1
	v_add3_u32 v59, v61, v59, s26
	v_lshrrev_b32_e32 v58, 16, v58
	v_and_or_b32 v58, v59, s27, v58
	v_bfe_u32 v59, v62, 16, 1
	v_add3_u32 v59, v62, v59, s26
	v_bfe_u32 v62, v63, 16, 1
	v_lshrrev_b32_e32 v59, 16, v59
	v_add3_u32 v62, v63, v62, s26
	v_and_or_b32 v59, v62, s27, v59
	v_or_b32_e32 v62, s10, v11
	s_ashr_i32 s21, s20, 31
	v_ashrrev_i32_e32 v63, 31, v62
	v_lshl_add_u64 v[60:61], s[20:21], 1, v[8:9]
	v_lshlrev_b64 v[62:63], 12, v[62:63]
	v_lshl_add_u64 v[62:63], v[60:61], 0, v[62:63]
	global_store_dwordx4 v[62:63], v[56:59], off
	ds_read_b32 v56, v43 offset:32
	ds_read_b32 v57, v43 offset:164
	ds_read_b32 v58, v43 offset:296
	ds_read_b32 v59, v43 offset:428
	ds_read_b32 v62, v43 offset:560
	ds_read_b32 v63, v43 offset:692
	ds_read_b32 v65, v43 offset:824
	ds_read_b32 v68, v43 offset:956
	s_waitcnt lgkmcnt(0)
	v_bfe_u32 v69, v56, 16, 1
	v_add3_u32 v56, v56, v69, s26
	v_bfe_u32 v69, v57, 16, 1
	v_add3_u32 v57, v57, v69, s26
	v_bfe_u32 v69, v58, 16, 1
	v_add3_u32 v58, v58, v69, s26
	v_bfe_u32 v69, v59, 16, 1
	v_add3_u32 v59, v59, v69, s26
	v_lshrrev_b32_e32 v56, 16, v56
	v_lshrrev_b32_e32 v58, 16, v58
	v_and_or_b32 v56, v57, s27, v56
	v_and_or_b32 v57, v59, s27, v58
	v_bfe_u32 v58, v62, 16, 1
	v_add3_u32 v58, v62, v58, s26
	v_bfe_u32 v59, v63, 16, 1
	v_add3_u32 v59, v63, v59, s26
	v_lshrrev_b32_e32 v58, 16, v58
	v_and_or_b32 v58, v59, s27, v58
	v_bfe_u32 v59, v65, 16, 1
	v_add3_u32 v59, v65, v59, s26
	v_bfe_u32 v62, v68, 16, 1
	v_lshrrev_b32_e32 v59, 16, v59
	v_add3_u32 v62, v68, v62, s26
	v_and_or_b32 v59, v62, s27, v59
	v_or_b32_e32 v62, s10, v44
	v_ashrrev_i32_e32 v63, 31, v62
	v_lshlrev_b64 v[62:63], 12, v[62:63]
	v_lshl_add_u64 v[62:63], v[60:61], 0, v[62:63]
	global_store_dwordx4 v[62:63], v[56:59], off
	ds_read_b32 v56, v43 offset:64
	ds_read_b32 v57, v43 offset:196
	ds_read_b32 v58, v43 offset:328
	ds_read_b32 v59, v43 offset:460
	ds_read_b32 v62, v43 offset:592
	ds_read_b32 v63, v43 offset:724
	ds_read_b32 v65, v43 offset:856
	ds_read_b32 v68, v43 offset:988
	s_waitcnt lgkmcnt(0)
	v_bfe_u32 v69, v56, 16, 1
	v_add3_u32 v56, v56, v69, s26
	v_bfe_u32 v69, v57, 16, 1
	v_add3_u32 v57, v57, v69, s26
	v_bfe_u32 v69, v58, 16, 1
	v_add3_u32 v58, v58, v69, s26
	v_bfe_u32 v69, v59, 16, 1
	v_add3_u32 v59, v59, v69, s26
	v_lshrrev_b32_e32 v56, 16, v56
	v_lshrrev_b32_e32 v58, 16, v58
	v_and_or_b32 v56, v57, s27, v56
	v_and_or_b32 v57, v59, s27, v58
	v_bfe_u32 v58, v62, 16, 1
	v_add3_u32 v58, v62, v58, s26
	v_bfe_u32 v59, v63, 16, 1
	v_add3_u32 v59, v63, v59, s26
	v_lshrrev_b32_e32 v58, 16, v58
	v_and_or_b32 v58, v59, s27, v58
	v_bfe_u32 v59, v65, 16, 1
	v_add3_u32 v59, v65, v59, s26
	v_bfe_u32 v62, v68, 16, 1
	v_lshrrev_b32_e32 v59, 16, v59
	v_add3_u32 v62, v68, v62, s26
	v_and_or_b32 v59, v62, s27, v59
	v_or_b32_e32 v62, s10, v45
	v_ashrrev_i32_e32 v63, 31, v62
	v_lshlrev_b64 v[62:63], 12, v[62:63]
	v_lshl_add_u64 v[62:63], v[60:61], 0, v[62:63]
	global_store_dwordx4 v[62:63], v[56:59], off
	ds_read_b32 v56, v43 offset:96
	ds_read_b32 v57, v43 offset:228
	ds_read_b32 v58, v43 offset:360
	ds_read_b32 v59, v43 offset:492
	ds_read_b32 v62, v43 offset:624
	ds_read_b32 v63, v43 offset:756
	ds_read_b32 v65, v43 offset:888
	ds_read_b32 v68, v43 offset:1020
	s_waitcnt lgkmcnt(0)
	v_bfe_u32 v69, v56, 16, 1
	v_add3_u32 v56, v56, v69, s26
	v_bfe_u32 v69, v57, 16, 1
	v_add3_u32 v57, v57, v69, s26
	v_bfe_u32 v69, v58, 16, 1
	v_add3_u32 v58, v58, v69, s26
	v_bfe_u32 v69, v59, 16, 1
	v_add3_u32 v59, v59, v69, s26
	v_lshrrev_b32_e32 v56, 16, v56
	v_lshrrev_b32_e32 v58, 16, v58
	v_and_or_b32 v56, v57, s27, v56
	v_and_or_b32 v57, v59, s27, v58
	v_bfe_u32 v58, v62, 16, 1
	v_add3_u32 v58, v62, v58, s26
	v_bfe_u32 v59, v63, 16, 1
	v_add3_u32 v59, v63, v59, s26
	v_lshrrev_b32_e32 v58, 16, v58
	v_and_or_b32 v58, v59, s27, v58
	v_bfe_u32 v59, v65, 16, 1
	v_add3_u32 v59, v65, v59, s26
	v_bfe_u32 v62, v68, 16, 1
	v_lshrrev_b32_e32 v59, 16, v59
	v_add3_u32 v62, v68, v62, s26
	v_and_or_b32 v59, v62, s27, v59
	v_or_b32_e32 v62, s10, v46
	v_ashrrev_i32_e32 v63, 31, v62
	v_lshlrev_b64 v[62:63], 12, v[62:63]
	v_lshl_add_u64 v[60:61], v[60:61], 0, v[62:63]
	global_store_dwordx4 v[60:61], v[56:59], off
	s_waitcnt lgkmcnt(0)
	v_readlane_b32 s2, v252, 49
	v_readlane_b32 s37, v252, 1
	v_readlane_b32 s38, v252, 2
	v_readlane_b32 s39, v252, 3
	v_readlane_b32 s40, v252, 4
	v_readlane_b32 s41, v252, 5
	v_readlane_b32 s42, v252, 6
	v_readlane_b32 s43, v252, 7
	v_readlane_b32 s48, v252, 12
	v_readlane_b32 s49, v252, 13
	v_readlane_b32 s50, v252, 14
	v_readlane_b32 s51, v252, 15
	s_branch .LBB0_22

; #define LAS __attribute__((address_space(3)))
; __device__ __forceinline__ void transpose_item(const float* W, int K, int N, bf16_t* WT, int drow0, int k0, int n0, LAS float* scr, int lane) {
; #pragma unroll
;     for (int i = 0; i < 32; ++i) { const int kk = 2 * i + (lane >> 5); scr[kk * 33 + (lane & 31)] = __builtin_nontemporal_load(&W[(size_t)(k0 + kk) * N + n0 + (lane & 31)]); }
; __global__ void __launch_bounds__(512, 2) fwd_kernel(Params p) {
;     ...
;         for (int it = gw; it < 32 * 129; it += NGW) { const int kb = it / 129, nb = it % 129; transpose_item(p.in[9], DM, 4128, (bf16_t*)(ws + OFF_WIN), nb * 32, kb * 64, nb * 32, scr, lane); }
.LBB0_29:
	s_mul_hi_i32 s26, s25, 0xfe03f81
	s_lshr_b32 s27, s26, 31
	s_ashr_i32 s26, s26, 3
	s_add_i32 s26, s26, s27
	s_mul_i32 s27, s26, 0xffffefe0
	s_add_i32 s28, s10, s27
	s_lshl_b32 s26, s26, 6
	s_ashr_i32 s29, s28, 31
	v_or_b32_e32 v49, s26, v10
	v_or_b32_e32 v57, s26, v7
	v_or_b32_e32 v59, s26, v8
	v_or_b32_e32 v61, s26, v9
	v_or_b32_e32 v65, s26, v12
	v_or_b32_e32 v76, s26, v13
	v_or_b32_e32 v78, s26, v14
	v_or_b32_e32 v80, s26, v15
	v_or_b32_e32 v82, s26, v16
	v_or_b32_e32 v84, s26, v17
	v_or_b32_e32 v86, s26, v18
	v_or_b32_e32 v88, s26, v19
	v_or_b32_e32 v90, s26, v20
	v_or_b32_e32 v92, s26, v21
	v_or_b32_e32 v94, s26, v22
	s_ashr_i32 s27, s26, 31
	v_lshl_add_u64 v[54:55], s[28:29], 2, v[0:1]
	v_or_b32_e32 v96, s26, v23
	v_or_b32_e32 v98, s26, v24
	v_or_b32_e32 v100, s26, v25
	v_or_b32_e32 v102, s26, v26
	v_or_b32_e32 v104, s26, v27
	v_or_b32_e32 v106, s26, v28
	v_or_b32_e32 v108, s26, v29
	v_or_b32_e32 v110, s26, v30
	v_or_b32_e32 v112, s26, v31
	v_or_b32_e32 v114, s26, v32
	v_or_b32_e32 v116, s26, v33
	v_or_b32_e32 v118, s26, v34
	v_or_b32_e32 v120, s26, v35
	v_or_b32_e32 v122, s26, v36
	v_or_b32_e32 v124, s26, v37
	v_or_b32_e32 v126, s26, v38
	v_or_b32_e32 v128, s26, v39
	v_lshl_add_u64 v[50:51], s[26:27], 1, v[2:3]
	v_mad_i64_i32 v[62:63], s[26:27], v49, s20, v[54:55]
	v_mad_i64_i32 v[68:69], s[26:27], v57, s20, v[54:55]
	v_mad_i64_i32 v[70:71], s[26:27], v59, s20, v[54:55]
	v_mad_i64_i32 v[72:73], s[26:27], v61, s20, v[54:55]
	v_mad_i64_i32 v[74:75], s[26:27], v65, s20, v[54:55]
	v_mad_i64_i32 v[76:77], s[26:27], v76, s20, v[54:55]
	v_mad_i64_i32 v[78:79], s[26:27], v78, s20, v[54:55]
	v_mad_i64_i32 v[80:81], s[26:27], v80, s20, v[54:55]
	v_mad_i64_i32 v[82:83], s[26:27], v82, s20, v[54:55]
	v_mad_i64_i32 v[84:85], s[26:27], v84, s20, v[54:55]
	v_mad_i64_i32 v[86:87], s[26:27], v86, s20, v[54:55]
	v_mad_i64_i32 v[88:89], s[26:27], v88, s20, v[54:55]
	v_mad_i64_i32 v[90:91], s[26:27], v90, s20, v[54:55]
	v_mad_i64_i32 v[92:93], s[26:27], v92, s20, v[54:55]
	v_mad_i64_i32 v[94:95], s[26:27], v94, s20, v[54:55]
	v_mad_i64_i32 v[96:97], s[26:27], v96, s20, v[54:55]
	v_mad_i64_i32 v[98:99], s[26:27], v98, s20, v[54:55]
	v_mad_i64_i32 v[100:101], s[26:27], v100, s20, v[54:55]
	v_mad_i64_i32 v[102:103], s[26:27], v102, s20, v[54:55]
	v_mad_i64_i32 v[104:105], s[26:27], v104, s20, v[54:55]
	v_mad_i64_i32 v[106:107], s[26:27], v106, s20, v[54:55]
	v_mad_i64_i32 v[108:109], s[26:27], v108, s20, v[54:55]
	v_mad_i64_i32 v[110:111], s[26:27], v110, s20, v[54:55]
	v_mad_i64_i32 v[112:113], s[26:27], v112, s20, v[54:55]
	v_mad_i64_i32 v[114:115], s[26:27], v114, s20, v[54:55]
	v_mad_i64_i32 v[116:117], s[26:27], v116, s20, v[54:55]
	v_mad_i64_i32 v[118:119], s[26:27], v118, s20, v[54:55]
	v_mad_i64_i32 v[120:121], s[26:27], v120, s20, v[54:55]
	v_mad_i64_i32 v[122:123], s[26:27], v122, s20, v[54:55]
	v_mad_i64_i32 v[124:125], s[26:27], v124, s20, v[54:55]
	v_mad_i64_i32 v[126:127], s[26:27], v126, s20, v[54:55]
	v_mad_i64_i32 v[54:55], s[26:27], v128, s20, v[54:55]
	global_load_dword v49, v[62:63], off nt
	s_nop 0
	global_load_dword v62, v[68:69], off nt
	global_load_dword v63, v[70:71], off nt
	global_load_dword v65, v[72:73], off nt
	s_nop 0
	global_load_dword v68, v[74:75], off nt
	global_load_dword v69, v[76:77], off nt
	global_load_dword v70, v[78:79], off nt
	global_load_dword v71, v[80:81], off nt
	global_load_dword v72, v[82:83], off nt
	global_load_dword v73, v[84:85], off nt
	global_load_dword v74, v[86:87], off nt
	global_load_dword v75, v[88:89], off nt
	global_load_dword v76, v[90:91], off nt
	global_load_dword v77, v[92:93], off nt
	global_load_dword v78, v[94:95], off nt
	global_load_dword v79, v[96:97], off nt
	global_load_dword v80, v[98:99], off nt
	global_load_dword v81, v[100:101], off nt
	global_load_dword v82, v[102:103], off nt
	global_load_dword v83, v[104:105], off nt
	global_load_dword v84, v[106:107], off nt
	global_load_dword v85, v[108:109], off nt
	global_load_dword v86, v[110:111], off nt
	global_load_dword v87, v[112:113], off nt
	global_load_dword v88, v[114:115], off nt
	global_load_dword v89, v[116:117], off nt
	global_load_dword v90, v[118:119], off nt
	global_load_dword v91, v[120:121], off nt
	global_load_dword v92, v[122:123], off nt
	global_load_dword v93, v[124:125], off nt
	global_load_dword v94, v[126:127], off nt
	global_load_dword v95, v[54:55], off nt
	v_add_u32_e32 v52, s28, v11
	v_ashrrev_i32_e32 v53, 31, v52
	v_add_u32_e32 v56, 8, v52
	v_add_u32_e32 v58, 16, v52
	v_add_u32_e32 v60, 24, v52
	v_lshlrev_b64 v[52:53], 12, v[52:53]
	v_ashrrev_i32_e32 v57, 31, v56
	v_ashrrev_i32_e32 v59, 31, v58
	v_ashrrev_i32_e32 v61, 31, v60
	s_waitcnt vmcnt(0)
; #define LAS __attribute__((address_space(3)))
; __device__ __forceinline__ unsigned pk2(float lo, float hi) { return f2bf(lo) | (f2bf(hi) << 16); }
; #define LDS_WAIT() asm volatile("s_waitcnt lgkmcnt(0)" ::: "memory")
; __device__ __forceinline__ void transpose_item(const float* W, int K, int N, bf16_t* WT, int drow0, int k0, int n0, LAS float* scr, int lane) {
;     ...
;     for (int i = 0; i < 32; ++i) { const int kk = 2 * i + (lane >> 5); scr[kk * 33 + (lane & 31)] = __builtin_nontemporal_load(&W[(size_t)(k0 + kk) * N + n0 + (lane & 31)]); }
;     LDS_WAIT();
;     const int c = lane & 7;
; #pragma unroll
;     for (int j = 0; j < 4; ++j) { const int n = (lane >> 3) + 8 * j; const LAS float* s = scr + (8 * c) * 33 + n;
;         u32x4 o; o.x = pk2(s[0 * 33], s[1 * 33]); o.y = pk2(s[2 * 33], s[3 * 33]); o.z = pk2(s[4 * 33], s[5 * 33]); o.w = pk2(s[6 * 33], s[7 * 33]);
;         *(u32x4*)(WT + (size_t)(drow0 + n) * K + k0 + 8 * c) = o; }
;     LDS_WAIT();
; __global__ void __launch_bounds__(512, 2) fwd_kernel(Params p) {
;     ...
;         for (int it = gw; it < 32 * 129; it += NGW) { const int kb = it / 129, nb = it % 129; transpose_item(p.in[9], DM, 4128, (bf16_t*)(ws + OFF_WIN), nb * 32, kb * 64, nb * 32, scr, lane); }
	ds_write2_b32 v41, v49, v62 offset1:66
	ds_write2_b32 v41, v63, v65 offset0:132 offset1:198
	ds_write2_b32 v42, v68, v69 offset0:8 offset1:74
	ds_write2_b32 v42, v70, v71 offset0:140 offset1:206
	ds_write2_b32 v43, v72, v73 offset0:16 offset1:82
	ds_write2_b32 v43, v74, v75 offset0:148 offset1:214
	ds_write2_b32 v44, v76, v77 offset0:24 offset1:90
	ds_write2_b32 v44, v78, v79 offset0:156 offset1:222
	ds_write2_b32 v45, v80, v81 offset0:32 offset1:98
	ds_write2_b32 v45, v82, v83 offset0:164 offset1:230
	ds_write2_b32 v46, v84, v85 offset0:40 offset1:106
	ds_write2_b32 v46, v86, v87 offset0:172 offset1:238
	ds_write2_b32 v47, v88, v89 offset0:48 offset1:114
	ds_write2_b32 v47, v90, v91 offset0:180 offset1:246
	ds_write2_b32 v48, v92, v93 offset0:56 offset1:122
	ds_write2_b32 v48, v94, v95 offset0:188 offset1:254
	v_lshl_add_u64 v[54:55], v[50:51], 0, v[52:53]
	v_lshlrev_b64 v[52:53], 12, v[56:57]
	v_lshlrev_b64 v[56:57], 12, v[58:59]
	v_lshlrev_b64 v[58:59], 12, v[60:61]
	s_waitcnt lgkmcnt(0)
	v_lshl_add_u64 v[60:61], v[50:51], 0, v[52:53]
	v_lshl_add_u64 v[56:57], v[50:51], 0, v[56:57]
	v_lshl_add_u64 v[58:59], v[50:51], 0, v[58:59]
	ds_read_b32 v49, v40
	ds_read_b32 v50, v40 offset:132
	ds_read_b32 v51, v40 offset:264
	ds_read_b32 v52, v40 offset:396
	ds_read_b32 v53, v40 offset:528
	ds_read_b32 v62, v40 offset:660
	ds_read_b32 v63, v40 offset:792
	ds_read_b32 v65, v40 offset:924
	s_waitcnt lgkmcnt(0)
	v_bfe_u32 v68, v49, 16, 1
	v_bfe_u32 v70, v51, 16, 1
	v_bfe_u32 v72, v53, 16, 1
	v_bfe_u32 v74, v63, 16, 1
	v_bfe_u32 v69, v50, 16, 1
	v_bfe_u32 v71, v52, 16, 1
	v_bfe_u32 v73, v62, 16, 1
	v_bfe_u32 v75, v65, 16, 1
	v_add3_u32 v49, v49, v68, s21
	v_add3_u32 v51, v51, v70, s21
	v_add3_u32 v53, v53, v72, s21
	v_add3_u32 v63, v63, v74, s21
	v_add3_u32 v50, v50, v69, s21
	v_add3_u32 v52, v52, v71, s21
	v_add3_u32 v62, v62, v73, s21
	v_add3_u32 v65, v65, v75, s21
	v_lshrrev_b32_e32 v49, 16, v49
	v_lshrrev_b32_e32 v51, 16, v51
	v_lshrrev_b32_e32 v53, 16, v53
	v_lshrrev_b32_e32 v63, 16, v63
	v_and_or_b32 v50, v50, s24, v49
	v_and_or_b32 v51, v52, s24, v51
	v_and_or_b32 v52, v62, s24, v53
	v_and_or_b32 v53, v65, s24, v63
	global_store_dwordx4 v[54:55], v[50:53], off
	ds_read_b32 v49, v40 offset:32
	ds_read_b32 v50, v40 offset:164
	ds_read_b32 v51, v40 offset:296
	ds_read_b32 v52, v40 offset:428
	ds_read_b32 v53, v40 offset:560
	ds_read_b32 v54, v40 offset:692
	ds_read_b32 v55, v40 offset:824
	ds_read_b32 v62, v40 offset:956
	s_waitcnt lgkmcnt(0)
	v_bfe_u32 v63, v49, 16, 1
	v_bfe_u32 v68, v51, 16, 1
	v_bfe_u32 v70, v53, 16, 1
	v_bfe_u32 v72, v55, 16, 1
	v_bfe_u32 v65, v50, 16, 1
	v_bfe_u32 v69, v52, 16, 1
	v_bfe_u32 v71, v54, 16, 1
	v_bfe_u32 v73, v62, 16, 1
	v_add3_u32 v49, v49, v63, s21
	v_add3_u32 v51, v51, v68, s21
	v_add3_u32 v53, v53, v70, s21
	v_add3_u32 v55, v55, v72, s21
	v_add3_u32 v50, v50, v65, s21
	v_add3_u32 v52, v52, v69, s21
	v_add3_u32 v54, v54, v71, s21
	v_add3_u32 v62, v62, v73, s21
	v_lshrrev_b32_e32 v49, 16, v49
	v_lshrrev_b32_e32 v51, 16, v51
	v_lshrrev_b32_e32 v53, 16, v53
	v_lshrrev_b32_e32 v55, 16, v55
	v_and_or_b32 v50, v50, s24, v49
	v_and_or_b32 v51, v52, s24, v51
	v_and_or_b32 v52, v54, s24, v53
	v_and_or_b32 v53, v62, s24, v55
	global_store_dwordx4 v[60:61], v[50:53], off
	ds_read_b32 v49, v40 offset:64
	ds_read_b32 v50, v40 offset:196
	ds_read_b32 v51, v40 offset:328
	ds_read_b32 v52, v40 offset:460
	ds_read_b32 v53, v40 offset:592
	ds_read_b32 v54, v40 offset:724
	ds_read_b32 v55, v40 offset:856
	ds_read_b32 v60, v40 offset:988
	s_waitcnt lgkmcnt(0)
	v_bfe_u32 v61, v49, 16, 1
	v_bfe_u32 v63, v51, 16, 1
	v_bfe_u32 v68, v53, 16, 1
	v_bfe_u32 v70, v55, 16, 1
	v_bfe_u32 v62, v50, 16, 1
	v_bfe_u32 v65, v52, 16, 1
	v_bfe_u32 v69, v54, 16, 1
	v_bfe_u32 v71, v60, 16, 1
	v_add3_u32 v49, v49, v61, s21
	v_add3_u32 v51, v51, v63, s21
	v_add3_u32 v53, v53, v68, s21
	v_add3_u32 v55, v55, v70, s21
	v_add3_u32 v50, v50, v62, s21
	v_add3_u32 v52, v52, v65, s21
	v_add3_u32 v54, v54, v69, s21
	v_add3_u32 v60, v60, v71, s21
	v_lshrrev_b32_e32 v49, 16, v49
	v_lshrrev_b32_e32 v51, 16, v51
	v_lshrrev_b32_e32 v53, 16, v53
	v_lshrrev_b32_e32 v55, 16, v55
	v_and_or_b32 v50, v50, s24, v49
	v_and_or_b32 v51, v52, s24, v51
	v_and_or_b32 v52, v54, s24, v53
	v_and_or_b32 v53, v60, s24, v55
	global_store_dwordx4 v[56:57], v[50:53], off
	ds_read_b32 v49, v40 offset:96
	ds_read_b32 v50, v40 offset:228
	ds_read_b32 v51, v40 offset:360
	ds_read_b32 v52, v40 offset:492
	ds_read_b32 v53, v40 offset:624
	ds_read_b32 v54, v40 offset:756
	ds_read_b32 v55, v40 offset:888
	ds_read_b32 v56, v40 offset:1020
	s_waitcnt lgkmcnt(0)
	v_bfe_u32 v57, v49, 16, 1
	v_bfe_u32 v61, v51, 16, 1
	v_bfe_u32 v63, v53, 16, 1
	v_bfe_u32 v68, v55, 16, 1
	v_bfe_u32 v60, v50, 16, 1
	v_bfe_u32 v62, v52, 16, 1
	v_bfe_u32 v65, v54, 16, 1
	v_bfe_u32 v69, v56, 16, 1
	v_add3_u32 v49, v49, v57, s21
	v_add3_u32 v51, v51, v61, s21
	v_add3_u32 v53, v53, v63, s21
	v_add3_u32 v55, v55, v68, s21
	v_add3_u32 v50, v50, v60, s21
	v_add3_u32 v52, v52, v62, s21
	v_add3_u32 v54, v54, v65, s21
	v_add3_u32 v56, v56, v69, s21
	v_lshrrev_b32_e32 v49, 16, v49
	v_lshrrev_b32_e32 v51, 16, v51
	v_lshrrev_b32_e32 v53, 16, v53
	v_lshrrev_b32_e32 v55, 16, v55
	v_and_or_b32 v50, v50, s24, v49
	v_and_or_b32 v51, v52, s24, v51
	v_and_or_b32 v52, v54, s24, v53
	v_and_or_b32 v53, v56, s24, v55
	global_store_dwordx4 v[58:59], v[50:53], off
	s_waitcnt lgkmcnt(0)
	s_add_i32 s25, s25, s3
	s_add_i32 s10, s10, s11
	s_cmpk_gt_i32 s25, 0x101f
	s_cbranch_scc0 .LBB0_29

; #define LAS __attribute__((address_space(3)))
; __device__ __forceinline__ void transpose_item(const float* W, int K, int N, bf16_t* WT, int drow0, int k0, int n0, LAS float* scr, int lane) {
; #pragma unroll
;     for (int i = 0; i < 32; ++i) { const int kk = 2 * i + (lane >> 5); scr[kk * 33 + (lane & 31)] = __builtin_nontemporal_load(&W[(size_t)(k0 + kk) * N + n0 + (lane & 31)]); }
; __global__ void __launch_bounds__(512, 2) fwd_kernel(Params p) {
;     ...
;         for (int it = gw; it < 32 * 64; it += NGW) { const int kb = it / 64, nb = it % 64; transpose_item(p.in[18], DM, DM, (bf16_t*)(ws + OFF_WOUT), nb * 32, kb * 64, nb * 32, scr, lane); }
.LBB0_32:
	s_ashr_i32 s24, s21, 31
	s_lshr_b32 s24, s24, 26
	s_add_i32 s24, s21, s24
	s_lshl_b32 s25, s24, 5
	s_andn2_b32 s24, s24, 63
	s_and_b32 s26, s25, 0xfffff800
	v_or_b32_e32 v48, s24, v10
	v_or_b32_e32 v60, s24, v13
	v_or_b32_e32 v62, s24, v14
	v_or_b32_e32 v68, s24, v15
	v_or_b32_e32 v70, s24, v16
	v_or_b32_e32 v72, s24, v17
	v_or_b32_e32 v74, s24, v18
	v_or_b32_e32 v76, s24, v19
	v_or_b32_e32 v78, s24, v20
	v_or_b32_e32 v80, s24, v21
	v_or_b32_e32 v82, s24, v22
	v_or_b32_e32 v84, s24, v23
	v_or_b32_e32 v86, s24, v24
	v_or_b32_e32 v88, s24, v25
	s_sub_i32 s26, s5, s26
	v_or_b32_e32 v50, s24, v6
	v_or_b32_e32 v52, s24, v7
	v_or_b32_e32 v54, s24, v8
	v_or_b32_e32 v56, s24, v9
	v_or_b32_e32 v58, s24, v12
	v_or_b32_e32 v90, s24, v26
	v_or_b32_e32 v92, s24, v27
	v_or_b32_e32 v94, s24, v28
	v_or_b32_e32 v96, s24, v29
	v_or_b32_e32 v98, s24, v30
	v_or_b32_e32 v100, s24, v31
	v_or_b32_e32 v102, s24, v32
	v_or_b32_e32 v104, s24, v33
	v_or_b32_e32 v106, s24, v34
	v_or_b32_e32 v108, s24, v35
	v_or_b32_e32 v110, s24, v36
	v_or_b32_e32 v112, s24, v37
	v_or_b32_e32 v114, s24, v38
	v_ashrrev_i32_e32 v49, 31, v48
	v_ashrrev_i32_e32 v61, 31, v60
	v_ashrrev_i32_e32 v63, 31, v62
	v_ashrrev_i32_e32 v69, 31, v68
	v_ashrrev_i32_e32 v71, 31, v70
	v_ashrrev_i32_e32 v73, 31, v72
	v_ashrrev_i32_e32 v75, 31, v74
	v_ashrrev_i32_e32 v77, 31, v76
	v_ashrrev_i32_e32 v79, 31, v78
	v_ashrrev_i32_e32 v81, 31, v80
	v_ashrrev_i32_e32 v83, 31, v82
	v_ashrrev_i32_e32 v85, 31, v84
	v_ashrrev_i32_e32 v87, 31, v86
	v_ashrrev_i32_e32 v89, 31, v88
	s_ashr_i32 s27, s26, 31
	v_ashrrev_i32_e32 v51, 31, v50
	v_ashrrev_i32_e32 v53, 31, v52
	v_ashrrev_i32_e32 v55, 31, v54
	v_ashrrev_i32_e32 v57, 31, v56
	v_ashrrev_i32_e32 v59, 31, v58
	v_ashrrev_i32_e32 v91, 31, v90
	v_ashrrev_i32_e32 v93, 31, v92
	v_ashrrev_i32_e32 v95, 31, v94
	v_ashrrev_i32_e32 v97, 31, v96
	v_ashrrev_i32_e32 v99, 31, v98
	v_ashrrev_i32_e32 v101, 31, v100
	v_ashrrev_i32_e32 v103, 31, v102
	v_ashrrev_i32_e32 v105, 31, v104
	v_ashrrev_i32_e32 v107, 31, v106
	v_ashrrev_i32_e32 v109, 31, v108
	v_ashrrev_i32_e32 v111, 31, v110
	v_ashrrev_i32_e32 v113, 31, v112
	v_ashrrev_i32_e32 v115, 31, v114
	v_lshlrev_b64 v[48:49], 13, v[48:49]
	v_lshlrev_b64 v[60:61], 13, v[60:61]
	v_lshlrev_b64 v[62:63], 13, v[62:63]
	v_lshlrev_b64 v[68:69], 13, v[68:69]
	v_lshlrev_b64 v[70:71], 13, v[70:71]
	v_lshlrev_b64 v[72:73], 13, v[72:73]
	v_lshlrev_b64 v[74:75], 13, v[74:75]
	v_lshlrev_b64 v[76:77], 13, v[76:77]
	v_lshlrev_b64 v[78:79], 13, v[78:79]
	v_lshlrev_b64 v[80:81], 13, v[80:81]
	v_lshlrev_b64 v[82:83], 13, v[82:83]
	v_lshlrev_b64 v[84:85], 13, v[84:85]
	v_lshlrev_b64 v[86:87], 13, v[86:87]
	v_lshlrev_b64 v[88:89], 13, v[88:89]
	v_lshl_add_u64 v[120:121], s[26:27], 2, v[0:1]
	v_lshlrev_b64 v[50:51], 13, v[50:51]
	v_lshlrev_b64 v[52:53], 13, v[52:53]
	v_lshlrev_b64 v[54:55], 13, v[54:55]
	v_lshlrev_b64 v[56:57], 13, v[56:57]
	v_lshlrev_b64 v[58:59], 13, v[58:59]
	v_lshlrev_b64 v[90:91], 13, v[90:91]
	v_lshlrev_b64 v[92:93], 13, v[92:93]
	v_lshlrev_b64 v[94:95], 13, v[94:95]
	v_lshlrev_b64 v[96:97], 13, v[96:97]
	v_lshlrev_b64 v[98:99], 13, v[98:99]
	v_lshlrev_b64 v[100:101], 13, v[100:101]
	v_lshlrev_b64 v[102:103], 13, v[102:103]
	v_lshlrev_b64 v[104:105], 13, v[104:105]
	v_lshlrev_b64 v[106:107], 13, v[106:107]
	v_lshlrev_b64 v[108:109], 13, v[108:109]
	v_lshlrev_b64 v[110:111], 13, v[110:111]
	v_lshlrev_b64 v[112:113], 13, v[112:113]
	v_lshlrev_b64 v[114:115], 13, v[114:115]
	v_lshl_add_u64 v[48:49], v[120:121], 0, v[48:49]
	v_lshl_add_u64 v[60:61], v[120:121], 0, v[60:61]
	v_lshl_add_u64 v[62:63], v[120:121], 0, v[62:63]
	v_lshl_add_u64 v[68:69], v[120:121], 0, v[68:69]
	v_lshl_add_u64 v[70:71], v[120:121], 0, v[70:71]
	v_lshl_add_u64 v[72:73], v[120:121], 0, v[72:73]
	v_lshl_add_u64 v[74:75], v[120:121], 0, v[74:75]
	v_lshl_add_u64 v[76:77], v[120:121], 0, v[76:77]
	v_lshl_add_u64 v[78:79], v[120:121], 0, v[78:79]
	v_lshl_add_u64 v[80:81], v[120:121], 0, v[80:81]
	v_lshl_add_u64 v[82:83], v[120:121], 0, v[82:83]
	v_lshl_add_u64 v[84:85], v[120:121], 0, v[84:85]
	v_lshl_add_u64 v[86:87], v[120:121], 0, v[86:87]
	v_lshl_add_u64 v[88:89], v[120:121], 0, v[88:89]
	v_lshl_add_u64 v[50:51], v[120:121], 0, v[50:51]
	v_lshl_add_u64 v[52:53], v[120:121], 0, v[52:53]
	v_lshl_add_u64 v[54:55], v[120:121], 0, v[54:55]
	v_lshl_add_u64 v[56:57], v[120:121], 0, v[56:57]
	v_lshl_add_u64 v[58:59], v[120:121], 0, v[58:59]
	v_lshl_add_u64 v[90:91], v[120:121], 0, v[90:91]
	v_lshl_add_u64 v[92:93], v[120:121], 0, v[92:93]
	v_lshl_add_u64 v[94:95], v[120:121], 0, v[94:95]
	v_lshl_add_u64 v[96:97], v[120:121], 0, v[96:97]
	v_lshl_add_u64 v[98:99], v[120:121], 0, v[98:99]
	v_lshl_add_u64 v[100:101], v[120:121], 0, v[100:101]
	v_lshl_add_u64 v[102:103], v[120:121], 0, v[102:103]
	v_lshl_add_u64 v[104:105], v[120:121], 0, v[104:105]
	v_lshl_add_u64 v[106:107], v[120:121], 0, v[106:107]
	v_lshl_add_u64 v[108:109], v[120:121], 0, v[108:109]
	v_lshl_add_u64 v[110:111], v[120:121], 0, v[110:111]
	v_lshl_add_u64 v[112:113], v[120:121], 0, v[112:113]
	v_lshl_add_u64 v[114:115], v[120:121], 0, v[114:115]
	global_load_dword v65, v[48:49], off nt
	global_load_dword v120, v[50:51], off nt
	global_load_dword v121, v[52:53], off nt
	global_load_dword v128, v[54:55], off nt
	global_load_dword v129, v[56:57], off nt
	global_load_dword v130, v[58:59], off nt
	s_nop 0
	global_load_dword v60, v[60:61], off nt
	s_nop 0
	global_load_dword v61, v[62:63], off nt
	s_nop 0
	global_load_dword v62, v[68:69], off nt
	global_load_dword v63, v[70:71], off nt
	s_nop 0
	global_load_dword v68, v[72:73], off nt
	global_load_dword v69, v[74:75], off nt
	global_load_dword v70, v[76:77], off nt
	global_load_dword v71, v[78:79], off nt
	s_nop 0
	global_load_dword v72, v[80:81], off nt
	global_load_dword v73, v[82:83], off nt
	global_load_dword v74, v[84:85], off nt
	global_load_dword v75, v[86:87], off nt
	global_load_dword v76, v[88:89], off nt
	global_load_dword v77, v[90:91], off nt
	global_load_dword v78, v[92:93], off nt
	global_load_dword v79, v[94:95], off nt
	global_load_dword v80, v[96:97], off nt
	global_load_dword v81, v[98:99], off nt
	global_load_dword v82, v[100:101], off nt
	global_load_dword v83, v[102:103], off nt
	global_load_dword v84, v[104:105], off nt
	global_load_dword v85, v[106:107], off nt
	global_load_dword v86, v[108:109], off nt
	global_load_dword v87, v[110:111], off nt
	global_load_dword v88, v[112:113], off nt
	global_load_dword v89, v[114:115], off nt
	v_add_u32_e32 v118, s26, v11
	v_add_u32_e32 v122, 8, v118
	v_add_u32_e32 v124, 16, v118
	s_ashr_i32 s25, s24, 31
	v_ashrrev_i32_e32 v123, 31, v122
	v_ashrrev_i32_e32 v125, 31, v124
	s_waitcnt vmcnt(0)
; #define LAS __attribute__((address_space(3)))
; __device__ __forceinline__ unsigned pk2(float lo, float hi) { return f2bf(lo) | (f2bf(hi) << 16); }
; #define LDS_WAIT() asm volatile("s_waitcnt lgkmcnt(0)" ::: "memory")
; __device__ __forceinline__ void transpose_item(const float* W, int K, int N, bf16_t* WT, int drow0, int k0, int n0, LAS float* scr, int lane) {
;     ...
;     for (int i = 0; i < 32; ++i) { const int kk = 2 * i + (lane >> 5); scr[kk * 33 + (lane & 31)] = __builtin_nontemporal_load(&W[(size_t)(k0 + kk) * N + n0 + (lane & 31)]); }
;     LDS_WAIT();
;     const int c = lane & 7;
; #pragma unroll
;     for (int j = 0; j < 4; ++j) { const int n = (lane >> 3) + 8 * j; const LAS float* s = scr + (8 * c) * 33 + n;
;         u32x4 o; o.x = pk2(s[0 * 33], s[1 * 33]); o.y = pk2(s[2 * 33], s[3 * 33]); o.z = pk2(s[4 * 33], s[5 * 33]); o.w = pk2(s[6 * 33], s[7 * 33]);
;         *(u32x4*)(WT + (size_t)(drow0 + n) * K + k0 + 8 * c) = o; }
;     LDS_WAIT();
; __global__ void __launch_bounds__(512, 2) fwd_kernel(Params p) {
;     ...
;         for (int it = gw; it < 32 * 64; it += NGW) { const int kb = it / 64, nb = it % 64; transpose_item(p.in[18], DM, DM, (bf16_t*)(ws + OFF_WOUT), nb * 32, kb * 64, nb * 32, scr, lane); }
	ds_write2_b32 v40, v65, v120 offset1:66
	ds_write2_b32 v40, v121, v128 offset0:132 offset1:198
	ds_write2_b32 v41, v129, v130 offset0:8 offset1:74
	ds_write2_b32 v41, v60, v61 offset0:140 offset1:206
	ds_write2_b32 v42, v62, v63 offset0:16 offset1:82
	ds_write2_b32 v42, v68, v69 offset0:148 offset1:214
	ds_write2_b32 v43, v70, v71 offset0:24 offset1:90
	ds_write2_b32 v43, v72, v73 offset0:156 offset1:222
	ds_write2_b32 v44, v74, v75 offset0:32 offset1:98
	ds_write2_b32 v44, v76, v77 offset0:164 offset1:230
	ds_write2_b32 v45, v78, v79 offset0:40 offset1:106
	ds_write2_b32 v45, v80, v81 offset0:172 offset1:238
	ds_write2_b32 v46, v82, v83 offset0:48 offset1:114
	ds_write2_b32 v46, v84, v85 offset0:180 offset1:246
	ds_write2_b32 v47, v86, v87 offset0:56 offset1:122
	ds_write2_b32 v47, v88, v89 offset0:188 offset1:254
	v_lshl_add_u64 v[116:117], s[24:25], 1, v[2:3]
	v_lshlrev_b64 v[48:49], 12, v[122:123]
	v_lshlrev_b64 v[50:51], 12, v[124:125]
	s_waitcnt lgkmcnt(0)
	v_lshl_add_u64 v[56:57], v[116:117], 0, v[48:49]
	v_lshl_add_u64 v[58:59], v[116:117], 0, v[50:51]
	ds_read_b32 v48, v39
	ds_read_b32 v49, v39 offset:132
	ds_read_b32 v50, v39 offset:264
	ds_read_b32 v51, v39 offset:396
	ds_read_b32 v60, v39 offset:528
	ds_read_b32 v61, v39 offset:660
	ds_read_b32 v62, v39 offset:792
	ds_read_b32 v63, v39 offset:924
	s_waitcnt lgkmcnt(0)
	v_bfe_u32 v65, v48, 16, 1
	v_bfe_u32 v69, v50, 16, 1
	v_bfe_u32 v71, v60, 16, 1
	v_bfe_u32 v73, v62, 16, 1
	v_ashrrev_i32_e32 v119, 31, v118
	v_bfe_u32 v68, v49, 16, 1
	v_bfe_u32 v70, v51, 16, 1
	v_bfe_u32 v72, v61, 16, 1
	v_bfe_u32 v74, v63, 16, 1
	v_add3_u32 v48, v48, v65, s11
	v_add3_u32 v50, v50, v69, s11
	v_add3_u32 v60, v60, v71, s11
	v_add3_u32 v62, v62, v73, s11
	v_add_u32_e32 v126, 24, v118
	v_lshlrev_b64 v[118:119], 12, v[118:119]
	v_add3_u32 v49, v49, v68, s11
	v_add3_u32 v51, v51, v70, s11
	v_add3_u32 v61, v61, v72, s11
	v_add3_u32 v63, v63, v74, s11
	v_lshrrev_b32_e32 v48, 16, v48
	v_lshrrev_b32_e32 v50, 16, v50
	v_lshrrev_b32_e32 v60, 16, v60
	v_lshrrev_b32_e32 v62, 16, v62
	v_lshl_add_u64 v[52:53], v[116:117], 0, v[118:119]
	v_and_or_b32 v48, v49, s20, v48
	v_and_or_b32 v49, v51, s20, v50
	v_and_or_b32 v50, v61, s20, v60
	v_and_or_b32 v51, v63, s20, v62
	global_store_dwordx4 v[52:53], v[48:51], off
	ds_read_b32 v48, v39 offset:32
	ds_read_b32 v49, v39 offset:164
	ds_read_b32 v50, v39 offset:296
	ds_read_b32 v51, v39 offset:428
	ds_read_b32 v52, v39 offset:560
	ds_read_b32 v53, v39 offset:692
	ds_read_b32 v60, v39 offset:824
	ds_read_b32 v61, v39 offset:956
	s_waitcnt lgkmcnt(0)
	v_bfe_u32 v62, v48, 16, 1
	v_bfe_u32 v65, v50, 16, 1
	v_bfe_u32 v69, v52, 16, 1
	v_bfe_u32 v71, v60, 16, 1
	v_bfe_u32 v63, v49, 16, 1
	v_bfe_u32 v68, v51, 16, 1
	v_bfe_u32 v70, v53, 16, 1
	v_bfe_u32 v72, v61, 16, 1
	v_add3_u32 v48, v48, v62, s11
	v_add3_u32 v50, v50, v65, s11
	v_add3_u32 v52, v52, v69, s11
	v_add3_u32 v60, v60, v71, s11
	v_add3_u32 v49, v49, v63, s11
	v_add3_u32 v51, v51, v68, s11
	v_add3_u32 v53, v53, v70, s11
	v_add3_u32 v61, v61, v72, s11
	v_lshrrev_b32_e32 v48, 16, v48
	v_lshrrev_b32_e32 v50, 16, v50
	v_lshrrev_b32_e32 v52, 16, v52
	v_lshrrev_b32_e32 v60, 16, v60
	v_and_or_b32 v48, v49, s20, v48
	v_and_or_b32 v49, v51, s20, v50
	v_and_or_b32 v50, v53, s20, v52
	v_and_or_b32 v51, v61, s20, v60
	global_store_dwordx4 v[56:57], v[48:51], off
	ds_read_b32 v48, v39 offset:64
	ds_read_b32 v49, v39 offset:196
	ds_read_b32 v50, v39 offset:328
	ds_read_b32 v51, v39 offset:460
	ds_read_b32 v52, v39 offset:592
	ds_read_b32 v53, v39 offset:724
	ds_read_b32 v56, v39 offset:856
	ds_read_b32 v57, v39 offset:988
	s_waitcnt lgkmcnt(0)
	v_bfe_u32 v60, v48, 16, 1
	v_bfe_u32 v62, v50, 16, 1
	v_bfe_u32 v65, v52, 16, 1
	v_bfe_u32 v69, v56, 16, 1
	v_bfe_u32 v61, v49, 16, 1
	v_bfe_u32 v63, v51, 16, 1
	v_bfe_u32 v68, v53, 16, 1
	v_bfe_u32 v70, v57, 16, 1
	v_add3_u32 v48, v48, v60, s11
	v_add3_u32 v50, v50, v62, s11
	v_add3_u32 v52, v52, v65, s11
	v_add3_u32 v56, v56, v69, s11
	v_add3_u32 v49, v49, v61, s11
	v_add3_u32 v51, v51, v63, s11
	v_add3_u32 v53, v53, v68, s11
	v_add3_u32 v57, v57, v70, s11
	v_lshrrev_b32_e32 v48, 16, v48
	v_lshrrev_b32_e32 v50, 16, v50
	v_lshrrev_b32_e32 v52, 16, v52
	v_lshrrev_b32_e32 v56, 16, v56
	v_and_or_b32 v48, v49, s20, v48
	v_and_or_b32 v49, v51, s20, v50
	v_and_or_b32 v50, v53, s20, v52
	v_and_or_b32 v51, v57, s20, v56
	global_store_dwordx4 v[58:59], v[48:51], off
	ds_read_b32 v48, v39 offset:96
	ds_read_b32 v49, v39 offset:228
	ds_read_b32 v50, v39 offset:360
	ds_read_b32 v51, v39 offset:492
	ds_read_b32 v52, v39 offset:624
	ds_read_b32 v53, v39 offset:756
	ds_read_b32 v56, v39 offset:888
	ds_read_b32 v57, v39 offset:1020
	s_waitcnt lgkmcnt(0)
	v_bfe_u32 v58, v48, 16, 1
	v_bfe_u32 v60, v50, 16, 1
	v_bfe_u32 v62, v52, 16, 1
	v_bfe_u32 v65, v56, 16, 1
	v_ashrrev_i32_e32 v127, 31, v126
	v_bfe_u32 v59, v49, 16, 1
	v_bfe_u32 v61, v51, 16, 1
	v_bfe_u32 v63, v53, 16, 1
	v_bfe_u32 v68, v57, 16, 1
	v_add3_u32 v48, v48, v58, s11
	v_add3_u32 v50, v50, v60, s11
	v_add3_u32 v52, v52, v62, s11
	v_add3_u32 v56, v56, v65, s11
	v_lshlrev_b64 v[54:55], 12, v[126:127]
	v_add3_u32 v49, v49, v59, s11
	v_add3_u32 v51, v51, v61, s11
	v_add3_u32 v53, v53, v63, s11
	v_add3_u32 v57, v57, v68, s11
	v_lshrrev_b32_e32 v48, 16, v48
	v_lshrrev_b32_e32 v50, 16, v50
	v_lshrrev_b32_e32 v52, 16, v52
	v_lshrrev_b32_e32 v56, 16, v56
	v_lshl_add_u64 v[54:55], v[116:117], 0, v[54:55]
	v_and_or_b32 v48, v49, s20, v48
	v_and_or_b32 v49, v51, s20, v50
	v_and_or_b32 v50, v53, s20, v52
	v_and_or_b32 v51, v57, s20, v56
	global_store_dwordx4 v[54:55], v[48:51], off
	s_waitcnt lgkmcnt(0)
	s_add_i32 s21, s21, s3
	s_add_i32 s5, s5, s10
	s_cmpk_gt_i32 s21, 0x7ff
	s_cbranch_scc0 .LBB0_32

; __global__ void __launch_bounds__(512, 2) fwd_kernel(Params p) {
;     ...
;         { u32x4* zp = (u32x4*)(ws + OFF_WIN + (size_t)4128 * DM * 2); const int nz = (NINP - 4128) * DM * 2 / 16;
;           for (int i = blockIdx.x * 512 + tid; i < nz; i += G * 512) zp[i] = (u32x4){0u, 0u, 0u, 0u}; }
.LBB0_35:
	v_add_u32_e32 v6, s20, v6
	v_cmp_lt_i32_e32 vcc, s5, v6
	global_store_dwordx4 v[8:9], v[0:3], off
	s_or_b64 s[26:27], vcc, s[26:27]
	v_lshl_add_u64 v[8:9], v[8:9], 0, s[24:25]
	s_andn2_b64 exec, exec, s[26:27]
	s_cbranch_execnz .LBB0_35

; __device__ __forceinline__ unsigned pk2(float lo, float hi) { return f2bf(lo) | (f2bf(hi) << 16); }
; template <int MODE>
; __device__ __forceinline__ void row_finish(const Params& p, int r, int lane, const float* gpost, const float* gnext, bf16_t* U, float coef, f32x4 (&h)[8], const u32x2 (&dw)[8]) {
;     ...
;     if (MODE != 3) {
;         float s2 = 0.f;
; #pragma unroll
;         for (int j = 0; j < 8; ++j) s2 += (h[j].x * h[j].x + h[j].y * h[j].y) + (h[j].z * h[j].z + h[j].w * h[j].w);
;         s2 = wave_sum(s2);
;         const float rs2 = rsqrtf(s2 * (1.f / DM) + EPS);
;         u32x2* up = (u32x2*)(U + (size_t)r * DM);
; #pragma unroll
;         for (int j = 0; j < 8; ++j) { const f32x4 g = ((const f32x4*)gnext)[lane + 64 * j]; const f32x4 v = h[j] * g * rs2;
;             u32x2 w; w.x = pk2(v.x, v.y); w.y = pk2(v.z, v.w); up[lane + 64 * j] = w; }
.LBB0_62:
	s_waitcnt vmcnt(0)
	v_pk_mul_f32 v[90:91], v[14:15], v[14:15]
	v_pk_mul_f32 v[92:93], v[30:31], v[30:31]
	v_pk_mul_f32 v[102:103], v[28:29], v[28:29]
	v_pk_mul_f32 v[104:105], v[12:13], v[12:13]
	v_mov_b32_e32 v107, v102
	v_mov_b32_e32 v106, v104
	v_mov_b32_e32 v102, v105
	v_mov_b32_e32 v104, v90
	v_mov_b32_e32 v105, v92
	v_mov_b32_e32 v92, v91
	v_pk_add_f32 v[102:103], v[106:107], v[102:103]
	v_pk_add_f32 v[90:91], v[104:105], v[92:93]
	v_pk_mul_f32 v[98:99], v[42:43], v[42:43]
	v_pk_add_f32 v[102:103], v[102:103], v[90:91]
	global_load_dwordx4 v[90:93], v[70:71], off
	v_pk_mul_f32 v[100:101], v[40:41], v[40:41]
	v_mul_f32_e32 v68, v44, v44
	v_pk_mov_b32 v[104:105], v[100:101], v[98:99] op_sel:[1,0]
	v_mov_b32_e32 v101, v99
	v_pk_add_f32 v[98:99], v[104:105], v[100:101]
	v_pk_fma_f32 v[100:101], v[44:45], v[44:45], v[68:69] op_sel_hi:[1,1,0]
	v_mul_f32_e32 v68, v46, v46
	v_pk_add_f32 v[102:103], v[102:103], v[102:103] op_sel_hi:[0,1]
	v_pk_add_f32 v[98:99], v[98:99], v[98:99] op_sel_hi:[0,1]
	v_pk_fma_f32 v[104:105], v[46:47], v[46:47], v[68:69] op_sel_hi:[1,1,0]
	v_mul_f32_e32 v100, v48, v48
	v_mul_f32_e32 v104, v49, v49
	v_mul_f32_e32 v98, v50, v50
	v_mul_f32_e32 v102, v51, v51
	v_pk_mul_f32 v[94:95], v[54:55], v[54:55]
	v_pk_mul_f32 v[96:97], v[52:53], v[52:53]
	v_pk_add_f32 v[100:101], v[100:101], v[104:105]
	v_pk_add_f32 v[98:99], v[98:99], v[102:103]
	v_mul_f32_e32 v68, v56, v56
	v_pk_add_f32 v[98:99], v[100:101], v[98:99]
	v_pk_mov_b32 v[100:101], v[96:97], v[94:95] op_sel:[1,0]
	v_mov_b32_e32 v97, v95
	v_pk_add_f32 v[94:95], v[100:101], v[96:97]
	v_pk_fma_f32 v[96:97], v[56:57], v[56:57], v[68:69] op_sel_hi:[1,1,0]
	v_mul_f32_e32 v68, v58, v58
	v_pk_add_f32 v[98:99], v[98:99], v[98:99] op_sel_hi:[0,1]
	v_pk_add_f32 v[94:95], v[94:95], v[94:95] op_sel_hi:[0,1]
	v_pk_fma_f32 v[100:101], v[58:59], v[58:59], v[68:69] op_sel_hi:[1,1,0]
	v_mul_f32_e32 v96, v60, v60
	v_mul_f32_e32 v100, v61, v61
	v_mul_f32_e32 v94, v62, v62
	v_mul_f32_e32 v98, v63, v63
	v_pk_add_f32 v[96:97], v[96:97], v[100:101]
	v_pk_add_f32 v[94:95], v[94:95], v[98:99]
	s_ashr_i32 s1, s0, 31
	v_pk_add_f32 v[94:95], v[96:97], v[94:95]
	s_lshl_b64 s[10:11], s[0:1], 12
	v_add_f32_e32 v68, v94, v95
	ds_bpermute_b32 v94, v65, v68
	s_waitcnt lgkmcnt(0)
	v_add_f32_e32 v68, v68, v94
	ds_bpermute_b32 v94, v84, v68
	s_waitcnt lgkmcnt(0)
	v_add_f32_e32 v68, v68, v94
	ds_bpermute_b32 v94, v85, v68
	s_waitcnt lgkmcnt(0)
	v_add_f32_e32 v68, v68, v94
	ds_bpermute_b32 v94, v86, v68
	s_waitcnt lgkmcnt(0)
	v_add_f32_e32 v68, v68, v94
	ds_bpermute_b32 v94, v87, v68
	s_waitcnt lgkmcnt(0)
	v_add_f32_e32 v68, v68, v94
	ds_bpermute_b32 v94, v88, v68
	s_waitcnt lgkmcnt(0)
	v_add_f32_e32 v68, v68, v94
	v_fmamk_f32 v68, v68, 0x3a000000, v89
	v_mul_f32_e32 v94, 0x4b800000, v68
	v_cmp_gt_f32_e32 vcc, s34, v68
	s_waitcnt vmcnt(0)
	v_pk_mul_f32 v[90:91], v[12:13], v[90:91]
	v_cndmask_b32_e32 v68, v68, v94, vcc
	v_rsq_f32_e32 v68, v68
	v_pk_mul_f32 v[92:93], v[14:15], v[92:93]
	v_mul_f32_e32 v94, 0x45800000, v68
	v_cndmask_b32_e32 v68, v68, v94, vcc
	v_pk_mul_f32 v[90:91], v[90:91], v[68:69] op_sel_hi:[1,0]
	v_pk_mul_f32 v[92:93], v[92:93], v[68:69] op_sel_hi:[1,0]
	v_bfe_u32 v94, v90, 16, 1
	v_bfe_u32 v95, v91, 16, 1
	v_bfe_u32 v96, v92, 16, 1
	v_add3_u32 v90, v90, v94, s33
	v_bfe_u32 v97, v93, 16, 1
	v_add3_u32 v91, v91, v95, s33
	v_add3_u32 v92, v92, v96, s33
	v_lshrrev_b32_e32 v90, 16, v90
	v_lshrrev_b32_e32 v92, 16, v92
	v_and_or_b32 v90, v91, s35, v90
	v_add3_u32 v91, v93, v97, s33
	v_and_or_b32 v91, v91, s35, v92
	v_lshl_add_u64 v[94:95], v[82:83], 0, s[10:11]
	global_store_dwordx2 v[94:95], v[90:91], off
	global_load_dwordx4 v[90:93], v[70:71], off offset:1024
	s_waitcnt vmcnt(0)
	v_pk_mul_f32 v[92:93], v[30:31], v[92:93]
	v_pk_mul_f32 v[90:91], v[28:29], v[90:91]
	v_pk_mul_f32 v[92:93], v[92:93], v[68:69] op_sel_hi:[1,0]
	v_pk_mul_f32 v[90:91], v[90:91], v[68:69] op_sel_hi:[1,0]
	v_bfe_u32 v98, v92, 16, 1
	v_bfe_u32 v96, v90, 16, 1
	v_bfe_u32 v97, v91, 16, 1
	v_bfe_u32 v99, v93, 16, 1
	v_add3_u32 v90, v90, v96, s33
	v_add3_u32 v92, v92, v98, s33
	v_add3_u32 v91, v91, v97, s33
	v_add3_u32 v93, v93, v99, s33
	v_lshrrev_b32_e32 v90, 16, v90
	v_lshrrev_b32_e32 v92, 16, v92
	v_and_or_b32 v90, v91, s35, v90
	v_and_or_b32 v91, v93, s35, v92
	global_store_dwordx2 v[94:95], v[90:91], off offset:512
	global_load_dwordx4 v[90:93], v[70:71], off offset:2048
	s_waitcnt vmcnt(0)
	v_pk_mul_f32 v[92:93], v[42:43], v[92:93]
	v_pk_mul_f32 v[90:91], v[40:41], v[90:91]
	v_pk_mul_f32 v[92:93], v[92:93], v[68:69] op_sel_hi:[1,0]
	v_pk_mul_f32 v[90:91], v[90:91], v[68:69] op_sel_hi:[1,0]
	v_bfe_u32 v98, v92, 16, 1
	v_bfe_u32 v96, v90, 16, 1
	v_bfe_u32 v97, v91, 16, 1
	v_bfe_u32 v99, v93, 16, 1
	v_add3_u32 v90, v90, v96, s33
	v_add3_u32 v92, v92, v98, s33
	v_add3_u32 v91, v91, v97, s33
	v_add3_u32 v93, v93, v99, s33
	v_lshrrev_b32_e32 v90, 16, v90
	v_lshrrev_b32_e32 v92, 16, v92
	v_and_or_b32 v90, v91, s35, v90
	v_and_or_b32 v91, v93, s35, v92
	global_store_dwordx2 v[94:95], v[90:91], off offset:1024
	global_load_dwordx4 v[90:93], v[70:71], off offset:3072
	s_waitcnt vmcnt(0)
	v_pk_mul_f32 v[92:93], v[46:47], v[92:93]
	v_pk_mul_f32 v[90:91], v[44:45], v[90:91]
	v_pk_mul_f32 v[92:93], v[92:93], v[68:69] op_sel_hi:[1,0]
	v_pk_mul_f32 v[90:91], v[90:91], v[68:69] op_sel_hi:[1,0]
	v_bfe_u32 v98, v92, 16, 1
	v_bfe_u32 v96, v90, 16, 1
	v_bfe_u32 v97, v91, 16, 1
	v_bfe_u32 v99, v93, 16, 1
	v_add3_u32 v90, v90, v96, s33
	v_add3_u32 v92, v92, v98, s33
	v_add3_u32 v91, v91, v97, s33
	v_add3_u32 v93, v93, v99, s33
	v_lshrrev_b32_e32 v90, 16, v90
	v_lshrrev_b32_e32 v92, 16, v92
	v_and_or_b32 v90, v91, s35, v90
	v_and_or_b32 v91, v93, s35, v92
	global_store_dwordx2 v[94:95], v[90:91], off offset:1536
	global_load_dwordx4 v[90:93], v[72:73], off
	s_waitcnt vmcnt(0)
; __device__ __forceinline__ unsigned pk2(float lo, float hi) { return f2bf(lo) | (f2bf(hi) << 16); }
; template <int MODE>
; __device__ __forceinline__ void row_finish(const Params& p, int r, int lane, const float* gpost, const float* gnext, bf16_t* U, float coef, f32x4 (&h)[8], const u32x2 (&dw)[8]) {
;     ...
;     if (r >= ROWS) { if (MODE != 3) { u32x4* up = (u32x4*)(U + (size_t)r * DM);
; #pragma unroll
;             for (int j = 0; j < 4; ++j) up[lane + 64 * j] = (u32x4){0u, 0u, 0u, 0u}; } return; }
;     ...
;         float s2 = 0.f;
; #pragma unroll
;         for (int j = 0; j < 8; ++j) s2 += (h[j].x * h[j].x + h[j].y * h[j].y) + (h[j].z * h[j].z + h[j].w * h[j].w);
;         s2 = wave_sum(s2);
;     ...
;         for (int j = 0; j < 8; ++j) { const f32x4 g = ((const f32x4*)gnext)[lane + 64 * j]; const f32x4 v = h[j] * g * rs2;
;             u32x2 w; w.x = pk2(v.x, v.y); w.y = pk2(v.z, v.w); up[lane + 64 * j] = w; }
	v_pk_mul_f32 v[92:93], v[50:51], v[92:93]
	v_pk_mul_f32 v[90:91], v[48:49], v[90:91]
	v_pk_mul_f32 v[92:93], v[92:93], v[68:69] op_sel_hi:[1,0]
	v_pk_mul_f32 v[90:91], v[90:91], v[68:69] op_sel_hi:[1,0]
	v_bfe_u32 v98, v92, 16, 1
	v_bfe_u32 v96, v90, 16, 1
	v_bfe_u32 v97, v91, 16, 1
	v_bfe_u32 v99, v93, 16, 1
	v_add3_u32 v90, v90, v96, s33
	v_add3_u32 v92, v92, v98, s33
	v_add3_u32 v91, v91, v97, s33
	v_add3_u32 v93, v93, v99, s33
	v_lshrrev_b32_e32 v90, 16, v90
	v_lshrrev_b32_e32 v92, 16, v92
	v_and_or_b32 v90, v91, s35, v90
	v_and_or_b32 v91, v93, s35, v92
	global_store_dwordx2 v[94:95], v[90:91], off offset:2048
	global_load_dwordx4 v[90:93], v[74:75], off
	s_waitcnt vmcnt(0)
	v_pk_mul_f32 v[92:93], v[54:55], v[92:93]
	v_pk_mul_f32 v[90:91], v[52:53], v[90:91]
	v_pk_mul_f32 v[92:93], v[68:69], v[92:93] op_sel_hi:[0,1]
	v_pk_mul_f32 v[90:91], v[68:69], v[90:91] op_sel_hi:[0,1]
	v_bfe_u32 v96, v90, 16, 1
	v_bfe_u32 v98, v92, 16, 1
	v_bfe_u32 v97, v91, 16, 1
	v_bfe_u32 v99, v93, 16, 1
	v_add3_u32 v90, v90, v96, s33
	v_add3_u32 v92, v92, v98, s33
	v_add3_u32 v91, v91, v97, s33
	v_add3_u32 v93, v93, v99, s33
	v_lshrrev_b32_e32 v90, 16, v90
	v_lshrrev_b32_e32 v92, 16, v92
	v_and_or_b32 v90, v91, s35, v90
	v_and_or_b32 v91, v93, s35, v92
	global_store_dwordx2 v[94:95], v[90:91], off offset:2560
	global_load_dwordx4 v[90:93], v[76:77], off
	s_waitcnt vmcnt(0)
	v_pk_mul_f32 v[92:93], v[58:59], v[92:93]
	v_pk_mul_f32 v[90:91], v[56:57], v[90:91]
	v_pk_mul_f32 v[92:93], v[68:69], v[92:93] op_sel_hi:[0,1]
	v_pk_mul_f32 v[90:91], v[68:69], v[90:91] op_sel_hi:[0,1]
	v_bfe_u32 v96, v90, 16, 1
	v_bfe_u32 v98, v92, 16, 1
	v_bfe_u32 v97, v91, 16, 1
	v_bfe_u32 v99, v93, 16, 1
	v_add3_u32 v90, v90, v96, s33
	v_add3_u32 v92, v92, v98, s33
	v_add3_u32 v91, v91, v97, s33
	v_add3_u32 v93, v93, v99, s33
	v_lshrrev_b32_e32 v90, 16, v90
	v_lshrrev_b32_e32 v92, 16, v92
	v_and_or_b32 v90, v91, s35, v90
	v_and_or_b32 v91, v93, s35, v92
	global_store_dwordx2 v[94:95], v[90:91], off offset:3072
	global_load_dwordx4 v[90:93], v[78:79], off
	s_waitcnt vmcnt(0)
	v_pk_mul_f32 v[92:93], v[62:63], v[92:93]
	v_pk_mul_f32 v[90:91], v[60:61], v[90:91]
	v_pk_mul_f32 v[92:93], v[68:69], v[92:93] op_sel_hi:[0,1]
	v_pk_mul_f32 v[90:91], v[68:69], v[90:91] op_sel_hi:[0,1]
	v_bfe_u32 v68, v90, 16, 1
	v_bfe_u32 v96, v91, 16, 1
	v_bfe_u32 v97, v92, 16, 1
	v_bfe_u32 v98, v93, 16, 1
	v_add3_u32 v68, v90, v68, s33
	v_add3_u32 v90, v91, v96, s33
	v_add3_u32 v91, v92, v97, s33
	v_add3_u32 v92, v93, v98, s33
	v_lshrrev_b32_e32 v68, 16, v68
	v_lshrrev_b32_e32 v91, 16, v91
	v_and_or_b32 v90, v90, s35, v68
	v_and_or_b32 v91, v92, s35, v91
	global_store_dwordx2 v[94:95], v[90:91], off offset:3584
	s_cbranch_execnz .LBB0_52
.LBB0_63:
	s_mov_b32 s1, s9
	s_mov_b32 s10, s9
	s_mov_b32 s11, s9
	s_lshl_b64 s[0:1], s[0:1], 12
	s_mov_b32 s8, s9
	v_mov_b64_e32 v[94:95], s[10:11]
	v_lshl_add_u64 v[90:91], v[80:81], 0, s[0:1]
	v_mov_b64_e32 v[92:93], s[8:9]
	global_store_dwordx4 v[90:91], v[92:95], off
	global_store_dwordx4 v[90:91], v[92:95], off offset:1024
	global_store_dwordx4 v[90:91], v[92:95], off offset:2048
	global_store_dwordx4 v[90:91], v[92:95], off offset:3072
	s_cmp_gt_i32 s20, 0x80ff
	s_cbranch_scc1 .LBB0_38
.LBB0_64:
	s_andn2_b64 vcc, exec, s[24:25]
	s_mov_b64 s[0:1], -1
	s_cbranch_vccnz .LBB0_66
	s_waitcnt vmcnt(0)
	v_mov_b32_e32 v92, v5
	v_mov_b32_e32 v93, v1
	v_mov_b32_e32 v90, v4
	v_mov_b32_e32 v91, v0
	v_pk_mul_f32 v[92:93], v[92:93], v[92:93]
	v_mov_b32_e32 v94, v7
	v_mov_b32_e32 v95, v3
	v_pk_fma_f32 v[90:91], v[90:91], v[90:91], v[92:93]
	v_mov_b32_e32 v92, v6
	v_mov_b32_e32 v93, v2
	v_pk_mul_f32 v[94:95], v[94:95], v[94:95]
	v_pk_mul_f32 v[96:97], v[10:11], v[10:11]
	v_pk_fma_f32 v[92:93], v[92:93], v[92:93], v[94:95]
	v_pk_mul_f32 v[98:99], v[8:9], v[8:9]
	v_pk_add_f32 v[90:91], v[90:91], v[92:93]
	v_pk_mov_b32 v[100:101], v[98:99], v[96:97] op_sel:[1,0]
	v_pk_add_f32 v[94:95], v[90:91], v[90:91] op_sel_hi:[0,1]
	global_load_dwordx4 v[90:93], v[70:71], off
	v_mov_b32_e32 v99, v97
	v_mul_f32_e32 v68, v16, v16
	v_pk_add_f32 v[96:97], v[100:101], v[98:99]
	v_pk_fma_f32 v[98:99], v[16:17], v[16:17], v[68:69] op_sel_hi:[1,1,0]
	v_mul_f32_e32 v68, v18, v18
	v_pk_add_f32 v[96:97], v[96:97], v[96:97] op_sel_hi:[0,1]
	v_pk_fma_f32 v[100:101], v[18:19], v[18:19], v[68:69] op_sel_hi:[1,1,0]
	v_mul_f32_e32 v98, v32, v32
	v_mul_f32_e32 v100, v33, v33
	v_mul_f32_e32 v96, v34, v34
	v_mul_f32_e32 v94, v35, v35
	v_pk_add_f32 v[98:99], v[98:99], v[100:101]
	v_pk_add_f32 v[94:95], v[96:97], v[94:95]
	v_pk_mul_f32 v[96:97], v[38:39], v[38:39]
	v_pk_add_f32 v[94:95], v[98:99], v[94:95]
	v_pk_mul_f32 v[98:99], v[36:37], v[36:37]
	v_mul_f32_e32 v68, v24, v24
	v_pk_mov_b32 v[100:101], v[98:99], v[96:97] op_sel:[1,0]
	v_mov_b32_e32 v99, v97
	v_pk_add_f32 v[96:97], v[100:101], v[98:99]
	v_pk_fma_f32 v[98:99], v[24:25], v[24:25], v[68:69] op_sel_hi:[1,1,0]
	v_mul_f32_e32 v68, v26, v26
	v_pk_add_f32 v[94:95], v[94:95], v[94:95] op_sel_hi:[0,1]
	v_pk_add_f32 v[96:97], v[96:97], v[96:97] op_sel_hi:[0,1]
	v_pk_fma_f32 v[100:101], v[26:27], v[26:27], v[68:69] op_sel_hi:[1,1,0]
	v_mul_f32_e32 v98, v20, v20
	v_mul_f32_e32 v100, v21, v21
	v_mul_f32_e32 v96, v22, v22
	v_mul_f32_e32 v94, v23, v23
	v_pk_add_f32 v[98:99], v[98:99], v[100:101]
	v_pk_add_f32 v[94:95], v[96:97], v[94:95]
	s_ashr_i32 s21, s20, 31
	v_pk_add_f32 v[94:95], v[98:99], v[94:95]
	s_lshl_b64 s[0:1], s[20:21], 12
	v_add_f32_e32 v68, v94, v95
	ds_bpermute_b32 v94, v65, v68
	s_waitcnt lgkmcnt(0)
	v_add_f32_e32 v68, v68, v94
	ds_bpermute_b32 v94, v84, v68
	s_waitcnt lgkmcnt(0)
	v_add_f32_e32 v68, v68, v94
	ds_bpermute_b32 v94, v85, v68
	s_waitcnt lgkmcnt(0)
; __device__ __forceinline__ unsigned pk2(float lo, float hi) { return f2bf(lo) | (f2bf(hi) << 16); }
; template <int MODE>
; __device__ __forceinline__ void row_finish(const Params& p, int r, int lane, const float* gpost, const float* gnext, bf16_t* U, float coef, f32x4 (&h)[8], const u32x2 (&dw)[8]) {
;     ...
;     if (r >= ROWS) { if (MODE != 3) { u32x4* up = (u32x4*)(U + (size_t)r * DM);
; #pragma unroll
;             for (int j = 0; j < 4; ++j) up[lane + 64 * j] = (u32x4){0u, 0u, 0u, 0u}; } return; }
;     ...
;         for (int j = 0; j < 8; ++j) s2 += (h[j].x * h[j].x + h[j].y * h[j].y) + (h[j].z * h[j].z + h[j].w * h[j].w);
;         s2 = wave_sum(s2);
;         const float rs2 = rsqrtf(s2 * (1.f / DM) + EPS);
;         u32x2* up = (u32x2*)(U + (size_t)r * DM);
; #pragma unroll
;         for (int j = 0; j < 8; ++j) { const f32x4 g = ((const f32x4*)gnext)[lane + 64 * j]; const f32x4 v = h[j] * g * rs2;
;             u32x2 w; w.x = pk2(v.x, v.y); w.y = pk2(v.z, v.w); up[lane + 64 * j] = w; }
	v_add_f32_e32 v68, v68, v94
	ds_bpermute_b32 v94, v86, v68
	s_waitcnt lgkmcnt(0)
	v_add_f32_e32 v68, v68, v94
	ds_bpermute_b32 v94, v87, v68
	s_waitcnt lgkmcnt(0)
	v_add_f32_e32 v68, v68, v94
	ds_bpermute_b32 v94, v88, v68
	s_waitcnt lgkmcnt(0)
	v_add_f32_e32 v68, v68, v94
	v_fmamk_f32 v68, v68, 0x3a000000, v89
	v_mul_f32_e32 v94, 0x4b800000, v68
	v_cmp_gt_f32_e32 vcc, s34, v68
	s_waitcnt vmcnt(0)
	v_pk_mul_f32 v[90:91], v[0:1], v[90:91]
	v_cndmask_b32_e32 v68, v68, v94, vcc
	v_rsq_f32_e32 v68, v68
	v_pk_mul_f32 v[92:93], v[2:3], v[92:93]
	v_mul_f32_e32 v94, 0x45800000, v68
	v_cndmask_b32_e32 v68, v68, v94, vcc
	v_pk_mul_f32 v[90:91], v[90:91], v[68:69] op_sel_hi:[1,0]
	v_pk_mul_f32 v[92:93], v[92:93], v[68:69] op_sel_hi:[1,0]
	v_bfe_u32 v94, v90, 16, 1
	v_bfe_u32 v95, v91, 16, 1
	v_bfe_u32 v96, v92, 16, 1
	v_add3_u32 v90, v90, v94, s33
	v_bfe_u32 v97, v93, 16, 1
	v_add3_u32 v91, v91, v95, s33
	v_add3_u32 v92, v92, v96, s33
	v_lshrrev_b32_e32 v90, 16, v90
	v_lshrrev_b32_e32 v92, 16, v92
	v_and_or_b32 v90, v91, s35, v90
	v_add3_u32 v91, v93, v97, s33
	v_and_or_b32 v91, v91, s35, v92
	v_lshl_add_u64 v[94:95], v[82:83], 0, s[0:1]
	global_store_dwordx2 v[94:95], v[90:91], off
	global_load_dwordx4 v[90:93], v[70:71], off offset:1024
	s_mov_b64 s[0:1], 0
	s_waitcnt vmcnt(0)
	v_pk_mul_f32 v[92:93], v[6:7], v[92:93]
	v_pk_mul_f32 v[90:91], v[4:5], v[90:91]
	v_pk_mul_f32 v[92:93], v[92:93], v[68:69] op_sel_hi:[1,0]
	v_pk_mul_f32 v[90:91], v[90:91], v[68:69] op_sel_hi:[1,0]
	v_bfe_u32 v98, v92, 16, 1
	v_bfe_u32 v96, v90, 16, 1
	v_bfe_u32 v97, v91, 16, 1
	v_bfe_u32 v99, v93, 16, 1
	v_add3_u32 v90, v90, v96, s33
	v_add3_u32 v92, v92, v98, s33
	v_add3_u32 v91, v91, v97, s33
	v_add3_u32 v93, v93, v99, s33
	v_lshrrev_b32_e32 v90, 16, v90
	v_lshrrev_b32_e32 v92, 16, v92
	v_and_or_b32 v90, v91, s35, v90
	v_and_or_b32 v91, v93, s35, v92
	global_store_dwordx2 v[94:95], v[90:91], off offset:512
	global_load_dwordx4 v[90:93], v[70:71], off offset:2048
	s_waitcnt vmcnt(0)
	v_pk_mul_f32 v[92:93], v[10:11], v[92:93]
	v_pk_mul_f32 v[90:91], v[8:9], v[90:91]
	v_pk_mul_f32 v[92:93], v[92:93], v[68:69] op_sel_hi:[1,0]
	v_pk_mul_f32 v[90:91], v[90:91], v[68:69] op_sel_hi:[1,0]
	v_bfe_u32 v98, v92, 16, 1
	v_bfe_u32 v96, v90, 16, 1
	v_bfe_u32 v97, v91, 16, 1
	v_bfe_u32 v99, v93, 16, 1
	v_add3_u32 v90, v90, v96, s33
	v_add3_u32 v92, v92, v98, s33
	v_add3_u32 v91, v91, v97, s33
	v_add3_u32 v93, v93, v99, s33
	v_lshrrev_b32_e32 v90, 16, v90
	v_lshrrev_b32_e32 v92, 16, v92
	v_and_or_b32 v90, v91, s35, v90
	v_and_or_b32 v91, v93, s35, v92
	global_store_dwordx2 v[94:95], v[90:91], off offset:1024
	global_load_dwordx4 v[90:93], v[70:71], off offset:3072
	s_waitcnt vmcnt(0)
	v_pk_mul_f32 v[92:93], v[18:19], v[92:93]
	v_pk_mul_f32 v[90:91], v[16:17], v[90:91]
	v_pk_mul_f32 v[92:93], v[92:93], v[68:69] op_sel_hi:[1,0]
	v_pk_mul_f32 v[90:91], v[90:91], v[68:69] op_sel_hi:[1,0]
	v_bfe_u32 v98, v92, 16, 1
	v_bfe_u32 v96, v90, 16, 1
	v_bfe_u32 v97, v91, 16, 1
	v_bfe_u32 v99, v93, 16, 1
	v_add3_u32 v90, v90, v96, s33
	v_add3_u32 v92, v92, v98, s33
	v_add3_u32 v91, v91, v97, s33
	v_add3_u32 v93, v93, v99, s33
	v_lshrrev_b32_e32 v90, 16, v90
	v_lshrrev_b32_e32 v92, 16, v92
	v_and_or_b32 v90, v91, s35, v90
	v_and_or_b32 v91, v93, s35, v92
	global_store_dwordx2 v[94:95], v[90:91], off offset:1536
	global_load_dwordx4 v[90:93], v[72:73], off
	s_waitcnt vmcnt(0)
	v_pk_mul_f32 v[92:93], v[34:35], v[92:93]
	v_pk_mul_f32 v[90:91], v[32:33], v[90:91]
	v_pk_mul_f32 v[92:93], v[92:93], v[68:69] op_sel_hi:[1,0]
	v_pk_mul_f32 v[90:91], v[90:91], v[68:69] op_sel_hi:[1,0]
	v_bfe_u32 v98, v92, 16, 1
	v_bfe_u32 v96, v90, 16, 1
	v_bfe_u32 v97, v91, 16, 1
	v_bfe_u32 v99, v93, 16, 1
	v_add3_u32 v90, v90, v96, s33
	v_add3_u32 v92, v92, v98, s33
	v_add3_u32 v91, v91, v97, s33
	v_add3_u32 v93, v93, v99, s33
	v_lshrrev_b32_e32 v90, 16, v90
	v_lshrrev_b32_e32 v92, 16, v92
	v_and_or_b32 v90, v91, s35, v90
	v_and_or_b32 v91, v93, s35, v92
	global_store_dwordx2 v[94:95], v[90:91], off offset:2048
	global_load_dwordx4 v[90:93], v[74:75], off
	s_waitcnt vmcnt(0)
	v_pk_mul_f32 v[92:93], v[38:39], v[92:93]
	v_pk_mul_f32 v[90:91], v[36:37], v[90:91]
	v_pk_mul_f32 v[92:93], v[68:69], v[92:93] op_sel_hi:[0,1]
	v_pk_mul_f32 v[90:91], v[68:69], v[90:91] op_sel_hi:[0,1]
	v_bfe_u32 v96, v90, 16, 1
	v_bfe_u32 v98, v92, 16, 1
	v_bfe_u32 v97, v91, 16, 1
	v_bfe_u32 v99, v93, 16, 1
	v_add3_u32 v90, v90, v96, s33
	v_add3_u32 v92, v92, v98, s33
	v_add3_u32 v91, v91, v97, s33
	v_add3_u32 v93, v93, v99, s33
	v_lshrrev_b32_e32 v90, 16, v90
	v_lshrrev_b32_e32 v92, 16, v92
	v_and_or_b32 v90, v91, s35, v90
	v_and_or_b32 v91, v93, s35, v92
	global_store_dwordx2 v[94:95], v[90:91], off offset:2560
	global_load_dwordx4 v[90:93], v[76:77], off
	s_waitcnt vmcnt(0)
	v_pk_mul_f32 v[92:93], v[26:27], v[92:93]
	v_pk_mul_f32 v[90:91], v[24:25], v[90:91]
	v_pk_mul_f32 v[92:93], v[68:69], v[92:93] op_sel_hi:[0,1]
	v_pk_mul_f32 v[90:91], v[68:69], v[90:91] op_sel_hi:[0,1]
	v_bfe_u32 v96, v90, 16, 1
	v_bfe_u32 v98, v92, 16, 1
	v_bfe_u32 v97, v91, 16, 1
	v_bfe_u32 v99, v93, 16, 1
	v_add3_u32 v90, v90, v96, s33
	v_add3_u32 v92, v92, v98, s33
	v_add3_u32 v91, v91, v97, s33
	v_add3_u32 v93, v93, v99, s33
	v_lshrrev_b32_e32 v90, 16, v90
	v_lshrrev_b32_e32 v92, 16, v92
	v_and_or_b32 v90, v91, s35, v90
	v_and_or_b32 v91, v93, s35, v92
	global_store_dwordx2 v[94:95], v[90:91], off offset:3072
	global_load_dwordx4 v[90:93], v[78:79], off
	s_waitcnt vmcnt(0)
	v_pk_mul_f32 v[92:93], v[22:23], v[92:93]
	v_pk_mul_f32 v[90:91], v[20:21], v[90:91]
	v_pk_mul_f32 v[92:93], v[68:69], v[92:93] op_sel_hi:[0,1]
	v_pk_mul_f32 v[90:91], v[68:69], v[90:91] op_sel_hi:[0,1]
	v_bfe_u32 v68, v90, 16, 1
	v_bfe_u32 v96, v91, 16, 1
	v_bfe_u32 v97, v92, 16, 1
	v_bfe_u32 v98, v93, 16, 1
	v_add3_u32 v68, v90, v68, s33
	v_add3_u32 v90, v91, v96, s33
	v_add3_u32 v91, v92, v97, s33
	v_add3_u32 v92, v93, v98, s33
	v_lshrrev_b32_e32 v68, 16, v68
	v_lshrrev_b32_e32 v91, 16, v91
	v_and_or_b32 v90, v90, s35, v68
	v_and_or_b32 v91, v92, s35, v91
	global_store_dwordx2 v[94:95], v[90:91], off offset:3584
.LBB0_66:
	s_andn2_b64 vcc, exec, s[0:1]
	s_cbranch_vccnz .LBB0_38
	s_mov_b32 s21, s9
	s_mov_b32 s10, s9
	s_mov_b32 s11, s9
	s_lshl_b64 s[0:1], s[20:21], 12
	s_mov_b32 s8, s9
	v_mov_b64_e32 v[94:95], s[10:11]
	v_lshl_add_u64 v[90:91], v[80:81], 0, s[0:1]
	v_mov_b64_e32 v[92:93], s[8:9]
	global_store_dwordx4 v[90:91], v[92:95], off
	global_store_dwordx4 v[90:91], v[92:95], off offset:1024
	global_store_dwordx4 v[90:91], v[92:95], off offset:2048
	global_store_dwordx4 v[90:91], v[92:95], off offset:3072
	s_branch .LBB0_38

; template <int MODE>
; __device__ __forceinline__ void row_finish(const Params& p, int r, int lane, const float* gpost, const float* gnext, bf16_t* U, float coef, f32x4 (&h)[8], const u32x2 (&dw)[8]) {
;     ...
;     if (MODE >= 1) {
;         f32x4 d[8]; float ss = 0.f;
; #pragma unroll
;         for (int j = 0; j < 8; ++j) { const u32x2 w = dw[j]; d[j] = (f32x4){bflo(w.x), bfhi(w.x), bflo(w.y), bfhi(w.y)};
;             ss += (d[j].x * d[j].x + d[j].y * d[j].y) + (d[j].z * d[j].z + d[j].w * d[j].w); }
;         ss = wave_sum(ss);
;         const float rs = rsqrtf(ss * (1.f / DM) + EPS) * coef;
;         f32x4* hd = (f32x4*)hrow(p, r);
; #pragma unroll
;         for (int j = 0; j < 8; ++j) { const f32x4 g = ((const f32x4*)gpost)[lane + 64 * j]; h[j] = h[j] + d[j] * g * rs; __builtin_nontemporal_store(h[j], &hd[lane + 64 * j]); }
;     ...
;         float s2 = 0.f;
; #pragma unroll
;         for (int j = 0; j < 8; ++j) s2 += (h[j].x * h[j].x + h[j].y * h[j].y) + (h[j].z * h[j].z + h[j].w * h[j].w);
;         s2 = wave_sum(s2);
.LBB0_186:
	s_andn2_b64 vcc, exec, s[6:7]
	s_mov_b64 s[6:7], -1
	s_cbranch_vccnz .LBB0_188
	s_waitcnt vmcnt(0) lgkmcnt(0)
	v_and_b32_e32 v173, 0xffff0000, v150
	v_and_b32_e32 v172, 0xffff0000, v152
	v_and_b32_e32 v175, 0xffff0000, v151
	v_and_b32_e32 v174, 0xffff0000, v153
	v_lshlrev_b32_e32 v71, 16, v150
	v_lshlrev_b32_e32 v70, 16, v152
	v_lshlrev_b32_e32 v69, 16, v151
	v_lshlrev_b32_e32 v68, 16, v153
	v_pk_mul_f32 v[64:65], v[172:173], v[172:173]
	v_pk_mul_f32 v[66:67], v[174:175], v[174:175]
	v_pk_fma_f32 v[64:65], v[70:71], v[70:71], v[64:65]
	v_pk_fma_f32 v[66:67], v[68:69], v[68:69], v[66:67]
	v_and_b32_e32 v73, 0xffff0000, v155
	v_pk_add_f32 v[64:65], v[64:65], v[66:67]
	v_and_b32_e32 v72, 0xffff0000, v154
	v_pk_add_f32 v[64:65], v[64:65], v[64:65] op_sel_hi:[0,1]
	v_lshlrev_b32_e32 v75, 16, v155
	v_lshlrev_b32_e32 v74, 16, v154
	v_pk_mul_f32 v[66:67], v[72:73], v[72:73]
	v_lshlrev_b32_e32 v76, 16, v156
	v_and_b32_e32 v77, 0xffff0000, v156
	v_lshlrev_b32_e32 v78, 16, v157
	v_lshlrev_b32_e32 v80, 16, v158
	v_pk_fma_f32 v[66:67], v[74:75], v[74:75], v[66:67]
	v_mul_f32_e32 v81, v76, v76
	v_mul_f32_e32 v85, v77, v77
	v_and_b32_e32 v79, 0xffff0000, v157
	v_mul_f32_e32 v64, v78, v78
	v_mov_b32_e32 v84, v80
	v_pk_add_f32 v[66:67], v[66:67], v[66:67] op_sel_hi:[0,1]
	v_pk_fma_f32 v[86:87], v[78:79], v[78:79], v[64:65] op_sel_hi:[1,1,0]
	v_and_b32_e32 v179, 0xffff0000, v158
	v_lshlrev_b32_e32 v82, 16, v159
	v_and_b32_e32 v83, 0xffff0000, v159
	v_pk_add_f32 v[84:85], v[80:81], v[84:85]
	v_mul_f32_e32 v86, v179, v179
	v_mul_f32_e32 v66, v82, v82
	v_mul_f32_e32 v64, v83, v83
	v_mul_f32_e32 v88, v80, v80
	v_mov_b32_e32 v89, v85
	v_pk_add_f32 v[84:85], v[88:89], v[86:87]
	v_pk_add_f32 v[64:65], v[66:67], v[64:65]
	v_and_b32_e32 v87, 0xffff0000, v161
	v_pk_add_f32 v[64:65], v[84:85], v[64:65]
	v_and_b32_e32 v86, 0xffff0000, v160
	v_pk_add_f32 v[64:65], v[64:65], v[64:65] op_sel_hi:[0,1]
	v_lshlrev_b32_e32 v85, 16, v161
	v_lshlrev_b32_e32 v84, 16, v160
	v_pk_mul_f32 v[66:67], v[86:87], v[86:87]
	v_lshlrev_b32_e32 v88, 16, v162
	v_and_b32_e32 v89, 0xffff0000, v162
	v_lshlrev_b32_e32 v90, 16, v163
	v_lshlrev_b32_e32 v92, 16, v164
	v_pk_fma_f32 v[66:67], v[84:85], v[84:85], v[66:67]
	v_mul_f32_e32 v93, v88, v88
	v_mul_f32_e32 v181, v89, v89
	v_and_b32_e32 v91, 0xffff0000, v163
	v_mul_f32_e32 v64, v90, v90
	v_mov_b32_e32 v180, v92
	v_pk_add_f32 v[66:67], v[66:67], v[66:67] op_sel_hi:[0,1]
	v_pk_fma_f32 v[182:183], v[90:91], v[90:91], v[64:65] op_sel_hi:[1,1,0]
	v_and_b32_e32 v178, 0xffff0000, v164
	v_lshlrev_b32_e32 v94, 16, v165
	v_and_b32_e32 v95, 0xffff0000, v165
	v_pk_add_f32 v[180:181], v[92:93], v[180:181]
	v_mul_f32_e32 v182, v178, v178
	v_mul_f32_e32 v66, v94, v94
	v_mul_f32_e32 v64, v95, v95
	v_mul_f32_e32 v184, v92, v92
	v_mov_b32_e32 v185, v181
	v_pk_add_f32 v[180:181], v[184:185], v[182:183]
	v_pk_add_f32 v[64:65], v[66:67], v[64:65]
	s_add_u32 s5, s84, s60
	v_pk_add_f32 v[64:65], v[180:181], v[64:65]
	s_addc_u32 s6, 0, s61
	v_add_f32_e32 v64, v64, v65
	ds_bpermute_b32 v65, v97, v64
	s_add_u32 s10, s56, s60
	s_addc_u32 s7, s57, s61
	s_cmp_lt_i32 s85, 0x8000
	s_cselect_b32 s7, s7, s6
	s_waitcnt lgkmcnt(0)
	v_add_f32_e32 v64, v64, v65
	ds_bpermute_b32 v65, v99, v64
	s_cselect_b32 s6, s10, s5
	v_mov_b32_e32 v180, v71
	v_mov_b32_e32 v181, v173
	s_cselect_b32 s5, s15, s71
	s_waitcnt lgkmcnt(0)
	v_add_f32_e32 v64, v64, v65
	ds_bpermute_b32 v65, v101, v64
	s_cselect_b32 s10, s14, s70
	s_lshl_b64 s[6:7], s[6:7], 13
	s_add_u32 s6, s10, s6
	s_addc_u32 s7, s5, s7
	s_waitcnt lgkmcnt(0)
	v_add_f32_e32 v64, v64, v65
	ds_bpermute_b32 v65, v103, v64
	v_lshlrev_b32_e32 v81, 4, v96
	v_mov_b32_e32 v71, v172
	v_lshlrev_b32_e32 v93, 4, v98
	s_waitcnt lgkmcnt(0)
	v_add_f32_e32 v64, v64, v65
	ds_bpermute_b32 v65, v105, v64
	s_waitcnt lgkmcnt(0)
	v_add_f32_e32 v64, v64, v65
	ds_bpermute_b32 v65, v127, v64
	s_waitcnt lgkmcnt(0)
	v_add_f32_e32 v64, v64, v65
	v_fmamk_f32 v64, v64, 0x3a000000, v176
	v_cmp_gt_f32_e32 vcc, s75, v64
	v_mul_f32_e32 v65, 0x4b800000, v64
	s_nop 0
	v_cndmask_b32_e32 v64, v64, v65, vcc
	v_rsq_f32_e32 v64, v64
	s_nop 0
	v_mul_f32_e32 v65, 0x45800000, v64
	v_cndmask_b32_e32 v64, v64, v65, vcc
	v_mul_f32_e32 v170, 0.5, v64
	global_load_dwordx4 v[64:67], v[106:107], off
	s_waitcnt vmcnt(0)
	v_pk_mul_f32 v[64:65], v[180:181], v[64:65]
	v_mov_b32_e32 v180, v69
	v_mov_b32_e32 v181, v175
	v_pk_mul_f32 v[66:67], v[180:181], v[66:67]
	v_pk_fma_f32 v[64:65], v[64:65], v[170:171], v[0:1] op_sel_hi:[1,0,1]
	v_pk_fma_f32 v[66:67], v[66:67], v[170:171], v[2:3] op_sel_hi:[1,0,1]
	global_store_dwordx4 v81, v[64:67], s[6:7] nt
	global_load_dwordx4 v[180:183], v[106:107], off offset:1024
	v_mov_b32_e32 v69, v174
	s_waitcnt vmcnt(0)
	v_pk_mul_f32 v[172:173], v[70:71], v[180:181]
	v_pk_mul_f32 v[68:69], v[68:69], v[182:183]
	v_mov_b32_e32 v180, v74
	v_pk_fma_f32 v[70:71], v[68:69], v[170:171], v[38:39] op_sel_hi:[1,0,1]
	v_pk_fma_f32 v[68:69], v[172:173], v[170:171], v[36:37] op_sel_hi:[1,0,1]
	global_store_dwordx4 v81, v[68:71], s[6:7] offset:1024 nt
	global_load_dwordx4 v[172:175], v[106:107], off offset:2048
	v_mov_b32_e32 v181, v72
	v_mov_b32_e32 v72, v75
	s_waitcnt vmcnt(0)
	v_pk_mul_f32 v[172:173], v[172:173], v[180:181]
	v_pk_mul_f32 v[72:73], v[174:175], v[72:73]
	v_mov_b32_e32 v180, v84
	v_pk_fma_f32 v[74:75], v[72:73], v[170:171], v[42:43] op_sel_hi:[1,0,1]
	v_pk_fma_f32 v[72:73], v[172:173], v[170:171], v[40:41] op_sel_hi:[1,0,1]
	global_store_dwordx4 v81, v[72:75], s[6:7] offset:2048 nt
	global_load_dwordx4 v[172:175], v[106:107], off offset:3072
	v_mov_b32_e32 v181, v86
	v_mov_b32_e32 v86, v85
	s_waitcnt vmcnt(0)
; __device__ __forceinline__ unsigned pk2(float lo, float hi) { return f2bf(lo) | (f2bf(hi) << 16); }
; template <int MODE>
; __device__ __forceinline__ void row_finish(const Params& p, int r, int lane, const float* gpost, const float* gnext, bf16_t* U, float coef, f32x4 (&h)[8], const u32x2 (&dw)[8]) {
;     ...
;         for (int j = 0; j < 8; ++j) { const f32x4 g = ((const f32x4*)gpost)[lane + 64 * j]; h[j] = h[j] + d[j] * g * rs; __builtin_nontemporal_store(h[j], &hd[lane + 64 * j]); }
;     }
;     if (MODE != 3) {
;         float s2 = 0.f;
; #pragma unroll
;         for (int j = 0; j < 8; ++j) s2 += (h[j].x * h[j].x + h[j].y * h[j].y) + (h[j].z * h[j].z + h[j].w * h[j].w);
;         s2 = wave_sum(s2);
;         const float rs2 = rsqrtf(s2 * (1.f / DM) + EPS);
;         u32x2* up = (u32x2*)(U + (size_t)r * DM);
; #pragma unroll
;         for (int j = 0; j < 8; ++j) { const f32x4 g = ((const f32x4*)gnext)[lane + 64 * j]; const f32x4 v = h[j] * g * rs2;
;             u32x2 w; w.x = pk2(v.x, v.y); w.y = pk2(v.z, v.w); up[lane + 64 * j] = w; }
	v_pk_mul_f32 v[78:79], v[78:79], v[174:175]
	v_pk_mul_f32 v[76:77], v[76:77], v[172:173]
	v_pk_fma_f32 v[78:79], v[78:79], v[170:171], v[46:47] op_sel_hi:[1,0,1]
	v_pk_fma_f32 v[76:77], v[76:77], v[170:171], v[44:45] op_sel_hi:[1,0,1]
	global_store_dwordx4 v81, v[76:79], s[6:7] offset:3072 nt
	global_load_dwordx4 v[172:175], v[108:109], off
	v_mov_b32_e32 v81, v179
	v_mov_b32_e32 v179, v71
	s_waitcnt vmcnt(0)
	v_pk_mul_f32 v[80:81], v[80:81], v[172:173]
	v_pk_mul_f32 v[82:83], v[82:83], v[174:175]
	v_pk_fma_f32 v[80:81], v[80:81], v[170:171], v[48:49] op_sel_hi:[1,0,1]
	v_pk_fma_f32 v[82:83], v[82:83], v[170:171], v[50:51] op_sel_hi:[1,0,1]
	global_store_dwordx4 v93, v[80:83], s[6:7] nt
	global_load_dwordx4 v[172:175], v[110:111], off
	v_lshlrev_b32_e32 v93, 4, v100
	s_waitcnt vmcnt(0)
	v_pk_mul_f32 v[172:173], v[172:173], v[180:181]
	v_pk_mul_f32 v[84:85], v[174:175], v[86:87]
	s_nop 0
	v_pk_fma_f32 v[86:87], v[170:171], v[84:85], v[54:55] op_sel_hi:[0,1,1]
	v_pk_fma_f32 v[84:85], v[170:171], v[172:173], v[52:53] op_sel_hi:[0,1,1]
	global_store_dwordx4 v93, v[84:87], s[6:7] nt
	global_load_dwordx4 v[172:175], v[112:113], off
	v_lshlrev_b32_e32 v93, 4, v102
	s_waitcnt vmcnt(0)
	v_pk_mul_f32 v[90:91], v[90:91], v[174:175]
	v_pk_mul_f32 v[88:89], v[88:89], v[172:173]
	v_pk_fma_f32 v[90:91], v[170:171], v[90:91], v[58:59] op_sel_hi:[0,1,1]
	v_pk_fma_f32 v[88:89], v[170:171], v[88:89], v[56:57] op_sel_hi:[0,1,1]
	global_store_dwordx4 v93, v[88:91], s[6:7] nt
	global_load_dwordx4 v[172:175], v[114:115], off
	v_mov_b32_e32 v93, v178
	v_mov_b32_e32 v178, v67
	v_pk_mul_f32 v[178:179], v[178:179], v[178:179]
	s_waitcnt vmcnt(0)
	v_pk_mul_f32 v[94:95], v[94:95], v[174:175]
	v_mov_b32_e32 v174, v65
	v_mov_b32_e32 v175, v69
	v_pk_mul_f32 v[92:93], v[92:93], v[172:173]
	v_mov_b32_e32 v172, v64
	v_mov_b32_e32 v173, v68
	v_pk_mul_f32 v[174:175], v[174:175], v[174:175]
	v_pk_fma_f32 v[94:95], v[170:171], v[94:95], v[62:63] op_sel_hi:[0,1,1]
	v_pk_fma_f32 v[172:173], v[172:173], v[172:173], v[174:175]
	v_mov_b32_e32 v174, v66
	v_mov_b32_e32 v175, v70
	v_pk_fma_f32 v[174:175], v[174:175], v[174:175], v[178:179]
	v_pk_fma_f32 v[92:93], v[170:171], v[92:93], v[60:61] op_sel_hi:[0,1,1]
	v_lshlrev_b32_e32 v170, 4, v104
	v_pk_add_f32 v[172:173], v[172:173], v[174:175]
	v_pk_mul_f32 v[174:175], v[72:73], v[72:73]
	v_pk_mul_f32 v[178:179], v[74:75], v[74:75]
	global_store_dwordx4 v170, v[92:95], s[6:7] nt
	v_pk_mov_b32 v[180:181], v[174:175], v[178:179] op_sel:[1,0]
	v_mov_b32_e32 v175, v179
	v_mul_f32_e32 v170, v76, v76
	v_pk_add_f32 v[174:175], v[180:181], v[174:175]
	v_pk_fma_f32 v[178:179], v[76:77], v[76:77], v[170:171] op_sel_hi:[1,1,0]
	v_mul_f32_e32 v170, v78, v78
	v_pk_add_f32 v[172:173], v[172:173], v[172:173] op_sel_hi:[0,1]
	v_pk_add_f32 v[174:175], v[174:175], v[174:175] op_sel_hi:[0,1]
	v_pk_fma_f32 v[180:181], v[78:79], v[78:79], v[170:171] op_sel_hi:[1,1,0]
	v_mul_f32_e32 v178, v80, v80
	v_mul_f32_e32 v180, v81, v81
	v_mul_f32_e32 v174, v82, v82
	v_mul_f32_e32 v172, v83, v83
	v_pk_add_f32 v[178:179], v[178:179], v[180:181]
	v_pk_add_f32 v[172:173], v[174:175], v[172:173]
	v_pk_mul_f32 v[174:175], v[84:85], v[84:85]
	v_pk_add_f32 v[172:173], v[178:179], v[172:173]
	v_pk_mul_f32 v[178:179], v[86:87], v[86:87]
	v_mul_f32_e32 v170, v88, v88
	v_pk_mov_b32 v[180:181], v[174:175], v[178:179] op_sel:[1,0]
	v_mov_b32_e32 v175, v179
	v_pk_add_f32 v[174:175], v[180:181], v[174:175]
	v_pk_fma_f32 v[178:179], v[88:89], v[88:89], v[170:171] op_sel_hi:[1,1,0]
	v_mul_f32_e32 v170, v90, v90
	v_pk_add_f32 v[172:173], v[172:173], v[172:173] op_sel_hi:[0,1]
	v_pk_add_f32 v[174:175], v[174:175], v[174:175] op_sel_hi:[0,1]
	v_pk_fma_f32 v[180:181], v[90:91], v[90:91], v[170:171] op_sel_hi:[1,1,0]
	v_mul_f32_e32 v178, v92, v92
	v_mul_f32_e32 v180, v93, v93
	v_mul_f32_e32 v174, v94, v94
	v_mul_f32_e32 v172, v95, v95
	v_pk_add_f32 v[178:179], v[178:179], v[180:181]
	v_pk_add_f32 v[172:173], v[174:175], v[172:173]
	s_mov_b64 s[6:7], 0
	v_pk_add_f32 v[172:173], v[178:179], v[172:173]
	s_nop 0
	v_add_f32_e32 v170, v172, v173
	ds_bpermute_b32 v172, v97, v170
	s_waitcnt lgkmcnt(0)
	v_add_f32_e32 v170, v170, v172
	ds_bpermute_b32 v172, v99, v170
	s_waitcnt lgkmcnt(0)
	v_add_f32_e32 v170, v170, v172
	ds_bpermute_b32 v172, v101, v170
	s_waitcnt lgkmcnt(0)
	v_add_f32_e32 v170, v170, v172
	ds_bpermute_b32 v172, v103, v170
	s_waitcnt lgkmcnt(0)
	v_add_f32_e32 v170, v170, v172
	ds_bpermute_b32 v172, v105, v170
	s_waitcnt lgkmcnt(0)
	v_add_f32_e32 v170, v170, v172
	ds_bpermute_b32 v172, v127, v170
	s_waitcnt lgkmcnt(0)
	v_add_f32_e32 v170, v170, v172
	v_fmamk_f32 v170, v170, 0x3a000000, v176
	v_cmp_gt_f32_e32 vcc, s75, v170
	v_mul_f32_e32 v172, 0x4b800000, v170
	s_nop 0
	v_cndmask_b32_e32 v170, v170, v172, vcc
	v_rsq_f32_e32 v170, v170
	s_nop 0
	v_mul_f32_e32 v172, 0x45800000, v170
	v_cndmask_b32_e32 v170, v170, v172, vcc
	global_load_dwordx4 v[172:175], v[116:117], off
	s_waitcnt vmcnt(0)
	v_pk_mul_f32 v[172:173], v[64:65], v[172:173]
	s_nop 0
	v_pk_mul_f32 v[172:173], v[172:173], v[170:171] op_sel_hi:[1,0]
	v_pk_mul_f32 v[174:175], v[66:67], v[174:175]
	v_bfe_u32 v178, v172, 16, 1
	v_add3_u32 v172, v172, v178, s73
	v_bfe_u32 v178, v173, 16, 1
	v_pk_mul_f32 v[174:175], v[174:175], v[170:171] op_sel_hi:[1,0]
	v_lshrrev_b32_e32 v172, 16, v172
	v_add3_u32 v173, v173, v178, s73
	v_and_or_b32 v172, v173, s20, v172
	v_bfe_u32 v173, v174, 16, 1
	v_add3_u32 v173, v174, v173, s73
	v_bfe_u32 v174, v175, 16, 1
	v_lshrrev_b32_e32 v173, 16, v173
	v_add3_u32 v174, v175, v174, s73
	v_and_or_b32 v173, v174, s20, v173
	v_lshl_add_u64 v[174:175], s[62:63], 0, v[166:167]
	v_add_co_u32_e32 v182, vcc, s30, v174
	s_nop 1
	v_addc_co_u32_e32 v183, vcc, 0, v175, vcc
	global_store_dwordx2 v[182:183], v[172:173], off offset:3328
	global_load_dwordx4 v[178:181], v[116:117], off offset:1024
	s_waitcnt vmcnt(0)
; __device__ __forceinline__ unsigned pk2(float lo, float hi) { return f2bf(lo) | (f2bf(hi) << 16); }
; template <int MODE>
; __device__ __forceinline__ void row_finish(const Params& p, int r, int lane, const float* gpost, const float* gnext, bf16_t* U, float coef, f32x4 (&h)[8], const u32x2 (&dw)[8]) {
;     ...
;     if (r >= ROWS) { if (MODE != 3) { u32x4* up = (u32x4*)(U + (size_t)r * DM);
; #pragma unroll
;             for (int j = 0; j < 4; ++j) up[lane + 64 * j] = (u32x4){0u, 0u, 0u, 0u}; } return; }
;     ...
;         for (int j = 0; j < 8; ++j) { const f32x4 g = ((const f32x4*)gnext)[lane + 64 * j]; const f32x4 v = h[j] * g * rs2;
;             u32x2 w; w.x = pk2(v.x, v.y); w.y = pk2(v.z, v.w); up[lane + 64 * j] = w; }
	v_pk_mul_f32 v[172:173], v[68:69], v[178:179]
	s_nop 0
	v_pk_mul_f32 v[172:173], v[172:173], v[170:171] op_sel_hi:[1,0]
	v_pk_mul_f32 v[178:179], v[70:71], v[180:181]
	v_bfe_u32 v180, v172, 16, 1
	v_add3_u32 v172, v172, v180, s73
	v_bfe_u32 v180, v173, 16, 1
	v_pk_mul_f32 v[178:179], v[178:179], v[170:171] op_sel_hi:[1,0]
	v_lshrrev_b32_e32 v172, 16, v172
	v_add3_u32 v173, v173, v180, s73
	v_and_or_b32 v172, v173, s20, v172
	v_bfe_u32 v173, v178, 16, 1
	v_add3_u32 v173, v178, v173, s73
	v_bfe_u32 v178, v179, 16, 1
	v_lshrrev_b32_e32 v173, 16, v173
	v_add3_u32 v178, v179, v178, s73
	v_and_or_b32 v173, v178, s20, v173
	global_store_dwordx2 v[182:183], v[172:173], off offset:3840
	global_load_dwordx4 v[178:181], v[116:117], off offset:2048
	s_waitcnt vmcnt(0)
	v_pk_mul_f32 v[172:173], v[72:73], v[178:179]
	s_nop 0
	v_pk_mul_f32 v[172:173], v[172:173], v[170:171] op_sel_hi:[1,0]
	v_pk_mul_f32 v[178:179], v[74:75], v[180:181]
	v_bfe_u32 v180, v172, 16, 1
	v_add3_u32 v172, v172, v180, s73
	v_bfe_u32 v180, v173, 16, 1
	v_pk_mul_f32 v[178:179], v[178:179], v[170:171] op_sel_hi:[1,0]
	v_lshrrev_b32_e32 v172, 16, v172
	v_add3_u32 v173, v173, v180, s73
	v_and_or_b32 v180, v173, s20, v172
	v_bfe_u32 v172, v178, 16, 1
	v_add3_u32 v172, v178, v172, s73
	v_bfe_u32 v173, v179, 16, 1
	v_lshrrev_b32_e32 v172, 16, v172
	v_add3_u32 v173, v179, v173, s73
	v_and_or_b32 v181, v173, s20, v172
	v_add_co_u32_e32 v172, vcc, s31, v174
	s_nop 1
	v_addc_co_u32_e32 v173, vcc, 0, v175, vcc
	global_store_dwordx2 v[172:173], v[180:181], off offset:256
	global_load_dwordx4 v[178:181], v[116:117], off offset:3072
	s_waitcnt vmcnt(0)
	v_pk_mul_f32 v[174:175], v[76:77], v[178:179]
	s_nop 0
	v_pk_mul_f32 v[174:175], v[174:175], v[170:171] op_sel_hi:[1,0]
	v_pk_mul_f32 v[178:179], v[78:79], v[180:181]
	v_bfe_u32 v180, v174, 16, 1
	v_add3_u32 v174, v174, v180, s73
	v_bfe_u32 v180, v175, 16, 1
	v_pk_mul_f32 v[178:179], v[178:179], v[170:171] op_sel_hi:[1,0]
	v_lshrrev_b32_e32 v174, 16, v174
	v_add3_u32 v175, v175, v180, s73
	v_and_or_b32 v174, v175, s20, v174
	v_bfe_u32 v175, v178, 16, 1
	v_add3_u32 v175, v178, v175, s73
	v_bfe_u32 v178, v179, 16, 1
	v_lshrrev_b32_e32 v175, 16, v175
	v_add3_u32 v178, v179, v178, s73
	v_and_or_b32 v175, v178, s20, v175
	global_store_dwordx2 v[172:173], v[174:175], off offset:768
	global_load_dwordx4 v[178:181], v[118:119], off
	s_waitcnt vmcnt(0)
	v_pk_mul_f32 v[174:175], v[80:81], v[178:179]
	s_nop 0
	v_pk_mul_f32 v[174:175], v[174:175], v[170:171] op_sel_hi:[1,0]
	v_pk_mul_f32 v[178:179], v[82:83], v[180:181]
	v_bfe_u32 v180, v174, 16, 1
	v_add3_u32 v174, v174, v180, s73
	v_bfe_u32 v180, v175, 16, 1
	v_pk_mul_f32 v[178:179], v[178:179], v[170:171] op_sel_hi:[1,0]
	v_lshrrev_b32_e32 v174, 16, v174
	v_add3_u32 v175, v175, v180, s73
	v_and_or_b32 v174, v175, s20, v174
	v_bfe_u32 v175, v178, 16, 1
	v_add3_u32 v175, v178, v175, s73
	v_bfe_u32 v178, v179, 16, 1
	v_lshrrev_b32_e32 v175, 16, v175
	v_add3_u32 v178, v179, v178, s73
	v_and_or_b32 v175, v178, s20, v175
	global_store_dwordx2 v[172:173], v[174:175], off offset:1280
	global_load_dwordx4 v[178:181], v[120:121], off
	s_waitcnt vmcnt(0)
	v_pk_mul_f32 v[174:175], v[84:85], v[178:179]
	s_nop 0
	v_pk_mul_f32 v[174:175], v[174:175], v[170:171] op_sel_hi:[1,0]
	v_pk_mul_f32 v[178:179], v[86:87], v[180:181]
	v_bfe_u32 v180, v174, 16, 1
	v_add3_u32 v174, v174, v180, s73
	v_bfe_u32 v180, v175, 16, 1
	v_pk_mul_f32 v[178:179], v[178:179], v[170:171] op_sel_hi:[1,0]
	v_lshrrev_b32_e32 v174, 16, v174
	v_add3_u32 v175, v175, v180, s73
	v_and_or_b32 v174, v175, s20, v174
	v_bfe_u32 v175, v178, 16, 1
	v_add3_u32 v175, v178, v175, s73
	v_bfe_u32 v178, v179, 16, 1
	v_lshrrev_b32_e32 v175, 16, v175
	v_add3_u32 v178, v179, v178, s73
	v_and_or_b32 v175, v178, s20, v175
	global_store_dwordx2 v[172:173], v[174:175], off offset:1792
	global_load_dwordx4 v[178:181], v[122:123], off
	s_waitcnt vmcnt(0)
	v_pk_mul_f32 v[174:175], v[88:89], v[178:179]
	s_nop 0
	v_pk_mul_f32 v[174:175], v[174:175], v[170:171] op_sel_hi:[1,0]
	v_pk_mul_f32 v[178:179], v[90:91], v[180:181]
	v_bfe_u32 v180, v174, 16, 1
	v_add3_u32 v174, v174, v180, s73
	v_bfe_u32 v180, v175, 16, 1
	v_pk_mul_f32 v[178:179], v[178:179], v[170:171] op_sel_hi:[1,0]
	v_lshrrev_b32_e32 v174, 16, v174
	v_add3_u32 v175, v175, v180, s73
	v_and_or_b32 v174, v175, s20, v174
	v_bfe_u32 v175, v178, 16, 1
	v_add3_u32 v175, v178, v175, s73
	v_bfe_u32 v178, v179, 16, 1
	v_lshrrev_b32_e32 v175, 16, v175
	v_add3_u32 v178, v179, v178, s73
	v_and_or_b32 v175, v178, s20, v175
	global_store_dwordx2 v[172:173], v[174:175], off offset:2304
	global_load_dwordx4 v[178:181], v[124:125], off
	s_waitcnt vmcnt(0)
	v_pk_mul_f32 v[174:175], v[92:93], v[178:179]
	v_pk_mul_f32 v[178:179], v[94:95], v[180:181]
	v_pk_mul_f32 v[174:175], v[174:175], v[170:171] op_sel_hi:[1,0]
	v_pk_mul_f32 v[178:179], v[178:179], v[170:171] op_sel_hi:[1,0]
	v_bfe_u32 v170, v174, 16, 1
	v_add3_u32 v170, v174, v170, s73
	v_bfe_u32 v174, v175, 16, 1
	v_lshrrev_b32_e32 v170, 16, v170
	v_add3_u32 v174, v175, v174, s73
	v_and_or_b32 v174, v174, s20, v170
	v_bfe_u32 v170, v178, 16, 1
	v_add3_u32 v170, v178, v170, s73
	v_bfe_u32 v175, v179, 16, 1
	v_lshrrev_b32_e32 v170, 16, v170
	v_add3_u32 v175, v179, v175, s73
	v_and_or_b32 v175, v175, s20, v170
	global_store_dwordx2 v[172:173], v[174:175], off offset:2816
.LBB0_188:
	s_andn2_b64 vcc, exec, s[6:7]
	s_cbranch_vccnz .LBB0_190
	v_lshl_add_u64 v[64:65], s[62:63], 0, v[168:169]
	v_add_co_u32_e32 v66, vcc, 0xa2f1000, v64
	s_mov_b32 s6, s4
	s_nop 0
	v_addc_co_u32_e32 v67, vcc, 0, v65, vcc
	s_mov_b32 s7, s4
	s_mov_b32 s5, s4
	v_mov_b64_e32 v[70:71], s[6:7]
	v_add_co_u32_e32 v64, vcc, 0xa2f2000, v64
	v_mov_b64_e32 v[68:69], s[4:5]
	s_nop 0
	v_addc_co_u32_e32 v65, vcc, 0, v65, vcc
	global_store_dwordx4 v[66:67], v[68:71], off offset:3328
	global_store_dwordx4 v[64:65], v[68:71], off offset:256
	global_store_dwordx4 v[64:65], v[68:71], off offset:1280
	global_store_dwordx4 v[64:65], v[68:71], off offset:2304
	s_waitcnt vmcnt(0)
	v_mov_b32_e32 v95, v63
	v_mov_b32_e32 v94, v62
	v_mov_b32_e32 v93, v61
	v_mov_b32_e32 v92, v60
	v_mov_b32_e32 v91, v59
	v_mov_b32_e32 v90, v58
	v_mov_b32_e32 v89, v57
	v_mov_b32_e32 v88, v56
	v_mov_b32_e32 v87, v55
	v_mov_b32_e32 v86, v54
	v_mov_b32_e32 v85, v53
	v_mov_b32_e32 v84, v52
	v_mov_b32_e32 v83, v51
	v_mov_b32_e32 v82, v50
	v_mov_b32_e32 v81, v49
	v_mov_b32_e32 v80, v48
	v_mov_b32_e32 v79, v47
	v_mov_b32_e32 v78, v46
	v_mov_b32_e32 v77, v45
	v_mov_b32_e32 v76, v44
	v_mov_b32_e32 v75, v43
	v_mov_b32_e32 v74, v42
	v_mov_b32_e32 v73, v41
	v_mov_b32_e32 v72, v40
	v_mov_b32_e32 v71, v39
	v_mov_b32_e32 v70, v38
	v_mov_b32_e32 v69, v37
	v_mov_b32_e32 v68, v36
	v_mov_b32_e32 v67, v3
	v_mov_b32_e32 v66, v2
	v_mov_b32_e32 v65, v1
	v_mov_b32_e32 v64, v0

; template <int MODE>
; __device__ __forceinline__ void row_finish(const Params& p, int r, int lane, const float* gpost, const float* gnext, bf16_t* U, float coef, f32x4 (&h)[8], const u32x2 (&dw)[8]) {
;     ...
;     if (MODE >= 1) {
;         f32x4 d[8]; float ss = 0.f;
; #pragma unroll
;         for (int j = 0; j < 8; ++j) { const u32x2 w = dw[j]; d[j] = (f32x4){bflo(w.x), bfhi(w.x), bflo(w.y), bfhi(w.y)};
;             ss += (d[j].x * d[j].x + d[j].y * d[j].y) + (d[j].z * d[j].z + d[j].w * d[j].w); }
;         ss = wave_sum(ss);
;         const float rs = rsqrtf(ss * (1.f / DM) + EPS) * coef;
;         f32x4* hd = (f32x4*)hrow(p, r);
; #pragma unroll
;         for (int j = 0; j < 8; ++j) { const f32x4 g = ((const f32x4*)gpost)[lane + 64 * j]; h[j] = h[j] + d[j] * g * rs; __builtin_nontemporal_store(h[j], &hd[lane + 64 * j]); }
;     ...
;         float s2 = 0.f;
; #pragma unroll
;         for (int j = 0; j < 8; ++j) s2 += (h[j].x * h[j].x + h[j].y * h[j].y) + (h[j].z * h[j].z + h[j].w * h[j].w);
;         s2 = wave_sum(s2);
.LBB0_191:
	s_andn2_b64 vcc, exec, s[28:29]
	s_mov_b64 s[6:7], -1
	s_cbranch_vccnz .LBB0_193
	s_waitcnt vmcnt(0) lgkmcnt(0)
	v_and_b32_e32 v71, 0xffff0000, v134
	v_and_b32_e32 v70, 0xffff0000, v136
	v_and_b32_e32 v175, 0xffff0000, v135
	v_and_b32_e32 v174, 0xffff0000, v137
	v_lshlrev_b32_e32 v69, 16, v134
	v_lshlrev_b32_e32 v68, 16, v136
	v_lshlrev_b32_e32 v173, 16, v135
	v_lshlrev_b32_e32 v172, 16, v137
	v_pk_mul_f32 v[64:65], v[70:71], v[70:71]
	v_pk_mul_f32 v[66:67], v[174:175], v[174:175]
	v_pk_fma_f32 v[64:65], v[68:69], v[68:69], v[64:65]
	v_pk_fma_f32 v[66:67], v[172:173], v[172:173], v[66:67]
	v_and_b32_e32 v75, 0xffff0000, v139
	v_pk_add_f32 v[64:65], v[64:65], v[66:67]
	v_and_b32_e32 v74, 0xffff0000, v138
	v_pk_add_f32 v[64:65], v[64:65], v[64:65] op_sel_hi:[0,1]
	v_lshlrev_b32_e32 v73, 16, v139
	v_lshlrev_b32_e32 v72, 16, v138
	v_pk_mul_f32 v[66:67], v[74:75], v[74:75]
	v_lshlrev_b32_e32 v76, 16, v140
	v_and_b32_e32 v77, 0xffff0000, v140
	v_lshlrev_b32_e32 v78, 16, v141
	v_lshlrev_b32_e32 v80, 16, v142
	v_pk_fma_f32 v[66:67], v[72:73], v[72:73], v[66:67]
	v_mul_f32_e32 v81, v76, v76
	v_mul_f32_e32 v85, v77, v77
	v_and_b32_e32 v79, 0xffff0000, v141
	v_mul_f32_e32 v64, v78, v78
	v_mov_b32_e32 v84, v80
	v_pk_add_f32 v[66:67], v[66:67], v[66:67] op_sel_hi:[0,1]
	v_pk_fma_f32 v[86:87], v[78:79], v[78:79], v[64:65] op_sel_hi:[1,1,0]
	v_and_b32_e32 v179, 0xffff0000, v142
	v_lshlrev_b32_e32 v82, 16, v143
	v_and_b32_e32 v83, 0xffff0000, v143
	v_pk_add_f32 v[84:85], v[80:81], v[84:85]
	v_mul_f32_e32 v86, v179, v179
	v_mul_f32_e32 v66, v82, v82
	v_mul_f32_e32 v64, v83, v83
	v_mul_f32_e32 v88, v80, v80
	v_mov_b32_e32 v89, v85
	v_pk_add_f32 v[84:85], v[88:89], v[86:87]
	v_pk_add_f32 v[64:65], v[66:67], v[64:65]
	v_and_b32_e32 v87, 0xffff0000, v145
	v_pk_add_f32 v[64:65], v[84:85], v[64:65]
	v_and_b32_e32 v86, 0xffff0000, v144
	v_pk_add_f32 v[64:65], v[64:65], v[64:65] op_sel_hi:[0,1]
	v_lshlrev_b32_e32 v85, 16, v145
	v_lshlrev_b32_e32 v84, 16, v144
	v_pk_mul_f32 v[66:67], v[86:87], v[86:87]
	v_lshlrev_b32_e32 v88, 16, v146
	v_and_b32_e32 v89, 0xffff0000, v146
	v_lshlrev_b32_e32 v90, 16, v147
	v_lshlrev_b32_e32 v92, 16, v148
	v_pk_fma_f32 v[66:67], v[84:85], v[84:85], v[66:67]
	v_mul_f32_e32 v93, v88, v88
	v_mul_f32_e32 v181, v89, v89
	v_and_b32_e32 v91, 0xffff0000, v147
	v_mul_f32_e32 v64, v90, v90
	v_mov_b32_e32 v180, v92
	v_pk_add_f32 v[66:67], v[66:67], v[66:67] op_sel_hi:[0,1]
	v_pk_fma_f32 v[182:183], v[90:91], v[90:91], v[64:65] op_sel_hi:[1,1,0]
	v_and_b32_e32 v178, 0xffff0000, v148
	v_lshlrev_b32_e32 v94, 16, v149
	v_and_b32_e32 v95, 0xffff0000, v149
	v_pk_add_f32 v[180:181], v[92:93], v[180:181]
	v_mul_f32_e32 v182, v178, v178
	v_mul_f32_e32 v66, v94, v94
	v_mul_f32_e32 v64, v95, v95
	v_mul_f32_e32 v184, v92, v92
	v_mov_b32_e32 v185, v181
	v_pk_add_f32 v[180:181], v[184:185], v[182:183]
	v_pk_add_f32 v[64:65], v[66:67], v[64:65]
	s_add_u32 s5, s84, s60
	v_pk_add_f32 v[64:65], v[180:181], v[64:65]
	s_addc_u32 s6, 0, s61
	v_add_f32_e32 v64, v64, v65
	ds_bpermute_b32 v65, v97, v64
	s_add_u32 s5, s5, 1
	s_addc_u32 s6, s6, 0
	s_add_u32 s7, s56, s60
	s_addc_u32 s10, s57, s61
	s_waitcnt lgkmcnt(0)
	v_add_f32_e32 v64, v64, v65
	ds_bpermute_b32 v65, v99, v64
	s_add_u32 s11, s7, 1
	s_addc_u32 s7, s10, 0
	s_cmp_lt_i32 s65, 0x8000
	s_cselect_b32 s7, s7, s6
	s_waitcnt lgkmcnt(0)
	v_add_f32_e32 v64, v64, v65
	ds_bpermute_b32 v65, v101, v64
	s_cselect_b32 s6, s11, s5
	v_mov_b32_e32 v180, v69
	v_mov_b32_e32 v181, v71
	s_cselect_b32 s5, s15, s71
	s_waitcnt lgkmcnt(0)
	v_add_f32_e32 v64, v64, v65
	ds_bpermute_b32 v65, v103, v64
	s_cselect_b32 s10, s14, s70
	s_lshl_b64 s[6:7], s[6:7], 13
	s_add_u32 s6, s10, s6
	s_addc_u32 s7, s5, s7
	s_waitcnt lgkmcnt(0)
	v_add_f32_e32 v64, v64, v65
	ds_bpermute_b32 v65, v105, v64
	v_lshlrev_b32_e32 v81, 4, v96
	v_mov_b32_e32 v69, v70
	v_lshlrev_b32_e32 v93, 4, v98
	s_waitcnt lgkmcnt(0)
	v_add_f32_e32 v64, v64, v65
	ds_bpermute_b32 v65, v127, v64
	s_waitcnt lgkmcnt(0)
	v_add_f32_e32 v64, v64, v65
	v_fmamk_f32 v64, v64, 0x3a000000, v176
	v_cmp_gt_f32_e32 vcc, s75, v64
	v_mul_f32_e32 v65, 0x4b800000, v64
	s_nop 0
	v_cndmask_b32_e32 v64, v64, v65, vcc
	v_rsq_f32_e32 v64, v64
	s_nop 0
	v_mul_f32_e32 v65, 0x45800000, v64
	v_cndmask_b32_e32 v64, v64, v65, vcc
	v_mul_f32_e32 v170, 0.5, v64
	global_load_dwordx4 v[64:67], v[106:107], off
	s_waitcnt vmcnt(0)
	v_pk_mul_f32 v[64:65], v[180:181], v[64:65]
	v_mov_b32_e32 v180, v173
	v_mov_b32_e32 v181, v175
	v_pk_mul_f32 v[66:67], v[180:181], v[66:67]
	v_pk_fma_f32 v[64:65], v[64:65], v[170:171], v[4:5] op_sel_hi:[1,0,1]
	v_pk_fma_f32 v[66:67], v[66:67], v[170:171], v[6:7] op_sel_hi:[1,0,1]
	global_store_dwordx4 v81, v[64:67], s[6:7] nt
	global_load_dwordx4 v[180:183], v[106:107], off offset:1024
	v_mov_b32_e32 v173, v174
	s_waitcnt vmcnt(0)
	v_pk_mul_f32 v[172:173], v[172:173], v[182:183]
	v_pk_mul_f32 v[68:69], v[68:69], v[180:181]
	v_pk_fma_f32 v[70:71], v[172:173], v[170:171], v[10:11] op_sel_hi:[1,0,1]
	v_pk_fma_f32 v[68:69], v[68:69], v[170:171], v[8:9] op_sel_hi:[1,0,1]
	global_store_dwordx4 v81, v[68:71], s[6:7] offset:1024 nt
	global_load_dwordx4 v[172:175], v[106:107], off offset:2048
	v_mov_b32_e32 v180, v73
	v_mov_b32_e32 v181, v75
	v_mov_b32_e32 v73, v74
	s_waitcnt vmcnt(0)
	v_pk_mul_f32 v[174:175], v[174:175], v[180:181]
	v_pk_mul_f32 v[72:73], v[172:173], v[72:73]
	v_pk_fma_f32 v[74:75], v[174:175], v[170:171], v[14:15] op_sel_hi:[1,0,1]
	v_pk_fma_f32 v[72:73], v[72:73], v[170:171], v[12:13] op_sel_hi:[1,0,1]
	global_store_dwordx4 v81, v[72:75], s[6:7] offset:2048 nt
	global_load_dwordx4 v[172:175], v[106:107], off offset:3072
	v_mov_b32_e32 v180, v85
	v_mov_b32_e32 v181, v87
	v_mov_b32_e32 v85, v86
	s_waitcnt vmcnt(0)
; __device__ __forceinline__ unsigned pk2(float lo, float hi) { return f2bf(lo) | (f2bf(hi) << 16); }
; template <int MODE>
; __device__ __forceinline__ void row_finish(const Params& p, int r, int lane, const float* gpost, const float* gnext, bf16_t* U, float coef, f32x4 (&h)[8], const u32x2 (&dw)[8]) {
;     ...
;         for (int j = 0; j < 8; ++j) { const f32x4 g = ((const f32x4*)gpost)[lane + 64 * j]; h[j] = h[j] + d[j] * g * rs; __builtin_nontemporal_store(h[j], &hd[lane + 64 * j]); }
;     }
;     if (MODE != 3) {
;         float s2 = 0.f;
; #pragma unroll
;         for (int j = 0; j < 8; ++j) s2 += (h[j].x * h[j].x + h[j].y * h[j].y) + (h[j].z * h[j].z + h[j].w * h[j].w);
;         s2 = wave_sum(s2);
;         const float rs2 = rsqrtf(s2 * (1.f / DM) + EPS);
;         u32x2* up = (u32x2*)(U + (size_t)r * DM);
; #pragma unroll
;         for (int j = 0; j < 8; ++j) { const f32x4 g = ((const f32x4*)gnext)[lane + 64 * j]; const f32x4 v = h[j] * g * rs2;
;             u32x2 w; w.x = pk2(v.x, v.y); w.y = pk2(v.z, v.w); up[lane + 64 * j] = w; }
	v_pk_mul_f32 v[78:79], v[78:79], v[174:175]
	v_pk_mul_f32 v[76:77], v[76:77], v[172:173]
	v_pk_fma_f32 v[78:79], v[78:79], v[170:171], v[18:19] op_sel_hi:[1,0,1]
	v_pk_fma_f32 v[76:77], v[76:77], v[170:171], v[16:17] op_sel_hi:[1,0,1]
	global_store_dwordx4 v81, v[76:79], s[6:7] offset:3072 nt
	global_load_dwordx4 v[172:175], v[108:109], off
	v_mov_b32_e32 v81, v179
	v_mov_b32_e32 v179, v71
	s_waitcnt vmcnt(0)
	v_pk_mul_f32 v[80:81], v[80:81], v[172:173]
	v_pk_mul_f32 v[82:83], v[82:83], v[174:175]
	v_pk_fma_f32 v[80:81], v[80:81], v[170:171], v[20:21] op_sel_hi:[1,0,1]
	v_pk_fma_f32 v[82:83], v[82:83], v[170:171], v[22:23] op_sel_hi:[1,0,1]
	global_store_dwordx4 v93, v[80:83], s[6:7] nt
	global_load_dwordx4 v[172:175], v[110:111], off
	v_lshlrev_b32_e32 v93, 4, v100
	s_waitcnt vmcnt(0)
	v_pk_mul_f32 v[174:175], v[174:175], v[180:181]
	v_pk_mul_f32 v[84:85], v[172:173], v[84:85]
	v_pk_fma_f32 v[86:87], v[170:171], v[174:175], v[26:27] op_sel_hi:[0,1,1]
	v_pk_fma_f32 v[84:85], v[170:171], v[84:85], v[24:25] op_sel_hi:[0,1,1]
	global_store_dwordx4 v93, v[84:87], s[6:7] nt
	global_load_dwordx4 v[172:175], v[112:113], off
	v_lshlrev_b32_e32 v93, 4, v102
	s_waitcnt vmcnt(0)
	v_pk_mul_f32 v[90:91], v[90:91], v[174:175]
	v_pk_mul_f32 v[88:89], v[88:89], v[172:173]
	v_pk_fma_f32 v[90:91], v[170:171], v[90:91], v[30:31] op_sel_hi:[0,1,1]
	v_pk_fma_f32 v[88:89], v[170:171], v[88:89], v[28:29] op_sel_hi:[0,1,1]
	global_store_dwordx4 v93, v[88:91], s[6:7] nt
	global_load_dwordx4 v[172:175], v[114:115], off
	v_mov_b32_e32 v93, v178
	v_mov_b32_e32 v178, v67
	v_pk_mul_f32 v[178:179], v[178:179], v[178:179]
	s_waitcnt vmcnt(0)
	v_pk_mul_f32 v[94:95], v[94:95], v[174:175]
	v_mov_b32_e32 v174, v65
	v_mov_b32_e32 v175, v69
	v_pk_mul_f32 v[92:93], v[92:93], v[172:173]
	v_mov_b32_e32 v172, v64
	v_mov_b32_e32 v173, v68
	v_pk_mul_f32 v[174:175], v[174:175], v[174:175]
	v_pk_fma_f32 v[94:95], v[170:171], v[94:95], v[34:35] op_sel_hi:[0,1,1]
	v_pk_fma_f32 v[172:173], v[172:173], v[172:173], v[174:175]
	v_mov_b32_e32 v174, v66
	v_mov_b32_e32 v175, v70
	v_pk_fma_f32 v[174:175], v[174:175], v[174:175], v[178:179]
	v_pk_fma_f32 v[92:93], v[170:171], v[92:93], v[32:33] op_sel_hi:[0,1,1]
	v_lshlrev_b32_e32 v170, 4, v104
	v_pk_add_f32 v[172:173], v[172:173], v[174:175]
	v_pk_mul_f32 v[174:175], v[72:73], v[72:73]
	v_pk_mul_f32 v[178:179], v[74:75], v[74:75]
	global_store_dwordx4 v170, v[92:95], s[6:7] nt
	v_pk_mov_b32 v[180:181], v[174:175], v[178:179] op_sel:[1,0]
	v_mov_b32_e32 v175, v179
	v_mul_f32_e32 v170, v76, v76
	v_pk_add_f32 v[174:175], v[180:181], v[174:175]
	v_pk_fma_f32 v[178:179], v[76:77], v[76:77], v[170:171] op_sel_hi:[1,1,0]
	v_mul_f32_e32 v170, v78, v78
	v_pk_add_f32 v[172:173], v[172:173], v[172:173] op_sel_hi:[0,1]
	v_pk_add_f32 v[174:175], v[174:175], v[174:175] op_sel_hi:[0,1]
	v_pk_fma_f32 v[180:181], v[78:79], v[78:79], v[170:171] op_sel_hi:[1,1,0]
	v_mul_f32_e32 v178, v80, v80
	v_mul_f32_e32 v180, v81, v81
	v_mul_f32_e32 v174, v82, v82
	v_mul_f32_e32 v172, v83, v83
	v_pk_add_f32 v[178:179], v[178:179], v[180:181]
	v_pk_add_f32 v[172:173], v[174:175], v[172:173]
	v_pk_mul_f32 v[174:175], v[84:85], v[84:85]
	v_pk_add_f32 v[172:173], v[178:179], v[172:173]
	v_pk_mul_f32 v[178:179], v[86:87], v[86:87]
	v_mul_f32_e32 v170, v88, v88
	v_pk_mov_b32 v[180:181], v[174:175], v[178:179] op_sel:[1,0]
	v_mov_b32_e32 v175, v179
	v_pk_add_f32 v[174:175], v[180:181], v[174:175]
	v_pk_fma_f32 v[178:179], v[88:89], v[88:89], v[170:171] op_sel_hi:[1,1,0]
	v_mul_f32_e32 v170, v90, v90
	v_pk_add_f32 v[172:173], v[172:173], v[172:173] op_sel_hi:[0,1]
	v_pk_add_f32 v[174:175], v[174:175], v[174:175] op_sel_hi:[0,1]
	v_pk_fma_f32 v[180:181], v[90:91], v[90:91], v[170:171] op_sel_hi:[1,1,0]
	v_mul_f32_e32 v178, v92, v92
	v_mul_f32_e32 v180, v93, v93
	v_mul_f32_e32 v174, v94, v94
	v_mul_f32_e32 v172, v95, v95
	v_pk_add_f32 v[178:179], v[178:179], v[180:181]
	v_pk_add_f32 v[172:173], v[174:175], v[172:173]
	s_mov_b64 s[6:7], 0
	v_pk_add_f32 v[172:173], v[178:179], v[172:173]
	s_nop 0
	v_add_f32_e32 v170, v172, v173
	ds_bpermute_b32 v172, v97, v170
	s_waitcnt lgkmcnt(0)
	v_add_f32_e32 v170, v170, v172
	ds_bpermute_b32 v172, v99, v170
	s_waitcnt lgkmcnt(0)
	v_add_f32_e32 v170, v170, v172
	ds_bpermute_b32 v172, v101, v170
	s_waitcnt lgkmcnt(0)
	v_add_f32_e32 v170, v170, v172
	ds_bpermute_b32 v172, v103, v170
	s_waitcnt lgkmcnt(0)
	v_add_f32_e32 v170, v170, v172
	ds_bpermute_b32 v172, v105, v170
	s_waitcnt lgkmcnt(0)
	v_add_f32_e32 v170, v170, v172
	ds_bpermute_b32 v172, v127, v170
	s_waitcnt lgkmcnt(0)
	v_add_f32_e32 v170, v170, v172
	v_fmamk_f32 v170, v170, 0x3a000000, v176
	v_cmp_gt_f32_e32 vcc, s75, v170
	v_mul_f32_e32 v172, 0x4b800000, v170
	s_nop 0
	v_cndmask_b32_e32 v170, v170, v172, vcc
	v_rsq_f32_e32 v170, v170
	s_nop 0
	v_mul_f32_e32 v172, 0x45800000, v170
	v_cndmask_b32_e32 v170, v170, v172, vcc
	global_load_dwordx4 v[172:175], v[116:117], off
	s_waitcnt vmcnt(0)
	v_pk_mul_f32 v[172:173], v[64:65], v[172:173]
	s_nop 0
	v_pk_mul_f32 v[172:173], v[172:173], v[170:171] op_sel_hi:[1,0]
	v_pk_mul_f32 v[174:175], v[66:67], v[174:175]
	v_bfe_u32 v178, v172, 16, 1
	v_add3_u32 v172, v172, v178, s73
	v_bfe_u32 v178, v173, 16, 1
	v_pk_mul_f32 v[174:175], v[174:175], v[170:171] op_sel_hi:[1,0]
	v_lshrrev_b32_e32 v172, 16, v172
	v_add3_u32 v173, v173, v178, s73
	v_and_or_b32 v172, v173, s20, v172
	v_bfe_u32 v173, v174, 16, 1
	v_add3_u32 v173, v174, v173, s73
	v_bfe_u32 v174, v175, 16, 1
	v_lshrrev_b32_e32 v173, 16, v173
	v_add3_u32 v174, v175, v174, s73
	v_and_or_b32 v173, v174, s20, v173
	v_lshl_add_u64 v[174:175], s[62:63], 0, v[166:167]
	v_add_co_u32_e32 v182, vcc, s31, v174
	s_nop 1
	v_addc_co_u32_e32 v183, vcc, 0, v175, vcc
	global_store_dwordx2 v[182:183], v[172:173], off offset:3328
	global_load_dwordx4 v[178:181], v[116:117], off offset:1024
	s_waitcnt vmcnt(0)
; __device__ __forceinline__ unsigned pk2(float lo, float hi) { return f2bf(lo) | (f2bf(hi) << 16); }
; template <int MODE>
; __device__ __forceinline__ void row_finish(const Params& p, int r, int lane, const float* gpost, const float* gnext, bf16_t* U, float coef, f32x4 (&h)[8], const u32x2 (&dw)[8]) {
;     ...
;     if (r >= ROWS) { if (MODE != 3) { u32x4* up = (u32x4*)(U + (size_t)r * DM);
; #pragma unroll
;             for (int j = 0; j < 4; ++j) up[lane + 64 * j] = (u32x4){0u, 0u, 0u, 0u}; } return; }
;     ...
;         for (int j = 0; j < 8; ++j) { const f32x4 g = ((const f32x4*)gnext)[lane + 64 * j]; const f32x4 v = h[j] * g * rs2;
;             u32x2 w; w.x = pk2(v.x, v.y); w.y = pk2(v.z, v.w); up[lane + 64 * j] = w; }
	v_pk_mul_f32 v[172:173], v[68:69], v[178:179]
	s_nop 0
	v_pk_mul_f32 v[172:173], v[172:173], v[170:171] op_sel_hi:[1,0]
	v_pk_mul_f32 v[178:179], v[70:71], v[180:181]
	v_bfe_u32 v180, v172, 16, 1
	v_add3_u32 v172, v172, v180, s73
	v_bfe_u32 v180, v173, 16, 1
	v_pk_mul_f32 v[178:179], v[178:179], v[170:171] op_sel_hi:[1,0]
	v_lshrrev_b32_e32 v172, 16, v172
	v_add3_u32 v173, v173, v180, s73
	v_and_or_b32 v172, v173, s20, v172
	v_bfe_u32 v173, v178, 16, 1
	v_add3_u32 v173, v178, v173, s73
	v_bfe_u32 v178, v179, 16, 1
	v_lshrrev_b32_e32 v173, 16, v173
	v_add3_u32 v178, v179, v178, s73
	v_and_or_b32 v173, v178, s20, v173
	global_store_dwordx2 v[182:183], v[172:173], off offset:3840
	global_load_dwordx4 v[178:181], v[116:117], off offset:2048
	s_waitcnt vmcnt(0)
	v_pk_mul_f32 v[172:173], v[72:73], v[178:179]
	s_nop 0
	v_pk_mul_f32 v[172:173], v[172:173], v[170:171] op_sel_hi:[1,0]
	v_pk_mul_f32 v[178:179], v[74:75], v[180:181]
	v_bfe_u32 v180, v172, 16, 1
	v_add3_u32 v172, v172, v180, s73
	v_bfe_u32 v180, v173, 16, 1
	v_pk_mul_f32 v[178:179], v[178:179], v[170:171] op_sel_hi:[1,0]
	v_lshrrev_b32_e32 v172, 16, v172
	v_add3_u32 v173, v173, v180, s73
	v_and_or_b32 v180, v173, s20, v172
	v_bfe_u32 v172, v178, 16, 1
	v_add3_u32 v172, v178, v172, s73
	v_bfe_u32 v173, v179, 16, 1
	v_lshrrev_b32_e32 v172, 16, v172
	v_add3_u32 v173, v179, v173, s73
	v_and_or_b32 v181, v173, s20, v172
	v_add_co_u32_e32 v172, vcc, s74, v174
	s_nop 1
	v_addc_co_u32_e32 v173, vcc, 0, v175, vcc
	global_store_dwordx2 v[172:173], v[180:181], off offset:256
	global_load_dwordx4 v[178:181], v[116:117], off offset:3072
	s_waitcnt vmcnt(0)
	v_pk_mul_f32 v[174:175], v[76:77], v[178:179]
	s_nop 0
	v_pk_mul_f32 v[174:175], v[174:175], v[170:171] op_sel_hi:[1,0]
	v_pk_mul_f32 v[178:179], v[78:79], v[180:181]
	v_bfe_u32 v180, v174, 16, 1
	v_add3_u32 v174, v174, v180, s73
	v_bfe_u32 v180, v175, 16, 1
	v_pk_mul_f32 v[178:179], v[178:179], v[170:171] op_sel_hi:[1,0]
	v_lshrrev_b32_e32 v174, 16, v174
	v_add3_u32 v175, v175, v180, s73
	v_and_or_b32 v174, v175, s20, v174
	v_bfe_u32 v175, v178, 16, 1
	v_add3_u32 v175, v178, v175, s73
	v_bfe_u32 v178, v179, 16, 1
	v_lshrrev_b32_e32 v175, 16, v175
	v_add3_u32 v178, v179, v178, s73
	v_and_or_b32 v175, v178, s20, v175
	global_store_dwordx2 v[172:173], v[174:175], off offset:768
	global_load_dwordx4 v[178:181], v[118:119], off
	s_waitcnt vmcnt(0)
	v_pk_mul_f32 v[174:175], v[80:81], v[178:179]
	s_nop 0
	v_pk_mul_f32 v[174:175], v[174:175], v[170:171] op_sel_hi:[1,0]
	v_pk_mul_f32 v[178:179], v[82:83], v[180:181]
	v_bfe_u32 v180, v174, 16, 1
	v_add3_u32 v174, v174, v180, s73
	v_bfe_u32 v180, v175, 16, 1
	v_pk_mul_f32 v[178:179], v[178:179], v[170:171] op_sel_hi:[1,0]
	v_lshrrev_b32_e32 v174, 16, v174
	v_add3_u32 v175, v175, v180, s73
	v_and_or_b32 v174, v175, s20, v174
	v_bfe_u32 v175, v178, 16, 1
	v_add3_u32 v175, v178, v175, s73
	v_bfe_u32 v178, v179, 16, 1
	v_lshrrev_b32_e32 v175, 16, v175
	v_add3_u32 v178, v179, v178, s73
	v_and_or_b32 v175, v178, s20, v175
	global_store_dwordx2 v[172:173], v[174:175], off offset:1280
	global_load_dwordx4 v[178:181], v[120:121], off
	s_waitcnt vmcnt(0)
	v_pk_mul_f32 v[174:175], v[84:85], v[178:179]
	s_nop 0
	v_pk_mul_f32 v[174:175], v[174:175], v[170:171] op_sel_hi:[1,0]
	v_pk_mul_f32 v[178:179], v[86:87], v[180:181]
	v_bfe_u32 v180, v174, 16, 1
	v_add3_u32 v174, v174, v180, s73
	v_bfe_u32 v180, v175, 16, 1
	v_pk_mul_f32 v[178:179], v[178:179], v[170:171] op_sel_hi:[1,0]
	v_lshrrev_b32_e32 v174, 16, v174
	v_add3_u32 v175, v175, v180, s73
	v_and_or_b32 v174, v175, s20, v174
	v_bfe_u32 v175, v178, 16, 1
	v_add3_u32 v175, v178, v175, s73
	v_bfe_u32 v178, v179, 16, 1
	v_lshrrev_b32_e32 v175, 16, v175
	v_add3_u32 v178, v179, v178, s73
	v_and_or_b32 v175, v178, s20, v175
	global_store_dwordx2 v[172:173], v[174:175], off offset:1792
	global_load_dwordx4 v[178:181], v[122:123], off
	s_waitcnt vmcnt(0)
	v_pk_mul_f32 v[174:175], v[88:89], v[178:179]
	s_nop 0
	v_pk_mul_f32 v[174:175], v[174:175], v[170:171] op_sel_hi:[1,0]
	v_pk_mul_f32 v[178:179], v[90:91], v[180:181]
	v_bfe_u32 v180, v174, 16, 1
	v_add3_u32 v174, v174, v180, s73
	v_bfe_u32 v180, v175, 16, 1
	v_pk_mul_f32 v[178:179], v[178:179], v[170:171] op_sel_hi:[1,0]
	v_lshrrev_b32_e32 v174, 16, v174
	v_add3_u32 v175, v175, v180, s73
	v_and_or_b32 v174, v175, s20, v174
	v_bfe_u32 v175, v178, 16, 1
	v_add3_u32 v175, v178, v175, s73
	v_bfe_u32 v178, v179, 16, 1
	v_lshrrev_b32_e32 v175, 16, v175
	v_add3_u32 v178, v179, v178, s73
	v_and_or_b32 v175, v178, s20, v175
	global_store_dwordx2 v[172:173], v[174:175], off offset:2304
	global_load_dwordx4 v[178:181], v[124:125], off
	s_waitcnt vmcnt(0)
	v_pk_mul_f32 v[174:175], v[92:93], v[178:179]
	v_pk_mul_f32 v[178:179], v[94:95], v[180:181]
	v_pk_mul_f32 v[174:175], v[174:175], v[170:171] op_sel_hi:[1,0]
	v_pk_mul_f32 v[178:179], v[178:179], v[170:171] op_sel_hi:[1,0]
	v_bfe_u32 v170, v174, 16, 1
	v_add3_u32 v170, v174, v170, s73
	v_bfe_u32 v174, v175, 16, 1
	v_lshrrev_b32_e32 v170, 16, v170
	v_add3_u32 v174, v175, v174, s73
	v_and_or_b32 v174, v174, s20, v170
	v_bfe_u32 v170, v178, 16, 1
	v_add3_u32 v170, v178, v170, s73
	v_bfe_u32 v175, v179, 16, 1
	v_lshrrev_b32_e32 v170, 16, v170
	v_add3_u32 v175, v179, v175, s73
	v_and_or_b32 v175, v175, s20, v170
	global_store_dwordx2 v[172:173], v[174:175], off offset:2816
.LBB0_193:
	s_andn2_b64 vcc, exec, s[6:7]
	s_cbranch_vccnz .LBB0_164
	v_lshl_add_u64 v[64:65], s[62:63], 0, v[168:169]
	v_add_co_u32_e32 v66, vcc, 0xa2f2000, v64
	s_mov_b32 s6, s4
	s_nop 0
	v_addc_co_u32_e32 v67, vcc, 0, v65, vcc
	s_mov_b32 s7, s4
	s_mov_b32 s5, s4
	v_mov_b64_e32 v[70:71], s[6:7]
	v_add_co_u32_e32 v64, vcc, 0xa2f3000, v64
	v_mov_b64_e32 v[68:69], s[4:5]
	s_nop 0
	v_addc_co_u32_e32 v65, vcc, 0, v65, vcc
	global_store_dwordx4 v[66:67], v[68:71], off offset:3328
	global_store_dwordx4 v[64:65], v[68:71], off offset:256
	global_store_dwordx4 v[64:65], v[68:71], off offset:1280
	global_store_dwordx4 v[64:65], v[68:71], off offset:2304
	s_waitcnt vmcnt(0)
	v_mov_b64_e32 v[66:67], v[6:7]
	v_mov_b64_e32 v[74:75], v[14:15]
	v_mov_b64_e32 v[70:71], v[10:11]
	v_mov_b64_e32 v[78:79], v[18:19]
	v_mov_b64_e32 v[82:83], v[22:23]
	v_mov_b64_e32 v[86:87], v[26:27]
	v_mov_b64_e32 v[90:91], v[30:31]
	v_mov_b64_e32 v[94:95], v[34:35]
	v_mov_b64_e32 v[64:65], v[4:5]
	v_mov_b64_e32 v[68:69], v[8:9]
	v_mov_b64_e32 v[72:73], v[12:13]
	v_mov_b64_e32 v[76:77], v[16:17]
	v_mov_b64_e32 v[80:81], v[20:21]
	v_mov_b64_e32 v[84:85], v[24:25]
	v_mov_b64_e32 v[88:89], v[28:29]
	v_mov_b64_e32 v[92:93], v[32:33]
	s_branch .LBB0_164

; __device__ __forceinline__ unsigned cvt_pk_bf16(float lo, float hi) { unsigned r; asm volatile("v_cvt_pk_bf16_f32 %0, %1, %2" : "=v"(r) : "v"(lo), "v"(hi)); return r; }
;     __device__ __forceinline__ void operator()(const f32x4 (&acc)[2][2][4][2], const Unit& u, int wr, int wc, int fr, int fq) const {
;         const int row0 = u.pm * BM + wr * 64 + fr, col0 = u.pn * BM + wc * 32 + 8 * fq;
; #pragma unroll
;         for (int ai = 0; ai < 2; ++ai)
; #pragma unroll
;             for (int m = 0; m < 4; ++m) { bf16_t* rowp = O + (size_t)(row0 + ai * HALF + m * 16) * ldc + col0;
; #pragma unroll
;                 for (int bj = 0; bj < 2; ++bj) { const f32x4 v0 = acc[ai][bj][m][0], v1 = acc[ai][bj][m][1];
;                     u32x4 w; w.x = cvt_pk_bf16(v0[0], v0[1]); w.y = cvt_pk_bf16(v0[2], v0[3]); w.z = cvt_pk_bf16(v1[0], v1[1]); w.w = cvt_pk_bf16(v1[2], v1[3]);
;                     *(u32x4*)(rowp + bj * HALF) = w; } }
.LBB0_274:
	v_lshl_add_u32 v150, s87, 8, v146
	v_lshl_or_b32 v144, s86, 8, v148
	v_ashrrev_i32_e32 v151, 31, v150
	v_ashrrev_i32_e32 v145, 31, v144
	v_lshlrev_b64 v[152:153], 12, v[150:151]
	v_lshl_add_u64 v[152:153], s[26:27], 0, v[152:153]
	v_lshlrev_b64 v[154:155], 1, v[144:145]
	v_lshl_add_u64 v[144:145], v[152:153], 0, v[154:155]
	v_cvt_pk_bf16_f32 v124, v124, v125
	v_cvt_pk_bf16_f32 v125, v126, v127
	v_cvt_pk_bf16_f32 v126, v120, v121
	v_cvt_pk_bf16_f32 v127, v122, v123
	global_store_dwordx4 v[144:145], v[124:127], off
	v_cvt_pk_bf16_f32 v112, v112, v113
	v_cvt_pk_bf16_f32 v113, v114, v115
	v_cvt_pk_bf16_f32 v114, v104, v105
	v_or_b32_e32 v104, 16, v150
	v_ashrrev_i32_e32 v105, 31, v104
	v_lshlrev_b64 v[104:105], 12, v[104:105]
	v_lshl_add_u64 v[104:105], s[26:27], 0, v[104:105]
	v_cvt_pk_bf16_f32 v115, v106, v107
	global_store_dwordx4 v[144:145], v[112:115], off offset:256
	s_mov_b64 s[10:11], 0x80000
	s_nop 0
	v_lshl_add_u64 v[112:113], v[104:105], 0, v[154:155]
	v_cvt_pk_bf16_f32 v104, v116, v117
	v_cvt_pk_bf16_f32 v105, v118, v119
	v_cvt_pk_bf16_f32 v106, v108, v109
	v_cvt_pk_bf16_f32 v107, v110, v111
	global_store_dwordx4 v[112:113], v[104:107], off
	v_cvt_pk_bf16_f32 v96, v96, v97
	v_cvt_pk_bf16_f32 v97, v98, v99
	v_cvt_pk_bf16_f32 v98, v88, v89
	v_or_b32_e32 v88, 32, v150
	v_ashrrev_i32_e32 v89, 31, v88
	v_lshlrev_b64 v[88:89], 12, v[88:89]
	v_lshl_add_u64 v[88:89], s[26:27], 0, v[88:89]
	v_cvt_pk_bf16_f32 v99, v90, v91
	global_store_dwordx4 v[112:113], v[96:99], off offset:256
	s_nop 1
	v_lshl_add_u64 v[96:97], v[88:89], 0, v[154:155]
	v_cvt_pk_bf16_f32 v88, v100, v101
	v_cvt_pk_bf16_f32 v89, v102, v103
	v_cvt_pk_bf16_f32 v90, v92, v93
	v_cvt_pk_bf16_f32 v91, v94, v95
	global_store_dwordx4 v[96:97], v[88:91], off
	v_cvt_pk_bf16_f32 v80, v80, v81
	v_cvt_pk_bf16_f32 v81, v82, v83
	v_cvt_pk_bf16_f32 v82, v72, v73
	v_or_b32_e32 v72, 48, v150
	v_ashrrev_i32_e32 v73, 31, v72
	v_lshlrev_b64 v[72:73], 12, v[72:73]
	v_lshl_add_u64 v[72:73], s[26:27], 0, v[72:73]
	v_cvt_pk_bf16_f32 v83, v74, v75
	global_store_dwordx4 v[96:97], v[80:83], off offset:256
	s_nop 1
	v_lshl_add_u64 v[80:81], v[72:73], 0, v[154:155]
	v_cvt_pk_bf16_f32 v72, v84, v85
	v_cvt_pk_bf16_f32 v73, v86, v87
	v_cvt_pk_bf16_f32 v74, v76, v77
	v_cvt_pk_bf16_f32 v75, v78, v79
	global_store_dwordx4 v[80:81], v[72:75], off
	v_cvt_pk_bf16_f32 v68, v68, v69
	v_cvt_pk_bf16_f32 v69, v70, v71
	v_cvt_pk_bf16_f32 v70, v64, v65
	v_lshl_add_u64 v[64:65], v[144:145], 0, s[10:11]
	s_mov_b32 s10, 0x80000
	v_cvt_pk_bf16_f32 v71, v66, v67
	global_store_dwordx4 v[80:81], v[68:71], off offset:256
	v_cvt_pk_bf16_f32 v60, v60, v61
	v_cvt_pk_bf16_f32 v61, v62, v63
	v_cvt_pk_bf16_f32 v62, v56, v57
	v_add_co_u32_e32 v56, vcc, s10, v144
	v_cvt_pk_bf16_f32 v63, v58, v59
	s_mov_b64 s[10:11], 0x90000
	s_nop 0
	v_addc_co_u32_e32 v57, vcc, 0, v145, vcc
	global_store_dwordx4 v[56:57], v[60:63], off
	v_cvt_pk_bf16_f32 v48, v48, v49
	v_cvt_pk_bf16_f32 v49, v50, v51
	v_cvt_pk_bf16_f32 v50, v40, v41
	v_cvt_pk_bf16_f32 v51, v42, v43
	global_store_dwordx4 v[64:65], v[48:51], off offset:256
	v_cvt_pk_bf16_f32 v40, v52, v53
	v_cvt_pk_bf16_f32 v41, v54, v55
	v_cvt_pk_bf16_f32 v42, v44, v45
	v_cvt_pk_bf16_f32 v43, v46, v47
	s_nop 1
	v_lshl_add_u64 v[48:49], v[144:145], 0, s[10:11]
	s_mov_b32 s10, 0x90000
	v_add_co_u32_e32 v44, vcc, s10, v144
	s_mov_b64 s[10:11], 0xa0000
	s_nop 0
	v_addc_co_u32_e32 v45, vcc, 0, v145, vcc
	global_store_dwordx4 v[44:45], v[40:43], off
	v_cvt_pk_bf16_f32 v32, v32, v33
	v_cvt_pk_bf16_f32 v33, v34, v35
	v_cvt_pk_bf16_f32 v34, v24, v25
	v_cvt_pk_bf16_f32 v35, v26, v27
	global_store_dwordx4 v[48:49], v[32:35], off offset:256
	v_cvt_pk_bf16_f32 v24, v36, v37
	v_cvt_pk_bf16_f32 v25, v38, v39
	v_cvt_pk_bf16_f32 v26, v28, v29
	v_cvt_pk_bf16_f32 v27, v30, v31
	s_nop 1
	v_lshl_add_u64 v[32:33], v[144:145], 0, s[10:11]
	s_mov_b32 s10, 0xa0000
	v_add_co_u32_e32 v28, vcc, s10, v144
	s_mov_b64 s[10:11], 0xb0000
	s_nop 0
	v_addc_co_u32_e32 v29, vcc, 0, v145, vcc
	global_store_dwordx4 v[28:29], v[24:27], off
	v_cvt_pk_bf16_f32 v16, v16, v17
	v_cvt_pk_bf16_f32 v17, v18, v19
	v_cvt_pk_bf16_f32 v18, v8, v9
	v_cvt_pk_bf16_f32 v19, v10, v11
	global_store_dwordx4 v[32:33], v[16:19], off offset:256
	v_cvt_pk_bf16_f32 v8, v20, v21
	v_cvt_pk_bf16_f32 v9, v22, v23
	v_cvt_pk_bf16_f32 v10, v12, v13
	v_cvt_pk_bf16_f32 v11, v14, v15
	s_nop 1
	v_lshl_add_u64 v[16:17], v[144:145], 0, s[10:11]
	s_mov_b32 s10, 0xb0000
	v_add_co_u32_e32 v12, vcc, s10, v144
	s_nop 1
	v_addc_co_u32_e32 v13, vcc, 0, v145, vcc
	s_and_b64 vcc, exec, s[36:37]
	s_mov_b64 s[36:37], -1
	global_store_dwordx4 v[12:13], v[8:11], off
	v_cvt_pk_bf16_f32 v4, v4, v5
	v_cvt_pk_bf16_f32 v5, v6, v7
	v_cvt_pk_bf16_f32 v6, v0, v1
	v_cvt_pk_bf16_f32 v7, v2, v3
	global_store_dwordx4 v[16:17], v[4:7], off offset:256
	s_cbranch_vccnz .LBB0_259
	s_andn2_b64 vcc, exec, s[6:7]
	s_cbranch_vccnz .LBB0_258
	s_barrier
	s_branch .LBB0_258

; template <int MODE>
; __device__ __forceinline__ void row_finish(const Params& p, int r, int lane, const float* gpost, const float* gnext, bf16_t* U, float coef, f32x4 (&h)[8], const u32x2 (&dw)[8]) {
;     ...
;     if (MODE >= 1) {
;         f32x4 d[8]; float ss = 0.f;
; #pragma unroll
;         for (int j = 0; j < 8; ++j) { const u32x2 w = dw[j]; d[j] = (f32x4){bflo(w.x), bfhi(w.x), bflo(w.y), bfhi(w.y)};
;             ss += (d[j].x * d[j].x + d[j].y * d[j].y) + (d[j].z * d[j].z + d[j].w * d[j].w); }
;         ss = wave_sum(ss);
;         const float rs = rsqrtf(ss * (1.f / DM) + EPS) * coef;
;         f32x4* hd = (f32x4*)hrow(p, r);
; #pragma unroll
;         for (int j = 0; j < 8; ++j) { const f32x4 g = ((const f32x4*)gpost)[lane + 64 * j]; h[j] = h[j] + d[j] * g * rs; __builtin_nontemporal_store(h[j], &hd[lane + 64 * j]); }
;     ...
;         float s2 = 0.f;
; #pragma unroll
;         for (int j = 0; j < 8; ++j) s2 += (h[j].x * h[j].x + h[j].y * h[j].y) + (h[j].z * h[j].z + h[j].w * h[j].w);
;         s2 = wave_sum(s2);
.LBB0_307:
	s_andn2_b64 vcc, exec, s[6:7]
	s_mov_b64 s[6:7], -1
	s_cbranch_vccnz .LBB0_309
	s_waitcnt vmcnt(0) lgkmcnt(0)
	v_and_b32_e32 v173, 0xffff0000, v150
	v_and_b32_e32 v172, 0xffff0000, v152
	v_and_b32_e32 v175, 0xffff0000, v151
	v_and_b32_e32 v174, 0xffff0000, v153
	v_lshlrev_b32_e32 v71, 16, v150
	v_lshlrev_b32_e32 v70, 16, v152
	v_lshlrev_b32_e32 v69, 16, v151
	v_lshlrev_b32_e32 v68, 16, v153
	v_pk_mul_f32 v[64:65], v[172:173], v[172:173]
	v_pk_mul_f32 v[66:67], v[174:175], v[174:175]
	v_pk_fma_f32 v[64:65], v[70:71], v[70:71], v[64:65]
	v_pk_fma_f32 v[66:67], v[68:69], v[68:69], v[66:67]
	v_and_b32_e32 v73, 0xffff0000, v155
	v_pk_add_f32 v[64:65], v[64:65], v[66:67]
	v_and_b32_e32 v72, 0xffff0000, v154
	v_pk_add_f32 v[64:65], v[64:65], v[64:65] op_sel_hi:[0,1]
	v_lshlrev_b32_e32 v75, 16, v155
	v_lshlrev_b32_e32 v74, 16, v154
	v_pk_mul_f32 v[66:67], v[72:73], v[72:73]
	v_lshlrev_b32_e32 v76, 16, v156
	v_and_b32_e32 v77, 0xffff0000, v156
	v_lshlrev_b32_e32 v78, 16, v157
	v_lshlrev_b32_e32 v80, 16, v158
	v_pk_fma_f32 v[66:67], v[74:75], v[74:75], v[66:67]
	v_mul_f32_e32 v81, v76, v76
	v_mul_f32_e32 v85, v77, v77
	v_and_b32_e32 v79, 0xffff0000, v157
	v_mul_f32_e32 v64, v78, v78
	v_mov_b32_e32 v84, v80
	v_pk_add_f32 v[66:67], v[66:67], v[66:67] op_sel_hi:[0,1]
	v_pk_fma_f32 v[86:87], v[78:79], v[78:79], v[64:65] op_sel_hi:[1,1,0]
	v_and_b32_e32 v179, 0xffff0000, v158
	v_lshlrev_b32_e32 v82, 16, v159
	v_and_b32_e32 v83, 0xffff0000, v159
	v_pk_add_f32 v[84:85], v[80:81], v[84:85]
	v_mul_f32_e32 v86, v179, v179
	v_mul_f32_e32 v66, v82, v82
	v_mul_f32_e32 v64, v83, v83
	v_mul_f32_e32 v88, v80, v80
	v_mov_b32_e32 v89, v85
	v_pk_add_f32 v[84:85], v[88:89], v[86:87]
	v_pk_add_f32 v[64:65], v[66:67], v[64:65]
	v_and_b32_e32 v87, 0xffff0000, v161
	v_pk_add_f32 v[64:65], v[84:85], v[64:65]
	v_and_b32_e32 v86, 0xffff0000, v160
	v_pk_add_f32 v[64:65], v[64:65], v[64:65] op_sel_hi:[0,1]
	v_lshlrev_b32_e32 v85, 16, v161
	v_lshlrev_b32_e32 v84, 16, v160
	v_pk_mul_f32 v[66:67], v[86:87], v[86:87]
	v_lshlrev_b32_e32 v88, 16, v162
	v_and_b32_e32 v89, 0xffff0000, v162
	v_lshlrev_b32_e32 v90, 16, v163
	v_lshlrev_b32_e32 v92, 16, v164
	v_pk_fma_f32 v[66:67], v[84:85], v[84:85], v[66:67]
	v_mul_f32_e32 v93, v88, v88
	v_mul_f32_e32 v181, v89, v89
	v_and_b32_e32 v91, 0xffff0000, v163
	v_mul_f32_e32 v64, v90, v90
	v_mov_b32_e32 v180, v92
	v_pk_add_f32 v[66:67], v[66:67], v[66:67] op_sel_hi:[0,1]
	v_pk_fma_f32 v[182:183], v[90:91], v[90:91], v[64:65] op_sel_hi:[1,1,0]
	v_and_b32_e32 v178, 0xffff0000, v164
	v_lshlrev_b32_e32 v94, 16, v165
	v_and_b32_e32 v95, 0xffff0000, v165
	v_pk_add_f32 v[180:181], v[92:93], v[180:181]
	v_mul_f32_e32 v182, v178, v178
	v_mul_f32_e32 v66, v94, v94
	v_mul_f32_e32 v64, v95, v95
	v_mul_f32_e32 v184, v92, v92
	v_mov_b32_e32 v185, v181
	v_pk_add_f32 v[180:181], v[184:185], v[182:183]
	v_pk_add_f32 v[64:65], v[66:67], v[64:65]
	s_add_u32 s5, s69, s0
	v_pk_add_f32 v[64:65], v[180:181], v[64:65]
	s_addc_u32 s6, 0, s1
	v_add_f32_e32 v64, v64, v65
	ds_bpermute_b32 v65, v97, v64
	s_add_u32 s10, s76, s0
	s_addc_u32 s7, s77, s1
	s_cmp_lt_i32 s80, 0x8000
	s_cselect_b32 s7, s7, s6
	s_waitcnt lgkmcnt(0)
	v_add_f32_e32 v64, v64, v65
	ds_bpermute_b32 v65, v99, v64
	s_cselect_b32 s6, s10, s5
	v_mov_b32_e32 v180, v71
	v_mov_b32_e32 v181, v173
	s_cselect_b32 s5, s15, s71
	s_waitcnt lgkmcnt(0)
	v_add_f32_e32 v64, v64, v65
	ds_bpermute_b32 v65, v101, v64
	s_cselect_b32 s10, s14, s70
	s_lshl_b64 s[6:7], s[6:7], 13
	s_add_u32 s6, s10, s6
	s_addc_u32 s7, s5, s7
	s_waitcnt lgkmcnt(0)
	v_add_f32_e32 v64, v64, v65
	ds_bpermute_b32 v65, v103, v64
	v_lshlrev_b32_e32 v81, 4, v96
	v_mov_b32_e32 v71, v172
	v_lshlrev_b32_e32 v93, 4, v98
	s_waitcnt lgkmcnt(0)
	v_add_f32_e32 v64, v64, v65
	ds_bpermute_b32 v65, v105, v64
	s_waitcnt lgkmcnt(0)
	v_add_f32_e32 v64, v64, v65
	ds_bpermute_b32 v65, v127, v64
	s_waitcnt lgkmcnt(0)
	v_add_f32_e32 v64, v64, v65
	v_fmamk_f32 v64, v64, 0x3a000000, v176
	v_cmp_gt_f32_e32 vcc, s75, v64
	v_mul_f32_e32 v65, 0x4b800000, v64
	s_nop 0
	v_cndmask_b32_e32 v64, v64, v65, vcc
	v_rsq_f32_e32 v64, v64
	s_nop 0
	v_mul_f32_e32 v65, 0x45800000, v64
	v_cndmask_b32_e32 v64, v64, v65, vcc
	v_mul_f32_e32 v170, 0.5, v64
	global_load_dwordx4 v[64:67], v[106:107], off
	s_waitcnt vmcnt(0)
	v_pk_mul_f32 v[64:65], v[180:181], v[64:65]
	v_mov_b32_e32 v180, v69
	v_mov_b32_e32 v181, v175
	v_pk_mul_f32 v[66:67], v[180:181], v[66:67]
	v_pk_fma_f32 v[64:65], v[64:65], v[170:171], v[0:1] op_sel_hi:[1,0,1]
	v_pk_fma_f32 v[66:67], v[66:67], v[170:171], v[2:3] op_sel_hi:[1,0,1]
	global_store_dwordx4 v81, v[64:67], s[6:7] nt
	global_load_dwordx4 v[180:183], v[106:107], off offset:1024
	v_mov_b32_e32 v69, v174
	s_waitcnt vmcnt(0)
	v_pk_mul_f32 v[172:173], v[70:71], v[180:181]
	v_pk_mul_f32 v[68:69], v[68:69], v[182:183]
	v_mov_b32_e32 v180, v74
	v_pk_fma_f32 v[70:71], v[68:69], v[170:171], v[38:39] op_sel_hi:[1,0,1]
	v_pk_fma_f32 v[68:69], v[172:173], v[170:171], v[36:37] op_sel_hi:[1,0,1]
	global_store_dwordx4 v81, v[68:71], s[6:7] offset:1024 nt
	global_load_dwordx4 v[172:175], v[106:107], off offset:2048
	v_mov_b32_e32 v181, v72
	v_mov_b32_e32 v72, v75
	s_waitcnt vmcnt(0)
	v_pk_mul_f32 v[172:173], v[172:173], v[180:181]
	v_pk_mul_f32 v[72:73], v[174:175], v[72:73]
	v_mov_b32_e32 v180, v84
	v_pk_fma_f32 v[74:75], v[72:73], v[170:171], v[42:43] op_sel_hi:[1,0,1]
	v_pk_fma_f32 v[72:73], v[172:173], v[170:171], v[40:41] op_sel_hi:[1,0,1]
	global_store_dwordx4 v81, v[72:75], s[6:7] offset:2048 nt
	global_load_dwordx4 v[172:175], v[106:107], off offset:3072
	v_mov_b32_e32 v181, v86
	v_mov_b32_e32 v86, v85
	s_waitcnt vmcnt(0)
; __device__ __forceinline__ unsigned pk2(float lo, float hi) { return f2bf(lo) | (f2bf(hi) << 16); }
; template <int MODE>
; __device__ __forceinline__ void row_finish(const Params& p, int r, int lane, const float* gpost, const float* gnext, bf16_t* U, float coef, f32x4 (&h)[8], const u32x2 (&dw)[8]) {
;     ...
;         for (int j = 0; j < 8; ++j) { const f32x4 g = ((const f32x4*)gpost)[lane + 64 * j]; h[j] = h[j] + d[j] * g * rs; __builtin_nontemporal_store(h[j], &hd[lane + 64 * j]); }
;     }
;     if (MODE != 3) {
;         float s2 = 0.f;
; #pragma unroll
;         for (int j = 0; j < 8; ++j) s2 += (h[j].x * h[j].x + h[j].y * h[j].y) + (h[j].z * h[j].z + h[j].w * h[j].w);
;         s2 = wave_sum(s2);
;         const float rs2 = rsqrtf(s2 * (1.f / DM) + EPS);
;         u32x2* up = (u32x2*)(U + (size_t)r * DM);
; #pragma unroll
;         for (int j = 0; j < 8; ++j) { const f32x4 g = ((const f32x4*)gnext)[lane + 64 * j]; const f32x4 v = h[j] * g * rs2;
;             u32x2 w; w.x = pk2(v.x, v.y); w.y = pk2(v.z, v.w); up[lane + 64 * j] = w; }
	v_pk_mul_f32 v[78:79], v[78:79], v[174:175]
	v_pk_mul_f32 v[76:77], v[76:77], v[172:173]
	v_pk_fma_f32 v[78:79], v[78:79], v[170:171], v[46:47] op_sel_hi:[1,0,1]
	v_pk_fma_f32 v[76:77], v[76:77], v[170:171], v[44:45] op_sel_hi:[1,0,1]
	global_store_dwordx4 v81, v[76:79], s[6:7] offset:3072 nt
	global_load_dwordx4 v[172:175], v[108:109], off
	v_mov_b32_e32 v81, v179
	v_mov_b32_e32 v179, v71
	s_waitcnt vmcnt(0)
	v_pk_mul_f32 v[80:81], v[80:81], v[172:173]
	v_pk_mul_f32 v[82:83], v[82:83], v[174:175]
	v_pk_fma_f32 v[80:81], v[80:81], v[170:171], v[48:49] op_sel_hi:[1,0,1]
	v_pk_fma_f32 v[82:83], v[82:83], v[170:171], v[50:51] op_sel_hi:[1,0,1]
	global_store_dwordx4 v93, v[80:83], s[6:7] nt
	global_load_dwordx4 v[172:175], v[110:111], off
	v_lshlrev_b32_e32 v93, 4, v100
	s_waitcnt vmcnt(0)
	v_pk_mul_f32 v[172:173], v[172:173], v[180:181]
	v_pk_mul_f32 v[84:85], v[174:175], v[86:87]
	s_nop 0
	v_pk_fma_f32 v[86:87], v[170:171], v[84:85], v[54:55] op_sel_hi:[0,1,1]
	v_pk_fma_f32 v[84:85], v[170:171], v[172:173], v[52:53] op_sel_hi:[0,1,1]
	global_store_dwordx4 v93, v[84:87], s[6:7] nt
	global_load_dwordx4 v[172:175], v[112:113], off
	v_lshlrev_b32_e32 v93, 4, v102
	s_waitcnt vmcnt(0)
	v_pk_mul_f32 v[90:91], v[90:91], v[174:175]
	v_pk_mul_f32 v[88:89], v[88:89], v[172:173]
	v_pk_fma_f32 v[90:91], v[170:171], v[90:91], v[58:59] op_sel_hi:[0,1,1]
	v_pk_fma_f32 v[88:89], v[170:171], v[88:89], v[56:57] op_sel_hi:[0,1,1]
	global_store_dwordx4 v93, v[88:91], s[6:7] nt
	global_load_dwordx4 v[172:175], v[114:115], off
	v_mov_b32_e32 v93, v178
	v_mov_b32_e32 v178, v67
	v_pk_mul_f32 v[178:179], v[178:179], v[178:179]
	s_waitcnt vmcnt(0)
	v_pk_mul_f32 v[94:95], v[94:95], v[174:175]
	v_mov_b32_e32 v174, v65
	v_mov_b32_e32 v175, v69
	v_pk_mul_f32 v[92:93], v[92:93], v[172:173]
	v_mov_b32_e32 v172, v64
	v_mov_b32_e32 v173, v68
	v_pk_mul_f32 v[174:175], v[174:175], v[174:175]
	v_pk_fma_f32 v[94:95], v[170:171], v[94:95], v[62:63] op_sel_hi:[0,1,1]
	v_pk_fma_f32 v[172:173], v[172:173], v[172:173], v[174:175]
	v_mov_b32_e32 v174, v66
	v_mov_b32_e32 v175, v70
	v_pk_fma_f32 v[174:175], v[174:175], v[174:175], v[178:179]
	v_pk_fma_f32 v[92:93], v[170:171], v[92:93], v[60:61] op_sel_hi:[0,1,1]
	v_lshlrev_b32_e32 v170, 4, v104
	v_pk_add_f32 v[172:173], v[172:173], v[174:175]
	v_pk_mul_f32 v[174:175], v[72:73], v[72:73]
	v_pk_mul_f32 v[178:179], v[74:75], v[74:75]
	global_store_dwordx4 v170, v[92:95], s[6:7] nt
	v_pk_mov_b32 v[180:181], v[174:175], v[178:179] op_sel:[1,0]
	v_mov_b32_e32 v175, v179
	v_mul_f32_e32 v170, v76, v76
	v_pk_add_f32 v[174:175], v[180:181], v[174:175]
	v_pk_fma_f32 v[178:179], v[76:77], v[76:77], v[170:171] op_sel_hi:[1,1,0]
	v_mul_f32_e32 v170, v78, v78
	v_pk_add_f32 v[172:173], v[172:173], v[172:173] op_sel_hi:[0,1]
	v_pk_add_f32 v[174:175], v[174:175], v[174:175] op_sel_hi:[0,1]
	v_pk_fma_f32 v[180:181], v[78:79], v[78:79], v[170:171] op_sel_hi:[1,1,0]
	v_mul_f32_e32 v178, v80, v80
	v_mul_f32_e32 v180, v81, v81
	v_mul_f32_e32 v174, v82, v82
	v_mul_f32_e32 v172, v83, v83
	v_pk_add_f32 v[178:179], v[178:179], v[180:181]
	v_pk_add_f32 v[172:173], v[174:175], v[172:173]
	v_pk_mul_f32 v[174:175], v[84:85], v[84:85]
	v_pk_add_f32 v[172:173], v[178:179], v[172:173]
	v_pk_mul_f32 v[178:179], v[86:87], v[86:87]
	v_mul_f32_e32 v170, v88, v88
	v_pk_mov_b32 v[180:181], v[174:175], v[178:179] op_sel:[1,0]
	v_mov_b32_e32 v175, v179
	v_pk_add_f32 v[174:175], v[180:181], v[174:175]
	v_pk_fma_f32 v[178:179], v[88:89], v[88:89], v[170:171] op_sel_hi:[1,1,0]
	v_mul_f32_e32 v170, v90, v90
	v_pk_add_f32 v[172:173], v[172:173], v[172:173] op_sel_hi:[0,1]
	v_pk_add_f32 v[174:175], v[174:175], v[174:175] op_sel_hi:[0,1]
	v_pk_fma_f32 v[180:181], v[90:91], v[90:91], v[170:171] op_sel_hi:[1,1,0]
	v_mul_f32_e32 v178, v92, v92
	v_mul_f32_e32 v180, v93, v93
	v_mul_f32_e32 v174, v94, v94
	v_mul_f32_e32 v172, v95, v95
	v_pk_add_f32 v[178:179], v[178:179], v[180:181]
	v_pk_add_f32 v[172:173], v[174:175], v[172:173]
	s_mov_b64 s[6:7], 0
	v_pk_add_f32 v[172:173], v[178:179], v[172:173]
	s_nop 0
	v_add_f32_e32 v170, v172, v173
	ds_bpermute_b32 v172, v97, v170
	s_waitcnt lgkmcnt(0)
	v_add_f32_e32 v170, v170, v172
	ds_bpermute_b32 v172, v99, v170
	s_waitcnt lgkmcnt(0)
	v_add_f32_e32 v170, v170, v172
	ds_bpermute_b32 v172, v101, v170
	s_waitcnt lgkmcnt(0)
	v_add_f32_e32 v170, v170, v172
	ds_bpermute_b32 v172, v103, v170
	s_waitcnt lgkmcnt(0)
	v_add_f32_e32 v170, v170, v172
	ds_bpermute_b32 v172, v105, v170
	s_waitcnt lgkmcnt(0)
	v_add_f32_e32 v170, v170, v172
	ds_bpermute_b32 v172, v127, v170
	s_waitcnt lgkmcnt(0)
	v_add_f32_e32 v170, v170, v172
	v_fmamk_f32 v170, v170, 0x3a000000, v176
	v_cmp_gt_f32_e32 vcc, s75, v170
	v_mul_f32_e32 v172, 0x4b800000, v170
	s_nop 0
	v_cndmask_b32_e32 v170, v170, v172, vcc
	v_rsq_f32_e32 v170, v170
	s_nop 0
	v_mul_f32_e32 v172, 0x45800000, v170
	v_cndmask_b32_e32 v170, v170, v172, vcc
	global_load_dwordx4 v[172:175], v[116:117], off
	s_waitcnt vmcnt(0)
	v_pk_mul_f32 v[172:173], v[64:65], v[172:173]
	s_nop 0
	v_pk_mul_f32 v[172:173], v[172:173], v[170:171] op_sel_hi:[1,0]
	v_pk_mul_f32 v[174:175], v[66:67], v[174:175]
	v_bfe_u32 v178, v172, 16, 1
	v_add3_u32 v172, v172, v178, s73
	v_bfe_u32 v178, v173, 16, 1
	v_pk_mul_f32 v[174:175], v[174:175], v[170:171] op_sel_hi:[1,0]
	v_lshrrev_b32_e32 v172, 16, v172
	v_add3_u32 v173, v173, v178, s73
	v_and_or_b32 v172, v173, s20, v172
	v_bfe_u32 v173, v174, 16, 1
	v_add3_u32 v173, v174, v173, s73
	v_bfe_u32 v174, v175, 16, 1
	v_lshrrev_b32_e32 v173, 16, v173
	v_add3_u32 v174, v175, v174, s73
	v_and_or_b32 v173, v174, s20, v173
	v_lshl_add_u64 v[174:175], s[56:57], 0, v[166:167]
	v_add_co_u32_e32 v182, vcc, s30, v174
	s_nop 1
	v_addc_co_u32_e32 v183, vcc, 0, v175, vcc
	global_store_dwordx2 v[182:183], v[172:173], off offset:3328
	global_load_dwordx4 v[178:181], v[116:117], off offset:1024
	s_waitcnt vmcnt(0)
; __device__ __forceinline__ unsigned pk2(float lo, float hi) { return f2bf(lo) | (f2bf(hi) << 16); }
; template <int MODE>
; __device__ __forceinline__ void row_finish(const Params& p, int r, int lane, const float* gpost, const float* gnext, bf16_t* U, float coef, f32x4 (&h)[8], const u32x2 (&dw)[8]) {
;     ...
;     if (r >= ROWS) { if (MODE != 3) { u32x4* up = (u32x4*)(U + (size_t)r * DM);
; #pragma unroll
;             for (int j = 0; j < 4; ++j) up[lane + 64 * j] = (u32x4){0u, 0u, 0u, 0u}; } return; }
;     ...
;         for (int j = 0; j < 8; ++j) { const f32x4 g = ((const f32x4*)gnext)[lane + 64 * j]; const f32x4 v = h[j] * g * rs2;
;             u32x2 w; w.x = pk2(v.x, v.y); w.y = pk2(v.z, v.w); up[lane + 64 * j] = w; }
	v_pk_mul_f32 v[172:173], v[68:69], v[178:179]
	s_nop 0
	v_pk_mul_f32 v[172:173], v[172:173], v[170:171] op_sel_hi:[1,0]
	v_pk_mul_f32 v[178:179], v[70:71], v[180:181]
	v_bfe_u32 v180, v172, 16, 1
	v_add3_u32 v172, v172, v180, s73
	v_bfe_u32 v180, v173, 16, 1
	v_pk_mul_f32 v[178:179], v[178:179], v[170:171] op_sel_hi:[1,0]
	v_lshrrev_b32_e32 v172, 16, v172
	v_add3_u32 v173, v173, v180, s73
	v_and_or_b32 v172, v173, s20, v172
	v_bfe_u32 v173, v178, 16, 1
	v_add3_u32 v173, v178, v173, s73
	v_bfe_u32 v178, v179, 16, 1
	v_lshrrev_b32_e32 v173, 16, v173
	v_add3_u32 v178, v179, v178, s73
	v_and_or_b32 v173, v178, s20, v173
	global_store_dwordx2 v[182:183], v[172:173], off offset:3840
	global_load_dwordx4 v[178:181], v[116:117], off offset:2048
	s_waitcnt vmcnt(0)
	v_pk_mul_f32 v[172:173], v[72:73], v[178:179]
	s_nop 0
	v_pk_mul_f32 v[172:173], v[172:173], v[170:171] op_sel_hi:[1,0]
	v_pk_mul_f32 v[178:179], v[74:75], v[180:181]
	v_bfe_u32 v180, v172, 16, 1
	v_add3_u32 v172, v172, v180, s73
	v_bfe_u32 v180, v173, 16, 1
	v_pk_mul_f32 v[178:179], v[178:179], v[170:171] op_sel_hi:[1,0]
	v_lshrrev_b32_e32 v172, 16, v172
	v_add3_u32 v173, v173, v180, s73
	v_and_or_b32 v180, v173, s20, v172
	v_bfe_u32 v172, v178, 16, 1
	v_add3_u32 v172, v178, v172, s73
	v_bfe_u32 v173, v179, 16, 1
	v_lshrrev_b32_e32 v172, 16, v172
	v_add3_u32 v173, v179, v173, s73
	v_and_or_b32 v181, v173, s20, v172
	v_add_co_u32_e32 v172, vcc, s31, v174
	s_nop 1
	v_addc_co_u32_e32 v173, vcc, 0, v175, vcc
	global_store_dwordx2 v[172:173], v[180:181], off offset:256
	global_load_dwordx4 v[178:181], v[116:117], off offset:3072
	s_waitcnt vmcnt(0)
	v_pk_mul_f32 v[174:175], v[76:77], v[178:179]
	s_nop 0
	v_pk_mul_f32 v[174:175], v[174:175], v[170:171] op_sel_hi:[1,0]
	v_pk_mul_f32 v[178:179], v[78:79], v[180:181]
	v_bfe_u32 v180, v174, 16, 1
	v_add3_u32 v174, v174, v180, s73
	v_bfe_u32 v180, v175, 16, 1
	v_pk_mul_f32 v[178:179], v[178:179], v[170:171] op_sel_hi:[1,0]
	v_lshrrev_b32_e32 v174, 16, v174
	v_add3_u32 v175, v175, v180, s73
	v_and_or_b32 v174, v175, s20, v174
	v_bfe_u32 v175, v178, 16, 1
	v_add3_u32 v175, v178, v175, s73
	v_bfe_u32 v178, v179, 16, 1
	v_lshrrev_b32_e32 v175, 16, v175
	v_add3_u32 v178, v179, v178, s73
	v_and_or_b32 v175, v178, s20, v175
	global_store_dwordx2 v[172:173], v[174:175], off offset:768
	global_load_dwordx4 v[178:181], v[118:119], off
	s_waitcnt vmcnt(0)
	v_pk_mul_f32 v[174:175], v[80:81], v[178:179]
	s_nop 0
	v_pk_mul_f32 v[174:175], v[174:175], v[170:171] op_sel_hi:[1,0]
	v_pk_mul_f32 v[178:179], v[82:83], v[180:181]
	v_bfe_u32 v180, v174, 16, 1
	v_add3_u32 v174, v174, v180, s73
	v_bfe_u32 v180, v175, 16, 1
	v_pk_mul_f32 v[178:179], v[178:179], v[170:171] op_sel_hi:[1,0]
	v_lshrrev_b32_e32 v174, 16, v174
	v_add3_u32 v175, v175, v180, s73
	v_and_or_b32 v174, v175, s20, v174
	v_bfe_u32 v175, v178, 16, 1
	v_add3_u32 v175, v178, v175, s73
	v_bfe_u32 v178, v179, 16, 1
	v_lshrrev_b32_e32 v175, 16, v175
	v_add3_u32 v178, v179, v178, s73
	v_and_or_b32 v175, v178, s20, v175
	global_store_dwordx2 v[172:173], v[174:175], off offset:1280
	global_load_dwordx4 v[178:181], v[120:121], off
	s_waitcnt vmcnt(0)
	v_pk_mul_f32 v[174:175], v[84:85], v[178:179]
	s_nop 0
	v_pk_mul_f32 v[174:175], v[174:175], v[170:171] op_sel_hi:[1,0]
	v_pk_mul_f32 v[178:179], v[86:87], v[180:181]
	v_bfe_u32 v180, v174, 16, 1
	v_add3_u32 v174, v174, v180, s73
	v_bfe_u32 v180, v175, 16, 1
	v_pk_mul_f32 v[178:179], v[178:179], v[170:171] op_sel_hi:[1,0]
	v_lshrrev_b32_e32 v174, 16, v174
	v_add3_u32 v175, v175, v180, s73
	v_and_or_b32 v174, v175, s20, v174
	v_bfe_u32 v175, v178, 16, 1
	v_add3_u32 v175, v178, v175, s73
	v_bfe_u32 v178, v179, 16, 1
	v_lshrrev_b32_e32 v175, 16, v175
	v_add3_u32 v178, v179, v178, s73
	v_and_or_b32 v175, v178, s20, v175
	global_store_dwordx2 v[172:173], v[174:175], off offset:1792
	global_load_dwordx4 v[178:181], v[122:123], off
	s_waitcnt vmcnt(0)
	v_pk_mul_f32 v[174:175], v[88:89], v[178:179]
	s_nop 0
	v_pk_mul_f32 v[174:175], v[174:175], v[170:171] op_sel_hi:[1,0]
	v_pk_mul_f32 v[178:179], v[90:91], v[180:181]
	v_bfe_u32 v180, v174, 16, 1
	v_add3_u32 v174, v174, v180, s73
	v_bfe_u32 v180, v175, 16, 1
	v_pk_mul_f32 v[178:179], v[178:179], v[170:171] op_sel_hi:[1,0]
	v_lshrrev_b32_e32 v174, 16, v174
	v_add3_u32 v175, v175, v180, s73
	v_and_or_b32 v174, v175, s20, v174
	v_bfe_u32 v175, v178, 16, 1
	v_add3_u32 v175, v178, v175, s73
	v_bfe_u32 v178, v179, 16, 1
	v_lshrrev_b32_e32 v175, 16, v175
	v_add3_u32 v178, v179, v178, s73
	v_and_or_b32 v175, v178, s20, v175
	global_store_dwordx2 v[172:173], v[174:175], off offset:2304
	global_load_dwordx4 v[178:181], v[124:125], off
	s_waitcnt vmcnt(0)
	v_pk_mul_f32 v[174:175], v[92:93], v[178:179]
	v_pk_mul_f32 v[178:179], v[94:95], v[180:181]
	v_pk_mul_f32 v[174:175], v[174:175], v[170:171] op_sel_hi:[1,0]
	v_pk_mul_f32 v[178:179], v[178:179], v[170:171] op_sel_hi:[1,0]
	v_bfe_u32 v170, v174, 16, 1
	v_add3_u32 v170, v174, v170, s73
	v_bfe_u32 v174, v175, 16, 1
	v_lshrrev_b32_e32 v170, 16, v170
	v_add3_u32 v174, v175, v174, s73
	v_and_or_b32 v174, v174, s20, v170
	v_bfe_u32 v170, v178, 16, 1
	v_add3_u32 v170, v178, v170, s73
	v_bfe_u32 v175, v179, 16, 1
	v_lshrrev_b32_e32 v170, 16, v170
	v_add3_u32 v175, v179, v175, s73
	v_and_or_b32 v175, v175, s20, v170
	global_store_dwordx2 v[172:173], v[174:175], off offset:2816
.LBB0_309:
	s_andn2_b64 vcc, exec, s[6:7]
	s_cbranch_vccnz .LBB0_311
	v_lshl_add_u64 v[64:65], s[56:57], 0, v[168:169]
	v_add_co_u32_e32 v66, vcc, 0xa2f1000, v64
	s_mov_b32 s6, s4
	s_nop 0
	v_addc_co_u32_e32 v67, vcc, 0, v65, vcc
	s_mov_b32 s7, s4
	s_mov_b32 s5, s4
	v_mov_b64_e32 v[70:71], s[6:7]
	v_add_co_u32_e32 v64, vcc, 0xa2f2000, v64
	v_mov_b64_e32 v[68:69], s[4:5]
	s_nop 0
	v_addc_co_u32_e32 v65, vcc, 0, v65, vcc
	global_store_dwordx4 v[66:67], v[68:71], off offset:3328
	global_store_dwordx4 v[64:65], v[68:71], off offset:256
	global_store_dwordx4 v[64:65], v[68:71], off offset:1280
	global_store_dwordx4 v[64:65], v[68:71], off offset:2304
	s_waitcnt vmcnt(0)
	v_mov_b32_e32 v95, v63
	v_mov_b32_e32 v94, v62
	v_mov_b32_e32 v93, v61
	v_mov_b32_e32 v92, v60
	v_mov_b32_e32 v91, v59
	v_mov_b32_e32 v90, v58
	v_mov_b32_e32 v89, v57
	v_mov_b32_e32 v88, v56
	v_mov_b32_e32 v87, v55
	v_mov_b32_e32 v86, v54
	v_mov_b32_e32 v85, v53
	v_mov_b32_e32 v84, v52
	v_mov_b32_e32 v83, v51
	v_mov_b32_e32 v82, v50
	v_mov_b32_e32 v81, v49
	v_mov_b32_e32 v80, v48
	v_mov_b32_e32 v79, v47
	v_mov_b32_e32 v78, v46
	v_mov_b32_e32 v77, v45
	v_mov_b32_e32 v76, v44
	v_mov_b32_e32 v75, v43
	v_mov_b32_e32 v74, v42
	v_mov_b32_e32 v73, v41
	v_mov_b32_e32 v72, v40
	v_mov_b32_e32 v71, v39
	v_mov_b32_e32 v70, v38
	v_mov_b32_e32 v69, v37
	v_mov_b32_e32 v68, v36
	v_mov_b32_e32 v67, v3
	v_mov_b32_e32 v66, v2
	v_mov_b32_e32 v65, v1
	v_mov_b32_e32 v64, v0

; template <int MODE>
; __device__ __forceinline__ void row_finish(const Params& p, int r, int lane, const float* gpost, const float* gnext, bf16_t* U, float coef, f32x4 (&h)[8], const u32x2 (&dw)[8]) {
;     ...
;     if (MODE >= 1) {
;         f32x4 d[8]; float ss = 0.f;
; #pragma unroll
;         for (int j = 0; j < 8; ++j) { const u32x2 w = dw[j]; d[j] = (f32x4){bflo(w.x), bfhi(w.x), bflo(w.y), bfhi(w.y)};
;             ss += (d[j].x * d[j].x + d[j].y * d[j].y) + (d[j].z * d[j].z + d[j].w * d[j].w); }
;         ss = wave_sum(ss);
;         const float rs = rsqrtf(ss * (1.f / DM) + EPS) * coef;
;         f32x4* hd = (f32x4*)hrow(p, r);
; #pragma unroll
;         for (int j = 0; j < 8; ++j) { const f32x4 g = ((const f32x4*)gpost)[lane + 64 * j]; h[j] = h[j] + d[j] * g * rs; __builtin_nontemporal_store(h[j], &hd[lane + 64 * j]); }
.LBB0_312:
	s_andn2_b64 vcc, exec, s[28:29]
	s_mov_b64 s[6:7], -1
	s_cbranch_vccnz .LBB0_314
	s_waitcnt vmcnt(0) lgkmcnt(0)
	v_and_b32_e32 v71, 0xffff0000, v134
	v_and_b32_e32 v70, 0xffff0000, v136
	v_and_b32_e32 v175, 0xffff0000, v135
	v_and_b32_e32 v174, 0xffff0000, v137
	v_lshlrev_b32_e32 v69, 16, v134
	v_lshlrev_b32_e32 v68, 16, v136
	v_lshlrev_b32_e32 v173, 16, v135
	v_lshlrev_b32_e32 v172, 16, v137
	v_pk_mul_f32 v[64:65], v[70:71], v[70:71]
	v_pk_mul_f32 v[66:67], v[174:175], v[174:175]
	v_pk_fma_f32 v[64:65], v[68:69], v[68:69], v[64:65]
	v_pk_fma_f32 v[66:67], v[172:173], v[172:173], v[66:67]
	v_and_b32_e32 v75, 0xffff0000, v139
	v_pk_add_f32 v[64:65], v[64:65], v[66:67]
	v_and_b32_e32 v74, 0xffff0000, v138
	v_pk_add_f32 v[64:65], v[64:65], v[64:65] op_sel_hi:[0,1]
	v_lshlrev_b32_e32 v73, 16, v139
	v_lshlrev_b32_e32 v72, 16, v138
	v_pk_mul_f32 v[66:67], v[74:75], v[74:75]
	v_lshlrev_b32_e32 v76, 16, v140
	v_and_b32_e32 v77, 0xffff0000, v140
	v_lshlrev_b32_e32 v78, 16, v141
	v_lshlrev_b32_e32 v80, 16, v142
	v_pk_fma_f32 v[66:67], v[72:73], v[72:73], v[66:67]
	v_mul_f32_e32 v81, v76, v76
	v_mul_f32_e32 v85, v77, v77
	v_and_b32_e32 v79, 0xffff0000, v141
	v_mul_f32_e32 v64, v78, v78
	v_mov_b32_e32 v84, v80
	v_pk_add_f32 v[66:67], v[66:67], v[66:67] op_sel_hi:[0,1]
	v_pk_fma_f32 v[86:87], v[78:79], v[78:79], v[64:65] op_sel_hi:[1,1,0]
	v_and_b32_e32 v179, 0xffff0000, v142
	v_lshlrev_b32_e32 v82, 16, v143
	v_and_b32_e32 v83, 0xffff0000, v143
	v_pk_add_f32 v[84:85], v[80:81], v[84:85]
	v_mul_f32_e32 v86, v179, v179
	v_mul_f32_e32 v66, v82, v82
	v_mul_f32_e32 v64, v83, v83
	v_mul_f32_e32 v88, v80, v80
	v_mov_b32_e32 v89, v85
	v_pk_add_f32 v[84:85], v[88:89], v[86:87]
	v_pk_add_f32 v[64:65], v[66:67], v[64:65]
	v_and_b32_e32 v87, 0xffff0000, v145
	v_pk_add_f32 v[64:65], v[84:85], v[64:65]
	v_and_b32_e32 v86, 0xffff0000, v144
	v_pk_add_f32 v[64:65], v[64:65], v[64:65] op_sel_hi:[0,1]
	v_lshlrev_b32_e32 v85, 16, v145
	v_lshlrev_b32_e32 v84, 16, v144
	v_pk_mul_f32 v[66:67], v[86:87], v[86:87]
	v_lshlrev_b32_e32 v88, 16, v146
	v_and_b32_e32 v89, 0xffff0000, v146
	v_lshlrev_b32_e32 v90, 16, v147
	v_lshlrev_b32_e32 v92, 16, v148
	v_pk_fma_f32 v[66:67], v[84:85], v[84:85], v[66:67]
	v_mul_f32_e32 v93, v88, v88
	v_mul_f32_e32 v181, v89, v89
	v_and_b32_e32 v91, 0xffff0000, v147
	v_mul_f32_e32 v64, v90, v90
	v_mov_b32_e32 v180, v92
	v_pk_add_f32 v[66:67], v[66:67], v[66:67] op_sel_hi:[0,1]
	v_pk_fma_f32 v[182:183], v[90:91], v[90:91], v[64:65] op_sel_hi:[1,1,0]
	v_and_b32_e32 v178, 0xffff0000, v148
	v_lshlrev_b32_e32 v94, 16, v149
	v_and_b32_e32 v95, 0xffff0000, v149
	v_pk_add_f32 v[180:181], v[92:93], v[180:181]
	v_mul_f32_e32 v182, v178, v178
	v_mul_f32_e32 v66, v94, v94
	v_mul_f32_e32 v64, v95, v95
	v_mul_f32_e32 v184, v92, v92
	v_mov_b32_e32 v185, v181
	v_pk_add_f32 v[180:181], v[184:185], v[182:183]
	v_pk_add_f32 v[64:65], v[66:67], v[64:65]
	s_add_u32 s5, s69, s0
	v_pk_add_f32 v[64:65], v[180:181], v[64:65]
	s_addc_u32 s6, 0, s1
	v_add_f32_e32 v64, v64, v65
	ds_bpermute_b32 v65, v97, v64
	s_add_u32 s5, s5, 1
	s_addc_u32 s6, s6, 0
	s_add_u32 s7, s76, s0
	s_addc_u32 s10, s77, s1
	s_waitcnt lgkmcnt(0)
	v_add_f32_e32 v64, v64, v65
	ds_bpermute_b32 v65, v99, v64
	s_add_u32 s11, s7, 1
	s_addc_u32 s7, s10, 0
	s_cmp_lt_i32 s59, 0x8000
	s_cselect_b32 s7, s7, s6
	s_waitcnt lgkmcnt(0)
	v_add_f32_e32 v64, v64, v65
	ds_bpermute_b32 v65, v101, v64
	s_cselect_b32 s6, s11, s5
	v_mov_b32_e32 v180, v69
	v_mov_b32_e32 v181, v71
	s_cselect_b32 s5, s15, s71
	s_waitcnt lgkmcnt(0)
	v_add_f32_e32 v64, v64, v65
	ds_bpermute_b32 v65, v103, v64
	s_cselect_b32 s10, s14, s70
	s_lshl_b64 s[6:7], s[6:7], 13
	s_add_u32 s6, s10, s6
	s_addc_u32 s7, s5, s7
	s_waitcnt lgkmcnt(0)
	v_add_f32_e32 v64, v64, v65
	ds_bpermute_b32 v65, v105, v64
	v_lshlrev_b32_e32 v81, 4, v96
	v_mov_b32_e32 v69, v70
	v_lshlrev_b32_e32 v93, 4, v98
	s_waitcnt lgkmcnt(0)
	v_add_f32_e32 v64, v64, v65
	ds_bpermute_b32 v65, v127, v64
	s_waitcnt lgkmcnt(0)
	v_add_f32_e32 v64, v64, v65
	v_fmamk_f32 v64, v64, 0x3a000000, v176
	v_cmp_gt_f32_e32 vcc, s75, v64
	v_mul_f32_e32 v65, 0x4b800000, v64
	s_nop 0
	v_cndmask_b32_e32 v64, v64, v65, vcc
	v_rsq_f32_e32 v64, v64
	s_nop 0
	v_mul_f32_e32 v65, 0x45800000, v64
	v_cndmask_b32_e32 v64, v64, v65, vcc
	v_mul_f32_e32 v170, 0.5, v64
	global_load_dwordx4 v[64:67], v[106:107], off
	s_waitcnt vmcnt(0)
	v_pk_mul_f32 v[64:65], v[180:181], v[64:65]
	v_mov_b32_e32 v180, v173
	v_mov_b32_e32 v181, v175
	v_pk_mul_f32 v[66:67], v[180:181], v[66:67]
	v_pk_fma_f32 v[64:65], v[64:65], v[170:171], v[4:5] op_sel_hi:[1,0,1]
	v_pk_fma_f32 v[66:67], v[66:67], v[170:171], v[6:7] op_sel_hi:[1,0,1]
	global_store_dwordx4 v81, v[64:67], s[6:7] nt
	global_load_dwordx4 v[180:183], v[106:107], off offset:1024
	v_mov_b32_e32 v173, v174
	s_waitcnt vmcnt(0)
	v_pk_mul_f32 v[172:173], v[172:173], v[182:183]
	v_pk_mul_f32 v[68:69], v[68:69], v[180:181]
	v_pk_fma_f32 v[70:71], v[172:173], v[170:171], v[10:11] op_sel_hi:[1,0,1]
	v_pk_fma_f32 v[68:69], v[68:69], v[170:171], v[8:9] op_sel_hi:[1,0,1]
	global_store_dwordx4 v81, v[68:71], s[6:7] offset:1024 nt
	global_load_dwordx4 v[172:175], v[106:107], off offset:2048
	v_mov_b32_e32 v180, v73
	v_mov_b32_e32 v181, v75
	v_mov_b32_e32 v73, v74
	s_waitcnt vmcnt(0)
	v_pk_mul_f32 v[174:175], v[174:175], v[180:181]
	v_pk_mul_f32 v[72:73], v[172:173], v[72:73]
	v_pk_fma_f32 v[74:75], v[174:175], v[170:171], v[14:15] op_sel_hi:[1,0,1]
	v_pk_fma_f32 v[72:73], v[72:73], v[170:171], v[12:13] op_sel_hi:[1,0,1]
	global_store_dwordx4 v81, v[72:75], s[6:7] offset:2048 nt
	global_load_dwordx4 v[172:175], v[106:107], off offset:3072
	v_mov_b32_e32 v180, v85
	v_mov_b32_e32 v181, v87
	v_mov_b32_e32 v85, v86
	s_waitcnt vmcnt(0)
; __device__ __forceinline__ unsigned pk2(float lo, float hi) { return f2bf(lo) | (f2bf(hi) << 16); }
; template <int MODE>
; __device__ __forceinline__ void row_finish(const Params& p, int r, int lane, const float* gpost, const float* gnext, bf16_t* U, float coef, f32x4 (&h)[8], const u32x2 (&dw)[8]) {
;     ...
;         for (int j = 0; j < 8; ++j) { const f32x4 g = ((const f32x4*)gpost)[lane + 64 * j]; h[j] = h[j] + d[j] * g * rs; __builtin_nontemporal_store(h[j], &hd[lane + 64 * j]); }
;     }
;     if (MODE != 3) {
;         float s2 = 0.f;
; #pragma unroll
;         for (int j = 0; j < 8; ++j) s2 += (h[j].x * h[j].x + h[j].y * h[j].y) + (h[j].z * h[j].z + h[j].w * h[j].w);
;         s2 = wave_sum(s2);
;         const float rs2 = rsqrtf(s2 * (1.f / DM) + EPS);
;         u32x2* up = (u32x2*)(U + (size_t)r * DM);
; #pragma unroll
;         for (int j = 0; j < 8; ++j) { const f32x4 g = ((const f32x4*)gnext)[lane + 64 * j]; const f32x4 v = h[j] * g * rs2;
;             u32x2 w; w.x = pk2(v.x, v.y); w.y = pk2(v.z, v.w); up[lane + 64 * j] = w; }
	v_pk_mul_f32 v[78:79], v[78:79], v[174:175]
	v_pk_mul_f32 v[76:77], v[76:77], v[172:173]
	v_pk_fma_f32 v[78:79], v[78:79], v[170:171], v[18:19] op_sel_hi:[1,0,1]
	v_pk_fma_f32 v[76:77], v[76:77], v[170:171], v[16:17] op_sel_hi:[1,0,1]
	global_store_dwordx4 v81, v[76:79], s[6:7] offset:3072 nt
	global_load_dwordx4 v[172:175], v[108:109], off
	v_mov_b32_e32 v81, v179
	v_mov_b32_e32 v179, v71
	s_waitcnt vmcnt(0)
	v_pk_mul_f32 v[80:81], v[80:81], v[172:173]
	v_pk_mul_f32 v[82:83], v[82:83], v[174:175]
	v_pk_fma_f32 v[80:81], v[80:81], v[170:171], v[20:21] op_sel_hi:[1,0,1]
	v_pk_fma_f32 v[82:83], v[82:83], v[170:171], v[22:23] op_sel_hi:[1,0,1]
	global_store_dwordx4 v93, v[80:83], s[6:7] nt
	global_load_dwordx4 v[172:175], v[110:111], off
	v_lshlrev_b32_e32 v93, 4, v100
	s_waitcnt vmcnt(0)
	v_pk_mul_f32 v[174:175], v[174:175], v[180:181]
	v_pk_mul_f32 v[84:85], v[172:173], v[84:85]
	v_pk_fma_f32 v[86:87], v[170:171], v[174:175], v[26:27] op_sel_hi:[0,1,1]
	v_pk_fma_f32 v[84:85], v[170:171], v[84:85], v[24:25] op_sel_hi:[0,1,1]
	global_store_dwordx4 v93, v[84:87], s[6:7] nt
	global_load_dwordx4 v[172:175], v[112:113], off
	v_lshlrev_b32_e32 v93, 4, v102
	s_waitcnt vmcnt(0)
	v_pk_mul_f32 v[90:91], v[90:91], v[174:175]
	v_pk_mul_f32 v[88:89], v[88:89], v[172:173]
	v_pk_fma_f32 v[90:91], v[170:171], v[90:91], v[30:31] op_sel_hi:[0,1,1]
	v_pk_fma_f32 v[88:89], v[170:171], v[88:89], v[28:29] op_sel_hi:[0,1,1]
	global_store_dwordx4 v93, v[88:91], s[6:7] nt
	global_load_dwordx4 v[172:175], v[114:115], off
	v_mov_b32_e32 v93, v178
	v_mov_b32_e32 v178, v67
	v_pk_mul_f32 v[178:179], v[178:179], v[178:179]
	s_waitcnt vmcnt(0)
	v_pk_mul_f32 v[94:95], v[94:95], v[174:175]
	v_mov_b32_e32 v174, v65
	v_mov_b32_e32 v175, v69
	v_pk_mul_f32 v[92:93], v[92:93], v[172:173]
	v_mov_b32_e32 v172, v64
	v_mov_b32_e32 v173, v68
	v_pk_mul_f32 v[174:175], v[174:175], v[174:175]
	v_pk_fma_f32 v[94:95], v[170:171], v[94:95], v[34:35] op_sel_hi:[0,1,1]
	v_pk_fma_f32 v[172:173], v[172:173], v[172:173], v[174:175]
	v_mov_b32_e32 v174, v66
	v_mov_b32_e32 v175, v70
	v_pk_fma_f32 v[174:175], v[174:175], v[174:175], v[178:179]
	v_pk_fma_f32 v[92:93], v[170:171], v[92:93], v[32:33] op_sel_hi:[0,1,1]
	v_lshlrev_b32_e32 v170, 4, v104
	v_pk_add_f32 v[172:173], v[172:173], v[174:175]
	v_pk_mul_f32 v[174:175], v[72:73], v[72:73]
	v_pk_mul_f32 v[178:179], v[74:75], v[74:75]
	global_store_dwordx4 v170, v[92:95], s[6:7] nt
	v_pk_mov_b32 v[180:181], v[174:175], v[178:179] op_sel:[1,0]
	v_mov_b32_e32 v175, v179
	v_mul_f32_e32 v170, v76, v76
	v_pk_add_f32 v[174:175], v[180:181], v[174:175]
	v_pk_fma_f32 v[178:179], v[76:77], v[76:77], v[170:171] op_sel_hi:[1,1,0]
	v_mul_f32_e32 v170, v78, v78
	v_pk_add_f32 v[172:173], v[172:173], v[172:173] op_sel_hi:[0,1]
	v_pk_add_f32 v[174:175], v[174:175], v[174:175] op_sel_hi:[0,1]
	v_pk_fma_f32 v[180:181], v[78:79], v[78:79], v[170:171] op_sel_hi:[1,1,0]
	v_mul_f32_e32 v178, v80, v80
	v_mul_f32_e32 v180, v81, v81
	v_mul_f32_e32 v174, v82, v82
	v_mul_f32_e32 v172, v83, v83
	v_pk_add_f32 v[178:179], v[178:179], v[180:181]
	v_pk_add_f32 v[172:173], v[174:175], v[172:173]
	v_pk_mul_f32 v[174:175], v[84:85], v[84:85]
	v_pk_add_f32 v[172:173], v[178:179], v[172:173]
	v_pk_mul_f32 v[178:179], v[86:87], v[86:87]
	v_mul_f32_e32 v170, v88, v88
	v_pk_mov_b32 v[180:181], v[174:175], v[178:179] op_sel:[1,0]
	v_mov_b32_e32 v175, v179
	v_pk_add_f32 v[174:175], v[180:181], v[174:175]
	v_pk_fma_f32 v[178:179], v[88:89], v[88:89], v[170:171] op_sel_hi:[1,1,0]
	v_mul_f32_e32 v170, v90, v90
	v_pk_add_f32 v[172:173], v[172:173], v[172:173] op_sel_hi:[0,1]
	v_pk_add_f32 v[174:175], v[174:175], v[174:175] op_sel_hi:[0,1]
	v_pk_fma_f32 v[180:181], v[90:91], v[90:91], v[170:171] op_sel_hi:[1,1,0]
	v_mul_f32_e32 v178, v92, v92
	v_mul_f32_e32 v180, v93, v93
	v_mul_f32_e32 v174, v94, v94
	v_mul_f32_e32 v172, v95, v95
	v_pk_add_f32 v[178:179], v[178:179], v[180:181]
	v_pk_add_f32 v[172:173], v[174:175], v[172:173]
	s_mov_b64 s[6:7], 0
	v_pk_add_f32 v[172:173], v[178:179], v[172:173]
	s_nop 0
	v_add_f32_e32 v170, v172, v173
	ds_bpermute_b32 v172, v97, v170
	s_waitcnt lgkmcnt(0)
	v_add_f32_e32 v170, v170, v172
	ds_bpermute_b32 v172, v99, v170
	s_waitcnt lgkmcnt(0)
	v_add_f32_e32 v170, v170, v172
	ds_bpermute_b32 v172, v101, v170
	s_waitcnt lgkmcnt(0)
	v_add_f32_e32 v170, v170, v172
	ds_bpermute_b32 v172, v103, v170
	s_waitcnt lgkmcnt(0)
	v_add_f32_e32 v170, v170, v172
	ds_bpermute_b32 v172, v105, v170
	s_waitcnt lgkmcnt(0)
	v_add_f32_e32 v170, v170, v172
	ds_bpermute_b32 v172, v127, v170
	s_waitcnt lgkmcnt(0)
	v_add_f32_e32 v170, v170, v172
	v_fmamk_f32 v170, v170, 0x3a000000, v176
	v_cmp_gt_f32_e32 vcc, s75, v170
	v_mul_f32_e32 v172, 0x4b800000, v170
	s_nop 0
	v_cndmask_b32_e32 v170, v170, v172, vcc
	v_rsq_f32_e32 v170, v170
	s_nop 0
	v_mul_f32_e32 v172, 0x45800000, v170
	v_cndmask_b32_e32 v170, v170, v172, vcc
	global_load_dwordx4 v[172:175], v[116:117], off
	s_waitcnt vmcnt(0)
	v_pk_mul_f32 v[172:173], v[64:65], v[172:173]
	s_nop 0
	v_pk_mul_f32 v[172:173], v[172:173], v[170:171] op_sel_hi:[1,0]
	v_pk_mul_f32 v[174:175], v[66:67], v[174:175]
	v_bfe_u32 v178, v172, 16, 1
	v_add3_u32 v172, v172, v178, s73
	v_bfe_u32 v178, v173, 16, 1
	v_pk_mul_f32 v[174:175], v[174:175], v[170:171] op_sel_hi:[1,0]
	v_lshrrev_b32_e32 v172, 16, v172
	v_add3_u32 v173, v173, v178, s73
	v_and_or_b32 v172, v173, s20, v172
	v_bfe_u32 v173, v174, 16, 1
	v_add3_u32 v173, v174, v173, s73
	v_bfe_u32 v174, v175, 16, 1
	v_lshrrev_b32_e32 v173, 16, v173
	v_add3_u32 v174, v175, v174, s73
	v_and_or_b32 v173, v174, s20, v173
	v_lshl_add_u64 v[174:175], s[56:57], 0, v[166:167]
	v_add_co_u32_e32 v182, vcc, s31, v174
	s_nop 1
	v_addc_co_u32_e32 v183, vcc, 0, v175, vcc
	global_store_dwordx2 v[182:183], v[172:173], off offset:3328
	global_load_dwordx4 v[178:181], v[116:117], off offset:1024
	s_waitcnt vmcnt(0)
; __device__ __forceinline__ unsigned pk2(float lo, float hi) { return f2bf(lo) | (f2bf(hi) << 16); }
; template <int MODE>
; __device__ __forceinline__ void row_finish(const Params& p, int r, int lane, const float* gpost, const float* gnext, bf16_t* U, float coef, f32x4 (&h)[8], const u32x2 (&dw)[8]) {
;     ...
;     if (r >= ROWS) { if (MODE != 3) { u32x4* up = (u32x4*)(U + (size_t)r * DM);
; #pragma unroll
;             for (int j = 0; j < 4; ++j) up[lane + 64 * j] = (u32x4){0u, 0u, 0u, 0u}; } return; }
;     ...
;         for (int j = 0; j < 8; ++j) { const f32x4 g = ((const f32x4*)gnext)[lane + 64 * j]; const f32x4 v = h[j] * g * rs2;
;             u32x2 w; w.x = pk2(v.x, v.y); w.y = pk2(v.z, v.w); up[lane + 64 * j] = w; }
;     ...
;         for (int k = 0; k < 8; k += 2) {
;             f32x4 ha[8], hb[8]; u32x2 da[8], db[8];
;             row_load<MODE>(p, r0 + k, lane, Dsrc, ha, da);
;             row_load<MODE>(p, r0 + k + 1, lane, Dsrc, hb, db);
;             row_finish<MODE>(p, r0 + k, lane, gpost, gnext, U, coef, ha, da);
;             row_finish<MODE>(p, r0 + k + 1, lane, gpost, gnext, U, coef, hb, db);
;         }
	v_pk_mul_f32 v[172:173], v[68:69], v[178:179]
	s_nop 0
	v_pk_mul_f32 v[172:173], v[172:173], v[170:171] op_sel_hi:[1,0]
	v_pk_mul_f32 v[178:179], v[70:71], v[180:181]
	v_bfe_u32 v180, v172, 16, 1
	v_add3_u32 v172, v172, v180, s73
	v_bfe_u32 v180, v173, 16, 1
	v_pk_mul_f32 v[178:179], v[178:179], v[170:171] op_sel_hi:[1,0]
	v_lshrrev_b32_e32 v172, 16, v172
	v_add3_u32 v173, v173, v180, s73
	v_and_or_b32 v172, v173, s20, v172
	v_bfe_u32 v173, v178, 16, 1
	v_add3_u32 v173, v178, v173, s73
	v_bfe_u32 v178, v179, 16, 1
	v_lshrrev_b32_e32 v173, 16, v173
	v_add3_u32 v178, v179, v178, s73
	v_and_or_b32 v173, v178, s20, v173
	global_store_dwordx2 v[182:183], v[172:173], off offset:3840
	global_load_dwordx4 v[178:181], v[116:117], off offset:2048
	s_waitcnt vmcnt(0)
	v_pk_mul_f32 v[172:173], v[72:73], v[178:179]
	s_nop 0
	v_pk_mul_f32 v[172:173], v[172:173], v[170:171] op_sel_hi:[1,0]
	v_pk_mul_f32 v[178:179], v[74:75], v[180:181]
	v_bfe_u32 v180, v172, 16, 1
	v_add3_u32 v172, v172, v180, s73
	v_bfe_u32 v180, v173, 16, 1
	v_pk_mul_f32 v[178:179], v[178:179], v[170:171] op_sel_hi:[1,0]
	v_lshrrev_b32_e32 v172, 16, v172
	v_add3_u32 v173, v173, v180, s73
	v_and_or_b32 v180, v173, s20, v172
	v_bfe_u32 v172, v178, 16, 1
	v_add3_u32 v172, v178, v172, s73
	v_bfe_u32 v173, v179, 16, 1
	v_lshrrev_b32_e32 v172, 16, v172
	v_add3_u32 v173, v179, v173, s73
	v_and_or_b32 v181, v173, s20, v172
	v_add_co_u32_e32 v172, vcc, s74, v174
	s_nop 1
	v_addc_co_u32_e32 v173, vcc, 0, v175, vcc
	global_store_dwordx2 v[172:173], v[180:181], off offset:256
	global_load_dwordx4 v[178:181], v[116:117], off offset:3072
	s_waitcnt vmcnt(0)
	v_pk_mul_f32 v[174:175], v[76:77], v[178:179]
	s_nop 0
	v_pk_mul_f32 v[174:175], v[174:175], v[170:171] op_sel_hi:[1,0]
	v_pk_mul_f32 v[178:179], v[78:79], v[180:181]
	v_bfe_u32 v180, v174, 16, 1
	v_add3_u32 v174, v174, v180, s73
	v_bfe_u32 v180, v175, 16, 1
	v_pk_mul_f32 v[178:179], v[178:179], v[170:171] op_sel_hi:[1,0]
	v_lshrrev_b32_e32 v174, 16, v174
	v_add3_u32 v175, v175, v180, s73
	v_and_or_b32 v174, v175, s20, v174
	v_bfe_u32 v175, v178, 16, 1
	v_add3_u32 v175, v178, v175, s73
	v_bfe_u32 v178, v179, 16, 1
	v_lshrrev_b32_e32 v175, 16, v175
	v_add3_u32 v178, v179, v178, s73
	v_and_or_b32 v175, v178, s20, v175
	global_store_dwordx2 v[172:173], v[174:175], off offset:768
	global_load_dwordx4 v[178:181], v[118:119], off
	s_waitcnt vmcnt(0)
	v_pk_mul_f32 v[174:175], v[80:81], v[178:179]
	s_nop 0
	v_pk_mul_f32 v[174:175], v[174:175], v[170:171] op_sel_hi:[1,0]
	v_pk_mul_f32 v[178:179], v[82:83], v[180:181]
	v_bfe_u32 v180, v174, 16, 1
	v_add3_u32 v174, v174, v180, s73
	v_bfe_u32 v180, v175, 16, 1
	v_pk_mul_f32 v[178:179], v[178:179], v[170:171] op_sel_hi:[1,0]
	v_lshrrev_b32_e32 v174, 16, v174
	v_add3_u32 v175, v175, v180, s73
	v_and_or_b32 v174, v175, s20, v174
	v_bfe_u32 v175, v178, 16, 1
	v_add3_u32 v175, v178, v175, s73
	v_bfe_u32 v178, v179, 16, 1
	v_lshrrev_b32_e32 v175, 16, v175
	v_add3_u32 v178, v179, v178, s73
	v_and_or_b32 v175, v178, s20, v175
	global_store_dwordx2 v[172:173], v[174:175], off offset:1280
	global_load_dwordx4 v[178:181], v[120:121], off
	s_waitcnt vmcnt(0)
	v_pk_mul_f32 v[174:175], v[84:85], v[178:179]
	s_nop 0
	v_pk_mul_f32 v[174:175], v[174:175], v[170:171] op_sel_hi:[1,0]
	v_pk_mul_f32 v[178:179], v[86:87], v[180:181]
	v_bfe_u32 v180, v174, 16, 1
	v_add3_u32 v174, v174, v180, s73
	v_bfe_u32 v180, v175, 16, 1
	v_pk_mul_f32 v[178:179], v[178:179], v[170:171] op_sel_hi:[1,0]
	v_lshrrev_b32_e32 v174, 16, v174
	v_add3_u32 v175, v175, v180, s73
	v_and_or_b32 v174, v175, s20, v174
	v_bfe_u32 v175, v178, 16, 1
	v_add3_u32 v175, v178, v175, s73
	v_bfe_u32 v178, v179, 16, 1
	v_lshrrev_b32_e32 v175, 16, v175
	v_add3_u32 v178, v179, v178, s73
	v_and_or_b32 v175, v178, s20, v175
	global_store_dwordx2 v[172:173], v[174:175], off offset:1792
	global_load_dwordx4 v[178:181], v[122:123], off
	s_waitcnt vmcnt(0)
	v_pk_mul_f32 v[174:175], v[88:89], v[178:179]
	s_nop 0
	v_pk_mul_f32 v[174:175], v[174:175], v[170:171] op_sel_hi:[1,0]
	v_pk_mul_f32 v[178:179], v[90:91], v[180:181]
	v_bfe_u32 v180, v174, 16, 1
	v_add3_u32 v174, v174, v180, s73
	v_bfe_u32 v180, v175, 16, 1
	v_pk_mul_f32 v[178:179], v[178:179], v[170:171] op_sel_hi:[1,0]
	v_lshrrev_b32_e32 v174, 16, v174
	v_add3_u32 v175, v175, v180, s73
	v_and_or_b32 v174, v175, s20, v174
	v_bfe_u32 v175, v178, 16, 1
	v_add3_u32 v175, v178, v175, s73
	v_bfe_u32 v178, v179, 16, 1
	v_lshrrev_b32_e32 v175, 16, v175
	v_add3_u32 v178, v179, v178, s73
	v_and_or_b32 v175, v178, s20, v175
	global_store_dwordx2 v[172:173], v[174:175], off offset:2304
	global_load_dwordx4 v[178:181], v[124:125], off
	s_waitcnt vmcnt(0)
	v_pk_mul_f32 v[174:175], v[92:93], v[178:179]
	v_pk_mul_f32 v[178:179], v[94:95], v[180:181]
	v_pk_mul_f32 v[174:175], v[174:175], v[170:171] op_sel_hi:[1,0]
	v_pk_mul_f32 v[178:179], v[178:179], v[170:171] op_sel_hi:[1,0]
	v_bfe_u32 v170, v174, 16, 1
	v_add3_u32 v170, v174, v170, s73
	v_bfe_u32 v174, v175, 16, 1
	v_lshrrev_b32_e32 v170, 16, v170
	v_add3_u32 v174, v175, v174, s73
	v_and_or_b32 v174, v174, s20, v170
	v_bfe_u32 v170, v178, 16, 1
	v_add3_u32 v170, v178, v170, s73
	v_bfe_u32 v175, v179, 16, 1
	v_lshrrev_b32_e32 v170, 16, v170
	v_add3_u32 v175, v179, v175, s73
	v_and_or_b32 v175, v175, s20, v170
	global_store_dwordx2 v[172:173], v[174:175], off offset:2816
.LBB0_314:
	s_andn2_b64 vcc, exec, s[6:7]
	s_cbranch_vccnz .LBB0_285
	v_lshl_add_u64 v[64:65], s[56:57], 0, v[168:169]
	v_add_co_u32_e32 v66, vcc, 0xa2f2000, v64
	s_mov_b32 s6, s4
	s_nop 0
	v_addc_co_u32_e32 v67, vcc, 0, v65, vcc
	s_mov_b32 s7, s4
	s_mov_b32 s5, s4
	v_mov_b64_e32 v[70:71], s[6:7]
	v_add_co_u32_e32 v64, vcc, 0xa2f3000, v64
	v_mov_b64_e32 v[68:69], s[4:5]
	s_nop 0
	v_addc_co_u32_e32 v65, vcc, 0, v65, vcc
	global_store_dwordx4 v[66:67], v[68:71], off offset:3328
	global_store_dwordx4 v[64:65], v[68:71], off offset:256
	global_store_dwordx4 v[64:65], v[68:71], off offset:1280
	global_store_dwordx4 v[64:65], v[68:71], off offset:2304
	s_waitcnt vmcnt(0)
	v_mov_b64_e32 v[66:67], v[6:7]
	v_mov_b64_e32 v[74:75], v[14:15]
	v_mov_b64_e32 v[70:71], v[10:11]
	v_mov_b64_e32 v[78:79], v[18:19]
	v_mov_b64_e32 v[82:83], v[22:23]
	v_mov_b64_e32 v[86:87], v[26:27]
	v_mov_b64_e32 v[90:91], v[30:31]
	v_mov_b64_e32 v[94:95], v[34:35]
	v_mov_b64_e32 v[64:65], v[4:5]
	v_mov_b64_e32 v[68:69], v[8:9]
	v_mov_b64_e32 v[72:73], v[12:13]
	v_mov_b64_e32 v[76:77], v[16:17]
	v_mov_b64_e32 v[80:81], v[20:21]
	v_mov_b64_e32 v[84:85], v[24:25]
	v_mov_b64_e32 v[88:89], v[28:29]
	v_mov_b64_e32 v[92:93], v[32:33]
	s_branch .LBB0_285

; __device__ __forceinline__ unsigned cvt_pk_bf16(float lo, float hi) { unsigned r; asm volatile("v_cvt_pk_bf16_f32 %0, %1, %2" : "=v"(r) : "v"(lo), "v"(hi)); return r; }
;     __device__ __forceinline__ void operator()(const f32x4 (&acc)[2][2][4][2], const Unit& u, int wr, int wc, int fr, int fq) const {
;         const int row0 = u.pm * BM + wr * 64 + fr, col0 = u.pn * BM + wc * 32 + 8 * fq;
; #pragma unroll
;         for (int ai = 0; ai < 2; ++ai)
; #pragma unroll
;             for (int m = 0; m < 4; ++m) { bf16_t* rowp = O + (size_t)(row0 + ai * HALF + m * 16) * ldc + col0;
; #pragma unroll
;                 for (int bj = 0; bj < 2; ++bj) { const f32x4 v0 = acc[ai][bj][m][0], v1 = acc[ai][bj][m][1];
;                     u32x4 w; w.x = cvt_pk_bf16(v0[0], v0[1]); w.y = cvt_pk_bf16(v0[2], v0[3]); w.z = cvt_pk_bf16(v1[0], v1[1]); w.w = cvt_pk_bf16(v1[2], v1[3]);
;                     *(u32x4*)(rowp + bj * HALF) = w; } }
.LBB0_385:
	v_lshl_add_u32 v150, s63, 8, v143
	v_lshl_or_b32 v140, s64, 8, v145
	v_ashrrev_i32_e32 v151, 31, v150
	v_ashrrev_i32_e32 v141, 31, v140
	v_lshlrev_b64 v[152:153], 12, v[150:151]
	v_lshl_add_u64 v[152:153], s[8:9], 0, v[152:153]
	v_lshlrev_b64 v[154:155], 1, v[140:141]
	v_lshl_add_u64 v[140:141], v[152:153], 0, v[154:155]
	v_cvt_pk_bf16_f32 v124, v124, v125
	v_cvt_pk_bf16_f32 v125, v126, v127
	v_cvt_pk_bf16_f32 v126, v120, v121
	v_cvt_pk_bf16_f32 v127, v122, v123
	global_store_dwordx4 v[140:141], v[124:127], off
	v_cvt_pk_bf16_f32 v112, v112, v113
	v_cvt_pk_bf16_f32 v113, v114, v115
	v_cvt_pk_bf16_f32 v114, v104, v105
	v_or_b32_e32 v104, 16, v150
	v_ashrrev_i32_e32 v105, 31, v104
	v_lshlrev_b64 v[104:105], 12, v[104:105]
	v_lshl_add_u64 v[104:105], s[8:9], 0, v[104:105]
	v_cvt_pk_bf16_f32 v115, v106, v107
	global_store_dwordx4 v[140:141], v[112:115], off offset:256
	s_mov_b64 s[38:39], 0x80000
	s_nop 0
	v_lshl_add_u64 v[112:113], v[104:105], 0, v[154:155]
	v_cvt_pk_bf16_f32 v104, v116, v117
	v_cvt_pk_bf16_f32 v105, v118, v119
	v_cvt_pk_bf16_f32 v106, v108, v109
	v_cvt_pk_bf16_f32 v107, v110, v111
	global_store_dwordx4 v[112:113], v[104:107], off
	v_cvt_pk_bf16_f32 v96, v96, v97
	v_cvt_pk_bf16_f32 v97, v98, v99
	v_cvt_pk_bf16_f32 v98, v88, v89
	v_or_b32_e32 v88, 32, v150
	v_ashrrev_i32_e32 v89, 31, v88
	v_lshlrev_b64 v[88:89], 12, v[88:89]
	v_lshl_add_u64 v[88:89], s[8:9], 0, v[88:89]
	v_cvt_pk_bf16_f32 v99, v90, v91
	global_store_dwordx4 v[112:113], v[96:99], off offset:256
	s_nop 1
	v_lshl_add_u64 v[96:97], v[88:89], 0, v[154:155]
	v_cvt_pk_bf16_f32 v88, v100, v101
	v_cvt_pk_bf16_f32 v89, v102, v103
	v_cvt_pk_bf16_f32 v90, v92, v93
	v_cvt_pk_bf16_f32 v91, v94, v95
	global_store_dwordx4 v[96:97], v[88:91], off
	v_cvt_pk_bf16_f32 v80, v80, v81
	v_cvt_pk_bf16_f32 v81, v82, v83
	v_cvt_pk_bf16_f32 v82, v72, v73
	v_or_b32_e32 v72, 48, v150
	v_ashrrev_i32_e32 v73, 31, v72
	v_lshlrev_b64 v[72:73], 12, v[72:73]
	v_lshl_add_u64 v[72:73], s[8:9], 0, v[72:73]
	v_cvt_pk_bf16_f32 v83, v74, v75
	global_store_dwordx4 v[96:97], v[80:83], off offset:256
	s_nop 1
	v_lshl_add_u64 v[80:81], v[72:73], 0, v[154:155]
	v_cvt_pk_bf16_f32 v72, v84, v85
	v_cvt_pk_bf16_f32 v73, v86, v87
	v_cvt_pk_bf16_f32 v74, v76, v77
	v_cvt_pk_bf16_f32 v75, v78, v79
	global_store_dwordx4 v[80:81], v[72:75], off
	v_cvt_pk_bf16_f32 v68, v68, v69
	v_cvt_pk_bf16_f32 v69, v70, v71
	v_cvt_pk_bf16_f32 v70, v64, v65
	v_lshl_add_u64 v[64:65], v[140:141], 0, s[38:39]
	s_mov_b32 s38, 0x80000
	v_cvt_pk_bf16_f32 v71, v66, v67
	global_store_dwordx4 v[80:81], v[68:71], off offset:256
	v_cvt_pk_bf16_f32 v60, v60, v61
	v_cvt_pk_bf16_f32 v61, v62, v63
	v_cvt_pk_bf16_f32 v62, v56, v57
	v_add_co_u32_e32 v56, vcc, s38, v140
	v_cvt_pk_bf16_f32 v63, v58, v59
	s_mov_b64 s[38:39], 0x90000
	s_nop 0
	v_addc_co_u32_e32 v57, vcc, 0, v141, vcc
	global_store_dwordx4 v[56:57], v[60:63], off
	v_cvt_pk_bf16_f32 v48, v48, v49
	v_cvt_pk_bf16_f32 v49, v50, v51
	v_cvt_pk_bf16_f32 v50, v40, v41
	v_cvt_pk_bf16_f32 v51, v42, v43
	global_store_dwordx4 v[64:65], v[48:51], off offset:256
	v_cvt_pk_bf16_f32 v40, v52, v53
	v_cvt_pk_bf16_f32 v41, v54, v55
	v_cvt_pk_bf16_f32 v42, v44, v45
	v_cvt_pk_bf16_f32 v43, v46, v47
	s_nop 1
	v_lshl_add_u64 v[48:49], v[140:141], 0, s[38:39]
	s_mov_b32 s38, 0x90000
	v_add_co_u32_e32 v44, vcc, s38, v140
	s_mov_b64 s[38:39], 0xa0000
	s_nop 0
	v_addc_co_u32_e32 v45, vcc, 0, v141, vcc
	global_store_dwordx4 v[44:45], v[40:43], off
	v_cvt_pk_bf16_f32 v32, v32, v33
	v_cvt_pk_bf16_f32 v33, v34, v35
	v_cvt_pk_bf16_f32 v34, v24, v25
	v_cvt_pk_bf16_f32 v35, v26, v27
	global_store_dwordx4 v[48:49], v[32:35], off offset:256
	v_cvt_pk_bf16_f32 v24, v36, v37
	v_cvt_pk_bf16_f32 v25, v38, v39
	v_cvt_pk_bf16_f32 v26, v28, v29
	v_cvt_pk_bf16_f32 v27, v30, v31
	s_nop 1
	v_lshl_add_u64 v[32:33], v[140:141], 0, s[38:39]
	s_mov_b32 s38, 0xa0000
	v_add_co_u32_e32 v28, vcc, s38, v140
	s_mov_b64 s[38:39], 0xb0000
	s_nop 0
	v_addc_co_u32_e32 v29, vcc, 0, v141, vcc
	global_store_dwordx4 v[28:29], v[24:27], off
	v_cvt_pk_bf16_f32 v16, v16, v17
	v_cvt_pk_bf16_f32 v17, v18, v19
	v_cvt_pk_bf16_f32 v18, v8, v9
	v_cvt_pk_bf16_f32 v19, v10, v11
	global_store_dwordx4 v[32:33], v[16:19], off offset:256
	v_cvt_pk_bf16_f32 v8, v20, v21
	v_cvt_pk_bf16_f32 v9, v22, v23
	v_cvt_pk_bf16_f32 v10, v12, v13
	v_cvt_pk_bf16_f32 v11, v14, v15
	s_nop 1
	v_lshl_add_u64 v[16:17], v[140:141], 0, s[38:39]
	s_mov_b32 s38, 0xb0000
	v_add_co_u32_e32 v12, vcc, s38, v140
	s_nop 1
	v_addc_co_u32_e32 v13, vcc, 0, v141, vcc
	s_and_b64 vcc, exec, s[36:37]
	s_mov_b64 s[36:37], -1
	global_store_dwordx4 v[12:13], v[8:11], off
	v_cvt_pk_bf16_f32 v4, v4, v5
	v_cvt_pk_bf16_f32 v5, v6, v7
	v_cvt_pk_bf16_f32 v6, v0, v1
	v_cvt_pk_bf16_f32 v7, v2, v3
	global_store_dwordx4 v[16:17], v[4:7], off offset:256
	s_cbranch_vccnz .LBB0_374
	s_andn2_b64 vcc, exec, s[6:7]
	s_cbranch_vccnz .LBB0_373
	s_barrier
	s_branch .LBB0_373

; template <int MODE>
; __device__ __forceinline__ void row_finish(const Params& p, int r, int lane, const float* gpost, const float* gnext, bf16_t* U, float coef, f32x4 (&h)[8], const u32x2 (&dw)[8]) {
;     ...
;     if (MODE >= 1) {
;         f32x4 d[8]; float ss = 0.f;
; #pragma unroll
;         for (int j = 0; j < 8; ++j) { const u32x2 w = dw[j]; d[j] = (f32x4){bflo(w.x), bfhi(w.x), bflo(w.y), bfhi(w.y)};
;             ss += (d[j].x * d[j].x + d[j].y * d[j].y) + (d[j].z * d[j].z + d[j].w * d[j].w); }
;         ss = wave_sum(ss);
;         const float rs = rsqrtf(ss * (1.f / DM) + EPS) * coef;
;         f32x4* hd = (f32x4*)hrow(p, r);
; #pragma unroll
;         for (int j = 0; j < 8; ++j) { const f32x4 g = ((const f32x4*)gpost)[lane + 64 * j]; h[j] = h[j] + d[j] * g * rs; __builtin_nontemporal_store(h[j], &hd[lane + 64 * j]); }
.LBB0_418:
	s_andn2_b64 vcc, exec, s[6:7]
	s_mov_b64 s[6:7], -1
	s_cbranch_vccnz .LBB0_420
	s_waitcnt vmcnt(0) lgkmcnt(0)
	v_and_b32_e32 v169, 0xffff0000, v146
	v_and_b32_e32 v168, 0xffff0000, v148
	v_and_b32_e32 v171, 0xffff0000, v147
	v_and_b32_e32 v170, 0xffff0000, v149
	v_lshlrev_b32_e32 v71, 16, v146
	v_lshlrev_b32_e32 v70, 16, v148
	v_lshlrev_b32_e32 v69, 16, v147
	v_lshlrev_b32_e32 v68, 16, v149
	v_pk_mul_f32 v[64:65], v[168:169], v[168:169]
	v_pk_mul_f32 v[66:67], v[170:171], v[170:171]
	v_pk_fma_f32 v[64:65], v[70:71], v[70:71], v[64:65]
	v_pk_fma_f32 v[66:67], v[68:69], v[68:69], v[66:67]
	v_and_b32_e32 v73, 0xffff0000, v151
	v_pk_add_f32 v[64:65], v[64:65], v[66:67]
	v_and_b32_e32 v72, 0xffff0000, v150
	v_pk_add_f32 v[64:65], v[64:65], v[64:65] op_sel_hi:[0,1]
	v_lshlrev_b32_e32 v75, 16, v151
	v_lshlrev_b32_e32 v74, 16, v150
	v_pk_mul_f32 v[66:67], v[72:73], v[72:73]
	v_lshlrev_b32_e32 v76, 16, v152
	v_and_b32_e32 v77, 0xffff0000, v152
	v_lshlrev_b32_e32 v78, 16, v153
	v_lshlrev_b32_e32 v80, 16, v154
	v_pk_fma_f32 v[66:67], v[74:75], v[74:75], v[66:67]
	v_mul_f32_e32 v81, v76, v76
	v_mul_f32_e32 v85, v77, v77
	v_and_b32_e32 v79, 0xffff0000, v153
	v_mul_f32_e32 v64, v78, v78
	v_mov_b32_e32 v84, v80
	v_pk_add_f32 v[66:67], v[66:67], v[66:67] op_sel_hi:[0,1]
	v_pk_fma_f32 v[86:87], v[78:79], v[78:79], v[64:65] op_sel_hi:[1,1,0]
	v_and_b32_e32 v173, 0xffff0000, v154
	v_lshlrev_b32_e32 v82, 16, v155
	v_and_b32_e32 v83, 0xffff0000, v155
	v_pk_add_f32 v[84:85], v[80:81], v[84:85]
	v_mul_f32_e32 v86, v173, v173
	v_mul_f32_e32 v66, v82, v82
	v_mul_f32_e32 v64, v83, v83
	v_mul_f32_e32 v88, v80, v80
	v_mov_b32_e32 v89, v85
	v_pk_add_f32 v[84:85], v[88:89], v[86:87]
	v_pk_add_f32 v[64:65], v[66:67], v[64:65]
	v_and_b32_e32 v87, 0xffff0000, v157
	v_pk_add_f32 v[64:65], v[84:85], v[64:65]
	v_and_b32_e32 v86, 0xffff0000, v156
	v_pk_add_f32 v[64:65], v[64:65], v[64:65] op_sel_hi:[0,1]
	v_lshlrev_b32_e32 v85, 16, v157
	v_lshlrev_b32_e32 v84, 16, v156
	v_pk_mul_f32 v[66:67], v[86:87], v[86:87]
	v_lshlrev_b32_e32 v88, 16, v158
	v_and_b32_e32 v89, 0xffff0000, v158
	v_lshlrev_b32_e32 v90, 16, v159
	v_lshlrev_b32_e32 v92, 16, v160
	v_pk_fma_f32 v[66:67], v[84:85], v[84:85], v[66:67]
	v_mul_f32_e32 v93, v88, v88
	v_mul_f32_e32 v175, v89, v89
	v_and_b32_e32 v91, 0xffff0000, v159
	v_mul_f32_e32 v64, v90, v90
	v_mov_b32_e32 v174, v92
	v_pk_add_f32 v[66:67], v[66:67], v[66:67] op_sel_hi:[0,1]
	v_pk_fma_f32 v[176:177], v[90:91], v[90:91], v[64:65] op_sel_hi:[1,1,0]
	v_and_b32_e32 v99, 0xffff0000, v160
	v_lshlrev_b32_e32 v94, 16, v161
	v_and_b32_e32 v95, 0xffff0000, v161
	v_pk_add_f32 v[174:175], v[92:93], v[174:175]
	v_mul_f32_e32 v176, v99, v99
	v_mul_f32_e32 v66, v94, v94
	v_mul_f32_e32 v64, v95, v95
	v_mul_f32_e32 v178, v92, v92
	v_mov_b32_e32 v179, v175
	v_pk_add_f32 v[174:175], v[178:179], v[176:177]
	v_pk_add_f32 v[64:65], v[66:67], v[64:65]
	s_add_u32 s5, s60, s38
	v_pk_add_f32 v[64:65], v[174:175], v[64:65]
	s_addc_u32 s6, 0, s39
	v_add_f32_e32 v64, v64, v65
	ds_bpermute_b32 v65, v97, v64
	s_add_u32 s48, s26, s38
	s_addc_u32 s7, s27, s39
	s_cmp_lt_i32 s61, 0x8000
	s_cselect_b32 s7, s7, s6
	s_waitcnt lgkmcnt(0)
	v_add_f32_e32 v64, v64, v65
	ds_bpermute_b32 v65, v101, v64
	s_cselect_b32 s6, s48, s5
	v_mov_b32_e32 v174, v71
	v_mov_b32_e32 v175, v169
	s_cselect_b32 s5, s15, s71
	s_waitcnt lgkmcnt(0)
	v_add_f32_e32 v64, v64, v65
	ds_bpermute_b32 v65, v103, v64
	s_cselect_b32 s48, s14, s70
	s_lshl_b64 s[6:7], s[6:7], 13
	s_add_u32 s6, s48, s6
	s_addc_u32 s7, s5, s7
	s_waitcnt lgkmcnt(0)
	v_add_f32_e32 v64, v64, v65
	ds_bpermute_b32 v65, v105, v64
	v_lshlrev_b32_e32 v81, 4, v96
	v_mov_b32_e32 v71, v168
	v_lshlrev_b32_e32 v93, 4, v100
	s_waitcnt lgkmcnt(0)
	v_add_f32_e32 v64, v64, v65
	ds_bpermute_b32 v65, v107, v64
	s_waitcnt lgkmcnt(0)
	v_add_f32_e32 v64, v64, v65
	ds_bpermute_b32 v65, v129, v64
	s_waitcnt lgkmcnt(0)
	v_add_f32_e32 v64, v64, v65
	v_fmamk_f32 v64, v64, 0x3a000000, v172
	v_cmp_gt_f32_e32 vcc, s58, v64
	v_mul_f32_e32 v65, 0x4b800000, v64
	s_nop 0
	v_cndmask_b32_e32 v64, v64, v65, vcc
	v_rsq_f32_e32 v64, v64
	s_nop 0
	v_mul_f32_e32 v65, 0x45800000, v64
	v_cndmask_b32_e32 v64, v64, v65, vcc
	v_mul_f32_e32 v166, 0.5, v64
	global_load_dwordx4 v[64:67], v[108:109], off
	s_waitcnt vmcnt(0)
	v_pk_mul_f32 v[64:65], v[174:175], v[64:65]
	v_mov_b32_e32 v174, v69
	v_mov_b32_e32 v175, v171
	v_pk_mul_f32 v[66:67], v[174:175], v[66:67]
	v_pk_fma_f32 v[64:65], v[64:65], v[166:167], v[0:1] op_sel_hi:[1,0,1]
	v_pk_fma_f32 v[66:67], v[66:67], v[166:167], v[2:3] op_sel_hi:[1,0,1]
	global_store_dwordx4 v81, v[64:67], s[6:7] nt
	global_load_dwordx4 v[174:177], v[108:109], off offset:1024
	v_mov_b32_e32 v69, v170
	s_waitcnt vmcnt(0)
	v_pk_mul_f32 v[168:169], v[70:71], v[174:175]
	v_pk_mul_f32 v[68:69], v[68:69], v[176:177]
	v_mov_b32_e32 v174, v74
	v_pk_fma_f32 v[70:71], v[68:69], v[166:167], v[38:39] op_sel_hi:[1,0,1]
	v_pk_fma_f32 v[68:69], v[168:169], v[166:167], v[36:37] op_sel_hi:[1,0,1]
	global_store_dwordx4 v81, v[68:71], s[6:7] offset:1024 nt
	global_load_dwordx4 v[168:171], v[108:109], off offset:2048
	v_mov_b32_e32 v175, v72
	v_mov_b32_e32 v72, v75
	s_waitcnt vmcnt(0)
	v_pk_mul_f32 v[168:169], v[168:169], v[174:175]
	v_pk_mul_f32 v[72:73], v[170:171], v[72:73]
	v_mov_b32_e32 v174, v84
	v_pk_fma_f32 v[74:75], v[72:73], v[166:167], v[42:43] op_sel_hi:[1,0,1]
	v_pk_fma_f32 v[72:73], v[168:169], v[166:167], v[40:41] op_sel_hi:[1,0,1]
	global_store_dwordx4 v81, v[72:75], s[6:7] offset:2048 nt
	global_load_dwordx4 v[168:171], v[108:109], off offset:3072
	v_mov_b32_e32 v175, v86
	v_mov_b32_e32 v86, v85
	s_waitcnt vmcnt(0)
; __device__ __forceinline__ unsigned pk2(float lo, float hi) { return f2bf(lo) | (f2bf(hi) << 16); }
; template <int MODE>
; __device__ __forceinline__ void row_finish(const Params& p, int r, int lane, const float* gpost, const float* gnext, bf16_t* U, float coef, f32x4 (&h)[8], const u32x2 (&dw)[8]) {
;     ...
;         for (int j = 0; j < 8; ++j) { const f32x4 g = ((const f32x4*)gpost)[lane + 64 * j]; h[j] = h[j] + d[j] * g * rs; __builtin_nontemporal_store(h[j], &hd[lane + 64 * j]); }
;     }
;     if (MODE != 3) {
;         float s2 = 0.f;
; #pragma unroll
;         for (int j = 0; j < 8; ++j) s2 += (h[j].x * h[j].x + h[j].y * h[j].y) + (h[j].z * h[j].z + h[j].w * h[j].w);
;         s2 = wave_sum(s2);
;         const float rs2 = rsqrtf(s2 * (1.f / DM) + EPS);
;         u32x2* up = (u32x2*)(U + (size_t)r * DM);
; #pragma unroll
;         for (int j = 0; j < 8; ++j) { const f32x4 g = ((const f32x4*)gnext)[lane + 64 * j]; const f32x4 v = h[j] * g * rs2;
;             u32x2 w; w.x = pk2(v.x, v.y); w.y = pk2(v.z, v.w); up[lane + 64 * j] = w; }
	v_pk_mul_f32 v[78:79], v[78:79], v[170:171]
	v_pk_mul_f32 v[76:77], v[76:77], v[168:169]
	v_pk_fma_f32 v[78:79], v[78:79], v[166:167], v[46:47] op_sel_hi:[1,0,1]
	v_pk_fma_f32 v[76:77], v[76:77], v[166:167], v[44:45] op_sel_hi:[1,0,1]
	global_store_dwordx4 v81, v[76:79], s[6:7] offset:3072 nt
	global_load_dwordx4 v[168:171], v[110:111], off
	v_mov_b32_e32 v81, v173
	s_waitcnt vmcnt(0)
	v_pk_mul_f32 v[80:81], v[80:81], v[168:169]
	v_pk_mul_f32 v[82:83], v[82:83], v[170:171]
	v_pk_fma_f32 v[80:81], v[80:81], v[166:167], v[48:49] op_sel_hi:[1,0,1]
	v_pk_fma_f32 v[82:83], v[82:83], v[166:167], v[50:51] op_sel_hi:[1,0,1]
	global_store_dwordx4 v93, v[80:83], s[6:7] nt
	global_load_dwordx4 v[168:171], v[112:113], off
	v_lshlrev_b32_e32 v93, 4, v102
	s_waitcnt vmcnt(0)
	v_pk_mul_f32 v[168:169], v[168:169], v[174:175]
	v_pk_mul_f32 v[84:85], v[170:171], v[86:87]
	v_mov_b32_e32 v174, v67
	v_pk_fma_f32 v[86:87], v[166:167], v[84:85], v[54:55] op_sel_hi:[0,1,1]
	v_pk_fma_f32 v[84:85], v[166:167], v[168:169], v[52:53] op_sel_hi:[0,1,1]
	global_store_dwordx4 v93, v[84:87], s[6:7] nt
	global_load_dwordx4 v[168:171], v[114:115], off
	v_lshlrev_b32_e32 v93, 4, v104
	v_mov_b32_e32 v175, v71
	v_pk_mul_f32 v[174:175], v[174:175], v[174:175]
	s_waitcnt vmcnt(0)
	v_pk_mul_f32 v[90:91], v[90:91], v[170:171]
	v_pk_mul_f32 v[88:89], v[88:89], v[168:169]
	v_pk_fma_f32 v[90:91], v[166:167], v[90:91], v[58:59] op_sel_hi:[0,1,1]
	v_pk_fma_f32 v[88:89], v[166:167], v[88:89], v[56:57] op_sel_hi:[0,1,1]
	global_store_dwordx4 v93, v[88:91], s[6:7] nt
	global_load_dwordx4 v[168:171], v[116:117], off
	v_mov_b32_e32 v93, v99
	v_lshlrev_b32_e32 v99, 4, v106
	s_waitcnt vmcnt(0)
	v_pk_mul_f32 v[94:95], v[94:95], v[170:171]
	v_mov_b32_e32 v170, v65
	v_mov_b32_e32 v171, v69
	v_pk_mul_f32 v[92:93], v[92:93], v[168:169]
	v_mov_b32_e32 v168, v64
	v_mov_b32_e32 v169, v68
	v_pk_mul_f32 v[170:171], v[170:171], v[170:171]
	v_pk_fma_f32 v[94:95], v[166:167], v[94:95], v[62:63] op_sel_hi:[0,1,1]
	v_pk_fma_f32 v[168:169], v[168:169], v[168:169], v[170:171]
	v_mov_b32_e32 v170, v66
	v_mov_b32_e32 v171, v70
	v_pk_fma_f32 v[170:171], v[170:171], v[170:171], v[174:175]
	v_pk_mul_f32 v[174:175], v[74:75], v[74:75]
	v_pk_add_f32 v[168:169], v[168:169], v[170:171]
	v_pk_mul_f32 v[170:171], v[72:73], v[72:73]
	v_pk_fma_f32 v[92:93], v[166:167], v[92:93], v[60:61] op_sel_hi:[0,1,1]
	v_pk_mov_b32 v[176:177], v[170:171], v[174:175] op_sel:[1,0]
	v_mov_b32_e32 v171, v175
	v_mul_f32_e32 v166, v76, v76
	v_pk_add_f32 v[170:171], v[176:177], v[170:171]
	v_pk_fma_f32 v[174:175], v[76:77], v[76:77], v[166:167] op_sel_hi:[1,1,0]
	v_mul_f32_e32 v166, v78, v78
	v_pk_add_f32 v[168:169], v[168:169], v[168:169] op_sel_hi:[0,1]
	v_pk_add_f32 v[170:171], v[170:171], v[170:171] op_sel_hi:[0,1]
	v_pk_fma_f32 v[176:177], v[78:79], v[78:79], v[166:167] op_sel_hi:[1,1,0]
	v_mul_f32_e32 v174, v80, v80
	v_mul_f32_e32 v176, v81, v81
	v_mul_f32_e32 v170, v82, v82
	v_mul_f32_e32 v168, v83, v83
	v_pk_add_f32 v[174:175], v[174:175], v[176:177]
	v_pk_add_f32 v[168:169], v[170:171], v[168:169]
	v_pk_mul_f32 v[170:171], v[84:85], v[84:85]
	v_pk_add_f32 v[168:169], v[174:175], v[168:169]
	v_pk_mul_f32 v[174:175], v[86:87], v[86:87]
	v_mul_f32_e32 v166, v88, v88
	v_pk_mov_b32 v[176:177], v[170:171], v[174:175] op_sel:[1,0]
	v_mov_b32_e32 v171, v175
	v_pk_add_f32 v[170:171], v[176:177], v[170:171]
	v_pk_fma_f32 v[174:175], v[88:89], v[88:89], v[166:167] op_sel_hi:[1,1,0]
	v_mul_f32_e32 v166, v90, v90
	v_pk_add_f32 v[168:169], v[168:169], v[168:169] op_sel_hi:[0,1]
	v_pk_add_f32 v[170:171], v[170:171], v[170:171] op_sel_hi:[0,1]
	v_pk_fma_f32 v[176:177], v[90:91], v[90:91], v[166:167] op_sel_hi:[1,1,0]
	v_mul_f32_e32 v174, v92, v92
	v_mul_f32_e32 v176, v93, v93
	v_mul_f32_e32 v170, v94, v94
	v_mul_f32_e32 v168, v95, v95
	v_pk_add_f32 v[174:175], v[174:175], v[176:177]
	v_pk_add_f32 v[168:169], v[170:171], v[168:169]
	global_store_dwordx4 v99, v[92:95], s[6:7] nt
	v_pk_add_f32 v[168:169], v[174:175], v[168:169]
	s_mov_b64 s[6:7], 0
	v_add_f32_e32 v99, v168, v169
	global_load_dwordx4 v[168:171], v[118:119], off
	ds_bpermute_b32 v166, v97, v99
	s_waitcnt lgkmcnt(0)
	v_add_f32_e32 v99, v99, v166
	ds_bpermute_b32 v166, v101, v99
	s_waitcnt lgkmcnt(0)
	v_add_f32_e32 v99, v99, v166
	ds_bpermute_b32 v166, v103, v99
	s_waitcnt lgkmcnt(0)
	v_add_f32_e32 v99, v99, v166
	ds_bpermute_b32 v166, v105, v99
	s_waitcnt lgkmcnt(0)
	v_add_f32_e32 v99, v99, v166
	ds_bpermute_b32 v166, v107, v99
	s_waitcnt lgkmcnt(0)
	v_add_f32_e32 v99, v99, v166
	ds_bpermute_b32 v166, v129, v99
	s_waitcnt lgkmcnt(0)
	v_add_f32_e32 v99, v99, v166
	v_fmamk_f32 v99, v99, 0x3a000000, v172
	v_cmp_gt_f32_e32 vcc, s58, v99
	v_mul_f32_e32 v166, 0x4b800000, v99
	s_waitcnt vmcnt(0)
	v_pk_mul_f32 v[168:169], v[64:65], v[168:169]
	v_cndmask_b32_e32 v99, v99, v166, vcc
	v_rsq_f32_e32 v99, v99
	v_pk_mul_f32 v[170:171], v[66:67], v[170:171]
	v_mul_f32_e32 v166, 0x45800000, v99
	v_cndmask_b32_e32 v166, v99, v166, vcc
	v_pk_mul_f32 v[168:169], v[168:169], v[166:167] op_sel_hi:[1,0]
	v_pk_mul_f32 v[170:171], v[170:171], v[166:167] op_sel_hi:[1,0]
	v_bfe_u32 v99, v168, 16, 1
	v_add3_u32 v99, v168, v99, s56
	v_bfe_u32 v168, v169, 16, 1
	v_lshrrev_b32_e32 v99, 16, v99
	v_add3_u32 v168, v169, v168, s56
	v_and_or_b32 v168, v168, s57, v99
	v_bfe_u32 v99, v170, 16, 1
	v_bfe_u32 v169, v171, 16, 1
	v_add3_u32 v99, v170, v99, s56
	v_add3_u32 v169, v171, v169, s56
	v_lshl_add_u64 v[170:171], s[46:47], 0, v[162:163]
	v_lshrrev_b32_e32 v99, 16, v99
	v_add_co_u32_e32 v178, vcc, s30, v170
	v_and_or_b32 v169, v169, s57, v99
	s_nop 0
	v_addc_co_u32_e32 v179, vcc, 0, v171, vcc
	global_store_dwordx2 v[178:179], v[168:169], off offset:3328
	global_load_dwordx4 v[174:177], v[118:119], off offset:1024
	s_waitcnt vmcnt(0)
; __device__ __forceinline__ unsigned pk2(float lo, float hi) { return f2bf(lo) | (f2bf(hi) << 16); }
; template <int MODE>
; __device__ __forceinline__ void row_finish(const Params& p, int r, int lane, const float* gpost, const float* gnext, bf16_t* U, float coef, f32x4 (&h)[8], const u32x2 (&dw)[8]) {
;     ...
;     if (r >= ROWS) { if (MODE != 3) { u32x4* up = (u32x4*)(U + (size_t)r * DM);
; #pragma unroll
;             for (int j = 0; j < 4; ++j) up[lane + 64 * j] = (u32x4){0u, 0u, 0u, 0u}; } return; }
;     ...
;         for (int j = 0; j < 8; ++j) { const f32x4 g = ((const f32x4*)gnext)[lane + 64 * j]; const f32x4 v = h[j] * g * rs2;
;             u32x2 w; w.x = pk2(v.x, v.y); w.y = pk2(v.z, v.w); up[lane + 64 * j] = w; }
	v_pk_mul_f32 v[168:169], v[68:69], v[174:175]
	s_nop 0
	v_pk_mul_f32 v[168:169], v[168:169], v[166:167] op_sel_hi:[1,0]
	v_pk_mul_f32 v[174:175], v[70:71], v[176:177]
	v_bfe_u32 v99, v168, 16, 1
	v_add3_u32 v99, v168, v99, s56
	v_bfe_u32 v168, v169, 16, 1
	v_pk_mul_f32 v[174:175], v[174:175], v[166:167] op_sel_hi:[1,0]
	v_lshrrev_b32_e32 v99, 16, v99
	v_add3_u32 v168, v169, v168, s56
	v_and_or_b32 v168, v168, s57, v99
	v_bfe_u32 v99, v174, 16, 1
	v_add3_u32 v99, v174, v99, s56
	v_bfe_u32 v169, v175, 16, 1
	v_lshrrev_b32_e32 v99, 16, v99
	v_add3_u32 v169, v175, v169, s56
	v_and_or_b32 v169, v169, s57, v99
	global_store_dwordx2 v[178:179], v[168:169], off offset:3840
	global_load_dwordx4 v[174:177], v[118:119], off offset:2048
	s_waitcnt vmcnt(0)
	v_pk_mul_f32 v[168:169], v[72:73], v[174:175]
	s_nop 0
	v_pk_mul_f32 v[168:169], v[168:169], v[166:167] op_sel_hi:[1,0]
	v_pk_mul_f32 v[174:175], v[74:75], v[176:177]
	v_bfe_u32 v99, v168, 16, 1
	v_add3_u32 v99, v168, v99, s56
	v_bfe_u32 v168, v169, 16, 1
	v_pk_mul_f32 v[174:175], v[174:175], v[166:167] op_sel_hi:[1,0]
	v_lshrrev_b32_e32 v99, 16, v99
	v_add3_u32 v168, v169, v168, s56
	v_and_or_b32 v176, v168, s57, v99
	v_bfe_u32 v99, v174, 16, 1
	v_add3_u32 v99, v174, v99, s56
	v_bfe_u32 v168, v175, 16, 1
	v_lshrrev_b32_e32 v99, 16, v99
	v_add3_u32 v168, v175, v168, s56
	v_and_or_b32 v177, v168, s57, v99
	v_add_co_u32_e32 v168, vcc, s31, v170
	s_nop 1
	v_addc_co_u32_e32 v169, vcc, 0, v171, vcc
	global_store_dwordx2 v[168:169], v[176:177], off offset:256
	global_load_dwordx4 v[174:177], v[118:119], off offset:3072
	s_waitcnt vmcnt(0)
	v_pk_mul_f32 v[170:171], v[76:77], v[174:175]
	s_nop 0
	v_pk_mul_f32 v[170:171], v[170:171], v[166:167] op_sel_hi:[1,0]
	v_pk_mul_f32 v[174:175], v[78:79], v[176:177]
	v_bfe_u32 v99, v170, 16, 1
	v_add3_u32 v99, v170, v99, s56
	v_bfe_u32 v170, v171, 16, 1
	v_pk_mul_f32 v[174:175], v[174:175], v[166:167] op_sel_hi:[1,0]
	v_lshrrev_b32_e32 v99, 16, v99
	v_add3_u32 v170, v171, v170, s56
	v_and_or_b32 v170, v170, s57, v99
	v_bfe_u32 v99, v174, 16, 1
	v_add3_u32 v99, v174, v99, s56
	v_bfe_u32 v171, v175, 16, 1
	v_lshrrev_b32_e32 v99, 16, v99
	v_add3_u32 v171, v175, v171, s56
	v_and_or_b32 v171, v171, s57, v99
	global_store_dwordx2 v[168:169], v[170:171], off offset:768
	global_load_dwordx4 v[174:177], v[120:121], off
	s_waitcnt vmcnt(0)
	v_pk_mul_f32 v[170:171], v[80:81], v[174:175]
	s_nop 0
	v_pk_mul_f32 v[170:171], v[170:171], v[166:167] op_sel_hi:[1,0]
	v_pk_mul_f32 v[174:175], v[82:83], v[176:177]
	v_bfe_u32 v99, v170, 16, 1
	v_add3_u32 v99, v170, v99, s56
	v_bfe_u32 v170, v171, 16, 1
	v_pk_mul_f32 v[174:175], v[174:175], v[166:167] op_sel_hi:[1,0]
	v_lshrrev_b32_e32 v99, 16, v99
	v_add3_u32 v170, v171, v170, s56
	v_and_or_b32 v170, v170, s57, v99
	v_bfe_u32 v99, v174, 16, 1
	v_add3_u32 v99, v174, v99, s56
	v_bfe_u32 v171, v175, 16, 1
	v_lshrrev_b32_e32 v99, 16, v99
	v_add3_u32 v171, v175, v171, s56
	v_and_or_b32 v171, v171, s57, v99
	global_store_dwordx2 v[168:169], v[170:171], off offset:1280
	global_load_dwordx4 v[174:177], v[122:123], off
	s_waitcnt vmcnt(0)
	v_pk_mul_f32 v[170:171], v[84:85], v[174:175]
	s_nop 0
	v_pk_mul_f32 v[170:171], v[170:171], v[166:167] op_sel_hi:[1,0]
	v_pk_mul_f32 v[174:175], v[86:87], v[176:177]
	v_bfe_u32 v99, v170, 16, 1
	v_add3_u32 v99, v170, v99, s56
	v_bfe_u32 v170, v171, 16, 1
	v_pk_mul_f32 v[174:175], v[174:175], v[166:167] op_sel_hi:[1,0]
	v_lshrrev_b32_e32 v99, 16, v99
	v_add3_u32 v170, v171, v170, s56
	v_and_or_b32 v170, v170, s57, v99
	v_bfe_u32 v99, v174, 16, 1
	v_add3_u32 v99, v174, v99, s56
	v_bfe_u32 v171, v175, 16, 1
	v_lshrrev_b32_e32 v99, 16, v99
	v_add3_u32 v171, v175, v171, s56
	v_and_or_b32 v171, v171, s57, v99
	global_store_dwordx2 v[168:169], v[170:171], off offset:1792
	global_load_dwordx4 v[174:177], v[124:125], off
	s_waitcnt vmcnt(0)
	v_pk_mul_f32 v[170:171], v[88:89], v[174:175]
	s_nop 0
	v_pk_mul_f32 v[170:171], v[170:171], v[166:167] op_sel_hi:[1,0]
	v_pk_mul_f32 v[174:175], v[90:91], v[176:177]
	v_bfe_u32 v99, v170, 16, 1
	v_add3_u32 v99, v170, v99, s56
	v_bfe_u32 v170, v171, 16, 1
	v_pk_mul_f32 v[174:175], v[174:175], v[166:167] op_sel_hi:[1,0]
	v_lshrrev_b32_e32 v99, 16, v99
	v_add3_u32 v170, v171, v170, s56
	v_and_or_b32 v170, v170, s57, v99
	v_bfe_u32 v99, v174, 16, 1
	v_add3_u32 v99, v174, v99, s56
	v_bfe_u32 v171, v175, 16, 1
	v_lshrrev_b32_e32 v99, 16, v99
	v_add3_u32 v171, v175, v171, s56
	v_and_or_b32 v171, v171, s57, v99
	global_store_dwordx2 v[168:169], v[170:171], off offset:2304
	global_load_dwordx4 v[174:177], v[126:127], off
	s_waitcnt vmcnt(0)
	v_pk_mul_f32 v[170:171], v[92:93], v[174:175]
	s_nop 0
	v_pk_mul_f32 v[170:171], v[170:171], v[166:167] op_sel_hi:[1,0]
	v_pk_mul_f32 v[174:175], v[94:95], v[176:177]
	v_bfe_u32 v99, v170, 16, 1
	v_pk_mul_f32 v[174:175], v[174:175], v[166:167] op_sel_hi:[1,0]
	v_add3_u32 v99, v170, v99, s56
	v_bfe_u32 v166, v171, 16, 1
	v_lshrrev_b32_e32 v99, 16, v99
	v_add3_u32 v166, v171, v166, s56
	v_and_or_b32 v170, v166, s57, v99
	v_bfe_u32 v99, v174, 16, 1
	v_add3_u32 v99, v174, v99, s56
	v_bfe_u32 v166, v175, 16, 1
	v_lshrrev_b32_e32 v99, 16, v99
	v_add3_u32 v166, v175, v166, s56
	v_and_or_b32 v171, v166, s57, v99
	global_store_dwordx2 v[168:169], v[170:171], off offset:2816
.LBB0_420:
	s_andn2_b64 vcc, exec, s[6:7]
	s_cbranch_vccnz .LBB0_422
	v_lshl_add_u64 v[64:65], s[46:47], 0, v[164:165]
	v_add_co_u32_e32 v66, vcc, 0xa2f1000, v64
	s_mov_b32 s6, s4
	s_nop 0
	v_addc_co_u32_e32 v67, vcc, 0, v65, vcc
	s_mov_b32 s7, s4
	s_mov_b32 s5, s4
	v_mov_b64_e32 v[70:71], s[6:7]
	v_add_co_u32_e32 v64, vcc, 0xa2f2000, v64
	v_mov_b64_e32 v[68:69], s[4:5]
	s_nop 0
	v_addc_co_u32_e32 v65, vcc, 0, v65, vcc
	global_store_dwordx4 v[66:67], v[68:71], off offset:3328
	global_store_dwordx4 v[64:65], v[68:71], off offset:256
	global_store_dwordx4 v[64:65], v[68:71], off offset:1280
	global_store_dwordx4 v[64:65], v[68:71], off offset:2304
	s_waitcnt vmcnt(0)
	v_mov_b32_e32 v95, v63
	v_mov_b32_e32 v94, v62
	v_mov_b32_e32 v93, v61
	v_mov_b32_e32 v92, v60
	v_mov_b32_e32 v91, v59
	v_mov_b32_e32 v90, v58
	v_mov_b32_e32 v89, v57
	v_mov_b32_e32 v88, v56
	v_mov_b32_e32 v87, v55
	v_mov_b32_e32 v86, v54
	v_mov_b32_e32 v85, v53
	v_mov_b32_e32 v84, v52
	v_mov_b32_e32 v83, v51
	v_mov_b32_e32 v82, v50
	v_mov_b32_e32 v81, v49
	v_mov_b32_e32 v80, v48
	v_mov_b32_e32 v79, v47
	v_mov_b32_e32 v78, v46
	v_mov_b32_e32 v77, v45
	v_mov_b32_e32 v76, v44
	v_mov_b32_e32 v75, v43
	v_mov_b32_e32 v74, v42
	v_mov_b32_e32 v73, v41
	v_mov_b32_e32 v72, v40
	v_mov_b32_e32 v71, v39
	v_mov_b32_e32 v70, v38
	v_mov_b32_e32 v69, v37
	v_mov_b32_e32 v68, v36
	v_mov_b32_e32 v67, v3
	v_mov_b32_e32 v66, v2
	v_mov_b32_e32 v65, v1
	v_mov_b32_e32 v64, v0

; template <int MODE>
; __device__ __forceinline__ void row_finish(const Params& p, int r, int lane, const float* gpost, const float* gnext, bf16_t* U, float coef, f32x4 (&h)[8], const u32x2 (&dw)[8]) {
;     ...
;     if (MODE >= 1) {
;         f32x4 d[8]; float ss = 0.f;
; #pragma unroll
;         for (int j = 0; j < 8; ++j) { const u32x2 w = dw[j]; d[j] = (f32x4){bflo(w.x), bfhi(w.x), bflo(w.y), bfhi(w.y)};
;             ss += (d[j].x * d[j].x + d[j].y * d[j].y) + (d[j].z * d[j].z + d[j].w * d[j].w); }
;         ss = wave_sum(ss);
;         const float rs = rsqrtf(ss * (1.f / DM) + EPS) * coef;
;         f32x4* hd = (f32x4*)hrow(p, r);
; #pragma unroll
;         for (int j = 0; j < 8; ++j) { const f32x4 g = ((const f32x4*)gpost)[lane + 64 * j]; h[j] = h[j] + d[j] * g * rs; __builtin_nontemporal_store(h[j], &hd[lane + 64 * j]); }
.LBB0_423:
	s_andn2_b64 vcc, exec, s[28:29]
	s_mov_b64 s[6:7], -1
	s_cbranch_vccnz .LBB0_425
	s_waitcnt vmcnt(0) lgkmcnt(0)
	v_and_b32_e32 v71, 0xffff0000, v130
	v_and_b32_e32 v70, 0xffff0000, v132
	v_and_b32_e32 v171, 0xffff0000, v131
	v_and_b32_e32 v170, 0xffff0000, v133
	v_lshlrev_b32_e32 v69, 16, v130
	v_lshlrev_b32_e32 v68, 16, v132
	v_lshlrev_b32_e32 v169, 16, v131
	v_lshlrev_b32_e32 v168, 16, v133
	v_pk_mul_f32 v[64:65], v[70:71], v[70:71]
	v_pk_mul_f32 v[66:67], v[170:171], v[170:171]
	v_pk_fma_f32 v[64:65], v[68:69], v[68:69], v[64:65]
	v_pk_fma_f32 v[66:67], v[168:169], v[168:169], v[66:67]
	v_and_b32_e32 v75, 0xffff0000, v135
	v_pk_add_f32 v[64:65], v[64:65], v[66:67]
	v_and_b32_e32 v74, 0xffff0000, v134
	v_pk_add_f32 v[64:65], v[64:65], v[64:65] op_sel_hi:[0,1]
	v_lshlrev_b32_e32 v73, 16, v135
	v_lshlrev_b32_e32 v72, 16, v134
	v_pk_mul_f32 v[66:67], v[74:75], v[74:75]
	v_lshlrev_b32_e32 v76, 16, v136
	v_and_b32_e32 v77, 0xffff0000, v136
	v_lshlrev_b32_e32 v78, 16, v137
	v_lshlrev_b32_e32 v80, 16, v138
	v_pk_fma_f32 v[66:67], v[72:73], v[72:73], v[66:67]
	v_mul_f32_e32 v81, v76, v76
	v_mul_f32_e32 v85, v77, v77
	v_and_b32_e32 v79, 0xffff0000, v137
	v_mul_f32_e32 v64, v78, v78
	v_mov_b32_e32 v84, v80
	v_pk_add_f32 v[66:67], v[66:67], v[66:67] op_sel_hi:[0,1]
	v_pk_fma_f32 v[86:87], v[78:79], v[78:79], v[64:65] op_sel_hi:[1,1,0]
	v_and_b32_e32 v173, 0xffff0000, v138
	v_lshlrev_b32_e32 v82, 16, v139
	v_and_b32_e32 v83, 0xffff0000, v139
	v_pk_add_f32 v[84:85], v[80:81], v[84:85]
	v_mul_f32_e32 v86, v173, v173
	v_mul_f32_e32 v66, v82, v82
	v_mul_f32_e32 v64, v83, v83
	v_mul_f32_e32 v88, v80, v80
	v_mov_b32_e32 v89, v85
	v_pk_add_f32 v[84:85], v[88:89], v[86:87]
	v_pk_add_f32 v[64:65], v[66:67], v[64:65]
	v_and_b32_e32 v87, 0xffff0000, v141
	v_pk_add_f32 v[64:65], v[84:85], v[64:65]
	v_and_b32_e32 v86, 0xffff0000, v140
	v_pk_add_f32 v[64:65], v[64:65], v[64:65] op_sel_hi:[0,1]
	v_lshlrev_b32_e32 v85, 16, v141
	v_lshlrev_b32_e32 v84, 16, v140
	v_pk_mul_f32 v[66:67], v[86:87], v[86:87]
	v_lshlrev_b32_e32 v88, 16, v142
	v_and_b32_e32 v89, 0xffff0000, v142
	v_lshlrev_b32_e32 v90, 16, v143
	v_lshlrev_b32_e32 v92, 16, v144
	v_pk_fma_f32 v[66:67], v[84:85], v[84:85], v[66:67]
	v_mul_f32_e32 v93, v88, v88
	v_mul_f32_e32 v175, v89, v89
	v_and_b32_e32 v91, 0xffff0000, v143
	v_mul_f32_e32 v64, v90, v90
	v_mov_b32_e32 v174, v92
	v_pk_add_f32 v[66:67], v[66:67], v[66:67] op_sel_hi:[0,1]
	v_pk_fma_f32 v[176:177], v[90:91], v[90:91], v[64:65] op_sel_hi:[1,1,0]
	v_and_b32_e32 v99, 0xffff0000, v144
	v_lshlrev_b32_e32 v94, 16, v145
	v_and_b32_e32 v95, 0xffff0000, v145
	v_pk_add_f32 v[174:175], v[92:93], v[174:175]
	v_mul_f32_e32 v176, v99, v99
	v_mul_f32_e32 v66, v94, v94
	v_mul_f32_e32 v64, v95, v95
	v_mul_f32_e32 v178, v92, v92
	v_mov_b32_e32 v179, v175
	v_pk_add_f32 v[174:175], v[178:179], v[176:177]
	v_pk_add_f32 v[64:65], v[66:67], v[64:65]
	s_add_u32 s5, s60, s38
	v_pk_add_f32 v[64:65], v[174:175], v[64:65]
	s_addc_u32 s6, 0, s39
	v_add_f32_e32 v64, v64, v65
	ds_bpermute_b32 v65, v97, v64
	s_add_u32 s5, s5, 1
	s_addc_u32 s6, s6, 0
	s_add_u32 s7, s26, s38
	s_addc_u32 s28, s27, s39
	s_waitcnt lgkmcnt(0)
	v_add_f32_e32 v64, v64, v65
	ds_bpermute_b32 v65, v101, v64
	s_add_u32 s29, s7, 1
	s_addc_u32 s7, s28, 0
	s_cmp_lt_i32 s49, 0x8000
	s_cselect_b32 s7, s7, s6
	s_waitcnt lgkmcnt(0)
	v_add_f32_e32 v64, v64, v65
	ds_bpermute_b32 v65, v103, v64
	s_cselect_b32 s6, s29, s5
	v_mov_b32_e32 v174, v69
	v_mov_b32_e32 v175, v71
	s_cselect_b32 s5, s15, s71
	s_waitcnt lgkmcnt(0)
	v_add_f32_e32 v64, v64, v65
	ds_bpermute_b32 v65, v105, v64
	s_cselect_b32 s28, s14, s70
	s_lshl_b64 s[6:7], s[6:7], 13
	s_add_u32 s6, s28, s6
	s_addc_u32 s7, s5, s7
	s_waitcnt lgkmcnt(0)
	v_add_f32_e32 v64, v64, v65
	ds_bpermute_b32 v65, v107, v64
	v_lshlrev_b32_e32 v81, 4, v96
	v_mov_b32_e32 v69, v70
	v_lshlrev_b32_e32 v93, 4, v100
	s_mov_b32 s5, 0xa2f3000
	s_waitcnt lgkmcnt(0)
	v_add_f32_e32 v64, v64, v65
	ds_bpermute_b32 v65, v129, v64
	s_waitcnt lgkmcnt(0)
	v_add_f32_e32 v64, v64, v65
	v_fmamk_f32 v64, v64, 0x3a000000, v172
	v_cmp_gt_f32_e32 vcc, s58, v64
	v_mul_f32_e32 v65, 0x4b800000, v64
	s_nop 0
	v_cndmask_b32_e32 v64, v64, v65, vcc
	v_rsq_f32_e32 v64, v64
	s_nop 0
	v_mul_f32_e32 v65, 0x45800000, v64
	v_cndmask_b32_e32 v64, v64, v65, vcc
	v_mul_f32_e32 v166, 0.5, v64
	global_load_dwordx4 v[64:67], v[108:109], off
	s_waitcnt vmcnt(0)
	v_pk_mul_f32 v[64:65], v[174:175], v[64:65]
	v_mov_b32_e32 v174, v169
	v_mov_b32_e32 v175, v171
	v_pk_mul_f32 v[66:67], v[174:175], v[66:67]
	v_pk_fma_f32 v[64:65], v[64:65], v[166:167], v[4:5] op_sel_hi:[1,0,1]
	v_pk_fma_f32 v[66:67], v[66:67], v[166:167], v[6:7] op_sel_hi:[1,0,1]
	global_store_dwordx4 v81, v[64:67], s[6:7] nt
	global_load_dwordx4 v[174:177], v[108:109], off offset:1024
	v_mov_b32_e32 v169, v170
	s_waitcnt vmcnt(0)
	v_pk_mul_f32 v[168:169], v[168:169], v[176:177]
	v_pk_mul_f32 v[68:69], v[68:69], v[174:175]
	v_pk_fma_f32 v[70:71], v[168:169], v[166:167], v[10:11] op_sel_hi:[1,0,1]
	v_pk_fma_f32 v[68:69], v[68:69], v[166:167], v[8:9] op_sel_hi:[1,0,1]
	global_store_dwordx4 v81, v[68:71], s[6:7] offset:1024 nt
	global_load_dwordx4 v[168:171], v[108:109], off offset:2048
	v_mov_b32_e32 v174, v73
	v_mov_b32_e32 v175, v75
	v_mov_b32_e32 v73, v74
	s_waitcnt vmcnt(0)
	v_pk_mul_f32 v[170:171], v[170:171], v[174:175]
	v_pk_mul_f32 v[72:73], v[168:169], v[72:73]
	v_pk_fma_f32 v[74:75], v[170:171], v[166:167], v[14:15] op_sel_hi:[1,0,1]
	v_pk_fma_f32 v[72:73], v[72:73], v[166:167], v[12:13] op_sel_hi:[1,0,1]
	global_store_dwordx4 v81, v[72:75], s[6:7] offset:2048 nt
	global_load_dwordx4 v[168:171], v[108:109], off offset:3072
	v_mov_b32_e32 v174, v85
	v_mov_b32_e32 v175, v87
	v_mov_b32_e32 v85, v86
	s_waitcnt vmcnt(0)
; __device__ __forceinline__ unsigned pk2(float lo, float hi) { return f2bf(lo) | (f2bf(hi) << 16); }
; template <int MODE>
; __device__ __forceinline__ void row_finish(const Params& p, int r, int lane, const float* gpost, const float* gnext, bf16_t* U, float coef, f32x4 (&h)[8], const u32x2 (&dw)[8]) {
;     ...
;         for (int j = 0; j < 8; ++j) { const f32x4 g = ((const f32x4*)gpost)[lane + 64 * j]; h[j] = h[j] + d[j] * g * rs; __builtin_nontemporal_store(h[j], &hd[lane + 64 * j]); }
;     }
;     if (MODE != 3) {
;         float s2 = 0.f;
; #pragma unroll
;         for (int j = 0; j < 8; ++j) s2 += (h[j].x * h[j].x + h[j].y * h[j].y) + (h[j].z * h[j].z + h[j].w * h[j].w);
;         s2 = wave_sum(s2);
;         const float rs2 = rsqrtf(s2 * (1.f / DM) + EPS);
;         u32x2* up = (u32x2*)(U + (size_t)r * DM);
; #pragma unroll
;         for (int j = 0; j < 8; ++j) { const f32x4 g = ((const f32x4*)gnext)[lane + 64 * j]; const f32x4 v = h[j] * g * rs2;
;             u32x2 w; w.x = pk2(v.x, v.y); w.y = pk2(v.z, v.w); up[lane + 64 * j] = w; }
	v_pk_mul_f32 v[78:79], v[78:79], v[170:171]
	v_pk_mul_f32 v[76:77], v[76:77], v[168:169]
	v_pk_fma_f32 v[78:79], v[78:79], v[166:167], v[18:19] op_sel_hi:[1,0,1]
	v_pk_fma_f32 v[76:77], v[76:77], v[166:167], v[16:17] op_sel_hi:[1,0,1]
	global_store_dwordx4 v81, v[76:79], s[6:7] offset:3072 nt
	global_load_dwordx4 v[168:171], v[110:111], off
	v_mov_b32_e32 v81, v173
	s_waitcnt vmcnt(0)
	v_pk_mul_f32 v[80:81], v[80:81], v[168:169]
	v_pk_mul_f32 v[82:83], v[82:83], v[170:171]
	v_pk_fma_f32 v[80:81], v[80:81], v[166:167], v[20:21] op_sel_hi:[1,0,1]
	v_pk_fma_f32 v[82:83], v[82:83], v[166:167], v[22:23] op_sel_hi:[1,0,1]
	global_store_dwordx4 v93, v[80:83], s[6:7] nt
	global_load_dwordx4 v[168:171], v[112:113], off
	v_lshlrev_b32_e32 v93, 4, v102
	s_waitcnt vmcnt(0)
	v_pk_mul_f32 v[170:171], v[170:171], v[174:175]
	v_pk_mul_f32 v[84:85], v[168:169], v[84:85]
	v_pk_fma_f32 v[86:87], v[166:167], v[170:171], v[26:27] op_sel_hi:[0,1,1]
	v_pk_fma_f32 v[84:85], v[166:167], v[84:85], v[24:25] op_sel_hi:[0,1,1]
	global_store_dwordx4 v93, v[84:87], s[6:7] nt
	global_load_dwordx4 v[168:171], v[114:115], off
	v_lshlrev_b32_e32 v93, 4, v104
	v_mov_b32_e32 v174, v67
	v_mov_b32_e32 v175, v71
	v_pk_mul_f32 v[174:175], v[174:175], v[174:175]
	s_waitcnt vmcnt(0)
	v_pk_mul_f32 v[90:91], v[90:91], v[170:171]
	v_pk_mul_f32 v[88:89], v[88:89], v[168:169]
	v_pk_fma_f32 v[90:91], v[166:167], v[90:91], v[30:31] op_sel_hi:[0,1,1]
	v_pk_fma_f32 v[88:89], v[166:167], v[88:89], v[28:29] op_sel_hi:[0,1,1]
	global_store_dwordx4 v93, v[88:91], s[6:7] nt
	global_load_dwordx4 v[168:171], v[116:117], off
	v_mov_b32_e32 v93, v99
	v_lshlrev_b32_e32 v99, 4, v106
	s_waitcnt vmcnt(0)
	v_pk_mul_f32 v[94:95], v[94:95], v[170:171]
	v_mov_b32_e32 v170, v65
	v_mov_b32_e32 v171, v69
	v_pk_mul_f32 v[92:93], v[92:93], v[168:169]
	v_mov_b32_e32 v168, v64
	v_mov_b32_e32 v169, v68
	v_pk_mul_f32 v[170:171], v[170:171], v[170:171]
	v_pk_fma_f32 v[94:95], v[166:167], v[94:95], v[34:35] op_sel_hi:[0,1,1]
	v_pk_fma_f32 v[168:169], v[168:169], v[168:169], v[170:171]
	v_mov_b32_e32 v170, v66
	v_mov_b32_e32 v171, v70
	v_pk_fma_f32 v[170:171], v[170:171], v[170:171], v[174:175]
	v_pk_mul_f32 v[174:175], v[74:75], v[74:75]
	v_pk_add_f32 v[168:169], v[168:169], v[170:171]
	v_pk_mul_f32 v[170:171], v[72:73], v[72:73]
	v_pk_fma_f32 v[92:93], v[166:167], v[92:93], v[32:33] op_sel_hi:[0,1,1]
	v_pk_mov_b32 v[176:177], v[170:171], v[174:175] op_sel:[1,0]
	v_mov_b32_e32 v171, v175
	v_mul_f32_e32 v166, v76, v76
	v_pk_add_f32 v[170:171], v[176:177], v[170:171]
	v_pk_fma_f32 v[174:175], v[76:77], v[76:77], v[166:167] op_sel_hi:[1,1,0]
	v_mul_f32_e32 v166, v78, v78
	v_pk_add_f32 v[168:169], v[168:169], v[168:169] op_sel_hi:[0,1]
	v_pk_add_f32 v[170:171], v[170:171], v[170:171] op_sel_hi:[0,1]
	v_pk_fma_f32 v[176:177], v[78:79], v[78:79], v[166:167] op_sel_hi:[1,1,0]
	v_mul_f32_e32 v174, v80, v80
	v_mul_f32_e32 v176, v81, v81
	v_mul_f32_e32 v170, v82, v82
	v_mul_f32_e32 v168, v83, v83
	v_pk_add_f32 v[174:175], v[174:175], v[176:177]
	v_pk_add_f32 v[168:169], v[170:171], v[168:169]
	v_pk_mul_f32 v[170:171], v[84:85], v[84:85]
	v_pk_add_f32 v[168:169], v[174:175], v[168:169]
	v_pk_mul_f32 v[174:175], v[86:87], v[86:87]
	v_mul_f32_e32 v166, v88, v88
	v_pk_mov_b32 v[176:177], v[170:171], v[174:175] op_sel:[1,0]
	v_mov_b32_e32 v171, v175
	v_pk_add_f32 v[170:171], v[176:177], v[170:171]
	v_pk_fma_f32 v[174:175], v[88:89], v[88:89], v[166:167] op_sel_hi:[1,1,0]
	v_mul_f32_e32 v166, v90, v90
	v_pk_add_f32 v[168:169], v[168:169], v[168:169] op_sel_hi:[0,1]
	v_pk_add_f32 v[170:171], v[170:171], v[170:171] op_sel_hi:[0,1]
	v_pk_fma_f32 v[176:177], v[90:91], v[90:91], v[166:167] op_sel_hi:[1,1,0]
	v_mul_f32_e32 v174, v92, v92
	v_mul_f32_e32 v176, v93, v93
	v_mul_f32_e32 v170, v94, v94
	v_mul_f32_e32 v168, v95, v95
	v_pk_add_f32 v[174:175], v[174:175], v[176:177]
	v_pk_add_f32 v[168:169], v[170:171], v[168:169]
	global_store_dwordx4 v99, v[92:95], s[6:7] nt
	v_pk_add_f32 v[168:169], v[174:175], v[168:169]
	s_mov_b64 s[6:7], 0
	v_add_f32_e32 v99, v168, v169
	global_load_dwordx4 v[168:171], v[118:119], off
	ds_bpermute_b32 v166, v97, v99
	s_waitcnt lgkmcnt(0)
	v_add_f32_e32 v99, v99, v166
	ds_bpermute_b32 v166, v101, v99
	s_waitcnt lgkmcnt(0)
	v_add_f32_e32 v99, v99, v166
	ds_bpermute_b32 v166, v103, v99
	s_waitcnt lgkmcnt(0)
	v_add_f32_e32 v99, v99, v166
	ds_bpermute_b32 v166, v105, v99
	s_waitcnt lgkmcnt(0)
	v_add_f32_e32 v99, v99, v166
	ds_bpermute_b32 v166, v107, v99
	s_waitcnt lgkmcnt(0)
	v_add_f32_e32 v99, v99, v166
	ds_bpermute_b32 v166, v129, v99
	s_waitcnt lgkmcnt(0)
	v_add_f32_e32 v99, v99, v166
	v_fmamk_f32 v99, v99, 0x3a000000, v172
	v_cmp_gt_f32_e32 vcc, s58, v99
	v_mul_f32_e32 v166, 0x4b800000, v99
	s_waitcnt vmcnt(0)
	v_pk_mul_f32 v[168:169], v[64:65], v[168:169]
	v_cndmask_b32_e32 v99, v99, v166, vcc
	v_rsq_f32_e32 v99, v99
	v_pk_mul_f32 v[170:171], v[66:67], v[170:171]
	v_mul_f32_e32 v166, 0x45800000, v99
	v_cndmask_b32_e32 v166, v99, v166, vcc
	v_pk_mul_f32 v[168:169], v[168:169], v[166:167] op_sel_hi:[1,0]
	v_pk_mul_f32 v[170:171], v[170:171], v[166:167] op_sel_hi:[1,0]
	v_bfe_u32 v99, v168, 16, 1
	v_add3_u32 v99, v168, v99, s56
	v_bfe_u32 v168, v169, 16, 1
	v_lshrrev_b32_e32 v99, 16, v99
	v_add3_u32 v168, v169, v168, s56
	v_and_or_b32 v168, v168, s57, v99
	v_bfe_u32 v99, v170, 16, 1
	v_bfe_u32 v169, v171, 16, 1
	v_add3_u32 v99, v170, v99, s56
	v_add3_u32 v169, v171, v169, s56
	v_lshl_add_u64 v[170:171], s[46:47], 0, v[162:163]
	v_lshrrev_b32_e32 v99, 16, v99
	v_add_co_u32_e32 v178, vcc, s31, v170
	v_and_or_b32 v169, v169, s57, v99
	s_nop 0
	v_addc_co_u32_e32 v179, vcc, 0, v171, vcc
	global_store_dwordx2 v[178:179], v[168:169], off offset:3328
	global_load_dwordx4 v[174:177], v[118:119], off offset:1024
	s_waitcnt vmcnt(0)
; __device__ __forceinline__ unsigned pk2(float lo, float hi) { return f2bf(lo) | (f2bf(hi) << 16); }
; template <int MODE>
; __device__ __forceinline__ void row_finish(const Params& p, int r, int lane, const float* gpost, const float* gnext, bf16_t* U, float coef, f32x4 (&h)[8], const u32x2 (&dw)[8]) {
;     ...
;     if (r >= ROWS) { if (MODE != 3) { u32x4* up = (u32x4*)(U + (size_t)r * DM);
; #pragma unroll
;             for (int j = 0; j < 4; ++j) up[lane + 64 * j] = (u32x4){0u, 0u, 0u, 0u}; } return; }
;     ...
;         for (int j = 0; j < 8; ++j) { const f32x4 g = ((const f32x4*)gnext)[lane + 64 * j]; const f32x4 v = h[j] * g * rs2;
;             u32x2 w; w.x = pk2(v.x, v.y); w.y = pk2(v.z, v.w); up[lane + 64 * j] = w; }
;     ...
;         for (int k = 0; k < 8; k += 2) {
;             f32x4 ha[8], hb[8]; u32x2 da[8], db[8];
;             row_load<MODE>(p, r0 + k, lane, Dsrc, ha, da);
;             row_load<MODE>(p, r0 + k + 1, lane, Dsrc, hb, db);
;             row_finish<MODE>(p, r0 + k, lane, gpost, gnext, U, coef, ha, da);
;             row_finish<MODE>(p, r0 + k + 1, lane, gpost, gnext, U, coef, hb, db);
;         }
	v_pk_mul_f32 v[168:169], v[68:69], v[174:175]
	s_nop 0
	v_pk_mul_f32 v[168:169], v[168:169], v[166:167] op_sel_hi:[1,0]
	v_pk_mul_f32 v[174:175], v[70:71], v[176:177]
	v_bfe_u32 v99, v168, 16, 1
	v_add3_u32 v99, v168, v99, s56
	v_bfe_u32 v168, v169, 16, 1
	v_pk_mul_f32 v[174:175], v[174:175], v[166:167] op_sel_hi:[1,0]
	v_lshrrev_b32_e32 v99, 16, v99
	v_add3_u32 v168, v169, v168, s56
	v_and_or_b32 v168, v168, s57, v99
	v_bfe_u32 v99, v174, 16, 1
	v_add3_u32 v99, v174, v99, s56
	v_bfe_u32 v169, v175, 16, 1
	v_lshrrev_b32_e32 v99, 16, v99
	v_add3_u32 v169, v175, v169, s56
	v_and_or_b32 v169, v169, s57, v99
	global_store_dwordx2 v[178:179], v[168:169], off offset:3840
	global_load_dwordx4 v[174:177], v[118:119], off offset:2048
	s_waitcnt vmcnt(0)
	v_pk_mul_f32 v[168:169], v[72:73], v[174:175]
	s_nop 0
	v_pk_mul_f32 v[168:169], v[168:169], v[166:167] op_sel_hi:[1,0]
	v_pk_mul_f32 v[174:175], v[74:75], v[176:177]
	v_bfe_u32 v99, v168, 16, 1
	v_add3_u32 v99, v168, v99, s56
	v_bfe_u32 v168, v169, 16, 1
	v_pk_mul_f32 v[174:175], v[174:175], v[166:167] op_sel_hi:[1,0]
	v_lshrrev_b32_e32 v99, 16, v99
	v_add3_u32 v168, v169, v168, s56
	v_and_or_b32 v176, v168, s57, v99
	v_bfe_u32 v99, v174, 16, 1
	v_add3_u32 v99, v174, v99, s56
	v_bfe_u32 v168, v175, 16, 1
	v_lshrrev_b32_e32 v99, 16, v99
	v_add3_u32 v168, v175, v168, s56
	v_and_or_b32 v177, v168, s57, v99
	v_add_co_u32_e32 v168, vcc, s5, v170
	s_nop 1
	v_addc_co_u32_e32 v169, vcc, 0, v171, vcc
	global_store_dwordx2 v[168:169], v[176:177], off offset:256
	global_load_dwordx4 v[174:177], v[118:119], off offset:3072
	s_waitcnt vmcnt(0)
	v_pk_mul_f32 v[170:171], v[76:77], v[174:175]
	s_nop 0
	v_pk_mul_f32 v[170:171], v[170:171], v[166:167] op_sel_hi:[1,0]
	v_pk_mul_f32 v[174:175], v[78:79], v[176:177]
	v_bfe_u32 v99, v170, 16, 1
	v_add3_u32 v99, v170, v99, s56
	v_bfe_u32 v170, v171, 16, 1
	v_pk_mul_f32 v[174:175], v[174:175], v[166:167] op_sel_hi:[1,0]
	v_lshrrev_b32_e32 v99, 16, v99
	v_add3_u32 v170, v171, v170, s56
	v_and_or_b32 v170, v170, s57, v99
	v_bfe_u32 v99, v174, 16, 1
	v_add3_u32 v99, v174, v99, s56
	v_bfe_u32 v171, v175, 16, 1
	v_lshrrev_b32_e32 v99, 16, v99
	v_add3_u32 v171, v175, v171, s56
	v_and_or_b32 v171, v171, s57, v99
	global_store_dwordx2 v[168:169], v[170:171], off offset:768
	global_load_dwordx4 v[174:177], v[120:121], off
	s_waitcnt vmcnt(0)
	v_pk_mul_f32 v[170:171], v[80:81], v[174:175]
	s_nop 0
	v_pk_mul_f32 v[170:171], v[170:171], v[166:167] op_sel_hi:[1,0]
	v_pk_mul_f32 v[174:175], v[82:83], v[176:177]
	v_bfe_u32 v99, v170, 16, 1
	v_add3_u32 v99, v170, v99, s56
	v_bfe_u32 v170, v171, 16, 1
	v_pk_mul_f32 v[174:175], v[174:175], v[166:167] op_sel_hi:[1,0]
	v_lshrrev_b32_e32 v99, 16, v99
	v_add3_u32 v170, v171, v170, s56
	v_and_or_b32 v170, v170, s57, v99
	v_bfe_u32 v99, v174, 16, 1
	v_add3_u32 v99, v174, v99, s56
	v_bfe_u32 v171, v175, 16, 1
	v_lshrrev_b32_e32 v99, 16, v99
	v_add3_u32 v171, v175, v171, s56
	v_and_or_b32 v171, v171, s57, v99
	global_store_dwordx2 v[168:169], v[170:171], off offset:1280
	global_load_dwordx4 v[174:177], v[122:123], off
	s_waitcnt vmcnt(0)
	v_pk_mul_f32 v[170:171], v[84:85], v[174:175]
	s_nop 0
	v_pk_mul_f32 v[170:171], v[170:171], v[166:167] op_sel_hi:[1,0]
	v_pk_mul_f32 v[174:175], v[86:87], v[176:177]
	v_bfe_u32 v99, v170, 16, 1
	v_add3_u32 v99, v170, v99, s56
	v_bfe_u32 v170, v171, 16, 1
	v_pk_mul_f32 v[174:175], v[174:175], v[166:167] op_sel_hi:[1,0]
	v_lshrrev_b32_e32 v99, 16, v99
	v_add3_u32 v170, v171, v170, s56
	v_and_or_b32 v170, v170, s57, v99
	v_bfe_u32 v99, v174, 16, 1
	v_add3_u32 v99, v174, v99, s56
	v_bfe_u32 v171, v175, 16, 1
	v_lshrrev_b32_e32 v99, 16, v99
	v_add3_u32 v171, v175, v171, s56
	v_and_or_b32 v171, v171, s57, v99
	global_store_dwordx2 v[168:169], v[170:171], off offset:1792
	global_load_dwordx4 v[174:177], v[124:125], off
	s_waitcnt vmcnt(0)
	v_pk_mul_f32 v[170:171], v[88:89], v[174:175]
	s_nop 0
	v_pk_mul_f32 v[170:171], v[170:171], v[166:167] op_sel_hi:[1,0]
	v_pk_mul_f32 v[174:175], v[90:91], v[176:177]
	v_bfe_u32 v99, v170, 16, 1
	v_add3_u32 v99, v170, v99, s56
	v_bfe_u32 v170, v171, 16, 1
	v_pk_mul_f32 v[174:175], v[174:175], v[166:167] op_sel_hi:[1,0]
	v_lshrrev_b32_e32 v99, 16, v99
	v_add3_u32 v170, v171, v170, s56
	v_and_or_b32 v170, v170, s57, v99
	v_bfe_u32 v99, v174, 16, 1
	v_add3_u32 v99, v174, v99, s56
	v_bfe_u32 v171, v175, 16, 1
	v_lshrrev_b32_e32 v99, 16, v99
	v_add3_u32 v171, v175, v171, s56
	v_and_or_b32 v171, v171, s57, v99
	global_store_dwordx2 v[168:169], v[170:171], off offset:2304
	global_load_dwordx4 v[174:177], v[126:127], off
	s_waitcnt vmcnt(0)
	v_pk_mul_f32 v[170:171], v[92:93], v[174:175]
	s_nop 0
	v_pk_mul_f32 v[170:171], v[170:171], v[166:167] op_sel_hi:[1,0]
	v_pk_mul_f32 v[174:175], v[94:95], v[176:177]
	v_bfe_u32 v99, v170, 16, 1
	v_pk_mul_f32 v[174:175], v[174:175], v[166:167] op_sel_hi:[1,0]
	v_add3_u32 v99, v170, v99, s56
	v_bfe_u32 v166, v171, 16, 1
	v_lshrrev_b32_e32 v99, 16, v99
	v_add3_u32 v166, v171, v166, s56
	v_and_or_b32 v170, v166, s57, v99
	v_bfe_u32 v99, v174, 16, 1
	v_add3_u32 v99, v174, v99, s56
	v_bfe_u32 v166, v175, 16, 1
	v_lshrrev_b32_e32 v99, 16, v99
	v_add3_u32 v166, v175, v166, s56
	v_and_or_b32 v171, v166, s57, v99
	global_store_dwordx2 v[168:169], v[170:171], off offset:2816
.LBB0_425:
	s_andn2_b64 vcc, exec, s[6:7]
	s_cbranch_vccnz .LBB0_396
	v_lshl_add_u64 v[64:65], s[46:47], 0, v[164:165]
	v_add_co_u32_e32 v66, vcc, 0xa2f2000, v64
	s_mov_b32 s6, s4
	s_nop 0
	v_addc_co_u32_e32 v67, vcc, 0, v65, vcc
	s_mov_b32 s7, s4
	s_mov_b32 s5, s4
	v_mov_b64_e32 v[70:71], s[6:7]
	v_add_co_u32_e32 v64, vcc, 0xa2f3000, v64
	v_mov_b64_e32 v[68:69], s[4:5]
	s_nop 0
	v_addc_co_u32_e32 v65, vcc, 0, v65, vcc
	global_store_dwordx4 v[66:67], v[68:71], off offset:3328
	global_store_dwordx4 v[64:65], v[68:71], off offset:256
	global_store_dwordx4 v[64:65], v[68:71], off offset:1280
	global_store_dwordx4 v[64:65], v[68:71], off offset:2304
	s_waitcnt vmcnt(0)
	v_mov_b64_e32 v[66:67], v[6:7]
	v_mov_b64_e32 v[74:75], v[14:15]
	v_mov_b64_e32 v[70:71], v[10:11]
	v_mov_b64_e32 v[78:79], v[18:19]
	v_mov_b64_e32 v[82:83], v[22:23]
	v_mov_b64_e32 v[86:87], v[26:27]
	v_mov_b64_e32 v[90:91], v[30:31]
	v_mov_b64_e32 v[94:95], v[34:35]
	v_mov_b64_e32 v[64:65], v[4:5]
	v_mov_b64_e32 v[68:69], v[8:9]
	v_mov_b64_e32 v[72:73], v[12:13]
	v_mov_b64_e32 v[76:77], v[16:17]
	v_mov_b64_e32 v[80:81], v[20:21]
	v_mov_b64_e32 v[84:85], v[24:25]
	v_mov_b64_e32 v[88:89], v[28:29]
	v_mov_b64_e32 v[92:93], v[32:33]
	s_branch .LBB0_396

; template <int MODE>
; __device__ __forceinline__ void row_finish(const Params& p, int r, int lane, const float* gpost, const float* gnext, bf16_t* U, float coef, f32x4 (&h)[8], const u32x2 (&dw)[8]) {
;     ...
;     if (MODE >= 1) {
;         f32x4 d[8]; float ss = 0.f;
; #pragma unroll
;         for (int j = 0; j < 8; ++j) { const u32x2 w = dw[j]; d[j] = (f32x4){bflo(w.x), bfhi(w.x), bflo(w.y), bfhi(w.y)};
;             ss += (d[j].x * d[j].x + d[j].y * d[j].y) + (d[j].z * d[j].z + d[j].w * d[j].w); }
;         ss = wave_sum(ss);
;         const float rs = rsqrtf(ss * (1.f / DM) + EPS) * coef;
;         f32x4* hd = (f32x4*)hrow(p, r);
; #pragma unroll
;         for (int j = 0; j < 8; ++j) { const f32x4 g = ((const f32x4*)gpost)[lane + 64 * j]; h[j] = h[j] + d[j] * g * rs; __builtin_nontemporal_store(h[j], &hd[lane + 64 * j]); }
.LBB0_456:
	s_andn2_b64 vcc, exec, s[6:7]
	s_mov_b64 s[6:7], -1
	s_cbranch_vccnz .LBB0_458
	s_waitcnt vmcnt(0) lgkmcnt(0)
	v_and_b32_e32 v169, 0xffff0000, v146
	v_and_b32_e32 v168, 0xffff0000, v148
	v_and_b32_e32 v171, 0xffff0000, v147
	v_and_b32_e32 v170, 0xffff0000, v149
	v_lshlrev_b32_e32 v71, 16, v146
	v_lshlrev_b32_e32 v70, 16, v148
	v_lshlrev_b32_e32 v69, 16, v147
	v_lshlrev_b32_e32 v68, 16, v149
	v_pk_mul_f32 v[64:65], v[168:169], v[168:169]
	v_pk_mul_f32 v[66:67], v[170:171], v[170:171]
	v_pk_fma_f32 v[64:65], v[70:71], v[70:71], v[64:65]
	v_pk_fma_f32 v[66:67], v[68:69], v[68:69], v[66:67]
	v_and_b32_e32 v73, 0xffff0000, v151
	v_pk_add_f32 v[64:65], v[64:65], v[66:67]
	v_and_b32_e32 v72, 0xffff0000, v150
	v_pk_add_f32 v[64:65], v[64:65], v[64:65] op_sel_hi:[0,1]
	v_lshlrev_b32_e32 v75, 16, v151
	v_lshlrev_b32_e32 v74, 16, v150
	v_pk_mul_f32 v[66:67], v[72:73], v[72:73]
	v_lshlrev_b32_e32 v76, 16, v152
	v_and_b32_e32 v77, 0xffff0000, v152
	v_lshlrev_b32_e32 v78, 16, v153
	v_lshlrev_b32_e32 v80, 16, v154
	v_pk_fma_f32 v[66:67], v[74:75], v[74:75], v[66:67]
	v_mul_f32_e32 v81, v76, v76
	v_mul_f32_e32 v85, v77, v77
	v_and_b32_e32 v79, 0xffff0000, v153
	v_mul_f32_e32 v64, v78, v78
	v_mov_b32_e32 v84, v80
	v_pk_add_f32 v[66:67], v[66:67], v[66:67] op_sel_hi:[0,1]
	v_pk_fma_f32 v[86:87], v[78:79], v[78:79], v[64:65] op_sel_hi:[1,1,0]
	v_and_b32_e32 v173, 0xffff0000, v154
	v_lshlrev_b32_e32 v82, 16, v155
	v_and_b32_e32 v83, 0xffff0000, v155
	v_pk_add_f32 v[84:85], v[80:81], v[84:85]
	v_mul_f32_e32 v86, v173, v173
	v_mul_f32_e32 v66, v82, v82
	v_mul_f32_e32 v64, v83, v83
	v_mul_f32_e32 v88, v80, v80
	v_mov_b32_e32 v89, v85
	v_pk_add_f32 v[84:85], v[88:89], v[86:87]
	v_pk_add_f32 v[64:65], v[66:67], v[64:65]
	v_and_b32_e32 v87, 0xffff0000, v157
	v_pk_add_f32 v[64:65], v[84:85], v[64:65]
	v_and_b32_e32 v86, 0xffff0000, v156
	v_pk_add_f32 v[64:65], v[64:65], v[64:65] op_sel_hi:[0,1]
	v_lshlrev_b32_e32 v85, 16, v157
	v_lshlrev_b32_e32 v84, 16, v156
	v_pk_mul_f32 v[66:67], v[86:87], v[86:87]
	v_lshlrev_b32_e32 v88, 16, v158
	v_and_b32_e32 v89, 0xffff0000, v158
	v_lshlrev_b32_e32 v90, 16, v159
	v_lshlrev_b32_e32 v92, 16, v160
	v_pk_fma_f32 v[66:67], v[84:85], v[84:85], v[66:67]
	v_mul_f32_e32 v93, v88, v88
	v_mul_f32_e32 v175, v89, v89
	v_and_b32_e32 v91, 0xffff0000, v159
	v_mul_f32_e32 v64, v90, v90
	v_mov_b32_e32 v174, v92
	v_pk_add_f32 v[66:67], v[66:67], v[66:67] op_sel_hi:[0,1]
	v_pk_fma_f32 v[176:177], v[90:91], v[90:91], v[64:65] op_sel_hi:[1,1,0]
	v_and_b32_e32 v172, 0xffff0000, v160
	v_lshlrev_b32_e32 v94, 16, v161
	v_and_b32_e32 v95, 0xffff0000, v161
	v_pk_add_f32 v[174:175], v[92:93], v[174:175]
	v_mul_f32_e32 v176, v172, v172
	v_mul_f32_e32 v66, v94, v94
	v_mul_f32_e32 v64, v95, v95
	v_mul_f32_e32 v178, v92, v92
	v_mov_b32_e32 v179, v175
	v_pk_add_f32 v[174:175], v[178:179], v[176:177]
	v_pk_add_f32 v[64:65], v[66:67], v[64:65]
	s_add_u32 s5, s60, s38
	v_pk_add_f32 v[64:65], v[174:175], v[64:65]
	s_addc_u32 s6, 0, s39
	v_add_f32_e32 v64, v64, v65
	ds_bpermute_b32 v65, v97, v64
	s_add_u32 s48, s24, s38
	s_addc_u32 s7, s25, s39
	s_cmp_lt_i32 s61, 0x8000
	s_cselect_b32 s7, s7, s6
	s_waitcnt lgkmcnt(0)
	v_add_f32_e32 v64, v64, v65
	ds_bpermute_b32 v65, v101, v64
	s_cselect_b32 s6, s48, s5
	v_mov_b32_e32 v174, v71
	v_mov_b32_e32 v175, v169
	s_cselect_b32 s5, s15, s71
	s_waitcnt lgkmcnt(0)
	v_add_f32_e32 v64, v64, v65
	ds_bpermute_b32 v65, v103, v64
	s_cselect_b32 s48, s14, s70
	s_lshl_b64 s[6:7], s[6:7], 13
	s_add_u32 s6, s48, s6
	s_addc_u32 s7, s5, s7
	s_waitcnt lgkmcnt(0)
	v_add_f32_e32 v64, v64, v65
	ds_bpermute_b32 v65, v105, v64
	v_lshlrev_b32_e32 v81, 4, v96
	v_mov_b32_e32 v71, v168
	v_lshlrev_b32_e32 v93, 4, v100
	s_waitcnt lgkmcnt(0)
	v_add_f32_e32 v64, v64, v65
	ds_bpermute_b32 v65, v107, v64
	s_waitcnt lgkmcnt(0)
	v_add_f32_e32 v64, v64, v65
	ds_bpermute_b32 v65, v129, v64
	s_waitcnt lgkmcnt(0)
	v_add_f32_e32 v64, v64, v65
	v_fmamk_f32 v64, v64, 0x3a000000, v167
	v_cmp_gt_f32_e32 vcc, s58, v64
	v_mul_f32_e32 v65, 0x4b800000, v64
	s_nop 0
	v_cndmask_b32_e32 v64, v64, v65, vcc
	v_rsq_f32_e32 v64, v64
	s_nop 0
	v_mul_f32_e32 v65, 0x45800000, v64
	v_cndmask_b32_e32 v64, v64, v65, vcc
	v_mul_f32_e32 v166, 0.5, v64
	global_load_dwordx4 v[64:67], v[108:109], off
	s_waitcnt vmcnt(0)
	v_pk_mul_f32 v[64:65], v[174:175], v[64:65]
	v_mov_b32_e32 v174, v69
	v_mov_b32_e32 v175, v171
	v_pk_mul_f32 v[66:67], v[174:175], v[66:67]
	v_pk_fma_f32 v[64:65], v[64:65], v[166:167], v[0:1] op_sel_hi:[1,0,1]
	v_pk_fma_f32 v[66:67], v[66:67], v[166:167], v[2:3] op_sel_hi:[1,0,1]
	global_store_dwordx4 v81, v[64:67], s[6:7] nt
	global_load_dwordx4 v[174:177], v[108:109], off offset:1024
	v_mov_b32_e32 v69, v170
	s_waitcnt vmcnt(0)
	v_pk_mul_f32 v[168:169], v[70:71], v[174:175]
	v_pk_mul_f32 v[68:69], v[68:69], v[176:177]
	v_mov_b32_e32 v174, v74
	v_pk_fma_f32 v[70:71], v[68:69], v[166:167], v[38:39] op_sel_hi:[1,0,1]
	v_pk_fma_f32 v[68:69], v[168:169], v[166:167], v[36:37] op_sel_hi:[1,0,1]
	global_store_dwordx4 v81, v[68:71], s[6:7] offset:1024 nt
	global_load_dwordx4 v[168:171], v[108:109], off offset:2048
	v_mov_b32_e32 v175, v72
	v_mov_b32_e32 v72, v75
	s_waitcnt vmcnt(0)
	v_pk_mul_f32 v[168:169], v[168:169], v[174:175]
	v_pk_mul_f32 v[72:73], v[170:171], v[72:73]
	v_mov_b32_e32 v174, v84
	v_pk_fma_f32 v[74:75], v[72:73], v[166:167], v[42:43] op_sel_hi:[1,0,1]
	v_pk_fma_f32 v[72:73], v[168:169], v[166:167], v[40:41] op_sel_hi:[1,0,1]
	global_store_dwordx4 v81, v[72:75], s[6:7] offset:2048 nt
	global_load_dwordx4 v[168:171], v[108:109], off offset:3072
	v_mov_b32_e32 v175, v86
	v_mov_b32_e32 v86, v85
	s_waitcnt vmcnt(0)
; __device__ __forceinline__ unsigned pk2(float lo, float hi) { return f2bf(lo) | (f2bf(hi) << 16); }
; template <int MODE>
; __device__ __forceinline__ void row_finish(const Params& p, int r, int lane, const float* gpost, const float* gnext, bf16_t* U, float coef, f32x4 (&h)[8], const u32x2 (&dw)[8]) {
;     ...
;         for (int j = 0; j < 8; ++j) { const f32x4 g = ((const f32x4*)gpost)[lane + 64 * j]; h[j] = h[j] + d[j] * g * rs; __builtin_nontemporal_store(h[j], &hd[lane + 64 * j]); }
;     }
;     if (MODE != 3) {
;         float s2 = 0.f;
; #pragma unroll
;         for (int j = 0; j < 8; ++j) s2 += (h[j].x * h[j].x + h[j].y * h[j].y) + (h[j].z * h[j].z + h[j].w * h[j].w);
;         s2 = wave_sum(s2);
;         const float rs2 = rsqrtf(s2 * (1.f / DM) + EPS);
;         u32x2* up = (u32x2*)(U + (size_t)r * DM);
; #pragma unroll
;         for (int j = 0; j < 8; ++j) { const f32x4 g = ((const f32x4*)gnext)[lane + 64 * j]; const f32x4 v = h[j] * g * rs2;
;             u32x2 w; w.x = pk2(v.x, v.y); w.y = pk2(v.z, v.w); up[lane + 64 * j] = w; }
	v_pk_mul_f32 v[78:79], v[78:79], v[170:171]
	v_pk_mul_f32 v[76:77], v[76:77], v[168:169]
	v_pk_fma_f32 v[78:79], v[78:79], v[166:167], v[46:47] op_sel_hi:[1,0,1]
	v_pk_fma_f32 v[76:77], v[76:77], v[166:167], v[44:45] op_sel_hi:[1,0,1]
	global_store_dwordx4 v81, v[76:79], s[6:7] offset:3072 nt
	global_load_dwordx4 v[168:171], v[110:111], off
	v_mov_b32_e32 v81, v173
	v_mov_b32_e32 v173, v71
	s_waitcnt vmcnt(0)
	v_pk_mul_f32 v[80:81], v[80:81], v[168:169]
	v_pk_mul_f32 v[82:83], v[82:83], v[170:171]
	v_pk_fma_f32 v[80:81], v[80:81], v[166:167], v[48:49] op_sel_hi:[1,0,1]
	v_pk_fma_f32 v[82:83], v[82:83], v[166:167], v[50:51] op_sel_hi:[1,0,1]
	global_store_dwordx4 v93, v[80:83], s[6:7] nt
	global_load_dwordx4 v[168:171], v[112:113], off
	v_lshlrev_b32_e32 v93, 4, v102
	s_waitcnt vmcnt(0)
	v_pk_mul_f32 v[168:169], v[168:169], v[174:175]
	v_pk_mul_f32 v[84:85], v[170:171], v[86:87]
	s_nop 0
	v_pk_fma_f32 v[86:87], v[166:167], v[84:85], v[54:55] op_sel_hi:[0,1,1]
	v_pk_fma_f32 v[84:85], v[166:167], v[168:169], v[52:53] op_sel_hi:[0,1,1]
	global_store_dwordx4 v93, v[84:87], s[6:7] nt
	global_load_dwordx4 v[168:171], v[114:115], off
	v_lshlrev_b32_e32 v93, 4, v104
	s_waitcnt vmcnt(0)
	v_pk_mul_f32 v[90:91], v[90:91], v[170:171]
	v_pk_mul_f32 v[88:89], v[88:89], v[168:169]
	v_pk_fma_f32 v[90:91], v[166:167], v[90:91], v[58:59] op_sel_hi:[0,1,1]
	v_pk_fma_f32 v[88:89], v[166:167], v[88:89], v[56:57] op_sel_hi:[0,1,1]
	global_store_dwordx4 v93, v[88:91], s[6:7] nt
	global_load_dwordx4 v[168:171], v[116:117], off
	v_mov_b32_e32 v93, v172
	v_mov_b32_e32 v172, v67
	v_pk_mul_f32 v[172:173], v[172:173], v[172:173]
	s_waitcnt vmcnt(0)
	v_pk_mul_f32 v[94:95], v[94:95], v[170:171]
	v_mov_b32_e32 v170, v65
	v_mov_b32_e32 v171, v69
	v_pk_mul_f32 v[92:93], v[92:93], v[168:169]
	v_mov_b32_e32 v168, v64
	v_mov_b32_e32 v169, v68
	v_pk_mul_f32 v[170:171], v[170:171], v[170:171]
	v_pk_fma_f32 v[94:95], v[166:167], v[94:95], v[62:63] op_sel_hi:[0,1,1]
	v_pk_fma_f32 v[168:169], v[168:169], v[168:169], v[170:171]
	v_mov_b32_e32 v170, v66
	v_mov_b32_e32 v171, v70
	v_pk_fma_f32 v[170:171], v[170:171], v[170:171], v[172:173]
	v_pk_fma_f32 v[92:93], v[166:167], v[92:93], v[60:61] op_sel_hi:[0,1,1]
	v_lshlrev_b32_e32 v166, 4, v106
	v_pk_add_f32 v[168:169], v[168:169], v[170:171]
	v_pk_mul_f32 v[170:171], v[72:73], v[72:73]
	v_pk_mul_f32 v[172:173], v[74:75], v[74:75]
	global_store_dwordx4 v166, v[92:95], s[6:7] nt
	v_pk_mov_b32 v[174:175], v[170:171], v[172:173] op_sel:[1,0]
	v_mov_b32_e32 v171, v173
	v_mul_f32_e32 v166, v76, v76
	v_pk_add_f32 v[170:171], v[174:175], v[170:171]
	v_pk_fma_f32 v[172:173], v[76:77], v[76:77], v[166:167] op_sel_hi:[1,1,0]
	v_mul_f32_e32 v166, v78, v78
	v_pk_add_f32 v[168:169], v[168:169], v[168:169] op_sel_hi:[0,1]
	v_pk_add_f32 v[170:171], v[170:171], v[170:171] op_sel_hi:[0,1]
	v_pk_fma_f32 v[174:175], v[78:79], v[78:79], v[166:167] op_sel_hi:[1,1,0]
	v_mul_f32_e32 v172, v80, v80
	v_mul_f32_e32 v174, v81, v81
	v_mul_f32_e32 v170, v82, v82
	v_mul_f32_e32 v168, v83, v83
	v_pk_add_f32 v[172:173], v[172:173], v[174:175]
	v_pk_add_f32 v[168:169], v[170:171], v[168:169]
	v_pk_mul_f32 v[170:171], v[84:85], v[84:85]
	v_pk_add_f32 v[168:169], v[172:173], v[168:169]
	v_pk_mul_f32 v[172:173], v[86:87], v[86:87]
	v_mul_f32_e32 v166, v88, v88
	v_pk_mov_b32 v[174:175], v[170:171], v[172:173] op_sel:[1,0]
	v_mov_b32_e32 v171, v173
	v_pk_add_f32 v[170:171], v[174:175], v[170:171]
	v_pk_fma_f32 v[172:173], v[88:89], v[88:89], v[166:167] op_sel_hi:[1,1,0]
	v_mul_f32_e32 v166, v90, v90
	v_pk_add_f32 v[168:169], v[168:169], v[168:169] op_sel_hi:[0,1]
	v_pk_add_f32 v[170:171], v[170:171], v[170:171] op_sel_hi:[0,1]
	v_pk_fma_f32 v[174:175], v[90:91], v[90:91], v[166:167] op_sel_hi:[1,1,0]
	v_mul_f32_e32 v172, v92, v92
	v_mul_f32_e32 v174, v93, v93
	v_mul_f32_e32 v170, v94, v94
	v_mul_f32_e32 v168, v95, v95
	v_pk_add_f32 v[172:173], v[172:173], v[174:175]
	v_pk_add_f32 v[168:169], v[170:171], v[168:169]
	s_mov_b64 s[6:7], 0
	v_pk_add_f32 v[168:169], v[172:173], v[168:169]
	s_nop 0
	v_add_f32_e32 v166, v168, v169
	ds_bpermute_b32 v168, v97, v166
	s_waitcnt lgkmcnt(0)
	v_add_f32_e32 v166, v166, v168
	ds_bpermute_b32 v168, v101, v166
	s_waitcnt lgkmcnt(0)
	v_add_f32_e32 v166, v166, v168
	ds_bpermute_b32 v168, v103, v166
	s_waitcnt lgkmcnt(0)
	v_add_f32_e32 v166, v166, v168
	ds_bpermute_b32 v168, v105, v166
	s_waitcnt lgkmcnt(0)
	v_add_f32_e32 v166, v166, v168
	ds_bpermute_b32 v168, v107, v166
	s_waitcnt lgkmcnt(0)
	v_add_f32_e32 v166, v166, v168
	ds_bpermute_b32 v168, v129, v166
	s_waitcnt lgkmcnt(0)
	v_add_f32_e32 v166, v166, v168
	v_fmamk_f32 v166, v166, 0x3a000000, v167
	v_cmp_gt_f32_e32 vcc, s58, v166
	v_mul_f32_e32 v168, 0x4b800000, v166
	s_nop 0
	v_cndmask_b32_e32 v166, v166, v168, vcc
	v_rsq_f32_e32 v166, v166
	s_nop 0
	v_mul_f32_e32 v168, 0x45800000, v166
	v_cndmask_b32_e32 v166, v166, v168, vcc
	global_load_dwordx4 v[168:171], v[118:119], off
	s_waitcnt vmcnt(0)
	v_pk_mul_f32 v[168:169], v[64:65], v[168:169]
	s_nop 0
	v_pk_mul_f32 v[168:169], v[168:169], v[166:167] op_sel_hi:[1,0]
	v_pk_mul_f32 v[170:171], v[66:67], v[170:171]
	v_bfe_u32 v172, v168, 16, 1
	v_add3_u32 v168, v168, v172, s56
	v_bfe_u32 v172, v169, 16, 1
	v_pk_mul_f32 v[170:171], v[170:171], v[166:167] op_sel_hi:[1,0]
	v_lshrrev_b32_e32 v168, 16, v168
	v_add3_u32 v169, v169, v172, s56
	v_and_or_b32 v168, v169, s57, v168
	v_bfe_u32 v169, v170, 16, 1
	v_add3_u32 v169, v170, v169, s56
	v_bfe_u32 v170, v171, 16, 1
	v_lshrrev_b32_e32 v169, 16, v169
	v_add3_u32 v170, v171, v170, s56
	v_and_or_b32 v169, v170, s57, v169
	v_lshl_add_u64 v[170:171], s[46:47], 0, v[162:163]
	v_add_co_u32_e32 v176, vcc, s30, v170
	s_nop 1
	v_addc_co_u32_e32 v177, vcc, 0, v171, vcc
	global_store_dwordx2 v[176:177], v[168:169], off offset:3328
	global_load_dwordx4 v[172:175], v[118:119], off offset:1024
	s_waitcnt vmcnt(0)
; __device__ __forceinline__ unsigned pk2(float lo, float hi) { return f2bf(lo) | (f2bf(hi) << 16); }
; template <int MODE>
; __device__ __forceinline__ void row_finish(const Params& p, int r, int lane, const float* gpost, const float* gnext, bf16_t* U, float coef, f32x4 (&h)[8], const u32x2 (&dw)[8]) {
;     ...
;         for (int j = 0; j < 8; ++j) { const f32x4 g = ((const f32x4*)gnext)[lane + 64 * j]; const f32x4 v = h[j] * g * rs2;
;             u32x2 w; w.x = pk2(v.x, v.y); w.y = pk2(v.z, v.w); up[lane + 64 * j] = w; }
	v_pk_mul_f32 v[168:169], v[68:69], v[172:173]
	s_nop 0
	v_pk_mul_f32 v[168:169], v[168:169], v[166:167] op_sel_hi:[1,0]
	v_pk_mul_f32 v[172:173], v[70:71], v[174:175]
	v_bfe_u32 v174, v168, 16, 1
	v_add3_u32 v168, v168, v174, s56
	v_bfe_u32 v174, v169, 16, 1
	v_pk_mul_f32 v[172:173], v[172:173], v[166:167] op_sel_hi:[1,0]
	v_lshrrev_b32_e32 v168, 16, v168
	v_add3_u32 v169, v169, v174, s56
	v_and_or_b32 v168, v169, s57, v168
	v_bfe_u32 v169, v172, 16, 1
	v_add3_u32 v169, v172, v169, s56
	v_bfe_u32 v172, v173, 16, 1
	v_lshrrev_b32_e32 v169, 16, v169
	v_add3_u32 v172, v173, v172, s56
	v_and_or_b32 v169, v172, s57, v169
	global_store_dwordx2 v[176:177], v[168:169], off offset:3840
	global_load_dwordx4 v[172:175], v[118:119], off offset:2048
	s_waitcnt vmcnt(0)
	v_pk_mul_f32 v[168:169], v[72:73], v[172:173]
	s_nop 0
	v_pk_mul_f32 v[168:169], v[168:169], v[166:167] op_sel_hi:[1,0]
	v_pk_mul_f32 v[172:173], v[74:75], v[174:175]
	v_bfe_u32 v174, v168, 16, 1
	v_add3_u32 v168, v168, v174, s56
	v_bfe_u32 v174, v169, 16, 1
	v_pk_mul_f32 v[172:173], v[172:173], v[166:167] op_sel_hi:[1,0]
	v_lshrrev_b32_e32 v168, 16, v168
	v_add3_u32 v169, v169, v174, s56
	v_and_or_b32 v174, v169, s57, v168
	v_bfe_u32 v168, v172, 16, 1
	v_add3_u32 v168, v172, v168, s56
	v_bfe_u32 v169, v173, 16, 1
	v_lshrrev_b32_e32 v168, 16, v168
	v_add3_u32 v169, v173, v169, s56
	v_and_or_b32 v175, v169, s57, v168
	v_add_co_u32_e32 v168, vcc, s31, v170
	s_nop 1
	v_addc_co_u32_e32 v169, vcc, 0, v171, vcc
	global_store_dwordx2 v[168:169], v[174:175], off offset:256
	global_load_dwordx4 v[170:173], v[118:119], off offset:3072
	s_waitcnt vmcnt(0)
	v_pk_mul_f32 v[170:171], v[76:77], v[170:171]
	s_nop 0
	v_pk_mul_f32 v[170:171], v[170:171], v[166:167] op_sel_hi:[1,0]
	v_pk_mul_f32 v[172:173], v[78:79], v[172:173]
	v_bfe_u32 v174, v170, 16, 1
	v_add3_u32 v170, v170, v174, s56
	v_bfe_u32 v174, v171, 16, 1
	v_pk_mul_f32 v[172:173], v[172:173], v[166:167] op_sel_hi:[1,0]
	v_lshrrev_b32_e32 v170, 16, v170
	v_add3_u32 v171, v171, v174, s56
	v_and_or_b32 v170, v171, s57, v170
	v_bfe_u32 v171, v172, 16, 1
	v_add3_u32 v171, v172, v171, s56
	v_bfe_u32 v172, v173, 16, 1
	v_lshrrev_b32_e32 v171, 16, v171
	v_add3_u32 v172, v173, v172, s56
	v_and_or_b32 v171, v172, s57, v171
	global_store_dwordx2 v[168:169], v[170:171], off offset:768
	global_load_dwordx4 v[170:173], v[120:121], off
	s_waitcnt vmcnt(0)
	v_pk_mul_f32 v[170:171], v[80:81], v[170:171]
	s_nop 0
	v_pk_mul_f32 v[170:171], v[170:171], v[166:167] op_sel_hi:[1,0]
	v_pk_mul_f32 v[172:173], v[82:83], v[172:173]
	v_bfe_u32 v174, v170, 16, 1
	v_add3_u32 v170, v170, v174, s56
	v_bfe_u32 v174, v171, 16, 1
	v_pk_mul_f32 v[172:173], v[172:173], v[166:167] op_sel_hi:[1,0]
	v_lshrrev_b32_e32 v170, 16, v170
	v_add3_u32 v171, v171, v174, s56
	v_and_or_b32 v170, v171, s57, v170
	v_bfe_u32 v171, v172, 16, 1
	v_add3_u32 v171, v172, v171, s56
	v_bfe_u32 v172, v173, 16, 1
	v_lshrrev_b32_e32 v171, 16, v171
	v_add3_u32 v172, v173, v172, s56
	v_and_or_b32 v171, v172, s57, v171
	global_store_dwordx2 v[168:169], v[170:171], off offset:1280
	global_load_dwordx4 v[170:173], v[122:123], off
	s_waitcnt vmcnt(0)
	v_pk_mul_f32 v[170:171], v[84:85], v[170:171]
	s_nop 0
	v_pk_mul_f32 v[170:171], v[170:171], v[166:167] op_sel_hi:[1,0]
	v_pk_mul_f32 v[172:173], v[86:87], v[172:173]
	v_bfe_u32 v174, v170, 16, 1
	v_add3_u32 v170, v170, v174, s56
	v_bfe_u32 v174, v171, 16, 1
	v_pk_mul_f32 v[172:173], v[172:173], v[166:167] op_sel_hi:[1,0]
	v_lshrrev_b32_e32 v170, 16, v170
	v_add3_u32 v171, v171, v174, s56
	v_and_or_b32 v170, v171, s57, v170
	v_bfe_u32 v171, v172, 16, 1
	v_add3_u32 v171, v172, v171, s56
	v_bfe_u32 v172, v173, 16, 1
	v_lshrrev_b32_e32 v171, 16, v171
	v_add3_u32 v172, v173, v172, s56
	v_and_or_b32 v171, v172, s57, v171
	global_store_dwordx2 v[168:169], v[170:171], off offset:1792
	global_load_dwordx4 v[170:173], v[124:125], off
	s_waitcnt vmcnt(0)
	v_pk_mul_f32 v[170:171], v[88:89], v[170:171]
	s_nop 0
	v_pk_mul_f32 v[170:171], v[170:171], v[166:167] op_sel_hi:[1,0]
	v_pk_mul_f32 v[172:173], v[90:91], v[172:173]
	v_bfe_u32 v174, v170, 16, 1
	v_add3_u32 v170, v170, v174, s56
	v_bfe_u32 v174, v171, 16, 1
	v_pk_mul_f32 v[172:173], v[172:173], v[166:167] op_sel_hi:[1,0]
	v_lshrrev_b32_e32 v170, 16, v170
	v_add3_u32 v171, v171, v174, s56
	v_and_or_b32 v170, v171, s57, v170
	v_bfe_u32 v171, v172, 16, 1
	v_add3_u32 v171, v172, v171, s56
	v_bfe_u32 v172, v173, 16, 1
	v_lshrrev_b32_e32 v171, 16, v171
	v_add3_u32 v172, v173, v172, s56
	v_and_or_b32 v171, v172, s57, v171
	global_store_dwordx2 v[168:169], v[170:171], off offset:2304
	global_load_dwordx4 v[170:173], v[126:127], off
	s_waitcnt vmcnt(0)
	v_pk_mul_f32 v[170:171], v[92:93], v[170:171]
	v_pk_mul_f32 v[172:173], v[94:95], v[172:173]
	v_pk_mul_f32 v[170:171], v[170:171], v[166:167] op_sel_hi:[1,0]
	v_pk_mul_f32 v[172:173], v[172:173], v[166:167] op_sel_hi:[1,0]
	v_bfe_u32 v166, v170, 16, 1
	v_add3_u32 v166, v170, v166, s56
	v_bfe_u32 v170, v171, 16, 1
	v_lshrrev_b32_e32 v166, 16, v166
	v_add3_u32 v170, v171, v170, s56
	v_and_or_b32 v170, v170, s57, v166
	v_bfe_u32 v166, v172, 16, 1
	v_add3_u32 v166, v172, v166, s56
	v_bfe_u32 v171, v173, 16, 1
	v_lshrrev_b32_e32 v166, 16, v166
	v_add3_u32 v171, v173, v171, s56
	v_and_or_b32 v171, v171, s57, v166
	global_store_dwordx2 v[168:169], v[170:171], off offset:2816

; template <int MODE>
; __device__ __forceinline__ void row_finish(const Params& p, int r, int lane, const float* gpost, const float* gnext, bf16_t* U, float coef, f32x4 (&h)[8], const u32x2 (&dw)[8]) {
;     ...
;     if (MODE >= 1) {
;         f32x4 d[8]; float ss = 0.f;
; #pragma unroll
;         for (int j = 0; j < 8; ++j) { const u32x2 w = dw[j]; d[j] = (f32x4){bflo(w.x), bfhi(w.x), bflo(w.y), bfhi(w.y)};
;             ss += (d[j].x * d[j].x + d[j].y * d[j].y) + (d[j].z * d[j].z + d[j].w * d[j].w); }
;         ss = wave_sum(ss);
;         const float rs = rsqrtf(ss * (1.f / DM) + EPS) * coef;
;         f32x4* hd = (f32x4*)hrow(p, r);
; #pragma unroll
;         for (int j = 0; j < 8; ++j) { const f32x4 g = ((const f32x4*)gpost)[lane + 64 * j]; h[j] = h[j] + d[j] * g * rs; __builtin_nontemporal_store(h[j], &hd[lane + 64 * j]); }
.LBB0_461:
	s_andn2_b64 vcc, exec, s[28:29]
	s_mov_b64 s[6:7], -1
	s_cbranch_vccnz .LBB0_463
	s_waitcnt vmcnt(0) lgkmcnt(0)
	v_and_b32_e32 v71, 0xffff0000, v130
	v_and_b32_e32 v70, 0xffff0000, v132
	v_and_b32_e32 v171, 0xffff0000, v131
	v_and_b32_e32 v170, 0xffff0000, v133
	v_lshlrev_b32_e32 v69, 16, v130
	v_lshlrev_b32_e32 v68, 16, v132
	v_lshlrev_b32_e32 v169, 16, v131
	v_lshlrev_b32_e32 v168, 16, v133
	v_pk_mul_f32 v[64:65], v[70:71], v[70:71]
	v_pk_mul_f32 v[66:67], v[170:171], v[170:171]
	v_pk_fma_f32 v[64:65], v[68:69], v[68:69], v[64:65]
	v_pk_fma_f32 v[66:67], v[168:169], v[168:169], v[66:67]
	v_and_b32_e32 v75, 0xffff0000, v135
	v_pk_add_f32 v[64:65], v[64:65], v[66:67]
	v_and_b32_e32 v74, 0xffff0000, v134
	v_pk_add_f32 v[64:65], v[64:65], v[64:65] op_sel_hi:[0,1]
	v_lshlrev_b32_e32 v73, 16, v135
	v_lshlrev_b32_e32 v72, 16, v134
	v_pk_mul_f32 v[66:67], v[74:75], v[74:75]
	v_lshlrev_b32_e32 v76, 16, v136
	v_and_b32_e32 v77, 0xffff0000, v136
	v_lshlrev_b32_e32 v78, 16, v137
	v_lshlrev_b32_e32 v80, 16, v138
	v_pk_fma_f32 v[66:67], v[72:73], v[72:73], v[66:67]
	v_mul_f32_e32 v81, v76, v76
	v_mul_f32_e32 v85, v77, v77
	v_and_b32_e32 v79, 0xffff0000, v137
	v_mul_f32_e32 v64, v78, v78
	v_mov_b32_e32 v84, v80
	v_pk_add_f32 v[66:67], v[66:67], v[66:67] op_sel_hi:[0,1]
	v_pk_fma_f32 v[86:87], v[78:79], v[78:79], v[64:65] op_sel_hi:[1,1,0]
	v_and_b32_e32 v173, 0xffff0000, v138
	v_lshlrev_b32_e32 v82, 16, v139
	v_and_b32_e32 v83, 0xffff0000, v139
	v_pk_add_f32 v[84:85], v[80:81], v[84:85]
	v_mul_f32_e32 v86, v173, v173
	v_mul_f32_e32 v66, v82, v82
	v_mul_f32_e32 v64, v83, v83
	v_mul_f32_e32 v88, v80, v80
	v_mov_b32_e32 v89, v85
	v_pk_add_f32 v[84:85], v[88:89], v[86:87]
	v_pk_add_f32 v[64:65], v[66:67], v[64:65]
	v_and_b32_e32 v87, 0xffff0000, v141
	v_pk_add_f32 v[64:65], v[84:85], v[64:65]
	v_and_b32_e32 v86, 0xffff0000, v140
	v_pk_add_f32 v[64:65], v[64:65], v[64:65] op_sel_hi:[0,1]
	v_lshlrev_b32_e32 v85, 16, v141
	v_lshlrev_b32_e32 v84, 16, v140
	v_pk_mul_f32 v[66:67], v[86:87], v[86:87]
	v_lshlrev_b32_e32 v88, 16, v142
	v_and_b32_e32 v89, 0xffff0000, v142
	v_lshlrev_b32_e32 v90, 16, v143
	v_lshlrev_b32_e32 v92, 16, v144
	v_pk_fma_f32 v[66:67], v[84:85], v[84:85], v[66:67]
	v_mul_f32_e32 v93, v88, v88
	v_mul_f32_e32 v175, v89, v89
	v_and_b32_e32 v91, 0xffff0000, v143
	v_mul_f32_e32 v64, v90, v90
	v_mov_b32_e32 v174, v92
	v_pk_add_f32 v[66:67], v[66:67], v[66:67] op_sel_hi:[0,1]
	v_pk_fma_f32 v[176:177], v[90:91], v[90:91], v[64:65] op_sel_hi:[1,1,0]
	v_and_b32_e32 v172, 0xffff0000, v144
	v_lshlrev_b32_e32 v94, 16, v145
	v_and_b32_e32 v95, 0xffff0000, v145
	v_pk_add_f32 v[174:175], v[92:93], v[174:175]
	v_mul_f32_e32 v176, v172, v172
	v_mul_f32_e32 v66, v94, v94
	v_mul_f32_e32 v64, v95, v95
	v_mul_f32_e32 v178, v92, v92
	v_mov_b32_e32 v179, v175
	v_pk_add_f32 v[174:175], v[178:179], v[176:177]
	v_pk_add_f32 v[64:65], v[66:67], v[64:65]
	s_add_u32 s5, s60, s38
	v_pk_add_f32 v[64:65], v[174:175], v[64:65]
	s_addc_u32 s6, 0, s39
	v_add_f32_e32 v64, v64, v65
	ds_bpermute_b32 v65, v97, v64
	s_add_u32 s5, s5, 1
	s_addc_u32 s6, s6, 0
	s_add_u32 s7, s24, s38
	s_addc_u32 s28, s25, s39
	s_waitcnt lgkmcnt(0)
	v_add_f32_e32 v64, v64, v65
	ds_bpermute_b32 v65, v101, v64
	s_add_u32 s29, s7, 1
	s_addc_u32 s7, s28, 0
	s_cmp_lt_i32 s49, 0x8000
	s_cselect_b32 s7, s7, s6
	s_waitcnt lgkmcnt(0)
	v_add_f32_e32 v64, v64, v65
	ds_bpermute_b32 v65, v103, v64
	s_cselect_b32 s6, s29, s5
	v_mov_b32_e32 v174, v69
	v_mov_b32_e32 v175, v71
	s_cselect_b32 s5, s15, s71
	s_waitcnt lgkmcnt(0)
	v_add_f32_e32 v64, v64, v65
	ds_bpermute_b32 v65, v105, v64
	s_cselect_b32 s28, s14, s70
	s_lshl_b64 s[6:7], s[6:7], 13
	s_add_u32 s6, s28, s6
	s_addc_u32 s7, s5, s7
	s_waitcnt lgkmcnt(0)
	v_add_f32_e32 v64, v64, v65
	ds_bpermute_b32 v65, v107, v64
	v_lshlrev_b32_e32 v81, 4, v96
	v_mov_b32_e32 v69, v70
	v_lshlrev_b32_e32 v93, 4, v100
	s_mov_b32 s5, 0xa2f3000
	s_waitcnt lgkmcnt(0)
	v_add_f32_e32 v64, v64, v65
	ds_bpermute_b32 v65, v129, v64
	s_waitcnt lgkmcnt(0)
	v_add_f32_e32 v64, v64, v65
	v_fmamk_f32 v64, v64, 0x3a000000, v167
	v_cmp_gt_f32_e32 vcc, s58, v64
	v_mul_f32_e32 v65, 0x4b800000, v64
	s_nop 0
	v_cndmask_b32_e32 v64, v64, v65, vcc
	v_rsq_f32_e32 v64, v64
	s_nop 0
	v_mul_f32_e32 v65, 0x45800000, v64
	v_cndmask_b32_e32 v64, v64, v65, vcc
	v_mul_f32_e32 v166, 0.5, v64
	global_load_dwordx4 v[64:67], v[108:109], off
	s_waitcnt vmcnt(0)
	v_pk_mul_f32 v[64:65], v[174:175], v[64:65]
	v_mov_b32_e32 v174, v169
	v_mov_b32_e32 v175, v171
	v_pk_mul_f32 v[66:67], v[174:175], v[66:67]
	v_pk_fma_f32 v[64:65], v[64:65], v[166:167], v[4:5] op_sel_hi:[1,0,1]
	v_pk_fma_f32 v[66:67], v[66:67], v[166:167], v[6:7] op_sel_hi:[1,0,1]
	global_store_dwordx4 v81, v[64:67], s[6:7] nt
	global_load_dwordx4 v[174:177], v[108:109], off offset:1024
	v_mov_b32_e32 v169, v170
	s_waitcnt vmcnt(0)
	v_pk_mul_f32 v[168:169], v[168:169], v[176:177]
	v_pk_mul_f32 v[68:69], v[68:69], v[174:175]
	v_pk_fma_f32 v[70:71], v[168:169], v[166:167], v[10:11] op_sel_hi:[1,0,1]
	v_pk_fma_f32 v[68:69], v[68:69], v[166:167], v[8:9] op_sel_hi:[1,0,1]
	global_store_dwordx4 v81, v[68:71], s[6:7] offset:1024 nt
	global_load_dwordx4 v[168:171], v[108:109], off offset:2048
	v_mov_b32_e32 v174, v73
	v_mov_b32_e32 v175, v75
	v_mov_b32_e32 v73, v74
	s_waitcnt vmcnt(0)
	v_pk_mul_f32 v[170:171], v[170:171], v[174:175]
	v_pk_mul_f32 v[72:73], v[168:169], v[72:73]
	v_pk_fma_f32 v[74:75], v[170:171], v[166:167], v[14:15] op_sel_hi:[1,0,1]
	v_pk_fma_f32 v[72:73], v[72:73], v[166:167], v[12:13] op_sel_hi:[1,0,1]
	global_store_dwordx4 v81, v[72:75], s[6:7] offset:2048 nt
	global_load_dwordx4 v[168:171], v[108:109], off offset:3072
	v_mov_b32_e32 v174, v85
	v_mov_b32_e32 v175, v87
	v_mov_b32_e32 v85, v86
	s_waitcnt vmcnt(0)
; __device__ __forceinline__ unsigned pk2(float lo, float hi) { return f2bf(lo) | (f2bf(hi) << 16); }
; template <int MODE>
; __device__ __forceinline__ void row_finish(const Params& p, int r, int lane, const float* gpost, const float* gnext, bf16_t* U, float coef, f32x4 (&h)[8], const u32x2 (&dw)[8]) {
;     ...
;         for (int j = 0; j < 8; ++j) { const f32x4 g = ((const f32x4*)gpost)[lane + 64 * j]; h[j] = h[j] + d[j] * g * rs; __builtin_nontemporal_store(h[j], &hd[lane + 64 * j]); }
;     }
;     if (MODE != 3) {
;         float s2 = 0.f;
; #pragma unroll
;         for (int j = 0; j < 8; ++j) s2 += (h[j].x * h[j].x + h[j].y * h[j].y) + (h[j].z * h[j].z + h[j].w * h[j].w);
;         s2 = wave_sum(s2);
;         const float rs2 = rsqrtf(s2 * (1.f / DM) + EPS);
;         u32x2* up = (u32x2*)(U + (size_t)r * DM);
; #pragma unroll
;         for (int j = 0; j < 8; ++j) { const f32x4 g = ((const f32x4*)gnext)[lane + 64 * j]; const f32x4 v = h[j] * g * rs2;
;             u32x2 w; w.x = pk2(v.x, v.y); w.y = pk2(v.z, v.w); up[lane + 64 * j] = w; }
	v_pk_mul_f32 v[78:79], v[78:79], v[170:171]
	v_pk_mul_f32 v[76:77], v[76:77], v[168:169]
	v_pk_fma_f32 v[78:79], v[78:79], v[166:167], v[18:19] op_sel_hi:[1,0,1]
	v_pk_fma_f32 v[76:77], v[76:77], v[166:167], v[16:17] op_sel_hi:[1,0,1]
	global_store_dwordx4 v81, v[76:79], s[6:7] offset:3072 nt
	global_load_dwordx4 v[168:171], v[110:111], off
	v_mov_b32_e32 v81, v173
	v_mov_b32_e32 v173, v71
	s_waitcnt vmcnt(0)
	v_pk_mul_f32 v[80:81], v[80:81], v[168:169]
	v_pk_mul_f32 v[82:83], v[82:83], v[170:171]
	v_pk_fma_f32 v[80:81], v[80:81], v[166:167], v[20:21] op_sel_hi:[1,0,1]
	v_pk_fma_f32 v[82:83], v[82:83], v[166:167], v[22:23] op_sel_hi:[1,0,1]
	global_store_dwordx4 v93, v[80:83], s[6:7] nt
	global_load_dwordx4 v[168:171], v[112:113], off
	v_lshlrev_b32_e32 v93, 4, v102
	s_waitcnt vmcnt(0)
	v_pk_mul_f32 v[170:171], v[170:171], v[174:175]
	v_pk_mul_f32 v[84:85], v[168:169], v[84:85]
	v_pk_fma_f32 v[86:87], v[166:167], v[170:171], v[26:27] op_sel_hi:[0,1,1]
	v_pk_fma_f32 v[84:85], v[166:167], v[84:85], v[24:25] op_sel_hi:[0,1,1]
	global_store_dwordx4 v93, v[84:87], s[6:7] nt
	global_load_dwordx4 v[168:171], v[114:115], off
	v_lshlrev_b32_e32 v93, 4, v104
	s_waitcnt vmcnt(0)
	v_pk_mul_f32 v[90:91], v[90:91], v[170:171]
	v_pk_mul_f32 v[88:89], v[88:89], v[168:169]
	v_pk_fma_f32 v[90:91], v[166:167], v[90:91], v[30:31] op_sel_hi:[0,1,1]
	v_pk_fma_f32 v[88:89], v[166:167], v[88:89], v[28:29] op_sel_hi:[0,1,1]
	global_store_dwordx4 v93, v[88:91], s[6:7] nt
	global_load_dwordx4 v[168:171], v[116:117], off
	v_mov_b32_e32 v93, v172
	v_mov_b32_e32 v172, v67
	v_pk_mul_f32 v[172:173], v[172:173], v[172:173]
	s_waitcnt vmcnt(0)
	v_pk_mul_f32 v[94:95], v[94:95], v[170:171]
	v_mov_b32_e32 v170, v65
	v_mov_b32_e32 v171, v69
	v_pk_mul_f32 v[92:93], v[92:93], v[168:169]
	v_mov_b32_e32 v168, v64
	v_mov_b32_e32 v169, v68
	v_pk_mul_f32 v[170:171], v[170:171], v[170:171]
	v_pk_fma_f32 v[94:95], v[166:167], v[94:95], v[34:35] op_sel_hi:[0,1,1]
	v_pk_fma_f32 v[168:169], v[168:169], v[168:169], v[170:171]
	v_mov_b32_e32 v170, v66
	v_mov_b32_e32 v171, v70
	v_pk_fma_f32 v[170:171], v[170:171], v[170:171], v[172:173]
	v_pk_fma_f32 v[92:93], v[166:167], v[92:93], v[32:33] op_sel_hi:[0,1,1]
	v_lshlrev_b32_e32 v166, 4, v106
	v_pk_add_f32 v[168:169], v[168:169], v[170:171]
	v_pk_mul_f32 v[170:171], v[72:73], v[72:73]
	v_pk_mul_f32 v[172:173], v[74:75], v[74:75]
	global_store_dwordx4 v166, v[92:95], s[6:7] nt
	v_pk_mov_b32 v[174:175], v[170:171], v[172:173] op_sel:[1,0]
	v_mov_b32_e32 v171, v173
	v_mul_f32_e32 v166, v76, v76
	v_pk_add_f32 v[170:171], v[174:175], v[170:171]
	v_pk_fma_f32 v[172:173], v[76:77], v[76:77], v[166:167] op_sel_hi:[1,1,0]
	v_mul_f32_e32 v166, v78, v78
	v_pk_add_f32 v[168:169], v[168:169], v[168:169] op_sel_hi:[0,1]
	v_pk_add_f32 v[170:171], v[170:171], v[170:171] op_sel_hi:[0,1]
	v_pk_fma_f32 v[174:175], v[78:79], v[78:79], v[166:167] op_sel_hi:[1,1,0]
	v_mul_f32_e32 v172, v80, v80
	v_mul_f32_e32 v174, v81, v81
	v_mul_f32_e32 v170, v82, v82
	v_mul_f32_e32 v168, v83, v83
	v_pk_add_f32 v[172:173], v[172:173], v[174:175]
	v_pk_add_f32 v[168:169], v[170:171], v[168:169]
	v_pk_mul_f32 v[170:171], v[84:85], v[84:85]
	v_pk_add_f32 v[168:169], v[172:173], v[168:169]
	v_pk_mul_f32 v[172:173], v[86:87], v[86:87]
	v_mul_f32_e32 v166, v88, v88
	v_pk_mov_b32 v[174:175], v[170:171], v[172:173] op_sel:[1,0]
	v_mov_b32_e32 v171, v173
	v_pk_add_f32 v[170:171], v[174:175], v[170:171]
	v_pk_fma_f32 v[172:173], v[88:89], v[88:89], v[166:167] op_sel_hi:[1,1,0]
	v_mul_f32_e32 v166, v90, v90
	v_pk_add_f32 v[168:169], v[168:169], v[168:169] op_sel_hi:[0,1]
	v_pk_add_f32 v[170:171], v[170:171], v[170:171] op_sel_hi:[0,1]
	v_pk_fma_f32 v[174:175], v[90:91], v[90:91], v[166:167] op_sel_hi:[1,1,0]
	v_mul_f32_e32 v172, v92, v92
	v_mul_f32_e32 v174, v93, v93
	v_mul_f32_e32 v170, v94, v94
	v_mul_f32_e32 v168, v95, v95
	v_pk_add_f32 v[172:173], v[172:173], v[174:175]
	v_pk_add_f32 v[168:169], v[170:171], v[168:169]
	s_mov_b64 s[6:7], 0
	v_pk_add_f32 v[168:169], v[172:173], v[168:169]
	s_nop 0
	v_add_f32_e32 v166, v168, v169
	ds_bpermute_b32 v168, v97, v166
	s_waitcnt lgkmcnt(0)
	v_add_f32_e32 v166, v166, v168
	ds_bpermute_b32 v168, v101, v166
	s_waitcnt lgkmcnt(0)
	v_add_f32_e32 v166, v166, v168
	ds_bpermute_b32 v168, v103, v166
	s_waitcnt lgkmcnt(0)
	v_add_f32_e32 v166, v166, v168
	ds_bpermute_b32 v168, v105, v166
	s_waitcnt lgkmcnt(0)
	v_add_f32_e32 v166, v166, v168
	ds_bpermute_b32 v168, v107, v166
	s_waitcnt lgkmcnt(0)
	v_add_f32_e32 v166, v166, v168
	ds_bpermute_b32 v168, v129, v166
	s_waitcnt lgkmcnt(0)
	v_add_f32_e32 v166, v166, v168
	v_fmamk_f32 v166, v166, 0x3a000000, v167
	v_cmp_gt_f32_e32 vcc, s58, v166
	v_mul_f32_e32 v168, 0x4b800000, v166
	s_nop 0
	v_cndmask_b32_e32 v166, v166, v168, vcc
	v_rsq_f32_e32 v166, v166
	s_nop 0
	v_mul_f32_e32 v168, 0x45800000, v166
	v_cndmask_b32_e32 v166, v166, v168, vcc
	global_load_dwordx4 v[168:171], v[118:119], off
	s_waitcnt vmcnt(0)
	v_pk_mul_f32 v[168:169], v[64:65], v[168:169]
	s_nop 0
	v_pk_mul_f32 v[168:169], v[168:169], v[166:167] op_sel_hi:[1,0]
	v_pk_mul_f32 v[170:171], v[66:67], v[170:171]
	v_bfe_u32 v172, v168, 16, 1
	v_add3_u32 v168, v168, v172, s56
	v_bfe_u32 v172, v169, 16, 1
	v_pk_mul_f32 v[170:171], v[170:171], v[166:167] op_sel_hi:[1,0]
	v_lshrrev_b32_e32 v168, 16, v168
	v_add3_u32 v169, v169, v172, s56
	v_and_or_b32 v168, v169, s57, v168
	v_bfe_u32 v169, v170, 16, 1
	v_add3_u32 v169, v170, v169, s56
	v_bfe_u32 v170, v171, 16, 1
	v_lshrrev_b32_e32 v169, 16, v169
	v_add3_u32 v170, v171, v170, s56
	v_and_or_b32 v169, v170, s57, v169
	v_lshl_add_u64 v[170:171], s[46:47], 0, v[162:163]
	v_add_co_u32_e32 v176, vcc, s31, v170
	s_nop 1
	v_addc_co_u32_e32 v177, vcc, 0, v171, vcc
	global_store_dwordx2 v[176:177], v[168:169], off offset:3328
	global_load_dwordx4 v[172:175], v[118:119], off offset:1024
	s_waitcnt vmcnt(0)
; __device__ __forceinline__ unsigned pk2(float lo, float hi) { return f2bf(lo) | (f2bf(hi) << 16); }
; template <int MODE>
; __device__ __forceinline__ void row_finish(const Params& p, int r, int lane, const float* gpost, const float* gnext, bf16_t* U, float coef, f32x4 (&h)[8], const u32x2 (&dw)[8]) {
;     ...
;         for (int j = 0; j < 8; ++j) { const f32x4 g = ((const f32x4*)gnext)[lane + 64 * j]; const f32x4 v = h[j] * g * rs2;
;             u32x2 w; w.x = pk2(v.x, v.y); w.y = pk2(v.z, v.w); up[lane + 64 * j] = w; }
	v_pk_mul_f32 v[168:169], v[68:69], v[172:173]
	s_nop 0
	v_pk_mul_f32 v[168:169], v[168:169], v[166:167] op_sel_hi:[1,0]
	v_pk_mul_f32 v[172:173], v[70:71], v[174:175]
	v_bfe_u32 v174, v168, 16, 1
	v_add3_u32 v168, v168, v174, s56
	v_bfe_u32 v174, v169, 16, 1
	v_pk_mul_f32 v[172:173], v[172:173], v[166:167] op_sel_hi:[1,0]
	v_lshrrev_b32_e32 v168, 16, v168
	v_add3_u32 v169, v169, v174, s56
	v_and_or_b32 v168, v169, s57, v168
	v_bfe_u32 v169, v172, 16, 1
	v_add3_u32 v169, v172, v169, s56
	v_bfe_u32 v172, v173, 16, 1
	v_lshrrev_b32_e32 v169, 16, v169
	v_add3_u32 v172, v173, v172, s56
	v_and_or_b32 v169, v172, s57, v169
	global_store_dwordx2 v[176:177], v[168:169], off offset:3840
	global_load_dwordx4 v[172:175], v[118:119], off offset:2048
	s_waitcnt vmcnt(0)
	v_pk_mul_f32 v[168:169], v[72:73], v[172:173]
	s_nop 0
	v_pk_mul_f32 v[168:169], v[168:169], v[166:167] op_sel_hi:[1,0]
	v_pk_mul_f32 v[172:173], v[74:75], v[174:175]
	v_bfe_u32 v174, v168, 16, 1
	v_add3_u32 v168, v168, v174, s56
	v_bfe_u32 v174, v169, 16, 1
	v_pk_mul_f32 v[172:173], v[172:173], v[166:167] op_sel_hi:[1,0]
	v_lshrrev_b32_e32 v168, 16, v168
	v_add3_u32 v169, v169, v174, s56
	v_and_or_b32 v174, v169, s57, v168
	v_bfe_u32 v168, v172, 16, 1
	v_add3_u32 v168, v172, v168, s56
	v_bfe_u32 v169, v173, 16, 1
	v_lshrrev_b32_e32 v168, 16, v168
	v_add3_u32 v169, v173, v169, s56
	v_and_or_b32 v175, v169, s57, v168
	v_add_co_u32_e32 v168, vcc, s5, v170
	s_nop 1
	v_addc_co_u32_e32 v169, vcc, 0, v171, vcc
	global_store_dwordx2 v[168:169], v[174:175], off offset:256
	global_load_dwordx4 v[170:173], v[118:119], off offset:3072
	s_waitcnt vmcnt(0)
	v_pk_mul_f32 v[170:171], v[76:77], v[170:171]
	s_nop 0
	v_pk_mul_f32 v[170:171], v[170:171], v[166:167] op_sel_hi:[1,0]
	v_pk_mul_f32 v[172:173], v[78:79], v[172:173]
	v_bfe_u32 v174, v170, 16, 1
	v_add3_u32 v170, v170, v174, s56
	v_bfe_u32 v174, v171, 16, 1
	v_pk_mul_f32 v[172:173], v[172:173], v[166:167] op_sel_hi:[1,0]
	v_lshrrev_b32_e32 v170, 16, v170
	v_add3_u32 v171, v171, v174, s56
	v_and_or_b32 v170, v171, s57, v170
	v_bfe_u32 v171, v172, 16, 1
	v_add3_u32 v171, v172, v171, s56
	v_bfe_u32 v172, v173, 16, 1
	v_lshrrev_b32_e32 v171, 16, v171
	v_add3_u32 v172, v173, v172, s56
	v_and_or_b32 v171, v172, s57, v171
	global_store_dwordx2 v[168:169], v[170:171], off offset:768
	global_load_dwordx4 v[170:173], v[120:121], off
	s_waitcnt vmcnt(0)
	v_pk_mul_f32 v[170:171], v[80:81], v[170:171]
	s_nop 0
	v_pk_mul_f32 v[170:171], v[170:171], v[166:167] op_sel_hi:[1,0]
	v_pk_mul_f32 v[172:173], v[82:83], v[172:173]
	v_bfe_u32 v174, v170, 16, 1
	v_add3_u32 v170, v170, v174, s56
	v_bfe_u32 v174, v171, 16, 1
	v_pk_mul_f32 v[172:173], v[172:173], v[166:167] op_sel_hi:[1,0]
	v_lshrrev_b32_e32 v170, 16, v170
	v_add3_u32 v171, v171, v174, s56
	v_and_or_b32 v170, v171, s57, v170
	v_bfe_u32 v171, v172, 16, 1
	v_add3_u32 v171, v172, v171, s56
	v_bfe_u32 v172, v173, 16, 1
	v_lshrrev_b32_e32 v171, 16, v171
	v_add3_u32 v172, v173, v172, s56
	v_and_or_b32 v171, v172, s57, v171
	global_store_dwordx2 v[168:169], v[170:171], off offset:1280
	global_load_dwordx4 v[170:173], v[122:123], off
	s_waitcnt vmcnt(0)
	v_pk_mul_f32 v[170:171], v[84:85], v[170:171]
	s_nop 0
	v_pk_mul_f32 v[170:171], v[170:171], v[166:167] op_sel_hi:[1,0]
	v_pk_mul_f32 v[172:173], v[86:87], v[172:173]
	v_bfe_u32 v174, v170, 16, 1
	v_add3_u32 v170, v170, v174, s56
	v_bfe_u32 v174, v171, 16, 1
	v_pk_mul_f32 v[172:173], v[172:173], v[166:167] op_sel_hi:[1,0]
	v_lshrrev_b32_e32 v170, 16, v170
	v_add3_u32 v171, v171, v174, s56
	v_and_or_b32 v170, v171, s57, v170
	v_bfe_u32 v171, v172, 16, 1
	v_add3_u32 v171, v172, v171, s56
	v_bfe_u32 v172, v173, 16, 1
	v_lshrrev_b32_e32 v171, 16, v171
	v_add3_u32 v172, v173, v172, s56
	v_and_or_b32 v171, v172, s57, v171
	global_store_dwordx2 v[168:169], v[170:171], off offset:1792
	global_load_dwordx4 v[170:173], v[124:125], off
	s_waitcnt vmcnt(0)
	v_pk_mul_f32 v[170:171], v[88:89], v[170:171]
	s_nop 0
	v_pk_mul_f32 v[170:171], v[170:171], v[166:167] op_sel_hi:[1,0]
	v_pk_mul_f32 v[172:173], v[90:91], v[172:173]
	v_bfe_u32 v174, v170, 16, 1
	v_add3_u32 v170, v170, v174, s56
	v_bfe_u32 v174, v171, 16, 1
	v_pk_mul_f32 v[172:173], v[172:173], v[166:167] op_sel_hi:[1,0]
	v_lshrrev_b32_e32 v170, 16, v170
	v_add3_u32 v171, v171, v174, s56
	v_and_or_b32 v170, v171, s57, v170
	v_bfe_u32 v171, v172, 16, 1
	v_add3_u32 v171, v172, v171, s56
	v_bfe_u32 v172, v173, 16, 1
	v_lshrrev_b32_e32 v171, 16, v171
	v_add3_u32 v172, v173, v172, s56
	v_and_or_b32 v171, v172, s57, v171
	global_store_dwordx2 v[168:169], v[170:171], off offset:2304
	global_load_dwordx4 v[170:173], v[126:127], off
	s_waitcnt vmcnt(0)
	v_pk_mul_f32 v[170:171], v[92:93], v[170:171]
	v_pk_mul_f32 v[172:173], v[94:95], v[172:173]
	v_pk_mul_f32 v[170:171], v[170:171], v[166:167] op_sel_hi:[1,0]
	v_pk_mul_f32 v[172:173], v[172:173], v[166:167] op_sel_hi:[1,0]
	v_bfe_u32 v166, v170, 16, 1
	v_add3_u32 v166, v170, v166, s56
	v_bfe_u32 v170, v171, 16, 1
	v_lshrrev_b32_e32 v166, 16, v166
	v_add3_u32 v170, v171, v170, s56
	v_and_or_b32 v170, v170, s57, v166
	v_bfe_u32 v166, v172, 16, 1
	v_add3_u32 v166, v172, v166, s56
	v_bfe_u32 v171, v173, 16, 1
	v_lshrrev_b32_e32 v166, 16, v166
	v_add3_u32 v171, v173, v171, s56
	v_and_or_b32 v171, v171, s57, v166
	global_store_dwordx2 v[168:169], v[170:171], off offset:2816

; template <int MODE>
; __device__ __forceinline__ void row_finish(const Params& p, int r, int lane, const float* gpost, const float* gnext, bf16_t* U, float coef, f32x4 (&h)[8], const u32x2 (&dw)[8]) {
;     ...
;     if (MODE >= 1) {
;         f32x4 d[8]; float ss = 0.f;
; #pragma unroll
;         for (int j = 0; j < 8; ++j) { const u32x2 w = dw[j]; d[j] = (f32x4){bflo(w.x), bfhi(w.x), bflo(w.y), bfhi(w.y)};
;             ss += (d[j].x * d[j].x + d[j].y * d[j].y) + (d[j].z * d[j].z + d[j].w * d[j].w); }
;         ss = wave_sum(ss);
;         const float rs = rsqrtf(ss * (1.f / DM) + EPS) * coef;
;         f32x4* hd = (f32x4*)hrow(p, r);
; #pragma unroll
;         for (int j = 0; j < 8; ++j) { const f32x4 g = ((const f32x4*)gpost)[lane + 64 * j]; h[j] = h[j] + d[j] * g * rs; __builtin_nontemporal_store(h[j], &hd[lane + 64 * j]); }
.LBB0_547:
	s_waitcnt lgkmcnt(0)
	v_and_b32_e32 v193, 0xffff0000, v146
	v_and_b32_e32 v192, 0xffff0000, v148
	v_and_b32_e32 v195, 0xffff0000, v147
	v_and_b32_e32 v194, 0xffff0000, v149
	v_lshlrev_b32_e32 v191, 16, v146
	v_lshlrev_b32_e32 v190, 16, v148
	v_lshlrev_b32_e32 v189, 16, v147
	v_lshlrev_b32_e32 v188, 16, v149
	v_pk_mul_f32 v[162:163], v[192:193], v[192:193]
	v_pk_mul_f32 v[164:165], v[194:195], v[194:195]
	v_pk_fma_f32 v[162:163], v[190:191], v[190:191], v[162:163]
	v_pk_fma_f32 v[164:165], v[188:189], v[188:189], v[164:165]
	v_and_b32_e32 v185, 0xffff0000, v151
	v_pk_add_f32 v[162:163], v[162:163], v[164:165]
	v_and_b32_e32 v184, 0xffff0000, v150
	v_pk_add_f32 v[162:163], v[162:163], v[162:163] op_sel_hi:[0,1]
	v_lshlrev_b32_e32 v187, 16, v151
	v_lshlrev_b32_e32 v186, 16, v150
	v_pk_mul_f32 v[164:165], v[184:185], v[184:185]
	v_lshlrev_b32_e32 v180, 16, v152
	v_and_b32_e32 v181, 0xffff0000, v152
	v_lshlrev_b32_e32 v182, 16, v153
	v_lshlrev_b32_e32 v176, 16, v154
	v_pk_fma_f32 v[164:165], v[186:187], v[186:187], v[164:165]
	v_mul_f32_e32 v177, v180, v180
	v_mul_f32_e32 v167, v181, v181
	v_and_b32_e32 v183, 0xffff0000, v153
	v_mul_f32_e32 v162, v182, v182
	v_mov_b32_e32 v166, v176
	v_pk_add_f32 v[164:165], v[164:165], v[164:165] op_sel_hi:[0,1]
	v_pk_fma_f32 v[168:169], v[182:183], v[182:183], v[162:163] op_sel_hi:[1,1,0]
	v_and_b32_e32 v199, 0xffff0000, v154
	v_lshlrev_b32_e32 v178, 16, v155
	v_and_b32_e32 v179, 0xffff0000, v155
	v_pk_add_f32 v[166:167], v[176:177], v[166:167]
	v_mul_f32_e32 v168, v199, v199
	v_mul_f32_e32 v164, v178, v178
	v_mul_f32_e32 v162, v179, v179
	v_mul_f32_e32 v170, v176, v176
	v_mov_b32_e32 v171, v167
	v_pk_add_f32 v[166:167], v[170:171], v[168:169]
	v_pk_add_f32 v[162:163], v[164:165], v[162:163]
	v_and_b32_e32 v175, 0xffff0000, v157
	v_pk_add_f32 v[162:163], v[166:167], v[162:163]
	v_and_b32_e32 v174, 0xffff0000, v156
	v_pk_add_f32 v[200:201], v[162:163], v[162:163] op_sel_hi:[0,1]
	v_lshlrev_b32_e32 v173, 16, v157
	v_lshlrev_b32_e32 v172, 16, v156
	v_pk_mul_f32 v[162:163], v[174:175], v[174:175]
	v_lshlrev_b32_e32 v168, 16, v158
	v_pk_fma_f32 v[162:163], v[172:173], v[172:173], v[162:163]
	v_lshlrev_b32_e32 v170, 16, v159
	v_pk_add_f32 v[202:203], v[162:163], v[162:163] op_sel_hi:[0,1]
	v_mul_f32_e32 v163, v168, v168
	v_and_b32_e32 v171, 0xffff0000, v159
	v_mul_f32_e32 v162, v170, v170
	v_and_b32_e32 v169, 0xffff0000, v158
	v_pk_fma_f32 v[206:207], v[170:171], v[170:171], v[162:163] op_sel_hi:[1,1,0]
	v_lshlrev_b32_e32 v162, 16, v160
	v_mul_f32_e32 v205, v169, v169
	v_mov_b32_e32 v204, v162
	v_and_b32_e32 v167, 0xffff0000, v160
	v_lshlrev_b32_e32 v164, 16, v161
	v_and_b32_e32 v165, 0xffff0000, v161
	v_pk_add_f32 v[204:205], v[162:163], v[204:205]
	v_mul_f32_e32 v206, v167, v167
	v_mul_f32_e32 v202, v164, v164
	v_mul_f32_e32 v200, v165, v165
	v_mul_f32_e32 v208, v162, v162
	v_mov_b32_e32 v209, v205
	v_pk_add_f32 v[204:205], v[208:209], v[206:207]
	v_pk_add_f32 v[200:201], v[202:203], v[200:201]
	s_add_i32 s1, s6, 0xffff8000
	v_pk_add_f32 v[200:201], v[204:205], v[200:201]
	s_ashr_i32 s7, s6, 31
	v_add_f32_e32 v163, v200, v201
	global_load_dwordx4 v[200:203], v[106:107], off
	ds_bpermute_b32 v166, v99, v163
	s_cmp_lt_i32 s6, 0x8000
	s_cselect_b32 s25, s7, 0
	s_cselect_b32 s24, s6, s1
	v_mov_b32_e32 v204, v191
	s_waitcnt lgkmcnt(0)
	v_add_f32_e32 v163, v163, v166
	ds_bpermute_b32 v166, v101, v163
	v_mov_b32_e32 v205, v193
	s_cselect_b32 s1, s15, s71
	s_cselect_b32 s4, s14, s70
	s_lshl_b64 s[24:25], s[24:25], 13
	s_waitcnt lgkmcnt(0)
	v_add_f32_e32 v163, v163, v166
	ds_bpermute_b32 v166, v103, v163
	s_add_u32 s24, s4, s24
	s_addc_u32 s25, s1, s25
	v_mov_b32_e32 v191, v192
	v_mov_b32_e32 v192, v186
	s_waitcnt lgkmcnt(0)
	v_add_f32_e32 v163, v163, v166
	ds_bpermute_b32 v166, v105, v163
	v_mov_b32_e32 v193, v184
	v_mov_b32_e32 v184, v187
	v_mov_b32_e32 v177, v199
	s_waitcnt lgkmcnt(0)
	v_add_f32_e32 v163, v163, v166
	ds_bpermute_b32 v166, v196, v163
	s_waitcnt lgkmcnt(0)
	v_add_f32_e32 v163, v163, v166
	ds_bpermute_b32 v166, v197, v163
	s_waitcnt lgkmcnt(0)
	v_add_f32_e32 v163, v163, v166
	v_fmamk_f32 v163, v163, 0x3a000000, v198
	v_cmp_gt_f32_e32 vcc, s31, v163
	v_mul_f32_e32 v166, 0x4b800000, v163
	s_waitcnt vmcnt(0)
	v_pk_mul_f32 v[200:201], v[204:205], v[200:201]
	v_cndmask_b32_e32 v163, v163, v166, vcc
	v_rsq_f32_e32 v163, v163
	v_mov_b32_e32 v204, v189
	v_mov_b32_e32 v205, v195
	v_pk_mul_f32 v[202:203], v[204:205], v[202:203]
	v_mul_f32_e32 v166, 0x45800000, v163
	v_cndmask_b32_e32 v163, v163, v166, vcc
	v_mul_f32_e32 v166, 0.5, v163
	v_pk_fma_f32 v[2:3], v[202:203], v[166:167], v[2:3] op_sel_hi:[1,0,1]
	v_pk_fma_f32 v[0:1], v[200:201], v[166:167], v[0:1] op_sel_hi:[1,0,1]
	v_lshlrev_b32_e32 v163, 4, v96
	global_store_dwordx4 v163, v[0:3], s[24:25] nt
	global_load_dwordx4 v[200:203], v[106:107], off offset:1024
	v_mov_b32_e32 v189, v194
	s_waitcnt vmcnt(0)
	v_pk_mul_f32 v[190:191], v[190:191], v[200:201]
	v_pk_mul_f32 v[188:189], v[188:189], v[202:203]
	v_pk_fma_f32 v[4:5], v[190:191], v[166:167], v[4:5] op_sel_hi:[1,0,1]
	v_pk_fma_f32 v[6:7], v[188:189], v[166:167], v[6:7] op_sel_hi:[1,0,1]
	global_store_dwordx4 v163, v[4:7], s[24:25] offset:1024 nt
	global_load_dwordx4 v[188:191], v[106:107], off offset:2048
	s_waitcnt vmcnt(0)
	v_pk_mul_f32 v[188:189], v[188:189], v[192:193]
	v_pk_mul_f32 v[184:185], v[190:191], v[184:185]
	v_pk_fma_f32 v[8:9], v[188:189], v[166:167], v[8:9] op_sel_hi:[1,0,1]
	v_pk_fma_f32 v[10:11], v[184:185], v[166:167], v[10:11] op_sel_hi:[1,0,1]
	global_store_dwordx4 v163, v[8:11], s[24:25] offset:2048 nt
	global_load_dwordx4 v[184:187], v[106:107], off offset:3072
	s_waitcnt vmcnt(0)
; __device__ __forceinline__ unsigned pk2(float lo, float hi) { return f2bf(lo) | (f2bf(hi) << 16); }
; template <int MODE>
; __device__ __forceinline__ void row_finish(const Params& p, int r, int lane, const float* gpost, const float* gnext, bf16_t* U, float coef, f32x4 (&h)[8], const u32x2 (&dw)[8]) {
;     ...
;         for (int j = 0; j < 8; ++j) { const f32x4 g = ((const f32x4*)gpost)[lane + 64 * j]; h[j] = h[j] + d[j] * g * rs; __builtin_nontemporal_store(h[j], &hd[lane + 64 * j]); }
;     }
;     if (MODE != 3) {
;         float s2 = 0.f;
; #pragma unroll
;         for (int j = 0; j < 8; ++j) s2 += (h[j].x * h[j].x + h[j].y * h[j].y) + (h[j].z * h[j].z + h[j].w * h[j].w);
;         s2 = wave_sum(s2);
;         const float rs2 = rsqrtf(s2 * (1.f / DM) + EPS);
;         u32x2* up = (u32x2*)(U + (size_t)r * DM);
; #pragma unroll
;         for (int j = 0; j < 8; ++j) { const f32x4 g = ((const f32x4*)gnext)[lane + 64 * j]; const f32x4 v = h[j] * g * rs2;
;             u32x2 w; w.x = pk2(v.x, v.y); w.y = pk2(v.z, v.w); up[lane + 64 * j] = w; }
	v_pk_mul_f32 v[182:183], v[182:183], v[186:187]
	v_pk_mul_f32 v[180:181], v[180:181], v[184:185]
	v_pk_fma_f32 v[14:15], v[182:183], v[166:167], v[14:15] op_sel_hi:[1,0,1]
	v_pk_fma_f32 v[12:13], v[180:181], v[166:167], v[12:13] op_sel_hi:[1,0,1]
	global_store_dwordx4 v163, v[12:15], s[24:25] offset:3072 nt
	global_load_dwordx4 v[180:183], v[108:109], off
	v_lshlrev_b32_e32 v163, 4, v98
	s_waitcnt vmcnt(0)
	v_pk_mul_f32 v[176:177], v[176:177], v[180:181]
	v_pk_mul_f32 v[178:179], v[178:179], v[182:183]
	v_pk_fma_f32 v[16:17], v[176:177], v[166:167], v[16:17] op_sel_hi:[1,0,1]
	v_pk_fma_f32 v[18:19], v[178:179], v[166:167], v[18:19] op_sel_hi:[1,0,1]
	global_store_dwordx4 v163, v[16:19], s[24:25] nt
	global_load_dwordx4 v[176:179], v[110:111], off
	v_mov_b32_e32 v180, v172
	v_mov_b32_e32 v181, v174
	v_mov_b32_e32 v174, v173
	v_lshlrev_b32_e32 v163, 4, v100
	s_waitcnt vmcnt(0)
	v_pk_mul_f32 v[176:177], v[176:177], v[180:181]
	v_pk_mul_f32 v[172:173], v[178:179], v[174:175]
	v_pk_fma_f32 v[20:21], v[166:167], v[176:177], v[20:21] op_sel_hi:[0,1,1]
	v_pk_fma_f32 v[22:23], v[166:167], v[172:173], v[22:23] op_sel_hi:[0,1,1]
	global_store_dwordx4 v163, v[20:23], s[24:25] nt
	global_load_dwordx4 v[172:175], v[112:113], off
	v_lshlrev_b32_e32 v163, 4, v102
	s_waitcnt vmcnt(0)
	v_pk_mul_f32 v[170:171], v[170:171], v[174:175]
	v_pk_mul_f32 v[168:169], v[168:169], v[172:173]
	v_pk_fma_f32 v[26:27], v[166:167], v[170:171], v[26:27] op_sel_hi:[0,1,1]
	v_pk_fma_f32 v[24:25], v[166:167], v[168:169], v[24:25] op_sel_hi:[0,1,1]
	global_store_dwordx4 v163, v[24:27], s[24:25] nt
	global_load_dwordx4 v[168:171], v[114:115], off
	v_mov_b32_e32 v163, v167
	s_waitcnt vmcnt(0)
	v_pk_mul_f32 v[162:163], v[162:163], v[168:169]
	v_pk_mul_f32 v[164:165], v[164:165], v[170:171]
	v_pk_fma_f32 v[28:29], v[166:167], v[162:163], v[28:29] op_sel_hi:[0,1,1]
	v_pk_fma_f32 v[30:31], v[166:167], v[164:165], v[30:31] op_sel_hi:[0,1,1]
	v_lshlrev_b32_e32 v162, 4, v104
	v_mov_b32_e32 v164, v1
	v_mov_b32_e32 v165, v5
	global_store_dwordx4 v162, v[28:31], s[24:25] nt
	v_mov_b32_e32 v162, v0
	v_mov_b32_e32 v163, v4
	v_pk_mul_f32 v[164:165], v[164:165], v[164:165]
	v_mov_b32_e32 v166, v3
	v_mov_b32_e32 v167, v7
	v_pk_fma_f32 v[162:163], v[162:163], v[162:163], v[164:165]
	v_mov_b32_e32 v164, v2
	v_mov_b32_e32 v165, v6
	v_pk_mul_f32 v[166:167], v[166:167], v[166:167]
	s_lshl_b64 s[24:25], s[6:7], 12
	v_pk_fma_f32 v[164:165], v[164:165], v[164:165], v[166:167]
	v_pk_mul_f32 v[166:167], v[10:11], v[10:11]
	v_pk_add_f32 v[162:163], v[162:163], v[164:165]
	v_pk_mul_f32 v[164:165], v[8:9], v[8:9]
	v_pk_add_f32 v[162:163], v[162:163], v[162:163] op_sel_hi:[0,1]
	v_pk_mov_b32 v[168:169], v[164:165], v[166:167] op_sel:[1,0]
	v_mov_b32_e32 v165, v167
	v_mul_f32_e32 v162, v12, v12
	v_pk_add_f32 v[164:165], v[168:169], v[164:165]
	v_pk_fma_f32 v[166:167], v[12:13], v[12:13], v[162:163] op_sel_hi:[1,1,0]
	v_mul_f32_e32 v162, v14, v14
	v_pk_add_f32 v[164:165], v[164:165], v[164:165] op_sel_hi:[0,1]
	v_pk_fma_f32 v[168:169], v[14:15], v[14:15], v[162:163] op_sel_hi:[1,1,0]
	v_mul_f32_e32 v166, v16, v16
	v_mul_f32_e32 v168, v17, v17
	v_mul_f32_e32 v164, v18, v18
	v_mul_f32_e32 v162, v19, v19
	v_pk_add_f32 v[166:167], v[166:167], v[168:169]
	v_pk_add_f32 v[162:163], v[164:165], v[162:163]
	v_pk_mul_f32 v[164:165], v[20:21], v[20:21]
	v_pk_add_f32 v[162:163], v[166:167], v[162:163]
	v_pk_mul_f32 v[166:167], v[22:23], v[22:23]
	v_pk_add_f32 v[162:163], v[162:163], v[162:163] op_sel_hi:[0,1]
	v_pk_mov_b32 v[168:169], v[164:165], v[166:167] op_sel:[1,0]
	v_mov_b32_e32 v165, v167
	v_mul_f32_e32 v162, v24, v24
	v_pk_add_f32 v[164:165], v[168:169], v[164:165]
	v_pk_fma_f32 v[166:167], v[24:25], v[24:25], v[162:163] op_sel_hi:[1,1,0]
	v_mul_f32_e32 v162, v26, v26
	v_pk_add_f32 v[164:165], v[164:165], v[164:165] op_sel_hi:[0,1]
	v_pk_fma_f32 v[168:169], v[26:27], v[26:27], v[162:163] op_sel_hi:[1,1,0]
	v_mul_f32_e32 v166, v28, v28
	v_mul_f32_e32 v168, v29, v29
	v_mul_f32_e32 v164, v30, v30
	v_mul_f32_e32 v162, v31, v31
	v_pk_add_f32 v[166:167], v[166:167], v[168:169]
	v_pk_add_f32 v[162:163], v[164:165], v[162:163]
	s_nop 0
	v_pk_add_f32 v[162:163], v[166:167], v[162:163]
	global_load_dwordx4 v[164:167], v[116:117], off
	v_add_f32_e32 v162, v162, v163
	ds_bpermute_b32 v163, v99, v162
	s_waitcnt lgkmcnt(0)
	v_add_f32_e32 v162, v162, v163
	ds_bpermute_b32 v163, v101, v162
	s_waitcnt lgkmcnt(0)
	v_add_f32_e32 v162, v162, v163
	ds_bpermute_b32 v163, v103, v162
	s_waitcnt lgkmcnt(0)
	v_add_f32_e32 v162, v162, v163
	ds_bpermute_b32 v163, v105, v162
	s_waitcnt lgkmcnt(0)
	v_add_f32_e32 v162, v162, v163
	ds_bpermute_b32 v163, v196, v162
	s_waitcnt lgkmcnt(0)
	v_add_f32_e32 v162, v162, v163
	ds_bpermute_b32 v163, v197, v162
	s_waitcnt lgkmcnt(0)
	v_add_f32_e32 v162, v162, v163
	v_fmamk_f32 v162, v162, 0x3a000000, v198
	v_cmp_gt_f32_e32 vcc, s31, v162
	v_mul_f32_e32 v163, 0x4b800000, v162
	s_waitcnt vmcnt(0)
	v_pk_mul_f32 v[164:165], v[0:1], v[164:165]
	v_cndmask_b32_e32 v162, v162, v163, vcc
	v_rsq_f32_e32 v162, v162
	v_pk_mul_f32 v[166:167], v[2:3], v[166:167]
	v_mul_f32_e32 v163, 0x45800000, v162
	v_cndmask_b32_e32 v162, v162, v163, vcc
	v_pk_mul_f32 v[164:165], v[164:165], v[162:163] op_sel_hi:[1,0]
	v_pk_mul_f32 v[168:169], v[166:167], v[162:163] op_sel_hi:[1,0]
	v_bfe_u32 v163, v164, 16, 1
	v_add3_u32 v163, v164, v163, s23
	v_bfe_u32 v164, v165, 16, 1
	v_lshrrev_b32_e32 v163, 16, v163
	v_add3_u32 v164, v165, v164, s23
	v_and_or_b32 v166, v164, s30, v163
	v_bfe_u32 v163, v168, 16, 1
	v_add3_u32 v163, v168, v163, s23
	v_bfe_u32 v164, v169, 16, 1
	v_lshrrev_b32_e32 v163, 16, v163
	v_add3_u32 v164, v169, v164, s23
	v_and_or_b32 v167, v164, s30, v163
	v_lshl_add_u64 v[164:165], v[128:129], 0, s[24:25]
	global_store_dwordx2 v[164:165], v[166:167], off
	global_load_dwordx4 v[166:169], v[116:117], off offset:1024
	s_waitcnt vmcnt(0)
; __device__ __forceinline__ unsigned pk2(float lo, float hi) { return f2bf(lo) | (f2bf(hi) << 16); }
; template <int MODE>
; __device__ __forceinline__ void row_finish(const Params& p, int r, int lane, const float* gpost, const float* gnext, bf16_t* U, float coef, f32x4 (&h)[8], const u32x2 (&dw)[8]) {
;     ...
;     if (MODE != 3) {
;         float s2 = 0.f;
; #pragma unroll
;         for (int j = 0; j < 8; ++j) s2 += (h[j].x * h[j].x + h[j].y * h[j].y) + (h[j].z * h[j].z + h[j].w * h[j].w);
;         s2 = wave_sum(s2);
;         const float rs2 = rsqrtf(s2 * (1.f / DM) + EPS);
;         u32x2* up = (u32x2*)(U + (size_t)r * DM);
; #pragma unroll
;         for (int j = 0; j < 8; ++j) { const f32x4 g = ((const f32x4*)gnext)[lane + 64 * j]; const f32x4 v = h[j] * g * rs2;
;             u32x2 w; w.x = pk2(v.x, v.y); w.y = pk2(v.z, v.w); up[lane + 64 * j] = w; }
	v_pk_mul_f32 v[166:167], v[4:5], v[166:167]
	v_pk_mul_f32 v[168:169], v[6:7], v[168:169]
	v_pk_mul_f32 v[166:167], v[166:167], v[162:163] op_sel_hi:[1,0]
	v_pk_mul_f32 v[168:169], v[168:169], v[162:163] op_sel_hi:[1,0]
	v_bfe_u32 v163, v166, 16, 1
	v_add3_u32 v163, v166, v163, s23
	v_bfe_u32 v166, v167, 16, 1
	v_lshrrev_b32_e32 v163, 16, v163
	v_add3_u32 v166, v167, v166, s23
	v_and_or_b32 v166, v166, s30, v163
	v_bfe_u32 v163, v168, 16, 1
	v_add3_u32 v163, v168, v163, s23
	v_bfe_u32 v167, v169, 16, 1
	v_lshrrev_b32_e32 v163, 16, v163
	v_add3_u32 v167, v169, v167, s23
	v_and_or_b32 v167, v167, s30, v163
	global_store_dwordx2 v[164:165], v[166:167], off offset:512
	global_load_dwordx4 v[166:169], v[116:117], off offset:2048
	s_waitcnt vmcnt(0)
	v_pk_mul_f32 v[166:167], v[8:9], v[166:167]
	v_pk_mul_f32 v[168:169], v[10:11], v[168:169]
	v_pk_mul_f32 v[166:167], v[166:167], v[162:163] op_sel_hi:[1,0]
	v_pk_mul_f32 v[168:169], v[168:169], v[162:163] op_sel_hi:[1,0]
	v_bfe_u32 v163, v166, 16, 1
	v_add3_u32 v163, v166, v163, s23
	v_bfe_u32 v166, v167, 16, 1
	v_lshrrev_b32_e32 v163, 16, v163
	v_add3_u32 v166, v167, v166, s23
	v_and_or_b32 v166, v166, s30, v163
	v_bfe_u32 v163, v168, 16, 1
	v_add3_u32 v163, v168, v163, s23
	v_bfe_u32 v167, v169, 16, 1
	v_lshrrev_b32_e32 v163, 16, v163
	v_add3_u32 v167, v169, v167, s23
	v_and_or_b32 v167, v167, s30, v163
	global_store_dwordx2 v[164:165], v[166:167], off offset:1024
	global_load_dwordx4 v[166:169], v[116:117], off offset:3072
	s_waitcnt vmcnt(0)
	v_pk_mul_f32 v[166:167], v[12:13], v[166:167]
	v_pk_mul_f32 v[168:169], v[14:15], v[168:169]
	v_pk_mul_f32 v[166:167], v[166:167], v[162:163] op_sel_hi:[1,0]
	v_pk_mul_f32 v[168:169], v[168:169], v[162:163] op_sel_hi:[1,0]
	v_bfe_u32 v163, v166, 16, 1
	v_add3_u32 v163, v166, v163, s23
	v_bfe_u32 v166, v167, 16, 1
	v_lshrrev_b32_e32 v163, 16, v163
	v_add3_u32 v166, v167, v166, s23
	v_and_or_b32 v166, v166, s30, v163
	v_bfe_u32 v163, v168, 16, 1
	v_add3_u32 v163, v168, v163, s23
	v_bfe_u32 v167, v169, 16, 1
	v_lshrrev_b32_e32 v163, 16, v163
	v_add3_u32 v167, v169, v167, s23
	v_and_or_b32 v167, v167, s30, v163
	global_store_dwordx2 v[164:165], v[166:167], off offset:1536
	global_load_dwordx4 v[166:169], v[118:119], off
	s_waitcnt vmcnt(0)
	v_pk_mul_f32 v[166:167], v[16:17], v[166:167]
	v_pk_mul_f32 v[168:169], v[18:19], v[168:169]
	v_pk_mul_f32 v[166:167], v[166:167], v[162:163] op_sel_hi:[1,0]
	v_pk_mul_f32 v[168:169], v[168:169], v[162:163] op_sel_hi:[1,0]
	v_bfe_u32 v163, v166, 16, 1
	v_add3_u32 v163, v166, v163, s23
	v_bfe_u32 v166, v167, 16, 1
	v_lshrrev_b32_e32 v163, 16, v163
	v_add3_u32 v166, v167, v166, s23
	v_and_or_b32 v166, v166, s30, v163
	v_bfe_u32 v163, v168, 16, 1
	v_add3_u32 v163, v168, v163, s23
	v_bfe_u32 v167, v169, 16, 1
	v_lshrrev_b32_e32 v163, 16, v163
	v_add3_u32 v167, v169, v167, s23
	v_and_or_b32 v167, v167, s30, v163
	global_store_dwordx2 v[164:165], v[166:167], off offset:2048
	global_load_dwordx4 v[166:169], v[120:121], off
	s_waitcnt vmcnt(0)
	v_pk_mul_f32 v[166:167], v[20:21], v[166:167]
	v_pk_mul_f32 v[168:169], v[22:23], v[168:169]
	v_pk_mul_f32 v[166:167], v[166:167], v[162:163] op_sel_hi:[1,0]
	v_pk_mul_f32 v[168:169], v[168:169], v[162:163] op_sel_hi:[1,0]
	v_bfe_u32 v163, v166, 16, 1
	v_add3_u32 v163, v166, v163, s23
	v_bfe_u32 v166, v167, 16, 1
	v_lshrrev_b32_e32 v163, 16, v163
	v_add3_u32 v166, v167, v166, s23
	v_and_or_b32 v166, v166, s30, v163
	v_bfe_u32 v163, v168, 16, 1
	v_add3_u32 v163, v168, v163, s23
	v_bfe_u32 v167, v169, 16, 1
	v_lshrrev_b32_e32 v163, 16, v163
	v_add3_u32 v167, v169, v167, s23
	v_and_or_b32 v167, v167, s30, v163
	global_store_dwordx2 v[164:165], v[166:167], off offset:2560
	global_load_dwordx4 v[166:169], v[122:123], off
	s_waitcnt vmcnt(0)
	v_pk_mul_f32 v[166:167], v[24:25], v[166:167]
	v_pk_mul_f32 v[168:169], v[26:27], v[168:169]
	v_pk_mul_f32 v[166:167], v[166:167], v[162:163] op_sel_hi:[1,0]
	v_pk_mul_f32 v[168:169], v[168:169], v[162:163] op_sel_hi:[1,0]
	v_bfe_u32 v163, v166, 16, 1
	v_add3_u32 v163, v166, v163, s23
	v_bfe_u32 v166, v167, 16, 1
	v_lshrrev_b32_e32 v163, 16, v163
	v_add3_u32 v166, v167, v166, s23
	v_and_or_b32 v166, v166, s30, v163
	v_bfe_u32 v163, v168, 16, 1
	v_add3_u32 v163, v168, v163, s23
	v_bfe_u32 v167, v169, 16, 1
	v_lshrrev_b32_e32 v163, 16, v163
	v_add3_u32 v167, v169, v167, s23
	v_and_or_b32 v167, v167, s30, v163
	global_store_dwordx2 v[164:165], v[166:167], off offset:3072
	global_load_dwordx4 v[166:169], v[124:125], off
	s_waitcnt vmcnt(0)
	v_pk_mul_f32 v[166:167], v[28:29], v[166:167]
	v_pk_mul_f32 v[168:169], v[30:31], v[168:169]
	s_nop 0
	v_pk_mul_f32 v[168:169], v[168:169], v[162:163] op_sel_hi:[1,0]
	v_pk_mul_f32 v[162:163], v[166:167], v[162:163] op_sel_hi:[1,0]
	s_nop 0
	v_bfe_u32 v166, v162, 16, 1
	v_add3_u32 v162, v162, v166, s23
	v_bfe_u32 v166, v163, 16, 1
	v_lshrrev_b32_e32 v162, 16, v162
	v_add3_u32 v163, v163, v166, s23
	v_and_or_b32 v162, v163, s30, v162
	v_bfe_u32 v163, v168, 16, 1
	v_add3_u32 v163, v168, v163, s23
	v_bfe_u32 v166, v169, 16, 1
	v_lshrrev_b32_e32 v163, 16, v163
	v_add3_u32 v166, v169, v166, s23
	v_and_or_b32 v163, v166, s30, v163
	global_store_dwordx2 v[164:165], v[162:163], off offset:3584
	s_cbranch_execnz .LBB0_537
; template <int MODE>
; __device__ __forceinline__ void row_finish(const Params& p, int r, int lane, const float* gpost, const float* gnext, bf16_t* U, float coef, f32x4 (&h)[8], const u32x2 (&dw)[8]) {
;     ...
;     if (r >= ROWS) { if (MODE != 3) { u32x4* up = (u32x4*)(U + (size_t)r * DM);
; #pragma unroll
;             for (int j = 0; j < 4; ++j) up[lane + 64 * j] = (u32x4){0u, 0u, 0u, 0u}; } return; }
;     if (MODE >= 2 && r >= NTOKR) return;
;     if (MODE >= 1) {
;         f32x4 d[8]; float ss = 0.f;
; #pragma unroll
;         for (int j = 0; j < 8; ++j) { const u32x2 w = dw[j]; d[j] = (f32x4){bflo(w.x), bfhi(w.x), bflo(w.y), bfhi(w.y)};
;             ss += (d[j].x * d[j].x + d[j].y * d[j].y) + (d[j].z * d[j].z + d[j].w * d[j].w); }
;         ss = wave_sum(ss);
;         const float rs = rsqrtf(ss * (1.f / DM) + EPS) * coef;
.LBB0_548:
	s_mov_b32 s7, s5
	s_lshl_b64 s[6:7], s[6:7], 12
	s_mov_b32 s4, s5
	v_lshl_add_u64 v[0:1], v[126:127], 0, s[6:7]
	s_mov_b32 s6, s5
	s_mov_b32 s7, s5
	v_mov_b64_e32 v[2:3], s[4:5]
	v_mov_b64_e32 v[4:5], s[6:7]
	global_store_dwordx4 v[0:1], v[2:5], off
	global_store_dwordx4 v[0:1], v[2:5], off offset:1024
	global_store_dwordx4 v[0:1], v[2:5], off offset:2048
	global_store_dwordx4 v[0:1], v[2:5], off offset:3072
	v_mov_b32_e32 v0, v32
	v_mov_b32_e32 v1, v33
	v_mov_b32_e32 v2, v34
	v_mov_b32_e32 v3, v35
	v_mov_b32_e32 v4, v36
	v_mov_b32_e32 v5, v37
	v_mov_b32_e32 v6, v38
	v_mov_b32_e32 v7, v39
	v_mov_b32_e32 v8, v40
	v_mov_b32_e32 v9, v41
	v_mov_b32_e32 v10, v42
	v_mov_b32_e32 v11, v43
	v_mov_b32_e32 v12, v44
	v_mov_b32_e32 v13, v45
	v_mov_b32_e32 v14, v46
	v_mov_b32_e32 v15, v47
	v_mov_b32_e32 v16, v48
	v_mov_b32_e32 v17, v49
	v_mov_b32_e32 v18, v50
	v_mov_b32_e32 v19, v51
	v_mov_b32_e32 v20, v52
	v_mov_b32_e32 v21, v53
	v_mov_b32_e32 v22, v54
	v_mov_b32_e32 v23, v55
	v_mov_b32_e32 v24, v56
	v_mov_b32_e32 v25, v57
	v_mov_b32_e32 v26, v58
	v_mov_b32_e32 v27, v59
	v_mov_b32_e32 v28, v60
	v_mov_b32_e32 v29, v61
	v_mov_b32_e32 v30, v62
	v_mov_b32_e32 v31, v63
	s_cmp_gt_i32 s0, 0x80ff
	s_cbranch_scc1 .LBB0_523
.LBB0_549:
	s_andn2_b64 vcc, exec, s[8:9]
	s_mov_b64 s[6:7], -1
	s_cbranch_vccnz .LBB0_551
	s_waitcnt vmcnt(0) lgkmcnt(0)
	v_and_b32_e32 v39, 0xffff0000, v130
	v_and_b32_e32 v38, 0xffff0000, v132
	v_and_b32_e32 v167, 0xffff0000, v131
	v_and_b32_e32 v166, 0xffff0000, v133
	v_lshlrev_b32_e32 v37, 16, v130
	v_lshlrev_b32_e32 v36, 16, v132
	v_lshlrev_b32_e32 v165, 16, v131
	v_lshlrev_b32_e32 v164, 16, v133
	v_pk_mul_f32 v[32:33], v[38:39], v[38:39]
	v_pk_mul_f32 v[34:35], v[166:167], v[166:167]
	v_pk_fma_f32 v[32:33], v[36:37], v[36:37], v[32:33]
	v_pk_fma_f32 v[34:35], v[164:165], v[164:165], v[34:35]
	v_and_b32_e32 v43, 0xffff0000, v135
	v_pk_add_f32 v[32:33], v[32:33], v[34:35]
	v_and_b32_e32 v42, 0xffff0000, v134
	v_pk_add_f32 v[32:33], v[32:33], v[32:33] op_sel_hi:[0,1]
	v_lshlrev_b32_e32 v41, 16, v135
	v_lshlrev_b32_e32 v40, 16, v134
	v_pk_mul_f32 v[34:35], v[42:43], v[42:43]
	v_lshlrev_b32_e32 v44, 16, v136
	v_and_b32_e32 v45, 0xffff0000, v136
	v_lshlrev_b32_e32 v46, 16, v137
	v_lshlrev_b32_e32 v48, 16, v138
	v_pk_fma_f32 v[34:35], v[40:41], v[40:41], v[34:35]
	v_mul_f32_e32 v49, v44, v44
	v_mul_f32_e32 v53, v45, v45
	v_and_b32_e32 v47, 0xffff0000, v137
	v_mul_f32_e32 v32, v46, v46
	v_mov_b32_e32 v52, v48
	v_pk_add_f32 v[34:35], v[34:35], v[34:35] op_sel_hi:[0,1]
	v_pk_fma_f32 v[54:55], v[46:47], v[46:47], v[32:33] op_sel_hi:[1,1,0]
	v_and_b32_e32 v174, 0xffff0000, v138
	v_lshlrev_b32_e32 v50, 16, v139
	v_and_b32_e32 v51, 0xffff0000, v139
	v_pk_add_f32 v[52:53], v[48:49], v[52:53]
	v_mul_f32_e32 v54, v174, v174
	v_mul_f32_e32 v34, v50, v50
	v_mul_f32_e32 v32, v51, v51
	v_mul_f32_e32 v56, v48, v48
	v_mov_b32_e32 v57, v53
	v_pk_add_f32 v[52:53], v[56:57], v[54:55]
	v_pk_add_f32 v[32:33], v[34:35], v[32:33]
	v_and_b32_e32 v55, 0xffff0000, v141
	v_pk_add_f32 v[32:33], v[52:53], v[32:33]
	v_and_b32_e32 v54, 0xffff0000, v140
	v_pk_add_f32 v[32:33], v[32:33], v[32:33] op_sel_hi:[0,1]
	v_lshlrev_b32_e32 v53, 16, v141
	v_lshlrev_b32_e32 v52, 16, v140
	v_pk_mul_f32 v[34:35], v[54:55], v[54:55]
	v_lshlrev_b32_e32 v56, 16, v142
	v_and_b32_e32 v57, 0xffff0000, v142
	v_lshlrev_b32_e32 v58, 16, v143
	v_lshlrev_b32_e32 v60, 16, v144
	v_pk_fma_f32 v[34:35], v[52:53], v[52:53], v[34:35]
	v_mul_f32_e32 v61, v56, v56
	v_mul_f32_e32 v169, v57, v57
	v_and_b32_e32 v59, 0xffff0000, v143
	v_mul_f32_e32 v32, v58, v58
	v_mov_b32_e32 v168, v60
	v_pk_add_f32 v[34:35], v[34:35], v[34:35] op_sel_hi:[0,1]
	v_pk_fma_f32 v[170:171], v[58:59], v[58:59], v[32:33] op_sel_hi:[1,1,0]
	v_and_b32_e32 v163, 0xffff0000, v144
	v_lshlrev_b32_e32 v62, 16, v145
	v_and_b32_e32 v63, 0xffff0000, v145
	v_pk_add_f32 v[168:169], v[60:61], v[168:169]
	v_mul_f32_e32 v170, v163, v163
	v_mul_f32_e32 v34, v62, v62
	v_mul_f32_e32 v32, v63, v63
	v_mul_f32_e32 v172, v60, v60
	v_mov_b32_e32 v173, v169
	v_pk_add_f32 v[168:169], v[172:173], v[170:171]
	v_pk_add_f32 v[32:33], v[34:35], v[32:33]
	s_add_i32 s4, s0, 0xffff8000
	v_pk_add_f32 v[32:33], v[168:169], v[32:33]
	s_ashr_i32 s1, s0, 31
	v_add_f32_e32 v32, v32, v33
	ds_bpermute_b32 v33, v99, v32
	s_cmp_lt_i32 s0, 0x8000
	s_cselect_b32 s7, s1, 0
	s_cselect_b32 s6, s0, s4
	v_mov_b32_e32 v168, v37
	s_waitcnt lgkmcnt(0)
	v_add_f32_e32 v32, v32, v33
	ds_bpermute_b32 v33, v101, v32
	v_mov_b32_e32 v169, v39
	s_cselect_b32 s4, s15, s71
	s_cselect_b32 s8, s14, s70
	s_lshl_b64 s[6:7], s[6:7], 13
	s_waitcnt lgkmcnt(0)
	v_add_f32_e32 v32, v32, v33
	ds_bpermute_b32 v33, v103, v32
	s_add_u32 s6, s8, s6
	s_addc_u32 s7, s4, s7
	v_lshlrev_b32_e32 v49, 4, v96
	v_mov_b32_e32 v37, v38
	s_waitcnt lgkmcnt(0)
	v_add_f32_e32 v32, v32, v33
	ds_bpermute_b32 v33, v105, v32
	v_lshlrev_b32_e32 v61, 4, v98
	s_waitcnt lgkmcnt(0)
	v_add_f32_e32 v32, v32, v33
	ds_bpermute_b32 v33, v196, v32
	s_waitcnt lgkmcnt(0)
	v_add_f32_e32 v32, v32, v33
	ds_bpermute_b32 v33, v197, v32
	s_waitcnt lgkmcnt(0)
	v_add_f32_e32 v32, v32, v33
	v_fmamk_f32 v32, v32, 0x3a000000, v198
	v_cmp_gt_f32_e32 vcc, s31, v32
	v_mul_f32_e32 v33, 0x4b800000, v32
	s_nop 0
	v_cndmask_b32_e32 v32, v32, v33, vcc
	v_rsq_f32_e32 v32, v32
	s_nop 0
	v_mul_f32_e32 v33, 0x45800000, v32
	v_cndmask_b32_e32 v32, v32, v33, vcc
	v_mul_f32_e32 v162, 0.5, v32
	global_load_dwordx4 v[32:35], v[106:107], off
	s_waitcnt vmcnt(0)
; template <int MODE>
; __device__ __forceinline__ void row_finish(const Params& p, int r, int lane, const float* gpost, const float* gnext, bf16_t* U, float coef, f32x4 (&h)[8], const u32x2 (&dw)[8]) {
;     ...
;         f32x4* hd = (f32x4*)hrow(p, r);
; #pragma unroll
;         for (int j = 0; j < 8; ++j) { const f32x4 g = ((const f32x4*)gpost)[lane + 64 * j]; h[j] = h[j] + d[j] * g * rs; __builtin_nontemporal_store(h[j], &hd[lane + 64 * j]); }
;     }
;     if (MODE != 3) {
;         float s2 = 0.f;
; #pragma unroll
;         for (int j = 0; j < 8; ++j) s2 += (h[j].x * h[j].x + h[j].y * h[j].y) + (h[j].z * h[j].z + h[j].w * h[j].w);
;         s2 = wave_sum(s2);
;         const float rs2 = rsqrtf(s2 * (1.f / DM) + EPS);
	v_pk_mul_f32 v[32:33], v[168:169], v[32:33]
	v_mov_b32_e32 v168, v165
	v_mov_b32_e32 v169, v167
	v_pk_mul_f32 v[34:35], v[168:169], v[34:35]
	v_pk_fma_f32 v[32:33], v[32:33], v[162:163], v[64:65] op_sel_hi:[1,0,1]
	v_pk_fma_f32 v[34:35], v[34:35], v[162:163], v[66:67] op_sel_hi:[1,0,1]
	global_store_dwordx4 v49, v[32:35], s[6:7] nt
	global_load_dwordx4 v[168:171], v[106:107], off offset:1024
	v_mov_b32_e32 v165, v166
	s_waitcnt vmcnt(0)
	v_pk_mul_f32 v[164:165], v[164:165], v[170:171]
	v_pk_mul_f32 v[36:37], v[36:37], v[168:169]
	v_pk_fma_f32 v[38:39], v[164:165], v[162:163], v[70:71] op_sel_hi:[1,0,1]
	v_pk_fma_f32 v[36:37], v[36:37], v[162:163], v[68:69] op_sel_hi:[1,0,1]
	global_store_dwordx4 v49, v[36:39], s[6:7] offset:1024 nt
	global_load_dwordx4 v[164:167], v[106:107], off offset:2048
	v_mov_b32_e32 v168, v41
	v_mov_b32_e32 v169, v43
	v_mov_b32_e32 v41, v42
	s_waitcnt vmcnt(0)
	v_pk_mul_f32 v[166:167], v[166:167], v[168:169]
	v_pk_mul_f32 v[40:41], v[164:165], v[40:41]
	v_pk_fma_f32 v[42:43], v[166:167], v[162:163], v[74:75] op_sel_hi:[1,0,1]
	v_pk_fma_f32 v[40:41], v[40:41], v[162:163], v[72:73] op_sel_hi:[1,0,1]
	global_store_dwordx4 v49, v[40:43], s[6:7] offset:2048 nt
	global_load_dwordx4 v[164:167], v[106:107], off offset:3072
	v_mov_b32_e32 v168, v53
	v_mov_b32_e32 v169, v55
	v_mov_b32_e32 v53, v54
	s_waitcnt vmcnt(0)
	v_pk_mul_f32 v[46:47], v[46:47], v[166:167]
	v_pk_mul_f32 v[44:45], v[44:45], v[164:165]
	v_pk_fma_f32 v[46:47], v[46:47], v[162:163], v[78:79] op_sel_hi:[1,0,1]
	v_pk_fma_f32 v[44:45], v[44:45], v[162:163], v[76:77] op_sel_hi:[1,0,1]
	global_store_dwordx4 v49, v[44:47], s[6:7] offset:3072 nt
	global_load_dwordx4 v[164:167], v[108:109], off
	v_mov_b32_e32 v49, v174
	s_waitcnt vmcnt(0)
	v_pk_mul_f32 v[48:49], v[48:49], v[164:165]
	v_pk_mul_f32 v[50:51], v[50:51], v[166:167]
	v_pk_fma_f32 v[48:49], v[48:49], v[162:163], v[80:81] op_sel_hi:[1,0,1]
	v_pk_fma_f32 v[50:51], v[50:51], v[162:163], v[82:83] op_sel_hi:[1,0,1]
	global_store_dwordx4 v61, v[48:51], s[6:7] nt
	global_load_dwordx4 v[164:167], v[110:111], off
	v_lshlrev_b32_e32 v61, 4, v100
	s_waitcnt vmcnt(0)
	v_pk_mul_f32 v[166:167], v[166:167], v[168:169]
	v_pk_mul_f32 v[52:53], v[164:165], v[52:53]
	v_pk_fma_f32 v[54:55], v[162:163], v[166:167], v[86:87] op_sel_hi:[0,1,1]
	v_pk_fma_f32 v[52:53], v[162:163], v[52:53], v[84:85] op_sel_hi:[0,1,1]
	global_store_dwordx4 v61, v[52:55], s[6:7] nt
	global_load_dwordx4 v[164:167], v[112:113], off
	v_lshlrev_b32_e32 v61, 4, v102
	s_waitcnt vmcnt(0)
	v_pk_mul_f32 v[58:59], v[58:59], v[166:167]
	v_pk_mul_f32 v[56:57], v[56:57], v[164:165]
	v_pk_fma_f32 v[58:59], v[162:163], v[58:59], v[90:91] op_sel_hi:[0,1,1]
	v_pk_fma_f32 v[56:57], v[162:163], v[56:57], v[88:89] op_sel_hi:[0,1,1]
	global_store_dwordx4 v61, v[56:59], s[6:7] nt
	global_load_dwordx4 v[164:167], v[114:115], off
	v_mov_b32_e32 v61, v163
	s_waitcnt vmcnt(0)
	v_pk_mul_f32 v[60:61], v[60:61], v[164:165]
	v_pk_mul_f32 v[62:63], v[62:63], v[166:167]
	v_pk_fma_f32 v[60:61], v[162:163], v[60:61], v[92:93] op_sel_hi:[0,1,1]
	v_pk_fma_f32 v[62:63], v[162:163], v[62:63], v[94:95] op_sel_hi:[0,1,1]
	v_lshlrev_b32_e32 v162, 4, v104
	v_mov_b32_e32 v164, v33
	v_mov_b32_e32 v165, v37
	global_store_dwordx4 v162, v[60:63], s[6:7] nt
	v_mov_b32_e32 v162, v32
	v_mov_b32_e32 v163, v36
	v_pk_mul_f32 v[164:165], v[164:165], v[164:165]
	v_mov_b32_e32 v166, v35
	v_mov_b32_e32 v167, v39
	v_pk_fma_f32 v[162:163], v[162:163], v[162:163], v[164:165]
	v_mov_b32_e32 v164, v34
	v_mov_b32_e32 v165, v38
	v_pk_mul_f32 v[166:167], v[166:167], v[166:167]
	s_lshl_b64 s[6:7], s[0:1], 12
	v_pk_fma_f32 v[164:165], v[164:165], v[164:165], v[166:167]
	v_pk_mul_f32 v[166:167], v[42:43], v[42:43]
	v_pk_add_f32 v[162:163], v[162:163], v[164:165]
	v_pk_mul_f32 v[164:165], v[40:41], v[40:41]
	v_pk_add_f32 v[162:163], v[162:163], v[162:163] op_sel_hi:[0,1]
	v_pk_mov_b32 v[168:169], v[164:165], v[166:167] op_sel:[1,0]
	v_mov_b32_e32 v165, v167
	v_mul_f32_e32 v162, v44, v44
	v_pk_add_f32 v[164:165], v[168:169], v[164:165]
	v_pk_fma_f32 v[166:167], v[44:45], v[44:45], v[162:163] op_sel_hi:[1,1,0]
	v_mul_f32_e32 v162, v46, v46
	v_pk_add_f32 v[164:165], v[164:165], v[164:165] op_sel_hi:[0,1]
	v_pk_fma_f32 v[168:169], v[46:47], v[46:47], v[162:163] op_sel_hi:[1,1,0]
	v_mul_f32_e32 v166, v48, v48
	v_mul_f32_e32 v168, v49, v49
	v_mul_f32_e32 v164, v50, v50
	v_mul_f32_e32 v162, v51, v51
	v_pk_add_f32 v[166:167], v[166:167], v[168:169]
	v_pk_add_f32 v[162:163], v[164:165], v[162:163]
	v_pk_mul_f32 v[164:165], v[52:53], v[52:53]
	v_pk_add_f32 v[162:163], v[166:167], v[162:163]
	v_pk_mul_f32 v[166:167], v[54:55], v[54:55]
	v_pk_add_f32 v[162:163], v[162:163], v[162:163] op_sel_hi:[0,1]
	v_pk_mov_b32 v[168:169], v[164:165], v[166:167] op_sel:[1,0]
	v_mov_b32_e32 v165, v167
	v_mul_f32_e32 v162, v56, v56
	v_pk_add_f32 v[164:165], v[168:169], v[164:165]
	v_pk_fma_f32 v[166:167], v[56:57], v[56:57], v[162:163] op_sel_hi:[1,1,0]
	v_mul_f32_e32 v162, v58, v58
	v_pk_add_f32 v[164:165], v[164:165], v[164:165] op_sel_hi:[0,1]
	v_pk_fma_f32 v[168:169], v[58:59], v[58:59], v[162:163] op_sel_hi:[1,1,0]
	v_mul_f32_e32 v166, v60, v60
	v_mul_f32_e32 v168, v61, v61
	v_mul_f32_e32 v164, v62, v62
	v_mul_f32_e32 v162, v63, v63
	v_pk_add_f32 v[166:167], v[166:167], v[168:169]
	v_pk_add_f32 v[162:163], v[164:165], v[162:163]
	s_nop 0
	v_pk_add_f32 v[162:163], v[166:167], v[162:163]
	global_load_dwordx4 v[164:167], v[116:117], off
	v_add_f32_e32 v162, v162, v163
	ds_bpermute_b32 v163, v99, v162
	s_waitcnt lgkmcnt(0)
	v_add_f32_e32 v162, v162, v163
	ds_bpermute_b32 v163, v101, v162
	s_waitcnt lgkmcnt(0)
; __device__ __forceinline__ unsigned pk2(float lo, float hi) { return f2bf(lo) | (f2bf(hi) << 16); }
; template <int MODE>
; __device__ __forceinline__ void row_finish(const Params& p, int r, int lane, const float* gpost, const float* gnext, bf16_t* U, float coef, f32x4 (&h)[8], const u32x2 (&dw)[8]) {
;     ...
;         s2 = wave_sum(s2);
;         const float rs2 = rsqrtf(s2 * (1.f / DM) + EPS);
;         u32x2* up = (u32x2*)(U + (size_t)r * DM);
; #pragma unroll
;         for (int j = 0; j < 8; ++j) { const f32x4 g = ((const f32x4*)gnext)[lane + 64 * j]; const f32x4 v = h[j] * g * rs2;
;             u32x2 w; w.x = pk2(v.x, v.y); w.y = pk2(v.z, v.w); up[lane + 64 * j] = w; }
	v_add_f32_e32 v162, v162, v163
	ds_bpermute_b32 v163, v103, v162
	s_waitcnt lgkmcnt(0)
	v_add_f32_e32 v162, v162, v163
	ds_bpermute_b32 v163, v105, v162
	s_waitcnt lgkmcnt(0)
	v_add_f32_e32 v162, v162, v163
	ds_bpermute_b32 v163, v196, v162
	s_waitcnt lgkmcnt(0)
	v_add_f32_e32 v162, v162, v163
	ds_bpermute_b32 v163, v197, v162
	s_waitcnt lgkmcnt(0)
	v_add_f32_e32 v162, v162, v163
	v_fmamk_f32 v162, v162, 0x3a000000, v198
	v_cmp_gt_f32_e32 vcc, s31, v162
	v_mul_f32_e32 v163, 0x4b800000, v162
	s_waitcnt vmcnt(0)
	v_pk_mul_f32 v[164:165], v[32:33], v[164:165]
	v_cndmask_b32_e32 v162, v162, v163, vcc
	v_rsq_f32_e32 v162, v162
	v_pk_mul_f32 v[166:167], v[34:35], v[166:167]
	v_mul_f32_e32 v163, 0x45800000, v162
	v_cndmask_b32_e32 v162, v162, v163, vcc
	v_pk_mul_f32 v[164:165], v[164:165], v[162:163] op_sel_hi:[1,0]
	v_pk_mul_f32 v[168:169], v[166:167], v[162:163] op_sel_hi:[1,0]
	v_bfe_u32 v163, v164, 16, 1
	v_add3_u32 v163, v164, v163, s23
	v_bfe_u32 v164, v165, 16, 1
	v_lshrrev_b32_e32 v163, 16, v163
	v_add3_u32 v164, v165, v164, s23
	v_and_or_b32 v166, v164, s30, v163
	v_bfe_u32 v163, v168, 16, 1
	v_add3_u32 v163, v168, v163, s23
	v_bfe_u32 v164, v169, 16, 1
	v_lshrrev_b32_e32 v163, 16, v163
	v_add3_u32 v164, v169, v164, s23
	v_and_or_b32 v167, v164, s30, v163
	v_lshl_add_u64 v[164:165], v[128:129], 0, s[6:7]
	global_store_dwordx2 v[164:165], v[166:167], off
	global_load_dwordx4 v[166:169], v[116:117], off offset:1024
	s_mov_b64 s[6:7], 0
	s_waitcnt vmcnt(0)
	v_pk_mul_f32 v[166:167], v[36:37], v[166:167]
	v_pk_mul_f32 v[168:169], v[38:39], v[168:169]
	v_pk_mul_f32 v[166:167], v[166:167], v[162:163] op_sel_hi:[1,0]
	v_pk_mul_f32 v[168:169], v[168:169], v[162:163] op_sel_hi:[1,0]
	v_bfe_u32 v163, v166, 16, 1
	v_add3_u32 v163, v166, v163, s23
	v_bfe_u32 v166, v167, 16, 1
	v_lshrrev_b32_e32 v163, 16, v163
	v_add3_u32 v166, v167, v166, s23
	v_and_or_b32 v166, v166, s30, v163
	v_bfe_u32 v163, v168, 16, 1
	v_add3_u32 v163, v168, v163, s23
	v_bfe_u32 v167, v169, 16, 1
	v_lshrrev_b32_e32 v163, 16, v163
	v_add3_u32 v167, v169, v167, s23
	v_and_or_b32 v167, v167, s30, v163
	global_store_dwordx2 v[164:165], v[166:167], off offset:512
	global_load_dwordx4 v[166:169], v[116:117], off offset:2048
	s_waitcnt vmcnt(0)
	v_pk_mul_f32 v[166:167], v[40:41], v[166:167]
	v_pk_mul_f32 v[168:169], v[42:43], v[168:169]
	v_pk_mul_f32 v[166:167], v[166:167], v[162:163] op_sel_hi:[1,0]
	v_pk_mul_f32 v[168:169], v[168:169], v[162:163] op_sel_hi:[1,0]
	v_bfe_u32 v163, v166, 16, 1
	v_add3_u32 v163, v166, v163, s23
	v_bfe_u32 v166, v167, 16, 1
	v_lshrrev_b32_e32 v163, 16, v163
	v_add3_u32 v166, v167, v166, s23
	v_and_or_b32 v166, v166, s30, v163
	v_bfe_u32 v163, v168, 16, 1
	v_add3_u32 v163, v168, v163, s23
	v_bfe_u32 v167, v169, 16, 1
	v_lshrrev_b32_e32 v163, 16, v163
	v_add3_u32 v167, v169, v167, s23
	v_and_or_b32 v167, v167, s30, v163
	global_store_dwordx2 v[164:165], v[166:167], off offset:1024
	global_load_dwordx4 v[166:169], v[116:117], off offset:3072
	s_waitcnt vmcnt(0)
	v_pk_mul_f32 v[166:167], v[44:45], v[166:167]
	v_pk_mul_f32 v[168:169], v[46:47], v[168:169]
	v_pk_mul_f32 v[166:167], v[166:167], v[162:163] op_sel_hi:[1,0]
	v_pk_mul_f32 v[168:169], v[168:169], v[162:163] op_sel_hi:[1,0]
	v_bfe_u32 v163, v166, 16, 1
	v_add3_u32 v163, v166, v163, s23
	v_bfe_u32 v166, v167, 16, 1
	v_lshrrev_b32_e32 v163, 16, v163
	v_add3_u32 v166, v167, v166, s23
	v_and_or_b32 v166, v166, s30, v163
	v_bfe_u32 v163, v168, 16, 1
	v_add3_u32 v163, v168, v163, s23
	v_bfe_u32 v167, v169, 16, 1
	v_lshrrev_b32_e32 v163, 16, v163
	v_add3_u32 v167, v169, v167, s23
	v_and_or_b32 v167, v167, s30, v163
	global_store_dwordx2 v[164:165], v[166:167], off offset:1536
	global_load_dwordx4 v[166:169], v[118:119], off
	s_waitcnt vmcnt(0)
	v_pk_mul_f32 v[166:167], v[48:49], v[166:167]
	v_pk_mul_f32 v[168:169], v[50:51], v[168:169]
	v_pk_mul_f32 v[166:167], v[166:167], v[162:163] op_sel_hi:[1,0]
	v_pk_mul_f32 v[168:169], v[168:169], v[162:163] op_sel_hi:[1,0]
	v_bfe_u32 v163, v166, 16, 1
	v_add3_u32 v163, v166, v163, s23
	v_bfe_u32 v166, v167, 16, 1
	v_lshrrev_b32_e32 v163, 16, v163
	v_add3_u32 v166, v167, v166, s23
	v_and_or_b32 v166, v166, s30, v163
	v_bfe_u32 v163, v168, 16, 1
	v_add3_u32 v163, v168, v163, s23
	v_bfe_u32 v167, v169, 16, 1
	v_lshrrev_b32_e32 v163, 16, v163
	v_add3_u32 v167, v169, v167, s23
	v_and_or_b32 v167, v167, s30, v163
	global_store_dwordx2 v[164:165], v[166:167], off offset:2048
	global_load_dwordx4 v[166:169], v[120:121], off
	s_waitcnt vmcnt(0)
	v_pk_mul_f32 v[166:167], v[52:53], v[166:167]
	v_pk_mul_f32 v[168:169], v[54:55], v[168:169]
	v_pk_mul_f32 v[166:167], v[166:167], v[162:163] op_sel_hi:[1,0]
	v_pk_mul_f32 v[168:169], v[168:169], v[162:163] op_sel_hi:[1,0]
	v_bfe_u32 v163, v166, 16, 1
	v_add3_u32 v163, v166, v163, s23
	v_bfe_u32 v166, v167, 16, 1
	v_lshrrev_b32_e32 v163, 16, v163
	v_add3_u32 v166, v167, v166, s23
	v_and_or_b32 v166, v166, s30, v163
	v_bfe_u32 v163, v168, 16, 1
	v_add3_u32 v163, v168, v163, s23
	v_bfe_u32 v167, v169, 16, 1
	v_lshrrev_b32_e32 v163, 16, v163
	v_add3_u32 v167, v169, v167, s23
	v_and_or_b32 v167, v167, s30, v163
	global_store_dwordx2 v[164:165], v[166:167], off offset:2560
	global_load_dwordx4 v[166:169], v[122:123], off
	s_waitcnt vmcnt(0)
	v_pk_mul_f32 v[166:167], v[56:57], v[166:167]
	v_pk_mul_f32 v[168:169], v[58:59], v[168:169]
	v_pk_mul_f32 v[166:167], v[166:167], v[162:163] op_sel_hi:[1,0]
	v_pk_mul_f32 v[168:169], v[168:169], v[162:163] op_sel_hi:[1,0]
	v_bfe_u32 v163, v166, 16, 1
	v_add3_u32 v163, v166, v163, s23
	v_bfe_u32 v166, v167, 16, 1
	v_lshrrev_b32_e32 v163, 16, v163
	v_add3_u32 v166, v167, v166, s23
	v_and_or_b32 v166, v166, s30, v163
	v_bfe_u32 v163, v168, 16, 1
	v_add3_u32 v163, v168, v163, s23
	v_bfe_u32 v167, v169, 16, 1
	v_lshrrev_b32_e32 v163, 16, v163
	v_add3_u32 v167, v169, v167, s23
	v_and_or_b32 v167, v167, s30, v163
	global_store_dwordx2 v[164:165], v[166:167], off offset:3072
	global_load_dwordx4 v[166:169], v[124:125], off
	s_waitcnt vmcnt(0)
	v_pk_mul_f32 v[166:167], v[60:61], v[166:167]
	v_pk_mul_f32 v[168:169], v[62:63], v[168:169]
	s_nop 0
	v_pk_mul_f32 v[168:169], v[168:169], v[162:163] op_sel_hi:[1,0]
	v_pk_mul_f32 v[162:163], v[166:167], v[162:163] op_sel_hi:[1,0]
	s_nop 0
	v_bfe_u32 v166, v162, 16, 1
	v_add3_u32 v162, v162, v166, s23
	v_bfe_u32 v166, v163, 16, 1
	v_lshrrev_b32_e32 v162, 16, v162
	v_add3_u32 v163, v163, v166, s23
	v_and_or_b32 v162, v163, s30, v162
	v_bfe_u32 v163, v168, 16, 1
	v_add3_u32 v163, v168, v163, s23
	v_bfe_u32 v166, v169, 16, 1
	v_lshrrev_b32_e32 v163, 16, v163
	v_add3_u32 v166, v169, v166, s23
	v_and_or_b32 v163, v166, s30, v163
	global_store_dwordx2 v[164:165], v[162:163], off offset:3584
; template <int MODE>
; __device__ __forceinline__ void row_finish(const Params& p, int r, int lane, const float* gpost, const float* gnext, bf16_t* U, float coef, f32x4 (&h)[8], const u32x2 (&dw)[8]) {
;     if (r >= ROWSP) return;
;     if (r >= ROWS) { if (MODE != 3) { u32x4* up = (u32x4*)(U + (size_t)r * DM);
; #pragma unroll
;             for (int j = 0; j < 4; ++j) up[lane + 64 * j] = (u32x4){0u, 0u, 0u, 0u}; } return; }
.LBB0_551:
	s_andn2_b64 vcc, exec, s[6:7]
	s_cbranch_vccnz .LBB0_522
	s_mov_b32 s1, s5
	s_lshl_b64 s[6:7], s[0:1], 12
	v_lshl_add_u64 v[32:33], v[126:127], 0, s[6:7]
	s_mov_b32 s6, s5
	s_mov_b32 s7, s5
	s_mov_b32 s4, s5
	v_mov_b64_e32 v[36:37], s[6:7]
	v_mov_b64_e32 v[34:35], s[4:5]
	global_store_dwordx4 v[32:33], v[34:37], off
	global_store_dwordx4 v[32:33], v[34:37], off offset:1024
	global_store_dwordx4 v[32:33], v[34:37], off offset:2048
	global_store_dwordx4 v[32:33], v[34:37], off offset:3072
	s_waitcnt vmcnt(0)
	v_mov_b64_e32 v[32:33], v[64:65]
	v_mov_b64_e32 v[40:41], v[72:73]
	v_mov_b64_e32 v[36:37], v[68:69]
	v_mov_b64_e32 v[44:45], v[76:77]
	v_mov_b64_e32 v[48:49], v[80:81]
	v_mov_b64_e32 v[52:53], v[84:85]
	v_mov_b64_e32 v[56:57], v[88:89]
	v_mov_b64_e32 v[60:61], v[92:93]
	v_mov_b64_e32 v[34:35], v[66:67]
	v_mov_b64_e32 v[38:39], v[70:71]
	v_mov_b64_e32 v[42:43], v[74:75]
	v_mov_b64_e32 v[46:47], v[78:79]
	v_mov_b64_e32 v[50:51], v[82:83]
	v_mov_b64_e32 v[54:55], v[86:87]
	v_mov_b64_e32 v[58:59], v[90:91]
	v_mov_b64_e32 v[62:63], v[94:95]
	s_branch .LBB0_522

; __device__ __forceinline__ unsigned cvt_pk_bf16(float lo, float hi) { unsigned r; asm volatile("v_cvt_pk_bf16_f32 %0, %1, %2" : "=v"(r) : "v"(lo), "v"(hi)); return r; }
;     __device__ __forceinline__ void operator()(const f32x4 (&acc)[2][2][4][2], const Unit& u, int wr, int wc, int fr, int fq) const {
;     ...
;             bf16_t* base; int ld, ct;
;             if (pn < 4) { base = Q; ld = 1024; ct = pn; } else if (pn < 10) { base = Z; ld = 1024; ct = pn - 6; } else { base = XBC; ld = 1536; ct = pn - 10; }
;             base += ct * BM + c0;
; #pragma unroll
;             for (int ai = 0; ai < 2; ++ai)
; #pragma unroll
;                 for (int m = 0; m < 4; ++m) { bf16_t* rowp = base + (size_t)(row0 + ai * HALF + m * 16) * ld;
; #pragma unroll
;                     for (int bj = 0; bj < 2; ++bj) { const f32x4 v0 = acc[ai][bj][m][0], v1 = acc[ai][bj][m][1];
;                         u32x4 w; w.x = cvt_pk_bf16(v0[0], v0[1]); w.y = cvt_pk_bf16(v0[2], v0[3]); w.z = cvt_pk_bf16(v1[0], v1[1]); w.w = cvt_pk_bf16(v1[2], v1[3]);
;                         *(u32x4*)(rowp + bj * HALF) = w; } }
.LBB0_640:
	v_lshl_or_b32 v154, s28, 8, v160
	v_ashrrev_i32_e32 v155, 31, v154
	v_lshl_add_u64 v[154:155], v[154:155], 1, s[26:27]
	v_mad_i64_i32 v[172:173], s[26:27], s24, v152, 0
	v_lshl_add_u64 v[176:177], v[172:173], 1, v[154:155]
	v_cvt_pk_bf16_f32 v172, v124, v125
	v_cvt_pk_bf16_f32 v173, v126, v127
	v_cvt_pk_bf16_f32 v174, v120, v121
	v_cvt_pk_bf16_f32 v175, v122, v123
	global_store_dwordx4 v[176:177], v[172:175], off
	v_or_b32_e32 v136, 16, v152
	s_nop 0
	v_cvt_pk_bf16_f32 v172, v116, v117
	v_cvt_pk_bf16_f32 v173, v118, v119
	v_cvt_pk_bf16_f32 v174, v112, v113
	v_cvt_pk_bf16_f32 v175, v114, v115
	global_store_dwordx4 v[176:177], v[172:175], off offset:256
	s_nop 1
	v_mad_i64_i32 v[172:173], s[26:27], s24, v136, 0
	v_lshl_add_u64 v[176:177], v[172:173], 1, v[154:155]
	v_cvt_pk_bf16_f32 v172, v108, v109
	v_cvt_pk_bf16_f32 v173, v110, v111
	v_cvt_pk_bf16_f32 v174, v104, v105
	v_cvt_pk_bf16_f32 v175, v106, v107
	global_store_dwordx4 v[176:177], v[172:175], off
	v_or_b32_e32 v136, 32, v152
	s_nop 0
	v_cvt_pk_bf16_f32 v172, v100, v101
	v_cvt_pk_bf16_f32 v173, v102, v103
	v_cvt_pk_bf16_f32 v174, v96, v97
	v_cvt_pk_bf16_f32 v175, v98, v99
	global_store_dwordx4 v[176:177], v[172:175], off offset:256
	s_nop 1
	v_mad_i64_i32 v[172:173], s[26:27], s24, v136, 0
	v_lshl_add_u64 v[176:177], v[172:173], 1, v[154:155]
	v_cvt_pk_bf16_f32 v172, v92, v93
	v_cvt_pk_bf16_f32 v173, v94, v95
	v_cvt_pk_bf16_f32 v174, v88, v89
	v_cvt_pk_bf16_f32 v175, v90, v91
	global_store_dwordx4 v[176:177], v[172:175], off
	v_or_b32_e32 v136, 48, v152
	s_nop 0
	v_cvt_pk_bf16_f32 v172, v84, v85
	v_cvt_pk_bf16_f32 v173, v86, v87
	v_cvt_pk_bf16_f32 v174, v80, v81
	v_cvt_pk_bf16_f32 v175, v82, v83
	global_store_dwordx4 v[176:177], v[172:175], off offset:256
	s_nop 1
	v_mad_i64_i32 v[172:173], s[26:27], s24, v136, 0
	v_lshl_add_u64 v[176:177], v[172:173], 1, v[154:155]
	v_cvt_pk_bf16_f32 v172, v76, v77
	v_cvt_pk_bf16_f32 v173, v78, v79
	v_cvt_pk_bf16_f32 v174, v72, v73
	v_cvt_pk_bf16_f32 v175, v74, v75
	global_store_dwordx4 v[176:177], v[172:175], off
	v_add_u32_e32 v136, 0x80, v152
	s_nop 0
	v_cvt_pk_bf16_f32 v172, v68, v69
	v_cvt_pk_bf16_f32 v173, v70, v71
	v_cvt_pk_bf16_f32 v174, v64, v65
	v_cvt_pk_bf16_f32 v175, v66, v67
	global_store_dwordx4 v[176:177], v[172:175], off offset:256
	s_nop 1
	v_mad_i64_i32 v[172:173], s[26:27], s24, v136, 0
	v_lshl_add_u64 v[176:177], v[172:173], 1, v[154:155]
	v_cvt_pk_bf16_f32 v172, v60, v61
	v_cvt_pk_bf16_f32 v173, v62, v63
	v_cvt_pk_bf16_f32 v174, v56, v57
	v_cvt_pk_bf16_f32 v175, v58, v59
	global_store_dwordx4 v[176:177], v[172:175], off
	v_add_u32_e32 v136, 0x90, v152
	s_nop 0
	v_cvt_pk_bf16_f32 v172, v52, v53
	v_cvt_pk_bf16_f32 v173, v54, v55
	v_cvt_pk_bf16_f32 v174, v48, v49
	v_cvt_pk_bf16_f32 v175, v50, v51
	global_store_dwordx4 v[176:177], v[172:175], off offset:256
	s_nop 1
	v_mad_i64_i32 v[172:173], s[26:27], s24, v136, 0
	v_lshl_add_u64 v[176:177], v[172:173], 1, v[154:155]
	v_cvt_pk_bf16_f32 v172, v44, v45
	v_cvt_pk_bf16_f32 v173, v46, v47
	v_cvt_pk_bf16_f32 v174, v40, v41
	v_cvt_pk_bf16_f32 v175, v42, v43
	global_store_dwordx4 v[176:177], v[172:175], off
	v_add_u32_e32 v136, 0xa0, v152
	s_nop 0
	v_cvt_pk_bf16_f32 v172, v36, v37
	v_cvt_pk_bf16_f32 v173, v38, v39
	v_cvt_pk_bf16_f32 v174, v32, v33
	v_cvt_pk_bf16_f32 v175, v34, v35
	global_store_dwordx4 v[176:177], v[172:175], off offset:256
	s_nop 1
	v_mad_i64_i32 v[172:173], s[26:27], s24, v136, 0
	v_lshl_add_u64 v[176:177], v[172:173], 1, v[154:155]
	v_cvt_pk_bf16_f32 v172, v28, v29
	v_cvt_pk_bf16_f32 v173, v30, v31
	v_cvt_pk_bf16_f32 v174, v24, v25
	v_cvt_pk_bf16_f32 v175, v26, v27
	global_store_dwordx4 v[176:177], v[172:175], off
	v_add_u32_e32 v136, 0xb0, v152
	s_nop 0
	v_cvt_pk_bf16_f32 v172, v20, v21
	v_cvt_pk_bf16_f32 v173, v22, v23
	v_cvt_pk_bf16_f32 v174, v16, v17
	v_cvt_pk_bf16_f32 v175, v18, v19
	global_store_dwordx4 v[176:177], v[172:175], off offset:256
	s_nop 1
	v_mad_i64_i32 v[172:173], s[24:25], s24, v136, 0
	v_lshl_add_u64 v[154:155], v[172:173], 1, v[154:155]
	v_cvt_pk_bf16_f32 v172, v12, v13
	v_cvt_pk_bf16_f32 v173, v14, v15
	v_cvt_pk_bf16_f32 v174, v8, v9
	v_cvt_pk_bf16_f32 v175, v10, v11
	global_store_dwordx4 v[154:155], v[172:175], off
	s_mov_b64 s[24:25], 0
	s_nop 0
	v_cvt_pk_bf16_f32 v172, v4, v5
	v_cvt_pk_bf16_f32 v173, v6, v7
	v_cvt_pk_bf16_f32 v174, v0, v1
	v_cvt_pk_bf16_f32 v175, v2, v3
	global_store_dwordx4 v[154:155], v[172:175], off offset:256

; __device__ __forceinline__ unsigned cvt_pk_bf16(float lo, float hi) { unsigned r; asm volatile("v_cvt_pk_bf16_f32 %0, %1, %2" : "=v"(r) : "v"(lo), "v"(hi)); return r; }
;     __device__ __forceinline__ void operator()(const f32x4 (&acc)[2][2][4][2], const Unit& u, int wr, int wc, int fr, int fq) const {
;     ...
;                         int s, pos; row2sp(r, s, pos); const unsigned Lp = (unsigned)seq_Lpad(s), kb = (unsigned)seq_koff(s) * 4u;
; #pragma unroll
;                         for (int bj = 0; bj < 2; ++bj) { const f32x4 v0 = acc[ai][bj][m][0], v1 = acc[ai][bj][m][1];
;                             const unsigned c = (unsigned)(bj * HALF + c0), kvh = c >> 6, d = c & 63u;
;                             if (pn == 4) { u32x4 w; w.x = cvt_pk_bf16(v0[0], v0[1]); w.y = cvt_pk_bf16(v0[2], v0[3]); w.z = cvt_pk_bf16(v1[0], v1[1]); w.w = cvt_pk_bf16(v1[2], v1[3]);
;                                 *(u32x4*)(KP + (size_t)((kb + kvh * Lp + (unsigned)pos) * 64u + d)) = w; }
.LBB0_657:
	v_cvt_pk_bf16_f32 v116, v116, v117
	v_cvt_pk_bf16_f32 v117, v118, v119
	v_cvt_pk_bf16_f32 v118, v112, v113
	v_mad_u32_u24 v112, v151, s64, v154
	v_lshl_or_b32 v136, v112, 6, v161
	v_lshl_add_u64 v[112:113], v[136:137], 1, s[8:9]
	v_cvt_pk_bf16_f32 v119, v114, v115
	global_store_dwordx4 v[112:113], v[116:119], off

; __device__ __forceinline__ unsigned cvt_pk_bf16(float lo, float hi) { unsigned r; asm volatile("v_cvt_pk_bf16_f32 %0, %1, %2" : "=v"(r) : "v"(lo), "v"(hi)); return r; }
;     __device__ __forceinline__ void operator()(const f32x4 (&acc)[2][2][4][2], const Unit& u, int wr, int wc, int fr, int fq) const {
;     ...
;                         int s, pos; row2sp(r, s, pos); const unsigned Lp = (unsigned)seq_Lpad(s), kb = (unsigned)seq_koff(s) * 4u;
; #pragma unroll
;                         for (int bj = 0; bj < 2; ++bj) { const f32x4 v0 = acc[ai][bj][m][0], v1 = acc[ai][bj][m][1];
;                             const unsigned c = (unsigned)(bj * HALF + c0), kvh = c >> 6, d = c & 63u;
;                             if (pn == 4) { u32x4 w; w.x = cvt_pk_bf16(v0[0], v0[1]); w.y = cvt_pk_bf16(v0[2], v0[3]); w.z = cvt_pk_bf16(v1[0], v1[1]); w.w = cvt_pk_bf16(v1[2], v1[3]);
;                                 *(u32x4*)(KP + (size_t)((kb + kvh * Lp + (unsigned)pos) * 64u + d)) = w; }
.LBB0_671:
	v_cvt_pk_bf16_f32 v100, v100, v101
	v_cvt_pk_bf16_f32 v101, v102, v103
	v_cvt_pk_bf16_f32 v102, v96, v97
	v_mad_u32_u24 v96, v115, s64, v112
	v_lshl_or_b32 v136, v96, 6, v161
	v_lshl_add_u64 v[96:97], v[136:137], 1, s[8:9]
	v_cvt_pk_bf16_f32 v103, v98, v99
	global_store_dwordx4 v[96:97], v[100:103], off

; __device__ __forceinline__ unsigned cvt_pk_bf16(float lo, float hi) { unsigned r; asm volatile("v_cvt_pk_bf16_f32 %0, %1, %2" : "=v"(r) : "v"(lo), "v"(hi)); return r; }
;     __device__ __forceinline__ void operator()(const f32x4 (&acc)[2][2][4][2], const Unit& u, int wr, int wc, int fr, int fq) const {
;     ...
;                         int s, pos; row2sp(r, s, pos); const unsigned Lp = (unsigned)seq_Lpad(s), kb = (unsigned)seq_koff(s) * 4u;
; #pragma unroll
;                         for (int bj = 0; bj < 2; ++bj) { const f32x4 v0 = acc[ai][bj][m][0], v1 = acc[ai][bj][m][1];
;                             const unsigned c = (unsigned)(bj * HALF + c0), kvh = c >> 6, d = c & 63u;
;                             if (pn == 4) { u32x4 w; w.x = cvt_pk_bf16(v0[0], v0[1]); w.y = cvt_pk_bf16(v0[2], v0[3]); w.z = cvt_pk_bf16(v1[0], v1[1]); w.w = cvt_pk_bf16(v1[2], v1[3]);
;                                 *(u32x4*)(KP + (size_t)((kb + kvh * Lp + (unsigned)pos) * 64u + d)) = w; }
.LBB0_685:
	v_cvt_pk_bf16_f32 v84, v84, v85
	v_cvt_pk_bf16_f32 v85, v86, v87
	v_cvt_pk_bf16_f32 v86, v80, v81
	v_mad_u32_u24 v80, v99, s64, v96
	v_lshl_or_b32 v136, v80, 6, v161
	v_lshl_add_u64 v[80:81], v[136:137], 1, s[8:9]
	v_cvt_pk_bf16_f32 v87, v82, v83
	global_store_dwordx4 v[80:81], v[84:87], off

; __device__ __forceinline__ unsigned cvt_pk_bf16(float lo, float hi) { unsigned r; asm volatile("v_cvt_pk_bf16_f32 %0, %1, %2" : "=v"(r) : "v"(lo), "v"(hi)); return r; }
;     __device__ __forceinline__ void operator()(const f32x4 (&acc)[2][2][4][2], const Unit& u, int wr, int wc, int fr, int fq) const {
;     ...
;                         int s, pos; row2sp(r, s, pos); const unsigned Lp = (unsigned)seq_Lpad(s), kb = (unsigned)seq_koff(s) * 4u;
; #pragma unroll
;                         for (int bj = 0; bj < 2; ++bj) { const f32x4 v0 = acc[ai][bj][m][0], v1 = acc[ai][bj][m][1];
;                             const unsigned c = (unsigned)(bj * HALF + c0), kvh = c >> 6, d = c & 63u;
;                             if (pn == 4) { u32x4 w; w.x = cvt_pk_bf16(v0[0], v0[1]); w.y = cvt_pk_bf16(v0[2], v0[3]); w.z = cvt_pk_bf16(v1[0], v1[1]); w.w = cvt_pk_bf16(v1[2], v1[3]);
;                                 *(u32x4*)(KP + (size_t)((kb + kvh * Lp + (unsigned)pos) * 64u + d)) = w; }
.LBB0_699:
	v_cvt_pk_bf16_f32 v68, v68, v69
	v_cvt_pk_bf16_f32 v69, v70, v71
	v_cvt_pk_bf16_f32 v70, v64, v65
	v_mad_u32_u24 v64, v83, s64, v80
	v_lshl_or_b32 v136, v64, 6, v161
	v_lshl_add_u64 v[64:65], v[136:137], 1, s[8:9]
	v_cvt_pk_bf16_f32 v71, v66, v67
	global_store_dwordx4 v[64:65], v[68:71], off

; __device__ __forceinline__ unsigned cvt_pk_bf16(float lo, float hi) { unsigned r; asm volatile("v_cvt_pk_bf16_f32 %0, %1, %2" : "=v"(r) : "v"(lo), "v"(hi)); return r; }
;     __device__ __forceinline__ void operator()(const f32x4 (&acc)[2][2][4][2], const Unit& u, int wr, int wc, int fr, int fq) const {
;     ...
;                         int s, pos; row2sp(r, s, pos); const unsigned Lp = (unsigned)seq_Lpad(s), kb = (unsigned)seq_koff(s) * 4u;
; #pragma unroll
;                         for (int bj = 0; bj < 2; ++bj) { const f32x4 v0 = acc[ai][bj][m][0], v1 = acc[ai][bj][m][1];
;                             const unsigned c = (unsigned)(bj * HALF + c0), kvh = c >> 6, d = c & 63u;
;                             if (pn == 4) { u32x4 w; w.x = cvt_pk_bf16(v0[0], v0[1]); w.y = cvt_pk_bf16(v0[2], v0[3]); w.z = cvt_pk_bf16(v1[0], v1[1]); w.w = cvt_pk_bf16(v1[2], v1[3]);
;                                 *(u32x4*)(KP + (size_t)((kb + kvh * Lp + (unsigned)pos) * 64u + d)) = w; }
.LBB0_713:
	v_cvt_pk_bf16_f32 v52, v52, v53
	v_cvt_pk_bf16_f32 v53, v54, v55
	v_cvt_pk_bf16_f32 v54, v48, v49
	v_mad_u32_u24 v48, v67, s64, v64
	v_lshl_or_b32 v136, v48, 6, v161
	v_lshl_add_u64 v[48:49], v[136:137], 1, s[8:9]
	v_cvt_pk_bf16_f32 v55, v50, v51
	global_store_dwordx4 v[48:49], v[52:55], off

; __device__ __forceinline__ unsigned cvt_pk_bf16(float lo, float hi) { unsigned r; asm volatile("v_cvt_pk_bf16_f32 %0, %1, %2" : "=v"(r) : "v"(lo), "v"(hi)); return r; }
;     __device__ __forceinline__ void operator()(const f32x4 (&acc)[2][2][4][2], const Unit& u, int wr, int wc, int fr, int fq) const {
;     ...
;                         int s, pos; row2sp(r, s, pos); const unsigned Lp = (unsigned)seq_Lpad(s), kb = (unsigned)seq_koff(s) * 4u;
; #pragma unroll
;                         for (int bj = 0; bj < 2; ++bj) { const f32x4 v0 = acc[ai][bj][m][0], v1 = acc[ai][bj][m][1];
;                             const unsigned c = (unsigned)(bj * HALF + c0), kvh = c >> 6, d = c & 63u;
;                             if (pn == 4) { u32x4 w; w.x = cvt_pk_bf16(v0[0], v0[1]); w.y = cvt_pk_bf16(v0[2], v0[3]); w.z = cvt_pk_bf16(v1[0], v1[1]); w.w = cvt_pk_bf16(v1[2], v1[3]);
;                                 *(u32x4*)(KP + (size_t)((kb + kvh * Lp + (unsigned)pos) * 64u + d)) = w; }
.LBB0_727:
	v_cvt_pk_bf16_f32 v36, v36, v37
	v_cvt_pk_bf16_f32 v37, v38, v39
	v_cvt_pk_bf16_f32 v38, v32, v33
	v_mad_u32_u24 v32, v51, s64, v48
	v_lshl_or_b32 v136, v32, 6, v161
	v_lshl_add_u64 v[32:33], v[136:137], 1, s[8:9]
	v_cvt_pk_bf16_f32 v39, v34, v35
	global_store_dwordx4 v[32:33], v[36:39], off

; __device__ __forceinline__ unsigned cvt_pk_bf16(float lo, float hi) { unsigned r; asm volatile("v_cvt_pk_bf16_f32 %0, %1, %2" : "=v"(r) : "v"(lo), "v"(hi)); return r; }
;     __device__ __forceinline__ void operator()(const f32x4 (&acc)[2][2][4][2], const Unit& u, int wr, int wc, int fr, int fq) const {
;     ...
;                         int s, pos; row2sp(r, s, pos); const unsigned Lp = (unsigned)seq_Lpad(s), kb = (unsigned)seq_koff(s) * 4u;
; #pragma unroll
;                         for (int bj = 0; bj < 2; ++bj) { const f32x4 v0 = acc[ai][bj][m][0], v1 = acc[ai][bj][m][1];
;                             const unsigned c = (unsigned)(bj * HALF + c0), kvh = c >> 6, d = c & 63u;
;                             if (pn == 4) { u32x4 w; w.x = cvt_pk_bf16(v0[0], v0[1]); w.y = cvt_pk_bf16(v0[2], v0[3]); w.z = cvt_pk_bf16(v1[0], v1[1]); w.w = cvt_pk_bf16(v1[2], v1[3]);
;                                 *(u32x4*)(KP + (size_t)((kb + kvh * Lp + (unsigned)pos) * 64u + d)) = w; }
.LBB0_741:
	v_cvt_pk_bf16_f32 v20, v20, v21
	v_cvt_pk_bf16_f32 v21, v22, v23
	v_cvt_pk_bf16_f32 v22, v16, v17
	v_mad_u32_u24 v16, v35, s64, v32
	v_lshl_or_b32 v136, v16, 6, v161
	v_lshl_add_u64 v[16:17], v[136:137], 1, s[8:9]
	v_cvt_pk_bf16_f32 v23, v18, v19
	global_store_dwordx4 v[16:17], v[20:23], off

; __device__ __forceinline__ unsigned cvt_pk_bf16(float lo, float hi) { unsigned r; asm volatile("v_cvt_pk_bf16_f32 %0, %1, %2" : "=v"(r) : "v"(lo), "v"(hi)); return r; }
;     __device__ __forceinline__ void operator()(const f32x4 (&acc)[2][2][4][2], const Unit& u, int wr, int wc, int fr, int fq) const {
;     ...
;                         int s, pos; row2sp(r, s, pos); const unsigned Lp = (unsigned)seq_Lpad(s), kb = (unsigned)seq_koff(s) * 4u;
; #pragma unroll
;                         for (int bj = 0; bj < 2; ++bj) { const f32x4 v0 = acc[ai][bj][m][0], v1 = acc[ai][bj][m][1];
;                             const unsigned c = (unsigned)(bj * HALF + c0), kvh = c >> 6, d = c & 63u;
;                             if (pn == 4) { u32x4 w; w.x = cvt_pk_bf16(v0[0], v0[1]); w.y = cvt_pk_bf16(v0[2], v0[3]); w.z = cvt_pk_bf16(v1[0], v1[1]); w.w = cvt_pk_bf16(v1[2], v1[3]);
;                                 *(u32x4*)(KP + (size_t)((kb + kvh * Lp + (unsigned)pos) * 64u + d)) = w; }
.LBB0_755:
	v_cvt_pk_bf16_f32 v4, v4, v5
	v_cvt_pk_bf16_f32 v5, v6, v7
	v_cvt_pk_bf16_f32 v6, v0, v1
	v_mad_u32_u24 v0, v19, s64, v16
	v_lshl_or_b32 v136, v0, 6, v161
	v_lshl_add_u64 v[0:1], v[136:137], 1, s[8:9]
	v_cvt_pk_bf16_f32 v7, v2, v3
	global_store_dwordx4 v[0:1], v[4:7], off

; __device__ __forceinline__ unsigned f2bf(float f) { unsigned u = __builtin_bit_cast(unsigned, f); return (u + 0x7fffu + ((u >> 16) & 1u)) >> 16; }
; __device__ __forceinline__ unsigned cvt_pk_bf16(float lo, float hi) { unsigned r; asm volatile("v_cvt_pk_bf16_f32 %0, %1, %2" : "=v"(r) : "v"(lo), "v"(hi)); return r; }
;     __device__ __forceinline__ void operator()(const f32x4 (&acc)[2][2][4][2], const Unit& u, int wr, int wc, int fr, int fq) const {
;     ...
;                     int r = row0 + ai * HALF + m * 16; asm volatile("" : "+v"(r));
;                     if (r < ROWS) {
;                         int s, pos; row2sp(r, s, pos); const unsigned Lp = (unsigned)seq_Lpad(s), kb = (unsigned)seq_koff(s) * 4u;
; #pragma unroll
;                         for (int bj = 0; bj < 2; ++bj) { const f32x4 v0 = acc[ai][bj][m][0], v1 = acc[ai][bj][m][1];
;                             const unsigned c = (unsigned)(bj * HALF + c0), kvh = c >> 6, d = c & 63u;
;                             if (pn == 4) { u32x4 w; w.x = cvt_pk_bf16(v0[0], v0[1]); w.y = cvt_pk_bf16(v0[2], v0[3]); w.z = cvt_pk_bf16(v1[0], v1[1]); w.w = cvt_pk_bf16(v1[2], v1[3]);
;                                 *(u32x4*)(KP + (size_t)((kb + kvh * Lp + (unsigned)pos) * 64u + d)) = w; }
;                             else { unsigned vo = kb * 64u + (kvh * 64u + d) * Lp + (unsigned)pos;
; #pragma unroll
;                                 for (int i = 0; i < 4; ++i) { VT[vo] = (bf16_t)f2bf(v0[i]); vo += Lp; }
; #pragma unroll
;                                 for (int i = 0; i < 4; ++i) { VT[vo] = (bf16_t)f2bf(v1[i]); vo += Lp; } } }
.LBB0_759:
	v_mad_u32_u24 v136, v151, v160, v156
	v_bfe_u32 v154, v124, 16, 1
	v_add3_u32 v172, v124, v154, s74
	v_lshl_add_u64 v[154:155], v[136:137], 1, s[40:41]
	global_store_short_d16_hi v[154:155], v172, off
	v_add_u32_e32 v136, v136, v151
	v_bfe_u32 v154, v125, 16, 1
	v_add3_u32 v172, v125, v154, s74
	v_lshl_add_u64 v[154:155], v[136:137], 1, s[40:41]
	global_store_short_d16_hi v[154:155], v172, off
	v_add_u32_e32 v136, v136, v151
	v_bfe_u32 v154, v126, 16, 1
	v_add3_u32 v172, v126, v154, s74
	v_lshl_add_u64 v[154:155], v[136:137], 1, s[40:41]
	global_store_short_d16_hi v[154:155], v172, off
	v_add_u32_e32 v136, v136, v151
	v_bfe_u32 v154, v127, 16, 1
	v_add3_u32 v172, v127, v154, s74
	v_lshl_add_u64 v[154:155], v[136:137], 1, s[40:41]
	global_store_short_d16_hi v[154:155], v172, off
	v_add_u32_e32 v136, v136, v151
	v_bfe_u32 v154, v120, 16, 1
	v_add3_u32 v172, v120, v154, s74
	v_lshl_add_u64 v[154:155], v[136:137], 1, s[40:41]
	global_store_short_d16_hi v[154:155], v172, off
	v_add_u32_e32 v136, v136, v151
	v_bfe_u32 v154, v121, 16, 1
	v_add3_u32 v172, v121, v154, s74
	v_lshl_add_u64 v[154:155], v[136:137], 1, s[40:41]
	global_store_short_d16_hi v[154:155], v172, off
	v_add_u32_e32 v136, v136, v151
	v_bfe_u32 v154, v122, 16, 1
	v_add3_u32 v172, v122, v154, s74
	v_lshl_add_u64 v[154:155], v[136:137], 1, s[40:41]
	global_store_short_d16_hi v[154:155], v172, off
	v_add_u32_e32 v136, v136, v151
	v_bfe_u32 v154, v123, 16, 1
	v_add3_u32 v172, v123, v154, s74
	v_lshl_add_u64 v[154:155], v[136:137], 1, s[40:41]
	global_store_short_d16_hi v[154:155], v172, off
	v_mad_u64_u32 v[154:155], s[28:29], v153, s76, v[156:157]
	s_cbranch_execnz .LBB0_655
.LBB0_760:
	v_cvt_pk_bf16_f32 v124, v124, v125
	v_cvt_pk_bf16_f32 v125, v126, v127
	v_cvt_pk_bf16_f32 v126, v120, v121
	v_mad_u32_u24 v120, v151, s63, v154
	v_lshl_or_b32 v136, v120, 6, v161
	v_lshl_add_u64 v[120:121], v[136:137], 1, s[8:9]
	v_cvt_pk_bf16_f32 v127, v122, v123
	global_store_dwordx4 v[120:121], v[124:127], off
	s_andn2_b64 vcc, exec, s[24:25]
	s_mov_b64 s[28:29], -1
	s_cbranch_vccnz .LBB0_656
.LBB0_761:
	v_mad_u32_u24 v136, v151, v162, v156
	v_bfe_u32 v120, v116, 16, 1
	v_add3_u32 v122, v116, v120, s74
	v_lshl_add_u64 v[120:121], v[136:137], 1, s[40:41]
	global_store_short_d16_hi v[120:121], v122, off
	v_add_u32_e32 v136, v136, v151
	v_bfe_u32 v120, v117, 16, 1
	v_add3_u32 v122, v117, v120, s74
	v_lshl_add_u64 v[120:121], v[136:137], 1, s[40:41]
	global_store_short_d16_hi v[120:121], v122, off
	v_add_u32_e32 v136, v136, v151
	v_bfe_u32 v120, v118, 16, 1
	v_add3_u32 v122, v118, v120, s74
	v_lshl_add_u64 v[120:121], v[136:137], 1, s[40:41]
	global_store_short_d16_hi v[120:121], v122, off
	v_add_u32_e32 v136, v136, v151
	v_bfe_u32 v120, v119, 16, 1
	v_add3_u32 v122, v119, v120, s74
	v_lshl_add_u64 v[120:121], v[136:137], 1, s[40:41]
	global_store_short_d16_hi v[120:121], v122, off
	v_add_u32_e32 v136, v136, v151
	v_bfe_u32 v120, v112, 16, 1
	v_add3_u32 v122, v112, v120, s74
	v_lshl_add_u64 v[120:121], v[136:137], 1, s[40:41]
	global_store_short_d16_hi v[120:121], v122, off
	v_add_u32_e32 v136, v136, v151
	v_bfe_u32 v120, v113, 16, 1
	v_add3_u32 v122, v113, v120, s74
	v_lshl_add_u64 v[120:121], v[136:137], 1, s[40:41]
	global_store_short_d16_hi v[120:121], v122, off
	v_add_u32_e32 v136, v136, v151
	v_bfe_u32 v120, v114, 16, 1
	v_add3_u32 v122, v114, v120, s74
	v_lshl_add_u64 v[120:121], v[136:137], 1, s[40:41]
	global_store_short_d16_hi v[120:121], v122, off
	v_add_u32_e32 v136, v136, v151
	v_bfe_u32 v120, v115, 16, 1
	v_add3_u32 v122, v115, v120, s74
	v_lshl_add_u64 v[120:121], v[136:137], 1, s[40:41]
	global_store_short_d16_hi v[120:121], v122, off
	s_cbranch_execz .LBB0_657
	s_branch .LBB0_658
.LBB0_762:
	v_mad_u32_u24 v136, v115, v160, v114
	v_bfe_u32 v113, v108, 16, 1
	v_add3_u32 v113, v108, v113, s74
	v_lshl_add_u64 v[116:117], v[136:137], 1, s[40:41]
	global_store_short_d16_hi v[116:117], v113, off
	v_add_u32_e32 v136, v136, v115
	v_bfe_u32 v113, v109, 16, 1
	v_add3_u32 v113, v109, v113, s74
	v_lshl_add_u64 v[116:117], v[136:137], 1, s[40:41]
	global_store_short_d16_hi v[116:117], v113, off
	v_add_u32_e32 v136, v136, v115
	v_bfe_u32 v113, v110, 16, 1
	v_add3_u32 v113, v110, v113, s74
	v_lshl_add_u64 v[116:117], v[136:137], 1, s[40:41]
	global_store_short_d16_hi v[116:117], v113, off
	v_add_u32_e32 v136, v136, v115
	v_bfe_u32 v113, v111, 16, 1
	v_add3_u32 v113, v111, v113, s74
	v_lshl_add_u64 v[116:117], v[136:137], 1, s[40:41]
	global_store_short_d16_hi v[116:117], v113, off
	v_add_u32_e32 v136, v136, v115
	v_bfe_u32 v113, v104, 16, 1
	v_add3_u32 v113, v104, v113, s74
	v_lshl_add_u64 v[116:117], v[136:137], 1, s[40:41]
	global_store_short_d16_hi v[116:117], v113, off
	v_add_u32_e32 v136, v136, v115
	v_bfe_u32 v113, v105, 16, 1
	v_add3_u32 v113, v105, v113, s74
	v_lshl_add_u64 v[116:117], v[136:137], 1, s[40:41]
	global_store_short_d16_hi v[116:117], v113, off
	v_add_u32_e32 v136, v136, v115
	v_bfe_u32 v113, v106, 16, 1
	v_add3_u32 v113, v106, v113, s74
	v_lshl_add_u64 v[116:117], v[136:137], 1, s[40:41]
	global_store_short_d16_hi v[116:117], v113, off
	v_add_u32_e32 v136, v136, v115
	v_bfe_u32 v113, v107, 16, 1
	v_add3_u32 v113, v107, v113, s74
	v_lshl_add_u64 v[116:117], v[136:137], 1, s[40:41]
	global_store_short_d16_hi v[116:117], v113, off
	v_mad_u64_u32 v[112:113], s[28:29], v112, s76, v[114:115]
	s_cbranch_execnz .LBB0_669
.LBB0_763:
	v_cvt_pk_bf16_f32 v108, v108, v109
	v_cvt_pk_bf16_f32 v109, v110, v111
	v_cvt_pk_bf16_f32 v110, v104, v105
	v_mad_u32_u24 v104, v115, s63, v112
	v_lshl_or_b32 v136, v104, 6, v161
	v_lshl_add_u64 v[104:105], v[136:137], 1, s[8:9]
	v_cvt_pk_bf16_f32 v111, v106, v107
	global_store_dwordx4 v[104:105], v[108:111], off
	s_and_b64 vcc, exec, s[38:39]
	s_mov_b64 s[28:29], -1
	s_cbranch_vccnz .LBB0_670
; __device__ __forceinline__ unsigned f2bf(float f) { unsigned u = __builtin_bit_cast(unsigned, f); return (u + 0x7fffu + ((u >> 16) & 1u)) >> 16; }
; __device__ __forceinline__ unsigned cvt_pk_bf16(float lo, float hi) { unsigned r; asm volatile("v_cvt_pk_bf16_f32 %0, %1, %2" : "=v"(r) : "v"(lo), "v"(hi)); return r; }
;     __device__ __forceinline__ void operator()(const f32x4 (&acc)[2][2][4][2], const Unit& u, int wr, int wc, int fr, int fq) const {
;     ...
;                         for (int bj = 0; bj < 2; ++bj) { const f32x4 v0 = acc[ai][bj][m][0], v1 = acc[ai][bj][m][1];
;                             const unsigned c = (unsigned)(bj * HALF + c0), kvh = c >> 6, d = c & 63u;
;                             if (pn == 4) { u32x4 w; w.x = cvt_pk_bf16(v0[0], v0[1]); w.y = cvt_pk_bf16(v0[2], v0[3]); w.z = cvt_pk_bf16(v1[0], v1[1]); w.w = cvt_pk_bf16(v1[2], v1[3]);
;                                 *(u32x4*)(KP + (size_t)((kb + kvh * Lp + (unsigned)pos) * 64u + d)) = w; }
;                             else { unsigned vo = kb * 64u + (kvh * 64u + d) * Lp + (unsigned)pos;
; #pragma unroll
;                                 for (int i = 0; i < 4; ++i) { VT[vo] = (bf16_t)f2bf(v0[i]); vo += Lp; }
; #pragma unroll
;                                 for (int i = 0; i < 4; ++i) { VT[vo] = (bf16_t)f2bf(v1[i]); vo += Lp; } } }
.LBB0_764:
	v_mad_u32_u24 v136, v115, v162, v114
	v_bfe_u32 v104, v100, 16, 1
	v_add3_u32 v106, v100, v104, s74
	v_lshl_add_u64 v[104:105], v[136:137], 1, s[40:41]
	global_store_short_d16_hi v[104:105], v106, off
	v_add_u32_e32 v136, v136, v115
	v_bfe_u32 v104, v101, 16, 1
	v_add3_u32 v106, v101, v104, s74
	v_lshl_add_u64 v[104:105], v[136:137], 1, s[40:41]
	global_store_short_d16_hi v[104:105], v106, off
	v_add_u32_e32 v136, v136, v115
	v_bfe_u32 v104, v102, 16, 1
	v_add3_u32 v106, v102, v104, s74
	v_lshl_add_u64 v[104:105], v[136:137], 1, s[40:41]
	global_store_short_d16_hi v[104:105], v106, off
	v_add_u32_e32 v136, v136, v115
	v_bfe_u32 v104, v103, 16, 1
	v_add3_u32 v106, v103, v104, s74
	v_lshl_add_u64 v[104:105], v[136:137], 1, s[40:41]
	global_store_short_d16_hi v[104:105], v106, off
	v_add_u32_e32 v136, v136, v115
	v_bfe_u32 v104, v96, 16, 1
	v_add3_u32 v106, v96, v104, s74
	v_lshl_add_u64 v[104:105], v[136:137], 1, s[40:41]
	global_store_short_d16_hi v[104:105], v106, off
	v_add_u32_e32 v136, v136, v115
	v_bfe_u32 v104, v97, 16, 1
	v_add3_u32 v106, v97, v104, s74
	v_lshl_add_u64 v[104:105], v[136:137], 1, s[40:41]
	global_store_short_d16_hi v[104:105], v106, off
	v_add_u32_e32 v136, v136, v115
	v_bfe_u32 v104, v98, 16, 1
	v_add3_u32 v106, v98, v104, s74
	v_lshl_add_u64 v[104:105], v[136:137], 1, s[40:41]
	global_store_short_d16_hi v[104:105], v106, off
	v_add_u32_e32 v136, v136, v115
	v_bfe_u32 v104, v99, 16, 1
	v_add3_u32 v106, v99, v104, s74
	v_lshl_add_u64 v[104:105], v[136:137], 1, s[40:41]
	global_store_short_d16_hi v[104:105], v106, off
	s_cbranch_execz .LBB0_671
	s_branch .LBB0_672
.LBB0_765:
	v_mad_u32_u24 v136, v99, v160, v98
	v_bfe_u32 v97, v92, 16, 1
	v_add3_u32 v97, v92, v97, s74
	v_lshl_add_u64 v[100:101], v[136:137], 1, s[40:41]
	global_store_short_d16_hi v[100:101], v97, off
	v_add_u32_e32 v136, v136, v99
	v_bfe_u32 v97, v93, 16, 1
	v_add3_u32 v97, v93, v97, s74
	v_lshl_add_u64 v[100:101], v[136:137], 1, s[40:41]
	global_store_short_d16_hi v[100:101], v97, off
	v_add_u32_e32 v136, v136, v99
	v_bfe_u32 v97, v94, 16, 1
	v_add3_u32 v97, v94, v97, s74
	v_lshl_add_u64 v[100:101], v[136:137], 1, s[40:41]
	global_store_short_d16_hi v[100:101], v97, off
	v_add_u32_e32 v136, v136, v99
	v_bfe_u32 v97, v95, 16, 1
	v_add3_u32 v97, v95, v97, s74
	v_lshl_add_u64 v[100:101], v[136:137], 1, s[40:41]
	global_store_short_d16_hi v[100:101], v97, off
	v_add_u32_e32 v136, v136, v99
	v_bfe_u32 v97, v88, 16, 1
	v_add3_u32 v97, v88, v97, s74
	v_lshl_add_u64 v[100:101], v[136:137], 1, s[40:41]
	global_store_short_d16_hi v[100:101], v97, off
	v_add_u32_e32 v136, v136, v99
	v_bfe_u32 v97, v89, 16, 1
	v_add3_u32 v97, v89, v97, s74
	v_lshl_add_u64 v[100:101], v[136:137], 1, s[40:41]
	global_store_short_d16_hi v[100:101], v97, off
	v_add_u32_e32 v136, v136, v99
	v_bfe_u32 v97, v90, 16, 1
	v_add3_u32 v97, v90, v97, s74
	v_lshl_add_u64 v[100:101], v[136:137], 1, s[40:41]
	global_store_short_d16_hi v[100:101], v97, off
	v_add_u32_e32 v136, v136, v99
	v_bfe_u32 v97, v91, 16, 1
	v_add3_u32 v97, v91, v97, s74
	v_lshl_add_u64 v[100:101], v[136:137], 1, s[40:41]
	global_store_short_d16_hi v[100:101], v97, off
	v_mad_u64_u32 v[96:97], s[28:29], v96, s76, v[98:99]
	s_cbranch_execnz .LBB0_683
.LBB0_766:
	v_cvt_pk_bf16_f32 v92, v92, v93
	v_cvt_pk_bf16_f32 v93, v94, v95
	v_cvt_pk_bf16_f32 v94, v88, v89
	v_mad_u32_u24 v88, v99, s63, v96
	v_lshl_or_b32 v136, v88, 6, v161
	v_lshl_add_u64 v[88:89], v[136:137], 1, s[8:9]
	v_cvt_pk_bf16_f32 v95, v90, v91
	global_store_dwordx4 v[88:89], v[92:95], off
	s_and_b64 vcc, exec, s[38:39]
	s_mov_b64 s[28:29], -1
	s_cbranch_vccnz .LBB0_684
.LBB0_767:
	v_mad_u32_u24 v136, v99, v162, v98
	v_bfe_u32 v88, v84, 16, 1
	v_add3_u32 v90, v84, v88, s74
	v_lshl_add_u64 v[88:89], v[136:137], 1, s[40:41]
	global_store_short_d16_hi v[88:89], v90, off
	v_add_u32_e32 v136, v136, v99
	v_bfe_u32 v88, v85, 16, 1
	v_add3_u32 v90, v85, v88, s74
	v_lshl_add_u64 v[88:89], v[136:137], 1, s[40:41]
	global_store_short_d16_hi v[88:89], v90, off
	v_add_u32_e32 v136, v136, v99
	v_bfe_u32 v88, v86, 16, 1
	v_add3_u32 v90, v86, v88, s74
	v_lshl_add_u64 v[88:89], v[136:137], 1, s[40:41]
	global_store_short_d16_hi v[88:89], v90, off
	v_add_u32_e32 v136, v136, v99
	v_bfe_u32 v88, v87, 16, 1
	v_add3_u32 v90, v87, v88, s74
	v_lshl_add_u64 v[88:89], v[136:137], 1, s[40:41]
	global_store_short_d16_hi v[88:89], v90, off
	v_add_u32_e32 v136, v136, v99
	v_bfe_u32 v88, v80, 16, 1
	v_add3_u32 v90, v80, v88, s74
	v_lshl_add_u64 v[88:89], v[136:137], 1, s[40:41]
	global_store_short_d16_hi v[88:89], v90, off
	v_add_u32_e32 v136, v136, v99
	v_bfe_u32 v88, v81, 16, 1
	v_add3_u32 v90, v81, v88, s74
	v_lshl_add_u64 v[88:89], v[136:137], 1, s[40:41]
	global_store_short_d16_hi v[88:89], v90, off
	v_add_u32_e32 v136, v136, v99
	v_bfe_u32 v88, v82, 16, 1
	v_add3_u32 v90, v82, v88, s74
	v_lshl_add_u64 v[88:89], v[136:137], 1, s[40:41]
	global_store_short_d16_hi v[88:89], v90, off
	v_add_u32_e32 v136, v136, v99
	v_bfe_u32 v88, v83, 16, 1
	v_add3_u32 v90, v83, v88, s74
	v_lshl_add_u64 v[88:89], v[136:137], 1, s[40:41]
	global_store_short_d16_hi v[88:89], v90, off
	s_cbranch_execz .LBB0_685
	s_branch .LBB0_686
; __device__ __forceinline__ unsigned f2bf(float f) { unsigned u = __builtin_bit_cast(unsigned, f); return (u + 0x7fffu + ((u >> 16) & 1u)) >> 16; }
; __device__ __forceinline__ unsigned cvt_pk_bf16(float lo, float hi) { unsigned r; asm volatile("v_cvt_pk_bf16_f32 %0, %1, %2" : "=v"(r) : "v"(lo), "v"(hi)); return r; }
;     __device__ __forceinline__ void operator()(const f32x4 (&acc)[2][2][4][2], const Unit& u, int wr, int wc, int fr, int fq) const {
;     ...
;                         for (int bj = 0; bj < 2; ++bj) { const f32x4 v0 = acc[ai][bj][m][0], v1 = acc[ai][bj][m][1];
;                             const unsigned c = (unsigned)(bj * HALF + c0), kvh = c >> 6, d = c & 63u;
;                             if (pn == 4) { u32x4 w; w.x = cvt_pk_bf16(v0[0], v0[1]); w.y = cvt_pk_bf16(v0[2], v0[3]); w.z = cvt_pk_bf16(v1[0], v1[1]); w.w = cvt_pk_bf16(v1[2], v1[3]);
;                                 *(u32x4*)(KP + (size_t)((kb + kvh * Lp + (unsigned)pos) * 64u + d)) = w; }
;                             else { unsigned vo = kb * 64u + (kvh * 64u + d) * Lp + (unsigned)pos;
; #pragma unroll
;                                 for (int i = 0; i < 4; ++i) { VT[vo] = (bf16_t)f2bf(v0[i]); vo += Lp; }
; #pragma unroll
;                                 for (int i = 0; i < 4; ++i) { VT[vo] = (bf16_t)f2bf(v1[i]); vo += Lp; } } }
.LBB0_768:
	v_mad_u32_u24 v136, v83, v160, v82
	v_bfe_u32 v81, v76, 16, 1
	v_add3_u32 v81, v76, v81, s74
	v_lshl_add_u64 v[84:85], v[136:137], 1, s[40:41]
	global_store_short_d16_hi v[84:85], v81, off
	v_add_u32_e32 v136, v136, v83
	v_bfe_u32 v81, v77, 16, 1
	v_add3_u32 v81, v77, v81, s74
	v_lshl_add_u64 v[84:85], v[136:137], 1, s[40:41]
	global_store_short_d16_hi v[84:85], v81, off
	v_add_u32_e32 v136, v136, v83
	v_bfe_u32 v81, v78, 16, 1
	v_add3_u32 v81, v78, v81, s74
	v_lshl_add_u64 v[84:85], v[136:137], 1, s[40:41]
	global_store_short_d16_hi v[84:85], v81, off
	v_add_u32_e32 v136, v136, v83
	v_bfe_u32 v81, v79, 16, 1
	v_add3_u32 v81, v79, v81, s74
	v_lshl_add_u64 v[84:85], v[136:137], 1, s[40:41]
	global_store_short_d16_hi v[84:85], v81, off
	v_add_u32_e32 v136, v136, v83
	v_bfe_u32 v81, v72, 16, 1
	v_add3_u32 v81, v72, v81, s74
	v_lshl_add_u64 v[84:85], v[136:137], 1, s[40:41]
	global_store_short_d16_hi v[84:85], v81, off
	v_add_u32_e32 v136, v136, v83
	v_bfe_u32 v81, v73, 16, 1
	v_add3_u32 v81, v73, v81, s74
	v_lshl_add_u64 v[84:85], v[136:137], 1, s[40:41]
	global_store_short_d16_hi v[84:85], v81, off
	v_add_u32_e32 v136, v136, v83
	v_bfe_u32 v81, v74, 16, 1
	v_add3_u32 v81, v74, v81, s74
	v_lshl_add_u64 v[84:85], v[136:137], 1, s[40:41]
	global_store_short_d16_hi v[84:85], v81, off
	v_add_u32_e32 v136, v136, v83
	v_bfe_u32 v81, v75, 16, 1
	v_add3_u32 v81, v75, v81, s74
	v_lshl_add_u64 v[84:85], v[136:137], 1, s[40:41]
	global_store_short_d16_hi v[84:85], v81, off
	v_mad_u64_u32 v[80:81], s[28:29], v80, s76, v[82:83]
	s_cbranch_execnz .LBB0_697
.LBB0_769:
	v_cvt_pk_bf16_f32 v76, v76, v77
	v_cvt_pk_bf16_f32 v77, v78, v79
	v_cvt_pk_bf16_f32 v78, v72, v73
	v_mad_u32_u24 v72, v83, s63, v80
	v_lshl_or_b32 v136, v72, 6, v161
	v_lshl_add_u64 v[72:73], v[136:137], 1, s[8:9]
	v_cvt_pk_bf16_f32 v79, v74, v75
	global_store_dwordx4 v[72:73], v[76:79], off
	s_and_b64 vcc, exec, s[38:39]
	s_mov_b64 s[28:29], -1
	s_cbranch_vccnz .LBB0_698
.LBB0_770:
	v_mad_u32_u24 v136, v83, v162, v82
	v_bfe_u32 v72, v68, 16, 1
	v_add3_u32 v74, v68, v72, s74
	v_lshl_add_u64 v[72:73], v[136:137], 1, s[40:41]
	global_store_short_d16_hi v[72:73], v74, off
	v_add_u32_e32 v136, v136, v83
	v_bfe_u32 v72, v69, 16, 1
	v_add3_u32 v74, v69, v72, s74
	v_lshl_add_u64 v[72:73], v[136:137], 1, s[40:41]
	global_store_short_d16_hi v[72:73], v74, off
	v_add_u32_e32 v136, v136, v83
	v_bfe_u32 v72, v70, 16, 1
	v_add3_u32 v74, v70, v72, s74
	v_lshl_add_u64 v[72:73], v[136:137], 1, s[40:41]
	global_store_short_d16_hi v[72:73], v74, off
	v_add_u32_e32 v136, v136, v83
	v_bfe_u32 v72, v71, 16, 1
	v_add3_u32 v74, v71, v72, s74
	v_lshl_add_u64 v[72:73], v[136:137], 1, s[40:41]
	global_store_short_d16_hi v[72:73], v74, off
	v_add_u32_e32 v136, v136, v83
	v_bfe_u32 v72, v64, 16, 1
	v_add3_u32 v74, v64, v72, s74
	v_lshl_add_u64 v[72:73], v[136:137], 1, s[40:41]
	global_store_short_d16_hi v[72:73], v74, off
	v_add_u32_e32 v136, v136, v83
	v_bfe_u32 v72, v65, 16, 1
	v_add3_u32 v74, v65, v72, s74
	v_lshl_add_u64 v[72:73], v[136:137], 1, s[40:41]
	global_store_short_d16_hi v[72:73], v74, off
	v_add_u32_e32 v136, v136, v83
	v_bfe_u32 v72, v66, 16, 1
	v_add3_u32 v74, v66, v72, s74
	v_lshl_add_u64 v[72:73], v[136:137], 1, s[40:41]
	global_store_short_d16_hi v[72:73], v74, off
	v_add_u32_e32 v136, v136, v83
	v_bfe_u32 v72, v67, 16, 1
	v_add3_u32 v74, v67, v72, s74
	v_lshl_add_u64 v[72:73], v[136:137], 1, s[40:41]
	global_store_short_d16_hi v[72:73], v74, off
	s_cbranch_execz .LBB0_699
	s_branch .LBB0_700
.LBB0_771:
	v_mad_u32_u24 v136, v67, v160, v66
	v_bfe_u32 v65, v60, 16, 1
	v_add3_u32 v65, v60, v65, s74
	v_lshl_add_u64 v[68:69], v[136:137], 1, s[40:41]
	global_store_short_d16_hi v[68:69], v65, off
	v_add_u32_e32 v136, v136, v67
	v_bfe_u32 v65, v61, 16, 1
	v_add3_u32 v65, v61, v65, s74
	v_lshl_add_u64 v[68:69], v[136:137], 1, s[40:41]
	global_store_short_d16_hi v[68:69], v65, off
	v_add_u32_e32 v136, v136, v67
	v_bfe_u32 v65, v62, 16, 1
	v_add3_u32 v65, v62, v65, s74
	v_lshl_add_u64 v[68:69], v[136:137], 1, s[40:41]
	global_store_short_d16_hi v[68:69], v65, off
	v_add_u32_e32 v136, v136, v67
	v_bfe_u32 v65, v63, 16, 1
	v_add3_u32 v65, v63, v65, s74
	v_lshl_add_u64 v[68:69], v[136:137], 1, s[40:41]
	global_store_short_d16_hi v[68:69], v65, off
	v_add_u32_e32 v136, v136, v67
	v_bfe_u32 v65, v56, 16, 1
	v_add3_u32 v65, v56, v65, s74
	v_lshl_add_u64 v[68:69], v[136:137], 1, s[40:41]
	global_store_short_d16_hi v[68:69], v65, off
	v_add_u32_e32 v136, v136, v67
	v_bfe_u32 v65, v57, 16, 1
	v_add3_u32 v65, v57, v65, s74
	v_lshl_add_u64 v[68:69], v[136:137], 1, s[40:41]
	global_store_short_d16_hi v[68:69], v65, off
	v_add_u32_e32 v136, v136, v67
	v_bfe_u32 v65, v58, 16, 1
	v_add3_u32 v65, v58, v65, s74
	v_lshl_add_u64 v[68:69], v[136:137], 1, s[40:41]
	global_store_short_d16_hi v[68:69], v65, off
	v_add_u32_e32 v136, v136, v67
	v_bfe_u32 v65, v59, 16, 1
	v_add3_u32 v65, v59, v65, s74
	v_lshl_add_u64 v[68:69], v[136:137], 1, s[40:41]
	global_store_short_d16_hi v[68:69], v65, off
	v_mad_u64_u32 v[64:65], s[28:29], v64, s76, v[66:67]
	s_cbranch_execnz .LBB0_711
.LBB0_772:
	v_cvt_pk_bf16_f32 v60, v60, v61
	v_cvt_pk_bf16_f32 v61, v62, v63
	v_cvt_pk_bf16_f32 v62, v56, v57
	v_mad_u32_u24 v56, v67, s63, v64
	v_lshl_or_b32 v136, v56, 6, v161
	v_lshl_add_u64 v[56:57], v[136:137], 1, s[8:9]
	v_cvt_pk_bf16_f32 v63, v58, v59
	global_store_dwordx4 v[56:57], v[60:63], off
	s_and_b64 vcc, exec, s[38:39]
	s_mov_b64 s[28:29], -1
	s_cbranch_vccnz .LBB0_712
; __device__ __forceinline__ unsigned f2bf(float f) { unsigned u = __builtin_bit_cast(unsigned, f); return (u + 0x7fffu + ((u >> 16) & 1u)) >> 16; }
; __device__ __forceinline__ unsigned cvt_pk_bf16(float lo, float hi) { unsigned r; asm volatile("v_cvt_pk_bf16_f32 %0, %1, %2" : "=v"(r) : "v"(lo), "v"(hi)); return r; }
;     __device__ __forceinline__ void operator()(const f32x4 (&acc)[2][2][4][2], const Unit& u, int wr, int wc, int fr, int fq) const {
;     ...
;                         for (int bj = 0; bj < 2; ++bj) { const f32x4 v0 = acc[ai][bj][m][0], v1 = acc[ai][bj][m][1];
;                             const unsigned c = (unsigned)(bj * HALF + c0), kvh = c >> 6, d = c & 63u;
;                             if (pn == 4) { u32x4 w; w.x = cvt_pk_bf16(v0[0], v0[1]); w.y = cvt_pk_bf16(v0[2], v0[3]); w.z = cvt_pk_bf16(v1[0], v1[1]); w.w = cvt_pk_bf16(v1[2], v1[3]);
;                                 *(u32x4*)(KP + (size_t)((kb + kvh * Lp + (unsigned)pos) * 64u + d)) = w; }
;                             else { unsigned vo = kb * 64u + (kvh * 64u + d) * Lp + (unsigned)pos;
; #pragma unroll
;                                 for (int i = 0; i < 4; ++i) { VT[vo] = (bf16_t)f2bf(v0[i]); vo += Lp; }
; #pragma unroll
;                                 for (int i = 0; i < 4; ++i) { VT[vo] = (bf16_t)f2bf(v1[i]); vo += Lp; } } }
.LBB0_773:
	v_mad_u32_u24 v136, v67, v162, v66
	v_bfe_u32 v56, v52, 16, 1
	v_add3_u32 v58, v52, v56, s74
	v_lshl_add_u64 v[56:57], v[136:137], 1, s[40:41]
	global_store_short_d16_hi v[56:57], v58, off
	v_add_u32_e32 v136, v136, v67
	v_bfe_u32 v56, v53, 16, 1
	v_add3_u32 v58, v53, v56, s74
	v_lshl_add_u64 v[56:57], v[136:137], 1, s[40:41]
	global_store_short_d16_hi v[56:57], v58, off
	v_add_u32_e32 v136, v136, v67
	v_bfe_u32 v56, v54, 16, 1
	v_add3_u32 v58, v54, v56, s74
	v_lshl_add_u64 v[56:57], v[136:137], 1, s[40:41]
	global_store_short_d16_hi v[56:57], v58, off
	v_add_u32_e32 v136, v136, v67
	v_bfe_u32 v56, v55, 16, 1
	v_add3_u32 v58, v55, v56, s74
	v_lshl_add_u64 v[56:57], v[136:137], 1, s[40:41]
	global_store_short_d16_hi v[56:57], v58, off
	v_add_u32_e32 v136, v136, v67
	v_bfe_u32 v56, v48, 16, 1
	v_add3_u32 v58, v48, v56, s74
	v_lshl_add_u64 v[56:57], v[136:137], 1, s[40:41]
	global_store_short_d16_hi v[56:57], v58, off
	v_add_u32_e32 v136, v136, v67
	v_bfe_u32 v56, v49, 16, 1
	v_add3_u32 v58, v49, v56, s74
	v_lshl_add_u64 v[56:57], v[136:137], 1, s[40:41]
	global_store_short_d16_hi v[56:57], v58, off
	v_add_u32_e32 v136, v136, v67
	v_bfe_u32 v56, v50, 16, 1
	v_add3_u32 v58, v50, v56, s74
	v_lshl_add_u64 v[56:57], v[136:137], 1, s[40:41]
	global_store_short_d16_hi v[56:57], v58, off
	v_add_u32_e32 v136, v136, v67
	v_bfe_u32 v56, v51, 16, 1
	v_add3_u32 v58, v51, v56, s74
	v_lshl_add_u64 v[56:57], v[136:137], 1, s[40:41]
	global_store_short_d16_hi v[56:57], v58, off
	s_cbranch_execz .LBB0_713
	s_branch .LBB0_714
.LBB0_774:
	v_mad_u32_u24 v136, v51, v160, v50
	v_bfe_u32 v49, v44, 16, 1
	v_add3_u32 v49, v44, v49, s74
	v_lshl_add_u64 v[52:53], v[136:137], 1, s[40:41]
	global_store_short_d16_hi v[52:53], v49, off
	v_add_u32_e32 v136, v136, v51
	v_bfe_u32 v49, v45, 16, 1
	v_add3_u32 v49, v45, v49, s74
	v_lshl_add_u64 v[52:53], v[136:137], 1, s[40:41]
	global_store_short_d16_hi v[52:53], v49, off
	v_add_u32_e32 v136, v136, v51
	v_bfe_u32 v49, v46, 16, 1
	v_add3_u32 v49, v46, v49, s74
	v_lshl_add_u64 v[52:53], v[136:137], 1, s[40:41]
	global_store_short_d16_hi v[52:53], v49, off
	v_add_u32_e32 v136, v136, v51
	v_bfe_u32 v49, v47, 16, 1
	v_add3_u32 v49, v47, v49, s74
	v_lshl_add_u64 v[52:53], v[136:137], 1, s[40:41]
	global_store_short_d16_hi v[52:53], v49, off
	v_add_u32_e32 v136, v136, v51
	v_bfe_u32 v49, v40, 16, 1
	v_add3_u32 v49, v40, v49, s74
	v_lshl_add_u64 v[52:53], v[136:137], 1, s[40:41]
	global_store_short_d16_hi v[52:53], v49, off
	v_add_u32_e32 v136, v136, v51
	v_bfe_u32 v49, v41, 16, 1
	v_add3_u32 v49, v41, v49, s74
	v_lshl_add_u64 v[52:53], v[136:137], 1, s[40:41]
	global_store_short_d16_hi v[52:53], v49, off
	v_add_u32_e32 v136, v136, v51
	v_bfe_u32 v49, v42, 16, 1
	v_add3_u32 v49, v42, v49, s74
	v_lshl_add_u64 v[52:53], v[136:137], 1, s[40:41]
	global_store_short_d16_hi v[52:53], v49, off
	v_add_u32_e32 v136, v136, v51
	v_bfe_u32 v49, v43, 16, 1
	v_add3_u32 v49, v43, v49, s74
	v_lshl_add_u64 v[52:53], v[136:137], 1, s[40:41]
	global_store_short_d16_hi v[52:53], v49, off
	v_mad_u64_u32 v[48:49], s[28:29], v48, s76, v[50:51]
	s_cbranch_execnz .LBB0_725
.LBB0_775:
	v_cvt_pk_bf16_f32 v44, v44, v45
	v_cvt_pk_bf16_f32 v45, v46, v47
	v_cvt_pk_bf16_f32 v46, v40, v41
	v_mad_u32_u24 v40, v51, s63, v48
	v_lshl_or_b32 v136, v40, 6, v161
	v_lshl_add_u64 v[40:41], v[136:137], 1, s[8:9]
	v_cvt_pk_bf16_f32 v47, v42, v43
	global_store_dwordx4 v[40:41], v[44:47], off
	s_and_b64 vcc, exec, s[38:39]
	s_mov_b64 s[28:29], -1
	s_cbranch_vccnz .LBB0_726
.LBB0_776:
	v_mad_u32_u24 v136, v51, v162, v50
	v_bfe_u32 v40, v36, 16, 1
	v_add3_u32 v42, v36, v40, s74
	v_lshl_add_u64 v[40:41], v[136:137], 1, s[40:41]
	global_store_short_d16_hi v[40:41], v42, off
	v_add_u32_e32 v136, v136, v51
	v_bfe_u32 v40, v37, 16, 1
	v_add3_u32 v42, v37, v40, s74
	v_lshl_add_u64 v[40:41], v[136:137], 1, s[40:41]
	global_store_short_d16_hi v[40:41], v42, off
	v_add_u32_e32 v136, v136, v51
	v_bfe_u32 v40, v38, 16, 1
	v_add3_u32 v42, v38, v40, s74
	v_lshl_add_u64 v[40:41], v[136:137], 1, s[40:41]
	global_store_short_d16_hi v[40:41], v42, off
	v_add_u32_e32 v136, v136, v51
	v_bfe_u32 v40, v39, 16, 1
	v_add3_u32 v42, v39, v40, s74
	v_lshl_add_u64 v[40:41], v[136:137], 1, s[40:41]
	global_store_short_d16_hi v[40:41], v42, off
	v_add_u32_e32 v136, v136, v51
	v_bfe_u32 v40, v32, 16, 1
	v_add3_u32 v42, v32, v40, s74
	v_lshl_add_u64 v[40:41], v[136:137], 1, s[40:41]
	global_store_short_d16_hi v[40:41], v42, off
	v_add_u32_e32 v136, v136, v51
	v_bfe_u32 v40, v33, 16, 1
	v_add3_u32 v42, v33, v40, s74
	v_lshl_add_u64 v[40:41], v[136:137], 1, s[40:41]
	global_store_short_d16_hi v[40:41], v42, off
	v_add_u32_e32 v136, v136, v51
	v_bfe_u32 v40, v34, 16, 1
	v_add3_u32 v42, v34, v40, s74
	v_lshl_add_u64 v[40:41], v[136:137], 1, s[40:41]
	global_store_short_d16_hi v[40:41], v42, off
	v_add_u32_e32 v136, v136, v51
	v_bfe_u32 v40, v35, 16, 1
	v_add3_u32 v42, v35, v40, s74
	v_lshl_add_u64 v[40:41], v[136:137], 1, s[40:41]
	global_store_short_d16_hi v[40:41], v42, off
	s_cbranch_execz .LBB0_727
	s_branch .LBB0_728
; __device__ __forceinline__ unsigned f2bf(float f) { unsigned u = __builtin_bit_cast(unsigned, f); return (u + 0x7fffu + ((u >> 16) & 1u)) >> 16; }
; __device__ __forceinline__ unsigned cvt_pk_bf16(float lo, float hi) { unsigned r; asm volatile("v_cvt_pk_bf16_f32 %0, %1, %2" : "=v"(r) : "v"(lo), "v"(hi)); return r; }
;     __device__ __forceinline__ void operator()(const f32x4 (&acc)[2][2][4][2], const Unit& u, int wr, int wc, int fr, int fq) const {
;     ...
;                         for (int bj = 0; bj < 2; ++bj) { const f32x4 v0 = acc[ai][bj][m][0], v1 = acc[ai][bj][m][1];
;                             const unsigned c = (unsigned)(bj * HALF + c0), kvh = c >> 6, d = c & 63u;
;                             if (pn == 4) { u32x4 w; w.x = cvt_pk_bf16(v0[0], v0[1]); w.y = cvt_pk_bf16(v0[2], v0[3]); w.z = cvt_pk_bf16(v1[0], v1[1]); w.w = cvt_pk_bf16(v1[2], v1[3]);
;                                 *(u32x4*)(KP + (size_t)((kb + kvh * Lp + (unsigned)pos) * 64u + d)) = w; }
;                             else { unsigned vo = kb * 64u + (kvh * 64u + d) * Lp + (unsigned)pos;
; #pragma unroll
;                                 for (int i = 0; i < 4; ++i) { VT[vo] = (bf16_t)f2bf(v0[i]); vo += Lp; }
; #pragma unroll
;                                 for (int i = 0; i < 4; ++i) { VT[vo] = (bf16_t)f2bf(v1[i]); vo += Lp; } } }
.LBB0_777:
	v_mad_u32_u24 v136, v35, v160, v34
	v_bfe_u32 v33, v28, 16, 1
	v_add3_u32 v33, v28, v33, s74
	v_lshl_add_u64 v[36:37], v[136:137], 1, s[40:41]
	global_store_short_d16_hi v[36:37], v33, off
	v_add_u32_e32 v136, v136, v35
	v_bfe_u32 v33, v29, 16, 1
	v_add3_u32 v33, v29, v33, s74
	v_lshl_add_u64 v[36:37], v[136:137], 1, s[40:41]
	global_store_short_d16_hi v[36:37], v33, off
	v_add_u32_e32 v136, v136, v35
	v_bfe_u32 v33, v30, 16, 1
	v_add3_u32 v33, v30, v33, s74
	v_lshl_add_u64 v[36:37], v[136:137], 1, s[40:41]
	global_store_short_d16_hi v[36:37], v33, off
	v_add_u32_e32 v136, v136, v35
	v_bfe_u32 v33, v31, 16, 1
	v_add3_u32 v33, v31, v33, s74
	v_lshl_add_u64 v[36:37], v[136:137], 1, s[40:41]
	global_store_short_d16_hi v[36:37], v33, off
	v_add_u32_e32 v136, v136, v35
	v_bfe_u32 v33, v24, 16, 1
	v_add3_u32 v33, v24, v33, s74
	v_lshl_add_u64 v[36:37], v[136:137], 1, s[40:41]
	global_store_short_d16_hi v[36:37], v33, off
	v_add_u32_e32 v136, v136, v35
	v_bfe_u32 v33, v25, 16, 1
	v_add3_u32 v33, v25, v33, s74
	v_lshl_add_u64 v[36:37], v[136:137], 1, s[40:41]
	global_store_short_d16_hi v[36:37], v33, off
	v_add_u32_e32 v136, v136, v35
	v_bfe_u32 v33, v26, 16, 1
	v_add3_u32 v33, v26, v33, s74
	v_lshl_add_u64 v[36:37], v[136:137], 1, s[40:41]
	global_store_short_d16_hi v[36:37], v33, off
	v_add_u32_e32 v136, v136, v35
	v_bfe_u32 v33, v27, 16, 1
	v_add3_u32 v33, v27, v33, s74
	v_lshl_add_u64 v[36:37], v[136:137], 1, s[40:41]
	global_store_short_d16_hi v[36:37], v33, off
	v_mad_u64_u32 v[32:33], s[28:29], v32, s76, v[34:35]
	s_cbranch_execnz .LBB0_739
.LBB0_778:
	v_cvt_pk_bf16_f32 v28, v28, v29
	v_cvt_pk_bf16_f32 v29, v30, v31
	v_cvt_pk_bf16_f32 v30, v24, v25
	v_mad_u32_u24 v24, v35, s63, v32
	v_lshl_or_b32 v136, v24, 6, v161
	v_lshl_add_u64 v[24:25], v[136:137], 1, s[8:9]
	v_cvt_pk_bf16_f32 v31, v26, v27
	global_store_dwordx4 v[24:25], v[28:31], off
	s_and_b64 vcc, exec, s[38:39]
	s_mov_b64 s[28:29], -1
	s_cbranch_vccnz .LBB0_740
.LBB0_779:
	v_mad_u32_u24 v136, v35, v162, v34
	v_bfe_u32 v24, v20, 16, 1
	v_add3_u32 v26, v20, v24, s74
	v_lshl_add_u64 v[24:25], v[136:137], 1, s[40:41]
	global_store_short_d16_hi v[24:25], v26, off
	v_add_u32_e32 v136, v136, v35
	v_bfe_u32 v24, v21, 16, 1
	v_add3_u32 v26, v21, v24, s74
	v_lshl_add_u64 v[24:25], v[136:137], 1, s[40:41]
	global_store_short_d16_hi v[24:25], v26, off
	v_add_u32_e32 v136, v136, v35
	v_bfe_u32 v24, v22, 16, 1
	v_add3_u32 v26, v22, v24, s74
	v_lshl_add_u64 v[24:25], v[136:137], 1, s[40:41]
	global_store_short_d16_hi v[24:25], v26, off
	v_add_u32_e32 v136, v136, v35
	v_bfe_u32 v24, v23, 16, 1
	v_add3_u32 v26, v23, v24, s74
	v_lshl_add_u64 v[24:25], v[136:137], 1, s[40:41]
	global_store_short_d16_hi v[24:25], v26, off
	v_add_u32_e32 v136, v136, v35
	v_bfe_u32 v24, v16, 16, 1
	v_add3_u32 v26, v16, v24, s74
	v_lshl_add_u64 v[24:25], v[136:137], 1, s[40:41]
	global_store_short_d16_hi v[24:25], v26, off
	v_add_u32_e32 v136, v136, v35
	v_bfe_u32 v24, v17, 16, 1
	v_add3_u32 v26, v17, v24, s74
	v_lshl_add_u64 v[24:25], v[136:137], 1, s[40:41]
	global_store_short_d16_hi v[24:25], v26, off
	v_add_u32_e32 v136, v136, v35
	v_bfe_u32 v24, v18, 16, 1
	v_add3_u32 v26, v18, v24, s74
	v_lshl_add_u64 v[24:25], v[136:137], 1, s[40:41]
	global_store_short_d16_hi v[24:25], v26, off
	v_add_u32_e32 v136, v136, v35
	v_bfe_u32 v24, v19, 16, 1
	v_add3_u32 v26, v19, v24, s74
	v_lshl_add_u64 v[24:25], v[136:137], 1, s[40:41]
	global_store_short_d16_hi v[24:25], v26, off
	s_cbranch_execz .LBB0_741
	s_branch .LBB0_742
.LBB0_780:
	v_mad_u32_u24 v136, v19, v160, v18
	v_bfe_u32 v17, v12, 16, 1
	v_add3_u32 v17, v12, v17, s74
	v_lshl_add_u64 v[20:21], v[136:137], 1, s[40:41]
	global_store_short_d16_hi v[20:21], v17, off
	v_add_u32_e32 v136, v136, v19
	v_bfe_u32 v17, v13, 16, 1
	v_add3_u32 v17, v13, v17, s74
	v_lshl_add_u64 v[20:21], v[136:137], 1, s[40:41]
	global_store_short_d16_hi v[20:21], v17, off
	v_add_u32_e32 v136, v136, v19
	v_bfe_u32 v17, v14, 16, 1
	v_add3_u32 v17, v14, v17, s74
	v_lshl_add_u64 v[20:21], v[136:137], 1, s[40:41]
	global_store_short_d16_hi v[20:21], v17, off
	v_add_u32_e32 v136, v136, v19
	v_bfe_u32 v17, v15, 16, 1
	v_add3_u32 v17, v15, v17, s74
	v_lshl_add_u64 v[20:21], v[136:137], 1, s[40:41]
	global_store_short_d16_hi v[20:21], v17, off
	v_add_u32_e32 v136, v136, v19
	v_bfe_u32 v17, v8, 16, 1
	v_add3_u32 v17, v8, v17, s74
	v_lshl_add_u64 v[20:21], v[136:137], 1, s[40:41]
	global_store_short_d16_hi v[20:21], v17, off
	v_add_u32_e32 v136, v136, v19
	v_bfe_u32 v17, v9, 16, 1
	v_add3_u32 v17, v9, v17, s74
	v_lshl_add_u64 v[20:21], v[136:137], 1, s[40:41]
	global_store_short_d16_hi v[20:21], v17, off
	v_add_u32_e32 v136, v136, v19
	v_bfe_u32 v17, v10, 16, 1
	v_add3_u32 v17, v10, v17, s74
	v_lshl_add_u64 v[20:21], v[136:137], 1, s[40:41]
	global_store_short_d16_hi v[20:21], v17, off
	v_add_u32_e32 v136, v136, v19
	v_bfe_u32 v17, v11, 16, 1
	v_add3_u32 v17, v11, v17, s74
	v_lshl_add_u64 v[20:21], v[136:137], 1, s[40:41]
	global_store_short_d16_hi v[20:21], v17, off
	v_mad_u64_u32 v[16:17], s[24:25], v16, s76, v[18:19]
	s_cbranch_execnz .LBB0_753
.LBB0_781:
	v_cvt_pk_bf16_f32 v12, v12, v13
	v_cvt_pk_bf16_f32 v13, v14, v15
	v_cvt_pk_bf16_f32 v14, v8, v9
	v_mad_u32_u24 v8, v19, s63, v16
	v_lshl_or_b32 v136, v8, 6, v161
	v_lshl_add_u64 v[8:9], v[136:137], 1, s[8:9]
	v_cvt_pk_bf16_f32 v15, v10, v11
	global_store_dwordx4 v[8:9], v[12:15], off
	s_and_b64 vcc, exec, s[38:39]
	s_mov_b64 s[24:25], -1
	s_cbranch_vccnz .LBB0_754
.LBB0_782:
	v_mad_u32_u24 v136, v19, v162, v18
	v_bfe_u32 v8, v4, 16, 1
	v_add3_u32 v10, v4, v8, s74
	v_lshl_add_u64 v[8:9], v[136:137], 1, s[40:41]
	global_store_short_d16_hi v[8:9], v10, off
	v_add_u32_e32 v136, v136, v19
	v_bfe_u32 v8, v5, 16, 1
	v_add3_u32 v10, v5, v8, s74
	v_lshl_add_u64 v[8:9], v[136:137], 1, s[40:41]
	global_store_short_d16_hi v[8:9], v10, off
	v_add_u32_e32 v136, v136, v19
	v_bfe_u32 v8, v6, 16, 1
	v_add3_u32 v10, v6, v8, s74
	v_lshl_add_u64 v[8:9], v[136:137], 1, s[40:41]
	global_store_short_d16_hi v[8:9], v10, off
	v_add_u32_e32 v136, v136, v19
	v_bfe_u32 v8, v7, 16, 1
	v_add3_u32 v10, v7, v8, s74
	v_lshl_add_u64 v[8:9], v[136:137], 1, s[40:41]
	global_store_short_d16_hi v[8:9], v10, off
	v_add_u32_e32 v136, v136, v19
	v_bfe_u32 v8, v0, 16, 1
	v_add3_u32 v10, v0, v8, s74
	v_lshl_add_u64 v[8:9], v[136:137], 1, s[40:41]
	global_store_short_d16_hi v[8:9], v10, off
	v_add_u32_e32 v136, v136, v19
	v_bfe_u32 v8, v1, 16, 1
	v_add3_u32 v10, v1, v8, s74
	v_lshl_add_u64 v[8:9], v[136:137], 1, s[40:41]
	global_store_short_d16_hi v[8:9], v10, off
	v_add_u32_e32 v136, v136, v19
	v_bfe_u32 v8, v2, 16, 1
	v_add3_u32 v10, v2, v8, s74
	v_lshl_add_u64 v[8:9], v[136:137], 1, s[40:41]
	global_store_short_d16_hi v[8:9], v10, off
	v_add_u32_e32 v136, v136, v19
	v_bfe_u32 v8, v3, 16, 1
	v_add3_u32 v10, v3, v8, s74
	v_lshl_add_u64 v[8:9], v[136:137], 1, s[40:41]
	global_store_short_d16_hi v[8:9], v10, off
	s_cbranch_execz .LBB0_755
	s_branch .LBB0_756

;     __device__ __forceinline__ void operator()(const f32x4 (&acc)[2][2][4][2], const Unit& u, int wr, int wc, int fr, int fq) const {
;     ...
;                     for (int m = 0; m < 4; ++m) { const int r = row0 + ai * HALF + m * 16;
;                         const f32x4 v0 = acc[ai][0][m][0], v1 = acc[ai][0][m][1]; float* dp = DT + (size_t)r * 32 + c0;
; #pragma unroll
;                         for (int i = 0; i < 4; ++i) { float x0 = v0[i] + dt_bias[c0 + i], x1 = v1[i] + dt_bias[c0 + 4 + i];
;                             dp[i] = x0 > 20.f ? x0 : log1pf(__expf(x0)); dp[4 + i] = x1 > 20.f ? x1 : log1pf(__expf(x1)); }
.LBB0_785:
	s_or_b64 exec, exec, s[24:25]
	v_ashrrev_i32_e32 v153, 31, v152
	v_lshlrev_b64 v[154:155], 7, v[152:153]
	s_waitcnt vmcnt(0)
	v_add_f32_e32 v136, v120, v136
	v_lshl_add_u64 v[154:155], v[138:139], 0, v[154:155]
	v_cmp_nlt_f32_e32 vcc, s67, v136
	global_store_dword v[154:155], v151, off
	s_and_saveexec_b64 s[24:25], vcc
	s_cbranch_execz .LBB0_787
	v_mul_f32_e32 v136, 0x3fb8aa3b, v136
	v_exp_f32_e32 v136, v136
	s_nop 0
	v_add_f32_e32 v151, 1.0, v136
	v_frexp_mant_f32_e32 v174, v151
	v_cvt_f64_f32_e32 v[172:173], v151
	v_add_f32_e32 v156, -1.0, v151
	v_frexp_exp_i32_f64_e32 v172, v[172:173]
	v_cmp_gt_f32_e32 vcc, s68, v174
	v_sub_f32_e32 v175, v156, v151
	v_sub_f32_e32 v156, v136, v156
	v_subbrev_co_u32_e32 v180, vcc, 0, v172, vcc
	v_add_f32_e32 v175, 1.0, v175
	v_sub_u32_e32 v172, 0, v180
	v_add_f32_e32 v156, v156, v175
	v_ldexp_f32 v151, v151, v172
	v_ldexp_f32 v156, v156, v172
	v_add_f32_e32 v172, -1.0, v151
	v_add_f32_e32 v173, 1.0, v172
	v_sub_f32_e32 v173, v151, v173
	v_add_f32_e32 v174, v156, v173
	v_add_f32_e32 v173, 1.0, v151
	v_add_f32_e32 v175, -1.0, v173
	v_sub_f32_e32 v151, v151, v175
	v_add_f32_e32 v151, v156, v151
	v_add_f32_e32 v156, v173, v151
	v_rcp_f32_e32 v181, v156
	v_sub_f32_e32 v173, v156, v173
	v_sub_f32_e32 v151, v151, v173
	v_add_f32_e32 v173, v172, v174
	v_sub_f32_e32 v172, v173, v172
	v_mul_f32_e32 v183, v173, v181
	v_sub_f32_e32 v182, v174, v172
	v_mul_f32_e32 v174, v156, v183
	v_fma_f32 v176, v183, v156, -v174
	v_fmac_f32_e32 v176, v183, v151
	v_add_f32_e32 v172, v174, v176
	v_sub_f32_e32 v175, v173, v172
	v_pk_add_f32 v[178:179], v[172:173], v[174:175] neg_lo:[0,1] neg_hi:[0,1]
	v_mov_b32_e32 v177, v172
	v_pk_add_f32 v[172:173], v[178:179], v[176:177] neg_lo:[0,1] neg_hi:[0,1]
	v_cmp_neq_f32_e32 vcc, s70, v136
	v_add_f32_e32 v173, v182, v173
	v_add_f32_e32 v172, v172, v173
	v_add_f32_e32 v173, v175, v172
	v_mul_f32_e32 v182, v181, v173
	v_mul_f32_e32 v174, v156, v182
	v_fma_f32 v176, v182, v156, -v174
	v_fmac_f32_e32 v176, v182, v151
	v_sub_f32_e32 v151, v175, v173
	v_add_f32_e32 v151, v172, v151
	v_add_f32_e32 v172, v174, v176
	v_sub_f32_e32 v175, v173, v172
	v_pk_add_f32 v[178:179], v[172:173], v[174:175] neg_lo:[0,1] neg_hi:[0,1]
	v_mov_b32_e32 v177, v172
	v_pk_add_f32 v[172:173], v[178:179], v[176:177] neg_lo:[0,1] neg_hi:[0,1]
	v_add_f32_e32 v156, v183, v182
	v_add_f32_e32 v151, v151, v173
	v_add_f32_e32 v151, v172, v151
	v_add_f32_e32 v151, v175, v151
	v_sub_f32_e32 v172, v156, v183
	v_mul_f32_e32 v151, v181, v151
	v_sub_f32_e32 v172, v182, v172
	v_add_f32_e32 v173, v172, v151
	v_add_f32_e32 v174, v156, v173
	v_cvt_f32_i32_e32 v172, v180
	v_mul_f32_e32 v176, v174, v174
	v_fmamk_f32 v151, v176, 0x3e9b6dac, v166
	v_sub_f32_e32 v156, v174, v156
	v_fmaak_f32 v151, v176, v151, 0x3f2aaada
	v_sub_f32_e32 v156, v173, v156
	v_mul_f32_e32 v173, v174, v176
	v_pk_mul_f32 v[176:177], v[172:173], v[150:151]
	v_ldexp_f32 v175, v174, 1
	v_fma_f32 v174, v172, s69, -v176
	v_fmac_f32_e32 v174, 0xb102e308, v172
	v_pk_add_f32 v[172:173], v[176:177], v[174:175]
	v_ldexp_f32 v156, v156, 1
	v_sub_f32_e32 v151, v173, v175
	v_sub_f32_e32 v151, v177, v151
	v_add_f32_e32 v179, v156, v151
	v_mov_b32_e32 v178, v176
	v_pk_add_f32 v[176:177], v[172:173], v[176:177] neg_lo:[0,1] neg_hi:[0,1]
	v_pk_add_f32 v[180:181], v[172:173], v[178:179]
	v_mov_b32_e32 v175, v172
	v_mov_b32_e32 v177, v181
	v_pk_add_f32 v[182:183], v[174:175], v[176:177] neg_lo:[0,1] neg_hi:[0,1]
	v_pk_add_f32 v[174:175], v[174:175], v[176:177]
	v_mov_b32_e32 v178, v179
	v_pk_add_f32 v[176:177], v[174:175], v[172:173] op_sel:[1,0] op_sel_hi:[0,1] neg_lo:[0,1] neg_hi:[0,1]
	v_pk_add_f32 v[184:185], v[180:181], v[176:177] op_sel_hi:[1,0] neg_lo:[0,1] neg_hi:[0,1]
	v_mov_b32_e32 v180, v181
	v_mov_b32_e32 v181, v175
	v_pk_mov_b32 v[176:177], v[172:173], v[176:177] op_sel:[1,0]
	v_mov_b32_e32 v179, v172
	v_pk_add_f32 v[176:177], v[180:181], v[176:177] neg_lo:[0,1] neg_hi:[0,1]
	v_mov_b32_e32 v184, v182
	v_pk_add_f32 v[172:173], v[178:179], v[176:177] neg_lo:[0,1] neg_hi:[0,1]
	v_mov_b32_e32 v183, v175
	v_pk_add_f32 v[176:177], v[184:185], v[172:173]
	s_nop 0
	v_pk_add_f32 v[178:179], v[176:177], v[176:177] op_sel:[0,1] op_sel_hi:[1,0]
	s_nop 0
	v_pk_add_f32 v[174:175], v[174:175], v[178:179] op_sel:[1,0] op_sel_hi:[0,1]
	v_mov_b32_e32 v177, v174
	v_pk_add_f32 v[180:181], v[176:177], v[182:183] neg_lo:[0,1] neg_hi:[0,1]
	v_mov_b32_e32 v173, v178
	v_sub_f32_e32 v151, v176, v180
	v_pk_add_f32 v[172:173], v[172:173], v[180:181] neg_lo:[0,1] neg_hi:[0,1]
	v_sub_f32_e32 v151, v182, v151
	v_add_f32_e32 v151, v172, v151
	v_add_f32_e32 v151, v151, v173
	v_add_f32_e32 v151, v174, v151
	v_cndmask_b32_e32 v151, v167, v151, vcc
	v_cmp_ngt_f32_e32 vcc, -1.0, v136
	s_nop 1
	v_cndmask_b32_e32 v151, v168, v151, vcc
	v_cmp_neq_f32_e32 vcc, -1.0, v136
	s_nop 1
	v_cndmask_b32_e32 v151, v169, v151, vcc
	v_cmp_lt_f32_e64 vcc, |v136|, s71
	s_nop 1
	v_cndmask_b32_e32 v136, v151, v136, vcc
;     __device__ __forceinline__ void operator()(const f32x4 (&acc)[2][2][4][2], const Unit& u, int wr, int wc, int fr, int fq) const {
;     ...
;                     for (int m = 0; m < 4; ++m) { const int r = row0 + ai * HALF + m * 16;
;                         const f32x4 v0 = acc[ai][0][m][0], v1 = acc[ai][0][m][1]; float* dp = DT + (size_t)r * 32 + c0;
; #pragma unroll
;                         for (int i = 0; i < 4; ++i) { float x0 = v0[i] + dt_bias[c0 + i], x1 = v1[i] + dt_bias[c0 + 4 + i];
;                             dp[i] = x0 > 20.f ? x0 : log1pf(__expf(x0)); dp[4 + i] = x1 > 20.f ? x1 : log1pf(__expf(x1)); }
.LBB0_787:
	s_or_b64 exec, exec, s[24:25]
	global_store_dword v[154:155], v136, off offset:16
	global_load_dword v136, v[140:141], off offset:4
	s_waitcnt vmcnt(0)
	v_add_f32_e32 v151, v125, v136
	global_load_dword v136, v[140:141], off offset:20
	v_cmp_nlt_f32_e32 vcc, s67, v151
	s_and_saveexec_b64 s[24:25], vcc
	s_cbranch_execz .LBB0_789
	v_mul_f32_e32 v151, 0x3fb8aa3b, v151
	v_exp_f32_e32 v156, v151
	s_nop 0
	v_add_f32_e32 v151, 1.0, v156
	v_frexp_mant_f32_e32 v175, v151
	v_cvt_f64_f32_e32 v[172:173], v151
	v_add_f32_e32 v174, -1.0, v151
	v_frexp_exp_i32_f64_e32 v172, v[172:173]
	v_cmp_gt_f32_e32 vcc, s68, v175
	v_sub_f32_e32 v176, v174, v151
	v_sub_f32_e32 v174, v156, v174
	v_subbrev_co_u32_e32 v180, vcc, 0, v172, vcc
	v_add_f32_e32 v176, 1.0, v176
	v_sub_u32_e32 v172, 0, v180
	v_add_f32_e32 v174, v174, v176
	v_ldexp_f32 v151, v151, v172
	v_ldexp_f32 v172, v174, v172
	v_add_f32_e32 v174, -1.0, v151
	v_add_f32_e32 v173, 1.0, v174
	v_sub_f32_e32 v173, v151, v173
	v_add_f32_e32 v175, v172, v173
	v_add_f32_e32 v173, 1.0, v151
	v_add_f32_e32 v176, -1.0, v173
	v_sub_f32_e32 v151, v151, v176
	v_add_f32_e32 v151, v172, v151
	v_add_f32_e32 v181, v173, v151
	v_rcp_f32_e32 v182, v181
	v_sub_f32_e32 v172, v181, v173
	v_add_f32_e32 v173, v174, v175
	v_sub_f32_e32 v151, v151, v172
	v_mul_f32_e32 v184, v173, v182
	v_sub_f32_e32 v172, v173, v174
	v_mul_f32_e32 v174, v181, v184
	v_fma_f32 v176, v184, v181, -v174
	v_fmac_f32_e32 v176, v184, v151
	v_sub_f32_e32 v183, v175, v172
	v_add_f32_e32 v172, v174, v176
	v_sub_f32_e32 v175, v173, v172
	v_pk_add_f32 v[178:179], v[172:173], v[174:175] neg_lo:[0,1] neg_hi:[0,1]
	v_mov_b32_e32 v177, v172
	v_pk_add_f32 v[172:173], v[178:179], v[176:177] neg_lo:[0,1] neg_hi:[0,1]
	v_cmp_neq_f32_e32 vcc, s70, v156
	v_add_f32_e32 v173, v183, v173
	v_add_f32_e32 v172, v172, v173
	v_add_f32_e32 v173, v175, v172
	v_mul_f32_e32 v183, v182, v173
	v_mul_f32_e32 v174, v181, v183
	v_fma_f32 v176, v183, v181, -v174
	v_fmac_f32_e32 v176, v183, v151
	v_sub_f32_e32 v151, v175, v173
	v_add_f32_e32 v151, v172, v151
	v_add_f32_e32 v172, v174, v176
	v_sub_f32_e32 v175, v173, v172
	v_pk_add_f32 v[178:179], v[172:173], v[174:175] neg_lo:[0,1] neg_hi:[0,1]
	v_mov_b32_e32 v177, v172
	v_pk_add_f32 v[172:173], v[178:179], v[176:177] neg_lo:[0,1] neg_hi:[0,1]
	s_nop 0
	v_add_f32_e32 v151, v151, v173
	v_add_f32_e32 v151, v172, v151
	v_add_f32_e32 v173, v184, v183
	v_add_f32_e32 v151, v175, v151
	v_sub_f32_e32 v172, v173, v184
	v_mul_f32_e32 v151, v182, v151
	v_sub_f32_e32 v172, v183, v172
	v_add_f32_e32 v174, v172, v151
	v_add_f32_e32 v176, v173, v174
	v_cvt_f32_i32_e32 v172, v180
	v_mul_f32_e32 v177, v176, v176
	v_sub_f32_e32 v173, v176, v173
	v_fmamk_f32 v151, v177, 0x3e9b6dac, v166
	v_sub_f32_e32 v173, v174, v173
	v_fmaak_f32 v151, v177, v151, 0x3f2aaada
	v_ldexp_f32 v178, v173, 1
	v_mul_f32_e32 v173, v176, v177
	v_ldexp_f32 v175, v176, 1
	v_pk_mul_f32 v[176:177], v[172:173], v[150:151]
	s_nop 0
	v_fma_f32 v174, v172, s69, -v176
	v_fmac_f32_e32 v174, 0xb102e308, v172
	v_pk_add_f32 v[172:173], v[176:177], v[174:175]
	s_nop 0
	v_sub_f32_e32 v151, v173, v175
	v_sub_f32_e32 v151, v177, v151
	v_add_f32_e32 v179, v178, v151
	v_mov_b32_e32 v178, v176
	v_pk_add_f32 v[176:177], v[172:173], v[176:177] neg_lo:[0,1] neg_hi:[0,1]
	v_pk_add_f32 v[180:181], v[172:173], v[178:179]
	v_mov_b32_e32 v175, v172
	v_mov_b32_e32 v177, v181
	v_pk_add_f32 v[182:183], v[174:175], v[176:177] neg_lo:[0,1] neg_hi:[0,1]
	v_pk_add_f32 v[174:175], v[174:175], v[176:177]
	v_mov_b32_e32 v178, v179
	v_pk_add_f32 v[176:177], v[174:175], v[172:173] op_sel:[1,0] op_sel_hi:[0,1] neg_lo:[0,1] neg_hi:[0,1]
	v_pk_add_f32 v[184:185], v[180:181], v[176:177] op_sel_hi:[1,0] neg_lo:[0,1] neg_hi:[0,1]
	v_mov_b32_e32 v180, v181
	v_mov_b32_e32 v181, v175
	v_pk_mov_b32 v[176:177], v[172:173], v[176:177] op_sel:[1,0]
	v_mov_b32_e32 v179, v172
	v_pk_add_f32 v[176:177], v[180:181], v[176:177] neg_lo:[0,1] neg_hi:[0,1]
	v_mov_b32_e32 v184, v182
	v_pk_add_f32 v[172:173], v[178:179], v[176:177] neg_lo:[0,1] neg_hi:[0,1]
	v_mov_b32_e32 v183, v175
	v_pk_add_f32 v[176:177], v[184:185], v[172:173]
	s_nop 0
	v_pk_add_f32 v[178:179], v[176:177], v[176:177] op_sel:[0,1] op_sel_hi:[1,0]
	s_nop 0
	v_pk_add_f32 v[174:175], v[174:175], v[178:179] op_sel:[1,0] op_sel_hi:[0,1]
	v_mov_b32_e32 v177, v174
	v_pk_add_f32 v[180:181], v[176:177], v[182:183] neg_lo:[0,1] neg_hi:[0,1]
	v_mov_b32_e32 v173, v178
	v_sub_f32_e32 v151, v176, v180
	v_pk_add_f32 v[172:173], v[172:173], v[180:181] neg_lo:[0,1] neg_hi:[0,1]
	v_sub_f32_e32 v151, v182, v151
	v_add_f32_e32 v151, v172, v151
	v_add_f32_e32 v151, v151, v173
	v_add_f32_e32 v151, v174, v151
	v_cndmask_b32_e32 v151, v167, v151, vcc
	v_cmp_ngt_f32_e32 vcc, -1.0, v156
	s_nop 1
	v_cndmask_b32_e32 v151, v168, v151, vcc
	v_cmp_neq_f32_e32 vcc, -1.0, v156
	s_nop 1
	v_cndmask_b32_e32 v151, v169, v151, vcc
	v_cmp_lt_f32_e64 vcc, |v156|, s71
	s_nop 1
	v_cndmask_b32_e32 v151, v151, v156, vcc
;     __device__ __forceinline__ void operator()(const f32x4 (&acc)[2][2][4][2], const Unit& u, int wr, int wc, int fr, int fq) const {
;     ...
;                     for (int m = 0; m < 4; ++m) { const int r = row0 + ai * HALF + m * 16;
;                         const f32x4 v0 = acc[ai][0][m][0], v1 = acc[ai][0][m][1]; float* dp = DT + (size_t)r * 32 + c0;
; #pragma unroll
;                         for (int i = 0; i < 4; ++i) { float x0 = v0[i] + dt_bias[c0 + i], x1 = v1[i] + dt_bias[c0 + 4 + i];
;                             dp[i] = x0 > 20.f ? x0 : log1pf(__expf(x0)); dp[4 + i] = x1 > 20.f ? x1 : log1pf(__expf(x1)); }
.LBB0_789:
	s_or_b64 exec, exec, s[24:25]
	s_waitcnt vmcnt(0)
	v_add_f32_e32 v136, v121, v136
	v_cmp_nlt_f32_e32 vcc, s67, v136
	global_store_dword v[154:155], v151, off offset:4
	s_and_saveexec_b64 s[24:25], vcc
	s_cbranch_execz .LBB0_791
	v_mul_f32_e32 v136, 0x3fb8aa3b, v136
	v_exp_f32_e32 v136, v136
	s_nop 0
	v_add_f32_e32 v151, 1.0, v136
	v_frexp_mant_f32_e32 v174, v151
	v_cvt_f64_f32_e32 v[172:173], v151
	v_add_f32_e32 v156, -1.0, v151
	v_frexp_exp_i32_f64_e32 v172, v[172:173]
	v_cmp_gt_f32_e32 vcc, s68, v174
	v_sub_f32_e32 v175, v156, v151
	v_sub_f32_e32 v156, v136, v156
	v_subbrev_co_u32_e32 v180, vcc, 0, v172, vcc
	v_add_f32_e32 v175, 1.0, v175
	v_sub_u32_e32 v172, 0, v180
	v_add_f32_e32 v156, v156, v175
	v_ldexp_f32 v151, v151, v172
	v_ldexp_f32 v156, v156, v172
	v_add_f32_e32 v172, -1.0, v151
	v_add_f32_e32 v173, 1.0, v172
	v_sub_f32_e32 v173, v151, v173
	v_add_f32_e32 v174, v156, v173
	v_add_f32_e32 v173, 1.0, v151
	v_add_f32_e32 v175, -1.0, v173
	v_sub_f32_e32 v151, v151, v175
	v_add_f32_e32 v151, v156, v151
	v_add_f32_e32 v156, v173, v151
	v_rcp_f32_e32 v181, v156
	v_sub_f32_e32 v173, v156, v173
	v_sub_f32_e32 v151, v151, v173
	v_add_f32_e32 v173, v172, v174
	v_sub_f32_e32 v172, v173, v172
	v_mul_f32_e32 v183, v173, v181
	v_sub_f32_e32 v182, v174, v172
	v_mul_f32_e32 v174, v156, v183
	v_fma_f32 v176, v183, v156, -v174
	v_fmac_f32_e32 v176, v183, v151
	v_add_f32_e32 v172, v174, v176
	v_sub_f32_e32 v175, v173, v172
	v_pk_add_f32 v[178:179], v[172:173], v[174:175] neg_lo:[0,1] neg_hi:[0,1]
	v_mov_b32_e32 v177, v172
	v_pk_add_f32 v[172:173], v[178:179], v[176:177] neg_lo:[0,1] neg_hi:[0,1]
	v_cmp_neq_f32_e32 vcc, s70, v136
	v_add_f32_e32 v173, v182, v173
	v_add_f32_e32 v172, v172, v173
	v_add_f32_e32 v173, v175, v172
	v_mul_f32_e32 v182, v181, v173
	v_mul_f32_e32 v174, v156, v182
	v_fma_f32 v176, v182, v156, -v174
	v_fmac_f32_e32 v176, v182, v151
	v_sub_f32_e32 v151, v175, v173
	v_add_f32_e32 v151, v172, v151
	v_add_f32_e32 v172, v174, v176
	v_sub_f32_e32 v175, v173, v172
	v_pk_add_f32 v[178:179], v[172:173], v[174:175] neg_lo:[0,1] neg_hi:[0,1]
	v_mov_b32_e32 v177, v172
	v_pk_add_f32 v[172:173], v[178:179], v[176:177] neg_lo:[0,1] neg_hi:[0,1]
	v_add_f32_e32 v156, v183, v182
	v_add_f32_e32 v151, v151, v173
	v_add_f32_e32 v151, v172, v151
	v_add_f32_e32 v151, v175, v151
	v_sub_f32_e32 v172, v156, v183
	v_mul_f32_e32 v151, v181, v151
	v_sub_f32_e32 v172, v182, v172
	v_add_f32_e32 v173, v172, v151
	v_add_f32_e32 v174, v156, v173
	v_cvt_f32_i32_e32 v172, v180
	v_mul_f32_e32 v176, v174, v174
	v_fmamk_f32 v151, v176, 0x3e9b6dac, v166
	v_sub_f32_e32 v156, v174, v156
	v_fmaak_f32 v151, v176, v151, 0x3f2aaada
	v_sub_f32_e32 v156, v173, v156
	v_mul_f32_e32 v173, v174, v176
	v_pk_mul_f32 v[176:177], v[172:173], v[150:151]
	v_ldexp_f32 v175, v174, 1
	v_fma_f32 v174, v172, s69, -v176
	v_fmac_f32_e32 v174, 0xb102e308, v172
	v_pk_add_f32 v[172:173], v[176:177], v[174:175]
	v_ldexp_f32 v156, v156, 1
	v_sub_f32_e32 v151, v173, v175
	v_sub_f32_e32 v151, v177, v151
	v_add_f32_e32 v179, v156, v151
	v_mov_b32_e32 v178, v176
	v_pk_add_f32 v[176:177], v[172:173], v[176:177] neg_lo:[0,1] neg_hi:[0,1]
	v_pk_add_f32 v[180:181], v[172:173], v[178:179]
	v_mov_b32_e32 v175, v172
	v_mov_b32_e32 v177, v181
	v_pk_add_f32 v[182:183], v[174:175], v[176:177] neg_lo:[0,1] neg_hi:[0,1]
	v_pk_add_f32 v[174:175], v[174:175], v[176:177]
	v_mov_b32_e32 v178, v179
	v_pk_add_f32 v[176:177], v[174:175], v[172:173] op_sel:[1,0] op_sel_hi:[0,1] neg_lo:[0,1] neg_hi:[0,1]
	v_pk_add_f32 v[184:185], v[180:181], v[176:177] op_sel_hi:[1,0] neg_lo:[0,1] neg_hi:[0,1]
	v_mov_b32_e32 v180, v181
	v_mov_b32_e32 v181, v175
	v_pk_mov_b32 v[176:177], v[172:173], v[176:177] op_sel:[1,0]
	v_mov_b32_e32 v179, v172
	v_pk_add_f32 v[176:177], v[180:181], v[176:177] neg_lo:[0,1] neg_hi:[0,1]
	v_mov_b32_e32 v184, v182
	v_pk_add_f32 v[172:173], v[178:179], v[176:177] neg_lo:[0,1] neg_hi:[0,1]
	v_mov_b32_e32 v183, v175
	v_pk_add_f32 v[176:177], v[184:185], v[172:173]
	s_nop 0
	v_pk_add_f32 v[178:179], v[176:177], v[176:177] op_sel:[0,1] op_sel_hi:[1,0]
	s_nop 0
	v_pk_add_f32 v[174:175], v[174:175], v[178:179] op_sel:[1,0] op_sel_hi:[0,1]
	v_mov_b32_e32 v177, v174
	v_pk_add_f32 v[180:181], v[176:177], v[182:183] neg_lo:[0,1] neg_hi:[0,1]
	v_mov_b32_e32 v173, v178
	v_sub_f32_e32 v151, v176, v180
	v_pk_add_f32 v[172:173], v[172:173], v[180:181] neg_lo:[0,1] neg_hi:[0,1]
	v_sub_f32_e32 v151, v182, v151
	v_add_f32_e32 v151, v172, v151
	v_add_f32_e32 v151, v151, v173
	v_add_f32_e32 v151, v174, v151
	v_cndmask_b32_e32 v151, v167, v151, vcc
	v_cmp_ngt_f32_e32 vcc, -1.0, v136
	s_nop 1
	v_cndmask_b32_e32 v151, v168, v151, vcc
	v_cmp_neq_f32_e32 vcc, -1.0, v136
	s_nop 1
	v_cndmask_b32_e32 v151, v169, v151, vcc
	v_cmp_lt_f32_e64 vcc, |v136|, s71
	s_nop 1
	v_cndmask_b32_e32 v136, v151, v136, vcc
;     __device__ __forceinline__ void operator()(const f32x4 (&acc)[2][2][4][2], const Unit& u, int wr, int wc, int fr, int fq) const {
;     ...
;                     for (int m = 0; m < 4; ++m) { const int r = row0 + ai * HALF + m * 16;
;                         const f32x4 v0 = acc[ai][0][m][0], v1 = acc[ai][0][m][1]; float* dp = DT + (size_t)r * 32 + c0;
; #pragma unroll
;                         for (int i = 0; i < 4; ++i) { float x0 = v0[i] + dt_bias[c0 + i], x1 = v1[i] + dt_bias[c0 + 4 + i];
;                             dp[i] = x0 > 20.f ? x0 : log1pf(__expf(x0)); dp[4 + i] = x1 > 20.f ? x1 : log1pf(__expf(x1)); }
.LBB0_791:
	s_or_b64 exec, exec, s[24:25]
	global_store_dword v[154:155], v136, off offset:20
	global_load_dword v136, v[140:141], off offset:8
	s_waitcnt vmcnt(0)
	v_add_f32_e32 v151, v126, v136
	global_load_dword v136, v[140:141], off offset:24
	v_cmp_nlt_f32_e32 vcc, s67, v151
	s_and_saveexec_b64 s[24:25], vcc
	s_cbranch_execz .LBB0_793
	v_mul_f32_e32 v151, 0x3fb8aa3b, v151
	v_exp_f32_e32 v156, v151
	s_nop 0
	v_add_f32_e32 v151, 1.0, v156
	v_frexp_mant_f32_e32 v175, v151
	v_cvt_f64_f32_e32 v[172:173], v151
	v_add_f32_e32 v174, -1.0, v151
	v_frexp_exp_i32_f64_e32 v172, v[172:173]
	v_cmp_gt_f32_e32 vcc, s68, v175
	v_sub_f32_e32 v176, v174, v151
	v_sub_f32_e32 v174, v156, v174
	v_subbrev_co_u32_e32 v180, vcc, 0, v172, vcc
	v_add_f32_e32 v176, 1.0, v176
	v_sub_u32_e32 v172, 0, v180
	v_add_f32_e32 v174, v174, v176
	v_ldexp_f32 v151, v151, v172
	v_ldexp_f32 v172, v174, v172
	v_add_f32_e32 v174, -1.0, v151
	v_add_f32_e32 v173, 1.0, v174
	v_sub_f32_e32 v173, v151, v173
	v_add_f32_e32 v175, v172, v173
	v_add_f32_e32 v173, 1.0, v151
	v_add_f32_e32 v176, -1.0, v173
	v_sub_f32_e32 v151, v151, v176
	v_add_f32_e32 v151, v172, v151
	v_add_f32_e32 v181, v173, v151
	v_rcp_f32_e32 v182, v181
	v_sub_f32_e32 v172, v181, v173
	v_add_f32_e32 v173, v174, v175
	v_sub_f32_e32 v151, v151, v172
	v_mul_f32_e32 v184, v173, v182
	v_sub_f32_e32 v172, v173, v174
	v_mul_f32_e32 v174, v181, v184
	v_fma_f32 v176, v184, v181, -v174
	v_fmac_f32_e32 v176, v184, v151
	v_sub_f32_e32 v183, v175, v172
	v_add_f32_e32 v172, v174, v176
	v_sub_f32_e32 v175, v173, v172
	v_pk_add_f32 v[178:179], v[172:173], v[174:175] neg_lo:[0,1] neg_hi:[0,1]
	v_mov_b32_e32 v177, v172
	v_pk_add_f32 v[172:173], v[178:179], v[176:177] neg_lo:[0,1] neg_hi:[0,1]
	v_cmp_neq_f32_e32 vcc, s70, v156
	v_add_f32_e32 v173, v183, v173
	v_add_f32_e32 v172, v172, v173
	v_add_f32_e32 v173, v175, v172
	v_mul_f32_e32 v183, v182, v173
	v_mul_f32_e32 v174, v181, v183
	v_fma_f32 v176, v183, v181, -v174
	v_fmac_f32_e32 v176, v183, v151
	v_sub_f32_e32 v151, v175, v173
	v_add_f32_e32 v151, v172, v151
	v_add_f32_e32 v172, v174, v176
	v_sub_f32_e32 v175, v173, v172
	v_pk_add_f32 v[178:179], v[172:173], v[174:175] neg_lo:[0,1] neg_hi:[0,1]
	v_mov_b32_e32 v177, v172
	v_pk_add_f32 v[172:173], v[178:179], v[176:177] neg_lo:[0,1] neg_hi:[0,1]
	s_nop 0
	v_add_f32_e32 v151, v151, v173
	v_add_f32_e32 v151, v172, v151
	v_add_f32_e32 v173, v184, v183
	v_add_f32_e32 v151, v175, v151
	v_sub_f32_e32 v172, v173, v184
	v_mul_f32_e32 v151, v182, v151
	v_sub_f32_e32 v172, v183, v172
	v_add_f32_e32 v174, v172, v151
	v_add_f32_e32 v176, v173, v174
	v_cvt_f32_i32_e32 v172, v180
	v_mul_f32_e32 v177, v176, v176
	v_sub_f32_e32 v173, v176, v173
	v_fmamk_f32 v151, v177, 0x3e9b6dac, v166
	v_sub_f32_e32 v173, v174, v173
	v_fmaak_f32 v151, v177, v151, 0x3f2aaada
	v_ldexp_f32 v178, v173, 1
	v_mul_f32_e32 v173, v176, v177
	v_ldexp_f32 v175, v176, 1
	v_pk_mul_f32 v[176:177], v[172:173], v[150:151]
	s_nop 0
	v_fma_f32 v174, v172, s69, -v176
	v_fmac_f32_e32 v174, 0xb102e308, v172
	v_pk_add_f32 v[172:173], v[176:177], v[174:175]
	s_nop 0
	v_sub_f32_e32 v151, v173, v175
	v_sub_f32_e32 v151, v177, v151
	v_add_f32_e32 v179, v178, v151
	v_mov_b32_e32 v178, v176
	v_pk_add_f32 v[176:177], v[172:173], v[176:177] neg_lo:[0,1] neg_hi:[0,1]
	v_pk_add_f32 v[180:181], v[172:173], v[178:179]
	v_mov_b32_e32 v175, v172
	v_mov_b32_e32 v177, v181
	v_pk_add_f32 v[182:183], v[174:175], v[176:177] neg_lo:[0,1] neg_hi:[0,1]
	v_pk_add_f32 v[174:175], v[174:175], v[176:177]
	v_mov_b32_e32 v178, v179
	v_pk_add_f32 v[176:177], v[174:175], v[172:173] op_sel:[1,0] op_sel_hi:[0,1] neg_lo:[0,1] neg_hi:[0,1]
	v_pk_add_f32 v[184:185], v[180:181], v[176:177] op_sel_hi:[1,0] neg_lo:[0,1] neg_hi:[0,1]
	v_mov_b32_e32 v180, v181
	v_mov_b32_e32 v181, v175
	v_pk_mov_b32 v[176:177], v[172:173], v[176:177] op_sel:[1,0]
	v_mov_b32_e32 v179, v172
	v_pk_add_f32 v[176:177], v[180:181], v[176:177] neg_lo:[0,1] neg_hi:[0,1]
	v_mov_b32_e32 v184, v182
	v_pk_add_f32 v[172:173], v[178:179], v[176:177] neg_lo:[0,1] neg_hi:[0,1]
	v_mov_b32_e32 v183, v175
	v_pk_add_f32 v[176:177], v[184:185], v[172:173]
	s_nop 0
	v_pk_add_f32 v[178:179], v[176:177], v[176:177] op_sel:[0,1] op_sel_hi:[1,0]
	s_nop 0
	v_pk_add_f32 v[174:175], v[174:175], v[178:179] op_sel:[1,0] op_sel_hi:[0,1]
	v_mov_b32_e32 v177, v174
	v_pk_add_f32 v[180:181], v[176:177], v[182:183] neg_lo:[0,1] neg_hi:[0,1]
	v_mov_b32_e32 v173, v178
	v_sub_f32_e32 v151, v176, v180
	v_pk_add_f32 v[172:173], v[172:173], v[180:181] neg_lo:[0,1] neg_hi:[0,1]
	v_sub_f32_e32 v151, v182, v151
	v_add_f32_e32 v151, v172, v151
	v_add_f32_e32 v151, v151, v173
	v_add_f32_e32 v151, v174, v151
	v_cndmask_b32_e32 v151, v167, v151, vcc
	v_cmp_ngt_f32_e32 vcc, -1.0, v156
	s_nop 1
	v_cndmask_b32_e32 v151, v168, v151, vcc
	v_cmp_neq_f32_e32 vcc, -1.0, v156
	s_nop 1
	v_cndmask_b32_e32 v151, v169, v151, vcc
	v_cmp_lt_f32_e64 vcc, |v156|, s71
	s_nop 1
	v_cndmask_b32_e32 v151, v151, v156, vcc
;     __device__ __forceinline__ void operator()(const f32x4 (&acc)[2][2][4][2], const Unit& u, int wr, int wc, int fr, int fq) const {
;     ...
;                     for (int m = 0; m < 4; ++m) { const int r = row0 + ai * HALF + m * 16;
;                         const f32x4 v0 = acc[ai][0][m][0], v1 = acc[ai][0][m][1]; float* dp = DT + (size_t)r * 32 + c0;
; #pragma unroll
;                         for (int i = 0; i < 4; ++i) { float x0 = v0[i] + dt_bias[c0 + i], x1 = v1[i] + dt_bias[c0 + 4 + i];
;                             dp[i] = x0 > 20.f ? x0 : log1pf(__expf(x0)); dp[4 + i] = x1 > 20.f ? x1 : log1pf(__expf(x1)); }
.LBB0_793:
	s_or_b64 exec, exec, s[24:25]
	s_waitcnt vmcnt(0)
	v_add_f32_e32 v136, v122, v136
	v_cmp_nlt_f32_e32 vcc, s67, v136
	global_store_dword v[154:155], v151, off offset:8
	s_and_saveexec_b64 s[24:25], vcc
	s_cbranch_execz .LBB0_795
	v_mul_f32_e32 v136, 0x3fb8aa3b, v136
	v_exp_f32_e32 v136, v136
	s_nop 0
	v_add_f32_e32 v151, 1.0, v136
	v_frexp_mant_f32_e32 v174, v151
	v_cvt_f64_f32_e32 v[172:173], v151
	v_add_f32_e32 v156, -1.0, v151
	v_frexp_exp_i32_f64_e32 v172, v[172:173]
	v_cmp_gt_f32_e32 vcc, s68, v174
	v_sub_f32_e32 v175, v156, v151
	v_sub_f32_e32 v156, v136, v156
	v_subbrev_co_u32_e32 v180, vcc, 0, v172, vcc
	v_add_f32_e32 v175, 1.0, v175
	v_sub_u32_e32 v172, 0, v180
	v_add_f32_e32 v156, v156, v175
	v_ldexp_f32 v151, v151, v172
	v_ldexp_f32 v156, v156, v172
	v_add_f32_e32 v172, -1.0, v151
	v_add_f32_e32 v173, 1.0, v172
	v_sub_f32_e32 v173, v151, v173
	v_add_f32_e32 v174, v156, v173
	v_add_f32_e32 v173, 1.0, v151
	v_add_f32_e32 v175, -1.0, v173
	v_sub_f32_e32 v151, v151, v175
	v_add_f32_e32 v151, v156, v151
	v_add_f32_e32 v156, v173, v151
	v_rcp_f32_e32 v181, v156
	v_sub_f32_e32 v173, v156, v173
	v_sub_f32_e32 v151, v151, v173
	v_add_f32_e32 v173, v172, v174
	v_sub_f32_e32 v172, v173, v172
	v_mul_f32_e32 v183, v173, v181
	v_sub_f32_e32 v182, v174, v172
	v_mul_f32_e32 v174, v156, v183
	v_fma_f32 v176, v183, v156, -v174
	v_fmac_f32_e32 v176, v183, v151
	v_add_f32_e32 v172, v174, v176
	v_sub_f32_e32 v175, v173, v172
	v_pk_add_f32 v[178:179], v[172:173], v[174:175] neg_lo:[0,1] neg_hi:[0,1]
	v_mov_b32_e32 v177, v172
	v_pk_add_f32 v[172:173], v[178:179], v[176:177] neg_lo:[0,1] neg_hi:[0,1]
	v_cmp_neq_f32_e32 vcc, s70, v136
	v_add_f32_e32 v173, v182, v173
	v_add_f32_e32 v172, v172, v173
	v_add_f32_e32 v173, v175, v172
	v_mul_f32_e32 v182, v181, v173
	v_mul_f32_e32 v174, v156, v182
	v_fma_f32 v176, v182, v156, -v174
	v_fmac_f32_e32 v176, v182, v151
	v_sub_f32_e32 v151, v175, v173
	v_add_f32_e32 v151, v172, v151
	v_add_f32_e32 v172, v174, v176
	v_sub_f32_e32 v175, v173, v172
	v_pk_add_f32 v[178:179], v[172:173], v[174:175] neg_lo:[0,1] neg_hi:[0,1]
	v_mov_b32_e32 v177, v172
	v_pk_add_f32 v[172:173], v[178:179], v[176:177] neg_lo:[0,1] neg_hi:[0,1]
	v_add_f32_e32 v156, v183, v182
	v_add_f32_e32 v151, v151, v173
	v_add_f32_e32 v151, v172, v151
	v_add_f32_e32 v151, v175, v151
	v_sub_f32_e32 v172, v156, v183
	v_mul_f32_e32 v151, v181, v151
	v_sub_f32_e32 v172, v182, v172
	v_add_f32_e32 v173, v172, v151
	v_add_f32_e32 v174, v156, v173
	v_cvt_f32_i32_e32 v172, v180
	v_mul_f32_e32 v176, v174, v174
	v_fmamk_f32 v151, v176, 0x3e9b6dac, v166
	v_sub_f32_e32 v156, v174, v156
	v_fmaak_f32 v151, v176, v151, 0x3f2aaada
	v_sub_f32_e32 v156, v173, v156
	v_mul_f32_e32 v173, v174, v176
	v_pk_mul_f32 v[176:177], v[172:173], v[150:151]
	v_ldexp_f32 v175, v174, 1
	v_fma_f32 v174, v172, s69, -v176
	v_fmac_f32_e32 v174, 0xb102e308, v172
	v_pk_add_f32 v[172:173], v[176:177], v[174:175]
	v_ldexp_f32 v156, v156, 1
	v_sub_f32_e32 v151, v173, v175
	v_sub_f32_e32 v151, v177, v151
	v_add_f32_e32 v179, v156, v151
	v_mov_b32_e32 v178, v176
	v_pk_add_f32 v[176:177], v[172:173], v[176:177] neg_lo:[0,1] neg_hi:[0,1]
	v_pk_add_f32 v[180:181], v[172:173], v[178:179]
	v_mov_b32_e32 v175, v172
	v_mov_b32_e32 v177, v181
	v_pk_add_f32 v[182:183], v[174:175], v[176:177] neg_lo:[0,1] neg_hi:[0,1]
	v_pk_add_f32 v[174:175], v[174:175], v[176:177]
	v_mov_b32_e32 v178, v179
	v_pk_add_f32 v[176:177], v[174:175], v[172:173] op_sel:[1,0] op_sel_hi:[0,1] neg_lo:[0,1] neg_hi:[0,1]
	v_pk_add_f32 v[184:185], v[180:181], v[176:177] op_sel_hi:[1,0] neg_lo:[0,1] neg_hi:[0,1]
	v_mov_b32_e32 v180, v181
	v_mov_b32_e32 v181, v175
	v_pk_mov_b32 v[176:177], v[172:173], v[176:177] op_sel:[1,0]
	v_mov_b32_e32 v179, v172
	v_pk_add_f32 v[176:177], v[180:181], v[176:177] neg_lo:[0,1] neg_hi:[0,1]
	v_mov_b32_e32 v184, v182
	v_pk_add_f32 v[172:173], v[178:179], v[176:177] neg_lo:[0,1] neg_hi:[0,1]
	v_mov_b32_e32 v183, v175
	v_pk_add_f32 v[176:177], v[184:185], v[172:173]
	s_nop 0
	v_pk_add_f32 v[178:179], v[176:177], v[176:177] op_sel:[0,1] op_sel_hi:[1,0]
	s_nop 0
	v_pk_add_f32 v[174:175], v[174:175], v[178:179] op_sel:[1,0] op_sel_hi:[0,1]
	v_mov_b32_e32 v177, v174
	v_pk_add_f32 v[180:181], v[176:177], v[182:183] neg_lo:[0,1] neg_hi:[0,1]
	v_mov_b32_e32 v173, v178
	v_sub_f32_e32 v151, v176, v180
	v_pk_add_f32 v[172:173], v[172:173], v[180:181] neg_lo:[0,1] neg_hi:[0,1]
	v_sub_f32_e32 v151, v182, v151
	v_add_f32_e32 v151, v172, v151
	v_add_f32_e32 v151, v151, v173
	v_add_f32_e32 v151, v174, v151
	v_cndmask_b32_e32 v151, v167, v151, vcc
	v_cmp_ngt_f32_e32 vcc, -1.0, v136
	s_nop 1
	v_cndmask_b32_e32 v151, v168, v151, vcc
	v_cmp_neq_f32_e32 vcc, -1.0, v136
	s_nop 1
	v_cndmask_b32_e32 v151, v169, v151, vcc
	v_cmp_lt_f32_e64 vcc, |v136|, s71
	s_nop 1
	v_cndmask_b32_e32 v136, v151, v136, vcc
;     __device__ __forceinline__ void operator()(const f32x4 (&acc)[2][2][4][2], const Unit& u, int wr, int wc, int fr, int fq) const {
;     ...
;                     for (int m = 0; m < 4; ++m) { const int r = row0 + ai * HALF + m * 16;
;                         const f32x4 v0 = acc[ai][0][m][0], v1 = acc[ai][0][m][1]; float* dp = DT + (size_t)r * 32 + c0;
; #pragma unroll
;                         for (int i = 0; i < 4; ++i) { float x0 = v0[i] + dt_bias[c0 + i], x1 = v1[i] + dt_bias[c0 + 4 + i];
;                             dp[i] = x0 > 20.f ? x0 : log1pf(__expf(x0)); dp[4 + i] = x1 > 20.f ? x1 : log1pf(__expf(x1)); }
.LBB0_795:
	s_or_b64 exec, exec, s[24:25]
	global_store_dword v[154:155], v136, off offset:24
	global_load_dword v136, v[140:141], off offset:12
	s_waitcnt vmcnt(0)
	v_add_f32_e32 v151, v127, v136
	global_load_dword v136, v[140:141], off offset:28
	v_cmp_nlt_f32_e32 vcc, s67, v151
	s_and_saveexec_b64 s[24:25], vcc
	s_cbranch_execz .LBB0_797
	v_mul_f32_e32 v151, 0x3fb8aa3b, v151
	v_exp_f32_e32 v156, v151
	s_nop 0
	v_add_f32_e32 v151, 1.0, v156
	v_frexp_mant_f32_e32 v175, v151
	v_cvt_f64_f32_e32 v[172:173], v151
	v_add_f32_e32 v174, -1.0, v151
	v_frexp_exp_i32_f64_e32 v172, v[172:173]
	v_cmp_gt_f32_e32 vcc, s68, v175
	v_sub_f32_e32 v176, v174, v151
	v_sub_f32_e32 v174, v156, v174
	v_subbrev_co_u32_e32 v180, vcc, 0, v172, vcc
	v_add_f32_e32 v176, 1.0, v176
	v_sub_u32_e32 v172, 0, v180
	v_add_f32_e32 v174, v174, v176
	v_ldexp_f32 v151, v151, v172
	v_ldexp_f32 v172, v174, v172
	v_add_f32_e32 v174, -1.0, v151
	v_add_f32_e32 v173, 1.0, v174
	v_sub_f32_e32 v173, v151, v173
	v_add_f32_e32 v175, v172, v173
	v_add_f32_e32 v173, 1.0, v151
	v_add_f32_e32 v176, -1.0, v173
	v_sub_f32_e32 v151, v151, v176
	v_add_f32_e32 v151, v172, v151
	v_add_f32_e32 v181, v173, v151
	v_rcp_f32_e32 v182, v181
	v_sub_f32_e32 v172, v181, v173
	v_add_f32_e32 v173, v174, v175
	v_sub_f32_e32 v151, v151, v172
	v_mul_f32_e32 v184, v173, v182
	v_sub_f32_e32 v172, v173, v174
	v_mul_f32_e32 v174, v181, v184
	v_fma_f32 v176, v184, v181, -v174
	v_fmac_f32_e32 v176, v184, v151
	v_sub_f32_e32 v183, v175, v172
	v_add_f32_e32 v172, v174, v176
	v_sub_f32_e32 v175, v173, v172
	v_pk_add_f32 v[178:179], v[172:173], v[174:175] neg_lo:[0,1] neg_hi:[0,1]
	v_mov_b32_e32 v177, v172
	v_pk_add_f32 v[172:173], v[178:179], v[176:177] neg_lo:[0,1] neg_hi:[0,1]
	v_cmp_neq_f32_e32 vcc, s70, v156
	v_add_f32_e32 v173, v183, v173
	v_add_f32_e32 v172, v172, v173
	v_add_f32_e32 v173, v175, v172
	v_mul_f32_e32 v183, v182, v173
	v_mul_f32_e32 v174, v181, v183
	v_fma_f32 v176, v183, v181, -v174
	v_fmac_f32_e32 v176, v183, v151
	v_sub_f32_e32 v151, v175, v173
	v_add_f32_e32 v151, v172, v151
	v_add_f32_e32 v172, v174, v176
	v_sub_f32_e32 v175, v173, v172
	v_pk_add_f32 v[178:179], v[172:173], v[174:175] neg_lo:[0,1] neg_hi:[0,1]
	v_mov_b32_e32 v177, v172
	v_pk_add_f32 v[172:173], v[178:179], v[176:177] neg_lo:[0,1] neg_hi:[0,1]
	s_nop 0
	v_add_f32_e32 v151, v151, v173
	v_add_f32_e32 v151, v172, v151
	v_add_f32_e32 v173, v184, v183
	v_add_f32_e32 v151, v175, v151
	v_sub_f32_e32 v172, v173, v184
	v_mul_f32_e32 v151, v182, v151
	v_sub_f32_e32 v172, v183, v172
	v_add_f32_e32 v174, v172, v151
	v_add_f32_e32 v176, v173, v174
	v_cvt_f32_i32_e32 v172, v180
	v_mul_f32_e32 v177, v176, v176
	v_sub_f32_e32 v173, v176, v173
	v_fmamk_f32 v151, v177, 0x3e9b6dac, v166
	v_sub_f32_e32 v173, v174, v173
	v_fmaak_f32 v151, v177, v151, 0x3f2aaada
	v_ldexp_f32 v178, v173, 1
	v_mul_f32_e32 v173, v176, v177
	v_ldexp_f32 v175, v176, 1
	v_pk_mul_f32 v[176:177], v[172:173], v[150:151]
	s_nop 0
	v_fma_f32 v174, v172, s69, -v176
	v_fmac_f32_e32 v174, 0xb102e308, v172
	v_pk_add_f32 v[172:173], v[176:177], v[174:175]
	s_nop 0
	v_sub_f32_e32 v151, v173, v175
	v_sub_f32_e32 v151, v177, v151
	v_add_f32_e32 v179, v178, v151
	v_mov_b32_e32 v178, v176
	v_pk_add_f32 v[176:177], v[172:173], v[176:177] neg_lo:[0,1] neg_hi:[0,1]
	v_pk_add_f32 v[180:181], v[172:173], v[178:179]
	v_mov_b32_e32 v175, v172
	v_mov_b32_e32 v177, v181
	v_pk_add_f32 v[182:183], v[174:175], v[176:177] neg_lo:[0,1] neg_hi:[0,1]
	v_pk_add_f32 v[174:175], v[174:175], v[176:177]
	v_mov_b32_e32 v178, v179
	v_pk_add_f32 v[176:177], v[174:175], v[172:173] op_sel:[1,0] op_sel_hi:[0,1] neg_lo:[0,1] neg_hi:[0,1]
	v_pk_add_f32 v[184:185], v[180:181], v[176:177] op_sel_hi:[1,0] neg_lo:[0,1] neg_hi:[0,1]
	v_mov_b32_e32 v180, v181
	v_mov_b32_e32 v181, v175
	v_pk_mov_b32 v[176:177], v[172:173], v[176:177] op_sel:[1,0]
	v_mov_b32_e32 v179, v172
	v_pk_add_f32 v[176:177], v[180:181], v[176:177] neg_lo:[0,1] neg_hi:[0,1]
	v_mov_b32_e32 v184, v182
	v_pk_add_f32 v[172:173], v[178:179], v[176:177] neg_lo:[0,1] neg_hi:[0,1]
	v_mov_b32_e32 v183, v175
	v_pk_add_f32 v[176:177], v[184:185], v[172:173]
	s_nop 0
	v_pk_add_f32 v[178:179], v[176:177], v[176:177] op_sel:[0,1] op_sel_hi:[1,0]
	s_nop 0
	v_pk_add_f32 v[174:175], v[174:175], v[178:179] op_sel:[1,0] op_sel_hi:[0,1]
	v_mov_b32_e32 v177, v174
	v_pk_add_f32 v[180:181], v[176:177], v[182:183] neg_lo:[0,1] neg_hi:[0,1]
	v_mov_b32_e32 v173, v178
	v_sub_f32_e32 v151, v176, v180
	v_pk_add_f32 v[172:173], v[172:173], v[180:181] neg_lo:[0,1] neg_hi:[0,1]
	v_sub_f32_e32 v151, v182, v151
	v_add_f32_e32 v151, v172, v151
	v_add_f32_e32 v151, v151, v173
	v_add_f32_e32 v151, v174, v151
	v_cndmask_b32_e32 v151, v167, v151, vcc
	v_cmp_ngt_f32_e32 vcc, -1.0, v156
	s_nop 1
	v_cndmask_b32_e32 v151, v168, v151, vcc
	v_cmp_neq_f32_e32 vcc, -1.0, v156
	s_nop 1
	v_cndmask_b32_e32 v151, v169, v151, vcc
	v_cmp_lt_f32_e64 vcc, |v156|, s71
	s_nop 1
	v_cndmask_b32_e32 v151, v151, v156, vcc
;     __device__ __forceinline__ void operator()(const f32x4 (&acc)[2][2][4][2], const Unit& u, int wr, int wc, int fr, int fq) const {
;     ...
;                     for (int m = 0; m < 4; ++m) { const int r = row0 + ai * HALF + m * 16;
;                         const f32x4 v0 = acc[ai][0][m][0], v1 = acc[ai][0][m][1]; float* dp = DT + (size_t)r * 32 + c0;
; #pragma unroll
;                         for (int i = 0; i < 4; ++i) { float x0 = v0[i] + dt_bias[c0 + i], x1 = v1[i] + dt_bias[c0 + 4 + i];
;                             dp[i] = x0 > 20.f ? x0 : log1pf(__expf(x0)); dp[4 + i] = x1 > 20.f ? x1 : log1pf(__expf(x1)); }
.LBB0_797:
	s_or_b64 exec, exec, s[24:25]
	s_waitcnt vmcnt(0)
	v_add_f32_e32 v136, v123, v136
	v_cmp_nlt_f32_e32 vcc, s67, v136
	global_store_dword v[154:155], v151, off offset:12
	s_and_saveexec_b64 s[24:25], vcc
	s_cbranch_execz .LBB0_799
	v_mul_f32_e32 v136, 0x3fb8aa3b, v136
	v_exp_f32_e32 v136, v136
	s_nop 0
	v_add_f32_e32 v151, 1.0, v136
	v_frexp_mant_f32_e32 v174, v151
	v_cvt_f64_f32_e32 v[172:173], v151
	v_add_f32_e32 v156, -1.0, v151
	v_frexp_exp_i32_f64_e32 v172, v[172:173]
	v_cmp_gt_f32_e32 vcc, s68, v174
	v_sub_f32_e32 v175, v156, v151
	v_sub_f32_e32 v156, v136, v156
	v_subbrev_co_u32_e32 v180, vcc, 0, v172, vcc
	v_add_f32_e32 v175, 1.0, v175
	v_sub_u32_e32 v172, 0, v180
	v_add_f32_e32 v156, v156, v175
	v_ldexp_f32 v151, v151, v172
	v_ldexp_f32 v156, v156, v172
	v_add_f32_e32 v172, -1.0, v151
	v_add_f32_e32 v173, 1.0, v172
	v_sub_f32_e32 v173, v151, v173
	v_add_f32_e32 v174, v156, v173
	v_add_f32_e32 v173, 1.0, v151
	v_add_f32_e32 v175, -1.0, v173
	v_sub_f32_e32 v151, v151, v175
	v_add_f32_e32 v151, v156, v151
	v_add_f32_e32 v156, v173, v151
	v_rcp_f32_e32 v181, v156
	v_sub_f32_e32 v173, v156, v173
	v_sub_f32_e32 v151, v151, v173
	v_add_f32_e32 v173, v172, v174
	v_sub_f32_e32 v172, v173, v172
	v_mul_f32_e32 v183, v173, v181
	v_sub_f32_e32 v182, v174, v172
	v_mul_f32_e32 v174, v156, v183
	v_fma_f32 v176, v183, v156, -v174
	v_fmac_f32_e32 v176, v183, v151
	v_add_f32_e32 v172, v174, v176
	v_sub_f32_e32 v175, v173, v172
	v_pk_add_f32 v[178:179], v[172:173], v[174:175] neg_lo:[0,1] neg_hi:[0,1]
	v_mov_b32_e32 v177, v172
	v_pk_add_f32 v[172:173], v[178:179], v[176:177] neg_lo:[0,1] neg_hi:[0,1]
	v_cmp_neq_f32_e32 vcc, s70, v136
	v_add_f32_e32 v173, v182, v173
	v_add_f32_e32 v172, v172, v173
	v_add_f32_e32 v173, v175, v172
	v_mul_f32_e32 v182, v181, v173
	v_mul_f32_e32 v174, v156, v182
	v_fma_f32 v176, v182, v156, -v174
	v_fmac_f32_e32 v176, v182, v151
	v_sub_f32_e32 v151, v175, v173
	v_add_f32_e32 v151, v172, v151
	v_add_f32_e32 v172, v174, v176
	v_sub_f32_e32 v175, v173, v172
	v_pk_add_f32 v[178:179], v[172:173], v[174:175] neg_lo:[0,1] neg_hi:[0,1]
	v_mov_b32_e32 v177, v172
	v_pk_add_f32 v[172:173], v[178:179], v[176:177] neg_lo:[0,1] neg_hi:[0,1]
	v_add_f32_e32 v156, v183, v182
	v_add_f32_e32 v151, v151, v173
	v_add_f32_e32 v151, v172, v151
	v_add_f32_e32 v151, v175, v151
	v_sub_f32_e32 v172, v156, v183
	v_mul_f32_e32 v151, v181, v151
	v_sub_f32_e32 v172, v182, v172
	v_add_f32_e32 v173, v172, v151
	v_add_f32_e32 v174, v156, v173
	v_cvt_f32_i32_e32 v172, v180
	v_mul_f32_e32 v176, v174, v174
	v_fmamk_f32 v151, v176, 0x3e9b6dac, v166
	v_sub_f32_e32 v156, v174, v156
	v_fmaak_f32 v151, v176, v151, 0x3f2aaada
	v_sub_f32_e32 v156, v173, v156
	v_mul_f32_e32 v173, v174, v176
	v_pk_mul_f32 v[176:177], v[172:173], v[150:151]
	v_ldexp_f32 v175, v174, 1
	v_fma_f32 v174, v172, s69, -v176
	v_fmac_f32_e32 v174, 0xb102e308, v172
	v_pk_add_f32 v[172:173], v[176:177], v[174:175]
	v_ldexp_f32 v156, v156, 1
	v_sub_f32_e32 v151, v173, v175
	v_sub_f32_e32 v151, v177, v151
	v_add_f32_e32 v179, v156, v151
	v_mov_b32_e32 v178, v176
	v_pk_add_f32 v[176:177], v[172:173], v[176:177] neg_lo:[0,1] neg_hi:[0,1]
	v_pk_add_f32 v[180:181], v[172:173], v[178:179]
	v_mov_b32_e32 v175, v172
	v_mov_b32_e32 v177, v181
	v_pk_add_f32 v[182:183], v[174:175], v[176:177] neg_lo:[0,1] neg_hi:[0,1]
	v_pk_add_f32 v[174:175], v[174:175], v[176:177]
	v_mov_b32_e32 v178, v179
	v_pk_add_f32 v[176:177], v[174:175], v[172:173] op_sel:[1,0] op_sel_hi:[0,1] neg_lo:[0,1] neg_hi:[0,1]
	v_pk_add_f32 v[184:185], v[180:181], v[176:177] op_sel_hi:[1,0] neg_lo:[0,1] neg_hi:[0,1]
	v_mov_b32_e32 v180, v181
	v_mov_b32_e32 v181, v175
	v_pk_mov_b32 v[176:177], v[172:173], v[176:177] op_sel:[1,0]
	v_mov_b32_e32 v179, v172
	v_pk_add_f32 v[176:177], v[180:181], v[176:177] neg_lo:[0,1] neg_hi:[0,1]
	v_mov_b32_e32 v184, v182
	v_pk_add_f32 v[172:173], v[178:179], v[176:177] neg_lo:[0,1] neg_hi:[0,1]
	v_mov_b32_e32 v183, v175
	v_pk_add_f32 v[176:177], v[184:185], v[172:173]
	s_nop 0
	v_pk_add_f32 v[178:179], v[176:177], v[176:177] op_sel:[0,1] op_sel_hi:[1,0]
	s_nop 0
	v_pk_add_f32 v[174:175], v[174:175], v[178:179] op_sel:[1,0] op_sel_hi:[0,1]
	v_mov_b32_e32 v177, v174
	v_pk_add_f32 v[180:181], v[176:177], v[182:183] neg_lo:[0,1] neg_hi:[0,1]
	v_mov_b32_e32 v173, v178
	v_sub_f32_e32 v151, v176, v180
	v_pk_add_f32 v[172:173], v[172:173], v[180:181] neg_lo:[0,1] neg_hi:[0,1]
	v_sub_f32_e32 v151, v182, v151
	v_add_f32_e32 v151, v172, v151
	v_add_f32_e32 v151, v151, v173
	v_add_f32_e32 v151, v174, v151
	v_cndmask_b32_e32 v151, v167, v151, vcc
	v_cmp_ngt_f32_e32 vcc, -1.0, v136
	s_nop 1
	v_cndmask_b32_e32 v151, v168, v151, vcc
	v_cmp_neq_f32_e32 vcc, -1.0, v136
	s_nop 1
	v_cndmask_b32_e32 v151, v169, v151, vcc
	v_cmp_lt_f32_e64 vcc, |v136|, s71
	s_nop 1
	v_cndmask_b32_e32 v136, v151, v136, vcc
;     __device__ __forceinline__ void operator()(const f32x4 (&acc)[2][2][4][2], const Unit& u, int wr, int wc, int fr, int fq) const {
;     ...
;                     for (int m = 0; m < 4; ++m) { const int r = row0 + ai * HALF + m * 16;
;                         const f32x4 v0 = acc[ai][0][m][0], v1 = acc[ai][0][m][1]; float* dp = DT + (size_t)r * 32 + c0;
; #pragma unroll
;                         for (int i = 0; i < 4; ++i) { float x0 = v0[i] + dt_bias[c0 + i], x1 = v1[i] + dt_bias[c0 + 4 + i];
;                             dp[i] = x0 > 20.f ? x0 : log1pf(__expf(x0)); dp[4 + i] = x1 > 20.f ? x1 : log1pf(__expf(x1)); }
.LBB0_799:
	s_or_b64 exec, exec, s[24:25]
	global_store_dword v[154:155], v136, off offset:28
	global_load_dword v136, v[140:141], off
	s_waitcnt vmcnt(0)
	v_add_f32_e32 v151, v108, v136
	global_load_dword v136, v[140:141], off offset:16
	v_cmp_nlt_f32_e32 vcc, s67, v151
	s_and_saveexec_b64 s[24:25], vcc
	s_cbranch_execz .LBB0_801
	v_mul_f32_e32 v151, 0x3fb8aa3b, v151
	v_exp_f32_e32 v156, v151
	s_nop 0
	v_add_f32_e32 v151, 1.0, v156
	v_frexp_mant_f32_e32 v173, v151
	v_cvt_f64_f32_e32 v[154:155], v151
	v_add_f32_e32 v172, -1.0, v151
	v_frexp_exp_i32_f64_e32 v154, v[154:155]
	v_cmp_gt_f32_e32 vcc, s68, v173
	v_sub_f32_e32 v174, v172, v151
	v_sub_f32_e32 v172, v156, v172
	v_subbrev_co_u32_e32 v178, vcc, 0, v154, vcc
	v_add_f32_e32 v174, 1.0, v174
	v_sub_u32_e32 v154, 0, v178
	v_add_f32_e32 v172, v172, v174
	v_ldexp_f32 v151, v151, v154
	v_ldexp_f32 v154, v172, v154
	v_add_f32_e32 v172, -1.0, v151
	v_add_f32_e32 v155, 1.0, v172
	v_sub_f32_e32 v155, v151, v155
	v_add_f32_e32 v173, v154, v155
	v_add_f32_e32 v155, 1.0, v151
	v_add_f32_e32 v174, -1.0, v155
	v_sub_f32_e32 v151, v151, v174
	v_add_f32_e32 v151, v154, v151
	v_add_f32_e32 v179, v155, v151
	v_rcp_f32_e32 v180, v179
	v_sub_f32_e32 v154, v179, v155
	v_add_f32_e32 v155, v172, v173
	v_sub_f32_e32 v151, v151, v154
	v_mul_f32_e32 v182, v155, v180
	v_sub_f32_e32 v154, v155, v172
	v_mul_f32_e32 v172, v179, v182
	v_fma_f32 v174, v182, v179, -v172
	v_fmac_f32_e32 v174, v182, v151
	v_sub_f32_e32 v181, v173, v154
	v_add_f32_e32 v154, v172, v174
	v_sub_f32_e32 v173, v155, v154
	v_pk_add_f32 v[176:177], v[154:155], v[172:173] neg_lo:[0,1] neg_hi:[0,1]
	v_mov_b32_e32 v175, v154
	v_pk_add_f32 v[154:155], v[176:177], v[174:175] neg_lo:[0,1] neg_hi:[0,1]
	v_cmp_neq_f32_e32 vcc, s70, v156
	v_add_f32_e32 v155, v181, v155
	v_add_f32_e32 v154, v154, v155
	v_add_f32_e32 v155, v173, v154
	v_mul_f32_e32 v181, v180, v155
	v_mul_f32_e32 v172, v179, v181
	v_fma_f32 v174, v181, v179, -v172
	v_fmac_f32_e32 v174, v181, v151
	v_sub_f32_e32 v151, v173, v155
	v_add_f32_e32 v151, v154, v151
	v_add_f32_e32 v154, v172, v174
	v_sub_f32_e32 v173, v155, v154
	v_pk_add_f32 v[176:177], v[154:155], v[172:173] neg_lo:[0,1] neg_hi:[0,1]
	v_mov_b32_e32 v175, v154
	v_pk_add_f32 v[154:155], v[176:177], v[174:175] neg_lo:[0,1] neg_hi:[0,1]
	s_nop 0
	v_add_f32_e32 v151, v151, v155
	v_add_f32_e32 v151, v154, v151
	v_add_f32_e32 v155, v182, v181
	v_add_f32_e32 v151, v173, v151
	v_sub_f32_e32 v154, v155, v182
	v_mul_f32_e32 v151, v180, v151
	v_sub_f32_e32 v154, v181, v154
	v_add_f32_e32 v172, v154, v151
	v_add_f32_e32 v174, v155, v172
	v_cvt_f32_i32_e32 v154, v178
	v_mul_f32_e32 v175, v174, v174
	v_sub_f32_e32 v155, v174, v155
	v_fmamk_f32 v151, v175, 0x3e9b6dac, v166
	v_sub_f32_e32 v155, v172, v155
	v_fmaak_f32 v151, v175, v151, 0x3f2aaada
	v_ldexp_f32 v176, v155, 1
	v_mul_f32_e32 v155, v174, v175
	v_ldexp_f32 v173, v174, 1
	v_pk_mul_f32 v[174:175], v[154:155], v[150:151]
	s_nop 0
	v_fma_f32 v172, v154, s69, -v174
	v_fmac_f32_e32 v172, 0xb102e308, v154
	v_pk_add_f32 v[154:155], v[174:175], v[172:173]
	s_nop 0
	v_sub_f32_e32 v151, v155, v173
	v_sub_f32_e32 v151, v175, v151
	v_add_f32_e32 v177, v176, v151
	v_mov_b32_e32 v176, v174
	v_pk_add_f32 v[174:175], v[154:155], v[174:175] neg_lo:[0,1] neg_hi:[0,1]
	v_pk_add_f32 v[178:179], v[154:155], v[176:177]
	v_mov_b32_e32 v173, v154
	v_mov_b32_e32 v175, v179
	v_pk_add_f32 v[180:181], v[172:173], v[174:175] neg_lo:[0,1] neg_hi:[0,1]
	v_pk_add_f32 v[172:173], v[172:173], v[174:175]
	v_mov_b32_e32 v176, v177
	v_pk_add_f32 v[174:175], v[172:173], v[154:155] op_sel:[1,0] op_sel_hi:[0,1] neg_lo:[0,1] neg_hi:[0,1]
	v_pk_add_f32 v[182:183], v[178:179], v[174:175] op_sel_hi:[1,0] neg_lo:[0,1] neg_hi:[0,1]
	v_mov_b32_e32 v178, v179
	v_mov_b32_e32 v179, v173
	v_pk_mov_b32 v[174:175], v[154:155], v[174:175] op_sel:[1,0]
	v_mov_b32_e32 v177, v154
	v_pk_add_f32 v[174:175], v[178:179], v[174:175] neg_lo:[0,1] neg_hi:[0,1]
	v_mov_b32_e32 v182, v180
	v_pk_add_f32 v[154:155], v[176:177], v[174:175] neg_lo:[0,1] neg_hi:[0,1]
	v_mov_b32_e32 v181, v173
	v_pk_add_f32 v[174:175], v[182:183], v[154:155]
	s_nop 0
	v_pk_add_f32 v[176:177], v[174:175], v[174:175] op_sel:[0,1] op_sel_hi:[1,0]
	s_nop 0
	v_pk_add_f32 v[172:173], v[172:173], v[176:177] op_sel:[1,0] op_sel_hi:[0,1]
	v_mov_b32_e32 v175, v172
	v_pk_add_f32 v[178:179], v[174:175], v[180:181] neg_lo:[0,1] neg_hi:[0,1]
	v_mov_b32_e32 v155, v176
	v_sub_f32_e32 v151, v174, v178
	v_pk_add_f32 v[154:155], v[154:155], v[178:179] neg_lo:[0,1] neg_hi:[0,1]
	v_sub_f32_e32 v151, v180, v151
	v_add_f32_e32 v151, v154, v151
	v_add_f32_e32 v151, v151, v155
	v_add_f32_e32 v151, v172, v151
	v_cndmask_b32_e32 v151, v167, v151, vcc
	v_cmp_ngt_f32_e32 vcc, -1.0, v156
	s_nop 1
	v_cndmask_b32_e32 v151, v168, v151, vcc
	v_cmp_neq_f32_e32 vcc, -1.0, v156
	s_nop 1
	v_cndmask_b32_e32 v151, v169, v151, vcc
	v_cmp_lt_f32_e64 vcc, |v156|, s71
	s_nop 1
	v_cndmask_b32_e32 v151, v151, v156, vcc
;     __device__ __forceinline__ void operator()(const f32x4 (&acc)[2][2][4][2], const Unit& u, int wr, int wc, int fr, int fq) const {
;     ...
;                     for (int m = 0; m < 4; ++m) { const int r = row0 + ai * HALF + m * 16;
;                         const f32x4 v0 = acc[ai][0][m][0], v1 = acc[ai][0][m][1]; float* dp = DT + (size_t)r * 32 + c0;
; #pragma unroll
;                         for (int i = 0; i < 4; ++i) { float x0 = v0[i] + dt_bias[c0 + i], x1 = v1[i] + dt_bias[c0 + 4 + i];
;                             dp[i] = x0 > 20.f ? x0 : log1pf(__expf(x0)); dp[4 + i] = x1 > 20.f ? x1 : log1pf(__expf(x1)); }
.LBB0_801:
	s_or_b64 exec, exec, s[24:25]
	v_or_b32_e32 v154, 16, v152
	v_ashrrev_i32_e32 v155, 31, v154
	v_lshlrev_b64 v[154:155], 7, v[154:155]
	s_waitcnt vmcnt(0)
	v_add_f32_e32 v136, v104, v136
	v_lshl_add_u64 v[154:155], v[138:139], 0, v[154:155]
	v_cmp_nlt_f32_e32 vcc, s67, v136
	global_store_dword v[154:155], v151, off
	s_and_saveexec_b64 s[24:25], vcc
	s_cbranch_execz .LBB0_803
	v_mul_f32_e32 v136, 0x3fb8aa3b, v136
	v_exp_f32_e32 v136, v136
	s_nop 0
	v_add_f32_e32 v151, 1.0, v136
	v_frexp_mant_f32_e32 v174, v151
	v_cvt_f64_f32_e32 v[172:173], v151
	v_add_f32_e32 v156, -1.0, v151
	v_frexp_exp_i32_f64_e32 v172, v[172:173]
	v_cmp_gt_f32_e32 vcc, s68, v174
	v_sub_f32_e32 v175, v156, v151
	v_sub_f32_e32 v156, v136, v156
	v_subbrev_co_u32_e32 v180, vcc, 0, v172, vcc
	v_add_f32_e32 v175, 1.0, v175
	v_sub_u32_e32 v172, 0, v180
	v_add_f32_e32 v156, v156, v175
	v_ldexp_f32 v151, v151, v172
	v_ldexp_f32 v156, v156, v172
	v_add_f32_e32 v172, -1.0, v151
	v_add_f32_e32 v173, 1.0, v172
	v_sub_f32_e32 v173, v151, v173
	v_add_f32_e32 v174, v156, v173
	v_add_f32_e32 v173, 1.0, v151
	v_add_f32_e32 v175, -1.0, v173
	v_sub_f32_e32 v151, v151, v175
	v_add_f32_e32 v151, v156, v151
	v_add_f32_e32 v156, v173, v151
	v_rcp_f32_e32 v181, v156
	v_sub_f32_e32 v173, v156, v173
	v_sub_f32_e32 v151, v151, v173
	v_add_f32_e32 v173, v172, v174
	v_sub_f32_e32 v172, v173, v172
	v_mul_f32_e32 v183, v173, v181
	v_sub_f32_e32 v182, v174, v172
	v_mul_f32_e32 v174, v156, v183
	v_fma_f32 v176, v183, v156, -v174
	v_fmac_f32_e32 v176, v183, v151
	v_add_f32_e32 v172, v174, v176
	v_sub_f32_e32 v175, v173, v172
	v_pk_add_f32 v[178:179], v[172:173], v[174:175] neg_lo:[0,1] neg_hi:[0,1]
	v_mov_b32_e32 v177, v172
	v_pk_add_f32 v[172:173], v[178:179], v[176:177] neg_lo:[0,1] neg_hi:[0,1]
	v_cmp_neq_f32_e32 vcc, s70, v136
	v_add_f32_e32 v173, v182, v173
	v_add_f32_e32 v172, v172, v173
	v_add_f32_e32 v173, v175, v172
	v_mul_f32_e32 v182, v181, v173
	v_mul_f32_e32 v174, v156, v182
	v_fma_f32 v176, v182, v156, -v174
	v_fmac_f32_e32 v176, v182, v151
	v_sub_f32_e32 v151, v175, v173
	v_add_f32_e32 v151, v172, v151
	v_add_f32_e32 v172, v174, v176
	v_sub_f32_e32 v175, v173, v172
	v_pk_add_f32 v[178:179], v[172:173], v[174:175] neg_lo:[0,1] neg_hi:[0,1]
	v_mov_b32_e32 v177, v172
	v_pk_add_f32 v[172:173], v[178:179], v[176:177] neg_lo:[0,1] neg_hi:[0,1]
	v_add_f32_e32 v156, v183, v182
	v_add_f32_e32 v151, v151, v173
	v_add_f32_e32 v151, v172, v151
	v_add_f32_e32 v151, v175, v151
	v_sub_f32_e32 v172, v156, v183
	v_mul_f32_e32 v151, v181, v151
	v_sub_f32_e32 v172, v182, v172
	v_add_f32_e32 v173, v172, v151
	v_add_f32_e32 v174, v156, v173
	v_cvt_f32_i32_e32 v172, v180
	v_mul_f32_e32 v176, v174, v174
	v_fmamk_f32 v151, v176, 0x3e9b6dac, v166
	v_sub_f32_e32 v156, v174, v156
	v_fmaak_f32 v151, v176, v151, 0x3f2aaada
	v_sub_f32_e32 v156, v173, v156
	v_mul_f32_e32 v173, v174, v176
	v_pk_mul_f32 v[176:177], v[172:173], v[150:151]
	v_ldexp_f32 v175, v174, 1
	v_fma_f32 v174, v172, s69, -v176
	v_fmac_f32_e32 v174, 0xb102e308, v172
	v_pk_add_f32 v[172:173], v[176:177], v[174:175]
	v_ldexp_f32 v156, v156, 1
	v_sub_f32_e32 v151, v173, v175
	v_sub_f32_e32 v151, v177, v151
	v_add_f32_e32 v179, v156, v151
	v_mov_b32_e32 v178, v176
	v_pk_add_f32 v[176:177], v[172:173], v[176:177] neg_lo:[0,1] neg_hi:[0,1]
	v_pk_add_f32 v[180:181], v[172:173], v[178:179]
	v_mov_b32_e32 v175, v172
	v_mov_b32_e32 v177, v181
	v_pk_add_f32 v[182:183], v[174:175], v[176:177] neg_lo:[0,1] neg_hi:[0,1]
	v_pk_add_f32 v[174:175], v[174:175], v[176:177]
	v_mov_b32_e32 v178, v179
	v_pk_add_f32 v[176:177], v[174:175], v[172:173] op_sel:[1,0] op_sel_hi:[0,1] neg_lo:[0,1] neg_hi:[0,1]
	v_pk_add_f32 v[184:185], v[180:181], v[176:177] op_sel_hi:[1,0] neg_lo:[0,1] neg_hi:[0,1]
	v_mov_b32_e32 v180, v181
	v_mov_b32_e32 v181, v175
	v_pk_mov_b32 v[176:177], v[172:173], v[176:177] op_sel:[1,0]
	v_mov_b32_e32 v179, v172
	v_pk_add_f32 v[176:177], v[180:181], v[176:177] neg_lo:[0,1] neg_hi:[0,1]
	v_mov_b32_e32 v184, v182
	v_pk_add_f32 v[172:173], v[178:179], v[176:177] neg_lo:[0,1] neg_hi:[0,1]
	v_mov_b32_e32 v183, v175
	v_pk_add_f32 v[176:177], v[184:185], v[172:173]
	s_nop 0
	v_pk_add_f32 v[178:179], v[176:177], v[176:177] op_sel:[0,1] op_sel_hi:[1,0]
	s_nop 0
	v_pk_add_f32 v[174:175], v[174:175], v[178:179] op_sel:[1,0] op_sel_hi:[0,1]
	v_mov_b32_e32 v177, v174
	v_pk_add_f32 v[180:181], v[176:177], v[182:183] neg_lo:[0,1] neg_hi:[0,1]
	v_mov_b32_e32 v173, v178
	v_sub_f32_e32 v151, v176, v180
	v_pk_add_f32 v[172:173], v[172:173], v[180:181] neg_lo:[0,1] neg_hi:[0,1]
	v_sub_f32_e32 v151, v182, v151
	v_add_f32_e32 v151, v172, v151
	v_add_f32_e32 v151, v151, v173
	v_add_f32_e32 v151, v174, v151
	v_cndmask_b32_e32 v151, v167, v151, vcc
	v_cmp_ngt_f32_e32 vcc, -1.0, v136
	s_nop 1
	v_cndmask_b32_e32 v151, v168, v151, vcc
	v_cmp_neq_f32_e32 vcc, -1.0, v136
	s_nop 1
	v_cndmask_b32_e32 v151, v169, v151, vcc
	v_cmp_lt_f32_e64 vcc, |v136|, s71
	s_nop 1
	v_cndmask_b32_e32 v136, v151, v136, vcc
;     __device__ __forceinline__ void operator()(const f32x4 (&acc)[2][2][4][2], const Unit& u, int wr, int wc, int fr, int fq) const {
;     ...
;                     for (int m = 0; m < 4; ++m) { const int r = row0 + ai * HALF + m * 16;
;                         const f32x4 v0 = acc[ai][0][m][0], v1 = acc[ai][0][m][1]; float* dp = DT + (size_t)r * 32 + c0;
; #pragma unroll
;                         for (int i = 0; i < 4; ++i) { float x0 = v0[i] + dt_bias[c0 + i], x1 = v1[i] + dt_bias[c0 + 4 + i];
;                             dp[i] = x0 > 20.f ? x0 : log1pf(__expf(x0)); dp[4 + i] = x1 > 20.f ? x1 : log1pf(__expf(x1)); }
.LBB0_803:
	s_or_b64 exec, exec, s[24:25]
	global_store_dword v[154:155], v136, off offset:16
	global_load_dword v136, v[140:141], off offset:4
	s_waitcnt vmcnt(0)
	v_add_f32_e32 v151, v109, v136
	global_load_dword v136, v[140:141], off offset:20
	v_cmp_nlt_f32_e32 vcc, s67, v151
	s_and_saveexec_b64 s[24:25], vcc
	s_cbranch_execz .LBB0_805
	v_mul_f32_e32 v151, 0x3fb8aa3b, v151
	v_exp_f32_e32 v156, v151
	s_nop 0
	v_add_f32_e32 v151, 1.0, v156
	v_frexp_mant_f32_e32 v175, v151
	v_cvt_f64_f32_e32 v[172:173], v151
	v_add_f32_e32 v174, -1.0, v151
	v_frexp_exp_i32_f64_e32 v172, v[172:173]
	v_cmp_gt_f32_e32 vcc, s68, v175
	v_sub_f32_e32 v176, v174, v151
	v_sub_f32_e32 v174, v156, v174
	v_subbrev_co_u32_e32 v180, vcc, 0, v172, vcc
	v_add_f32_e32 v176, 1.0, v176
	v_sub_u32_e32 v172, 0, v180
	v_add_f32_e32 v174, v174, v176
	v_ldexp_f32 v151, v151, v172
	v_ldexp_f32 v172, v174, v172
	v_add_f32_e32 v174, -1.0, v151
	v_add_f32_e32 v173, 1.0, v174
	v_sub_f32_e32 v173, v151, v173
	v_add_f32_e32 v175, v172, v173
	v_add_f32_e32 v173, 1.0, v151
	v_add_f32_e32 v176, -1.0, v173
	v_sub_f32_e32 v151, v151, v176
	v_add_f32_e32 v151, v172, v151
	v_add_f32_e32 v181, v173, v151
	v_rcp_f32_e32 v182, v181
	v_sub_f32_e32 v172, v181, v173
	v_add_f32_e32 v173, v174, v175
	v_sub_f32_e32 v151, v151, v172
	v_mul_f32_e32 v184, v173, v182
	v_sub_f32_e32 v172, v173, v174
	v_mul_f32_e32 v174, v181, v184
	v_fma_f32 v176, v184, v181, -v174
	v_fmac_f32_e32 v176, v184, v151
	v_sub_f32_e32 v183, v175, v172
	v_add_f32_e32 v172, v174, v176
	v_sub_f32_e32 v175, v173, v172
	v_pk_add_f32 v[178:179], v[172:173], v[174:175] neg_lo:[0,1] neg_hi:[0,1]
	v_mov_b32_e32 v177, v172
	v_pk_add_f32 v[172:173], v[178:179], v[176:177] neg_lo:[0,1] neg_hi:[0,1]
	v_cmp_neq_f32_e32 vcc, s70, v156
	v_add_f32_e32 v173, v183, v173
	v_add_f32_e32 v172, v172, v173
	v_add_f32_e32 v173, v175, v172
	v_mul_f32_e32 v183, v182, v173
	v_mul_f32_e32 v174, v181, v183
	v_fma_f32 v176, v183, v181, -v174
	v_fmac_f32_e32 v176, v183, v151
	v_sub_f32_e32 v151, v175, v173
	v_add_f32_e32 v151, v172, v151
	v_add_f32_e32 v172, v174, v176
	v_sub_f32_e32 v175, v173, v172
	v_pk_add_f32 v[178:179], v[172:173], v[174:175] neg_lo:[0,1] neg_hi:[0,1]
	v_mov_b32_e32 v177, v172
	v_pk_add_f32 v[172:173], v[178:179], v[176:177] neg_lo:[0,1] neg_hi:[0,1]
	s_nop 0
	v_add_f32_e32 v151, v151, v173
	v_add_f32_e32 v151, v172, v151
	v_add_f32_e32 v173, v184, v183
	v_add_f32_e32 v151, v175, v151
	v_sub_f32_e32 v172, v173, v184
	v_mul_f32_e32 v151, v182, v151
	v_sub_f32_e32 v172, v183, v172
	v_add_f32_e32 v174, v172, v151
	v_add_f32_e32 v176, v173, v174
	v_cvt_f32_i32_e32 v172, v180
	v_mul_f32_e32 v177, v176, v176
	v_sub_f32_e32 v173, v176, v173
	v_fmamk_f32 v151, v177, 0x3e9b6dac, v166
	v_sub_f32_e32 v173, v174, v173
	v_fmaak_f32 v151, v177, v151, 0x3f2aaada
	v_ldexp_f32 v178, v173, 1
	v_mul_f32_e32 v173, v176, v177
	v_ldexp_f32 v175, v176, 1
	v_pk_mul_f32 v[176:177], v[172:173], v[150:151]
	s_nop 0
	v_fma_f32 v174, v172, s69, -v176
	v_fmac_f32_e32 v174, 0xb102e308, v172
	v_pk_add_f32 v[172:173], v[176:177], v[174:175]
	s_nop 0
	v_sub_f32_e32 v151, v173, v175
	v_sub_f32_e32 v151, v177, v151
	v_add_f32_e32 v179, v178, v151
	v_mov_b32_e32 v178, v176
	v_pk_add_f32 v[176:177], v[172:173], v[176:177] neg_lo:[0,1] neg_hi:[0,1]
	v_pk_add_f32 v[180:181], v[172:173], v[178:179]
	v_mov_b32_e32 v175, v172
	v_mov_b32_e32 v177, v181
	v_pk_add_f32 v[182:183], v[174:175], v[176:177] neg_lo:[0,1] neg_hi:[0,1]
	v_pk_add_f32 v[174:175], v[174:175], v[176:177]
	v_mov_b32_e32 v178, v179
	v_pk_add_f32 v[176:177], v[174:175], v[172:173] op_sel:[1,0] op_sel_hi:[0,1] neg_lo:[0,1] neg_hi:[0,1]
	v_pk_add_f32 v[184:185], v[180:181], v[176:177] op_sel_hi:[1,0] neg_lo:[0,1] neg_hi:[0,1]
	v_mov_b32_e32 v180, v181
	v_mov_b32_e32 v181, v175
	v_pk_mov_b32 v[176:177], v[172:173], v[176:177] op_sel:[1,0]
	v_mov_b32_e32 v179, v172
	v_pk_add_f32 v[176:177], v[180:181], v[176:177] neg_lo:[0,1] neg_hi:[0,1]
	v_mov_b32_e32 v184, v182
	v_pk_add_f32 v[172:173], v[178:179], v[176:177] neg_lo:[0,1] neg_hi:[0,1]
	v_mov_b32_e32 v183, v175
	v_pk_add_f32 v[176:177], v[184:185], v[172:173]
	s_nop 0
	v_pk_add_f32 v[178:179], v[176:177], v[176:177] op_sel:[0,1] op_sel_hi:[1,0]
	s_nop 0
	v_pk_add_f32 v[174:175], v[174:175], v[178:179] op_sel:[1,0] op_sel_hi:[0,1]
	v_mov_b32_e32 v177, v174
	v_pk_add_f32 v[180:181], v[176:177], v[182:183] neg_lo:[0,1] neg_hi:[0,1]
	v_mov_b32_e32 v173, v178
	v_sub_f32_e32 v151, v176, v180
	v_pk_add_f32 v[172:173], v[172:173], v[180:181] neg_lo:[0,1] neg_hi:[0,1]
	v_sub_f32_e32 v151, v182, v151
	v_add_f32_e32 v151, v172, v151
	v_add_f32_e32 v151, v151, v173
	v_add_f32_e32 v151, v174, v151
	v_cndmask_b32_e32 v151, v167, v151, vcc
	v_cmp_ngt_f32_e32 vcc, -1.0, v156
	s_nop 1
	v_cndmask_b32_e32 v151, v168, v151, vcc
	v_cmp_neq_f32_e32 vcc, -1.0, v156
	s_nop 1
	v_cndmask_b32_e32 v151, v169, v151, vcc
	v_cmp_lt_f32_e64 vcc, |v156|, s71
	s_nop 1
	v_cndmask_b32_e32 v151, v151, v156, vcc
;     __device__ __forceinline__ void operator()(const f32x4 (&acc)[2][2][4][2], const Unit& u, int wr, int wc, int fr, int fq) const {
;     ...
;                     for (int m = 0; m < 4; ++m) { const int r = row0 + ai * HALF + m * 16;
;                         const f32x4 v0 = acc[ai][0][m][0], v1 = acc[ai][0][m][1]; float* dp = DT + (size_t)r * 32 + c0;
; #pragma unroll
;                         for (int i = 0; i < 4; ++i) { float x0 = v0[i] + dt_bias[c0 + i], x1 = v1[i] + dt_bias[c0 + 4 + i];
;                             dp[i] = x0 > 20.f ? x0 : log1pf(__expf(x0)); dp[4 + i] = x1 > 20.f ? x1 : log1pf(__expf(x1)); }
.LBB0_805:
	s_or_b64 exec, exec, s[24:25]
	s_waitcnt vmcnt(0)
	v_add_f32_e32 v136, v105, v136
	v_cmp_nlt_f32_e32 vcc, s67, v136
	global_store_dword v[154:155], v151, off offset:4
	s_and_saveexec_b64 s[24:25], vcc
	s_cbranch_execz .LBB0_807
	v_mul_f32_e32 v136, 0x3fb8aa3b, v136
	v_exp_f32_e32 v136, v136
	s_nop 0
	v_add_f32_e32 v151, 1.0, v136
	v_frexp_mant_f32_e32 v174, v151
	v_cvt_f64_f32_e32 v[172:173], v151
	v_add_f32_e32 v156, -1.0, v151
	v_frexp_exp_i32_f64_e32 v172, v[172:173]
	v_cmp_gt_f32_e32 vcc, s68, v174
	v_sub_f32_e32 v175, v156, v151
	v_sub_f32_e32 v156, v136, v156
	v_subbrev_co_u32_e32 v180, vcc, 0, v172, vcc
	v_add_f32_e32 v175, 1.0, v175
	v_sub_u32_e32 v172, 0, v180
	v_add_f32_e32 v156, v156, v175
	v_ldexp_f32 v151, v151, v172
	v_ldexp_f32 v156, v156, v172
	v_add_f32_e32 v172, -1.0, v151
	v_add_f32_e32 v173, 1.0, v172
	v_sub_f32_e32 v173, v151, v173
	v_add_f32_e32 v174, v156, v173
	v_add_f32_e32 v173, 1.0, v151
	v_add_f32_e32 v175, -1.0, v173
	v_sub_f32_e32 v151, v151, v175
	v_add_f32_e32 v151, v156, v151
	v_add_f32_e32 v156, v173, v151
	v_rcp_f32_e32 v181, v156
	v_sub_f32_e32 v173, v156, v173
	v_sub_f32_e32 v151, v151, v173
	v_add_f32_e32 v173, v172, v174
	v_sub_f32_e32 v172, v173, v172
	v_mul_f32_e32 v183, v173, v181
	v_sub_f32_e32 v182, v174, v172
	v_mul_f32_e32 v174, v156, v183
	v_fma_f32 v176, v183, v156, -v174
	v_fmac_f32_e32 v176, v183, v151
	v_add_f32_e32 v172, v174, v176
	v_sub_f32_e32 v175, v173, v172
	v_pk_add_f32 v[178:179], v[172:173], v[174:175] neg_lo:[0,1] neg_hi:[0,1]
	v_mov_b32_e32 v177, v172
	v_pk_add_f32 v[172:173], v[178:179], v[176:177] neg_lo:[0,1] neg_hi:[0,1]
	v_cmp_neq_f32_e32 vcc, s70, v136
	v_add_f32_e32 v173, v182, v173
	v_add_f32_e32 v172, v172, v173
	v_add_f32_e32 v173, v175, v172
	v_mul_f32_e32 v182, v181, v173
	v_mul_f32_e32 v174, v156, v182
	v_fma_f32 v176, v182, v156, -v174
	v_fmac_f32_e32 v176, v182, v151
	v_sub_f32_e32 v151, v175, v173
	v_add_f32_e32 v151, v172, v151
	v_add_f32_e32 v172, v174, v176
	v_sub_f32_e32 v175, v173, v172
	v_pk_add_f32 v[178:179], v[172:173], v[174:175] neg_lo:[0,1] neg_hi:[0,1]
	v_mov_b32_e32 v177, v172
	v_pk_add_f32 v[172:173], v[178:179], v[176:177] neg_lo:[0,1] neg_hi:[0,1]
	v_add_f32_e32 v156, v183, v182
	v_add_f32_e32 v151, v151, v173
	v_add_f32_e32 v151, v172, v151
	v_add_f32_e32 v151, v175, v151
	v_sub_f32_e32 v172, v156, v183
	v_mul_f32_e32 v151, v181, v151
	v_sub_f32_e32 v172, v182, v172
	v_add_f32_e32 v173, v172, v151
	v_add_f32_e32 v174, v156, v173
	v_cvt_f32_i32_e32 v172, v180
	v_mul_f32_e32 v176, v174, v174
	v_fmamk_f32 v151, v176, 0x3e9b6dac, v166
	v_sub_f32_e32 v156, v174, v156
	v_fmaak_f32 v151, v176, v151, 0x3f2aaada
	v_sub_f32_e32 v156, v173, v156
	v_mul_f32_e32 v173, v174, v176
	v_pk_mul_f32 v[176:177], v[172:173], v[150:151]
	v_ldexp_f32 v175, v174, 1
	v_fma_f32 v174, v172, s69, -v176
	v_fmac_f32_e32 v174, 0xb102e308, v172
	v_pk_add_f32 v[172:173], v[176:177], v[174:175]
	v_ldexp_f32 v156, v156, 1
	v_sub_f32_e32 v151, v173, v175
	v_sub_f32_e32 v151, v177, v151
	v_add_f32_e32 v179, v156, v151
	v_mov_b32_e32 v178, v176
	v_pk_add_f32 v[176:177], v[172:173], v[176:177] neg_lo:[0,1] neg_hi:[0,1]
	v_pk_add_f32 v[180:181], v[172:173], v[178:179]
	v_mov_b32_e32 v175, v172
	v_mov_b32_e32 v177, v181
	v_pk_add_f32 v[182:183], v[174:175], v[176:177] neg_lo:[0,1] neg_hi:[0,1]
	v_pk_add_f32 v[174:175], v[174:175], v[176:177]
	v_mov_b32_e32 v178, v179
	v_pk_add_f32 v[176:177], v[174:175], v[172:173] op_sel:[1,0] op_sel_hi:[0,1] neg_lo:[0,1] neg_hi:[0,1]
	v_pk_add_f32 v[184:185], v[180:181], v[176:177] op_sel_hi:[1,0] neg_lo:[0,1] neg_hi:[0,1]
	v_mov_b32_e32 v180, v181
	v_mov_b32_e32 v181, v175
	v_pk_mov_b32 v[176:177], v[172:173], v[176:177] op_sel:[1,0]
	v_mov_b32_e32 v179, v172
	v_pk_add_f32 v[176:177], v[180:181], v[176:177] neg_lo:[0,1] neg_hi:[0,1]
	v_mov_b32_e32 v184, v182
	v_pk_add_f32 v[172:173], v[178:179], v[176:177] neg_lo:[0,1] neg_hi:[0,1]
	v_mov_b32_e32 v183, v175
	v_pk_add_f32 v[176:177], v[184:185], v[172:173]
	s_nop 0
	v_pk_add_f32 v[178:179], v[176:177], v[176:177] op_sel:[0,1] op_sel_hi:[1,0]
	s_nop 0
	v_pk_add_f32 v[174:175], v[174:175], v[178:179] op_sel:[1,0] op_sel_hi:[0,1]
	v_mov_b32_e32 v177, v174
	v_pk_add_f32 v[180:181], v[176:177], v[182:183] neg_lo:[0,1] neg_hi:[0,1]
	v_mov_b32_e32 v173, v178
	v_sub_f32_e32 v151, v176, v180
	v_pk_add_f32 v[172:173], v[172:173], v[180:181] neg_lo:[0,1] neg_hi:[0,1]
	v_sub_f32_e32 v151, v182, v151
	v_add_f32_e32 v151, v172, v151
	v_add_f32_e32 v151, v151, v173
	v_add_f32_e32 v151, v174, v151
	v_cndmask_b32_e32 v151, v167, v151, vcc
	v_cmp_ngt_f32_e32 vcc, -1.0, v136
	s_nop 1
	v_cndmask_b32_e32 v151, v168, v151, vcc
	v_cmp_neq_f32_e32 vcc, -1.0, v136
	s_nop 1
	v_cndmask_b32_e32 v151, v169, v151, vcc
	v_cmp_lt_f32_e64 vcc, |v136|, s71
	s_nop 1
	v_cndmask_b32_e32 v136, v151, v136, vcc
;     __device__ __forceinline__ void operator()(const f32x4 (&acc)[2][2][4][2], const Unit& u, int wr, int wc, int fr, int fq) const {
;     ...
;                     for (int m = 0; m < 4; ++m) { const int r = row0 + ai * HALF + m * 16;
;                         const f32x4 v0 = acc[ai][0][m][0], v1 = acc[ai][0][m][1]; float* dp = DT + (size_t)r * 32 + c0;
; #pragma unroll
;                         for (int i = 0; i < 4; ++i) { float x0 = v0[i] + dt_bias[c0 + i], x1 = v1[i] + dt_bias[c0 + 4 + i];
;                             dp[i] = x0 > 20.f ? x0 : log1pf(__expf(x0)); dp[4 + i] = x1 > 20.f ? x1 : log1pf(__expf(x1)); }
;                         __builtin_amdgcn_sched_barrier(0); }
.LBB0_807:
	s_or_b64 exec, exec, s[24:25]
	global_store_dword v[154:155], v136, off offset:20
	global_load_dword v136, v[140:141], off offset:8
	s_waitcnt vmcnt(0)
	v_add_f32_e32 v151, v110, v136
	global_load_dword v136, v[140:141], off offset:24
	v_cmp_nlt_f32_e32 vcc, s67, v151
	s_and_saveexec_b64 s[24:25], vcc
	s_cbranch_execz .LBB0_809
	v_mul_f32_e32 v151, 0x3fb8aa3b, v151
	v_exp_f32_e32 v156, v151
	s_nop 0
	v_add_f32_e32 v151, 1.0, v156
	v_frexp_mant_f32_e32 v175, v151
	v_cvt_f64_f32_e32 v[172:173], v151
	v_add_f32_e32 v174, -1.0, v151
	v_frexp_exp_i32_f64_e32 v172, v[172:173]
	v_cmp_gt_f32_e32 vcc, s68, v175
	v_sub_f32_e32 v176, v174, v151
	v_sub_f32_e32 v174, v156, v174
	v_subbrev_co_u32_e32 v180, vcc, 0, v172, vcc
	v_add_f32_e32 v176, 1.0, v176
	v_sub_u32_e32 v172, 0, v180
	v_add_f32_e32 v174, v174, v176
	v_ldexp_f32 v151, v151, v172
	v_ldexp_f32 v172, v174, v172
	v_add_f32_e32 v174, -1.0, v151
	v_add_f32_e32 v173, 1.0, v174
	v_sub_f32_e32 v173, v151, v173
	v_add_f32_e32 v175, v172, v173
	v_add_f32_e32 v173, 1.0, v151
	v_add_f32_e32 v176, -1.0, v173
	v_sub_f32_e32 v151, v151, v176
	v_add_f32_e32 v151, v172, v151
	v_add_f32_e32 v181, v173, v151
	v_rcp_f32_e32 v182, v181
	v_sub_f32_e32 v172, v181, v173
	v_add_f32_e32 v173, v174, v175
	v_sub_f32_e32 v151, v151, v172
	v_mul_f32_e32 v184, v173, v182
	v_sub_f32_e32 v172, v173, v174
	v_mul_f32_e32 v174, v181, v184
	v_fma_f32 v176, v184, v181, -v174
	v_fmac_f32_e32 v176, v184, v151
	v_sub_f32_e32 v183, v175, v172
	v_add_f32_e32 v172, v174, v176
	v_sub_f32_e32 v175, v173, v172
	v_pk_add_f32 v[178:179], v[172:173], v[174:175] neg_lo:[0,1] neg_hi:[0,1]
	v_mov_b32_e32 v177, v172
	v_pk_add_f32 v[172:173], v[178:179], v[176:177] neg_lo:[0,1] neg_hi:[0,1]
	v_cmp_neq_f32_e32 vcc, s70, v156
	v_add_f32_e32 v173, v183, v173
	v_add_f32_e32 v172, v172, v173
	v_add_f32_e32 v173, v175, v172
	v_mul_f32_e32 v183, v182, v173
	v_mul_f32_e32 v174, v181, v183
	v_fma_f32 v176, v183, v181, -v174
	v_fmac_f32_e32 v176, v183, v151
	v_sub_f32_e32 v151, v175, v173
	v_add_f32_e32 v151, v172, v151
	v_add_f32_e32 v172, v174, v176
	v_sub_f32_e32 v175, v173, v172
	v_pk_add_f32 v[178:179], v[172:173], v[174:175] neg_lo:[0,1] neg_hi:[0,1]
	v_mov_b32_e32 v177, v172
	v_pk_add_f32 v[172:173], v[178:179], v[176:177] neg_lo:[0,1] neg_hi:[0,1]
	s_nop 0
	v_add_f32_e32 v151, v151, v173
	v_add_f32_e32 v151, v172, v151
	v_add_f32_e32 v173, v184, v183
	v_add_f32_e32 v151, v175, v151
	v_sub_f32_e32 v172, v173, v184
	v_mul_f32_e32 v151, v182, v151
	v_sub_f32_e32 v172, v183, v172
	v_add_f32_e32 v174, v172, v151
	v_add_f32_e32 v176, v173, v174
	v_cvt_f32_i32_e32 v172, v180
	v_mul_f32_e32 v177, v176, v176
	v_sub_f32_e32 v173, v176, v173
	v_fmamk_f32 v151, v177, 0x3e9b6dac, v166
	v_sub_f32_e32 v173, v174, v173
	v_fmaak_f32 v151, v177, v151, 0x3f2aaada
	v_ldexp_f32 v178, v173, 1
	v_mul_f32_e32 v173, v176, v177
	v_ldexp_f32 v175, v176, 1
	v_pk_mul_f32 v[176:177], v[172:173], v[150:151]
	s_nop 0
	v_fma_f32 v174, v172, s69, -v176
	v_fmac_f32_e32 v174, 0xb102e308, v172
	v_pk_add_f32 v[172:173], v[176:177], v[174:175]
	s_nop 0
	v_sub_f32_e32 v151, v173, v175
	v_sub_f32_e32 v151, v177, v151
	v_add_f32_e32 v179, v178, v151
	v_mov_b32_e32 v178, v176
	v_pk_add_f32 v[176:177], v[172:173], v[176:177] neg_lo:[0,1] neg_hi:[0,1]
	v_pk_add_f32 v[180:181], v[172:173], v[178:179]
	v_mov_b32_e32 v175, v172
	v_mov_b32_e32 v177, v181
	v_pk_add_f32 v[182:183], v[174:175], v[176:177] neg_lo:[0,1] neg_hi:[0,1]
	v_pk_add_f32 v[174:175], v[174:175], v[176:177]
	v_mov_b32_e32 v178, v179
	v_pk_add_f32 v[176:177], v[174:175], v[172:173] op_sel:[1,0] op_sel_hi:[0,1] neg_lo:[0,1] neg_hi:[0,1]
	v_pk_add_f32 v[184:185], v[180:181], v[176:177] op_sel_hi:[1,0] neg_lo:[0,1] neg_hi:[0,1]
	v_mov_b32_e32 v180, v181
	v_mov_b32_e32 v181, v175
	v_pk_mov_b32 v[176:177], v[172:173], v[176:177] op_sel:[1,0]
	v_mov_b32_e32 v179, v172
	v_pk_add_f32 v[176:177], v[180:181], v[176:177] neg_lo:[0,1] neg_hi:[0,1]
	v_mov_b32_e32 v184, v182
	v_pk_add_f32 v[172:173], v[178:179], v[176:177] neg_lo:[0,1] neg_hi:[0,1]
	v_mov_b32_e32 v183, v175
	v_pk_add_f32 v[176:177], v[184:185], v[172:173]
	s_nop 0
	v_pk_add_f32 v[178:179], v[176:177], v[176:177] op_sel:[0,1] op_sel_hi:[1,0]
	s_nop 0
	v_pk_add_f32 v[174:175], v[174:175], v[178:179] op_sel:[1,0] op_sel_hi:[0,1]
	v_mov_b32_e32 v177, v174
	v_pk_add_f32 v[180:181], v[176:177], v[182:183] neg_lo:[0,1] neg_hi:[0,1]
	v_mov_b32_e32 v173, v178
	v_sub_f32_e32 v151, v176, v180
	v_pk_add_f32 v[172:173], v[172:173], v[180:181] neg_lo:[0,1] neg_hi:[0,1]
	v_sub_f32_e32 v151, v182, v151
	v_add_f32_e32 v151, v172, v151
	v_add_f32_e32 v151, v151, v173
	v_add_f32_e32 v151, v174, v151
	v_cndmask_b32_e32 v151, v167, v151, vcc
	v_cmp_ngt_f32_e32 vcc, -1.0, v156
	s_nop 1
	v_cndmask_b32_e32 v151, v168, v151, vcc
	v_cmp_neq_f32_e32 vcc, -1.0, v156
	s_nop 1
	v_cndmask_b32_e32 v151, v169, v151, vcc
	v_cmp_lt_f32_e64 vcc, |v156|, s71
	s_nop 1
	v_cndmask_b32_e32 v151, v151, v156, vcc
;     __device__ __forceinline__ void operator()(const f32x4 (&acc)[2][2][4][2], const Unit& u, int wr, int wc, int fr, int fq) const {
;     ...
;                     for (int m = 0; m < 4; ++m) { const int r = row0 + ai * HALF + m * 16;
;                         const f32x4 v0 = acc[ai][0][m][0], v1 = acc[ai][0][m][1]; float* dp = DT + (size_t)r * 32 + c0;
; #pragma unroll
;                         for (int i = 0; i < 4; ++i) { float x0 = v0[i] + dt_bias[c0 + i], x1 = v1[i] + dt_bias[c0 + 4 + i];
;                             dp[i] = x0 > 20.f ? x0 : log1pf(__expf(x0)); dp[4 + i] = x1 > 20.f ? x1 : log1pf(__expf(x1)); }
;                         __builtin_amdgcn_sched_barrier(0); }
.LBB0_809:
	s_or_b64 exec, exec, s[24:25]
	s_waitcnt vmcnt(0)
	v_add_f32_e32 v136, v106, v136
	v_cmp_nlt_f32_e32 vcc, s67, v136
	global_store_dword v[154:155], v151, off offset:8
	s_and_saveexec_b64 s[24:25], vcc
	s_cbranch_execz .LBB0_811
	v_mul_f32_e32 v136, 0x3fb8aa3b, v136
	v_exp_f32_e32 v136, v136
	s_nop 0
	v_add_f32_e32 v151, 1.0, v136
	v_frexp_mant_f32_e32 v174, v151
	v_cvt_f64_f32_e32 v[172:173], v151
	v_add_f32_e32 v156, -1.0, v151
	v_frexp_exp_i32_f64_e32 v172, v[172:173]
	v_cmp_gt_f32_e32 vcc, s68, v174
	v_sub_f32_e32 v175, v156, v151
	v_sub_f32_e32 v156, v136, v156
	v_subbrev_co_u32_e32 v180, vcc, 0, v172, vcc
	v_add_f32_e32 v175, 1.0, v175
	v_sub_u32_e32 v172, 0, v180
	v_add_f32_e32 v156, v156, v175
	v_ldexp_f32 v151, v151, v172
	v_ldexp_f32 v156, v156, v172
	v_add_f32_e32 v172, -1.0, v151
	v_add_f32_e32 v173, 1.0, v172
	v_sub_f32_e32 v173, v151, v173
	v_add_f32_e32 v174, v156, v173
	v_add_f32_e32 v173, 1.0, v151
	v_add_f32_e32 v175, -1.0, v173
	v_sub_f32_e32 v151, v151, v175
	v_add_f32_e32 v151, v156, v151
	v_add_f32_e32 v156, v173, v151
	v_rcp_f32_e32 v181, v156
	v_sub_f32_e32 v173, v156, v173
	v_sub_f32_e32 v151, v151, v173
	v_add_f32_e32 v173, v172, v174
	v_sub_f32_e32 v172, v173, v172
	v_mul_f32_e32 v183, v173, v181
	v_sub_f32_e32 v182, v174, v172
	v_mul_f32_e32 v174, v156, v183
	v_fma_f32 v176, v183, v156, -v174
	v_fmac_f32_e32 v176, v183, v151
	v_add_f32_e32 v172, v174, v176
	v_sub_f32_e32 v175, v173, v172
	v_pk_add_f32 v[178:179], v[172:173], v[174:175] neg_lo:[0,1] neg_hi:[0,1]
	v_mov_b32_e32 v177, v172
	v_pk_add_f32 v[172:173], v[178:179], v[176:177] neg_lo:[0,1] neg_hi:[0,1]
	v_cmp_neq_f32_e32 vcc, s70, v136
	v_add_f32_e32 v173, v182, v173
	v_add_f32_e32 v172, v172, v173
	v_add_f32_e32 v173, v175, v172
	v_mul_f32_e32 v182, v181, v173
	v_mul_f32_e32 v174, v156, v182
	v_fma_f32 v176, v182, v156, -v174
	v_fmac_f32_e32 v176, v182, v151
	v_sub_f32_e32 v151, v175, v173
	v_add_f32_e32 v151, v172, v151
	v_add_f32_e32 v172, v174, v176
	v_sub_f32_e32 v175, v173, v172
	v_pk_add_f32 v[178:179], v[172:173], v[174:175] neg_lo:[0,1] neg_hi:[0,1]
	v_mov_b32_e32 v177, v172
	v_pk_add_f32 v[172:173], v[178:179], v[176:177] neg_lo:[0,1] neg_hi:[0,1]
	v_add_f32_e32 v156, v183, v182
	v_add_f32_e32 v151, v151, v173
	v_add_f32_e32 v151, v172, v151
	v_add_f32_e32 v151, v175, v151
	v_sub_f32_e32 v172, v156, v183
	v_mul_f32_e32 v151, v181, v151
	v_sub_f32_e32 v172, v182, v172
	v_add_f32_e32 v173, v172, v151
	v_add_f32_e32 v174, v156, v173
	v_cvt_f32_i32_e32 v172, v180
	v_mul_f32_e32 v176, v174, v174
	v_fmamk_f32 v151, v176, 0x3e9b6dac, v166
	v_sub_f32_e32 v156, v174, v156
	v_fmaak_f32 v151, v176, v151, 0x3f2aaada
	v_sub_f32_e32 v156, v173, v156
	v_mul_f32_e32 v173, v174, v176
	v_pk_mul_f32 v[176:177], v[172:173], v[150:151]
	v_ldexp_f32 v175, v174, 1
	v_fma_f32 v174, v172, s69, -v176
	v_fmac_f32_e32 v174, 0xb102e308, v172
	v_pk_add_f32 v[172:173], v[176:177], v[174:175]
	v_ldexp_f32 v156, v156, 1
	v_sub_f32_e32 v151, v173, v175
	v_sub_f32_e32 v151, v177, v151
	v_add_f32_e32 v179, v156, v151
	v_mov_b32_e32 v178, v176
	v_pk_add_f32 v[176:177], v[172:173], v[176:177] neg_lo:[0,1] neg_hi:[0,1]
	v_pk_add_f32 v[180:181], v[172:173], v[178:179]
	v_mov_b32_e32 v175, v172
	v_mov_b32_e32 v177, v181
	v_pk_add_f32 v[182:183], v[174:175], v[176:177] neg_lo:[0,1] neg_hi:[0,1]
	v_pk_add_f32 v[174:175], v[174:175], v[176:177]
	v_mov_b32_e32 v178, v179
	v_pk_add_f32 v[176:177], v[174:175], v[172:173] op_sel:[1,0] op_sel_hi:[0,1] neg_lo:[0,1] neg_hi:[0,1]
	v_pk_add_f32 v[184:185], v[180:181], v[176:177] op_sel_hi:[1,0] neg_lo:[0,1] neg_hi:[0,1]
	v_mov_b32_e32 v180, v181
	v_mov_b32_e32 v181, v175
	v_pk_mov_b32 v[176:177], v[172:173], v[176:177] op_sel:[1,0]
	v_mov_b32_e32 v179, v172
	v_pk_add_f32 v[176:177], v[180:181], v[176:177] neg_lo:[0,1] neg_hi:[0,1]
	v_mov_b32_e32 v184, v182
	v_pk_add_f32 v[172:173], v[178:179], v[176:177] neg_lo:[0,1] neg_hi:[0,1]
	v_mov_b32_e32 v183, v175
	v_pk_add_f32 v[176:177], v[184:185], v[172:173]
	s_nop 0
	v_pk_add_f32 v[178:179], v[176:177], v[176:177] op_sel:[0,1] op_sel_hi:[1,0]
	s_nop 0
	v_pk_add_f32 v[174:175], v[174:175], v[178:179] op_sel:[1,0] op_sel_hi:[0,1]
	v_mov_b32_e32 v177, v174
	v_pk_add_f32 v[180:181], v[176:177], v[182:183] neg_lo:[0,1] neg_hi:[0,1]
	v_mov_b32_e32 v173, v178
	v_sub_f32_e32 v151, v176, v180
	v_pk_add_f32 v[172:173], v[172:173], v[180:181] neg_lo:[0,1] neg_hi:[0,1]
	v_sub_f32_e32 v151, v182, v151
	v_add_f32_e32 v151, v172, v151
	v_add_f32_e32 v151, v151, v173
	v_add_f32_e32 v151, v174, v151
	v_cndmask_b32_e32 v151, v167, v151, vcc
	v_cmp_ngt_f32_e32 vcc, -1.0, v136
	s_nop 1
	v_cndmask_b32_e32 v151, v168, v151, vcc
	v_cmp_neq_f32_e32 vcc, -1.0, v136
	s_nop 1
	v_cndmask_b32_e32 v151, v169, v151, vcc
	v_cmp_lt_f32_e64 vcc, |v136|, s71
	s_nop 1
	v_cndmask_b32_e32 v136, v151, v136, vcc
;     __device__ __forceinline__ void operator()(const f32x4 (&acc)[2][2][4][2], const Unit& u, int wr, int wc, int fr, int fq) const {
;     ...
;                     for (int m = 0; m < 4; ++m) { const int r = row0 + ai * HALF + m * 16;
;                         const f32x4 v0 = acc[ai][0][m][0], v1 = acc[ai][0][m][1]; float* dp = DT + (size_t)r * 32 + c0;
; #pragma unroll
;                         for (int i = 0; i < 4; ++i) { float x0 = v0[i] + dt_bias[c0 + i], x1 = v1[i] + dt_bias[c0 + 4 + i];
;                             dp[i] = x0 > 20.f ? x0 : log1pf(__expf(x0)); dp[4 + i] = x1 > 20.f ? x1 : log1pf(__expf(x1)); }
;                         __builtin_amdgcn_sched_barrier(0); }
.LBB0_811:
	s_or_b64 exec, exec, s[24:25]
	global_store_dword v[154:155], v136, off offset:24
	global_load_dword v136, v[140:141], off offset:12
	s_waitcnt vmcnt(0)
	v_add_f32_e32 v151, v111, v136
	global_load_dword v136, v[140:141], off offset:28
	v_cmp_nlt_f32_e32 vcc, s67, v151
	s_and_saveexec_b64 s[24:25], vcc
	s_cbranch_execz .LBB0_813
	v_mul_f32_e32 v151, 0x3fb8aa3b, v151
	v_exp_f32_e32 v156, v151
	s_nop 0
	v_add_f32_e32 v151, 1.0, v156
	v_frexp_mant_f32_e32 v175, v151
	v_cvt_f64_f32_e32 v[172:173], v151
	v_add_f32_e32 v174, -1.0, v151
	v_frexp_exp_i32_f64_e32 v172, v[172:173]
	v_cmp_gt_f32_e32 vcc, s68, v175
	v_sub_f32_e32 v176, v174, v151
	v_sub_f32_e32 v174, v156, v174
	v_subbrev_co_u32_e32 v180, vcc, 0, v172, vcc
	v_add_f32_e32 v176, 1.0, v176
	v_sub_u32_e32 v172, 0, v180
	v_add_f32_e32 v174, v174, v176
	v_ldexp_f32 v151, v151, v172
	v_ldexp_f32 v172, v174, v172
	v_add_f32_e32 v174, -1.0, v151
	v_add_f32_e32 v173, 1.0, v174
	v_sub_f32_e32 v173, v151, v173
	v_add_f32_e32 v175, v172, v173
	v_add_f32_e32 v173, 1.0, v151
	v_add_f32_e32 v176, -1.0, v173
	v_sub_f32_e32 v151, v151, v176
	v_add_f32_e32 v151, v172, v151
	v_add_f32_e32 v181, v173, v151
	v_rcp_f32_e32 v182, v181
	v_sub_f32_e32 v172, v181, v173
	v_add_f32_e32 v173, v174, v175
	v_sub_f32_e32 v151, v151, v172
	v_mul_f32_e32 v184, v173, v182
	v_sub_f32_e32 v172, v173, v174
	v_mul_f32_e32 v174, v181, v184
	v_fma_f32 v176, v184, v181, -v174
	v_fmac_f32_e32 v176, v184, v151
	v_sub_f32_e32 v183, v175, v172
	v_add_f32_e32 v172, v174, v176
	v_sub_f32_e32 v175, v173, v172
	v_pk_add_f32 v[178:179], v[172:173], v[174:175] neg_lo:[0,1] neg_hi:[0,1]
	v_mov_b32_e32 v177, v172
	v_pk_add_f32 v[172:173], v[178:179], v[176:177] neg_lo:[0,1] neg_hi:[0,1]
	v_cmp_neq_f32_e32 vcc, s70, v156
	v_add_f32_e32 v173, v183, v173
	v_add_f32_e32 v172, v172, v173
	v_add_f32_e32 v173, v175, v172
	v_mul_f32_e32 v183, v182, v173
	v_mul_f32_e32 v174, v181, v183
	v_fma_f32 v176, v183, v181, -v174
	v_fmac_f32_e32 v176, v183, v151
	v_sub_f32_e32 v151, v175, v173
	v_add_f32_e32 v151, v172, v151
	v_add_f32_e32 v172, v174, v176
	v_sub_f32_e32 v175, v173, v172
	v_pk_add_f32 v[178:179], v[172:173], v[174:175] neg_lo:[0,1] neg_hi:[0,1]
	v_mov_b32_e32 v177, v172
	v_pk_add_f32 v[172:173], v[178:179], v[176:177] neg_lo:[0,1] neg_hi:[0,1]
	s_nop 0
	v_add_f32_e32 v151, v151, v173
	v_add_f32_e32 v151, v172, v151
	v_add_f32_e32 v173, v184, v183
	v_add_f32_e32 v151, v175, v151
	v_sub_f32_e32 v172, v173, v184
	v_mul_f32_e32 v151, v182, v151
	v_sub_f32_e32 v172, v183, v172
	v_add_f32_e32 v174, v172, v151
	v_add_f32_e32 v176, v173, v174
	v_cvt_f32_i32_e32 v172, v180
	v_mul_f32_e32 v177, v176, v176
	v_sub_f32_e32 v173, v176, v173
	v_fmamk_f32 v151, v177, 0x3e9b6dac, v166
	v_sub_f32_e32 v173, v174, v173
	v_fmaak_f32 v151, v177, v151, 0x3f2aaada
	v_ldexp_f32 v178, v173, 1
	v_mul_f32_e32 v173, v176, v177
	v_ldexp_f32 v175, v176, 1
	v_pk_mul_f32 v[176:177], v[172:173], v[150:151]
	s_nop 0
	v_fma_f32 v174, v172, s69, -v176
	v_fmac_f32_e32 v174, 0xb102e308, v172
	v_pk_add_f32 v[172:173], v[176:177], v[174:175]
	s_nop 0
	v_sub_f32_e32 v151, v173, v175
	v_sub_f32_e32 v151, v177, v151
	v_add_f32_e32 v179, v178, v151
	v_mov_b32_e32 v178, v176
	v_pk_add_f32 v[176:177], v[172:173], v[176:177] neg_lo:[0,1] neg_hi:[0,1]
	v_pk_add_f32 v[180:181], v[172:173], v[178:179]
	v_mov_b32_e32 v175, v172
	v_mov_b32_e32 v177, v181
	v_pk_add_f32 v[182:183], v[174:175], v[176:177] neg_lo:[0,1] neg_hi:[0,1]
	v_pk_add_f32 v[174:175], v[174:175], v[176:177]
	v_mov_b32_e32 v178, v179
	v_pk_add_f32 v[176:177], v[174:175], v[172:173] op_sel:[1,0] op_sel_hi:[0,1] neg_lo:[0,1] neg_hi:[0,1]
	v_pk_add_f32 v[184:185], v[180:181], v[176:177] op_sel_hi:[1,0] neg_lo:[0,1] neg_hi:[0,1]
	v_mov_b32_e32 v180, v181
	v_mov_b32_e32 v181, v175
	v_pk_mov_b32 v[176:177], v[172:173], v[176:177] op_sel:[1,0]
	v_mov_b32_e32 v179, v172
	v_pk_add_f32 v[176:177], v[180:181], v[176:177] neg_lo:[0,1] neg_hi:[0,1]
	v_mov_b32_e32 v184, v182
	v_pk_add_f32 v[172:173], v[178:179], v[176:177] neg_lo:[0,1] neg_hi:[0,1]
	v_mov_b32_e32 v183, v175
	v_pk_add_f32 v[176:177], v[184:185], v[172:173]
	s_nop 0
	v_pk_add_f32 v[178:179], v[176:177], v[176:177] op_sel:[0,1] op_sel_hi:[1,0]
	s_nop 0
	v_pk_add_f32 v[174:175], v[174:175], v[178:179] op_sel:[1,0] op_sel_hi:[0,1]
	v_mov_b32_e32 v177, v174
	v_pk_add_f32 v[180:181], v[176:177], v[182:183] neg_lo:[0,1] neg_hi:[0,1]
	v_mov_b32_e32 v173, v178
	v_sub_f32_e32 v151, v176, v180
	v_pk_add_f32 v[172:173], v[172:173], v[180:181] neg_lo:[0,1] neg_hi:[0,1]
	v_sub_f32_e32 v151, v182, v151
	v_add_f32_e32 v151, v172, v151
	v_add_f32_e32 v151, v151, v173
	v_add_f32_e32 v151, v174, v151
	v_cndmask_b32_e32 v151, v167, v151, vcc
	v_cmp_ngt_f32_e32 vcc, -1.0, v156
	s_nop 1
	v_cndmask_b32_e32 v151, v168, v151, vcc
	v_cmp_neq_f32_e32 vcc, -1.0, v156
	s_nop 1
	v_cndmask_b32_e32 v151, v169, v151, vcc
	v_cmp_lt_f32_e64 vcc, |v156|, s71
	s_nop 1
	v_cndmask_b32_e32 v151, v151, v156, vcc
;     __device__ __forceinline__ void operator()(const f32x4 (&acc)[2][2][4][2], const Unit& u, int wr, int wc, int fr, int fq) const {
;     ...
;                     for (int m = 0; m < 4; ++m) { const int r = row0 + ai * HALF + m * 16;
;                         const f32x4 v0 = acc[ai][0][m][0], v1 = acc[ai][0][m][1]; float* dp = DT + (size_t)r * 32 + c0;
; #pragma unroll
;                         for (int i = 0; i < 4; ++i) { float x0 = v0[i] + dt_bias[c0 + i], x1 = v1[i] + dt_bias[c0 + 4 + i];
;                             dp[i] = x0 > 20.f ? x0 : log1pf(__expf(x0)); dp[4 + i] = x1 > 20.f ? x1 : log1pf(__expf(x1)); }
;                         __builtin_amdgcn_sched_barrier(0); }
.LBB0_813:
	s_or_b64 exec, exec, s[24:25]
	s_waitcnt vmcnt(0)
	v_add_f32_e32 v136, v107, v136
	v_cmp_nlt_f32_e32 vcc, s67, v136
	global_store_dword v[154:155], v151, off offset:12
	s_and_saveexec_b64 s[24:25], vcc
	s_cbranch_execz .LBB0_815
	v_mul_f32_e32 v136, 0x3fb8aa3b, v136
	v_exp_f32_e32 v136, v136
	s_nop 0
	v_add_f32_e32 v151, 1.0, v136
	v_frexp_mant_f32_e32 v174, v151
	v_cvt_f64_f32_e32 v[172:173], v151
	v_add_f32_e32 v156, -1.0, v151
	v_frexp_exp_i32_f64_e32 v172, v[172:173]
	v_cmp_gt_f32_e32 vcc, s68, v174
	v_sub_f32_e32 v175, v156, v151
	v_sub_f32_e32 v156, v136, v156
	v_subbrev_co_u32_e32 v180, vcc, 0, v172, vcc
	v_add_f32_e32 v175, 1.0, v175
	v_sub_u32_e32 v172, 0, v180
	v_add_f32_e32 v156, v156, v175
	v_ldexp_f32 v151, v151, v172
	v_ldexp_f32 v156, v156, v172
	v_add_f32_e32 v172, -1.0, v151
	v_add_f32_e32 v173, 1.0, v172
	v_sub_f32_e32 v173, v151, v173
	v_add_f32_e32 v174, v156, v173
	v_add_f32_e32 v173, 1.0, v151
	v_add_f32_e32 v175, -1.0, v173
	v_sub_f32_e32 v151, v151, v175
	v_add_f32_e32 v151, v156, v151
	v_add_f32_e32 v156, v173, v151
	v_rcp_f32_e32 v181, v156
	v_sub_f32_e32 v173, v156, v173
	v_sub_f32_e32 v151, v151, v173
	v_add_f32_e32 v173, v172, v174
	v_sub_f32_e32 v172, v173, v172
	v_mul_f32_e32 v183, v173, v181
	v_sub_f32_e32 v182, v174, v172
	v_mul_f32_e32 v174, v156, v183
	v_fma_f32 v176, v183, v156, -v174
	v_fmac_f32_e32 v176, v183, v151
	v_add_f32_e32 v172, v174, v176
	v_sub_f32_e32 v175, v173, v172
	v_pk_add_f32 v[178:179], v[172:173], v[174:175] neg_lo:[0,1] neg_hi:[0,1]
	v_mov_b32_e32 v177, v172
	v_pk_add_f32 v[172:173], v[178:179], v[176:177] neg_lo:[0,1] neg_hi:[0,1]
	v_cmp_neq_f32_e32 vcc, s70, v136
	v_add_f32_e32 v173, v182, v173
	v_add_f32_e32 v172, v172, v173
	v_add_f32_e32 v173, v175, v172
	v_mul_f32_e32 v182, v181, v173
	v_mul_f32_e32 v174, v156, v182
	v_fma_f32 v176, v182, v156, -v174
	v_fmac_f32_e32 v176, v182, v151
	v_sub_f32_e32 v151, v175, v173
	v_add_f32_e32 v151, v172, v151
	v_add_f32_e32 v172, v174, v176
	v_sub_f32_e32 v175, v173, v172
	v_pk_add_f32 v[178:179], v[172:173], v[174:175] neg_lo:[0,1] neg_hi:[0,1]
	v_mov_b32_e32 v177, v172
	v_pk_add_f32 v[172:173], v[178:179], v[176:177] neg_lo:[0,1] neg_hi:[0,1]
	v_add_f32_e32 v156, v183, v182
	v_add_f32_e32 v151, v151, v173
	v_add_f32_e32 v151, v172, v151
	v_add_f32_e32 v151, v175, v151
	v_sub_f32_e32 v172, v156, v183
	v_mul_f32_e32 v151, v181, v151
	v_sub_f32_e32 v172, v182, v172
	v_add_f32_e32 v173, v172, v151
	v_add_f32_e32 v174, v156, v173
	v_cvt_f32_i32_e32 v172, v180
	v_mul_f32_e32 v176, v174, v174
	v_fmamk_f32 v151, v176, 0x3e9b6dac, v166
	v_sub_f32_e32 v156, v174, v156
	v_fmaak_f32 v151, v176, v151, 0x3f2aaada
	v_sub_f32_e32 v156, v173, v156
	v_mul_f32_e32 v173, v174, v176
	v_pk_mul_f32 v[176:177], v[172:173], v[150:151]
	v_ldexp_f32 v175, v174, 1
	v_fma_f32 v174, v172, s69, -v176
	v_fmac_f32_e32 v174, 0xb102e308, v172
	v_pk_add_f32 v[172:173], v[176:177], v[174:175]
	v_ldexp_f32 v156, v156, 1
	v_sub_f32_e32 v151, v173, v175
	v_sub_f32_e32 v151, v177, v151
	v_add_f32_e32 v179, v156, v151
	v_mov_b32_e32 v178, v176
	v_pk_add_f32 v[176:177], v[172:173], v[176:177] neg_lo:[0,1] neg_hi:[0,1]
	v_pk_add_f32 v[180:181], v[172:173], v[178:179]
	v_mov_b32_e32 v175, v172
	v_mov_b32_e32 v177, v181
	v_pk_add_f32 v[182:183], v[174:175], v[176:177] neg_lo:[0,1] neg_hi:[0,1]
	v_pk_add_f32 v[174:175], v[174:175], v[176:177]
	v_mov_b32_e32 v178, v179
	v_pk_add_f32 v[176:177], v[174:175], v[172:173] op_sel:[1,0] op_sel_hi:[0,1] neg_lo:[0,1] neg_hi:[0,1]
	v_pk_add_f32 v[184:185], v[180:181], v[176:177] op_sel_hi:[1,0] neg_lo:[0,1] neg_hi:[0,1]
	v_mov_b32_e32 v180, v181
	v_mov_b32_e32 v181, v175
	v_pk_mov_b32 v[176:177], v[172:173], v[176:177] op_sel:[1,0]
	v_mov_b32_e32 v179, v172
	v_pk_add_f32 v[176:177], v[180:181], v[176:177] neg_lo:[0,1] neg_hi:[0,1]
	v_mov_b32_e32 v184, v182
	v_pk_add_f32 v[172:173], v[178:179], v[176:177] neg_lo:[0,1] neg_hi:[0,1]
	v_mov_b32_e32 v183, v175
	v_pk_add_f32 v[176:177], v[184:185], v[172:173]
	s_nop 0
	v_pk_add_f32 v[178:179], v[176:177], v[176:177] op_sel:[0,1] op_sel_hi:[1,0]
	s_nop 0
	v_pk_add_f32 v[174:175], v[174:175], v[178:179] op_sel:[1,0] op_sel_hi:[0,1]
	v_mov_b32_e32 v177, v174
	v_pk_add_f32 v[180:181], v[176:177], v[182:183] neg_lo:[0,1] neg_hi:[0,1]
	v_mov_b32_e32 v173, v178
	v_sub_f32_e32 v151, v176, v180
	v_pk_add_f32 v[172:173], v[172:173], v[180:181] neg_lo:[0,1] neg_hi:[0,1]
	v_sub_f32_e32 v151, v182, v151
	v_add_f32_e32 v151, v172, v151
	v_add_f32_e32 v151, v151, v173
	v_add_f32_e32 v151, v174, v151
	v_cndmask_b32_e32 v151, v167, v151, vcc
	v_cmp_ngt_f32_e32 vcc, -1.0, v136
	s_nop 1
	v_cndmask_b32_e32 v151, v168, v151, vcc
	v_cmp_neq_f32_e32 vcc, -1.0, v136
	s_nop 1
	v_cndmask_b32_e32 v151, v169, v151, vcc
	v_cmp_lt_f32_e64 vcc, |v136|, s71
	s_nop 1
	v_cndmask_b32_e32 v136, v151, v136, vcc
;     __device__ __forceinline__ void operator()(const f32x4 (&acc)[2][2][4][2], const Unit& u, int wr, int wc, int fr, int fq) const {
;     ...
;                     for (int m = 0; m < 4; ++m) { const int r = row0 + ai * HALF + m * 16;
;                         const f32x4 v0 = acc[ai][0][m][0], v1 = acc[ai][0][m][1]; float* dp = DT + (size_t)r * 32 + c0;
; #pragma unroll
;                         for (int i = 0; i < 4; ++i) { float x0 = v0[i] + dt_bias[c0 + i], x1 = v1[i] + dt_bias[c0 + 4 + i];
;                             dp[i] = x0 > 20.f ? x0 : log1pf(__expf(x0)); dp[4 + i] = x1 > 20.f ? x1 : log1pf(__expf(x1)); }
;                         __builtin_amdgcn_sched_barrier(0); }
.LBB0_815:
	s_or_b64 exec, exec, s[24:25]
	global_store_dword v[154:155], v136, off offset:28
	global_load_dword v136, v[140:141], off
	s_waitcnt vmcnt(0)
	v_add_f32_e32 v151, v92, v136
	global_load_dword v136, v[140:141], off offset:16
	v_cmp_nlt_f32_e32 vcc, s67, v151
	s_and_saveexec_b64 s[24:25], vcc
	s_cbranch_execz .LBB0_817
	v_mul_f32_e32 v151, 0x3fb8aa3b, v151
	v_exp_f32_e32 v156, v151
	s_nop 0
	v_add_f32_e32 v151, 1.0, v156
	v_frexp_mant_f32_e32 v173, v151
	v_cvt_f64_f32_e32 v[154:155], v151
	v_add_f32_e32 v172, -1.0, v151
	v_frexp_exp_i32_f64_e32 v154, v[154:155]
	v_cmp_gt_f32_e32 vcc, s68, v173
	v_sub_f32_e32 v174, v172, v151
	v_sub_f32_e32 v172, v156, v172
	v_subbrev_co_u32_e32 v178, vcc, 0, v154, vcc
	v_add_f32_e32 v174, 1.0, v174
	v_sub_u32_e32 v154, 0, v178
	v_add_f32_e32 v172, v172, v174
	v_ldexp_f32 v151, v151, v154
	v_ldexp_f32 v154, v172, v154
	v_add_f32_e32 v172, -1.0, v151
	v_add_f32_e32 v155, 1.0, v172
	v_sub_f32_e32 v155, v151, v155
	v_add_f32_e32 v173, v154, v155
	v_add_f32_e32 v155, 1.0, v151
	v_add_f32_e32 v174, -1.0, v155
	v_sub_f32_e32 v151, v151, v174
	v_add_f32_e32 v151, v154, v151
	v_add_f32_e32 v179, v155, v151
	v_rcp_f32_e32 v180, v179
	v_sub_f32_e32 v154, v179, v155
	v_add_f32_e32 v155, v172, v173
	v_sub_f32_e32 v151, v151, v154
	v_mul_f32_e32 v182, v155, v180
	v_sub_f32_e32 v154, v155, v172
	v_mul_f32_e32 v172, v179, v182
	v_fma_f32 v174, v182, v179, -v172
	v_fmac_f32_e32 v174, v182, v151
	v_sub_f32_e32 v181, v173, v154
	v_add_f32_e32 v154, v172, v174
	v_sub_f32_e32 v173, v155, v154
	v_pk_add_f32 v[176:177], v[154:155], v[172:173] neg_lo:[0,1] neg_hi:[0,1]
	v_mov_b32_e32 v175, v154
	v_pk_add_f32 v[154:155], v[176:177], v[174:175] neg_lo:[0,1] neg_hi:[0,1]
	v_cmp_neq_f32_e32 vcc, s70, v156
	v_add_f32_e32 v155, v181, v155
	v_add_f32_e32 v154, v154, v155
	v_add_f32_e32 v155, v173, v154
	v_mul_f32_e32 v181, v180, v155
	v_mul_f32_e32 v172, v179, v181
	v_fma_f32 v174, v181, v179, -v172
	v_fmac_f32_e32 v174, v181, v151
	v_sub_f32_e32 v151, v173, v155
	v_add_f32_e32 v151, v154, v151
	v_add_f32_e32 v154, v172, v174
	v_sub_f32_e32 v173, v155, v154
	v_pk_add_f32 v[176:177], v[154:155], v[172:173] neg_lo:[0,1] neg_hi:[0,1]
	v_mov_b32_e32 v175, v154
	v_pk_add_f32 v[154:155], v[176:177], v[174:175] neg_lo:[0,1] neg_hi:[0,1]
	s_nop 0
	v_add_f32_e32 v151, v151, v155
	v_add_f32_e32 v151, v154, v151
	v_add_f32_e32 v155, v182, v181
	v_add_f32_e32 v151, v173, v151
	v_sub_f32_e32 v154, v155, v182
	v_mul_f32_e32 v151, v180, v151
	v_sub_f32_e32 v154, v181, v154
	v_add_f32_e32 v172, v154, v151
	v_add_f32_e32 v174, v155, v172
	v_cvt_f32_i32_e32 v154, v178
	v_mul_f32_e32 v175, v174, v174
	v_sub_f32_e32 v155, v174, v155
	v_fmamk_f32 v151, v175, 0x3e9b6dac, v166
	v_sub_f32_e32 v155, v172, v155
	v_fmaak_f32 v151, v175, v151, 0x3f2aaada
	v_ldexp_f32 v176, v155, 1
	v_mul_f32_e32 v155, v174, v175
	v_ldexp_f32 v173, v174, 1
	v_pk_mul_f32 v[174:175], v[154:155], v[150:151]
	s_nop 0
	v_fma_f32 v172, v154, s69, -v174
	v_fmac_f32_e32 v172, 0xb102e308, v154
	v_pk_add_f32 v[154:155], v[174:175], v[172:173]
	s_nop 0
	v_sub_f32_e32 v151, v155, v173
	v_sub_f32_e32 v151, v175, v151
	v_add_f32_e32 v177, v176, v151
	v_mov_b32_e32 v176, v174
	v_pk_add_f32 v[174:175], v[154:155], v[174:175] neg_lo:[0,1] neg_hi:[0,1]
	v_pk_add_f32 v[178:179], v[154:155], v[176:177]
	v_mov_b32_e32 v173, v154
	v_mov_b32_e32 v175, v179
	v_pk_add_f32 v[180:181], v[172:173], v[174:175] neg_lo:[0,1] neg_hi:[0,1]
	v_pk_add_f32 v[172:173], v[172:173], v[174:175]
	v_mov_b32_e32 v176, v177
	v_pk_add_f32 v[174:175], v[172:173], v[154:155] op_sel:[1,0] op_sel_hi:[0,1] neg_lo:[0,1] neg_hi:[0,1]
	v_pk_add_f32 v[182:183], v[178:179], v[174:175] op_sel_hi:[1,0] neg_lo:[0,1] neg_hi:[0,1]
	v_mov_b32_e32 v178, v179
	v_mov_b32_e32 v179, v173
	v_pk_mov_b32 v[174:175], v[154:155], v[174:175] op_sel:[1,0]
	v_mov_b32_e32 v177, v154
	v_pk_add_f32 v[174:175], v[178:179], v[174:175] neg_lo:[0,1] neg_hi:[0,1]
	v_mov_b32_e32 v182, v180
	v_pk_add_f32 v[154:155], v[176:177], v[174:175] neg_lo:[0,1] neg_hi:[0,1]
	v_mov_b32_e32 v181, v173
	v_pk_add_f32 v[174:175], v[182:183], v[154:155]
	s_nop 0
	v_pk_add_f32 v[176:177], v[174:175], v[174:175] op_sel:[0,1] op_sel_hi:[1,0]
	s_nop 0
	v_pk_add_f32 v[172:173], v[172:173], v[176:177] op_sel:[1,0] op_sel_hi:[0,1]
	v_mov_b32_e32 v175, v172
	v_pk_add_f32 v[178:179], v[174:175], v[180:181] neg_lo:[0,1] neg_hi:[0,1]
	v_mov_b32_e32 v155, v176
	v_sub_f32_e32 v151, v174, v178
	v_pk_add_f32 v[154:155], v[154:155], v[178:179] neg_lo:[0,1] neg_hi:[0,1]
	v_sub_f32_e32 v151, v180, v151
	v_add_f32_e32 v151, v154, v151
	v_add_f32_e32 v151, v151, v155
	v_add_f32_e32 v151, v172, v151
	v_cndmask_b32_e32 v151, v167, v151, vcc
	v_cmp_ngt_f32_e32 vcc, -1.0, v156
	s_nop 1
	v_cndmask_b32_e32 v151, v168, v151, vcc
	v_cmp_neq_f32_e32 vcc, -1.0, v156
	s_nop 1
	v_cndmask_b32_e32 v151, v169, v151, vcc
	v_cmp_lt_f32_e64 vcc, |v156|, s71
	s_nop 1
	v_cndmask_b32_e32 v151, v151, v156, vcc
;     __device__ __forceinline__ void operator()(const f32x4 (&acc)[2][2][4][2], const Unit& u, int wr, int wc, int fr, int fq) const {
;     ...
;                     for (int m = 0; m < 4; ++m) { const int r = row0 + ai * HALF + m * 16;
;                         const f32x4 v0 = acc[ai][0][m][0], v1 = acc[ai][0][m][1]; float* dp = DT + (size_t)r * 32 + c0;
; #pragma unroll
;                         for (int i = 0; i < 4; ++i) { float x0 = v0[i] + dt_bias[c0 + i], x1 = v1[i] + dt_bias[c0 + 4 + i];
;                             dp[i] = x0 > 20.f ? x0 : log1pf(__expf(x0)); dp[4 + i] = x1 > 20.f ? x1 : log1pf(__expf(x1)); }
;                         __builtin_amdgcn_sched_barrier(0); }
.LBB0_817:
	s_or_b64 exec, exec, s[24:25]
	v_or_b32_e32 v154, 32, v152
	v_ashrrev_i32_e32 v155, 31, v154
	v_lshlrev_b64 v[154:155], 7, v[154:155]
	s_waitcnt vmcnt(0)
	v_add_f32_e32 v136, v88, v136
	v_lshl_add_u64 v[154:155], v[138:139], 0, v[154:155]
	v_cmp_nlt_f32_e32 vcc, s67, v136
	global_store_dword v[154:155], v151, off
	s_and_saveexec_b64 s[24:25], vcc
	s_cbranch_execz .LBB0_819
	v_mul_f32_e32 v136, 0x3fb8aa3b, v136
	v_exp_f32_e32 v136, v136
	s_nop 0
	v_add_f32_e32 v151, 1.0, v136
	v_frexp_mant_f32_e32 v174, v151
	v_cvt_f64_f32_e32 v[172:173], v151
	v_add_f32_e32 v156, -1.0, v151
	v_frexp_exp_i32_f64_e32 v172, v[172:173]
	v_cmp_gt_f32_e32 vcc, s68, v174
	v_sub_f32_e32 v175, v156, v151
	v_sub_f32_e32 v156, v136, v156
	v_subbrev_co_u32_e32 v180, vcc, 0, v172, vcc
	v_add_f32_e32 v175, 1.0, v175
	v_sub_u32_e32 v172, 0, v180
	v_add_f32_e32 v156, v156, v175
	v_ldexp_f32 v151, v151, v172
	v_ldexp_f32 v156, v156, v172
	v_add_f32_e32 v172, -1.0, v151
	v_add_f32_e32 v173, 1.0, v172
	v_sub_f32_e32 v173, v151, v173
	v_add_f32_e32 v174, v156, v173
	v_add_f32_e32 v173, 1.0, v151
	v_add_f32_e32 v175, -1.0, v173
	v_sub_f32_e32 v151, v151, v175
	v_add_f32_e32 v151, v156, v151
	v_add_f32_e32 v156, v173, v151
	v_rcp_f32_e32 v181, v156
	v_sub_f32_e32 v173, v156, v173
	v_sub_f32_e32 v151, v151, v173
	v_add_f32_e32 v173, v172, v174
	v_sub_f32_e32 v172, v173, v172
	v_mul_f32_e32 v183, v173, v181
	v_sub_f32_e32 v182, v174, v172
	v_mul_f32_e32 v174, v156, v183
	v_fma_f32 v176, v183, v156, -v174
	v_fmac_f32_e32 v176, v183, v151
	v_add_f32_e32 v172, v174, v176
	v_sub_f32_e32 v175, v173, v172
	v_pk_add_f32 v[178:179], v[172:173], v[174:175] neg_lo:[0,1] neg_hi:[0,1]
	v_mov_b32_e32 v177, v172
	v_pk_add_f32 v[172:173], v[178:179], v[176:177] neg_lo:[0,1] neg_hi:[0,1]
	v_cmp_neq_f32_e32 vcc, s70, v136
	v_add_f32_e32 v173, v182, v173
	v_add_f32_e32 v172, v172, v173
	v_add_f32_e32 v173, v175, v172
	v_mul_f32_e32 v182, v181, v173
	v_mul_f32_e32 v174, v156, v182
	v_fma_f32 v176, v182, v156, -v174
	v_fmac_f32_e32 v176, v182, v151
	v_sub_f32_e32 v151, v175, v173
	v_add_f32_e32 v151, v172, v151
	v_add_f32_e32 v172, v174, v176
	v_sub_f32_e32 v175, v173, v172
	v_pk_add_f32 v[178:179], v[172:173], v[174:175] neg_lo:[0,1] neg_hi:[0,1]
	v_mov_b32_e32 v177, v172
	v_pk_add_f32 v[172:173], v[178:179], v[176:177] neg_lo:[0,1] neg_hi:[0,1]
	v_add_f32_e32 v156, v183, v182
	v_add_f32_e32 v151, v151, v173
	v_add_f32_e32 v151, v172, v151
	v_add_f32_e32 v151, v175, v151
	v_sub_f32_e32 v172, v156, v183
	v_mul_f32_e32 v151, v181, v151
	v_sub_f32_e32 v172, v182, v172
	v_add_f32_e32 v173, v172, v151
	v_add_f32_e32 v174, v156, v173
	v_cvt_f32_i32_e32 v172, v180
	v_mul_f32_e32 v176, v174, v174
	v_fmamk_f32 v151, v176, 0x3e9b6dac, v166
	v_sub_f32_e32 v156, v174, v156
	v_fmaak_f32 v151, v176, v151, 0x3f2aaada
	v_sub_f32_e32 v156, v173, v156
	v_mul_f32_e32 v173, v174, v176
	v_pk_mul_f32 v[176:177], v[172:173], v[150:151]
	v_ldexp_f32 v175, v174, 1
	v_fma_f32 v174, v172, s69, -v176
	v_fmac_f32_e32 v174, 0xb102e308, v172
	v_pk_add_f32 v[172:173], v[176:177], v[174:175]
	v_ldexp_f32 v156, v156, 1
	v_sub_f32_e32 v151, v173, v175
	v_sub_f32_e32 v151, v177, v151
	v_add_f32_e32 v179, v156, v151
	v_mov_b32_e32 v178, v176
	v_pk_add_f32 v[176:177], v[172:173], v[176:177] neg_lo:[0,1] neg_hi:[0,1]
	v_pk_add_f32 v[180:181], v[172:173], v[178:179]
	v_mov_b32_e32 v175, v172
	v_mov_b32_e32 v177, v181
	v_pk_add_f32 v[182:183], v[174:175], v[176:177] neg_lo:[0,1] neg_hi:[0,1]
	v_pk_add_f32 v[174:175], v[174:175], v[176:177]
	v_mov_b32_e32 v178, v179
	v_pk_add_f32 v[176:177], v[174:175], v[172:173] op_sel:[1,0] op_sel_hi:[0,1] neg_lo:[0,1] neg_hi:[0,1]
	v_pk_add_f32 v[184:185], v[180:181], v[176:177] op_sel_hi:[1,0] neg_lo:[0,1] neg_hi:[0,1]
	v_mov_b32_e32 v180, v181
	v_mov_b32_e32 v181, v175
	v_pk_mov_b32 v[176:177], v[172:173], v[176:177] op_sel:[1,0]
	v_mov_b32_e32 v179, v172
	v_pk_add_f32 v[176:177], v[180:181], v[176:177] neg_lo:[0,1] neg_hi:[0,1]
	v_mov_b32_e32 v184, v182
	v_pk_add_f32 v[172:173], v[178:179], v[176:177] neg_lo:[0,1] neg_hi:[0,1]
	v_mov_b32_e32 v183, v175
	v_pk_add_f32 v[176:177], v[184:185], v[172:173]
	s_nop 0
	v_pk_add_f32 v[178:179], v[176:177], v[176:177] op_sel:[0,1] op_sel_hi:[1,0]
	s_nop 0
	v_pk_add_f32 v[174:175], v[174:175], v[178:179] op_sel:[1,0] op_sel_hi:[0,1]
	v_mov_b32_e32 v177, v174
	v_pk_add_f32 v[180:181], v[176:177], v[182:183] neg_lo:[0,1] neg_hi:[0,1]
	v_mov_b32_e32 v173, v178
	v_sub_f32_e32 v151, v176, v180
	v_pk_add_f32 v[172:173], v[172:173], v[180:181] neg_lo:[0,1] neg_hi:[0,1]
	v_sub_f32_e32 v151, v182, v151
	v_add_f32_e32 v151, v172, v151
	v_add_f32_e32 v151, v151, v173
	v_add_f32_e32 v151, v174, v151
	v_cndmask_b32_e32 v151, v167, v151, vcc
	v_cmp_ngt_f32_e32 vcc, -1.0, v136
	s_nop 1
	v_cndmask_b32_e32 v151, v168, v151, vcc
	v_cmp_neq_f32_e32 vcc, -1.0, v136
	s_nop 1
	v_cndmask_b32_e32 v151, v169, v151, vcc
	v_cmp_lt_f32_e64 vcc, |v136|, s71
	s_nop 1
	v_cndmask_b32_e32 v136, v151, v136, vcc
;     __device__ __forceinline__ void operator()(const f32x4 (&acc)[2][2][4][2], const Unit& u, int wr, int wc, int fr, int fq) const {
;     ...
;                     for (int m = 0; m < 4; ++m) { const int r = row0 + ai * HALF + m * 16;
;                         const f32x4 v0 = acc[ai][0][m][0], v1 = acc[ai][0][m][1]; float* dp = DT + (size_t)r * 32 + c0;
; #pragma unroll
;                         for (int i = 0; i < 4; ++i) { float x0 = v0[i] + dt_bias[c0 + i], x1 = v1[i] + dt_bias[c0 + 4 + i];
;                             dp[i] = x0 > 20.f ? x0 : log1pf(__expf(x0)); dp[4 + i] = x1 > 20.f ? x1 : log1pf(__expf(x1)); }
;                         __builtin_amdgcn_sched_barrier(0); }
.LBB0_819:
	s_or_b64 exec, exec, s[24:25]
	global_store_dword v[154:155], v136, off offset:16
	global_load_dword v136, v[140:141], off offset:4
	s_waitcnt vmcnt(0)
	v_add_f32_e32 v151, v93, v136
	global_load_dword v136, v[140:141], off offset:20
	v_cmp_nlt_f32_e32 vcc, s67, v151
	s_and_saveexec_b64 s[24:25], vcc
	s_cbranch_execz .LBB0_821
	v_mul_f32_e32 v151, 0x3fb8aa3b, v151
	v_exp_f32_e32 v156, v151
	s_nop 0
	v_add_f32_e32 v151, 1.0, v156
	v_frexp_mant_f32_e32 v175, v151
	v_cvt_f64_f32_e32 v[172:173], v151
	v_add_f32_e32 v174, -1.0, v151
	v_frexp_exp_i32_f64_e32 v172, v[172:173]
	v_cmp_gt_f32_e32 vcc, s68, v175
	v_sub_f32_e32 v176, v174, v151
	v_sub_f32_e32 v174, v156, v174
	v_subbrev_co_u32_e32 v180, vcc, 0, v172, vcc
	v_add_f32_e32 v176, 1.0, v176
	v_sub_u32_e32 v172, 0, v180
	v_add_f32_e32 v174, v174, v176
	v_ldexp_f32 v151, v151, v172
	v_ldexp_f32 v172, v174, v172
	v_add_f32_e32 v174, -1.0, v151
	v_add_f32_e32 v173, 1.0, v174
	v_sub_f32_e32 v173, v151, v173
	v_add_f32_e32 v175, v172, v173
	v_add_f32_e32 v173, 1.0, v151
	v_add_f32_e32 v176, -1.0, v173
	v_sub_f32_e32 v151, v151, v176
	v_add_f32_e32 v151, v172, v151
	v_add_f32_e32 v181, v173, v151
	v_rcp_f32_e32 v182, v181
	v_sub_f32_e32 v172, v181, v173
	v_add_f32_e32 v173, v174, v175
	v_sub_f32_e32 v151, v151, v172
	v_mul_f32_e32 v184, v173, v182
	v_sub_f32_e32 v172, v173, v174
	v_mul_f32_e32 v174, v181, v184
	v_fma_f32 v176, v184, v181, -v174
	v_fmac_f32_e32 v176, v184, v151
	v_sub_f32_e32 v183, v175, v172
	v_add_f32_e32 v172, v174, v176
	v_sub_f32_e32 v175, v173, v172
	v_pk_add_f32 v[178:179], v[172:173], v[174:175] neg_lo:[0,1] neg_hi:[0,1]
	v_mov_b32_e32 v177, v172
	v_pk_add_f32 v[172:173], v[178:179], v[176:177] neg_lo:[0,1] neg_hi:[0,1]
	v_cmp_neq_f32_e32 vcc, s70, v156
	v_add_f32_e32 v173, v183, v173
	v_add_f32_e32 v172, v172, v173
	v_add_f32_e32 v173, v175, v172
	v_mul_f32_e32 v183, v182, v173
	v_mul_f32_e32 v174, v181, v183
	v_fma_f32 v176, v183, v181, -v174
	v_fmac_f32_e32 v176, v183, v151
	v_sub_f32_e32 v151, v175, v173
	v_add_f32_e32 v151, v172, v151
	v_add_f32_e32 v172, v174, v176
	v_sub_f32_e32 v175, v173, v172
	v_pk_add_f32 v[178:179], v[172:173], v[174:175] neg_lo:[0,1] neg_hi:[0,1]
	v_mov_b32_e32 v177, v172
	v_pk_add_f32 v[172:173], v[178:179], v[176:177] neg_lo:[0,1] neg_hi:[0,1]
	s_nop 0
	v_add_f32_e32 v151, v151, v173
	v_add_f32_e32 v151, v172, v151
	v_add_f32_e32 v173, v184, v183
	v_add_f32_e32 v151, v175, v151
	v_sub_f32_e32 v172, v173, v184
	v_mul_f32_e32 v151, v182, v151
	v_sub_f32_e32 v172, v183, v172
	v_add_f32_e32 v174, v172, v151
	v_add_f32_e32 v176, v173, v174
	v_cvt_f32_i32_e32 v172, v180
	v_mul_f32_e32 v177, v176, v176
	v_sub_f32_e32 v173, v176, v173
	v_fmamk_f32 v151, v177, 0x3e9b6dac, v166
	v_sub_f32_e32 v173, v174, v173
	v_fmaak_f32 v151, v177, v151, 0x3f2aaada
	v_ldexp_f32 v178, v173, 1
	v_mul_f32_e32 v173, v176, v177
	v_ldexp_f32 v175, v176, 1
	v_pk_mul_f32 v[176:177], v[172:173], v[150:151]
	s_nop 0
	v_fma_f32 v174, v172, s69, -v176
	v_fmac_f32_e32 v174, 0xb102e308, v172
	v_pk_add_f32 v[172:173], v[176:177], v[174:175]
	s_nop 0
	v_sub_f32_e32 v151, v173, v175
	v_sub_f32_e32 v151, v177, v151
	v_add_f32_e32 v179, v178, v151
	v_mov_b32_e32 v178, v176
	v_pk_add_f32 v[176:177], v[172:173], v[176:177] neg_lo:[0,1] neg_hi:[0,1]
	v_pk_add_f32 v[180:181], v[172:173], v[178:179]
	v_mov_b32_e32 v175, v172
	v_mov_b32_e32 v177, v181
	v_pk_add_f32 v[182:183], v[174:175], v[176:177] neg_lo:[0,1] neg_hi:[0,1]
	v_pk_add_f32 v[174:175], v[174:175], v[176:177]
	v_mov_b32_e32 v178, v179
	v_pk_add_f32 v[176:177], v[174:175], v[172:173] op_sel:[1,0] op_sel_hi:[0,1] neg_lo:[0,1] neg_hi:[0,1]
	v_pk_add_f32 v[184:185], v[180:181], v[176:177] op_sel_hi:[1,0] neg_lo:[0,1] neg_hi:[0,1]
	v_mov_b32_e32 v180, v181
	v_mov_b32_e32 v181, v175
	v_pk_mov_b32 v[176:177], v[172:173], v[176:177] op_sel:[1,0]
	v_mov_b32_e32 v179, v172
	v_pk_add_f32 v[176:177], v[180:181], v[176:177] neg_lo:[0,1] neg_hi:[0,1]
	v_mov_b32_e32 v184, v182
	v_pk_add_f32 v[172:173], v[178:179], v[176:177] neg_lo:[0,1] neg_hi:[0,1]
	v_mov_b32_e32 v183, v175
	v_pk_add_f32 v[176:177], v[184:185], v[172:173]
	s_nop 0
	v_pk_add_f32 v[178:179], v[176:177], v[176:177] op_sel:[0,1] op_sel_hi:[1,0]
	s_nop 0
	v_pk_add_f32 v[174:175], v[174:175], v[178:179] op_sel:[1,0] op_sel_hi:[0,1]
	v_mov_b32_e32 v177, v174
	v_pk_add_f32 v[180:181], v[176:177], v[182:183] neg_lo:[0,1] neg_hi:[0,1]
	v_mov_b32_e32 v173, v178
	v_sub_f32_e32 v151, v176, v180
	v_pk_add_f32 v[172:173], v[172:173], v[180:181] neg_lo:[0,1] neg_hi:[0,1]
	v_sub_f32_e32 v151, v182, v151
	v_add_f32_e32 v151, v172, v151
	v_add_f32_e32 v151, v151, v173
	v_add_f32_e32 v151, v174, v151
	v_cndmask_b32_e32 v151, v167, v151, vcc
	v_cmp_ngt_f32_e32 vcc, -1.0, v156
	s_nop 1
	v_cndmask_b32_e32 v151, v168, v151, vcc
	v_cmp_neq_f32_e32 vcc, -1.0, v156
	s_nop 1
	v_cndmask_b32_e32 v151, v169, v151, vcc
	v_cmp_lt_f32_e64 vcc, |v156|, s71
	s_nop 1
	v_cndmask_b32_e32 v151, v151, v156, vcc
;     __device__ __forceinline__ void operator()(const f32x4 (&acc)[2][2][4][2], const Unit& u, int wr, int wc, int fr, int fq) const {
;     ...
;                     for (int m = 0; m < 4; ++m) { const int r = row0 + ai * HALF + m * 16;
;                         const f32x4 v0 = acc[ai][0][m][0], v1 = acc[ai][0][m][1]; float* dp = DT + (size_t)r * 32 + c0;
; #pragma unroll
;                         for (int i = 0; i < 4; ++i) { float x0 = v0[i] + dt_bias[c0 + i], x1 = v1[i] + dt_bias[c0 + 4 + i];
;                             dp[i] = x0 > 20.f ? x0 : log1pf(__expf(x0)); dp[4 + i] = x1 > 20.f ? x1 : log1pf(__expf(x1)); }
;                         __builtin_amdgcn_sched_barrier(0); }
.LBB0_821:
	s_or_b64 exec, exec, s[24:25]
	s_waitcnt vmcnt(0)
	v_add_f32_e32 v136, v89, v136
	v_cmp_nlt_f32_e32 vcc, s67, v136
	global_store_dword v[154:155], v151, off offset:4
	s_and_saveexec_b64 s[24:25], vcc
	s_cbranch_execz .LBB0_823
	v_mul_f32_e32 v136, 0x3fb8aa3b, v136
	v_exp_f32_e32 v136, v136
	s_nop 0
	v_add_f32_e32 v151, 1.0, v136
	v_frexp_mant_f32_e32 v174, v151
	v_cvt_f64_f32_e32 v[172:173], v151
	v_add_f32_e32 v156, -1.0, v151
	v_frexp_exp_i32_f64_e32 v172, v[172:173]
	v_cmp_gt_f32_e32 vcc, s68, v174
	v_sub_f32_e32 v175, v156, v151
	v_sub_f32_e32 v156, v136, v156
	v_subbrev_co_u32_e32 v180, vcc, 0, v172, vcc
	v_add_f32_e32 v175, 1.0, v175
	v_sub_u32_e32 v172, 0, v180
	v_add_f32_e32 v156, v156, v175
	v_ldexp_f32 v151, v151, v172
	v_ldexp_f32 v156, v156, v172
	v_add_f32_e32 v172, -1.0, v151
	v_add_f32_e32 v173, 1.0, v172
	v_sub_f32_e32 v173, v151, v173
	v_add_f32_e32 v174, v156, v173
	v_add_f32_e32 v173, 1.0, v151
	v_add_f32_e32 v175, -1.0, v173
	v_sub_f32_e32 v151, v151, v175
	v_add_f32_e32 v151, v156, v151
	v_add_f32_e32 v156, v173, v151
	v_rcp_f32_e32 v181, v156
	v_sub_f32_e32 v173, v156, v173
	v_sub_f32_e32 v151, v151, v173
	v_add_f32_e32 v173, v172, v174
	v_sub_f32_e32 v172, v173, v172
	v_mul_f32_e32 v183, v173, v181
	v_sub_f32_e32 v182, v174, v172
	v_mul_f32_e32 v174, v156, v183
	v_fma_f32 v176, v183, v156, -v174
	v_fmac_f32_e32 v176, v183, v151
	v_add_f32_e32 v172, v174, v176
	v_sub_f32_e32 v175, v173, v172
	v_pk_add_f32 v[178:179], v[172:173], v[174:175] neg_lo:[0,1] neg_hi:[0,1]
	v_mov_b32_e32 v177, v172
	v_pk_add_f32 v[172:173], v[178:179], v[176:177] neg_lo:[0,1] neg_hi:[0,1]
	v_cmp_neq_f32_e32 vcc, s70, v136
	v_add_f32_e32 v173, v182, v173
	v_add_f32_e32 v172, v172, v173
	v_add_f32_e32 v173, v175, v172
	v_mul_f32_e32 v182, v181, v173
	v_mul_f32_e32 v174, v156, v182
	v_fma_f32 v176, v182, v156, -v174
	v_fmac_f32_e32 v176, v182, v151
	v_sub_f32_e32 v151, v175, v173
	v_add_f32_e32 v151, v172, v151
	v_add_f32_e32 v172, v174, v176
	v_sub_f32_e32 v175, v173, v172
	v_pk_add_f32 v[178:179], v[172:173], v[174:175] neg_lo:[0,1] neg_hi:[0,1]
	v_mov_b32_e32 v177, v172
	v_pk_add_f32 v[172:173], v[178:179], v[176:177] neg_lo:[0,1] neg_hi:[0,1]
	v_add_f32_e32 v156, v183, v182
	v_add_f32_e32 v151, v151, v173
	v_add_f32_e32 v151, v172, v151
	v_add_f32_e32 v151, v175, v151
	v_sub_f32_e32 v172, v156, v183
	v_mul_f32_e32 v151, v181, v151
	v_sub_f32_e32 v172, v182, v172
	v_add_f32_e32 v173, v172, v151
	v_add_f32_e32 v174, v156, v173
	v_cvt_f32_i32_e32 v172, v180
	v_mul_f32_e32 v176, v174, v174
	v_fmamk_f32 v151, v176, 0x3e9b6dac, v166
	v_sub_f32_e32 v156, v174, v156
	v_fmaak_f32 v151, v176, v151, 0x3f2aaada
	v_sub_f32_e32 v156, v173, v156
	v_mul_f32_e32 v173, v174, v176
	v_pk_mul_f32 v[176:177], v[172:173], v[150:151]
	v_ldexp_f32 v175, v174, 1
	v_fma_f32 v174, v172, s69, -v176
	v_fmac_f32_e32 v174, 0xb102e308, v172
	v_pk_add_f32 v[172:173], v[176:177], v[174:175]
	v_ldexp_f32 v156, v156, 1
	v_sub_f32_e32 v151, v173, v175
	v_sub_f32_e32 v151, v177, v151
	v_add_f32_e32 v179, v156, v151
	v_mov_b32_e32 v178, v176
	v_pk_add_f32 v[176:177], v[172:173], v[176:177] neg_lo:[0,1] neg_hi:[0,1]
	v_pk_add_f32 v[180:181], v[172:173], v[178:179]
	v_mov_b32_e32 v175, v172
	v_mov_b32_e32 v177, v181
	v_pk_add_f32 v[182:183], v[174:175], v[176:177] neg_lo:[0,1] neg_hi:[0,1]
	v_pk_add_f32 v[174:175], v[174:175], v[176:177]
	v_mov_b32_e32 v178, v179
	v_pk_add_f32 v[176:177], v[174:175], v[172:173] op_sel:[1,0] op_sel_hi:[0,1] neg_lo:[0,1] neg_hi:[0,1]
	v_pk_add_f32 v[184:185], v[180:181], v[176:177] op_sel_hi:[1,0] neg_lo:[0,1] neg_hi:[0,1]
	v_mov_b32_e32 v180, v181
	v_mov_b32_e32 v181, v175
	v_pk_mov_b32 v[176:177], v[172:173], v[176:177] op_sel:[1,0]
	v_mov_b32_e32 v179, v172
	v_pk_add_f32 v[176:177], v[180:181], v[176:177] neg_lo:[0,1] neg_hi:[0,1]
	v_mov_b32_e32 v184, v182
	v_pk_add_f32 v[172:173], v[178:179], v[176:177] neg_lo:[0,1] neg_hi:[0,1]
	v_mov_b32_e32 v183, v175
	v_pk_add_f32 v[176:177], v[184:185], v[172:173]
	s_nop 0
	v_pk_add_f32 v[178:179], v[176:177], v[176:177] op_sel:[0,1] op_sel_hi:[1,0]
	s_nop 0
	v_pk_add_f32 v[174:175], v[174:175], v[178:179] op_sel:[1,0] op_sel_hi:[0,1]
	v_mov_b32_e32 v177, v174
	v_pk_add_f32 v[180:181], v[176:177], v[182:183] neg_lo:[0,1] neg_hi:[0,1]
	v_mov_b32_e32 v173, v178
	v_sub_f32_e32 v151, v176, v180
	v_pk_add_f32 v[172:173], v[172:173], v[180:181] neg_lo:[0,1] neg_hi:[0,1]
	v_sub_f32_e32 v151, v182, v151
	v_add_f32_e32 v151, v172, v151
	v_add_f32_e32 v151, v151, v173
	v_add_f32_e32 v151, v174, v151
	v_cndmask_b32_e32 v151, v167, v151, vcc
	v_cmp_ngt_f32_e32 vcc, -1.0, v136
	s_nop 1
	v_cndmask_b32_e32 v151, v168, v151, vcc
	v_cmp_neq_f32_e32 vcc, -1.0, v136
	s_nop 1
	v_cndmask_b32_e32 v151, v169, v151, vcc
	v_cmp_lt_f32_e64 vcc, |v136|, s71
	s_nop 1
	v_cndmask_b32_e32 v136, v151, v136, vcc
;     __device__ __forceinline__ void operator()(const f32x4 (&acc)[2][2][4][2], const Unit& u, int wr, int wc, int fr, int fq) const {
;     ...
;                     for (int m = 0; m < 4; ++m) { const int r = row0 + ai * HALF + m * 16;
;                         const f32x4 v0 = acc[ai][0][m][0], v1 = acc[ai][0][m][1]; float* dp = DT + (size_t)r * 32 + c0;
; #pragma unroll
;                         for (int i = 0; i < 4; ++i) { float x0 = v0[i] + dt_bias[c0 + i], x1 = v1[i] + dt_bias[c0 + 4 + i];
;                             dp[i] = x0 > 20.f ? x0 : log1pf(__expf(x0)); dp[4 + i] = x1 > 20.f ? x1 : log1pf(__expf(x1)); }
;                         __builtin_amdgcn_sched_barrier(0); }
.LBB0_823:
	s_or_b64 exec, exec, s[24:25]
	global_store_dword v[154:155], v136, off offset:20
	global_load_dword v136, v[140:141], off offset:8
	s_waitcnt vmcnt(0)
	v_add_f32_e32 v151, v94, v136
	global_load_dword v136, v[140:141], off offset:24
	v_cmp_nlt_f32_e32 vcc, s67, v151
	s_and_saveexec_b64 s[24:25], vcc
	s_cbranch_execz .LBB0_825
	v_mul_f32_e32 v151, 0x3fb8aa3b, v151
	v_exp_f32_e32 v156, v151
	s_nop 0
	v_add_f32_e32 v151, 1.0, v156
	v_frexp_mant_f32_e32 v175, v151
	v_cvt_f64_f32_e32 v[172:173], v151
	v_add_f32_e32 v174, -1.0, v151
	v_frexp_exp_i32_f64_e32 v172, v[172:173]
	v_cmp_gt_f32_e32 vcc, s68, v175
	v_sub_f32_e32 v176, v174, v151
	v_sub_f32_e32 v174, v156, v174
	v_subbrev_co_u32_e32 v180, vcc, 0, v172, vcc
	v_add_f32_e32 v176, 1.0, v176
	v_sub_u32_e32 v172, 0, v180
	v_add_f32_e32 v174, v174, v176
	v_ldexp_f32 v151, v151, v172
	v_ldexp_f32 v172, v174, v172
	v_add_f32_e32 v174, -1.0, v151
	v_add_f32_e32 v173, 1.0, v174
	v_sub_f32_e32 v173, v151, v173
	v_add_f32_e32 v175, v172, v173
	v_add_f32_e32 v173, 1.0, v151
	v_add_f32_e32 v176, -1.0, v173
	v_sub_f32_e32 v151, v151, v176
	v_add_f32_e32 v151, v172, v151
	v_add_f32_e32 v181, v173, v151
	v_rcp_f32_e32 v182, v181
	v_sub_f32_e32 v172, v181, v173
	v_add_f32_e32 v173, v174, v175
	v_sub_f32_e32 v151, v151, v172
	v_mul_f32_e32 v184, v173, v182
	v_sub_f32_e32 v172, v173, v174
	v_mul_f32_e32 v174, v181, v184
	v_fma_f32 v176, v184, v181, -v174
	v_fmac_f32_e32 v176, v184, v151
	v_sub_f32_e32 v183, v175, v172
	v_add_f32_e32 v172, v174, v176
	v_sub_f32_e32 v175, v173, v172
	v_pk_add_f32 v[178:179], v[172:173], v[174:175] neg_lo:[0,1] neg_hi:[0,1]
	v_mov_b32_e32 v177, v172
	v_pk_add_f32 v[172:173], v[178:179], v[176:177] neg_lo:[0,1] neg_hi:[0,1]
	v_cmp_neq_f32_e32 vcc, s70, v156
	v_add_f32_e32 v173, v183, v173
	v_add_f32_e32 v172, v172, v173
	v_add_f32_e32 v173, v175, v172
	v_mul_f32_e32 v183, v182, v173
	v_mul_f32_e32 v174, v181, v183
	v_fma_f32 v176, v183, v181, -v174
	v_fmac_f32_e32 v176, v183, v151
	v_sub_f32_e32 v151, v175, v173
	v_add_f32_e32 v151, v172, v151
	v_add_f32_e32 v172, v174, v176
	v_sub_f32_e32 v175, v173, v172
	v_pk_add_f32 v[178:179], v[172:173], v[174:175] neg_lo:[0,1] neg_hi:[0,1]
	v_mov_b32_e32 v177, v172
	v_pk_add_f32 v[172:173], v[178:179], v[176:177] neg_lo:[0,1] neg_hi:[0,1]
	s_nop 0
	v_add_f32_e32 v151, v151, v173
	v_add_f32_e32 v151, v172, v151
	v_add_f32_e32 v173, v184, v183
	v_add_f32_e32 v151, v175, v151
	v_sub_f32_e32 v172, v173, v184
	v_mul_f32_e32 v151, v182, v151
	v_sub_f32_e32 v172, v183, v172
	v_add_f32_e32 v174, v172, v151
	v_add_f32_e32 v176, v173, v174
	v_cvt_f32_i32_e32 v172, v180
	v_mul_f32_e32 v177, v176, v176
	v_sub_f32_e32 v173, v176, v173
	v_fmamk_f32 v151, v177, 0x3e9b6dac, v166
	v_sub_f32_e32 v173, v174, v173
	v_fmaak_f32 v151, v177, v151, 0x3f2aaada
	v_ldexp_f32 v178, v173, 1
	v_mul_f32_e32 v173, v176, v177
	v_ldexp_f32 v175, v176, 1
	v_pk_mul_f32 v[176:177], v[172:173], v[150:151]
	s_nop 0
	v_fma_f32 v174, v172, s69, -v176
	v_fmac_f32_e32 v174, 0xb102e308, v172
	v_pk_add_f32 v[172:173], v[176:177], v[174:175]
	s_nop 0
	v_sub_f32_e32 v151, v173, v175
	v_sub_f32_e32 v151, v177, v151
	v_add_f32_e32 v179, v178, v151
	v_mov_b32_e32 v178, v176
	v_pk_add_f32 v[176:177], v[172:173], v[176:177] neg_lo:[0,1] neg_hi:[0,1]
	v_pk_add_f32 v[180:181], v[172:173], v[178:179]
	v_mov_b32_e32 v175, v172
	v_mov_b32_e32 v177, v181
	v_pk_add_f32 v[182:183], v[174:175], v[176:177] neg_lo:[0,1] neg_hi:[0,1]
	v_pk_add_f32 v[174:175], v[174:175], v[176:177]
	v_mov_b32_e32 v178, v179
	v_pk_add_f32 v[176:177], v[174:175], v[172:173] op_sel:[1,0] op_sel_hi:[0,1] neg_lo:[0,1] neg_hi:[0,1]
	v_pk_add_f32 v[184:185], v[180:181], v[176:177] op_sel_hi:[1,0] neg_lo:[0,1] neg_hi:[0,1]
	v_mov_b32_e32 v180, v181
	v_mov_b32_e32 v181, v175
	v_pk_mov_b32 v[176:177], v[172:173], v[176:177] op_sel:[1,0]
	v_mov_b32_e32 v179, v172
	v_pk_add_f32 v[176:177], v[180:181], v[176:177] neg_lo:[0,1] neg_hi:[0,1]
	v_mov_b32_e32 v184, v182
	v_pk_add_f32 v[172:173], v[178:179], v[176:177] neg_lo:[0,1] neg_hi:[0,1]
	v_mov_b32_e32 v183, v175
	v_pk_add_f32 v[176:177], v[184:185], v[172:173]
	s_nop 0
	v_pk_add_f32 v[178:179], v[176:177], v[176:177] op_sel:[0,1] op_sel_hi:[1,0]
	s_nop 0
	v_pk_add_f32 v[174:175], v[174:175], v[178:179] op_sel:[1,0] op_sel_hi:[0,1]
	v_mov_b32_e32 v177, v174
	v_pk_add_f32 v[180:181], v[176:177], v[182:183] neg_lo:[0,1] neg_hi:[0,1]
	v_mov_b32_e32 v173, v178
	v_sub_f32_e32 v151, v176, v180
	v_pk_add_f32 v[172:173], v[172:173], v[180:181] neg_lo:[0,1] neg_hi:[0,1]
	v_sub_f32_e32 v151, v182, v151
	v_add_f32_e32 v151, v172, v151
	v_add_f32_e32 v151, v151, v173
	v_add_f32_e32 v151, v174, v151
	v_cndmask_b32_e32 v151, v167, v151, vcc
	v_cmp_ngt_f32_e32 vcc, -1.0, v156
	s_nop 1
	v_cndmask_b32_e32 v151, v168, v151, vcc
	v_cmp_neq_f32_e32 vcc, -1.0, v156
	s_nop 1
	v_cndmask_b32_e32 v151, v169, v151, vcc
	v_cmp_lt_f32_e64 vcc, |v156|, s71
	s_nop 1
	v_cndmask_b32_e32 v151, v151, v156, vcc
;     __device__ __forceinline__ void operator()(const f32x4 (&acc)[2][2][4][2], const Unit& u, int wr, int wc, int fr, int fq) const {
;     ...
;                     for (int m = 0; m < 4; ++m) { const int r = row0 + ai * HALF + m * 16;
;                         const f32x4 v0 = acc[ai][0][m][0], v1 = acc[ai][0][m][1]; float* dp = DT + (size_t)r * 32 + c0;
; #pragma unroll
;                         for (int i = 0; i < 4; ++i) { float x0 = v0[i] + dt_bias[c0 + i], x1 = v1[i] + dt_bias[c0 + 4 + i];
;                             dp[i] = x0 > 20.f ? x0 : log1pf(__expf(x0)); dp[4 + i] = x1 > 20.f ? x1 : log1pf(__expf(x1)); }
;                         __builtin_amdgcn_sched_barrier(0); }
.LBB0_825:
	s_or_b64 exec, exec, s[24:25]
	s_waitcnt vmcnt(0)
	v_add_f32_e32 v136, v90, v136
	v_cmp_nlt_f32_e32 vcc, s67, v136
	global_store_dword v[154:155], v151, off offset:8
	s_and_saveexec_b64 s[24:25], vcc
	s_cbranch_execz .LBB0_827
	v_mul_f32_e32 v136, 0x3fb8aa3b, v136
	v_exp_f32_e32 v136, v136
	s_nop 0
	v_add_f32_e32 v151, 1.0, v136
	v_frexp_mant_f32_e32 v174, v151
	v_cvt_f64_f32_e32 v[172:173], v151
	v_add_f32_e32 v156, -1.0, v151
	v_frexp_exp_i32_f64_e32 v172, v[172:173]
	v_cmp_gt_f32_e32 vcc, s68, v174
	v_sub_f32_e32 v175, v156, v151
	v_sub_f32_e32 v156, v136, v156
	v_subbrev_co_u32_e32 v180, vcc, 0, v172, vcc
	v_add_f32_e32 v175, 1.0, v175
	v_sub_u32_e32 v172, 0, v180
	v_add_f32_e32 v156, v156, v175
	v_ldexp_f32 v151, v151, v172
	v_ldexp_f32 v156, v156, v172
	v_add_f32_e32 v172, -1.0, v151
	v_add_f32_e32 v173, 1.0, v172
	v_sub_f32_e32 v173, v151, v173
	v_add_f32_e32 v174, v156, v173
	v_add_f32_e32 v173, 1.0, v151
	v_add_f32_e32 v175, -1.0, v173
	v_sub_f32_e32 v151, v151, v175
	v_add_f32_e32 v151, v156, v151
	v_add_f32_e32 v156, v173, v151
	v_rcp_f32_e32 v181, v156
	v_sub_f32_e32 v173, v156, v173
	v_sub_f32_e32 v151, v151, v173
	v_add_f32_e32 v173, v172, v174
	v_sub_f32_e32 v172, v173, v172
	v_mul_f32_e32 v183, v173, v181
	v_sub_f32_e32 v182, v174, v172
	v_mul_f32_e32 v174, v156, v183
	v_fma_f32 v176, v183, v156, -v174
	v_fmac_f32_e32 v176, v183, v151
	v_add_f32_e32 v172, v174, v176
	v_sub_f32_e32 v175, v173, v172
	v_pk_add_f32 v[178:179], v[172:173], v[174:175] neg_lo:[0,1] neg_hi:[0,1]
	v_mov_b32_e32 v177, v172
	v_pk_add_f32 v[172:173], v[178:179], v[176:177] neg_lo:[0,1] neg_hi:[0,1]
	v_cmp_neq_f32_e32 vcc, s70, v136
	v_add_f32_e32 v173, v182, v173
	v_add_f32_e32 v172, v172, v173
	v_add_f32_e32 v173, v175, v172
	v_mul_f32_e32 v182, v181, v173
	v_mul_f32_e32 v174, v156, v182
	v_fma_f32 v176, v182, v156, -v174
	v_fmac_f32_e32 v176, v182, v151
	v_sub_f32_e32 v151, v175, v173
	v_add_f32_e32 v151, v172, v151
	v_add_f32_e32 v172, v174, v176
	v_sub_f32_e32 v175, v173, v172
	v_pk_add_f32 v[178:179], v[172:173], v[174:175] neg_lo:[0,1] neg_hi:[0,1]
	v_mov_b32_e32 v177, v172
	v_pk_add_f32 v[172:173], v[178:179], v[176:177] neg_lo:[0,1] neg_hi:[0,1]
	v_add_f32_e32 v156, v183, v182
	v_add_f32_e32 v151, v151, v173
	v_add_f32_e32 v151, v172, v151
	v_add_f32_e32 v151, v175, v151
	v_sub_f32_e32 v172, v156, v183
	v_mul_f32_e32 v151, v181, v151
	v_sub_f32_e32 v172, v182, v172
	v_add_f32_e32 v173, v172, v151
	v_add_f32_e32 v174, v156, v173
	v_cvt_f32_i32_e32 v172, v180
	v_mul_f32_e32 v176, v174, v174
	v_fmamk_f32 v151, v176, 0x3e9b6dac, v166
	v_sub_f32_e32 v156, v174, v156
	v_fmaak_f32 v151, v176, v151, 0x3f2aaada
	v_sub_f32_e32 v156, v173, v156
	v_mul_f32_e32 v173, v174, v176
	v_pk_mul_f32 v[176:177], v[172:173], v[150:151]
	v_ldexp_f32 v175, v174, 1
	v_fma_f32 v174, v172, s69, -v176
	v_fmac_f32_e32 v174, 0xb102e308, v172
	v_pk_add_f32 v[172:173], v[176:177], v[174:175]
	v_ldexp_f32 v156, v156, 1
	v_sub_f32_e32 v151, v173, v175
	v_sub_f32_e32 v151, v177, v151
	v_add_f32_e32 v179, v156, v151
	v_mov_b32_e32 v178, v176
	v_pk_add_f32 v[176:177], v[172:173], v[176:177] neg_lo:[0,1] neg_hi:[0,1]
	v_pk_add_f32 v[180:181], v[172:173], v[178:179]
	v_mov_b32_e32 v175, v172
	v_mov_b32_e32 v177, v181
	v_pk_add_f32 v[182:183], v[174:175], v[176:177] neg_lo:[0,1] neg_hi:[0,1]
	v_pk_add_f32 v[174:175], v[174:175], v[176:177]
	v_mov_b32_e32 v178, v179
	v_pk_add_f32 v[176:177], v[174:175], v[172:173] op_sel:[1,0] op_sel_hi:[0,1] neg_lo:[0,1] neg_hi:[0,1]
	v_pk_add_f32 v[184:185], v[180:181], v[176:177] op_sel_hi:[1,0] neg_lo:[0,1] neg_hi:[0,1]
	v_mov_b32_e32 v180, v181
	v_mov_b32_e32 v181, v175
	v_pk_mov_b32 v[176:177], v[172:173], v[176:177] op_sel:[1,0]
	v_mov_b32_e32 v179, v172
	v_pk_add_f32 v[176:177], v[180:181], v[176:177] neg_lo:[0,1] neg_hi:[0,1]
	v_mov_b32_e32 v184, v182
	v_pk_add_f32 v[172:173], v[178:179], v[176:177] neg_lo:[0,1] neg_hi:[0,1]
	v_mov_b32_e32 v183, v175
	v_pk_add_f32 v[176:177], v[184:185], v[172:173]
	s_nop 0
	v_pk_add_f32 v[178:179], v[176:177], v[176:177] op_sel:[0,1] op_sel_hi:[1,0]
	s_nop 0
	v_pk_add_f32 v[174:175], v[174:175], v[178:179] op_sel:[1,0] op_sel_hi:[0,1]
	v_mov_b32_e32 v177, v174
	v_pk_add_f32 v[180:181], v[176:177], v[182:183] neg_lo:[0,1] neg_hi:[0,1]
	v_mov_b32_e32 v173, v178
	v_sub_f32_e32 v151, v176, v180
	v_pk_add_f32 v[172:173], v[172:173], v[180:181] neg_lo:[0,1] neg_hi:[0,1]
	v_sub_f32_e32 v151, v182, v151
	v_add_f32_e32 v151, v172, v151
	v_add_f32_e32 v151, v151, v173
	v_add_f32_e32 v151, v174, v151
	v_cndmask_b32_e32 v151, v167, v151, vcc
	v_cmp_ngt_f32_e32 vcc, -1.0, v136
	s_nop 1
	v_cndmask_b32_e32 v151, v168, v151, vcc
	v_cmp_neq_f32_e32 vcc, -1.0, v136
	s_nop 1
	v_cndmask_b32_e32 v151, v169, v151, vcc
	v_cmp_lt_f32_e64 vcc, |v136|, s71
	s_nop 1
	v_cndmask_b32_e32 v136, v151, v136, vcc
;     __device__ __forceinline__ void operator()(const f32x4 (&acc)[2][2][4][2], const Unit& u, int wr, int wc, int fr, int fq) const {
;     ...
;                     for (int m = 0; m < 4; ++m) { const int r = row0 + ai * HALF + m * 16;
;                         const f32x4 v0 = acc[ai][0][m][0], v1 = acc[ai][0][m][1]; float* dp = DT + (size_t)r * 32 + c0;
; #pragma unroll
;                         for (int i = 0; i < 4; ++i) { float x0 = v0[i] + dt_bias[c0 + i], x1 = v1[i] + dt_bias[c0 + 4 + i];
;                             dp[i] = x0 > 20.f ? x0 : log1pf(__expf(x0)); dp[4 + i] = x1 > 20.f ? x1 : log1pf(__expf(x1)); }
;                         __builtin_amdgcn_sched_barrier(0); }
.LBB0_827:
	s_or_b64 exec, exec, s[24:25]
	global_store_dword v[154:155], v136, off offset:24
	global_load_dword v136, v[140:141], off offset:12
	s_waitcnt vmcnt(0)
	v_add_f32_e32 v151, v95, v136
	global_load_dword v136, v[140:141], off offset:28
	v_cmp_nlt_f32_e32 vcc, s67, v151
	s_and_saveexec_b64 s[24:25], vcc
	s_cbranch_execz .LBB0_829
	v_mul_f32_e32 v151, 0x3fb8aa3b, v151
	v_exp_f32_e32 v156, v151
	s_nop 0
	v_add_f32_e32 v151, 1.0, v156
	v_frexp_mant_f32_e32 v175, v151
	v_cvt_f64_f32_e32 v[172:173], v151
	v_add_f32_e32 v174, -1.0, v151
	v_frexp_exp_i32_f64_e32 v172, v[172:173]
	v_cmp_gt_f32_e32 vcc, s68, v175
	v_sub_f32_e32 v176, v174, v151
	v_sub_f32_e32 v174, v156, v174
	v_subbrev_co_u32_e32 v180, vcc, 0, v172, vcc
	v_add_f32_e32 v176, 1.0, v176
	v_sub_u32_e32 v172, 0, v180
	v_add_f32_e32 v174, v174, v176
	v_ldexp_f32 v151, v151, v172
	v_ldexp_f32 v172, v174, v172
	v_add_f32_e32 v174, -1.0, v151
	v_add_f32_e32 v173, 1.0, v174
	v_sub_f32_e32 v173, v151, v173
	v_add_f32_e32 v175, v172, v173
	v_add_f32_e32 v173, 1.0, v151
	v_add_f32_e32 v176, -1.0, v173
	v_sub_f32_e32 v151, v151, v176
	v_add_f32_e32 v151, v172, v151
	v_add_f32_e32 v181, v173, v151
	v_rcp_f32_e32 v182, v181
	v_sub_f32_e32 v172, v181, v173
	v_add_f32_e32 v173, v174, v175
	v_sub_f32_e32 v151, v151, v172
	v_mul_f32_e32 v184, v173, v182
	v_sub_f32_e32 v172, v173, v174
	v_mul_f32_e32 v174, v181, v184
	v_fma_f32 v176, v184, v181, -v174
	v_fmac_f32_e32 v176, v184, v151
	v_sub_f32_e32 v183, v175, v172
	v_add_f32_e32 v172, v174, v176
	v_sub_f32_e32 v175, v173, v172
	v_pk_add_f32 v[178:179], v[172:173], v[174:175] neg_lo:[0,1] neg_hi:[0,1]
	v_mov_b32_e32 v177, v172
	v_pk_add_f32 v[172:173], v[178:179], v[176:177] neg_lo:[0,1] neg_hi:[0,1]
	v_cmp_neq_f32_e32 vcc, s70, v156
	v_add_f32_e32 v173, v183, v173
	v_add_f32_e32 v172, v172, v173
	v_add_f32_e32 v173, v175, v172
	v_mul_f32_e32 v183, v182, v173
	v_mul_f32_e32 v174, v181, v183
	v_fma_f32 v176, v183, v181, -v174
	v_fmac_f32_e32 v176, v183, v151
	v_sub_f32_e32 v151, v175, v173
	v_add_f32_e32 v151, v172, v151
	v_add_f32_e32 v172, v174, v176
	v_sub_f32_e32 v175, v173, v172
	v_pk_add_f32 v[178:179], v[172:173], v[174:175] neg_lo:[0,1] neg_hi:[0,1]
	v_mov_b32_e32 v177, v172
	v_pk_add_f32 v[172:173], v[178:179], v[176:177] neg_lo:[0,1] neg_hi:[0,1]
	s_nop 0
	v_add_f32_e32 v151, v151, v173
	v_add_f32_e32 v151, v172, v151
	v_add_f32_e32 v173, v184, v183
	v_add_f32_e32 v151, v175, v151
	v_sub_f32_e32 v172, v173, v184
	v_mul_f32_e32 v151, v182, v151
	v_sub_f32_e32 v172, v183, v172
	v_add_f32_e32 v174, v172, v151
	v_add_f32_e32 v176, v173, v174
	v_cvt_f32_i32_e32 v172, v180
	v_mul_f32_e32 v177, v176, v176
	v_sub_f32_e32 v173, v176, v173
	v_fmamk_f32 v151, v177, 0x3e9b6dac, v166
	v_sub_f32_e32 v173, v174, v173
	v_fmaak_f32 v151, v177, v151, 0x3f2aaada
	v_ldexp_f32 v178, v173, 1
	v_mul_f32_e32 v173, v176, v177
	v_ldexp_f32 v175, v176, 1
	v_pk_mul_f32 v[176:177], v[172:173], v[150:151]
	s_nop 0
	v_fma_f32 v174, v172, s69, -v176
	v_fmac_f32_e32 v174, 0xb102e308, v172
	v_pk_add_f32 v[172:173], v[176:177], v[174:175]
	s_nop 0
	v_sub_f32_e32 v151, v173, v175
	v_sub_f32_e32 v151, v177, v151
	v_add_f32_e32 v179, v178, v151
	v_mov_b32_e32 v178, v176
	v_pk_add_f32 v[176:177], v[172:173], v[176:177] neg_lo:[0,1] neg_hi:[0,1]
	v_pk_add_f32 v[180:181], v[172:173], v[178:179]
	v_mov_b32_e32 v175, v172
	v_mov_b32_e32 v177, v181
	v_pk_add_f32 v[182:183], v[174:175], v[176:177] neg_lo:[0,1] neg_hi:[0,1]
	v_pk_add_f32 v[174:175], v[174:175], v[176:177]
	v_mov_b32_e32 v178, v179
	v_pk_add_f32 v[176:177], v[174:175], v[172:173] op_sel:[1,0] op_sel_hi:[0,1] neg_lo:[0,1] neg_hi:[0,1]
	v_pk_add_f32 v[184:185], v[180:181], v[176:177] op_sel_hi:[1,0] neg_lo:[0,1] neg_hi:[0,1]
	v_mov_b32_e32 v180, v181
	v_mov_b32_e32 v181, v175
	v_pk_mov_b32 v[176:177], v[172:173], v[176:177] op_sel:[1,0]
	v_mov_b32_e32 v179, v172
	v_pk_add_f32 v[176:177], v[180:181], v[176:177] neg_lo:[0,1] neg_hi:[0,1]
	v_mov_b32_e32 v184, v182
	v_pk_add_f32 v[172:173], v[178:179], v[176:177] neg_lo:[0,1] neg_hi:[0,1]
	v_mov_b32_e32 v183, v175
	v_pk_add_f32 v[176:177], v[184:185], v[172:173]
	s_nop 0
	v_pk_add_f32 v[178:179], v[176:177], v[176:177] op_sel:[0,1] op_sel_hi:[1,0]
	s_nop 0
	v_pk_add_f32 v[174:175], v[174:175], v[178:179] op_sel:[1,0] op_sel_hi:[0,1]
	v_mov_b32_e32 v177, v174
	v_pk_add_f32 v[180:181], v[176:177], v[182:183] neg_lo:[0,1] neg_hi:[0,1]
	v_mov_b32_e32 v173, v178
	v_sub_f32_e32 v151, v176, v180
	v_pk_add_f32 v[172:173], v[172:173], v[180:181] neg_lo:[0,1] neg_hi:[0,1]
	v_sub_f32_e32 v151, v182, v151
	v_add_f32_e32 v151, v172, v151
	v_add_f32_e32 v151, v151, v173
	v_add_f32_e32 v151, v174, v151
	v_cndmask_b32_e32 v151, v167, v151, vcc
	v_cmp_ngt_f32_e32 vcc, -1.0, v156
	s_nop 1
	v_cndmask_b32_e32 v151, v168, v151, vcc
	v_cmp_neq_f32_e32 vcc, -1.0, v156
	s_nop 1
	v_cndmask_b32_e32 v151, v169, v151, vcc
	v_cmp_lt_f32_e64 vcc, |v156|, s71
	s_nop 1
	v_cndmask_b32_e32 v151, v151, v156, vcc
;     __device__ __forceinline__ void operator()(const f32x4 (&acc)[2][2][4][2], const Unit& u, int wr, int wc, int fr, int fq) const {
;     ...
;                     for (int m = 0; m < 4; ++m) { const int r = row0 + ai * HALF + m * 16;
;                         const f32x4 v0 = acc[ai][0][m][0], v1 = acc[ai][0][m][1]; float* dp = DT + (size_t)r * 32 + c0;
; #pragma unroll
;                         for (int i = 0; i < 4; ++i) { float x0 = v0[i] + dt_bias[c0 + i], x1 = v1[i] + dt_bias[c0 + 4 + i];
;                             dp[i] = x0 > 20.f ? x0 : log1pf(__expf(x0)); dp[4 + i] = x1 > 20.f ? x1 : log1pf(__expf(x1)); }
;                         __builtin_amdgcn_sched_barrier(0); }
.LBB0_829:
	s_or_b64 exec, exec, s[24:25]
	s_waitcnt vmcnt(0)
	v_add_f32_e32 v136, v91, v136
	v_cmp_nlt_f32_e32 vcc, s67, v136
	global_store_dword v[154:155], v151, off offset:12
	s_and_saveexec_b64 s[24:25], vcc
	s_cbranch_execz .LBB0_831
	v_mul_f32_e32 v136, 0x3fb8aa3b, v136
	v_exp_f32_e32 v136, v136
	s_nop 0
	v_add_f32_e32 v151, 1.0, v136
	v_frexp_mant_f32_e32 v174, v151
	v_cvt_f64_f32_e32 v[172:173], v151
	v_add_f32_e32 v156, -1.0, v151
	v_frexp_exp_i32_f64_e32 v172, v[172:173]
	v_cmp_gt_f32_e32 vcc, s68, v174
	v_sub_f32_e32 v175, v156, v151
	v_sub_f32_e32 v156, v136, v156
	v_subbrev_co_u32_e32 v180, vcc, 0, v172, vcc
	v_add_f32_e32 v175, 1.0, v175
	v_sub_u32_e32 v172, 0, v180
	v_add_f32_e32 v156, v156, v175
	v_ldexp_f32 v151, v151, v172
	v_ldexp_f32 v156, v156, v172
	v_add_f32_e32 v172, -1.0, v151
	v_add_f32_e32 v173, 1.0, v172
	v_sub_f32_e32 v173, v151, v173
	v_add_f32_e32 v174, v156, v173
	v_add_f32_e32 v173, 1.0, v151
	v_add_f32_e32 v175, -1.0, v173
	v_sub_f32_e32 v151, v151, v175
	v_add_f32_e32 v151, v156, v151
	v_add_f32_e32 v156, v173, v151
	v_rcp_f32_e32 v181, v156
	v_sub_f32_e32 v173, v156, v173
	v_sub_f32_e32 v151, v151, v173
	v_add_f32_e32 v173, v172, v174
	v_sub_f32_e32 v172, v173, v172
	v_mul_f32_e32 v183, v173, v181
	v_sub_f32_e32 v182, v174, v172
	v_mul_f32_e32 v174, v156, v183
	v_fma_f32 v176, v183, v156, -v174
	v_fmac_f32_e32 v176, v183, v151
	v_add_f32_e32 v172, v174, v176
	v_sub_f32_e32 v175, v173, v172
	v_pk_add_f32 v[178:179], v[172:173], v[174:175] neg_lo:[0,1] neg_hi:[0,1]
	v_mov_b32_e32 v177, v172
	v_pk_add_f32 v[172:173], v[178:179], v[176:177] neg_lo:[0,1] neg_hi:[0,1]
	v_cmp_neq_f32_e32 vcc, s70, v136
	v_add_f32_e32 v173, v182, v173
	v_add_f32_e32 v172, v172, v173
	v_add_f32_e32 v173, v175, v172
	v_mul_f32_e32 v182, v181, v173
	v_mul_f32_e32 v174, v156, v182
	v_fma_f32 v176, v182, v156, -v174
	v_fmac_f32_e32 v176, v182, v151
	v_sub_f32_e32 v151, v175, v173
	v_add_f32_e32 v151, v172, v151
	v_add_f32_e32 v172, v174, v176
	v_sub_f32_e32 v175, v173, v172
	v_pk_add_f32 v[178:179], v[172:173], v[174:175] neg_lo:[0,1] neg_hi:[0,1]
	v_mov_b32_e32 v177, v172
	v_pk_add_f32 v[172:173], v[178:179], v[176:177] neg_lo:[0,1] neg_hi:[0,1]
	v_add_f32_e32 v156, v183, v182
	v_add_f32_e32 v151, v151, v173
	v_add_f32_e32 v151, v172, v151
	v_add_f32_e32 v151, v175, v151
	v_sub_f32_e32 v172, v156, v183
	v_mul_f32_e32 v151, v181, v151
	v_sub_f32_e32 v172, v182, v172
	v_add_f32_e32 v173, v172, v151
	v_add_f32_e32 v174, v156, v173
	v_cvt_f32_i32_e32 v172, v180
	v_mul_f32_e32 v176, v174, v174
	v_fmamk_f32 v151, v176, 0x3e9b6dac, v166
	v_sub_f32_e32 v156, v174, v156
	v_fmaak_f32 v151, v176, v151, 0x3f2aaada
	v_sub_f32_e32 v156, v173, v156
	v_mul_f32_e32 v173, v174, v176
	v_pk_mul_f32 v[176:177], v[172:173], v[150:151]
	v_ldexp_f32 v175, v174, 1
	v_fma_f32 v174, v172, s69, -v176
	v_fmac_f32_e32 v174, 0xb102e308, v172
	v_pk_add_f32 v[172:173], v[176:177], v[174:175]
	v_ldexp_f32 v156, v156, 1
	v_sub_f32_e32 v151, v173, v175
	v_sub_f32_e32 v151, v177, v151
	v_add_f32_e32 v179, v156, v151
	v_mov_b32_e32 v178, v176
	v_pk_add_f32 v[176:177], v[172:173], v[176:177] neg_lo:[0,1] neg_hi:[0,1]
	v_pk_add_f32 v[180:181], v[172:173], v[178:179]
	v_mov_b32_e32 v175, v172
	v_mov_b32_e32 v177, v181
	v_pk_add_f32 v[182:183], v[174:175], v[176:177] neg_lo:[0,1] neg_hi:[0,1]
	v_pk_add_f32 v[174:175], v[174:175], v[176:177]
	v_mov_b32_e32 v178, v179
	v_pk_add_f32 v[176:177], v[174:175], v[172:173] op_sel:[1,0] op_sel_hi:[0,1] neg_lo:[0,1] neg_hi:[0,1]
	v_pk_add_f32 v[184:185], v[180:181], v[176:177] op_sel_hi:[1,0] neg_lo:[0,1] neg_hi:[0,1]
	v_mov_b32_e32 v180, v181
	v_mov_b32_e32 v181, v175
	v_pk_mov_b32 v[176:177], v[172:173], v[176:177] op_sel:[1,0]
	v_mov_b32_e32 v179, v172
	v_pk_add_f32 v[176:177], v[180:181], v[176:177] neg_lo:[0,1] neg_hi:[0,1]
	v_mov_b32_e32 v184, v182
	v_pk_add_f32 v[172:173], v[178:179], v[176:177] neg_lo:[0,1] neg_hi:[0,1]
	v_mov_b32_e32 v183, v175
	v_pk_add_f32 v[176:177], v[184:185], v[172:173]
	s_nop 0
	v_pk_add_f32 v[178:179], v[176:177], v[176:177] op_sel:[0,1] op_sel_hi:[1,0]
	s_nop 0
	v_pk_add_f32 v[174:175], v[174:175], v[178:179] op_sel:[1,0] op_sel_hi:[0,1]
	v_mov_b32_e32 v177, v174
	v_pk_add_f32 v[180:181], v[176:177], v[182:183] neg_lo:[0,1] neg_hi:[0,1]
	v_mov_b32_e32 v173, v178
	v_sub_f32_e32 v151, v176, v180
	v_pk_add_f32 v[172:173], v[172:173], v[180:181] neg_lo:[0,1] neg_hi:[0,1]
	v_sub_f32_e32 v151, v182, v151
	v_add_f32_e32 v151, v172, v151
	v_add_f32_e32 v151, v151, v173
	v_add_f32_e32 v151, v174, v151
	v_cndmask_b32_e32 v151, v167, v151, vcc
	v_cmp_ngt_f32_e32 vcc, -1.0, v136
	s_nop 1
	v_cndmask_b32_e32 v151, v168, v151, vcc
	v_cmp_neq_f32_e32 vcc, -1.0, v136
	s_nop 1
	v_cndmask_b32_e32 v151, v169, v151, vcc
	v_cmp_lt_f32_e64 vcc, |v136|, s71
	s_nop 1
	v_cndmask_b32_e32 v136, v151, v136, vcc
;     __device__ __forceinline__ void operator()(const f32x4 (&acc)[2][2][4][2], const Unit& u, int wr, int wc, int fr, int fq) const {
;     ...
;                     for (int m = 0; m < 4; ++m) { const int r = row0 + ai * HALF + m * 16;
;                         const f32x4 v0 = acc[ai][0][m][0], v1 = acc[ai][0][m][1]; float* dp = DT + (size_t)r * 32 + c0;
; #pragma unroll
;                         for (int i = 0; i < 4; ++i) { float x0 = v0[i] + dt_bias[c0 + i], x1 = v1[i] + dt_bias[c0 + 4 + i];
;                             dp[i] = x0 > 20.f ? x0 : log1pf(__expf(x0)); dp[4 + i] = x1 > 20.f ? x1 : log1pf(__expf(x1)); }
;                         __builtin_amdgcn_sched_barrier(0); }
.LBB0_831:
	s_or_b64 exec, exec, s[24:25]
	global_store_dword v[154:155], v136, off offset:28
	global_load_dword v136, v[140:141], off
	s_waitcnt vmcnt(0)
	v_add_f32_e32 v151, v76, v136
	global_load_dword v136, v[140:141], off offset:16
	v_cmp_nlt_f32_e32 vcc, s67, v151
	s_and_saveexec_b64 s[24:25], vcc
	s_cbranch_execz .LBB0_833
	v_mul_f32_e32 v151, 0x3fb8aa3b, v151
	v_exp_f32_e32 v156, v151
	s_nop 0
	v_add_f32_e32 v151, 1.0, v156
	v_frexp_mant_f32_e32 v173, v151
	v_cvt_f64_f32_e32 v[154:155], v151
	v_add_f32_e32 v172, -1.0, v151
	v_frexp_exp_i32_f64_e32 v154, v[154:155]
	v_cmp_gt_f32_e32 vcc, s68, v173
	v_sub_f32_e32 v174, v172, v151
	v_sub_f32_e32 v172, v156, v172
	v_subbrev_co_u32_e32 v178, vcc, 0, v154, vcc
	v_add_f32_e32 v174, 1.0, v174
	v_sub_u32_e32 v154, 0, v178
	v_add_f32_e32 v172, v172, v174
	v_ldexp_f32 v151, v151, v154
	v_ldexp_f32 v154, v172, v154
	v_add_f32_e32 v172, -1.0, v151
	v_add_f32_e32 v155, 1.0, v172
	v_sub_f32_e32 v155, v151, v155
	v_add_f32_e32 v173, v154, v155
	v_add_f32_e32 v155, 1.0, v151
	v_add_f32_e32 v174, -1.0, v155
	v_sub_f32_e32 v151, v151, v174
	v_add_f32_e32 v151, v154, v151
	v_add_f32_e32 v179, v155, v151
	v_rcp_f32_e32 v180, v179
	v_sub_f32_e32 v154, v179, v155
	v_add_f32_e32 v155, v172, v173
	v_sub_f32_e32 v151, v151, v154
	v_mul_f32_e32 v182, v155, v180
	v_sub_f32_e32 v154, v155, v172
	v_mul_f32_e32 v172, v179, v182
	v_fma_f32 v174, v182, v179, -v172
	v_fmac_f32_e32 v174, v182, v151
	v_sub_f32_e32 v181, v173, v154
	v_add_f32_e32 v154, v172, v174
	v_sub_f32_e32 v173, v155, v154
	v_pk_add_f32 v[176:177], v[154:155], v[172:173] neg_lo:[0,1] neg_hi:[0,1]
	v_mov_b32_e32 v175, v154
	v_pk_add_f32 v[154:155], v[176:177], v[174:175] neg_lo:[0,1] neg_hi:[0,1]
	v_cmp_neq_f32_e32 vcc, s70, v156
	v_add_f32_e32 v155, v181, v155
	v_add_f32_e32 v154, v154, v155
	v_add_f32_e32 v155, v173, v154
	v_mul_f32_e32 v181, v180, v155
	v_mul_f32_e32 v172, v179, v181
	v_fma_f32 v174, v181, v179, -v172
	v_fmac_f32_e32 v174, v181, v151
	v_sub_f32_e32 v151, v173, v155
	v_add_f32_e32 v151, v154, v151
	v_add_f32_e32 v154, v172, v174
	v_sub_f32_e32 v173, v155, v154
	v_pk_add_f32 v[176:177], v[154:155], v[172:173] neg_lo:[0,1] neg_hi:[0,1]
	v_mov_b32_e32 v175, v154
	v_pk_add_f32 v[154:155], v[176:177], v[174:175] neg_lo:[0,1] neg_hi:[0,1]
	s_nop 0
	v_add_f32_e32 v151, v151, v155
	v_add_f32_e32 v151, v154, v151
	v_add_f32_e32 v155, v182, v181
	v_add_f32_e32 v151, v173, v151
	v_sub_f32_e32 v154, v155, v182
	v_mul_f32_e32 v151, v180, v151
	v_sub_f32_e32 v154, v181, v154
	v_add_f32_e32 v172, v154, v151
	v_add_f32_e32 v174, v155, v172
	v_cvt_f32_i32_e32 v154, v178
	v_mul_f32_e32 v175, v174, v174
	v_sub_f32_e32 v155, v174, v155
	v_fmamk_f32 v151, v175, 0x3e9b6dac, v166
	v_sub_f32_e32 v155, v172, v155
	v_fmaak_f32 v151, v175, v151, 0x3f2aaada
	v_ldexp_f32 v176, v155, 1
	v_mul_f32_e32 v155, v174, v175
	v_ldexp_f32 v173, v174, 1
	v_pk_mul_f32 v[174:175], v[154:155], v[150:151]
	s_nop 0
	v_fma_f32 v172, v154, s69, -v174
	v_fmac_f32_e32 v172, 0xb102e308, v154
	v_pk_add_f32 v[154:155], v[174:175], v[172:173]
	s_nop 0
	v_sub_f32_e32 v151, v155, v173
	v_sub_f32_e32 v151, v175, v151
	v_add_f32_e32 v177, v176, v151
	v_mov_b32_e32 v176, v174
	v_pk_add_f32 v[174:175], v[154:155], v[174:175] neg_lo:[0,1] neg_hi:[0,1]
	v_pk_add_f32 v[178:179], v[154:155], v[176:177]
	v_mov_b32_e32 v173, v154
	v_mov_b32_e32 v175, v179
	v_pk_add_f32 v[180:181], v[172:173], v[174:175] neg_lo:[0,1] neg_hi:[0,1]
	v_pk_add_f32 v[172:173], v[172:173], v[174:175]
	v_mov_b32_e32 v176, v177
	v_pk_add_f32 v[174:175], v[172:173], v[154:155] op_sel:[1,0] op_sel_hi:[0,1] neg_lo:[0,1] neg_hi:[0,1]
	v_pk_add_f32 v[182:183], v[178:179], v[174:175] op_sel_hi:[1,0] neg_lo:[0,1] neg_hi:[0,1]
	v_mov_b32_e32 v178, v179
	v_mov_b32_e32 v179, v173
	v_pk_mov_b32 v[174:175], v[154:155], v[174:175] op_sel:[1,0]
	v_mov_b32_e32 v177, v154
	v_pk_add_f32 v[174:175], v[178:179], v[174:175] neg_lo:[0,1] neg_hi:[0,1]
	v_mov_b32_e32 v182, v180
	v_pk_add_f32 v[154:155], v[176:177], v[174:175] neg_lo:[0,1] neg_hi:[0,1]
	v_mov_b32_e32 v181, v173
	v_pk_add_f32 v[174:175], v[182:183], v[154:155]
	s_nop 0
	v_pk_add_f32 v[176:177], v[174:175], v[174:175] op_sel:[0,1] op_sel_hi:[1,0]
	s_nop 0
	v_pk_add_f32 v[172:173], v[172:173], v[176:177] op_sel:[1,0] op_sel_hi:[0,1]
	v_mov_b32_e32 v175, v172
	v_pk_add_f32 v[178:179], v[174:175], v[180:181] neg_lo:[0,1] neg_hi:[0,1]
	v_mov_b32_e32 v155, v176
	v_sub_f32_e32 v151, v174, v178
	v_pk_add_f32 v[154:155], v[154:155], v[178:179] neg_lo:[0,1] neg_hi:[0,1]
	v_sub_f32_e32 v151, v180, v151
	v_add_f32_e32 v151, v154, v151
	v_add_f32_e32 v151, v151, v155
	v_add_f32_e32 v151, v172, v151
	v_cndmask_b32_e32 v151, v167, v151, vcc
	v_cmp_ngt_f32_e32 vcc, -1.0, v156
	s_nop 1
	v_cndmask_b32_e32 v151, v168, v151, vcc
	v_cmp_neq_f32_e32 vcc, -1.0, v156
	s_nop 1
	v_cndmask_b32_e32 v151, v169, v151, vcc
	v_cmp_lt_f32_e64 vcc, |v156|, s71
	s_nop 1
	v_cndmask_b32_e32 v151, v151, v156, vcc
;     __device__ __forceinline__ void operator()(const f32x4 (&acc)[2][2][4][2], const Unit& u, int wr, int wc, int fr, int fq) const {
;     ...
;                     for (int m = 0; m < 4; ++m) { const int r = row0 + ai * HALF + m * 16;
;                         const f32x4 v0 = acc[ai][0][m][0], v1 = acc[ai][0][m][1]; float* dp = DT + (size_t)r * 32 + c0;
; #pragma unroll
;                         for (int i = 0; i < 4; ++i) { float x0 = v0[i] + dt_bias[c0 + i], x1 = v1[i] + dt_bias[c0 + 4 + i];
;                             dp[i] = x0 > 20.f ? x0 : log1pf(__expf(x0)); dp[4 + i] = x1 > 20.f ? x1 : log1pf(__expf(x1)); }
;                         __builtin_amdgcn_sched_barrier(0); }
.LBB0_833:
	s_or_b64 exec, exec, s[24:25]
	v_or_b32_e32 v154, 48, v152
	v_ashrrev_i32_e32 v155, 31, v154
	v_lshlrev_b64 v[154:155], 7, v[154:155]
	s_waitcnt vmcnt(0)
	v_add_f32_e32 v136, v72, v136
	v_lshl_add_u64 v[154:155], v[138:139], 0, v[154:155]
	v_cmp_nlt_f32_e32 vcc, s67, v136
	global_store_dword v[154:155], v151, off
	s_and_saveexec_b64 s[24:25], vcc
	s_cbranch_execz .LBB0_835
	v_mul_f32_e32 v136, 0x3fb8aa3b, v136
	v_exp_f32_e32 v136, v136
	s_nop 0
	v_add_f32_e32 v151, 1.0, v136
	v_frexp_mant_f32_e32 v174, v151
	v_cvt_f64_f32_e32 v[172:173], v151
	v_add_f32_e32 v156, -1.0, v151
	v_frexp_exp_i32_f64_e32 v172, v[172:173]
	v_cmp_gt_f32_e32 vcc, s68, v174
	v_sub_f32_e32 v175, v156, v151
	v_sub_f32_e32 v156, v136, v156
	v_subbrev_co_u32_e32 v180, vcc, 0, v172, vcc
	v_add_f32_e32 v175, 1.0, v175
	v_sub_u32_e32 v172, 0, v180
	v_add_f32_e32 v156, v156, v175
	v_ldexp_f32 v151, v151, v172
	v_ldexp_f32 v156, v156, v172
	v_add_f32_e32 v172, -1.0, v151
	v_add_f32_e32 v173, 1.0, v172
	v_sub_f32_e32 v173, v151, v173
	v_add_f32_e32 v174, v156, v173
	v_add_f32_e32 v173, 1.0, v151
	v_add_f32_e32 v175, -1.0, v173
	v_sub_f32_e32 v151, v151, v175
	v_add_f32_e32 v151, v156, v151
	v_add_f32_e32 v156, v173, v151
	v_rcp_f32_e32 v181, v156
	v_sub_f32_e32 v173, v156, v173
	v_sub_f32_e32 v151, v151, v173
	v_add_f32_e32 v173, v172, v174
	v_sub_f32_e32 v172, v173, v172
	v_mul_f32_e32 v183, v173, v181
	v_sub_f32_e32 v182, v174, v172
	v_mul_f32_e32 v174, v156, v183
	v_fma_f32 v176, v183, v156, -v174
	v_fmac_f32_e32 v176, v183, v151
	v_add_f32_e32 v172, v174, v176
	v_sub_f32_e32 v175, v173, v172
	v_pk_add_f32 v[178:179], v[172:173], v[174:175] neg_lo:[0,1] neg_hi:[0,1]
	v_mov_b32_e32 v177, v172
	v_pk_add_f32 v[172:173], v[178:179], v[176:177] neg_lo:[0,1] neg_hi:[0,1]
	v_cmp_neq_f32_e32 vcc, s70, v136
	v_add_f32_e32 v173, v182, v173
	v_add_f32_e32 v172, v172, v173
	v_add_f32_e32 v173, v175, v172
	v_mul_f32_e32 v182, v181, v173
	v_mul_f32_e32 v174, v156, v182
	v_fma_f32 v176, v182, v156, -v174
	v_fmac_f32_e32 v176, v182, v151
	v_sub_f32_e32 v151, v175, v173
	v_add_f32_e32 v151, v172, v151
	v_add_f32_e32 v172, v174, v176
	v_sub_f32_e32 v175, v173, v172
	v_pk_add_f32 v[178:179], v[172:173], v[174:175] neg_lo:[0,1] neg_hi:[0,1]
	v_mov_b32_e32 v177, v172
	v_pk_add_f32 v[172:173], v[178:179], v[176:177] neg_lo:[0,1] neg_hi:[0,1]
	v_add_f32_e32 v156, v183, v182
	v_add_f32_e32 v151, v151, v173
	v_add_f32_e32 v151, v172, v151
	v_add_f32_e32 v151, v175, v151
	v_sub_f32_e32 v172, v156, v183
	v_mul_f32_e32 v151, v181, v151
	v_sub_f32_e32 v172, v182, v172
	v_add_f32_e32 v173, v172, v151
	v_add_f32_e32 v174, v156, v173
	v_cvt_f32_i32_e32 v172, v180
	v_mul_f32_e32 v176, v174, v174
	v_fmamk_f32 v151, v176, 0x3e9b6dac, v166
	v_sub_f32_e32 v156, v174, v156
	v_fmaak_f32 v151, v176, v151, 0x3f2aaada
	v_sub_f32_e32 v156, v173, v156
	v_mul_f32_e32 v173, v174, v176
	v_pk_mul_f32 v[176:177], v[172:173], v[150:151]
	v_ldexp_f32 v175, v174, 1
	v_fma_f32 v174, v172, s69, -v176
	v_fmac_f32_e32 v174, 0xb102e308, v172
	v_pk_add_f32 v[172:173], v[176:177], v[174:175]
	v_ldexp_f32 v156, v156, 1
	v_sub_f32_e32 v151, v173, v175
	v_sub_f32_e32 v151, v177, v151
	v_add_f32_e32 v179, v156, v151
	v_mov_b32_e32 v178, v176
	v_pk_add_f32 v[176:177], v[172:173], v[176:177] neg_lo:[0,1] neg_hi:[0,1]
	v_pk_add_f32 v[180:181], v[172:173], v[178:179]
	v_mov_b32_e32 v175, v172
	v_mov_b32_e32 v177, v181
	v_pk_add_f32 v[182:183], v[174:175], v[176:177] neg_lo:[0,1] neg_hi:[0,1]
	v_pk_add_f32 v[174:175], v[174:175], v[176:177]
	v_mov_b32_e32 v178, v179
	v_pk_add_f32 v[176:177], v[174:175], v[172:173] op_sel:[1,0] op_sel_hi:[0,1] neg_lo:[0,1] neg_hi:[0,1]
	v_pk_add_f32 v[184:185], v[180:181], v[176:177] op_sel_hi:[1,0] neg_lo:[0,1] neg_hi:[0,1]
	v_mov_b32_e32 v180, v181
	v_mov_b32_e32 v181, v175
	v_pk_mov_b32 v[176:177], v[172:173], v[176:177] op_sel:[1,0]
	v_mov_b32_e32 v179, v172
	v_pk_add_f32 v[176:177], v[180:181], v[176:177] neg_lo:[0,1] neg_hi:[0,1]
	v_mov_b32_e32 v184, v182
	v_pk_add_f32 v[172:173], v[178:179], v[176:177] neg_lo:[0,1] neg_hi:[0,1]
	v_mov_b32_e32 v183, v175
	v_pk_add_f32 v[176:177], v[184:185], v[172:173]
	s_nop 0
	v_pk_add_f32 v[178:179], v[176:177], v[176:177] op_sel:[0,1] op_sel_hi:[1,0]
	s_nop 0
	v_pk_add_f32 v[174:175], v[174:175], v[178:179] op_sel:[1,0] op_sel_hi:[0,1]
	v_mov_b32_e32 v177, v174
	v_pk_add_f32 v[180:181], v[176:177], v[182:183] neg_lo:[0,1] neg_hi:[0,1]
	v_mov_b32_e32 v173, v178
	v_sub_f32_e32 v151, v176, v180
	v_pk_add_f32 v[172:173], v[172:173], v[180:181] neg_lo:[0,1] neg_hi:[0,1]
	v_sub_f32_e32 v151, v182, v151
	v_add_f32_e32 v151, v172, v151
	v_add_f32_e32 v151, v151, v173
	v_add_f32_e32 v151, v174, v151
	v_cndmask_b32_e32 v151, v167, v151, vcc
	v_cmp_ngt_f32_e32 vcc, -1.0, v136
	s_nop 1
	v_cndmask_b32_e32 v151, v168, v151, vcc
	v_cmp_neq_f32_e32 vcc, -1.0, v136
	s_nop 1
	v_cndmask_b32_e32 v151, v169, v151, vcc
	v_cmp_lt_f32_e64 vcc, |v136|, s71
	s_nop 1
	v_cndmask_b32_e32 v136, v151, v136, vcc
;     __device__ __forceinline__ void operator()(const f32x4 (&acc)[2][2][4][2], const Unit& u, int wr, int wc, int fr, int fq) const {
;     ...
;                     for (int m = 0; m < 4; ++m) { const int r = row0 + ai * HALF + m * 16;
;                         const f32x4 v0 = acc[ai][0][m][0], v1 = acc[ai][0][m][1]; float* dp = DT + (size_t)r * 32 + c0;
; #pragma unroll
;                         for (int i = 0; i < 4; ++i) { float x0 = v0[i] + dt_bias[c0 + i], x1 = v1[i] + dt_bias[c0 + 4 + i];
;                             dp[i] = x0 > 20.f ? x0 : log1pf(__expf(x0)); dp[4 + i] = x1 > 20.f ? x1 : log1pf(__expf(x1)); }
;                         __builtin_amdgcn_sched_barrier(0); }
.LBB0_835:
	s_or_b64 exec, exec, s[24:25]
	global_store_dword v[154:155], v136, off offset:16
	global_load_dword v136, v[140:141], off offset:4
	s_waitcnt vmcnt(0)
	v_add_f32_e32 v151, v77, v136
	global_load_dword v136, v[140:141], off offset:20
	v_cmp_nlt_f32_e32 vcc, s67, v151
	s_and_saveexec_b64 s[24:25], vcc
	s_cbranch_execz .LBB0_837
	v_mul_f32_e32 v151, 0x3fb8aa3b, v151
	v_exp_f32_e32 v156, v151
	s_nop 0
	v_add_f32_e32 v151, 1.0, v156
	v_frexp_mant_f32_e32 v175, v151
	v_cvt_f64_f32_e32 v[172:173], v151
	v_add_f32_e32 v174, -1.0, v151
	v_frexp_exp_i32_f64_e32 v172, v[172:173]
	v_cmp_gt_f32_e32 vcc, s68, v175
	v_sub_f32_e32 v176, v174, v151
	v_sub_f32_e32 v174, v156, v174
	v_subbrev_co_u32_e32 v180, vcc, 0, v172, vcc
	v_add_f32_e32 v176, 1.0, v176
	v_sub_u32_e32 v172, 0, v180
	v_add_f32_e32 v174, v174, v176
	v_ldexp_f32 v151, v151, v172
	v_ldexp_f32 v172, v174, v172
	v_add_f32_e32 v174, -1.0, v151
	v_add_f32_e32 v173, 1.0, v174
	v_sub_f32_e32 v173, v151, v173
	v_add_f32_e32 v175, v172, v173
	v_add_f32_e32 v173, 1.0, v151
	v_add_f32_e32 v176, -1.0, v173
	v_sub_f32_e32 v151, v151, v176
	v_add_f32_e32 v151, v172, v151
	v_add_f32_e32 v181, v173, v151
	v_rcp_f32_e32 v182, v181
	v_sub_f32_e32 v172, v181, v173
	v_add_f32_e32 v173, v174, v175
	v_sub_f32_e32 v151, v151, v172
	v_mul_f32_e32 v184, v173, v182
	v_sub_f32_e32 v172, v173, v174
	v_mul_f32_e32 v174, v181, v184
	v_fma_f32 v176, v184, v181, -v174
	v_fmac_f32_e32 v176, v184, v151
	v_sub_f32_e32 v183, v175, v172
	v_add_f32_e32 v172, v174, v176
	v_sub_f32_e32 v175, v173, v172
	v_pk_add_f32 v[178:179], v[172:173], v[174:175] neg_lo:[0,1] neg_hi:[0,1]
	v_mov_b32_e32 v177, v172
	v_pk_add_f32 v[172:173], v[178:179], v[176:177] neg_lo:[0,1] neg_hi:[0,1]
	v_cmp_neq_f32_e32 vcc, s70, v156
	v_add_f32_e32 v173, v183, v173
	v_add_f32_e32 v172, v172, v173
	v_add_f32_e32 v173, v175, v172
	v_mul_f32_e32 v183, v182, v173
	v_mul_f32_e32 v174, v181, v183
	v_fma_f32 v176, v183, v181, -v174
	v_fmac_f32_e32 v176, v183, v151
	v_sub_f32_e32 v151, v175, v173
	v_add_f32_e32 v151, v172, v151
	v_add_f32_e32 v172, v174, v176
	v_sub_f32_e32 v175, v173, v172
	v_pk_add_f32 v[178:179], v[172:173], v[174:175] neg_lo:[0,1] neg_hi:[0,1]
	v_mov_b32_e32 v177, v172
	v_pk_add_f32 v[172:173], v[178:179], v[176:177] neg_lo:[0,1] neg_hi:[0,1]
	s_nop 0
	v_add_f32_e32 v151, v151, v173
	v_add_f32_e32 v151, v172, v151
	v_add_f32_e32 v173, v184, v183
	v_add_f32_e32 v151, v175, v151
	v_sub_f32_e32 v172, v173, v184
	v_mul_f32_e32 v151, v182, v151
	v_sub_f32_e32 v172, v183, v172
	v_add_f32_e32 v174, v172, v151
	v_add_f32_e32 v176, v173, v174
	v_cvt_f32_i32_e32 v172, v180
	v_mul_f32_e32 v177, v176, v176
	v_sub_f32_e32 v173, v176, v173
	v_fmamk_f32 v151, v177, 0x3e9b6dac, v166
	v_sub_f32_e32 v173, v174, v173
	v_fmaak_f32 v151, v177, v151, 0x3f2aaada
	v_ldexp_f32 v178, v173, 1
	v_mul_f32_e32 v173, v176, v177
	v_ldexp_f32 v175, v176, 1
	v_pk_mul_f32 v[176:177], v[172:173], v[150:151]
	s_nop 0
	v_fma_f32 v174, v172, s69, -v176
	v_fmac_f32_e32 v174, 0xb102e308, v172
	v_pk_add_f32 v[172:173], v[176:177], v[174:175]
	s_nop 0
	v_sub_f32_e32 v151, v173, v175
	v_sub_f32_e32 v151, v177, v151
	v_add_f32_e32 v179, v178, v151
	v_mov_b32_e32 v178, v176
	v_pk_add_f32 v[176:177], v[172:173], v[176:177] neg_lo:[0,1] neg_hi:[0,1]
	v_pk_add_f32 v[180:181], v[172:173], v[178:179]
	v_mov_b32_e32 v175, v172
	v_mov_b32_e32 v177, v181
	v_pk_add_f32 v[182:183], v[174:175], v[176:177] neg_lo:[0,1] neg_hi:[0,1]
	v_pk_add_f32 v[174:175], v[174:175], v[176:177]
	v_mov_b32_e32 v178, v179
	v_pk_add_f32 v[176:177], v[174:175], v[172:173] op_sel:[1,0] op_sel_hi:[0,1] neg_lo:[0,1] neg_hi:[0,1]
	v_pk_add_f32 v[184:185], v[180:181], v[176:177] op_sel_hi:[1,0] neg_lo:[0,1] neg_hi:[0,1]
	v_mov_b32_e32 v180, v181
	v_mov_b32_e32 v181, v175
	v_pk_mov_b32 v[176:177], v[172:173], v[176:177] op_sel:[1,0]
	v_mov_b32_e32 v179, v172
	v_pk_add_f32 v[176:177], v[180:181], v[176:177] neg_lo:[0,1] neg_hi:[0,1]
	v_mov_b32_e32 v184, v182
	v_pk_add_f32 v[172:173], v[178:179], v[176:177] neg_lo:[0,1] neg_hi:[0,1]
	v_mov_b32_e32 v183, v175
	v_pk_add_f32 v[176:177], v[184:185], v[172:173]
	s_nop 0
	v_pk_add_f32 v[178:179], v[176:177], v[176:177] op_sel:[0,1] op_sel_hi:[1,0]
	s_nop 0
	v_pk_add_f32 v[174:175], v[174:175], v[178:179] op_sel:[1,0] op_sel_hi:[0,1]
	v_mov_b32_e32 v177, v174
	v_pk_add_f32 v[180:181], v[176:177], v[182:183] neg_lo:[0,1] neg_hi:[0,1]
	v_mov_b32_e32 v173, v178
	v_sub_f32_e32 v151, v176, v180
	v_pk_add_f32 v[172:173], v[172:173], v[180:181] neg_lo:[0,1] neg_hi:[0,1]
	v_sub_f32_e32 v151, v182, v151
	v_add_f32_e32 v151, v172, v151
	v_add_f32_e32 v151, v151, v173
	v_add_f32_e32 v151, v174, v151
	v_cndmask_b32_e32 v151, v167, v151, vcc
	v_cmp_ngt_f32_e32 vcc, -1.0, v156
	s_nop 1
	v_cndmask_b32_e32 v151, v168, v151, vcc
	v_cmp_neq_f32_e32 vcc, -1.0, v156
	s_nop 1
	v_cndmask_b32_e32 v151, v169, v151, vcc
	v_cmp_lt_f32_e64 vcc, |v156|, s71
	s_nop 1
	v_cndmask_b32_e32 v151, v151, v156, vcc
;     __device__ __forceinline__ void operator()(const f32x4 (&acc)[2][2][4][2], const Unit& u, int wr, int wc, int fr, int fq) const {
;     ...
;                     for (int m = 0; m < 4; ++m) { const int r = row0 + ai * HALF + m * 16;
;                         const f32x4 v0 = acc[ai][0][m][0], v1 = acc[ai][0][m][1]; float* dp = DT + (size_t)r * 32 + c0;
; #pragma unroll
;                         for (int i = 0; i < 4; ++i) { float x0 = v0[i] + dt_bias[c0 + i], x1 = v1[i] + dt_bias[c0 + 4 + i];
;                             dp[i] = x0 > 20.f ? x0 : log1pf(__expf(x0)); dp[4 + i] = x1 > 20.f ? x1 : log1pf(__expf(x1)); }
;                         __builtin_amdgcn_sched_barrier(0); }
.LBB0_837:
	s_or_b64 exec, exec, s[24:25]
	s_waitcnt vmcnt(0)
	v_add_f32_e32 v136, v73, v136
	v_cmp_nlt_f32_e32 vcc, s67, v136
	global_store_dword v[154:155], v151, off offset:4
	s_and_saveexec_b64 s[24:25], vcc
	s_cbranch_execz .LBB0_839
	v_mul_f32_e32 v136, 0x3fb8aa3b, v136
	v_exp_f32_e32 v136, v136
	s_nop 0
	v_add_f32_e32 v151, 1.0, v136
	v_frexp_mant_f32_e32 v174, v151
	v_cvt_f64_f32_e32 v[172:173], v151
	v_add_f32_e32 v156, -1.0, v151
	v_frexp_exp_i32_f64_e32 v172, v[172:173]
	v_cmp_gt_f32_e32 vcc, s68, v174
	v_sub_f32_e32 v175, v156, v151
	v_sub_f32_e32 v156, v136, v156
	v_subbrev_co_u32_e32 v180, vcc, 0, v172, vcc
	v_add_f32_e32 v175, 1.0, v175
	v_sub_u32_e32 v172, 0, v180
	v_add_f32_e32 v156, v156, v175
	v_ldexp_f32 v151, v151, v172
	v_ldexp_f32 v156, v156, v172
	v_add_f32_e32 v172, -1.0, v151
	v_add_f32_e32 v173, 1.0, v172
	v_sub_f32_e32 v173, v151, v173
	v_add_f32_e32 v174, v156, v173
	v_add_f32_e32 v173, 1.0, v151
	v_add_f32_e32 v175, -1.0, v173
	v_sub_f32_e32 v151, v151, v175
	v_add_f32_e32 v151, v156, v151
	v_add_f32_e32 v156, v173, v151
	v_rcp_f32_e32 v181, v156
	v_sub_f32_e32 v173, v156, v173
	v_sub_f32_e32 v151, v151, v173
	v_add_f32_e32 v173, v172, v174
	v_sub_f32_e32 v172, v173, v172
	v_mul_f32_e32 v183, v173, v181
	v_sub_f32_e32 v182, v174, v172
	v_mul_f32_e32 v174, v156, v183
	v_fma_f32 v176, v183, v156, -v174
	v_fmac_f32_e32 v176, v183, v151
	v_add_f32_e32 v172, v174, v176
	v_sub_f32_e32 v175, v173, v172
	v_pk_add_f32 v[178:179], v[172:173], v[174:175] neg_lo:[0,1] neg_hi:[0,1]
	v_mov_b32_e32 v177, v172
	v_pk_add_f32 v[172:173], v[178:179], v[176:177] neg_lo:[0,1] neg_hi:[0,1]
	v_cmp_neq_f32_e32 vcc, s70, v136
	v_add_f32_e32 v173, v182, v173
	v_add_f32_e32 v172, v172, v173
	v_add_f32_e32 v173, v175, v172
	v_mul_f32_e32 v182, v181, v173
	v_mul_f32_e32 v174, v156, v182
	v_fma_f32 v176, v182, v156, -v174
	v_fmac_f32_e32 v176, v182, v151
	v_sub_f32_e32 v151, v175, v173
	v_add_f32_e32 v151, v172, v151
	v_add_f32_e32 v172, v174, v176
	v_sub_f32_e32 v175, v173, v172
	v_pk_add_f32 v[178:179], v[172:173], v[174:175] neg_lo:[0,1] neg_hi:[0,1]
	v_mov_b32_e32 v177, v172
	v_pk_add_f32 v[172:173], v[178:179], v[176:177] neg_lo:[0,1] neg_hi:[0,1]
	v_add_f32_e32 v156, v183, v182
	v_add_f32_e32 v151, v151, v173
	v_add_f32_e32 v151, v172, v151
	v_add_f32_e32 v151, v175, v151
	v_sub_f32_e32 v172, v156, v183
	v_mul_f32_e32 v151, v181, v151
	v_sub_f32_e32 v172, v182, v172
	v_add_f32_e32 v173, v172, v151
	v_add_f32_e32 v174, v156, v173
	v_cvt_f32_i32_e32 v172, v180
	v_mul_f32_e32 v176, v174, v174
	v_fmamk_f32 v151, v176, 0x3e9b6dac, v166
	v_sub_f32_e32 v156, v174, v156
	v_fmaak_f32 v151, v176, v151, 0x3f2aaada
	v_sub_f32_e32 v156, v173, v156
	v_mul_f32_e32 v173, v174, v176
	v_pk_mul_f32 v[176:177], v[172:173], v[150:151]
	v_ldexp_f32 v175, v174, 1
	v_fma_f32 v174, v172, s69, -v176
	v_fmac_f32_e32 v174, 0xb102e308, v172
	v_pk_add_f32 v[172:173], v[176:177], v[174:175]
	v_ldexp_f32 v156, v156, 1
	v_sub_f32_e32 v151, v173, v175
	v_sub_f32_e32 v151, v177, v151
	v_add_f32_e32 v179, v156, v151
	v_mov_b32_e32 v178, v176
	v_pk_add_f32 v[176:177], v[172:173], v[176:177] neg_lo:[0,1] neg_hi:[0,1]
	v_pk_add_f32 v[180:181], v[172:173], v[178:179]
	v_mov_b32_e32 v175, v172
	v_mov_b32_e32 v177, v181
	v_pk_add_f32 v[182:183], v[174:175], v[176:177] neg_lo:[0,1] neg_hi:[0,1]
	v_pk_add_f32 v[174:175], v[174:175], v[176:177]
	v_mov_b32_e32 v178, v179
	v_pk_add_f32 v[176:177], v[174:175], v[172:173] op_sel:[1,0] op_sel_hi:[0,1] neg_lo:[0,1] neg_hi:[0,1]
	v_pk_add_f32 v[184:185], v[180:181], v[176:177] op_sel_hi:[1,0] neg_lo:[0,1] neg_hi:[0,1]
	v_mov_b32_e32 v180, v181
	v_mov_b32_e32 v181, v175
	v_pk_mov_b32 v[176:177], v[172:173], v[176:177] op_sel:[1,0]
	v_mov_b32_e32 v179, v172
	v_pk_add_f32 v[176:177], v[180:181], v[176:177] neg_lo:[0,1] neg_hi:[0,1]
	v_mov_b32_e32 v184, v182
	v_pk_add_f32 v[172:173], v[178:179], v[176:177] neg_lo:[0,1] neg_hi:[0,1]
	v_mov_b32_e32 v183, v175
	v_pk_add_f32 v[176:177], v[184:185], v[172:173]
	s_nop 0
	v_pk_add_f32 v[178:179], v[176:177], v[176:177] op_sel:[0,1] op_sel_hi:[1,0]
	s_nop 0
	v_pk_add_f32 v[174:175], v[174:175], v[178:179] op_sel:[1,0] op_sel_hi:[0,1]
	v_mov_b32_e32 v177, v174
	v_pk_add_f32 v[180:181], v[176:177], v[182:183] neg_lo:[0,1] neg_hi:[0,1]
	v_mov_b32_e32 v173, v178
	v_sub_f32_e32 v151, v176, v180
	v_pk_add_f32 v[172:173], v[172:173], v[180:181] neg_lo:[0,1] neg_hi:[0,1]
	v_sub_f32_e32 v151, v182, v151
	v_add_f32_e32 v151, v172, v151
	v_add_f32_e32 v151, v151, v173
	v_add_f32_e32 v151, v174, v151
	v_cndmask_b32_e32 v151, v167, v151, vcc
	v_cmp_ngt_f32_e32 vcc, -1.0, v136
	s_nop 1
	v_cndmask_b32_e32 v151, v168, v151, vcc
	v_cmp_neq_f32_e32 vcc, -1.0, v136
	s_nop 1
	v_cndmask_b32_e32 v151, v169, v151, vcc
	v_cmp_lt_f32_e64 vcc, |v136|, s71
	s_nop 1
	v_cndmask_b32_e32 v136, v151, v136, vcc
;     __device__ __forceinline__ void operator()(const f32x4 (&acc)[2][2][4][2], const Unit& u, int wr, int wc, int fr, int fq) const {
;     ...
;                     for (int m = 0; m < 4; ++m) { const int r = row0 + ai * HALF + m * 16;
;                         const f32x4 v0 = acc[ai][0][m][0], v1 = acc[ai][0][m][1]; float* dp = DT + (size_t)r * 32 + c0;
; #pragma unroll
;                         for (int i = 0; i < 4; ++i) { float x0 = v0[i] + dt_bias[c0 + i], x1 = v1[i] + dt_bias[c0 + 4 + i];
;                             dp[i] = x0 > 20.f ? x0 : log1pf(__expf(x0)); dp[4 + i] = x1 > 20.f ? x1 : log1pf(__expf(x1)); }
;                         __builtin_amdgcn_sched_barrier(0); }
.LBB0_839:
	s_or_b64 exec, exec, s[24:25]
	global_store_dword v[154:155], v136, off offset:20
	global_load_dword v136, v[140:141], off offset:8
	s_waitcnt vmcnt(0)
	v_add_f32_e32 v151, v78, v136
	global_load_dword v136, v[140:141], off offset:24
	v_cmp_nlt_f32_e32 vcc, s67, v151
	s_and_saveexec_b64 s[24:25], vcc
	s_cbranch_execz .LBB0_841
	v_mul_f32_e32 v151, 0x3fb8aa3b, v151
	v_exp_f32_e32 v156, v151
	s_nop 0
	v_add_f32_e32 v151, 1.0, v156
	v_frexp_mant_f32_e32 v175, v151
	v_cvt_f64_f32_e32 v[172:173], v151
	v_add_f32_e32 v174, -1.0, v151
	v_frexp_exp_i32_f64_e32 v172, v[172:173]
	v_cmp_gt_f32_e32 vcc, s68, v175
	v_sub_f32_e32 v176, v174, v151
	v_sub_f32_e32 v174, v156, v174
	v_subbrev_co_u32_e32 v180, vcc, 0, v172, vcc
	v_add_f32_e32 v176, 1.0, v176
	v_sub_u32_e32 v172, 0, v180
	v_add_f32_e32 v174, v174, v176
	v_ldexp_f32 v151, v151, v172
	v_ldexp_f32 v172, v174, v172
	v_add_f32_e32 v174, -1.0, v151
	v_add_f32_e32 v173, 1.0, v174
	v_sub_f32_e32 v173, v151, v173
	v_add_f32_e32 v175, v172, v173
	v_add_f32_e32 v173, 1.0, v151
	v_add_f32_e32 v176, -1.0, v173
	v_sub_f32_e32 v151, v151, v176
	v_add_f32_e32 v151, v172, v151
	v_add_f32_e32 v181, v173, v151
	v_rcp_f32_e32 v182, v181
	v_sub_f32_e32 v172, v181, v173
	v_add_f32_e32 v173, v174, v175
	v_sub_f32_e32 v151, v151, v172
	v_mul_f32_e32 v184, v173, v182
	v_sub_f32_e32 v172, v173, v174
	v_mul_f32_e32 v174, v181, v184
	v_fma_f32 v176, v184, v181, -v174
	v_fmac_f32_e32 v176, v184, v151
	v_sub_f32_e32 v183, v175, v172
	v_add_f32_e32 v172, v174, v176
	v_sub_f32_e32 v175, v173, v172
	v_pk_add_f32 v[178:179], v[172:173], v[174:175] neg_lo:[0,1] neg_hi:[0,1]
	v_mov_b32_e32 v177, v172
	v_pk_add_f32 v[172:173], v[178:179], v[176:177] neg_lo:[0,1] neg_hi:[0,1]
	v_cmp_neq_f32_e32 vcc, s70, v156
	v_add_f32_e32 v173, v183, v173
	v_add_f32_e32 v172, v172, v173
	v_add_f32_e32 v173, v175, v172
	v_mul_f32_e32 v183, v182, v173
	v_mul_f32_e32 v174, v181, v183
	v_fma_f32 v176, v183, v181, -v174
	v_fmac_f32_e32 v176, v183, v151
	v_sub_f32_e32 v151, v175, v173
	v_add_f32_e32 v151, v172, v151
	v_add_f32_e32 v172, v174, v176
	v_sub_f32_e32 v175, v173, v172
	v_pk_add_f32 v[178:179], v[172:173], v[174:175] neg_lo:[0,1] neg_hi:[0,1]
	v_mov_b32_e32 v177, v172
	v_pk_add_f32 v[172:173], v[178:179], v[176:177] neg_lo:[0,1] neg_hi:[0,1]
	s_nop 0
	v_add_f32_e32 v151, v151, v173
	v_add_f32_e32 v151, v172, v151
	v_add_f32_e32 v173, v184, v183
	v_add_f32_e32 v151, v175, v151
	v_sub_f32_e32 v172, v173, v184
	v_mul_f32_e32 v151, v182, v151
	v_sub_f32_e32 v172, v183, v172
	v_add_f32_e32 v174, v172, v151
	v_add_f32_e32 v176, v173, v174
	v_cvt_f32_i32_e32 v172, v180
	v_mul_f32_e32 v177, v176, v176
	v_sub_f32_e32 v173, v176, v173
	v_fmamk_f32 v151, v177, 0x3e9b6dac, v166
	v_sub_f32_e32 v173, v174, v173
	v_fmaak_f32 v151, v177, v151, 0x3f2aaada
	v_ldexp_f32 v178, v173, 1
	v_mul_f32_e32 v173, v176, v177
	v_ldexp_f32 v175, v176, 1
	v_pk_mul_f32 v[176:177], v[172:173], v[150:151]
	s_nop 0
	v_fma_f32 v174, v172, s69, -v176
	v_fmac_f32_e32 v174, 0xb102e308, v172
	v_pk_add_f32 v[172:173], v[176:177], v[174:175]
	s_nop 0
	v_sub_f32_e32 v151, v173, v175
	v_sub_f32_e32 v151, v177, v151
	v_add_f32_e32 v179, v178, v151
	v_mov_b32_e32 v178, v176
	v_pk_add_f32 v[176:177], v[172:173], v[176:177] neg_lo:[0,1] neg_hi:[0,1]
	v_pk_add_f32 v[180:181], v[172:173], v[178:179]
	v_mov_b32_e32 v175, v172
	v_mov_b32_e32 v177, v181
	v_pk_add_f32 v[182:183], v[174:175], v[176:177] neg_lo:[0,1] neg_hi:[0,1]
	v_pk_add_f32 v[174:175], v[174:175], v[176:177]
	v_mov_b32_e32 v178, v179
	v_pk_add_f32 v[176:177], v[174:175], v[172:173] op_sel:[1,0] op_sel_hi:[0,1] neg_lo:[0,1] neg_hi:[0,1]
	v_pk_add_f32 v[184:185], v[180:181], v[176:177] op_sel_hi:[1,0] neg_lo:[0,1] neg_hi:[0,1]
	v_mov_b32_e32 v180, v181
	v_mov_b32_e32 v181, v175
	v_pk_mov_b32 v[176:177], v[172:173], v[176:177] op_sel:[1,0]
	v_mov_b32_e32 v179, v172
	v_pk_add_f32 v[176:177], v[180:181], v[176:177] neg_lo:[0,1] neg_hi:[0,1]
	v_mov_b32_e32 v184, v182
	v_pk_add_f32 v[172:173], v[178:179], v[176:177] neg_lo:[0,1] neg_hi:[0,1]
	v_mov_b32_e32 v183, v175
	v_pk_add_f32 v[176:177], v[184:185], v[172:173]
	s_nop 0
	v_pk_add_f32 v[178:179], v[176:177], v[176:177] op_sel:[0,1] op_sel_hi:[1,0]
	s_nop 0
	v_pk_add_f32 v[174:175], v[174:175], v[178:179] op_sel:[1,0] op_sel_hi:[0,1]
	v_mov_b32_e32 v177, v174
	v_pk_add_f32 v[180:181], v[176:177], v[182:183] neg_lo:[0,1] neg_hi:[0,1]
	v_mov_b32_e32 v173, v178
	v_sub_f32_e32 v151, v176, v180
	v_pk_add_f32 v[172:173], v[172:173], v[180:181] neg_lo:[0,1] neg_hi:[0,1]
	v_sub_f32_e32 v151, v182, v151
	v_add_f32_e32 v151, v172, v151
	v_add_f32_e32 v151, v151, v173
	v_add_f32_e32 v151, v174, v151
	v_cndmask_b32_e32 v151, v167, v151, vcc
	v_cmp_ngt_f32_e32 vcc, -1.0, v156
	s_nop 1
	v_cndmask_b32_e32 v151, v168, v151, vcc
	v_cmp_neq_f32_e32 vcc, -1.0, v156
	s_nop 1
	v_cndmask_b32_e32 v151, v169, v151, vcc
	v_cmp_lt_f32_e64 vcc, |v156|, s71
	s_nop 1
	v_cndmask_b32_e32 v151, v151, v156, vcc
;     __device__ __forceinline__ void operator()(const f32x4 (&acc)[2][2][4][2], const Unit& u, int wr, int wc, int fr, int fq) const {
;     ...
;                     for (int m = 0; m < 4; ++m) { const int r = row0 + ai * HALF + m * 16;
;                         const f32x4 v0 = acc[ai][0][m][0], v1 = acc[ai][0][m][1]; float* dp = DT + (size_t)r * 32 + c0;
; #pragma unroll
;                         for (int i = 0; i < 4; ++i) { float x0 = v0[i] + dt_bias[c0 + i], x1 = v1[i] + dt_bias[c0 + 4 + i];
;                             dp[i] = x0 > 20.f ? x0 : log1pf(__expf(x0)); dp[4 + i] = x1 > 20.f ? x1 : log1pf(__expf(x1)); }
;                         __builtin_amdgcn_sched_barrier(0); }
.LBB0_841:
	s_or_b64 exec, exec, s[24:25]
	s_waitcnt vmcnt(0)
	v_add_f32_e32 v136, v74, v136
	v_cmp_nlt_f32_e32 vcc, s67, v136
	global_store_dword v[154:155], v151, off offset:8
	s_and_saveexec_b64 s[24:25], vcc
	s_cbranch_execz .LBB0_843
	v_mul_f32_e32 v136, 0x3fb8aa3b, v136
	v_exp_f32_e32 v136, v136
	s_nop 0
	v_add_f32_e32 v151, 1.0, v136
	v_frexp_mant_f32_e32 v174, v151
	v_cvt_f64_f32_e32 v[172:173], v151
	v_add_f32_e32 v156, -1.0, v151
	v_frexp_exp_i32_f64_e32 v172, v[172:173]
	v_cmp_gt_f32_e32 vcc, s68, v174
	v_sub_f32_e32 v175, v156, v151
	v_sub_f32_e32 v156, v136, v156
	v_subbrev_co_u32_e32 v180, vcc, 0, v172, vcc
	v_add_f32_e32 v175, 1.0, v175
	v_sub_u32_e32 v172, 0, v180
	v_add_f32_e32 v156, v156, v175
	v_ldexp_f32 v151, v151, v172
	v_ldexp_f32 v156, v156, v172
	v_add_f32_e32 v172, -1.0, v151
	v_add_f32_e32 v173, 1.0, v172
	v_sub_f32_e32 v173, v151, v173
	v_add_f32_e32 v174, v156, v173
	v_add_f32_e32 v173, 1.0, v151
	v_add_f32_e32 v175, -1.0, v173
	v_sub_f32_e32 v151, v151, v175
	v_add_f32_e32 v151, v156, v151
	v_add_f32_e32 v156, v173, v151
	v_rcp_f32_e32 v181, v156
	v_sub_f32_e32 v173, v156, v173
	v_sub_f32_e32 v151, v151, v173
	v_add_f32_e32 v173, v172, v174
	v_sub_f32_e32 v172, v173, v172
	v_mul_f32_e32 v183, v173, v181
	v_sub_f32_e32 v182, v174, v172
	v_mul_f32_e32 v174, v156, v183
	v_fma_f32 v176, v183, v156, -v174
	v_fmac_f32_e32 v176, v183, v151
	v_add_f32_e32 v172, v174, v176
	v_sub_f32_e32 v175, v173, v172
	v_pk_add_f32 v[178:179], v[172:173], v[174:175] neg_lo:[0,1] neg_hi:[0,1]
	v_mov_b32_e32 v177, v172
	v_pk_add_f32 v[172:173], v[178:179], v[176:177] neg_lo:[0,1] neg_hi:[0,1]
	v_cmp_neq_f32_e32 vcc, s70, v136
	v_add_f32_e32 v173, v182, v173
	v_add_f32_e32 v172, v172, v173
	v_add_f32_e32 v173, v175, v172
	v_mul_f32_e32 v182, v181, v173
	v_mul_f32_e32 v174, v156, v182
	v_fma_f32 v176, v182, v156, -v174
	v_fmac_f32_e32 v176, v182, v151
	v_sub_f32_e32 v151, v175, v173
	v_add_f32_e32 v151, v172, v151
	v_add_f32_e32 v172, v174, v176
	v_sub_f32_e32 v175, v173, v172
	v_pk_add_f32 v[178:179], v[172:173], v[174:175] neg_lo:[0,1] neg_hi:[0,1]
	v_mov_b32_e32 v177, v172
	v_pk_add_f32 v[172:173], v[178:179], v[176:177] neg_lo:[0,1] neg_hi:[0,1]
	v_add_f32_e32 v156, v183, v182
	v_add_f32_e32 v151, v151, v173
	v_add_f32_e32 v151, v172, v151
	v_add_f32_e32 v151, v175, v151
	v_sub_f32_e32 v172, v156, v183
	v_mul_f32_e32 v151, v181, v151
	v_sub_f32_e32 v172, v182, v172
	v_add_f32_e32 v173, v172, v151
	v_add_f32_e32 v174, v156, v173
	v_cvt_f32_i32_e32 v172, v180
	v_mul_f32_e32 v176, v174, v174
	v_fmamk_f32 v151, v176, 0x3e9b6dac, v166
	v_sub_f32_e32 v156, v174, v156
	v_fmaak_f32 v151, v176, v151, 0x3f2aaada
	v_sub_f32_e32 v156, v173, v156
	v_mul_f32_e32 v173, v174, v176
	v_pk_mul_f32 v[176:177], v[172:173], v[150:151]
	v_ldexp_f32 v175, v174, 1
	v_fma_f32 v174, v172, s69, -v176
	v_fmac_f32_e32 v174, 0xb102e308, v172
	v_pk_add_f32 v[172:173], v[176:177], v[174:175]
	v_ldexp_f32 v156, v156, 1
	v_sub_f32_e32 v151, v173, v175
	v_sub_f32_e32 v151, v177, v151
	v_add_f32_e32 v179, v156, v151
	v_mov_b32_e32 v178, v176
	v_pk_add_f32 v[176:177], v[172:173], v[176:177] neg_lo:[0,1] neg_hi:[0,1]
	v_pk_add_f32 v[180:181], v[172:173], v[178:179]
	v_mov_b32_e32 v175, v172
	v_mov_b32_e32 v177, v181
	v_pk_add_f32 v[182:183], v[174:175], v[176:177] neg_lo:[0,1] neg_hi:[0,1]
	v_pk_add_f32 v[174:175], v[174:175], v[176:177]
	v_mov_b32_e32 v178, v179
	v_pk_add_f32 v[176:177], v[174:175], v[172:173] op_sel:[1,0] op_sel_hi:[0,1] neg_lo:[0,1] neg_hi:[0,1]
	v_pk_add_f32 v[184:185], v[180:181], v[176:177] op_sel_hi:[1,0] neg_lo:[0,1] neg_hi:[0,1]
	v_mov_b32_e32 v180, v181
	v_mov_b32_e32 v181, v175
	v_pk_mov_b32 v[176:177], v[172:173], v[176:177] op_sel:[1,0]
	v_mov_b32_e32 v179, v172
	v_pk_add_f32 v[176:177], v[180:181], v[176:177] neg_lo:[0,1] neg_hi:[0,1]
	v_mov_b32_e32 v184, v182
	v_pk_add_f32 v[172:173], v[178:179], v[176:177] neg_lo:[0,1] neg_hi:[0,1]
	v_mov_b32_e32 v183, v175
	v_pk_add_f32 v[176:177], v[184:185], v[172:173]
	s_nop 0
	v_pk_add_f32 v[178:179], v[176:177], v[176:177] op_sel:[0,1] op_sel_hi:[1,0]
	s_nop 0
	v_pk_add_f32 v[174:175], v[174:175], v[178:179] op_sel:[1,0] op_sel_hi:[0,1]
	v_mov_b32_e32 v177, v174
	v_pk_add_f32 v[180:181], v[176:177], v[182:183] neg_lo:[0,1] neg_hi:[0,1]
	v_mov_b32_e32 v173, v178
	v_sub_f32_e32 v151, v176, v180
	v_pk_add_f32 v[172:173], v[172:173], v[180:181] neg_lo:[0,1] neg_hi:[0,1]
	v_sub_f32_e32 v151, v182, v151
	v_add_f32_e32 v151, v172, v151
	v_add_f32_e32 v151, v151, v173
	v_add_f32_e32 v151, v174, v151
	v_cndmask_b32_e32 v151, v167, v151, vcc
	v_cmp_ngt_f32_e32 vcc, -1.0, v136
	s_nop 1
	v_cndmask_b32_e32 v151, v168, v151, vcc
	v_cmp_neq_f32_e32 vcc, -1.0, v136
	s_nop 1
	v_cndmask_b32_e32 v151, v169, v151, vcc
	v_cmp_lt_f32_e64 vcc, |v136|, s71
	s_nop 1
	v_cndmask_b32_e32 v136, v151, v136, vcc
;     __device__ __forceinline__ void operator()(const f32x4 (&acc)[2][2][4][2], const Unit& u, int wr, int wc, int fr, int fq) const {
;     ...
;                     for (int m = 0; m < 4; ++m) { const int r = row0 + ai * HALF + m * 16;
;                         const f32x4 v0 = acc[ai][0][m][0], v1 = acc[ai][0][m][1]; float* dp = DT + (size_t)r * 32 + c0;
; #pragma unroll
;                         for (int i = 0; i < 4; ++i) { float x0 = v0[i] + dt_bias[c0 + i], x1 = v1[i] + dt_bias[c0 + 4 + i];
;                             dp[i] = x0 > 20.f ? x0 : log1pf(__expf(x0)); dp[4 + i] = x1 > 20.f ? x1 : log1pf(__expf(x1)); }
;                         __builtin_amdgcn_sched_barrier(0); }
.LBB0_843:
	s_or_b64 exec, exec, s[24:25]
	global_store_dword v[154:155], v136, off offset:24
	global_load_dword v136, v[140:141], off offset:12
	s_waitcnt vmcnt(0)
	v_add_f32_e32 v151, v79, v136
	global_load_dword v136, v[140:141], off offset:28
	v_cmp_nlt_f32_e32 vcc, s67, v151
	s_and_saveexec_b64 s[24:25], vcc
	s_cbranch_execz .LBB0_845
	v_mul_f32_e32 v151, 0x3fb8aa3b, v151
	v_exp_f32_e32 v156, v151
	s_nop 0
	v_add_f32_e32 v151, 1.0, v156
	v_frexp_mant_f32_e32 v175, v151
	v_cvt_f64_f32_e32 v[172:173], v151
	v_add_f32_e32 v174, -1.0, v151
	v_frexp_exp_i32_f64_e32 v172, v[172:173]
	v_cmp_gt_f32_e32 vcc, s68, v175
	v_sub_f32_e32 v176, v174, v151
	v_sub_f32_e32 v174, v156, v174
	v_subbrev_co_u32_e32 v180, vcc, 0, v172, vcc
	v_add_f32_e32 v176, 1.0, v176
	v_sub_u32_e32 v172, 0, v180
	v_add_f32_e32 v174, v174, v176
	v_ldexp_f32 v151, v151, v172
	v_ldexp_f32 v172, v174, v172
	v_add_f32_e32 v174, -1.0, v151
	v_add_f32_e32 v173, 1.0, v174
	v_sub_f32_e32 v173, v151, v173
	v_add_f32_e32 v175, v172, v173
	v_add_f32_e32 v173, 1.0, v151
	v_add_f32_e32 v176, -1.0, v173
	v_sub_f32_e32 v151, v151, v176
	v_add_f32_e32 v151, v172, v151
	v_add_f32_e32 v181, v173, v151
	v_rcp_f32_e32 v182, v181
	v_sub_f32_e32 v172, v181, v173
	v_add_f32_e32 v173, v174, v175
	v_sub_f32_e32 v151, v151, v172
	v_mul_f32_e32 v184, v173, v182
	v_sub_f32_e32 v172, v173, v174
	v_mul_f32_e32 v174, v181, v184
	v_fma_f32 v176, v184, v181, -v174
	v_fmac_f32_e32 v176, v184, v151
	v_sub_f32_e32 v183, v175, v172
	v_add_f32_e32 v172, v174, v176
	v_sub_f32_e32 v175, v173, v172
	v_pk_add_f32 v[178:179], v[172:173], v[174:175] neg_lo:[0,1] neg_hi:[0,1]
	v_mov_b32_e32 v177, v172
	v_pk_add_f32 v[172:173], v[178:179], v[176:177] neg_lo:[0,1] neg_hi:[0,1]
	v_cmp_neq_f32_e32 vcc, s70, v156
	v_add_f32_e32 v173, v183, v173
	v_add_f32_e32 v172, v172, v173
	v_add_f32_e32 v173, v175, v172
	v_mul_f32_e32 v183, v182, v173
	v_mul_f32_e32 v174, v181, v183
	v_fma_f32 v176, v183, v181, -v174
	v_fmac_f32_e32 v176, v183, v151
	v_sub_f32_e32 v151, v175, v173
	v_add_f32_e32 v151, v172, v151
	v_add_f32_e32 v172, v174, v176
	v_sub_f32_e32 v175, v173, v172
	v_pk_add_f32 v[178:179], v[172:173], v[174:175] neg_lo:[0,1] neg_hi:[0,1]
	v_mov_b32_e32 v177, v172
	v_pk_add_f32 v[172:173], v[178:179], v[176:177] neg_lo:[0,1] neg_hi:[0,1]
	s_nop 0
	v_add_f32_e32 v151, v151, v173
	v_add_f32_e32 v151, v172, v151
	v_add_f32_e32 v173, v184, v183
	v_add_f32_e32 v151, v175, v151
	v_sub_f32_e32 v172, v173, v184
	v_mul_f32_e32 v151, v182, v151
	v_sub_f32_e32 v172, v183, v172
	v_add_f32_e32 v174, v172, v151
	v_add_f32_e32 v176, v173, v174
	v_cvt_f32_i32_e32 v172, v180
	v_mul_f32_e32 v177, v176, v176
	v_sub_f32_e32 v173, v176, v173
	v_fmamk_f32 v151, v177, 0x3e9b6dac, v166
	v_sub_f32_e32 v173, v174, v173
	v_fmaak_f32 v151, v177, v151, 0x3f2aaada
	v_ldexp_f32 v178, v173, 1
	v_mul_f32_e32 v173, v176, v177
	v_ldexp_f32 v175, v176, 1
	v_pk_mul_f32 v[176:177], v[172:173], v[150:151]
	s_nop 0
	v_fma_f32 v174, v172, s69, -v176
	v_fmac_f32_e32 v174, 0xb102e308, v172
	v_pk_add_f32 v[172:173], v[176:177], v[174:175]
	s_nop 0
	v_sub_f32_e32 v151, v173, v175
	v_sub_f32_e32 v151, v177, v151
	v_add_f32_e32 v179, v178, v151
	v_mov_b32_e32 v178, v176
	v_pk_add_f32 v[176:177], v[172:173], v[176:177] neg_lo:[0,1] neg_hi:[0,1]
	v_pk_add_f32 v[180:181], v[172:173], v[178:179]
	v_mov_b32_e32 v175, v172
	v_mov_b32_e32 v177, v181
	v_pk_add_f32 v[182:183], v[174:175], v[176:177] neg_lo:[0,1] neg_hi:[0,1]
	v_pk_add_f32 v[174:175], v[174:175], v[176:177]
	v_mov_b32_e32 v178, v179
	v_pk_add_f32 v[176:177], v[174:175], v[172:173] op_sel:[1,0] op_sel_hi:[0,1] neg_lo:[0,1] neg_hi:[0,1]
	v_pk_add_f32 v[184:185], v[180:181], v[176:177] op_sel_hi:[1,0] neg_lo:[0,1] neg_hi:[0,1]
	v_mov_b32_e32 v180, v181
	v_mov_b32_e32 v181, v175
	v_pk_mov_b32 v[176:177], v[172:173], v[176:177] op_sel:[1,0]
	v_mov_b32_e32 v179, v172
	v_pk_add_f32 v[176:177], v[180:181], v[176:177] neg_lo:[0,1] neg_hi:[0,1]
	v_mov_b32_e32 v184, v182
	v_pk_add_f32 v[172:173], v[178:179], v[176:177] neg_lo:[0,1] neg_hi:[0,1]
	v_mov_b32_e32 v183, v175
	v_pk_add_f32 v[176:177], v[184:185], v[172:173]
	s_nop 0
	v_pk_add_f32 v[178:179], v[176:177], v[176:177] op_sel:[0,1] op_sel_hi:[1,0]
	s_nop 0
	v_pk_add_f32 v[174:175], v[174:175], v[178:179] op_sel:[1,0] op_sel_hi:[0,1]
	v_mov_b32_e32 v177, v174
	v_pk_add_f32 v[180:181], v[176:177], v[182:183] neg_lo:[0,1] neg_hi:[0,1]
	v_mov_b32_e32 v173, v178
	v_sub_f32_e32 v151, v176, v180
	v_pk_add_f32 v[172:173], v[172:173], v[180:181] neg_lo:[0,1] neg_hi:[0,1]
	v_sub_f32_e32 v151, v182, v151
	v_add_f32_e32 v151, v172, v151
	v_add_f32_e32 v151, v151, v173
	v_add_f32_e32 v151, v174, v151
	v_cndmask_b32_e32 v151, v167, v151, vcc
	v_cmp_ngt_f32_e32 vcc, -1.0, v156
	s_nop 1
	v_cndmask_b32_e32 v151, v168, v151, vcc
	v_cmp_neq_f32_e32 vcc, -1.0, v156
	s_nop 1
	v_cndmask_b32_e32 v151, v169, v151, vcc
	v_cmp_lt_f32_e64 vcc, |v156|, s71
	s_nop 1
	v_cndmask_b32_e32 v151, v151, v156, vcc
;     __device__ __forceinline__ void operator()(const f32x4 (&acc)[2][2][4][2], const Unit& u, int wr, int wc, int fr, int fq) const {
;     ...
;                     for (int m = 0; m < 4; ++m) { const int r = row0 + ai * HALF + m * 16;
;                         const f32x4 v0 = acc[ai][0][m][0], v1 = acc[ai][0][m][1]; float* dp = DT + (size_t)r * 32 + c0;
; #pragma unroll
;                         for (int i = 0; i < 4; ++i) { float x0 = v0[i] + dt_bias[c0 + i], x1 = v1[i] + dt_bias[c0 + 4 + i];
;                             dp[i] = x0 > 20.f ? x0 : log1pf(__expf(x0)); dp[4 + i] = x1 > 20.f ? x1 : log1pf(__expf(x1)); }
;                         __builtin_amdgcn_sched_barrier(0); }
.LBB0_845:
	s_or_b64 exec, exec, s[24:25]
	s_waitcnt vmcnt(0)
	v_add_f32_e32 v136, v75, v136
	v_cmp_nlt_f32_e32 vcc, s67, v136
	global_store_dword v[154:155], v151, off offset:12
	s_and_saveexec_b64 s[24:25], vcc
	s_cbranch_execz .LBB0_847
	v_mul_f32_e32 v136, 0x3fb8aa3b, v136
	v_exp_f32_e32 v136, v136
	s_nop 0
	v_add_f32_e32 v151, 1.0, v136
	v_frexp_mant_f32_e32 v174, v151
	v_cvt_f64_f32_e32 v[172:173], v151
	v_add_f32_e32 v156, -1.0, v151
	v_frexp_exp_i32_f64_e32 v172, v[172:173]
	v_cmp_gt_f32_e32 vcc, s68, v174
	v_sub_f32_e32 v175, v156, v151
	v_sub_f32_e32 v156, v136, v156
	v_subbrev_co_u32_e32 v180, vcc, 0, v172, vcc
	v_add_f32_e32 v175, 1.0, v175
	v_sub_u32_e32 v172, 0, v180
	v_add_f32_e32 v156, v156, v175
	v_ldexp_f32 v151, v151, v172
	v_ldexp_f32 v156, v156, v172
	v_add_f32_e32 v172, -1.0, v151
	v_add_f32_e32 v173, 1.0, v172
	v_sub_f32_e32 v173, v151, v173
	v_add_f32_e32 v174, v156, v173
	v_add_f32_e32 v173, 1.0, v151
	v_add_f32_e32 v175, -1.0, v173
	v_sub_f32_e32 v151, v151, v175
	v_add_f32_e32 v151, v156, v151
	v_add_f32_e32 v156, v173, v151
	v_rcp_f32_e32 v181, v156
	v_sub_f32_e32 v173, v156, v173
	v_sub_f32_e32 v151, v151, v173
	v_add_f32_e32 v173, v172, v174
	v_sub_f32_e32 v172, v173, v172
	v_mul_f32_e32 v183, v173, v181
	v_sub_f32_e32 v182, v174, v172
	v_mul_f32_e32 v174, v156, v183
	v_fma_f32 v176, v183, v156, -v174
	v_fmac_f32_e32 v176, v183, v151
	v_add_f32_e32 v172, v174, v176
	v_sub_f32_e32 v175, v173, v172
	v_pk_add_f32 v[178:179], v[172:173], v[174:175] neg_lo:[0,1] neg_hi:[0,1]
	v_mov_b32_e32 v177, v172
	v_pk_add_f32 v[172:173], v[178:179], v[176:177] neg_lo:[0,1] neg_hi:[0,1]
	v_cmp_neq_f32_e32 vcc, s70, v136
	v_add_f32_e32 v173, v182, v173
	v_add_f32_e32 v172, v172, v173
	v_add_f32_e32 v173, v175, v172
	v_mul_f32_e32 v182, v181, v173
	v_mul_f32_e32 v174, v156, v182
	v_fma_f32 v176, v182, v156, -v174
	v_fmac_f32_e32 v176, v182, v151
	v_sub_f32_e32 v151, v175, v173
	v_add_f32_e32 v151, v172, v151
	v_add_f32_e32 v172, v174, v176
	v_sub_f32_e32 v175, v173, v172
	v_pk_add_f32 v[178:179], v[172:173], v[174:175] neg_lo:[0,1] neg_hi:[0,1]
	v_mov_b32_e32 v177, v172
	v_pk_add_f32 v[172:173], v[178:179], v[176:177] neg_lo:[0,1] neg_hi:[0,1]
	v_add_f32_e32 v156, v183, v182
	v_add_f32_e32 v151, v151, v173
	v_add_f32_e32 v151, v172, v151
	v_add_f32_e32 v151, v175, v151
	v_sub_f32_e32 v172, v156, v183
	v_mul_f32_e32 v151, v181, v151
	v_sub_f32_e32 v172, v182, v172
	v_add_f32_e32 v173, v172, v151
	v_add_f32_e32 v174, v156, v173
	v_cvt_f32_i32_e32 v172, v180
	v_mul_f32_e32 v176, v174, v174
	v_fmamk_f32 v151, v176, 0x3e9b6dac, v166
	v_sub_f32_e32 v156, v174, v156
	v_fmaak_f32 v151, v176, v151, 0x3f2aaada
	v_sub_f32_e32 v156, v173, v156
	v_mul_f32_e32 v173, v174, v176
	v_pk_mul_f32 v[176:177], v[172:173], v[150:151]
	v_ldexp_f32 v175, v174, 1
	v_fma_f32 v174, v172, s69, -v176
	v_fmac_f32_e32 v174, 0xb102e308, v172
	v_pk_add_f32 v[172:173], v[176:177], v[174:175]
	v_ldexp_f32 v156, v156, 1
	v_sub_f32_e32 v151, v173, v175
	v_sub_f32_e32 v151, v177, v151
	v_add_f32_e32 v179, v156, v151
	v_mov_b32_e32 v178, v176
	v_pk_add_f32 v[176:177], v[172:173], v[176:177] neg_lo:[0,1] neg_hi:[0,1]
	v_pk_add_f32 v[180:181], v[172:173], v[178:179]
	v_mov_b32_e32 v175, v172
	v_mov_b32_e32 v177, v181
	v_pk_add_f32 v[182:183], v[174:175], v[176:177] neg_lo:[0,1] neg_hi:[0,1]
	v_pk_add_f32 v[174:175], v[174:175], v[176:177]
	v_mov_b32_e32 v178, v179
	v_pk_add_f32 v[176:177], v[174:175], v[172:173] op_sel:[1,0] op_sel_hi:[0,1] neg_lo:[0,1] neg_hi:[0,1]
	v_pk_add_f32 v[184:185], v[180:181], v[176:177] op_sel_hi:[1,0] neg_lo:[0,1] neg_hi:[0,1]
	v_mov_b32_e32 v180, v181
	v_mov_b32_e32 v181, v175
	v_pk_mov_b32 v[176:177], v[172:173], v[176:177] op_sel:[1,0]
	v_mov_b32_e32 v179, v172
	v_pk_add_f32 v[176:177], v[180:181], v[176:177] neg_lo:[0,1] neg_hi:[0,1]
	v_mov_b32_e32 v184, v182
	v_pk_add_f32 v[172:173], v[178:179], v[176:177] neg_lo:[0,1] neg_hi:[0,1]
	v_mov_b32_e32 v183, v175
	v_pk_add_f32 v[176:177], v[184:185], v[172:173]
	s_nop 0
	v_pk_add_f32 v[178:179], v[176:177], v[176:177] op_sel:[0,1] op_sel_hi:[1,0]
	s_nop 0
	v_pk_add_f32 v[174:175], v[174:175], v[178:179] op_sel:[1,0] op_sel_hi:[0,1]
	v_mov_b32_e32 v177, v174
	v_pk_add_f32 v[180:181], v[176:177], v[182:183] neg_lo:[0,1] neg_hi:[0,1]
	v_mov_b32_e32 v173, v178
	v_sub_f32_e32 v151, v176, v180
	v_pk_add_f32 v[172:173], v[172:173], v[180:181] neg_lo:[0,1] neg_hi:[0,1]
	v_sub_f32_e32 v151, v182, v151
	v_add_f32_e32 v151, v172, v151
	v_add_f32_e32 v151, v151, v173
	v_add_f32_e32 v151, v174, v151
	v_cndmask_b32_e32 v151, v167, v151, vcc
	v_cmp_ngt_f32_e32 vcc, -1.0, v136
	s_nop 1
	v_cndmask_b32_e32 v151, v168, v151, vcc
	v_cmp_neq_f32_e32 vcc, -1.0, v136
	s_nop 1
	v_cndmask_b32_e32 v151, v169, v151, vcc
	v_cmp_lt_f32_e64 vcc, |v136|, s71
	s_nop 1
	v_cndmask_b32_e32 v136, v151, v136, vcc
;     __device__ __forceinline__ void operator()(const f32x4 (&acc)[2][2][4][2], const Unit& u, int wr, int wc, int fr, int fq) const {
;     ...
;                     for (int m = 0; m < 4; ++m) { const int r = row0 + ai * HALF + m * 16;
;                         const f32x4 v0 = acc[ai][0][m][0], v1 = acc[ai][0][m][1]; float* dp = DT + (size_t)r * 32 + c0;
; #pragma unroll
;                         for (int i = 0; i < 4; ++i) { float x0 = v0[i] + dt_bias[c0 + i], x1 = v1[i] + dt_bias[c0 + 4 + i];
;                             dp[i] = x0 > 20.f ? x0 : log1pf(__expf(x0)); dp[4 + i] = x1 > 20.f ? x1 : log1pf(__expf(x1)); }
;                         __builtin_amdgcn_sched_barrier(0); }
.LBB0_847:
	s_or_b64 exec, exec, s[24:25]
	global_store_dword v[154:155], v136, off offset:28
	global_load_dword v136, v[140:141], off
	s_waitcnt vmcnt(0)
	v_add_f32_e32 v151, v60, v136
	global_load_dword v136, v[140:141], off offset:16
	v_cmp_nlt_f32_e32 vcc, s67, v151
	s_and_saveexec_b64 s[24:25], vcc
	s_cbranch_execz .LBB0_849
	v_mul_f32_e32 v151, 0x3fb8aa3b, v151
	v_exp_f32_e32 v156, v151
	s_nop 0
	v_add_f32_e32 v151, 1.0, v156
	v_frexp_mant_f32_e32 v173, v151
	v_cvt_f64_f32_e32 v[154:155], v151
	v_add_f32_e32 v172, -1.0, v151
	v_frexp_exp_i32_f64_e32 v154, v[154:155]
	v_cmp_gt_f32_e32 vcc, s68, v173
	v_sub_f32_e32 v174, v172, v151
	v_sub_f32_e32 v172, v156, v172
	v_subbrev_co_u32_e32 v178, vcc, 0, v154, vcc
	v_add_f32_e32 v174, 1.0, v174
	v_sub_u32_e32 v154, 0, v178
	v_add_f32_e32 v172, v172, v174
	v_ldexp_f32 v151, v151, v154
	v_ldexp_f32 v154, v172, v154
	v_add_f32_e32 v172, -1.0, v151
	v_add_f32_e32 v155, 1.0, v172
	v_sub_f32_e32 v155, v151, v155
	v_add_f32_e32 v173, v154, v155
	v_add_f32_e32 v155, 1.0, v151
	v_add_f32_e32 v174, -1.0, v155
	v_sub_f32_e32 v151, v151, v174
	v_add_f32_e32 v151, v154, v151
	v_add_f32_e32 v179, v155, v151
	v_rcp_f32_e32 v180, v179
	v_sub_f32_e32 v154, v179, v155
	v_add_f32_e32 v155, v172, v173
	v_sub_f32_e32 v151, v151, v154
	v_mul_f32_e32 v182, v155, v180
	v_sub_f32_e32 v154, v155, v172
	v_mul_f32_e32 v172, v179, v182
	v_fma_f32 v174, v182, v179, -v172
	v_fmac_f32_e32 v174, v182, v151
	v_sub_f32_e32 v181, v173, v154
	v_add_f32_e32 v154, v172, v174
	v_sub_f32_e32 v173, v155, v154
	v_pk_add_f32 v[176:177], v[154:155], v[172:173] neg_lo:[0,1] neg_hi:[0,1]
	v_mov_b32_e32 v175, v154
	v_pk_add_f32 v[154:155], v[176:177], v[174:175] neg_lo:[0,1] neg_hi:[0,1]
	v_cmp_neq_f32_e32 vcc, s70, v156
	v_add_f32_e32 v155, v181, v155
	v_add_f32_e32 v154, v154, v155
	v_add_f32_e32 v155, v173, v154
	v_mul_f32_e32 v181, v180, v155
	v_mul_f32_e32 v172, v179, v181
	v_fma_f32 v174, v181, v179, -v172
	v_fmac_f32_e32 v174, v181, v151
	v_sub_f32_e32 v151, v173, v155
	v_add_f32_e32 v151, v154, v151
	v_add_f32_e32 v154, v172, v174
	v_sub_f32_e32 v173, v155, v154
	v_pk_add_f32 v[176:177], v[154:155], v[172:173] neg_lo:[0,1] neg_hi:[0,1]
	v_mov_b32_e32 v175, v154
	v_pk_add_f32 v[154:155], v[176:177], v[174:175] neg_lo:[0,1] neg_hi:[0,1]
	s_nop 0
	v_add_f32_e32 v151, v151, v155
	v_add_f32_e32 v151, v154, v151
	v_add_f32_e32 v155, v182, v181
	v_add_f32_e32 v151, v173, v151
	v_sub_f32_e32 v154, v155, v182
	v_mul_f32_e32 v151, v180, v151
	v_sub_f32_e32 v154, v181, v154
	v_add_f32_e32 v172, v154, v151
	v_add_f32_e32 v174, v155, v172
	v_cvt_f32_i32_e32 v154, v178
	v_mul_f32_e32 v175, v174, v174
	v_sub_f32_e32 v155, v174, v155
	v_fmamk_f32 v151, v175, 0x3e9b6dac, v166
	v_sub_f32_e32 v155, v172, v155
	v_fmaak_f32 v151, v175, v151, 0x3f2aaada
	v_ldexp_f32 v176, v155, 1
	v_mul_f32_e32 v155, v174, v175
	v_ldexp_f32 v173, v174, 1
	v_pk_mul_f32 v[174:175], v[154:155], v[150:151]
	s_nop 0
	v_fma_f32 v172, v154, s69, -v174
	v_fmac_f32_e32 v172, 0xb102e308, v154
	v_pk_add_f32 v[154:155], v[174:175], v[172:173]
	s_nop 0
	v_sub_f32_e32 v151, v155, v173
	v_sub_f32_e32 v151, v175, v151
	v_add_f32_e32 v177, v176, v151
	v_mov_b32_e32 v176, v174
	v_pk_add_f32 v[174:175], v[154:155], v[174:175] neg_lo:[0,1] neg_hi:[0,1]
	v_pk_add_f32 v[178:179], v[154:155], v[176:177]
	v_mov_b32_e32 v173, v154
	v_mov_b32_e32 v175, v179
	v_pk_add_f32 v[180:181], v[172:173], v[174:175] neg_lo:[0,1] neg_hi:[0,1]
	v_pk_add_f32 v[172:173], v[172:173], v[174:175]
	v_mov_b32_e32 v176, v177
	v_pk_add_f32 v[174:175], v[172:173], v[154:155] op_sel:[1,0] op_sel_hi:[0,1] neg_lo:[0,1] neg_hi:[0,1]
	v_pk_add_f32 v[182:183], v[178:179], v[174:175] op_sel_hi:[1,0] neg_lo:[0,1] neg_hi:[0,1]
	v_mov_b32_e32 v178, v179
	v_mov_b32_e32 v179, v173
	v_pk_mov_b32 v[174:175], v[154:155], v[174:175] op_sel:[1,0]
	v_mov_b32_e32 v177, v154
	v_pk_add_f32 v[174:175], v[178:179], v[174:175] neg_lo:[0,1] neg_hi:[0,1]
	v_mov_b32_e32 v182, v180
	v_pk_add_f32 v[154:155], v[176:177], v[174:175] neg_lo:[0,1] neg_hi:[0,1]
	v_mov_b32_e32 v181, v173
	v_pk_add_f32 v[174:175], v[182:183], v[154:155]
	s_nop 0
	v_pk_add_f32 v[176:177], v[174:175], v[174:175] op_sel:[0,1] op_sel_hi:[1,0]
	s_nop 0
	v_pk_add_f32 v[172:173], v[172:173], v[176:177] op_sel:[1,0] op_sel_hi:[0,1]
	v_mov_b32_e32 v175, v172
	v_pk_add_f32 v[178:179], v[174:175], v[180:181] neg_lo:[0,1] neg_hi:[0,1]
	v_mov_b32_e32 v155, v176
	v_sub_f32_e32 v151, v174, v178
	v_pk_add_f32 v[154:155], v[154:155], v[178:179] neg_lo:[0,1] neg_hi:[0,1]
	v_sub_f32_e32 v151, v180, v151
	v_add_f32_e32 v151, v154, v151
	v_add_f32_e32 v151, v151, v155
	v_add_f32_e32 v151, v172, v151
	v_cndmask_b32_e32 v151, v167, v151, vcc
	v_cmp_ngt_f32_e32 vcc, -1.0, v156
	s_nop 1
	v_cndmask_b32_e32 v151, v168, v151, vcc
	v_cmp_neq_f32_e32 vcc, -1.0, v156
	s_nop 1
	v_cndmask_b32_e32 v151, v169, v151, vcc
	v_cmp_lt_f32_e64 vcc, |v156|, s71
	s_nop 1
	v_cndmask_b32_e32 v151, v151, v156, vcc
;     __device__ __forceinline__ void operator()(const f32x4 (&acc)[2][2][4][2], const Unit& u, int wr, int wc, int fr, int fq) const {
;     ...
;                     for (int m = 0; m < 4; ++m) { const int r = row0 + ai * HALF + m * 16;
;                         const f32x4 v0 = acc[ai][0][m][0], v1 = acc[ai][0][m][1]; float* dp = DT + (size_t)r * 32 + c0;
; #pragma unroll
;                         for (int i = 0; i < 4; ++i) { float x0 = v0[i] + dt_bias[c0 + i], x1 = v1[i] + dt_bias[c0 + 4 + i];
;                             dp[i] = x0 > 20.f ? x0 : log1pf(__expf(x0)); dp[4 + i] = x1 > 20.f ? x1 : log1pf(__expf(x1)); }
;                         __builtin_amdgcn_sched_barrier(0); }
.LBB0_849:
	s_or_b64 exec, exec, s[24:25]
	v_lshlrev_b64 v[154:155], 7, v[152:153]
	v_lshl_add_u64 v[154:155], v[138:139], 0, v[154:155]
	v_add_co_u32_e32 v172, vcc, 0x4000, v154
	s_waitcnt vmcnt(0)
	v_add_f32_e32 v136, v56, v136
	v_addc_co_u32_e32 v173, vcc, 0, v155, vcc
	v_cmp_nlt_f32_e32 vcc, s67, v136
	global_store_dword v[172:173], v151, off
	s_and_saveexec_b64 s[24:25], vcc
	s_cbranch_execz .LBB0_851
	v_mul_f32_e32 v136, 0x3fb8aa3b, v136
	v_exp_f32_e32 v136, v136
	s_nop 0
	v_add_f32_e32 v151, 1.0, v136
	v_frexp_mant_f32_e32 v174, v151
	v_cvt_f64_f32_e32 v[172:173], v151
	v_add_f32_e32 v156, -1.0, v151
	v_frexp_exp_i32_f64_e32 v172, v[172:173]
	v_cmp_gt_f32_e32 vcc, s68, v174
	v_sub_f32_e32 v175, v156, v151
	v_sub_f32_e32 v156, v136, v156
	v_subbrev_co_u32_e32 v180, vcc, 0, v172, vcc
	v_add_f32_e32 v175, 1.0, v175
	v_sub_u32_e32 v172, 0, v180
	v_add_f32_e32 v156, v156, v175
	v_ldexp_f32 v151, v151, v172
	v_ldexp_f32 v156, v156, v172
	v_add_f32_e32 v172, -1.0, v151
	v_add_f32_e32 v173, 1.0, v172
	v_sub_f32_e32 v173, v151, v173
	v_add_f32_e32 v174, v156, v173
	v_add_f32_e32 v173, 1.0, v151
	v_add_f32_e32 v175, -1.0, v173
	v_sub_f32_e32 v151, v151, v175
	v_add_f32_e32 v151, v156, v151
	v_add_f32_e32 v156, v173, v151
	v_rcp_f32_e32 v181, v156
	v_sub_f32_e32 v173, v156, v173
	v_sub_f32_e32 v151, v151, v173
	v_add_f32_e32 v173, v172, v174
	v_sub_f32_e32 v172, v173, v172
	v_mul_f32_e32 v183, v173, v181
	v_sub_f32_e32 v182, v174, v172
	v_mul_f32_e32 v174, v156, v183
	v_fma_f32 v176, v183, v156, -v174
	v_fmac_f32_e32 v176, v183, v151
	v_add_f32_e32 v172, v174, v176
	v_sub_f32_e32 v175, v173, v172
	v_pk_add_f32 v[178:179], v[172:173], v[174:175] neg_lo:[0,1] neg_hi:[0,1]
	v_mov_b32_e32 v177, v172
	v_pk_add_f32 v[172:173], v[178:179], v[176:177] neg_lo:[0,1] neg_hi:[0,1]
	v_cmp_neq_f32_e32 vcc, s70, v136
	v_add_f32_e32 v173, v182, v173
	v_add_f32_e32 v172, v172, v173
	v_add_f32_e32 v173, v175, v172
	v_mul_f32_e32 v182, v181, v173
	v_mul_f32_e32 v174, v156, v182
	v_fma_f32 v176, v182, v156, -v174
	v_fmac_f32_e32 v176, v182, v151
	v_sub_f32_e32 v151, v175, v173
	v_add_f32_e32 v151, v172, v151
	v_add_f32_e32 v172, v174, v176
	v_sub_f32_e32 v175, v173, v172
	v_pk_add_f32 v[178:179], v[172:173], v[174:175] neg_lo:[0,1] neg_hi:[0,1]
	v_mov_b32_e32 v177, v172
	v_pk_add_f32 v[172:173], v[178:179], v[176:177] neg_lo:[0,1] neg_hi:[0,1]
	v_add_f32_e32 v156, v183, v182
	v_add_f32_e32 v151, v151, v173
	v_add_f32_e32 v151, v172, v151
	v_add_f32_e32 v151, v175, v151
	v_sub_f32_e32 v172, v156, v183
	v_mul_f32_e32 v151, v181, v151
	v_sub_f32_e32 v172, v182, v172
	v_add_f32_e32 v173, v172, v151
	v_add_f32_e32 v174, v156, v173
	v_cvt_f32_i32_e32 v172, v180
	v_mul_f32_e32 v176, v174, v174
	v_fmamk_f32 v151, v176, 0x3e9b6dac, v166
	v_sub_f32_e32 v156, v174, v156
	v_fmaak_f32 v151, v176, v151, 0x3f2aaada
	v_sub_f32_e32 v156, v173, v156
	v_mul_f32_e32 v173, v174, v176
	v_pk_mul_f32 v[176:177], v[172:173], v[150:151]
	v_ldexp_f32 v175, v174, 1
	v_fma_f32 v174, v172, s69, -v176
	v_fmac_f32_e32 v174, 0xb102e308, v172
	v_pk_add_f32 v[172:173], v[176:177], v[174:175]
	v_ldexp_f32 v156, v156, 1
	v_sub_f32_e32 v151, v173, v175
	v_sub_f32_e32 v151, v177, v151
	v_add_f32_e32 v179, v156, v151
	v_mov_b32_e32 v178, v176
	v_pk_add_f32 v[176:177], v[172:173], v[176:177] neg_lo:[0,1] neg_hi:[0,1]
	v_pk_add_f32 v[180:181], v[172:173], v[178:179]
	v_mov_b32_e32 v175, v172
	v_mov_b32_e32 v177, v181
	v_pk_add_f32 v[182:183], v[174:175], v[176:177] neg_lo:[0,1] neg_hi:[0,1]
	v_pk_add_f32 v[174:175], v[174:175], v[176:177]
	v_mov_b32_e32 v178, v179
	v_pk_add_f32 v[176:177], v[174:175], v[172:173] op_sel:[1,0] op_sel_hi:[0,1] neg_lo:[0,1] neg_hi:[0,1]
	v_pk_add_f32 v[184:185], v[180:181], v[176:177] op_sel_hi:[1,0] neg_lo:[0,1] neg_hi:[0,1]
	v_mov_b32_e32 v180, v181
	v_mov_b32_e32 v181, v175
	v_pk_mov_b32 v[176:177], v[172:173], v[176:177] op_sel:[1,0]
	v_mov_b32_e32 v179, v172
	v_pk_add_f32 v[176:177], v[180:181], v[176:177] neg_lo:[0,1] neg_hi:[0,1]
	v_mov_b32_e32 v184, v182
	v_pk_add_f32 v[172:173], v[178:179], v[176:177] neg_lo:[0,1] neg_hi:[0,1]
	v_mov_b32_e32 v183, v175
	v_pk_add_f32 v[176:177], v[184:185], v[172:173]
	s_nop 0
	v_pk_add_f32 v[178:179], v[176:177], v[176:177] op_sel:[0,1] op_sel_hi:[1,0]
	s_nop 0
	v_pk_add_f32 v[174:175], v[174:175], v[178:179] op_sel:[1,0] op_sel_hi:[0,1]
	v_mov_b32_e32 v177, v174
	v_pk_add_f32 v[180:181], v[176:177], v[182:183] neg_lo:[0,1] neg_hi:[0,1]
	v_mov_b32_e32 v173, v178
	v_sub_f32_e32 v151, v176, v180
	v_pk_add_f32 v[172:173], v[172:173], v[180:181] neg_lo:[0,1] neg_hi:[0,1]
	v_sub_f32_e32 v151, v182, v151
	v_add_f32_e32 v151, v172, v151
	v_add_f32_e32 v151, v151, v173
	v_add_f32_e32 v151, v174, v151
	v_cndmask_b32_e32 v151, v167, v151, vcc
	v_cmp_ngt_f32_e32 vcc, -1.0, v136
	s_nop 1
	v_cndmask_b32_e32 v151, v168, v151, vcc
	v_cmp_neq_f32_e32 vcc, -1.0, v136
	s_nop 1
	v_cndmask_b32_e32 v151, v169, v151, vcc
	v_cmp_lt_f32_e64 vcc, |v136|, s71
	s_nop 1
	v_cndmask_b32_e32 v136, v151, v136, vcc
;     __device__ __forceinline__ void operator()(const f32x4 (&acc)[2][2][4][2], const Unit& u, int wr, int wc, int fr, int fq) const {
;     ...
;                     for (int m = 0; m < 4; ++m) { const int r = row0 + ai * HALF + m * 16;
;                         const f32x4 v0 = acc[ai][0][m][0], v1 = acc[ai][0][m][1]; float* dp = DT + (size_t)r * 32 + c0;
; #pragma unroll
;                         for (int i = 0; i < 4; ++i) { float x0 = v0[i] + dt_bias[c0 + i], x1 = v1[i] + dt_bias[c0 + 4 + i];
;                             dp[i] = x0 > 20.f ? x0 : log1pf(__expf(x0)); dp[4 + i] = x1 > 20.f ? x1 : log1pf(__expf(x1)); }
;                         __builtin_amdgcn_sched_barrier(0); }
.LBB0_851:
	s_or_b64 exec, exec, s[24:25]
	s_mov_b64 s[24:25], 0x4000
	v_lshl_add_u64 v[154:155], v[154:155], 0, s[24:25]
	global_store_dword v[154:155], v136, off offset:16
	global_load_dword v151, v[140:141], off offset:4
	s_nop 0
	global_load_dword v136, v[140:141], off offset:20
	s_waitcnt vmcnt(0)
	v_add_f32_e32 v151, v61, v151
	v_cmp_nlt_f32_e32 vcc, s67, v151
	s_and_saveexec_b64 s[24:25], vcc
	s_cbranch_execz .LBB0_853
	v_mul_f32_e32 v151, 0x3fb8aa3b, v151
	v_exp_f32_e32 v156, v151
	s_nop 0
	v_add_f32_e32 v151, 1.0, v156
	v_frexp_mant_f32_e32 v175, v151
	v_cvt_f64_f32_e32 v[172:173], v151
	v_add_f32_e32 v174, -1.0, v151
	v_frexp_exp_i32_f64_e32 v172, v[172:173]
	v_cmp_gt_f32_e32 vcc, s68, v175
	v_sub_f32_e32 v176, v174, v151
	v_sub_f32_e32 v174, v156, v174
	v_subbrev_co_u32_e32 v180, vcc, 0, v172, vcc
	v_add_f32_e32 v176, 1.0, v176
	v_sub_u32_e32 v172, 0, v180
	v_add_f32_e32 v174, v174, v176
	v_ldexp_f32 v151, v151, v172
	v_ldexp_f32 v172, v174, v172
	v_add_f32_e32 v174, -1.0, v151
	v_add_f32_e32 v173, 1.0, v174
	v_sub_f32_e32 v173, v151, v173
	v_add_f32_e32 v175, v172, v173
	v_add_f32_e32 v173, 1.0, v151
	v_add_f32_e32 v176, -1.0, v173
	v_sub_f32_e32 v151, v151, v176
	v_add_f32_e32 v151, v172, v151
	v_add_f32_e32 v181, v173, v151
	v_rcp_f32_e32 v182, v181
	v_sub_f32_e32 v172, v181, v173
	v_add_f32_e32 v173, v174, v175
	v_sub_f32_e32 v151, v151, v172
	v_mul_f32_e32 v184, v173, v182
	v_sub_f32_e32 v172, v173, v174
	v_mul_f32_e32 v174, v181, v184
	v_fma_f32 v176, v184, v181, -v174
	v_fmac_f32_e32 v176, v184, v151
	v_sub_f32_e32 v183, v175, v172
	v_add_f32_e32 v172, v174, v176
	v_sub_f32_e32 v175, v173, v172
	v_pk_add_f32 v[178:179], v[172:173], v[174:175] neg_lo:[0,1] neg_hi:[0,1]
	v_mov_b32_e32 v177, v172
	v_pk_add_f32 v[172:173], v[178:179], v[176:177] neg_lo:[0,1] neg_hi:[0,1]
	v_cmp_neq_f32_e32 vcc, s70, v156
	v_add_f32_e32 v173, v183, v173
	v_add_f32_e32 v172, v172, v173
	v_add_f32_e32 v173, v175, v172
	v_mul_f32_e32 v183, v182, v173
	v_mul_f32_e32 v174, v181, v183
	v_fma_f32 v176, v183, v181, -v174
	v_fmac_f32_e32 v176, v183, v151
	v_sub_f32_e32 v151, v175, v173
	v_add_f32_e32 v151, v172, v151
	v_add_f32_e32 v172, v174, v176
	v_sub_f32_e32 v175, v173, v172
	v_pk_add_f32 v[178:179], v[172:173], v[174:175] neg_lo:[0,1] neg_hi:[0,1]
	v_mov_b32_e32 v177, v172
	v_pk_add_f32 v[172:173], v[178:179], v[176:177] neg_lo:[0,1] neg_hi:[0,1]
	s_nop 0
	v_add_f32_e32 v151, v151, v173
	v_add_f32_e32 v151, v172, v151
	v_add_f32_e32 v173, v184, v183
	v_add_f32_e32 v151, v175, v151
	v_sub_f32_e32 v172, v173, v184
	v_mul_f32_e32 v151, v182, v151
	v_sub_f32_e32 v172, v183, v172
	v_add_f32_e32 v174, v172, v151
	v_add_f32_e32 v176, v173, v174
	v_cvt_f32_i32_e32 v172, v180
	v_mul_f32_e32 v177, v176, v176
	v_sub_f32_e32 v173, v176, v173
	v_fmamk_f32 v151, v177, 0x3e9b6dac, v166
	v_sub_f32_e32 v173, v174, v173
	v_fmaak_f32 v151, v177, v151, 0x3f2aaada
	v_ldexp_f32 v178, v173, 1
	v_mul_f32_e32 v173, v176, v177
	v_ldexp_f32 v175, v176, 1
	v_pk_mul_f32 v[176:177], v[172:173], v[150:151]
	s_nop 0
	v_fma_f32 v174, v172, s69, -v176
	v_fmac_f32_e32 v174, 0xb102e308, v172
	v_pk_add_f32 v[172:173], v[176:177], v[174:175]
	s_nop 0
	v_sub_f32_e32 v151, v173, v175
	v_sub_f32_e32 v151, v177, v151
	v_add_f32_e32 v179, v178, v151
	v_mov_b32_e32 v178, v176
	v_pk_add_f32 v[176:177], v[172:173], v[176:177] neg_lo:[0,1] neg_hi:[0,1]
	v_pk_add_f32 v[180:181], v[172:173], v[178:179]
	v_mov_b32_e32 v175, v172
	v_mov_b32_e32 v177, v181
	v_pk_add_f32 v[182:183], v[174:175], v[176:177] neg_lo:[0,1] neg_hi:[0,1]
	v_pk_add_f32 v[174:175], v[174:175], v[176:177]
	v_mov_b32_e32 v178, v179
	v_pk_add_f32 v[176:177], v[174:175], v[172:173] op_sel:[1,0] op_sel_hi:[0,1] neg_lo:[0,1] neg_hi:[0,1]
	v_pk_add_f32 v[184:185], v[180:181], v[176:177] op_sel_hi:[1,0] neg_lo:[0,1] neg_hi:[0,1]
	v_mov_b32_e32 v180, v181
	v_mov_b32_e32 v181, v175
	v_pk_mov_b32 v[176:177], v[172:173], v[176:177] op_sel:[1,0]
	v_mov_b32_e32 v179, v172
	v_pk_add_f32 v[176:177], v[180:181], v[176:177] neg_lo:[0,1] neg_hi:[0,1]
	v_mov_b32_e32 v184, v182
	v_pk_add_f32 v[172:173], v[178:179], v[176:177] neg_lo:[0,1] neg_hi:[0,1]
	v_mov_b32_e32 v183, v175
	v_pk_add_f32 v[176:177], v[184:185], v[172:173]
	s_nop 0
	v_pk_add_f32 v[178:179], v[176:177], v[176:177] op_sel:[0,1] op_sel_hi:[1,0]
	s_nop 0
	v_pk_add_f32 v[174:175], v[174:175], v[178:179] op_sel:[1,0] op_sel_hi:[0,1]
	v_mov_b32_e32 v177, v174
	v_pk_add_f32 v[180:181], v[176:177], v[182:183] neg_lo:[0,1] neg_hi:[0,1]
	v_mov_b32_e32 v173, v178
	v_sub_f32_e32 v151, v176, v180
	v_pk_add_f32 v[172:173], v[172:173], v[180:181] neg_lo:[0,1] neg_hi:[0,1]
	v_sub_f32_e32 v151, v182, v151
	v_add_f32_e32 v151, v172, v151
	v_add_f32_e32 v151, v151, v173
	v_add_f32_e32 v151, v174, v151
	v_cndmask_b32_e32 v151, v167, v151, vcc
	v_cmp_ngt_f32_e32 vcc, -1.0, v156
	s_nop 1
	v_cndmask_b32_e32 v151, v168, v151, vcc
	v_cmp_neq_f32_e32 vcc, -1.0, v156
	s_nop 1
	v_cndmask_b32_e32 v151, v169, v151, vcc
	v_cmp_lt_f32_e64 vcc, |v156|, s71
	s_nop 1
	v_cndmask_b32_e32 v151, v151, v156, vcc
;     __device__ __forceinline__ void operator()(const f32x4 (&acc)[2][2][4][2], const Unit& u, int wr, int wc, int fr, int fq) const {
;     ...
;                     for (int m = 0; m < 4; ++m) { const int r = row0 + ai * HALF + m * 16;
;                         const f32x4 v0 = acc[ai][0][m][0], v1 = acc[ai][0][m][1]; float* dp = DT + (size_t)r * 32 + c0;
; #pragma unroll
;                         for (int i = 0; i < 4; ++i) { float x0 = v0[i] + dt_bias[c0 + i], x1 = v1[i] + dt_bias[c0 + 4 + i];
;                             dp[i] = x0 > 20.f ? x0 : log1pf(__expf(x0)); dp[4 + i] = x1 > 20.f ? x1 : log1pf(__expf(x1)); }
;                         __builtin_amdgcn_sched_barrier(0); }
.LBB0_853:
	s_or_b64 exec, exec, s[24:25]
	v_add_f32_e32 v136, v57, v136
	v_cmp_nlt_f32_e32 vcc, s67, v136
	global_store_dword v[154:155], v151, off offset:4
	s_and_saveexec_b64 s[24:25], vcc
	s_cbranch_execz .LBB0_855
	v_mul_f32_e32 v136, 0x3fb8aa3b, v136
	v_exp_f32_e32 v136, v136
	s_nop 0
	v_add_f32_e32 v151, 1.0, v136
	v_frexp_mant_f32_e32 v174, v151
	v_cvt_f64_f32_e32 v[172:173], v151
	v_add_f32_e32 v156, -1.0, v151
	v_frexp_exp_i32_f64_e32 v172, v[172:173]
	v_cmp_gt_f32_e32 vcc, s68, v174
	v_sub_f32_e32 v175, v156, v151
	v_sub_f32_e32 v156, v136, v156
	v_subbrev_co_u32_e32 v180, vcc, 0, v172, vcc
	v_add_f32_e32 v175, 1.0, v175
	v_sub_u32_e32 v172, 0, v180
	v_add_f32_e32 v156, v156, v175
	v_ldexp_f32 v151, v151, v172
	v_ldexp_f32 v156, v156, v172
	v_add_f32_e32 v172, -1.0, v151
	v_add_f32_e32 v173, 1.0, v172
	v_sub_f32_e32 v173, v151, v173
	v_add_f32_e32 v174, v156, v173
	v_add_f32_e32 v173, 1.0, v151
	v_add_f32_e32 v175, -1.0, v173
	v_sub_f32_e32 v151, v151, v175
	v_add_f32_e32 v151, v156, v151
	v_add_f32_e32 v156, v173, v151
	v_rcp_f32_e32 v181, v156
	v_sub_f32_e32 v173, v156, v173
	v_sub_f32_e32 v151, v151, v173
	v_add_f32_e32 v173, v172, v174
	v_sub_f32_e32 v172, v173, v172
	v_mul_f32_e32 v183, v173, v181
	v_sub_f32_e32 v182, v174, v172
	v_mul_f32_e32 v174, v156, v183
	v_fma_f32 v176, v183, v156, -v174
	v_fmac_f32_e32 v176, v183, v151
	v_add_f32_e32 v172, v174, v176
	v_sub_f32_e32 v175, v173, v172
	v_pk_add_f32 v[178:179], v[172:173], v[174:175] neg_lo:[0,1] neg_hi:[0,1]
	v_mov_b32_e32 v177, v172
	v_pk_add_f32 v[172:173], v[178:179], v[176:177] neg_lo:[0,1] neg_hi:[0,1]
	v_cmp_neq_f32_e32 vcc, s70, v136
	v_add_f32_e32 v173, v182, v173
	v_add_f32_e32 v172, v172, v173
	v_add_f32_e32 v173, v175, v172
	v_mul_f32_e32 v182, v181, v173
	v_mul_f32_e32 v174, v156, v182
	v_fma_f32 v176, v182, v156, -v174
	v_fmac_f32_e32 v176, v182, v151
	v_sub_f32_e32 v151, v175, v173
	v_add_f32_e32 v151, v172, v151
	v_add_f32_e32 v172, v174, v176
	v_sub_f32_e32 v175, v173, v172
	v_pk_add_f32 v[178:179], v[172:173], v[174:175] neg_lo:[0,1] neg_hi:[0,1]
	v_mov_b32_e32 v177, v172
	v_pk_add_f32 v[172:173], v[178:179], v[176:177] neg_lo:[0,1] neg_hi:[0,1]
	v_add_f32_e32 v156, v183, v182
	v_add_f32_e32 v151, v151, v173
	v_add_f32_e32 v151, v172, v151
	v_add_f32_e32 v151, v175, v151
	v_sub_f32_e32 v172, v156, v183
	v_mul_f32_e32 v151, v181, v151
	v_sub_f32_e32 v172, v182, v172
	v_add_f32_e32 v173, v172, v151
	v_add_f32_e32 v174, v156, v173
	v_cvt_f32_i32_e32 v172, v180
	v_mul_f32_e32 v176, v174, v174
	v_fmamk_f32 v151, v176, 0x3e9b6dac, v166
	v_sub_f32_e32 v156, v174, v156
	v_fmaak_f32 v151, v176, v151, 0x3f2aaada
	v_sub_f32_e32 v156, v173, v156
	v_mul_f32_e32 v173, v174, v176
	v_pk_mul_f32 v[176:177], v[172:173], v[150:151]
	v_ldexp_f32 v175, v174, 1
	v_fma_f32 v174, v172, s69, -v176
	v_fmac_f32_e32 v174, 0xb102e308, v172
	v_pk_add_f32 v[172:173], v[176:177], v[174:175]
	v_ldexp_f32 v156, v156, 1
	v_sub_f32_e32 v151, v173, v175
	v_sub_f32_e32 v151, v177, v151
	v_add_f32_e32 v179, v156, v151
	v_mov_b32_e32 v178, v176
	v_pk_add_f32 v[176:177], v[172:173], v[176:177] neg_lo:[0,1] neg_hi:[0,1]
	v_pk_add_f32 v[180:181], v[172:173], v[178:179]
	v_mov_b32_e32 v175, v172
	v_mov_b32_e32 v177, v181
	v_pk_add_f32 v[182:183], v[174:175], v[176:177] neg_lo:[0,1] neg_hi:[0,1]
	v_pk_add_f32 v[174:175], v[174:175], v[176:177]
	v_mov_b32_e32 v178, v179
	v_pk_add_f32 v[176:177], v[174:175], v[172:173] op_sel:[1,0] op_sel_hi:[0,1] neg_lo:[0,1] neg_hi:[0,1]
	v_pk_add_f32 v[184:185], v[180:181], v[176:177] op_sel_hi:[1,0] neg_lo:[0,1] neg_hi:[0,1]
	v_mov_b32_e32 v180, v181
	v_mov_b32_e32 v181, v175
	v_pk_mov_b32 v[176:177], v[172:173], v[176:177] op_sel:[1,0]
	v_mov_b32_e32 v179, v172
	v_pk_add_f32 v[176:177], v[180:181], v[176:177] neg_lo:[0,1] neg_hi:[0,1]
	v_mov_b32_e32 v184, v182
	v_pk_add_f32 v[172:173], v[178:179], v[176:177] neg_lo:[0,1] neg_hi:[0,1]
	v_mov_b32_e32 v183, v175
	v_pk_add_f32 v[176:177], v[184:185], v[172:173]
	s_nop 0
	v_pk_add_f32 v[178:179], v[176:177], v[176:177] op_sel:[0,1] op_sel_hi:[1,0]
	s_nop 0
	v_pk_add_f32 v[174:175], v[174:175], v[178:179] op_sel:[1,0] op_sel_hi:[0,1]
	v_mov_b32_e32 v177, v174
	v_pk_add_f32 v[180:181], v[176:177], v[182:183] neg_lo:[0,1] neg_hi:[0,1]
	v_mov_b32_e32 v173, v178
	v_sub_f32_e32 v151, v176, v180
	v_pk_add_f32 v[172:173], v[172:173], v[180:181] neg_lo:[0,1] neg_hi:[0,1]
	v_sub_f32_e32 v151, v182, v151
	v_add_f32_e32 v151, v172, v151
	v_add_f32_e32 v151, v151, v173
	v_add_f32_e32 v151, v174, v151
	v_cndmask_b32_e32 v151, v167, v151, vcc
	v_cmp_ngt_f32_e32 vcc, -1.0, v136
	s_nop 1
	v_cndmask_b32_e32 v151, v168, v151, vcc
	v_cmp_neq_f32_e32 vcc, -1.0, v136
	s_nop 1
	v_cndmask_b32_e32 v151, v169, v151, vcc
	v_cmp_lt_f32_e64 vcc, |v136|, s71
	s_nop 1
	v_cndmask_b32_e32 v136, v151, v136, vcc
;     __device__ __forceinline__ void operator()(const f32x4 (&acc)[2][2][4][2], const Unit& u, int wr, int wc, int fr, int fq) const {
;     ...
;                         for (int i = 0; i < 4; ++i) { float x0 = v0[i] + dt_bias[c0 + i], x1 = v1[i] + dt_bias[c0 + 4 + i];
;                             dp[i] = x0 > 20.f ? x0 : log1pf(__expf(x0)); dp[4 + i] = x1 > 20.f ? x1 : log1pf(__expf(x1)); }
.LBB0_855:
	s_or_b64 exec, exec, s[24:25]
	global_store_dword v[154:155], v136, off offset:20
	global_load_dword v136, v[140:141], off offset:8
	s_waitcnt vmcnt(0)
	v_add_f32_e32 v151, v62, v136
	global_load_dword v136, v[140:141], off offset:24
	v_cmp_nlt_f32_e32 vcc, s67, v151
	s_and_saveexec_b64 s[24:25], vcc
	s_cbranch_execz .LBB0_857
	v_mul_f32_e32 v151, 0x3fb8aa3b, v151
	v_exp_f32_e32 v156, v151
	s_nop 0
	v_add_f32_e32 v151, 1.0, v156
	v_frexp_mant_f32_e32 v175, v151
	v_cvt_f64_f32_e32 v[172:173], v151
	v_add_f32_e32 v174, -1.0, v151
	v_frexp_exp_i32_f64_e32 v172, v[172:173]
	v_cmp_gt_f32_e32 vcc, s68, v175
	v_sub_f32_e32 v176, v174, v151
	v_sub_f32_e32 v174, v156, v174
	v_subbrev_co_u32_e32 v180, vcc, 0, v172, vcc
	v_add_f32_e32 v176, 1.0, v176
	v_sub_u32_e32 v172, 0, v180
	v_add_f32_e32 v174, v174, v176
	v_ldexp_f32 v151, v151, v172
	v_ldexp_f32 v172, v174, v172
	v_add_f32_e32 v174, -1.0, v151
	v_add_f32_e32 v173, 1.0, v174
	v_sub_f32_e32 v173, v151, v173
	v_add_f32_e32 v175, v172, v173
	v_add_f32_e32 v173, 1.0, v151
	v_add_f32_e32 v176, -1.0, v173
	v_sub_f32_e32 v151, v151, v176
	v_add_f32_e32 v151, v172, v151
	v_add_f32_e32 v181, v173, v151
	v_rcp_f32_e32 v182, v181
	v_sub_f32_e32 v172, v181, v173
	v_add_f32_e32 v173, v174, v175
	v_sub_f32_e32 v151, v151, v172
	v_mul_f32_e32 v184, v173, v182
	v_sub_f32_e32 v172, v173, v174
	v_mul_f32_e32 v174, v181, v184
	v_fma_f32 v176, v184, v181, -v174
	v_fmac_f32_e32 v176, v184, v151
	v_sub_f32_e32 v183, v175, v172
	v_add_f32_e32 v172, v174, v176
	v_sub_f32_e32 v175, v173, v172
	v_pk_add_f32 v[178:179], v[172:173], v[174:175] neg_lo:[0,1] neg_hi:[0,1]
	v_mov_b32_e32 v177, v172
	v_pk_add_f32 v[172:173], v[178:179], v[176:177] neg_lo:[0,1] neg_hi:[0,1]
	v_cmp_neq_f32_e32 vcc, s70, v156
	v_add_f32_e32 v173, v183, v173
	v_add_f32_e32 v172, v172, v173
	v_add_f32_e32 v173, v175, v172
	v_mul_f32_e32 v183, v182, v173
	v_mul_f32_e32 v174, v181, v183
	v_fma_f32 v176, v183, v181, -v174
	v_fmac_f32_e32 v176, v183, v151
	v_sub_f32_e32 v151, v175, v173
	v_add_f32_e32 v151, v172, v151
	v_add_f32_e32 v172, v174, v176
	v_sub_f32_e32 v175, v173, v172
	v_pk_add_f32 v[178:179], v[172:173], v[174:175] neg_lo:[0,1] neg_hi:[0,1]
	v_mov_b32_e32 v177, v172
	v_pk_add_f32 v[172:173], v[178:179], v[176:177] neg_lo:[0,1] neg_hi:[0,1]
	s_nop 0
	v_add_f32_e32 v151, v151, v173
	v_add_f32_e32 v151, v172, v151
	v_add_f32_e32 v173, v184, v183
	v_add_f32_e32 v151, v175, v151
	v_sub_f32_e32 v172, v173, v184
	v_mul_f32_e32 v151, v182, v151
	v_sub_f32_e32 v172, v183, v172
	v_add_f32_e32 v174, v172, v151
	v_add_f32_e32 v176, v173, v174
	v_cvt_f32_i32_e32 v172, v180
	v_mul_f32_e32 v177, v176, v176
	v_sub_f32_e32 v173, v176, v173
	v_fmamk_f32 v151, v177, 0x3e9b6dac, v166
	v_sub_f32_e32 v173, v174, v173
	v_fmaak_f32 v151, v177, v151, 0x3f2aaada
	v_ldexp_f32 v178, v173, 1
	v_mul_f32_e32 v173, v176, v177
	v_ldexp_f32 v175, v176, 1
	v_pk_mul_f32 v[176:177], v[172:173], v[150:151]
	s_nop 0
	v_fma_f32 v174, v172, s69, -v176
	v_fmac_f32_e32 v174, 0xb102e308, v172
	v_pk_add_f32 v[172:173], v[176:177], v[174:175]
	s_nop 0
	v_sub_f32_e32 v151, v173, v175
	v_sub_f32_e32 v151, v177, v151
	v_add_f32_e32 v179, v178, v151
	v_mov_b32_e32 v178, v176
	v_pk_add_f32 v[176:177], v[172:173], v[176:177] neg_lo:[0,1] neg_hi:[0,1]
	v_pk_add_f32 v[180:181], v[172:173], v[178:179]
	v_mov_b32_e32 v175, v172
	v_mov_b32_e32 v177, v181
	v_pk_add_f32 v[182:183], v[174:175], v[176:177] neg_lo:[0,1] neg_hi:[0,1]
	v_pk_add_f32 v[174:175], v[174:175], v[176:177]
	v_mov_b32_e32 v178, v179
	v_pk_add_f32 v[176:177], v[174:175], v[172:173] op_sel:[1,0] op_sel_hi:[0,1] neg_lo:[0,1] neg_hi:[0,1]
	v_pk_add_f32 v[184:185], v[180:181], v[176:177] op_sel_hi:[1,0] neg_lo:[0,1] neg_hi:[0,1]
	v_mov_b32_e32 v180, v181
	v_mov_b32_e32 v181, v175
	v_pk_mov_b32 v[176:177], v[172:173], v[176:177] op_sel:[1,0]
	v_mov_b32_e32 v179, v172
	v_pk_add_f32 v[176:177], v[180:181], v[176:177] neg_lo:[0,1] neg_hi:[0,1]
	v_mov_b32_e32 v184, v182
	v_pk_add_f32 v[172:173], v[178:179], v[176:177] neg_lo:[0,1] neg_hi:[0,1]
	v_mov_b32_e32 v183, v175
	v_pk_add_f32 v[176:177], v[184:185], v[172:173]
	s_nop 0
	v_pk_add_f32 v[178:179], v[176:177], v[176:177] op_sel:[0,1] op_sel_hi:[1,0]
	s_nop 0
	v_pk_add_f32 v[174:175], v[174:175], v[178:179] op_sel:[1,0] op_sel_hi:[0,1]
	v_mov_b32_e32 v177, v174
	v_pk_add_f32 v[180:181], v[176:177], v[182:183] neg_lo:[0,1] neg_hi:[0,1]
	v_mov_b32_e32 v173, v178
	v_sub_f32_e32 v151, v176, v180
	v_pk_add_f32 v[172:173], v[172:173], v[180:181] neg_lo:[0,1] neg_hi:[0,1]
	v_sub_f32_e32 v151, v182, v151
	v_add_f32_e32 v151, v172, v151
	v_add_f32_e32 v151, v151, v173
	v_add_f32_e32 v151, v174, v151
	v_cndmask_b32_e32 v151, v167, v151, vcc
	v_cmp_ngt_f32_e32 vcc, -1.0, v156
	s_nop 1
	v_cndmask_b32_e32 v151, v168, v151, vcc
	v_cmp_neq_f32_e32 vcc, -1.0, v156
	s_nop 1
	v_cndmask_b32_e32 v151, v169, v151, vcc
	v_cmp_lt_f32_e64 vcc, |v156|, s71
	s_nop 1
	v_cndmask_b32_e32 v151, v151, v156, vcc
;     __device__ __forceinline__ void operator()(const f32x4 (&acc)[2][2][4][2], const Unit& u, int wr, int wc, int fr, int fq) const {
;     ...
;                         for (int i = 0; i < 4; ++i) { float x0 = v0[i] + dt_bias[c0 + i], x1 = v1[i] + dt_bias[c0 + 4 + i];
;                             dp[i] = x0 > 20.f ? x0 : log1pf(__expf(x0)); dp[4 + i] = x1 > 20.f ? x1 : log1pf(__expf(x1)); }
.LBB0_857:
	s_or_b64 exec, exec, s[24:25]
	s_waitcnt vmcnt(0)
	v_add_f32_e32 v136, v58, v136
	v_cmp_nlt_f32_e32 vcc, s67, v136
	global_store_dword v[154:155], v151, off offset:8
	s_and_saveexec_b64 s[24:25], vcc
	s_cbranch_execz .LBB0_859
	v_mul_f32_e32 v136, 0x3fb8aa3b, v136
	v_exp_f32_e32 v136, v136
	s_nop 0
	v_add_f32_e32 v151, 1.0, v136
	v_frexp_mant_f32_e32 v174, v151
	v_cvt_f64_f32_e32 v[172:173], v151
	v_add_f32_e32 v156, -1.0, v151
	v_frexp_exp_i32_f64_e32 v172, v[172:173]
	v_cmp_gt_f32_e32 vcc, s68, v174
	v_sub_f32_e32 v175, v156, v151
	v_sub_f32_e32 v156, v136, v156
	v_subbrev_co_u32_e32 v180, vcc, 0, v172, vcc
	v_add_f32_e32 v175, 1.0, v175
	v_sub_u32_e32 v172, 0, v180
	v_add_f32_e32 v156, v156, v175
	v_ldexp_f32 v151, v151, v172
	v_ldexp_f32 v156, v156, v172
	v_add_f32_e32 v172, -1.0, v151
	v_add_f32_e32 v173, 1.0, v172
	v_sub_f32_e32 v173, v151, v173
	v_add_f32_e32 v174, v156, v173
	v_add_f32_e32 v173, 1.0, v151
	v_add_f32_e32 v175, -1.0, v173
	v_sub_f32_e32 v151, v151, v175
	v_add_f32_e32 v151, v156, v151
	v_add_f32_e32 v156, v173, v151
	v_rcp_f32_e32 v181, v156
	v_sub_f32_e32 v173, v156, v173
	v_sub_f32_e32 v151, v151, v173
	v_add_f32_e32 v173, v172, v174
	v_sub_f32_e32 v172, v173, v172
	v_mul_f32_e32 v183, v173, v181
	v_sub_f32_e32 v182, v174, v172
	v_mul_f32_e32 v174, v156, v183
	v_fma_f32 v176, v183, v156, -v174
	v_fmac_f32_e32 v176, v183, v151
	v_add_f32_e32 v172, v174, v176
	v_sub_f32_e32 v175, v173, v172
	v_pk_add_f32 v[178:179], v[172:173], v[174:175] neg_lo:[0,1] neg_hi:[0,1]
	v_mov_b32_e32 v177, v172
	v_pk_add_f32 v[172:173], v[178:179], v[176:177] neg_lo:[0,1] neg_hi:[0,1]
	v_cmp_neq_f32_e32 vcc, s70, v136
	v_add_f32_e32 v173, v182, v173
	v_add_f32_e32 v172, v172, v173
	v_add_f32_e32 v173, v175, v172
	v_mul_f32_e32 v182, v181, v173
	v_mul_f32_e32 v174, v156, v182
	v_fma_f32 v176, v182, v156, -v174
	v_fmac_f32_e32 v176, v182, v151
	v_sub_f32_e32 v151, v175, v173
	v_add_f32_e32 v151, v172, v151
	v_add_f32_e32 v172, v174, v176
	v_sub_f32_e32 v175, v173, v172
	v_pk_add_f32 v[178:179], v[172:173], v[174:175] neg_lo:[0,1] neg_hi:[0,1]
	v_mov_b32_e32 v177, v172
	v_pk_add_f32 v[172:173], v[178:179], v[176:177] neg_lo:[0,1] neg_hi:[0,1]
	v_add_f32_e32 v156, v183, v182
	v_add_f32_e32 v151, v151, v173
	v_add_f32_e32 v151, v172, v151
	v_add_f32_e32 v151, v175, v151
	v_sub_f32_e32 v172, v156, v183
	v_mul_f32_e32 v151, v181, v151
	v_sub_f32_e32 v172, v182, v172
	v_add_f32_e32 v173, v172, v151
	v_add_f32_e32 v174, v156, v173
	v_cvt_f32_i32_e32 v172, v180
	v_mul_f32_e32 v176, v174, v174
	v_fmamk_f32 v151, v176, 0x3e9b6dac, v166
	v_sub_f32_e32 v156, v174, v156
	v_fmaak_f32 v151, v176, v151, 0x3f2aaada
	v_sub_f32_e32 v156, v173, v156
	v_mul_f32_e32 v173, v174, v176
	v_pk_mul_f32 v[176:177], v[172:173], v[150:151]
	v_ldexp_f32 v175, v174, 1
	v_fma_f32 v174, v172, s69, -v176
	v_fmac_f32_e32 v174, 0xb102e308, v172
	v_pk_add_f32 v[172:173], v[176:177], v[174:175]
	v_ldexp_f32 v156, v156, 1
	v_sub_f32_e32 v151, v173, v175
	v_sub_f32_e32 v151, v177, v151
	v_add_f32_e32 v179, v156, v151
	v_mov_b32_e32 v178, v176
	v_pk_add_f32 v[176:177], v[172:173], v[176:177] neg_lo:[0,1] neg_hi:[0,1]
	v_pk_add_f32 v[180:181], v[172:173], v[178:179]
	v_mov_b32_e32 v175, v172
	v_mov_b32_e32 v177, v181
	v_pk_add_f32 v[182:183], v[174:175], v[176:177] neg_lo:[0,1] neg_hi:[0,1]
	v_pk_add_f32 v[174:175], v[174:175], v[176:177]
	v_mov_b32_e32 v178, v179
	v_pk_add_f32 v[176:177], v[174:175], v[172:173] op_sel:[1,0] op_sel_hi:[0,1] neg_lo:[0,1] neg_hi:[0,1]
	v_pk_add_f32 v[184:185], v[180:181], v[176:177] op_sel_hi:[1,0] neg_lo:[0,1] neg_hi:[0,1]
	v_mov_b32_e32 v180, v181
	v_mov_b32_e32 v181, v175
	v_pk_mov_b32 v[176:177], v[172:173], v[176:177] op_sel:[1,0]
	v_mov_b32_e32 v179, v172
	v_pk_add_f32 v[176:177], v[180:181], v[176:177] neg_lo:[0,1] neg_hi:[0,1]
	v_mov_b32_e32 v184, v182
	v_pk_add_f32 v[172:173], v[178:179], v[176:177] neg_lo:[0,1] neg_hi:[0,1]
	v_mov_b32_e32 v183, v175
	v_pk_add_f32 v[176:177], v[184:185], v[172:173]
	s_nop 0
	v_pk_add_f32 v[178:179], v[176:177], v[176:177] op_sel:[0,1] op_sel_hi:[1,0]
	s_nop 0
	v_pk_add_f32 v[174:175], v[174:175], v[178:179] op_sel:[1,0] op_sel_hi:[0,1]
	v_mov_b32_e32 v177, v174
	v_pk_add_f32 v[180:181], v[176:177], v[182:183] neg_lo:[0,1] neg_hi:[0,1]
	v_mov_b32_e32 v173, v178
	v_sub_f32_e32 v151, v176, v180
	v_pk_add_f32 v[172:173], v[172:173], v[180:181] neg_lo:[0,1] neg_hi:[0,1]
	v_sub_f32_e32 v151, v182, v151
	v_add_f32_e32 v151, v172, v151
	v_add_f32_e32 v151, v151, v173
	v_add_f32_e32 v151, v174, v151
	v_cndmask_b32_e32 v151, v167, v151, vcc
	v_cmp_ngt_f32_e32 vcc, -1.0, v136
	s_nop 1
	v_cndmask_b32_e32 v151, v168, v151, vcc
	v_cmp_neq_f32_e32 vcc, -1.0, v136
	s_nop 1
	v_cndmask_b32_e32 v151, v169, v151, vcc
	v_cmp_lt_f32_e64 vcc, |v136|, s71
	s_nop 1
	v_cndmask_b32_e32 v136, v151, v136, vcc
;     __device__ __forceinline__ void operator()(const f32x4 (&acc)[2][2][4][2], const Unit& u, int wr, int wc, int fr, int fq) const {
;     ...
;                         for (int i = 0; i < 4; ++i) { float x0 = v0[i] + dt_bias[c0 + i], x1 = v1[i] + dt_bias[c0 + 4 + i];
;                             dp[i] = x0 > 20.f ? x0 : log1pf(__expf(x0)); dp[4 + i] = x1 > 20.f ? x1 : log1pf(__expf(x1)); }
.LBB0_859:
	s_or_b64 exec, exec, s[24:25]
	global_store_dword v[154:155], v136, off offset:24
	global_load_dword v136, v[140:141], off offset:12
	s_waitcnt vmcnt(0)
	v_add_f32_e32 v151, v63, v136
	global_load_dword v136, v[140:141], off offset:28
	v_cmp_nlt_f32_e32 vcc, s67, v151
	s_and_saveexec_b64 s[24:25], vcc
	s_cbranch_execz .LBB0_861
	v_mul_f32_e32 v151, 0x3fb8aa3b, v151
	v_exp_f32_e32 v156, v151
	s_nop 0
	v_add_f32_e32 v151, 1.0, v156
	v_frexp_mant_f32_e32 v175, v151
	v_cvt_f64_f32_e32 v[172:173], v151
	v_add_f32_e32 v174, -1.0, v151
	v_frexp_exp_i32_f64_e32 v172, v[172:173]
	v_cmp_gt_f32_e32 vcc, s68, v175
	v_sub_f32_e32 v176, v174, v151
	v_sub_f32_e32 v174, v156, v174
	v_subbrev_co_u32_e32 v180, vcc, 0, v172, vcc
	v_add_f32_e32 v176, 1.0, v176
	v_sub_u32_e32 v172, 0, v180
	v_add_f32_e32 v174, v174, v176
	v_ldexp_f32 v151, v151, v172
	v_ldexp_f32 v172, v174, v172
	v_add_f32_e32 v174, -1.0, v151
	v_add_f32_e32 v173, 1.0, v174
	v_sub_f32_e32 v173, v151, v173
	v_add_f32_e32 v175, v172, v173
	v_add_f32_e32 v173, 1.0, v151
	v_add_f32_e32 v176, -1.0, v173
	v_sub_f32_e32 v151, v151, v176
	v_add_f32_e32 v151, v172, v151
	v_add_f32_e32 v181, v173, v151
	v_rcp_f32_e32 v182, v181
	v_sub_f32_e32 v172, v181, v173
	v_add_f32_e32 v173, v174, v175
	v_sub_f32_e32 v151, v151, v172
	v_mul_f32_e32 v184, v173, v182
	v_sub_f32_e32 v172, v173, v174
	v_mul_f32_e32 v174, v181, v184
	v_fma_f32 v176, v184, v181, -v174
	v_fmac_f32_e32 v176, v184, v151
	v_sub_f32_e32 v183, v175, v172
	v_add_f32_e32 v172, v174, v176
	v_sub_f32_e32 v175, v173, v172
	v_pk_add_f32 v[178:179], v[172:173], v[174:175] neg_lo:[0,1] neg_hi:[0,1]
	v_mov_b32_e32 v177, v172
	v_pk_add_f32 v[172:173], v[178:179], v[176:177] neg_lo:[0,1] neg_hi:[0,1]
	v_cmp_neq_f32_e32 vcc, s70, v156
	v_add_f32_e32 v173, v183, v173
	v_add_f32_e32 v172, v172, v173
	v_add_f32_e32 v173, v175, v172
	v_mul_f32_e32 v183, v182, v173
	v_mul_f32_e32 v174, v181, v183
	v_fma_f32 v176, v183, v181, -v174
	v_fmac_f32_e32 v176, v183, v151
	v_sub_f32_e32 v151, v175, v173
	v_add_f32_e32 v151, v172, v151
	v_add_f32_e32 v172, v174, v176
	v_sub_f32_e32 v175, v173, v172
	v_pk_add_f32 v[178:179], v[172:173], v[174:175] neg_lo:[0,1] neg_hi:[0,1]
	v_mov_b32_e32 v177, v172
	v_pk_add_f32 v[172:173], v[178:179], v[176:177] neg_lo:[0,1] neg_hi:[0,1]
	s_nop 0
	v_add_f32_e32 v151, v151, v173
	v_add_f32_e32 v151, v172, v151
	v_add_f32_e32 v173, v184, v183
	v_add_f32_e32 v151, v175, v151
	v_sub_f32_e32 v172, v173, v184
	v_mul_f32_e32 v151, v182, v151
	v_sub_f32_e32 v172, v183, v172
	v_add_f32_e32 v174, v172, v151
	v_add_f32_e32 v176, v173, v174
	v_cvt_f32_i32_e32 v172, v180
	v_mul_f32_e32 v177, v176, v176
	v_sub_f32_e32 v173, v176, v173
	v_fmamk_f32 v151, v177, 0x3e9b6dac, v166
	v_sub_f32_e32 v173, v174, v173
	v_fmaak_f32 v151, v177, v151, 0x3f2aaada
	v_ldexp_f32 v178, v173, 1
	v_mul_f32_e32 v173, v176, v177
	v_ldexp_f32 v175, v176, 1
	v_pk_mul_f32 v[176:177], v[172:173], v[150:151]
	s_nop 0
	v_fma_f32 v174, v172, s69, -v176
	v_fmac_f32_e32 v174, 0xb102e308, v172
	v_pk_add_f32 v[172:173], v[176:177], v[174:175]
	s_nop 0
	v_sub_f32_e32 v151, v173, v175
	v_sub_f32_e32 v151, v177, v151
	v_add_f32_e32 v179, v178, v151
	v_mov_b32_e32 v178, v176
	v_pk_add_f32 v[176:177], v[172:173], v[176:177] neg_lo:[0,1] neg_hi:[0,1]
	v_pk_add_f32 v[180:181], v[172:173], v[178:179]
	v_mov_b32_e32 v175, v172
	v_mov_b32_e32 v177, v181
	v_pk_add_f32 v[182:183], v[174:175], v[176:177] neg_lo:[0,1] neg_hi:[0,1]
	v_pk_add_f32 v[174:175], v[174:175], v[176:177]
	v_mov_b32_e32 v178, v179
	v_pk_add_f32 v[176:177], v[174:175], v[172:173] op_sel:[1,0] op_sel_hi:[0,1] neg_lo:[0,1] neg_hi:[0,1]
	v_pk_add_f32 v[184:185], v[180:181], v[176:177] op_sel_hi:[1,0] neg_lo:[0,1] neg_hi:[0,1]
	v_mov_b32_e32 v180, v181
	v_mov_b32_e32 v181, v175
	v_pk_mov_b32 v[176:177], v[172:173], v[176:177] op_sel:[1,0]
	v_mov_b32_e32 v179, v172
	v_pk_add_f32 v[176:177], v[180:181], v[176:177] neg_lo:[0,1] neg_hi:[0,1]
	v_mov_b32_e32 v184, v182
	v_pk_add_f32 v[172:173], v[178:179], v[176:177] neg_lo:[0,1] neg_hi:[0,1]
	v_mov_b32_e32 v183, v175
	v_pk_add_f32 v[176:177], v[184:185], v[172:173]
	s_nop 0
	v_pk_add_f32 v[178:179], v[176:177], v[176:177] op_sel:[0,1] op_sel_hi:[1,0]
	s_nop 0
	v_pk_add_f32 v[174:175], v[174:175], v[178:179] op_sel:[1,0] op_sel_hi:[0,1]
	v_mov_b32_e32 v177, v174
	v_pk_add_f32 v[180:181], v[176:177], v[182:183] neg_lo:[0,1] neg_hi:[0,1]
	v_mov_b32_e32 v173, v178
	v_sub_f32_e32 v151, v176, v180
	v_pk_add_f32 v[172:173], v[172:173], v[180:181] neg_lo:[0,1] neg_hi:[0,1]
	v_sub_f32_e32 v151, v182, v151
	v_add_f32_e32 v151, v172, v151
	v_add_f32_e32 v151, v151, v173
	v_add_f32_e32 v151, v174, v151
	v_cndmask_b32_e32 v151, v167, v151, vcc
	v_cmp_ngt_f32_e32 vcc, -1.0, v156
	s_nop 1
	v_cndmask_b32_e32 v151, v168, v151, vcc
	v_cmp_neq_f32_e32 vcc, -1.0, v156
	s_nop 1
	v_cndmask_b32_e32 v151, v169, v151, vcc
	v_cmp_lt_f32_e64 vcc, |v156|, s71
	s_nop 1
	v_cndmask_b32_e32 v151, v151, v156, vcc
;     __device__ __forceinline__ void operator()(const f32x4 (&acc)[2][2][4][2], const Unit& u, int wr, int wc, int fr, int fq) const {
;     ...
;                         for (int i = 0; i < 4; ++i) { float x0 = v0[i] + dt_bias[c0 + i], x1 = v1[i] + dt_bias[c0 + 4 + i];
;                             dp[i] = x0 > 20.f ? x0 : log1pf(__expf(x0)); dp[4 + i] = x1 > 20.f ? x1 : log1pf(__expf(x1)); }
.LBB0_861:
	s_or_b64 exec, exec, s[24:25]
	s_waitcnt vmcnt(0)
	v_add_f32_e32 v136, v59, v136
	v_cmp_nlt_f32_e32 vcc, s67, v136
	global_store_dword v[154:155], v151, off offset:12
	s_and_saveexec_b64 s[24:25], vcc
	s_cbranch_execz .LBB0_863
	v_mul_f32_e32 v136, 0x3fb8aa3b, v136
	v_exp_f32_e32 v136, v136
	s_nop 0
	v_add_f32_e32 v151, 1.0, v136
	v_frexp_mant_f32_e32 v174, v151
	v_cvt_f64_f32_e32 v[172:173], v151
	v_add_f32_e32 v156, -1.0, v151
	v_frexp_exp_i32_f64_e32 v172, v[172:173]
	v_cmp_gt_f32_e32 vcc, s68, v174
	v_sub_f32_e32 v175, v156, v151
	v_sub_f32_e32 v156, v136, v156
	v_subbrev_co_u32_e32 v180, vcc, 0, v172, vcc
	v_add_f32_e32 v175, 1.0, v175
	v_sub_u32_e32 v172, 0, v180
	v_add_f32_e32 v156, v156, v175
	v_ldexp_f32 v151, v151, v172
	v_ldexp_f32 v156, v156, v172
	v_add_f32_e32 v172, -1.0, v151
	v_add_f32_e32 v173, 1.0, v172
	v_sub_f32_e32 v173, v151, v173
	v_add_f32_e32 v174, v156, v173
	v_add_f32_e32 v173, 1.0, v151
	v_add_f32_e32 v175, -1.0, v173
	v_sub_f32_e32 v151, v151, v175
	v_add_f32_e32 v151, v156, v151
	v_add_f32_e32 v156, v173, v151
	v_rcp_f32_e32 v181, v156
	v_sub_f32_e32 v173, v156, v173
	v_sub_f32_e32 v151, v151, v173
	v_add_f32_e32 v173, v172, v174
	v_sub_f32_e32 v172, v173, v172
	v_mul_f32_e32 v183, v173, v181
	v_sub_f32_e32 v182, v174, v172
	v_mul_f32_e32 v174, v156, v183
	v_fma_f32 v176, v183, v156, -v174
	v_fmac_f32_e32 v176, v183, v151
	v_add_f32_e32 v172, v174, v176
	v_sub_f32_e32 v175, v173, v172
	v_pk_add_f32 v[178:179], v[172:173], v[174:175] neg_lo:[0,1] neg_hi:[0,1]
	v_mov_b32_e32 v177, v172
	v_pk_add_f32 v[172:173], v[178:179], v[176:177] neg_lo:[0,1] neg_hi:[0,1]
	v_cmp_neq_f32_e32 vcc, s70, v136
	v_add_f32_e32 v173, v182, v173
	v_add_f32_e32 v172, v172, v173
	v_add_f32_e32 v173, v175, v172
	v_mul_f32_e32 v182, v181, v173
	v_mul_f32_e32 v174, v156, v182
	v_fma_f32 v176, v182, v156, -v174
	v_fmac_f32_e32 v176, v182, v151
	v_sub_f32_e32 v151, v175, v173
	v_add_f32_e32 v151, v172, v151
	v_add_f32_e32 v172, v174, v176
	v_sub_f32_e32 v175, v173, v172
	v_pk_add_f32 v[178:179], v[172:173], v[174:175] neg_lo:[0,1] neg_hi:[0,1]
	v_mov_b32_e32 v177, v172
	v_pk_add_f32 v[172:173], v[178:179], v[176:177] neg_lo:[0,1] neg_hi:[0,1]
	v_add_f32_e32 v156, v183, v182
	v_add_f32_e32 v151, v151, v173
	v_add_f32_e32 v151, v172, v151
	v_add_f32_e32 v151, v175, v151
	v_sub_f32_e32 v172, v156, v183
	v_mul_f32_e32 v151, v181, v151
	v_sub_f32_e32 v172, v182, v172
	v_add_f32_e32 v173, v172, v151
	v_add_f32_e32 v174, v156, v173
	v_cvt_f32_i32_e32 v172, v180
	v_mul_f32_e32 v176, v174, v174
	v_fmamk_f32 v151, v176, 0x3e9b6dac, v166
	v_sub_f32_e32 v156, v174, v156
	v_fmaak_f32 v151, v176, v151, 0x3f2aaada
	v_sub_f32_e32 v156, v173, v156
	v_mul_f32_e32 v173, v174, v176
	v_pk_mul_f32 v[176:177], v[172:173], v[150:151]
	v_ldexp_f32 v175, v174, 1
	v_fma_f32 v174, v172, s69, -v176
	v_fmac_f32_e32 v174, 0xb102e308, v172
	v_pk_add_f32 v[172:173], v[176:177], v[174:175]
	v_ldexp_f32 v156, v156, 1
	v_sub_f32_e32 v151, v173, v175
	v_sub_f32_e32 v151, v177, v151
	v_add_f32_e32 v179, v156, v151
	v_mov_b32_e32 v178, v176
	v_pk_add_f32 v[176:177], v[172:173], v[176:177] neg_lo:[0,1] neg_hi:[0,1]
	v_pk_add_f32 v[180:181], v[172:173], v[178:179]
	v_mov_b32_e32 v175, v172
	v_mov_b32_e32 v177, v181
	v_pk_add_f32 v[182:183], v[174:175], v[176:177] neg_lo:[0,1] neg_hi:[0,1]
	v_pk_add_f32 v[174:175], v[174:175], v[176:177]
	v_mov_b32_e32 v178, v179
	v_pk_add_f32 v[176:177], v[174:175], v[172:173] op_sel:[1,0] op_sel_hi:[0,1] neg_lo:[0,1] neg_hi:[0,1]
	v_pk_add_f32 v[184:185], v[180:181], v[176:177] op_sel_hi:[1,0] neg_lo:[0,1] neg_hi:[0,1]
	v_mov_b32_e32 v180, v181
	v_mov_b32_e32 v181, v175
	v_pk_mov_b32 v[176:177], v[172:173], v[176:177] op_sel:[1,0]
	v_mov_b32_e32 v179, v172
	v_pk_add_f32 v[176:177], v[180:181], v[176:177] neg_lo:[0,1] neg_hi:[0,1]
	v_mov_b32_e32 v184, v182
	v_pk_add_f32 v[172:173], v[178:179], v[176:177] neg_lo:[0,1] neg_hi:[0,1]
	v_mov_b32_e32 v183, v175
	v_pk_add_f32 v[176:177], v[184:185], v[172:173]
	s_nop 0
	v_pk_add_f32 v[178:179], v[176:177], v[176:177] op_sel:[0,1] op_sel_hi:[1,0]
	s_nop 0
	v_pk_add_f32 v[174:175], v[174:175], v[178:179] op_sel:[1,0] op_sel_hi:[0,1]
	v_mov_b32_e32 v177, v174
	v_pk_add_f32 v[180:181], v[176:177], v[182:183] neg_lo:[0,1] neg_hi:[0,1]
	v_mov_b32_e32 v173, v178
	v_sub_f32_e32 v151, v176, v180
	v_pk_add_f32 v[172:173], v[172:173], v[180:181] neg_lo:[0,1] neg_hi:[0,1]
	v_sub_f32_e32 v151, v182, v151
	v_add_f32_e32 v151, v172, v151
	v_add_f32_e32 v151, v151, v173
	v_add_f32_e32 v151, v174, v151
	v_cndmask_b32_e32 v151, v167, v151, vcc
	v_cmp_ngt_f32_e32 vcc, -1.0, v136
	s_nop 1
	v_cndmask_b32_e32 v151, v168, v151, vcc
	v_cmp_neq_f32_e32 vcc, -1.0, v136
	s_nop 1
	v_cndmask_b32_e32 v151, v169, v151, vcc
	v_cmp_lt_f32_e64 vcc, |v136|, s71
	s_nop 1
	v_cndmask_b32_e32 v136, v151, v136, vcc
;     __device__ __forceinline__ void operator()(const f32x4 (&acc)[2][2][4][2], const Unit& u, int wr, int wc, int fr, int fq) const {
;     ...
;                         for (int i = 0; i < 4; ++i) { float x0 = v0[i] + dt_bias[c0 + i], x1 = v1[i] + dt_bias[c0 + 4 + i];
;                             dp[i] = x0 > 20.f ? x0 : log1pf(__expf(x0)); dp[4 + i] = x1 > 20.f ? x1 : log1pf(__expf(x1)); }
.LBB0_863:
	s_or_b64 exec, exec, s[24:25]
	global_store_dword v[154:155], v136, off offset:28
	global_load_dword v136, v[140:141], off
	s_waitcnt vmcnt(0)
	v_add_f32_e32 v151, v44, v136
	global_load_dword v136, v[140:141], off offset:16
	v_cmp_nlt_f32_e32 vcc, s67, v151
	s_and_saveexec_b64 s[24:25], vcc
	s_cbranch_execz .LBB0_865
	v_mul_f32_e32 v151, 0x3fb8aa3b, v151
	v_exp_f32_e32 v156, v151
	s_nop 0
	v_add_f32_e32 v151, 1.0, v156
	v_frexp_mant_f32_e32 v173, v151
	v_cvt_f64_f32_e32 v[154:155], v151
	v_add_f32_e32 v172, -1.0, v151
	v_frexp_exp_i32_f64_e32 v154, v[154:155]
	v_cmp_gt_f32_e32 vcc, s68, v173
	v_sub_f32_e32 v174, v172, v151
	v_sub_f32_e32 v172, v156, v172
	v_subbrev_co_u32_e32 v178, vcc, 0, v154, vcc
	v_add_f32_e32 v174, 1.0, v174
	v_sub_u32_e32 v154, 0, v178
	v_add_f32_e32 v172, v172, v174
	v_ldexp_f32 v151, v151, v154
	v_ldexp_f32 v154, v172, v154
	v_add_f32_e32 v172, -1.0, v151
	v_add_f32_e32 v155, 1.0, v172
	v_sub_f32_e32 v155, v151, v155
	v_add_f32_e32 v173, v154, v155
	v_add_f32_e32 v155, 1.0, v151
	v_add_f32_e32 v174, -1.0, v155
	v_sub_f32_e32 v151, v151, v174
	v_add_f32_e32 v151, v154, v151
	v_add_f32_e32 v179, v155, v151
	v_rcp_f32_e32 v180, v179
	v_sub_f32_e32 v154, v179, v155
	v_add_f32_e32 v155, v172, v173
	v_sub_f32_e32 v151, v151, v154
	v_mul_f32_e32 v182, v155, v180
	v_sub_f32_e32 v154, v155, v172
	v_mul_f32_e32 v172, v179, v182
	v_fma_f32 v174, v182, v179, -v172
	v_fmac_f32_e32 v174, v182, v151
	v_sub_f32_e32 v181, v173, v154
	v_add_f32_e32 v154, v172, v174
	v_sub_f32_e32 v173, v155, v154
	v_pk_add_f32 v[176:177], v[154:155], v[172:173] neg_lo:[0,1] neg_hi:[0,1]
	v_mov_b32_e32 v175, v154
	v_pk_add_f32 v[154:155], v[176:177], v[174:175] neg_lo:[0,1] neg_hi:[0,1]
	v_cmp_neq_f32_e32 vcc, s70, v156
	v_add_f32_e32 v155, v181, v155
	v_add_f32_e32 v154, v154, v155
	v_add_f32_e32 v155, v173, v154
	v_mul_f32_e32 v181, v180, v155
	v_mul_f32_e32 v172, v179, v181
	v_fma_f32 v174, v181, v179, -v172
	v_fmac_f32_e32 v174, v181, v151
	v_sub_f32_e32 v151, v173, v155
	v_add_f32_e32 v151, v154, v151
	v_add_f32_e32 v154, v172, v174
	v_sub_f32_e32 v173, v155, v154
	v_pk_add_f32 v[176:177], v[154:155], v[172:173] neg_lo:[0,1] neg_hi:[0,1]
	v_mov_b32_e32 v175, v154
	v_pk_add_f32 v[154:155], v[176:177], v[174:175] neg_lo:[0,1] neg_hi:[0,1]
	s_nop 0
	v_add_f32_e32 v151, v151, v155
	v_add_f32_e32 v151, v154, v151
	v_add_f32_e32 v155, v182, v181
	v_add_f32_e32 v151, v173, v151
	v_sub_f32_e32 v154, v155, v182
	v_mul_f32_e32 v151, v180, v151
	v_sub_f32_e32 v154, v181, v154
	v_add_f32_e32 v172, v154, v151
	v_add_f32_e32 v174, v155, v172
	v_cvt_f32_i32_e32 v154, v178
	v_mul_f32_e32 v175, v174, v174
	v_sub_f32_e32 v155, v174, v155
	v_fmamk_f32 v151, v175, 0x3e9b6dac, v166
	v_sub_f32_e32 v155, v172, v155
	v_fmaak_f32 v151, v175, v151, 0x3f2aaada
	v_ldexp_f32 v176, v155, 1
	v_mul_f32_e32 v155, v174, v175
	v_ldexp_f32 v173, v174, 1
	v_pk_mul_f32 v[174:175], v[154:155], v[150:151]
	s_nop 0
	v_fma_f32 v172, v154, s69, -v174
	v_fmac_f32_e32 v172, 0xb102e308, v154
	v_pk_add_f32 v[154:155], v[174:175], v[172:173]
	s_nop 0
	v_sub_f32_e32 v151, v155, v173
	v_sub_f32_e32 v151, v175, v151
	v_add_f32_e32 v177, v176, v151
	v_mov_b32_e32 v176, v174
	v_pk_add_f32 v[174:175], v[154:155], v[174:175] neg_lo:[0,1] neg_hi:[0,1]
	v_pk_add_f32 v[178:179], v[154:155], v[176:177]
	v_mov_b32_e32 v173, v154
	v_mov_b32_e32 v175, v179
	v_pk_add_f32 v[180:181], v[172:173], v[174:175] neg_lo:[0,1] neg_hi:[0,1]
	v_pk_add_f32 v[172:173], v[172:173], v[174:175]
	v_mov_b32_e32 v176, v177
	v_pk_add_f32 v[174:175], v[172:173], v[154:155] op_sel:[1,0] op_sel_hi:[0,1] neg_lo:[0,1] neg_hi:[0,1]
	v_pk_add_f32 v[182:183], v[178:179], v[174:175] op_sel_hi:[1,0] neg_lo:[0,1] neg_hi:[0,1]
	v_mov_b32_e32 v178, v179
	v_mov_b32_e32 v179, v173
	v_pk_mov_b32 v[174:175], v[154:155], v[174:175] op_sel:[1,0]
	v_mov_b32_e32 v177, v154
	v_pk_add_f32 v[174:175], v[178:179], v[174:175] neg_lo:[0,1] neg_hi:[0,1]
	v_mov_b32_e32 v182, v180
	v_pk_add_f32 v[154:155], v[176:177], v[174:175] neg_lo:[0,1] neg_hi:[0,1]
	v_mov_b32_e32 v181, v173
	v_pk_add_f32 v[174:175], v[182:183], v[154:155]
	s_nop 0
	v_pk_add_f32 v[176:177], v[174:175], v[174:175] op_sel:[0,1] op_sel_hi:[1,0]
	s_nop 0
	v_pk_add_f32 v[172:173], v[172:173], v[176:177] op_sel:[1,0] op_sel_hi:[0,1]
	v_mov_b32_e32 v175, v172
	v_pk_add_f32 v[178:179], v[174:175], v[180:181] neg_lo:[0,1] neg_hi:[0,1]
	v_mov_b32_e32 v155, v176
	v_sub_f32_e32 v151, v174, v178
	v_pk_add_f32 v[154:155], v[154:155], v[178:179] neg_lo:[0,1] neg_hi:[0,1]
	v_sub_f32_e32 v151, v180, v151
	v_add_f32_e32 v151, v154, v151
	v_add_f32_e32 v151, v151, v155
	v_add_f32_e32 v151, v172, v151
	v_cndmask_b32_e32 v151, v167, v151, vcc
	v_cmp_ngt_f32_e32 vcc, -1.0, v156
	s_nop 1
	v_cndmask_b32_e32 v151, v168, v151, vcc
	v_cmp_neq_f32_e32 vcc, -1.0, v156
	s_nop 1
	v_cndmask_b32_e32 v151, v169, v151, vcc
	v_cmp_lt_f32_e64 vcc, |v156|, s71
	s_nop 1
	v_cndmask_b32_e32 v151, v151, v156, vcc
;     __device__ __forceinline__ void operator()(const f32x4 (&acc)[2][2][4][2], const Unit& u, int wr, int wc, int fr, int fq) const {
;     ...
;                     for (int m = 0; m < 4; ++m) { const int r = row0 + ai * HALF + m * 16;
;                         const f32x4 v0 = acc[ai][0][m][0], v1 = acc[ai][0][m][1]; float* dp = DT + (size_t)r * 32 + c0;
; #pragma unroll
;                         for (int i = 0; i < 4; ++i) { float x0 = v0[i] + dt_bias[c0 + i], x1 = v1[i] + dt_bias[c0 + 4 + i];
;                             dp[i] = x0 > 20.f ? x0 : log1pf(__expf(x0)); dp[4 + i] = x1 > 20.f ? x1 : log1pf(__expf(x1)); }
.LBB0_865:
	s_or_b64 exec, exec, s[24:25]
	v_lshlrev_b64 v[154:155], 7, v[152:153]
	v_lshl_add_u64 v[154:155], v[138:139], 0, v[154:155]
	v_add_co_u32_e32 v172, vcc, 0x4000, v154
	s_waitcnt vmcnt(0)
	v_add_f32_e32 v136, v40, v136
	v_addc_co_u32_e32 v173, vcc, 0, v155, vcc
	v_cmp_nlt_f32_e32 vcc, s67, v136
	global_store_dword v[172:173], v151, off offset:2048
	s_and_saveexec_b64 s[24:25], vcc
	s_cbranch_execz .LBB0_867
	v_mul_f32_e32 v136, 0x3fb8aa3b, v136
	v_exp_f32_e32 v136, v136
	s_nop 0
	v_add_f32_e32 v151, 1.0, v136
	v_frexp_mant_f32_e32 v174, v151
	v_cvt_f64_f32_e32 v[172:173], v151
	v_add_f32_e32 v156, -1.0, v151
	v_frexp_exp_i32_f64_e32 v172, v[172:173]
	v_cmp_gt_f32_e32 vcc, s68, v174
	v_sub_f32_e32 v175, v156, v151
	v_sub_f32_e32 v156, v136, v156
	v_subbrev_co_u32_e32 v180, vcc, 0, v172, vcc
	v_add_f32_e32 v175, 1.0, v175
	v_sub_u32_e32 v172, 0, v180
	v_add_f32_e32 v156, v156, v175
	v_ldexp_f32 v151, v151, v172
	v_ldexp_f32 v156, v156, v172
	v_add_f32_e32 v172, -1.0, v151
	v_add_f32_e32 v173, 1.0, v172
	v_sub_f32_e32 v173, v151, v173
	v_add_f32_e32 v174, v156, v173
	v_add_f32_e32 v173, 1.0, v151
	v_add_f32_e32 v175, -1.0, v173
	v_sub_f32_e32 v151, v151, v175
	v_add_f32_e32 v151, v156, v151
	v_add_f32_e32 v156, v173, v151
	v_rcp_f32_e32 v181, v156
	v_sub_f32_e32 v173, v156, v173
	v_sub_f32_e32 v151, v151, v173
	v_add_f32_e32 v173, v172, v174
	v_sub_f32_e32 v172, v173, v172
	v_mul_f32_e32 v183, v173, v181
	v_sub_f32_e32 v182, v174, v172
	v_mul_f32_e32 v174, v156, v183
	v_fma_f32 v176, v183, v156, -v174
	v_fmac_f32_e32 v176, v183, v151
	v_add_f32_e32 v172, v174, v176
	v_sub_f32_e32 v175, v173, v172
	v_pk_add_f32 v[178:179], v[172:173], v[174:175] neg_lo:[0,1] neg_hi:[0,1]
	v_mov_b32_e32 v177, v172
	v_pk_add_f32 v[172:173], v[178:179], v[176:177] neg_lo:[0,1] neg_hi:[0,1]
	v_cmp_neq_f32_e32 vcc, s70, v136
	v_add_f32_e32 v173, v182, v173
	v_add_f32_e32 v172, v172, v173
	v_add_f32_e32 v173, v175, v172
	v_mul_f32_e32 v182, v181, v173
	v_mul_f32_e32 v174, v156, v182
	v_fma_f32 v176, v182, v156, -v174
	v_fmac_f32_e32 v176, v182, v151
	v_sub_f32_e32 v151, v175, v173
	v_add_f32_e32 v151, v172, v151
	v_add_f32_e32 v172, v174, v176
	v_sub_f32_e32 v175, v173, v172
	v_pk_add_f32 v[178:179], v[172:173], v[174:175] neg_lo:[0,1] neg_hi:[0,1]
	v_mov_b32_e32 v177, v172
	v_pk_add_f32 v[172:173], v[178:179], v[176:177] neg_lo:[0,1] neg_hi:[0,1]
	v_add_f32_e32 v156, v183, v182
	v_add_f32_e32 v151, v151, v173
	v_add_f32_e32 v151, v172, v151
	v_add_f32_e32 v151, v175, v151
	v_sub_f32_e32 v172, v156, v183
	v_mul_f32_e32 v151, v181, v151
	v_sub_f32_e32 v172, v182, v172
	v_add_f32_e32 v173, v172, v151
	v_add_f32_e32 v174, v156, v173
	v_cvt_f32_i32_e32 v172, v180
	v_mul_f32_e32 v176, v174, v174
	v_fmamk_f32 v151, v176, 0x3e9b6dac, v166
	v_sub_f32_e32 v156, v174, v156
	v_fmaak_f32 v151, v176, v151, 0x3f2aaada
	v_sub_f32_e32 v156, v173, v156
	v_mul_f32_e32 v173, v174, v176
	v_pk_mul_f32 v[176:177], v[172:173], v[150:151]
	v_ldexp_f32 v175, v174, 1
	v_fma_f32 v174, v172, s69, -v176
	v_fmac_f32_e32 v174, 0xb102e308, v172
	v_pk_add_f32 v[172:173], v[176:177], v[174:175]
	v_ldexp_f32 v156, v156, 1
	v_sub_f32_e32 v151, v173, v175
	v_sub_f32_e32 v151, v177, v151
	v_add_f32_e32 v179, v156, v151
	v_mov_b32_e32 v178, v176
	v_pk_add_f32 v[176:177], v[172:173], v[176:177] neg_lo:[0,1] neg_hi:[0,1]
	v_pk_add_f32 v[180:181], v[172:173], v[178:179]
	v_mov_b32_e32 v175, v172
	v_mov_b32_e32 v177, v181
	v_pk_add_f32 v[182:183], v[174:175], v[176:177] neg_lo:[0,1] neg_hi:[0,1]
	v_pk_add_f32 v[174:175], v[174:175], v[176:177]
	v_mov_b32_e32 v178, v179
	v_pk_add_f32 v[176:177], v[174:175], v[172:173] op_sel:[1,0] op_sel_hi:[0,1] neg_lo:[0,1] neg_hi:[0,1]
	v_pk_add_f32 v[184:185], v[180:181], v[176:177] op_sel_hi:[1,0] neg_lo:[0,1] neg_hi:[0,1]
	v_mov_b32_e32 v180, v181
	v_mov_b32_e32 v181, v175
	v_pk_mov_b32 v[176:177], v[172:173], v[176:177] op_sel:[1,0]
	v_mov_b32_e32 v179, v172
	v_pk_add_f32 v[176:177], v[180:181], v[176:177] neg_lo:[0,1] neg_hi:[0,1]
	v_mov_b32_e32 v184, v182
	v_pk_add_f32 v[172:173], v[178:179], v[176:177] neg_lo:[0,1] neg_hi:[0,1]
	v_mov_b32_e32 v183, v175
	v_pk_add_f32 v[176:177], v[184:185], v[172:173]
	s_nop 0
	v_pk_add_f32 v[178:179], v[176:177], v[176:177] op_sel:[0,1] op_sel_hi:[1,0]
	s_nop 0
	v_pk_add_f32 v[174:175], v[174:175], v[178:179] op_sel:[1,0] op_sel_hi:[0,1]
	v_mov_b32_e32 v177, v174
	v_pk_add_f32 v[180:181], v[176:177], v[182:183] neg_lo:[0,1] neg_hi:[0,1]
	v_mov_b32_e32 v173, v178
	v_sub_f32_e32 v151, v176, v180
	v_pk_add_f32 v[172:173], v[172:173], v[180:181] neg_lo:[0,1] neg_hi:[0,1]
	v_sub_f32_e32 v151, v182, v151
	v_add_f32_e32 v151, v172, v151
	v_add_f32_e32 v151, v151, v173
	v_add_f32_e32 v151, v174, v151
	v_cndmask_b32_e32 v151, v167, v151, vcc
	v_cmp_ngt_f32_e32 vcc, -1.0, v136
	s_nop 1
	v_cndmask_b32_e32 v151, v168, v151, vcc
	v_cmp_neq_f32_e32 vcc, -1.0, v136
	s_nop 1
	v_cndmask_b32_e32 v151, v169, v151, vcc
	v_cmp_lt_f32_e64 vcc, |v136|, s71
	s_nop 1
	v_cndmask_b32_e32 v136, v151, v136, vcc
;     __device__ __forceinline__ void operator()(const f32x4 (&acc)[2][2][4][2], const Unit& u, int wr, int wc, int fr, int fq) const {
;     ...
;                         for (int i = 0; i < 4; ++i) { float x0 = v0[i] + dt_bias[c0 + i], x1 = v1[i] + dt_bias[c0 + 4 + i];
;                             dp[i] = x0 > 20.f ? x0 : log1pf(__expf(x0)); dp[4 + i] = x1 > 20.f ? x1 : log1pf(__expf(x1)); }
.LBB0_867:
	s_or_b64 exec, exec, s[24:25]
	s_mov_b64 s[24:25], 0x4800
	v_lshl_add_u64 v[154:155], v[154:155], 0, s[24:25]
	global_store_dword v[154:155], v136, off offset:16
	global_load_dword v151, v[140:141], off offset:4
	s_nop 0
	global_load_dword v136, v[140:141], off offset:20
	s_waitcnt vmcnt(0)
	v_add_f32_e32 v151, v45, v151
	v_cmp_nlt_f32_e32 vcc, s67, v151
	s_and_saveexec_b64 s[24:25], vcc
	s_cbranch_execz .LBB0_869
	v_mul_f32_e32 v151, 0x3fb8aa3b, v151
	v_exp_f32_e32 v156, v151
	s_nop 0
	v_add_f32_e32 v151, 1.0, v156
	v_frexp_mant_f32_e32 v175, v151
	v_cvt_f64_f32_e32 v[172:173], v151
	v_add_f32_e32 v174, -1.0, v151
	v_frexp_exp_i32_f64_e32 v172, v[172:173]
	v_cmp_gt_f32_e32 vcc, s68, v175
	v_sub_f32_e32 v176, v174, v151
	v_sub_f32_e32 v174, v156, v174
	v_subbrev_co_u32_e32 v180, vcc, 0, v172, vcc
	v_add_f32_e32 v176, 1.0, v176
	v_sub_u32_e32 v172, 0, v180
	v_add_f32_e32 v174, v174, v176
	v_ldexp_f32 v151, v151, v172
	v_ldexp_f32 v172, v174, v172
	v_add_f32_e32 v174, -1.0, v151
	v_add_f32_e32 v173, 1.0, v174
	v_sub_f32_e32 v173, v151, v173
	v_add_f32_e32 v175, v172, v173
	v_add_f32_e32 v173, 1.0, v151
	v_add_f32_e32 v176, -1.0, v173
	v_sub_f32_e32 v151, v151, v176
	v_add_f32_e32 v151, v172, v151
	v_add_f32_e32 v181, v173, v151
	v_rcp_f32_e32 v182, v181
	v_sub_f32_e32 v172, v181, v173
	v_add_f32_e32 v173, v174, v175
	v_sub_f32_e32 v151, v151, v172
	v_mul_f32_e32 v184, v173, v182
	v_sub_f32_e32 v172, v173, v174
	v_mul_f32_e32 v174, v181, v184
	v_fma_f32 v176, v184, v181, -v174
	v_fmac_f32_e32 v176, v184, v151
	v_sub_f32_e32 v183, v175, v172
	v_add_f32_e32 v172, v174, v176
	v_sub_f32_e32 v175, v173, v172
	v_pk_add_f32 v[178:179], v[172:173], v[174:175] neg_lo:[0,1] neg_hi:[0,1]
	v_mov_b32_e32 v177, v172
	v_pk_add_f32 v[172:173], v[178:179], v[176:177] neg_lo:[0,1] neg_hi:[0,1]
	v_cmp_neq_f32_e32 vcc, s70, v156
	v_add_f32_e32 v173, v183, v173
	v_add_f32_e32 v172, v172, v173
	v_add_f32_e32 v173, v175, v172
	v_mul_f32_e32 v183, v182, v173
	v_mul_f32_e32 v174, v181, v183
	v_fma_f32 v176, v183, v181, -v174
	v_fmac_f32_e32 v176, v183, v151
	v_sub_f32_e32 v151, v175, v173
	v_add_f32_e32 v151, v172, v151
	v_add_f32_e32 v172, v174, v176
	v_sub_f32_e32 v175, v173, v172
	v_pk_add_f32 v[178:179], v[172:173], v[174:175] neg_lo:[0,1] neg_hi:[0,1]
	v_mov_b32_e32 v177, v172
	v_pk_add_f32 v[172:173], v[178:179], v[176:177] neg_lo:[0,1] neg_hi:[0,1]
	s_nop 0
	v_add_f32_e32 v151, v151, v173
	v_add_f32_e32 v151, v172, v151
	v_add_f32_e32 v173, v184, v183
	v_add_f32_e32 v151, v175, v151
	v_sub_f32_e32 v172, v173, v184
	v_mul_f32_e32 v151, v182, v151
	v_sub_f32_e32 v172, v183, v172
	v_add_f32_e32 v174, v172, v151
	v_add_f32_e32 v176, v173, v174
	v_cvt_f32_i32_e32 v172, v180
	v_mul_f32_e32 v177, v176, v176
	v_sub_f32_e32 v173, v176, v173
	v_fmamk_f32 v151, v177, 0x3e9b6dac, v166
	v_sub_f32_e32 v173, v174, v173
	v_fmaak_f32 v151, v177, v151, 0x3f2aaada
	v_ldexp_f32 v178, v173, 1
	v_mul_f32_e32 v173, v176, v177
	v_ldexp_f32 v175, v176, 1
	v_pk_mul_f32 v[176:177], v[172:173], v[150:151]
	s_nop 0
	v_fma_f32 v174, v172, s69, -v176
	v_fmac_f32_e32 v174, 0xb102e308, v172
	v_pk_add_f32 v[172:173], v[176:177], v[174:175]
	s_nop 0
	v_sub_f32_e32 v151, v173, v175
	v_sub_f32_e32 v151, v177, v151
	v_add_f32_e32 v179, v178, v151
	v_mov_b32_e32 v178, v176
	v_pk_add_f32 v[176:177], v[172:173], v[176:177] neg_lo:[0,1] neg_hi:[0,1]
	v_pk_add_f32 v[180:181], v[172:173], v[178:179]
	v_mov_b32_e32 v175, v172
	v_mov_b32_e32 v177, v181
	v_pk_add_f32 v[182:183], v[174:175], v[176:177] neg_lo:[0,1] neg_hi:[0,1]
	v_pk_add_f32 v[174:175], v[174:175], v[176:177]
	v_mov_b32_e32 v178, v179
	v_pk_add_f32 v[176:177], v[174:175], v[172:173] op_sel:[1,0] op_sel_hi:[0,1] neg_lo:[0,1] neg_hi:[0,1]
	v_pk_add_f32 v[184:185], v[180:181], v[176:177] op_sel_hi:[1,0] neg_lo:[0,1] neg_hi:[0,1]
	v_mov_b32_e32 v180, v181
	v_mov_b32_e32 v181, v175
	v_pk_mov_b32 v[176:177], v[172:173], v[176:177] op_sel:[1,0]
	v_mov_b32_e32 v179, v172
	v_pk_add_f32 v[176:177], v[180:181], v[176:177] neg_lo:[0,1] neg_hi:[0,1]
	v_mov_b32_e32 v184, v182
	v_pk_add_f32 v[172:173], v[178:179], v[176:177] neg_lo:[0,1] neg_hi:[0,1]
	v_mov_b32_e32 v183, v175
	v_pk_add_f32 v[176:177], v[184:185], v[172:173]
	s_nop 0
	v_pk_add_f32 v[178:179], v[176:177], v[176:177] op_sel:[0,1] op_sel_hi:[1,0]
	s_nop 0
	v_pk_add_f32 v[174:175], v[174:175], v[178:179] op_sel:[1,0] op_sel_hi:[0,1]
	v_mov_b32_e32 v177, v174
	v_pk_add_f32 v[180:181], v[176:177], v[182:183] neg_lo:[0,1] neg_hi:[0,1]
	v_mov_b32_e32 v173, v178
	v_sub_f32_e32 v151, v176, v180
	v_pk_add_f32 v[172:173], v[172:173], v[180:181] neg_lo:[0,1] neg_hi:[0,1]
	v_sub_f32_e32 v151, v182, v151
	v_add_f32_e32 v151, v172, v151
	v_add_f32_e32 v151, v151, v173
	v_add_f32_e32 v151, v174, v151
	v_cndmask_b32_e32 v151, v167, v151, vcc
	v_cmp_ngt_f32_e32 vcc, -1.0, v156
	s_nop 1
	v_cndmask_b32_e32 v151, v168, v151, vcc
	v_cmp_neq_f32_e32 vcc, -1.0, v156
	s_nop 1
	v_cndmask_b32_e32 v151, v169, v151, vcc
	v_cmp_lt_f32_e64 vcc, |v156|, s71
	s_nop 1
	v_cndmask_b32_e32 v151, v151, v156, vcc
;     __device__ __forceinline__ void operator()(const f32x4 (&acc)[2][2][4][2], const Unit& u, int wr, int wc, int fr, int fq) const {
;     ...
;                         for (int i = 0; i < 4; ++i) { float x0 = v0[i] + dt_bias[c0 + i], x1 = v1[i] + dt_bias[c0 + 4 + i];
;                             dp[i] = x0 > 20.f ? x0 : log1pf(__expf(x0)); dp[4 + i] = x1 > 20.f ? x1 : log1pf(__expf(x1)); }
.LBB0_869:
	s_or_b64 exec, exec, s[24:25]
	v_add_f32_e32 v136, v41, v136
	v_cmp_nlt_f32_e32 vcc, s67, v136
	global_store_dword v[154:155], v151, off offset:4
	s_and_saveexec_b64 s[24:25], vcc
	s_cbranch_execz .LBB0_871
	v_mul_f32_e32 v136, 0x3fb8aa3b, v136
	v_exp_f32_e32 v136, v136
	s_nop 0
	v_add_f32_e32 v151, 1.0, v136
	v_frexp_mant_f32_e32 v174, v151
	v_cvt_f64_f32_e32 v[172:173], v151
	v_add_f32_e32 v156, -1.0, v151
	v_frexp_exp_i32_f64_e32 v172, v[172:173]
	v_cmp_gt_f32_e32 vcc, s68, v174
	v_sub_f32_e32 v175, v156, v151
	v_sub_f32_e32 v156, v136, v156
	v_subbrev_co_u32_e32 v180, vcc, 0, v172, vcc
	v_add_f32_e32 v175, 1.0, v175
	v_sub_u32_e32 v172, 0, v180
	v_add_f32_e32 v156, v156, v175
	v_ldexp_f32 v151, v151, v172
	v_ldexp_f32 v156, v156, v172
	v_add_f32_e32 v172, -1.0, v151
	v_add_f32_e32 v173, 1.0, v172
	v_sub_f32_e32 v173, v151, v173
	v_add_f32_e32 v174, v156, v173
	v_add_f32_e32 v173, 1.0, v151
	v_add_f32_e32 v175, -1.0, v173
	v_sub_f32_e32 v151, v151, v175
	v_add_f32_e32 v151, v156, v151
	v_add_f32_e32 v156, v173, v151
	v_rcp_f32_e32 v181, v156
	v_sub_f32_e32 v173, v156, v173
	v_sub_f32_e32 v151, v151, v173
	v_add_f32_e32 v173, v172, v174
	v_sub_f32_e32 v172, v173, v172
	v_mul_f32_e32 v183, v173, v181
	v_sub_f32_e32 v182, v174, v172
	v_mul_f32_e32 v174, v156, v183
	v_fma_f32 v176, v183, v156, -v174
	v_fmac_f32_e32 v176, v183, v151
	v_add_f32_e32 v172, v174, v176
	v_sub_f32_e32 v175, v173, v172
	v_pk_add_f32 v[178:179], v[172:173], v[174:175] neg_lo:[0,1] neg_hi:[0,1]
	v_mov_b32_e32 v177, v172
	v_pk_add_f32 v[172:173], v[178:179], v[176:177] neg_lo:[0,1] neg_hi:[0,1]
	v_cmp_neq_f32_e32 vcc, s70, v136
	v_add_f32_e32 v173, v182, v173
	v_add_f32_e32 v172, v172, v173
	v_add_f32_e32 v173, v175, v172
	v_mul_f32_e32 v182, v181, v173
	v_mul_f32_e32 v174, v156, v182
	v_fma_f32 v176, v182, v156, -v174
	v_fmac_f32_e32 v176, v182, v151
	v_sub_f32_e32 v151, v175, v173
	v_add_f32_e32 v151, v172, v151
	v_add_f32_e32 v172, v174, v176
	v_sub_f32_e32 v175, v173, v172
	v_pk_add_f32 v[178:179], v[172:173], v[174:175] neg_lo:[0,1] neg_hi:[0,1]
	v_mov_b32_e32 v177, v172
	v_pk_add_f32 v[172:173], v[178:179], v[176:177] neg_lo:[0,1] neg_hi:[0,1]
	v_add_f32_e32 v156, v183, v182
	v_add_f32_e32 v151, v151, v173
	v_add_f32_e32 v151, v172, v151
	v_add_f32_e32 v151, v175, v151
	v_sub_f32_e32 v172, v156, v183
	v_mul_f32_e32 v151, v181, v151
	v_sub_f32_e32 v172, v182, v172
	v_add_f32_e32 v173, v172, v151
	v_add_f32_e32 v174, v156, v173
	v_cvt_f32_i32_e32 v172, v180
	v_mul_f32_e32 v176, v174, v174
	v_fmamk_f32 v151, v176, 0x3e9b6dac, v166
	v_sub_f32_e32 v156, v174, v156
	v_fmaak_f32 v151, v176, v151, 0x3f2aaada
	v_sub_f32_e32 v156, v173, v156
	v_mul_f32_e32 v173, v174, v176
	v_pk_mul_f32 v[176:177], v[172:173], v[150:151]
	v_ldexp_f32 v175, v174, 1
	v_fma_f32 v174, v172, s69, -v176
	v_fmac_f32_e32 v174, 0xb102e308, v172
	v_pk_add_f32 v[172:173], v[176:177], v[174:175]
	v_ldexp_f32 v156, v156, 1
	v_sub_f32_e32 v151, v173, v175
	v_sub_f32_e32 v151, v177, v151
	v_add_f32_e32 v179, v156, v151
	v_mov_b32_e32 v178, v176
	v_pk_add_f32 v[176:177], v[172:173], v[176:177] neg_lo:[0,1] neg_hi:[0,1]
	v_pk_add_f32 v[180:181], v[172:173], v[178:179]
	v_mov_b32_e32 v175, v172
	v_mov_b32_e32 v177, v181
	v_pk_add_f32 v[182:183], v[174:175], v[176:177] neg_lo:[0,1] neg_hi:[0,1]
	v_pk_add_f32 v[174:175], v[174:175], v[176:177]
	v_mov_b32_e32 v178, v179
	v_pk_add_f32 v[176:177], v[174:175], v[172:173] op_sel:[1,0] op_sel_hi:[0,1] neg_lo:[0,1] neg_hi:[0,1]
	v_pk_add_f32 v[184:185], v[180:181], v[176:177] op_sel_hi:[1,0] neg_lo:[0,1] neg_hi:[0,1]
	v_mov_b32_e32 v180, v181
	v_mov_b32_e32 v181, v175
	v_pk_mov_b32 v[176:177], v[172:173], v[176:177] op_sel:[1,0]
	v_mov_b32_e32 v179, v172
	v_pk_add_f32 v[176:177], v[180:181], v[176:177] neg_lo:[0,1] neg_hi:[0,1]
	v_mov_b32_e32 v184, v182
	v_pk_add_f32 v[172:173], v[178:179], v[176:177] neg_lo:[0,1] neg_hi:[0,1]
	v_mov_b32_e32 v183, v175
	v_pk_add_f32 v[176:177], v[184:185], v[172:173]
	s_nop 0
	v_pk_add_f32 v[178:179], v[176:177], v[176:177] op_sel:[0,1] op_sel_hi:[1,0]
	s_nop 0
	v_pk_add_f32 v[174:175], v[174:175], v[178:179] op_sel:[1,0] op_sel_hi:[0,1]
	v_mov_b32_e32 v177, v174
	v_pk_add_f32 v[180:181], v[176:177], v[182:183] neg_lo:[0,1] neg_hi:[0,1]
	v_mov_b32_e32 v173, v178
	v_sub_f32_e32 v151, v176, v180
	v_pk_add_f32 v[172:173], v[172:173], v[180:181] neg_lo:[0,1] neg_hi:[0,1]
	v_sub_f32_e32 v151, v182, v151
	v_add_f32_e32 v151, v172, v151
	v_add_f32_e32 v151, v151, v173
	v_add_f32_e32 v151, v174, v151
	v_cndmask_b32_e32 v151, v167, v151, vcc
	v_cmp_ngt_f32_e32 vcc, -1.0, v136
	s_nop 1
	v_cndmask_b32_e32 v151, v168, v151, vcc
	v_cmp_neq_f32_e32 vcc, -1.0, v136
	s_nop 1
	v_cndmask_b32_e32 v151, v169, v151, vcc
	v_cmp_lt_f32_e64 vcc, |v136|, s71
	s_nop 1
	v_cndmask_b32_e32 v136, v151, v136, vcc
;     __device__ __forceinline__ void operator()(const f32x4 (&acc)[2][2][4][2], const Unit& u, int wr, int wc, int fr, int fq) const {
;     ...
;                         for (int i = 0; i < 4; ++i) { float x0 = v0[i] + dt_bias[c0 + i], x1 = v1[i] + dt_bias[c0 + 4 + i];
;                             dp[i] = x0 > 20.f ? x0 : log1pf(__expf(x0)); dp[4 + i] = x1 > 20.f ? x1 : log1pf(__expf(x1)); }
.LBB0_871:
	s_or_b64 exec, exec, s[24:25]
	global_store_dword v[154:155], v136, off offset:20
	global_load_dword v136, v[140:141], off offset:8
	s_waitcnt vmcnt(0)
	v_add_f32_e32 v151, v46, v136
	global_load_dword v136, v[140:141], off offset:24
	v_cmp_nlt_f32_e32 vcc, s67, v151
	s_and_saveexec_b64 s[24:25], vcc
	s_cbranch_execz .LBB0_873
	v_mul_f32_e32 v151, 0x3fb8aa3b, v151
	v_exp_f32_e32 v156, v151
	s_nop 0
	v_add_f32_e32 v151, 1.0, v156
	v_frexp_mant_f32_e32 v175, v151
	v_cvt_f64_f32_e32 v[172:173], v151
	v_add_f32_e32 v174, -1.0, v151
	v_frexp_exp_i32_f64_e32 v172, v[172:173]
	v_cmp_gt_f32_e32 vcc, s68, v175
	v_sub_f32_e32 v176, v174, v151
	v_sub_f32_e32 v174, v156, v174
	v_subbrev_co_u32_e32 v180, vcc, 0, v172, vcc
	v_add_f32_e32 v176, 1.0, v176
	v_sub_u32_e32 v172, 0, v180
	v_add_f32_e32 v174, v174, v176
	v_ldexp_f32 v151, v151, v172
	v_ldexp_f32 v172, v174, v172
	v_add_f32_e32 v174, -1.0, v151
	v_add_f32_e32 v173, 1.0, v174
	v_sub_f32_e32 v173, v151, v173
	v_add_f32_e32 v175, v172, v173
	v_add_f32_e32 v173, 1.0, v151
	v_add_f32_e32 v176, -1.0, v173
	v_sub_f32_e32 v151, v151, v176
	v_add_f32_e32 v151, v172, v151
	v_add_f32_e32 v181, v173, v151
	v_rcp_f32_e32 v182, v181
	v_sub_f32_e32 v172, v181, v173
	v_add_f32_e32 v173, v174, v175
	v_sub_f32_e32 v151, v151, v172
	v_mul_f32_e32 v184, v173, v182
	v_sub_f32_e32 v172, v173, v174
	v_mul_f32_e32 v174, v181, v184
	v_fma_f32 v176, v184, v181, -v174
	v_fmac_f32_e32 v176, v184, v151
	v_sub_f32_e32 v183, v175, v172
	v_add_f32_e32 v172, v174, v176
	v_sub_f32_e32 v175, v173, v172
	v_pk_add_f32 v[178:179], v[172:173], v[174:175] neg_lo:[0,1] neg_hi:[0,1]
	v_mov_b32_e32 v177, v172
	v_pk_add_f32 v[172:173], v[178:179], v[176:177] neg_lo:[0,1] neg_hi:[0,1]
	v_cmp_neq_f32_e32 vcc, s70, v156
	v_add_f32_e32 v173, v183, v173
	v_add_f32_e32 v172, v172, v173
	v_add_f32_e32 v173, v175, v172
	v_mul_f32_e32 v183, v182, v173
	v_mul_f32_e32 v174, v181, v183
	v_fma_f32 v176, v183, v181, -v174
	v_fmac_f32_e32 v176, v183, v151
	v_sub_f32_e32 v151, v175, v173
	v_add_f32_e32 v151, v172, v151
	v_add_f32_e32 v172, v174, v176
	v_sub_f32_e32 v175, v173, v172
	v_pk_add_f32 v[178:179], v[172:173], v[174:175] neg_lo:[0,1] neg_hi:[0,1]
	v_mov_b32_e32 v177, v172
	v_pk_add_f32 v[172:173], v[178:179], v[176:177] neg_lo:[0,1] neg_hi:[0,1]
	s_nop 0
	v_add_f32_e32 v151, v151, v173
	v_add_f32_e32 v151, v172, v151
	v_add_f32_e32 v173, v184, v183
	v_add_f32_e32 v151, v175, v151
	v_sub_f32_e32 v172, v173, v184
	v_mul_f32_e32 v151, v182, v151
	v_sub_f32_e32 v172, v183, v172
	v_add_f32_e32 v174, v172, v151
	v_add_f32_e32 v176, v173, v174
	v_cvt_f32_i32_e32 v172, v180
	v_mul_f32_e32 v177, v176, v176
	v_sub_f32_e32 v173, v176, v173
	v_fmamk_f32 v151, v177, 0x3e9b6dac, v166
	v_sub_f32_e32 v173, v174, v173
	v_fmaak_f32 v151, v177, v151, 0x3f2aaada
	v_ldexp_f32 v178, v173, 1
	v_mul_f32_e32 v173, v176, v177
	v_ldexp_f32 v175, v176, 1
	v_pk_mul_f32 v[176:177], v[172:173], v[150:151]
	s_nop 0
	v_fma_f32 v174, v172, s69, -v176
	v_fmac_f32_e32 v174, 0xb102e308, v172
	v_pk_add_f32 v[172:173], v[176:177], v[174:175]
	s_nop 0
	v_sub_f32_e32 v151, v173, v175
	v_sub_f32_e32 v151, v177, v151
	v_add_f32_e32 v179, v178, v151
	v_mov_b32_e32 v178, v176
	v_pk_add_f32 v[176:177], v[172:173], v[176:177] neg_lo:[0,1] neg_hi:[0,1]
	v_pk_add_f32 v[180:181], v[172:173], v[178:179]
	v_mov_b32_e32 v175, v172
	v_mov_b32_e32 v177, v181
	v_pk_add_f32 v[182:183], v[174:175], v[176:177] neg_lo:[0,1] neg_hi:[0,1]
	v_pk_add_f32 v[174:175], v[174:175], v[176:177]
	v_mov_b32_e32 v178, v179
	v_pk_add_f32 v[176:177], v[174:175], v[172:173] op_sel:[1,0] op_sel_hi:[0,1] neg_lo:[0,1] neg_hi:[0,1]
	v_pk_add_f32 v[184:185], v[180:181], v[176:177] op_sel_hi:[1,0] neg_lo:[0,1] neg_hi:[0,1]
	v_mov_b32_e32 v180, v181
	v_mov_b32_e32 v181, v175
	v_pk_mov_b32 v[176:177], v[172:173], v[176:177] op_sel:[1,0]
	v_mov_b32_e32 v179, v172
	v_pk_add_f32 v[176:177], v[180:181], v[176:177] neg_lo:[0,1] neg_hi:[0,1]
	v_mov_b32_e32 v184, v182
	v_pk_add_f32 v[172:173], v[178:179], v[176:177] neg_lo:[0,1] neg_hi:[0,1]
	v_mov_b32_e32 v183, v175
	v_pk_add_f32 v[176:177], v[184:185], v[172:173]
	s_nop 0
	v_pk_add_f32 v[178:179], v[176:177], v[176:177] op_sel:[0,1] op_sel_hi:[1,0]
	s_nop 0
	v_pk_add_f32 v[174:175], v[174:175], v[178:179] op_sel:[1,0] op_sel_hi:[0,1]
	v_mov_b32_e32 v177, v174
	v_pk_add_f32 v[180:181], v[176:177], v[182:183] neg_lo:[0,1] neg_hi:[0,1]
	v_mov_b32_e32 v173, v178
	v_sub_f32_e32 v151, v176, v180
	v_pk_add_f32 v[172:173], v[172:173], v[180:181] neg_lo:[0,1] neg_hi:[0,1]
	v_sub_f32_e32 v151, v182, v151
	v_add_f32_e32 v151, v172, v151
	v_add_f32_e32 v151, v151, v173
	v_add_f32_e32 v151, v174, v151
	v_cndmask_b32_e32 v151, v167, v151, vcc
	v_cmp_ngt_f32_e32 vcc, -1.0, v156
	s_nop 1
	v_cndmask_b32_e32 v151, v168, v151, vcc
	v_cmp_neq_f32_e32 vcc, -1.0, v156
	s_nop 1
	v_cndmask_b32_e32 v151, v169, v151, vcc
	v_cmp_lt_f32_e64 vcc, |v156|, s71
	s_nop 1
	v_cndmask_b32_e32 v151, v151, v156, vcc
;     __device__ __forceinline__ void operator()(const f32x4 (&acc)[2][2][4][2], const Unit& u, int wr, int wc, int fr, int fq) const {
;     ...
;                         for (int i = 0; i < 4; ++i) { float x0 = v0[i] + dt_bias[c0 + i], x1 = v1[i] + dt_bias[c0 + 4 + i];
;                             dp[i] = x0 > 20.f ? x0 : log1pf(__expf(x0)); dp[4 + i] = x1 > 20.f ? x1 : log1pf(__expf(x1)); }
.LBB0_873:
	s_or_b64 exec, exec, s[24:25]
	s_waitcnt vmcnt(0)
	v_add_f32_e32 v136, v42, v136
	v_cmp_nlt_f32_e32 vcc, s67, v136
	global_store_dword v[154:155], v151, off offset:8
	s_and_saveexec_b64 s[24:25], vcc
	s_cbranch_execz .LBB0_875
	v_mul_f32_e32 v136, 0x3fb8aa3b, v136
	v_exp_f32_e32 v136, v136
	s_nop 0
	v_add_f32_e32 v151, 1.0, v136
	v_frexp_mant_f32_e32 v174, v151
	v_cvt_f64_f32_e32 v[172:173], v151
	v_add_f32_e32 v156, -1.0, v151
	v_frexp_exp_i32_f64_e32 v172, v[172:173]
	v_cmp_gt_f32_e32 vcc, s68, v174
	v_sub_f32_e32 v175, v156, v151
	v_sub_f32_e32 v156, v136, v156
	v_subbrev_co_u32_e32 v180, vcc, 0, v172, vcc
	v_add_f32_e32 v175, 1.0, v175
	v_sub_u32_e32 v172, 0, v180
	v_add_f32_e32 v156, v156, v175
	v_ldexp_f32 v151, v151, v172
	v_ldexp_f32 v156, v156, v172
	v_add_f32_e32 v172, -1.0, v151
	v_add_f32_e32 v173, 1.0, v172
	v_sub_f32_e32 v173, v151, v173
	v_add_f32_e32 v174, v156, v173
	v_add_f32_e32 v173, 1.0, v151
	v_add_f32_e32 v175, -1.0, v173
	v_sub_f32_e32 v151, v151, v175
	v_add_f32_e32 v151, v156, v151
	v_add_f32_e32 v156, v173, v151
	v_rcp_f32_e32 v181, v156
	v_sub_f32_e32 v173, v156, v173
	v_sub_f32_e32 v151, v151, v173
	v_add_f32_e32 v173, v172, v174
	v_sub_f32_e32 v172, v173, v172
	v_mul_f32_e32 v183, v173, v181
	v_sub_f32_e32 v182, v174, v172
	v_mul_f32_e32 v174, v156, v183
	v_fma_f32 v176, v183, v156, -v174
	v_fmac_f32_e32 v176, v183, v151
	v_add_f32_e32 v172, v174, v176
	v_sub_f32_e32 v175, v173, v172
	v_pk_add_f32 v[178:179], v[172:173], v[174:175] neg_lo:[0,1] neg_hi:[0,1]
	v_mov_b32_e32 v177, v172
	v_pk_add_f32 v[172:173], v[178:179], v[176:177] neg_lo:[0,1] neg_hi:[0,1]
	v_cmp_neq_f32_e32 vcc, s70, v136
	v_add_f32_e32 v173, v182, v173
	v_add_f32_e32 v172, v172, v173
	v_add_f32_e32 v173, v175, v172
	v_mul_f32_e32 v182, v181, v173
	v_mul_f32_e32 v174, v156, v182
	v_fma_f32 v176, v182, v156, -v174
	v_fmac_f32_e32 v176, v182, v151
	v_sub_f32_e32 v151, v175, v173
	v_add_f32_e32 v151, v172, v151
	v_add_f32_e32 v172, v174, v176
	v_sub_f32_e32 v175, v173, v172
	v_pk_add_f32 v[178:179], v[172:173], v[174:175] neg_lo:[0,1] neg_hi:[0,1]
	v_mov_b32_e32 v177, v172
	v_pk_add_f32 v[172:173], v[178:179], v[176:177] neg_lo:[0,1] neg_hi:[0,1]
	v_add_f32_e32 v156, v183, v182
	v_add_f32_e32 v151, v151, v173
	v_add_f32_e32 v151, v172, v151
	v_add_f32_e32 v151, v175, v151
	v_sub_f32_e32 v172, v156, v183
	v_mul_f32_e32 v151, v181, v151
	v_sub_f32_e32 v172, v182, v172
	v_add_f32_e32 v173, v172, v151
	v_add_f32_e32 v174, v156, v173
	v_cvt_f32_i32_e32 v172, v180
	v_mul_f32_e32 v176, v174, v174
	v_fmamk_f32 v151, v176, 0x3e9b6dac, v166
	v_sub_f32_e32 v156, v174, v156
	v_fmaak_f32 v151, v176, v151, 0x3f2aaada
	v_sub_f32_e32 v156, v173, v156
	v_mul_f32_e32 v173, v174, v176
	v_pk_mul_f32 v[176:177], v[172:173], v[150:151]
	v_ldexp_f32 v175, v174, 1
	v_fma_f32 v174, v172, s69, -v176
	v_fmac_f32_e32 v174, 0xb102e308, v172
	v_pk_add_f32 v[172:173], v[176:177], v[174:175]
	v_ldexp_f32 v156, v156, 1
	v_sub_f32_e32 v151, v173, v175
	v_sub_f32_e32 v151, v177, v151
	v_add_f32_e32 v179, v156, v151
	v_mov_b32_e32 v178, v176
	v_pk_add_f32 v[176:177], v[172:173], v[176:177] neg_lo:[0,1] neg_hi:[0,1]
	v_pk_add_f32 v[180:181], v[172:173], v[178:179]
	v_mov_b32_e32 v175, v172
	v_mov_b32_e32 v177, v181
	v_pk_add_f32 v[182:183], v[174:175], v[176:177] neg_lo:[0,1] neg_hi:[0,1]
	v_pk_add_f32 v[174:175], v[174:175], v[176:177]
	v_mov_b32_e32 v178, v179
	v_pk_add_f32 v[176:177], v[174:175], v[172:173] op_sel:[1,0] op_sel_hi:[0,1] neg_lo:[0,1] neg_hi:[0,1]
	v_pk_add_f32 v[184:185], v[180:181], v[176:177] op_sel_hi:[1,0] neg_lo:[0,1] neg_hi:[0,1]
	v_mov_b32_e32 v180, v181
	v_mov_b32_e32 v181, v175
	v_pk_mov_b32 v[176:177], v[172:173], v[176:177] op_sel:[1,0]
	v_mov_b32_e32 v179, v172
	v_pk_add_f32 v[176:177], v[180:181], v[176:177] neg_lo:[0,1] neg_hi:[0,1]
	v_mov_b32_e32 v184, v182
	v_pk_add_f32 v[172:173], v[178:179], v[176:177] neg_lo:[0,1] neg_hi:[0,1]
	v_mov_b32_e32 v183, v175
	v_pk_add_f32 v[176:177], v[184:185], v[172:173]
	s_nop 0
	v_pk_add_f32 v[178:179], v[176:177], v[176:177] op_sel:[0,1] op_sel_hi:[1,0]
	s_nop 0
	v_pk_add_f32 v[174:175], v[174:175], v[178:179] op_sel:[1,0] op_sel_hi:[0,1]
	v_mov_b32_e32 v177, v174
	v_pk_add_f32 v[180:181], v[176:177], v[182:183] neg_lo:[0,1] neg_hi:[0,1]
	v_mov_b32_e32 v173, v178
	v_sub_f32_e32 v151, v176, v180
	v_pk_add_f32 v[172:173], v[172:173], v[180:181] neg_lo:[0,1] neg_hi:[0,1]
	v_sub_f32_e32 v151, v182, v151
	v_add_f32_e32 v151, v172, v151
	v_add_f32_e32 v151, v151, v173
	v_add_f32_e32 v151, v174, v151
	v_cndmask_b32_e32 v151, v167, v151, vcc
	v_cmp_ngt_f32_e32 vcc, -1.0, v136
	s_nop 1
	v_cndmask_b32_e32 v151, v168, v151, vcc
	v_cmp_neq_f32_e32 vcc, -1.0, v136
	s_nop 1
	v_cndmask_b32_e32 v151, v169, v151, vcc
	v_cmp_lt_f32_e64 vcc, |v136|, s71
	s_nop 1
	v_cndmask_b32_e32 v136, v151, v136, vcc
;     __device__ __forceinline__ void operator()(const f32x4 (&acc)[2][2][4][2], const Unit& u, int wr, int wc, int fr, int fq) const {
;     ...
;                         for (int i = 0; i < 4; ++i) { float x0 = v0[i] + dt_bias[c0 + i], x1 = v1[i] + dt_bias[c0 + 4 + i];
;                             dp[i] = x0 > 20.f ? x0 : log1pf(__expf(x0)); dp[4 + i] = x1 > 20.f ? x1 : log1pf(__expf(x1)); }
.LBB0_875:
	s_or_b64 exec, exec, s[24:25]
	global_store_dword v[154:155], v136, off offset:24
	global_load_dword v136, v[140:141], off offset:12
	s_waitcnt vmcnt(0)
	v_add_f32_e32 v151, v47, v136
	global_load_dword v136, v[140:141], off offset:28
	v_cmp_nlt_f32_e32 vcc, s67, v151
	s_and_saveexec_b64 s[24:25], vcc
	s_cbranch_execz .LBB0_877
	v_mul_f32_e32 v151, 0x3fb8aa3b, v151
	v_exp_f32_e32 v156, v151
	s_nop 0
	v_add_f32_e32 v151, 1.0, v156
	v_frexp_mant_f32_e32 v175, v151
	v_cvt_f64_f32_e32 v[172:173], v151
	v_add_f32_e32 v174, -1.0, v151
	v_frexp_exp_i32_f64_e32 v172, v[172:173]
	v_cmp_gt_f32_e32 vcc, s68, v175
	v_sub_f32_e32 v176, v174, v151
	v_sub_f32_e32 v174, v156, v174
	v_subbrev_co_u32_e32 v180, vcc, 0, v172, vcc
	v_add_f32_e32 v176, 1.0, v176
	v_sub_u32_e32 v172, 0, v180
	v_add_f32_e32 v174, v174, v176
	v_ldexp_f32 v151, v151, v172
	v_ldexp_f32 v172, v174, v172
	v_add_f32_e32 v174, -1.0, v151
	v_add_f32_e32 v173, 1.0, v174
	v_sub_f32_e32 v173, v151, v173
	v_add_f32_e32 v175, v172, v173
	v_add_f32_e32 v173, 1.0, v151
	v_add_f32_e32 v176, -1.0, v173
	v_sub_f32_e32 v151, v151, v176
	v_add_f32_e32 v151, v172, v151
	v_add_f32_e32 v181, v173, v151
	v_rcp_f32_e32 v182, v181
	v_sub_f32_e32 v172, v181, v173
	v_add_f32_e32 v173, v174, v175
	v_sub_f32_e32 v151, v151, v172
	v_mul_f32_e32 v184, v173, v182
	v_sub_f32_e32 v172, v173, v174
	v_mul_f32_e32 v174, v181, v184
	v_fma_f32 v176, v184, v181, -v174
	v_fmac_f32_e32 v176, v184, v151
	v_sub_f32_e32 v183, v175, v172
	v_add_f32_e32 v172, v174, v176
	v_sub_f32_e32 v175, v173, v172
	v_pk_add_f32 v[178:179], v[172:173], v[174:175] neg_lo:[0,1] neg_hi:[0,1]
	v_mov_b32_e32 v177, v172
	v_pk_add_f32 v[172:173], v[178:179], v[176:177] neg_lo:[0,1] neg_hi:[0,1]
	v_cmp_neq_f32_e32 vcc, s70, v156
	v_add_f32_e32 v173, v183, v173
	v_add_f32_e32 v172, v172, v173
	v_add_f32_e32 v173, v175, v172
	v_mul_f32_e32 v183, v182, v173
	v_mul_f32_e32 v174, v181, v183
	v_fma_f32 v176, v183, v181, -v174
	v_fmac_f32_e32 v176, v183, v151
	v_sub_f32_e32 v151, v175, v173
	v_add_f32_e32 v151, v172, v151
	v_add_f32_e32 v172, v174, v176
	v_sub_f32_e32 v175, v173, v172
	v_pk_add_f32 v[178:179], v[172:173], v[174:175] neg_lo:[0,1] neg_hi:[0,1]
	v_mov_b32_e32 v177, v172
	v_pk_add_f32 v[172:173], v[178:179], v[176:177] neg_lo:[0,1] neg_hi:[0,1]
	s_nop 0
	v_add_f32_e32 v151, v151, v173
	v_add_f32_e32 v151, v172, v151
	v_add_f32_e32 v173, v184, v183
	v_add_f32_e32 v151, v175, v151
	v_sub_f32_e32 v172, v173, v184
	v_mul_f32_e32 v151, v182, v151
	v_sub_f32_e32 v172, v183, v172
	v_add_f32_e32 v174, v172, v151
	v_add_f32_e32 v176, v173, v174
	v_cvt_f32_i32_e32 v172, v180
	v_mul_f32_e32 v177, v176, v176
	v_sub_f32_e32 v173, v176, v173
	v_fmamk_f32 v151, v177, 0x3e9b6dac, v166
	v_sub_f32_e32 v173, v174, v173
	v_fmaak_f32 v151, v177, v151, 0x3f2aaada
	v_ldexp_f32 v178, v173, 1
	v_mul_f32_e32 v173, v176, v177
	v_ldexp_f32 v175, v176, 1
	v_pk_mul_f32 v[176:177], v[172:173], v[150:151]
	s_nop 0
	v_fma_f32 v174, v172, s69, -v176
	v_fmac_f32_e32 v174, 0xb102e308, v172
	v_pk_add_f32 v[172:173], v[176:177], v[174:175]
	s_nop 0
	v_sub_f32_e32 v151, v173, v175
	v_sub_f32_e32 v151, v177, v151
	v_add_f32_e32 v179, v178, v151
	v_mov_b32_e32 v178, v176
	v_pk_add_f32 v[176:177], v[172:173], v[176:177] neg_lo:[0,1] neg_hi:[0,1]
	v_pk_add_f32 v[180:181], v[172:173], v[178:179]
	v_mov_b32_e32 v175, v172
	v_mov_b32_e32 v177, v181
	v_pk_add_f32 v[182:183], v[174:175], v[176:177] neg_lo:[0,1] neg_hi:[0,1]
	v_pk_add_f32 v[174:175], v[174:175], v[176:177]
	v_mov_b32_e32 v178, v179
	v_pk_add_f32 v[176:177], v[174:175], v[172:173] op_sel:[1,0] op_sel_hi:[0,1] neg_lo:[0,1] neg_hi:[0,1]
	v_pk_add_f32 v[184:185], v[180:181], v[176:177] op_sel_hi:[1,0] neg_lo:[0,1] neg_hi:[0,1]
	v_mov_b32_e32 v180, v181
	v_mov_b32_e32 v181, v175
	v_pk_mov_b32 v[176:177], v[172:173], v[176:177] op_sel:[1,0]
	v_mov_b32_e32 v179, v172
	v_pk_add_f32 v[176:177], v[180:181], v[176:177] neg_lo:[0,1] neg_hi:[0,1]
	v_mov_b32_e32 v184, v182
	v_pk_add_f32 v[172:173], v[178:179], v[176:177] neg_lo:[0,1] neg_hi:[0,1]
	v_mov_b32_e32 v183, v175
	v_pk_add_f32 v[176:177], v[184:185], v[172:173]
	s_nop 0
	v_pk_add_f32 v[178:179], v[176:177], v[176:177] op_sel:[0,1] op_sel_hi:[1,0]
	s_nop 0
	v_pk_add_f32 v[174:175], v[174:175], v[178:179] op_sel:[1,0] op_sel_hi:[0,1]
	v_mov_b32_e32 v177, v174
	v_pk_add_f32 v[180:181], v[176:177], v[182:183] neg_lo:[0,1] neg_hi:[0,1]
	v_mov_b32_e32 v173, v178
	v_sub_f32_e32 v151, v176, v180
	v_pk_add_f32 v[172:173], v[172:173], v[180:181] neg_lo:[0,1] neg_hi:[0,1]
	v_sub_f32_e32 v151, v182, v151
	v_add_f32_e32 v151, v172, v151
	v_add_f32_e32 v151, v151, v173
	v_add_f32_e32 v151, v174, v151
	v_cndmask_b32_e32 v151, v167, v151, vcc
	v_cmp_ngt_f32_e32 vcc, -1.0, v156
	s_nop 1
	v_cndmask_b32_e32 v151, v168, v151, vcc
	v_cmp_neq_f32_e32 vcc, -1.0, v156
	s_nop 1
	v_cndmask_b32_e32 v151, v169, v151, vcc
	v_cmp_lt_f32_e64 vcc, |v156|, s71
	s_nop 1
	v_cndmask_b32_e32 v151, v151, v156, vcc
;     __device__ __forceinline__ void operator()(const f32x4 (&acc)[2][2][4][2], const Unit& u, int wr, int wc, int fr, int fq) const {
;     ...
;                         for (int i = 0; i < 4; ++i) { float x0 = v0[i] + dt_bias[c0 + i], x1 = v1[i] + dt_bias[c0 + 4 + i];
;                             dp[i] = x0 > 20.f ? x0 : log1pf(__expf(x0)); dp[4 + i] = x1 > 20.f ? x1 : log1pf(__expf(x1)); }
.LBB0_877:
	s_or_b64 exec, exec, s[24:25]
	s_waitcnt vmcnt(0)
	v_add_f32_e32 v136, v43, v136
	v_cmp_nlt_f32_e32 vcc, s67, v136
	global_store_dword v[154:155], v151, off offset:12
	s_and_saveexec_b64 s[24:25], vcc
	s_cbranch_execz .LBB0_879
	v_mul_f32_e32 v136, 0x3fb8aa3b, v136
	v_exp_f32_e32 v136, v136
	s_nop 0
	v_add_f32_e32 v151, 1.0, v136
	v_frexp_mant_f32_e32 v174, v151
	v_cvt_f64_f32_e32 v[172:173], v151
	v_add_f32_e32 v156, -1.0, v151
	v_frexp_exp_i32_f64_e32 v172, v[172:173]
	v_cmp_gt_f32_e32 vcc, s68, v174
	v_sub_f32_e32 v175, v156, v151
	v_sub_f32_e32 v156, v136, v156
	v_subbrev_co_u32_e32 v180, vcc, 0, v172, vcc
	v_add_f32_e32 v175, 1.0, v175
	v_sub_u32_e32 v172, 0, v180
	v_add_f32_e32 v156, v156, v175
	v_ldexp_f32 v151, v151, v172
	v_ldexp_f32 v156, v156, v172
	v_add_f32_e32 v172, -1.0, v151
	v_add_f32_e32 v173, 1.0, v172
	v_sub_f32_e32 v173, v151, v173
	v_add_f32_e32 v174, v156, v173
	v_add_f32_e32 v173, 1.0, v151
	v_add_f32_e32 v175, -1.0, v173
	v_sub_f32_e32 v151, v151, v175
	v_add_f32_e32 v151, v156, v151
	v_add_f32_e32 v156, v173, v151
	v_rcp_f32_e32 v181, v156
	v_sub_f32_e32 v173, v156, v173
	v_sub_f32_e32 v151, v151, v173
	v_add_f32_e32 v173, v172, v174
	v_sub_f32_e32 v172, v173, v172
	v_mul_f32_e32 v183, v173, v181
	v_sub_f32_e32 v182, v174, v172
	v_mul_f32_e32 v174, v156, v183
	v_fma_f32 v176, v183, v156, -v174
	v_fmac_f32_e32 v176, v183, v151
	v_add_f32_e32 v172, v174, v176
	v_sub_f32_e32 v175, v173, v172
	v_pk_add_f32 v[178:179], v[172:173], v[174:175] neg_lo:[0,1] neg_hi:[0,1]
	v_mov_b32_e32 v177, v172
	v_pk_add_f32 v[172:173], v[178:179], v[176:177] neg_lo:[0,1] neg_hi:[0,1]
	v_cmp_neq_f32_e32 vcc, s70, v136
	v_add_f32_e32 v173, v182, v173
	v_add_f32_e32 v172, v172, v173
	v_add_f32_e32 v173, v175, v172
	v_mul_f32_e32 v182, v181, v173
	v_mul_f32_e32 v174, v156, v182
	v_fma_f32 v176, v182, v156, -v174
	v_fmac_f32_e32 v176, v182, v151
	v_sub_f32_e32 v151, v175, v173
	v_add_f32_e32 v151, v172, v151
	v_add_f32_e32 v172, v174, v176
	v_sub_f32_e32 v175, v173, v172
	v_pk_add_f32 v[178:179], v[172:173], v[174:175] neg_lo:[0,1] neg_hi:[0,1]
	v_mov_b32_e32 v177, v172
	v_pk_add_f32 v[172:173], v[178:179], v[176:177] neg_lo:[0,1] neg_hi:[0,1]
	v_add_f32_e32 v156, v183, v182
	v_add_f32_e32 v151, v151, v173
	v_add_f32_e32 v151, v172, v151
	v_add_f32_e32 v151, v175, v151
	v_sub_f32_e32 v172, v156, v183
	v_mul_f32_e32 v151, v181, v151
	v_sub_f32_e32 v172, v182, v172
	v_add_f32_e32 v173, v172, v151
	v_add_f32_e32 v174, v156, v173
	v_cvt_f32_i32_e32 v172, v180
	v_mul_f32_e32 v176, v174, v174
	v_fmamk_f32 v151, v176, 0x3e9b6dac, v166
	v_sub_f32_e32 v156, v174, v156
	v_fmaak_f32 v151, v176, v151, 0x3f2aaada
	v_sub_f32_e32 v156, v173, v156
	v_mul_f32_e32 v173, v174, v176
	v_pk_mul_f32 v[176:177], v[172:173], v[150:151]
	v_ldexp_f32 v175, v174, 1
	v_fma_f32 v174, v172, s69, -v176
	v_fmac_f32_e32 v174, 0xb102e308, v172
	v_pk_add_f32 v[172:173], v[176:177], v[174:175]
	v_ldexp_f32 v156, v156, 1
	v_sub_f32_e32 v151, v173, v175
	v_sub_f32_e32 v151, v177, v151
	v_add_f32_e32 v179, v156, v151
	v_mov_b32_e32 v178, v176
	v_pk_add_f32 v[176:177], v[172:173], v[176:177] neg_lo:[0,1] neg_hi:[0,1]
	v_pk_add_f32 v[180:181], v[172:173], v[178:179]
	v_mov_b32_e32 v175, v172
	v_mov_b32_e32 v177, v181
	v_pk_add_f32 v[182:183], v[174:175], v[176:177] neg_lo:[0,1] neg_hi:[0,1]
	v_pk_add_f32 v[174:175], v[174:175], v[176:177]
	v_mov_b32_e32 v178, v179
	v_pk_add_f32 v[176:177], v[174:175], v[172:173] op_sel:[1,0] op_sel_hi:[0,1] neg_lo:[0,1] neg_hi:[0,1]
	v_pk_add_f32 v[184:185], v[180:181], v[176:177] op_sel_hi:[1,0] neg_lo:[0,1] neg_hi:[0,1]
	v_mov_b32_e32 v180, v181
	v_mov_b32_e32 v181, v175
	v_pk_mov_b32 v[176:177], v[172:173], v[176:177] op_sel:[1,0]
	v_mov_b32_e32 v179, v172
	v_pk_add_f32 v[176:177], v[180:181], v[176:177] neg_lo:[0,1] neg_hi:[0,1]
	v_mov_b32_e32 v184, v182
	v_pk_add_f32 v[172:173], v[178:179], v[176:177] neg_lo:[0,1] neg_hi:[0,1]
	v_mov_b32_e32 v183, v175
	v_pk_add_f32 v[176:177], v[184:185], v[172:173]
	s_nop 0
	v_pk_add_f32 v[178:179], v[176:177], v[176:177] op_sel:[0,1] op_sel_hi:[1,0]
	s_nop 0
	v_pk_add_f32 v[174:175], v[174:175], v[178:179] op_sel:[1,0] op_sel_hi:[0,1]
	v_mov_b32_e32 v177, v174
	v_pk_add_f32 v[180:181], v[176:177], v[182:183] neg_lo:[0,1] neg_hi:[0,1]
	v_mov_b32_e32 v173, v178
	v_sub_f32_e32 v151, v176, v180
	v_pk_add_f32 v[172:173], v[172:173], v[180:181] neg_lo:[0,1] neg_hi:[0,1]
	v_sub_f32_e32 v151, v182, v151
	v_add_f32_e32 v151, v172, v151
	v_add_f32_e32 v151, v151, v173
	v_add_f32_e32 v151, v174, v151
	v_cndmask_b32_e32 v151, v167, v151, vcc
	v_cmp_ngt_f32_e32 vcc, -1.0, v136
	s_nop 1
	v_cndmask_b32_e32 v151, v168, v151, vcc
	v_cmp_neq_f32_e32 vcc, -1.0, v136
	s_nop 1
	v_cndmask_b32_e32 v151, v169, v151, vcc
	v_cmp_lt_f32_e64 vcc, |v136|, s71
	s_nop 1
	v_cndmask_b32_e32 v136, v151, v136, vcc
;     __device__ __forceinline__ void operator()(const f32x4 (&acc)[2][2][4][2], const Unit& u, int wr, int wc, int fr, int fq) const {
;     ...
;                         for (int i = 0; i < 4; ++i) { float x0 = v0[i] + dt_bias[c0 + i], x1 = v1[i] + dt_bias[c0 + 4 + i];
;                             dp[i] = x0 > 20.f ? x0 : log1pf(__expf(x0)); dp[4 + i] = x1 > 20.f ? x1 : log1pf(__expf(x1)); }
.LBB0_879:
	s_or_b64 exec, exec, s[24:25]
	global_store_dword v[154:155], v136, off offset:28
	global_load_dword v136, v[140:141], off
	s_waitcnt vmcnt(0)
	v_add_f32_e32 v151, v28, v136
	global_load_dword v136, v[140:141], off offset:16
	v_cmp_nlt_f32_e32 vcc, s67, v151
	s_and_saveexec_b64 s[24:25], vcc
	s_cbranch_execz .LBB0_881
	v_mul_f32_e32 v151, 0x3fb8aa3b, v151
	v_exp_f32_e32 v156, v151
	s_nop 0
	v_add_f32_e32 v151, 1.0, v156
	v_frexp_mant_f32_e32 v173, v151
	v_cvt_f64_f32_e32 v[154:155], v151
	v_add_f32_e32 v172, -1.0, v151
	v_frexp_exp_i32_f64_e32 v154, v[154:155]
	v_cmp_gt_f32_e32 vcc, s68, v173
	v_sub_f32_e32 v174, v172, v151
	v_sub_f32_e32 v172, v156, v172
	v_subbrev_co_u32_e32 v178, vcc, 0, v154, vcc
	v_add_f32_e32 v174, 1.0, v174
	v_sub_u32_e32 v154, 0, v178
	v_add_f32_e32 v172, v172, v174
	v_ldexp_f32 v151, v151, v154
	v_ldexp_f32 v154, v172, v154
	v_add_f32_e32 v172, -1.0, v151
	v_add_f32_e32 v155, 1.0, v172
	v_sub_f32_e32 v155, v151, v155
	v_add_f32_e32 v173, v154, v155
	v_add_f32_e32 v155, 1.0, v151
	v_add_f32_e32 v174, -1.0, v155
	v_sub_f32_e32 v151, v151, v174
	v_add_f32_e32 v151, v154, v151
	v_add_f32_e32 v179, v155, v151
	v_rcp_f32_e32 v180, v179
	v_sub_f32_e32 v154, v179, v155
	v_add_f32_e32 v155, v172, v173
	v_sub_f32_e32 v151, v151, v154
	v_mul_f32_e32 v182, v155, v180
	v_sub_f32_e32 v154, v155, v172
	v_mul_f32_e32 v172, v179, v182
	v_fma_f32 v174, v182, v179, -v172
	v_fmac_f32_e32 v174, v182, v151
	v_sub_f32_e32 v181, v173, v154
	v_add_f32_e32 v154, v172, v174
	v_sub_f32_e32 v173, v155, v154
	v_pk_add_f32 v[176:177], v[154:155], v[172:173] neg_lo:[0,1] neg_hi:[0,1]
	v_mov_b32_e32 v175, v154
	v_pk_add_f32 v[154:155], v[176:177], v[174:175] neg_lo:[0,1] neg_hi:[0,1]
	v_cmp_neq_f32_e32 vcc, s70, v156
	v_add_f32_e32 v155, v181, v155
	v_add_f32_e32 v154, v154, v155
	v_add_f32_e32 v155, v173, v154
	v_mul_f32_e32 v181, v180, v155
	v_mul_f32_e32 v172, v179, v181
	v_fma_f32 v174, v181, v179, -v172
	v_fmac_f32_e32 v174, v181, v151
	v_sub_f32_e32 v151, v173, v155
	v_add_f32_e32 v151, v154, v151
	v_add_f32_e32 v154, v172, v174
	v_sub_f32_e32 v173, v155, v154
	v_pk_add_f32 v[176:177], v[154:155], v[172:173] neg_lo:[0,1] neg_hi:[0,1]
	v_mov_b32_e32 v175, v154
	v_pk_add_f32 v[154:155], v[176:177], v[174:175] neg_lo:[0,1] neg_hi:[0,1]
	s_nop 0
	v_add_f32_e32 v151, v151, v155
	v_add_f32_e32 v151, v154, v151
	v_add_f32_e32 v155, v182, v181
	v_add_f32_e32 v151, v173, v151
	v_sub_f32_e32 v154, v155, v182
	v_mul_f32_e32 v151, v180, v151
	v_sub_f32_e32 v154, v181, v154
	v_add_f32_e32 v172, v154, v151
	v_add_f32_e32 v174, v155, v172
	v_cvt_f32_i32_e32 v154, v178
	v_mul_f32_e32 v175, v174, v174
	v_sub_f32_e32 v155, v174, v155
	v_fmamk_f32 v151, v175, 0x3e9b6dac, v166
	v_sub_f32_e32 v155, v172, v155
	v_fmaak_f32 v151, v175, v151, 0x3f2aaada
	v_ldexp_f32 v176, v155, 1
	v_mul_f32_e32 v155, v174, v175
	v_ldexp_f32 v173, v174, 1
	v_pk_mul_f32 v[174:175], v[154:155], v[150:151]
	s_nop 0
	v_fma_f32 v172, v154, s69, -v174
	v_fmac_f32_e32 v172, 0xb102e308, v154
	v_pk_add_f32 v[154:155], v[174:175], v[172:173]
	s_nop 0
	v_sub_f32_e32 v151, v155, v173
	v_sub_f32_e32 v151, v175, v151
	v_add_f32_e32 v177, v176, v151
	v_mov_b32_e32 v176, v174
	v_pk_add_f32 v[174:175], v[154:155], v[174:175] neg_lo:[0,1] neg_hi:[0,1]
	v_pk_add_f32 v[178:179], v[154:155], v[176:177]
	v_mov_b32_e32 v173, v154
	v_mov_b32_e32 v175, v179
	v_pk_add_f32 v[180:181], v[172:173], v[174:175] neg_lo:[0,1] neg_hi:[0,1]
	v_pk_add_f32 v[172:173], v[172:173], v[174:175]
	v_mov_b32_e32 v176, v177
	v_pk_add_f32 v[174:175], v[172:173], v[154:155] op_sel:[1,0] op_sel_hi:[0,1] neg_lo:[0,1] neg_hi:[0,1]
	v_pk_add_f32 v[182:183], v[178:179], v[174:175] op_sel_hi:[1,0] neg_lo:[0,1] neg_hi:[0,1]
	v_mov_b32_e32 v178, v179
	v_mov_b32_e32 v179, v173
	v_pk_mov_b32 v[174:175], v[154:155], v[174:175] op_sel:[1,0]
	v_mov_b32_e32 v177, v154
	v_pk_add_f32 v[174:175], v[178:179], v[174:175] neg_lo:[0,1] neg_hi:[0,1]
	v_mov_b32_e32 v182, v180
	v_pk_add_f32 v[154:155], v[176:177], v[174:175] neg_lo:[0,1] neg_hi:[0,1]
	v_mov_b32_e32 v181, v173
	v_pk_add_f32 v[174:175], v[182:183], v[154:155]
	s_nop 0
	v_pk_add_f32 v[176:177], v[174:175], v[174:175] op_sel:[0,1] op_sel_hi:[1,0]
	s_nop 0
	v_pk_add_f32 v[172:173], v[172:173], v[176:177] op_sel:[1,0] op_sel_hi:[0,1]
	v_mov_b32_e32 v175, v172
	v_pk_add_f32 v[178:179], v[174:175], v[180:181] neg_lo:[0,1] neg_hi:[0,1]
	v_mov_b32_e32 v155, v176
	v_sub_f32_e32 v151, v174, v178
	v_pk_add_f32 v[154:155], v[154:155], v[178:179] neg_lo:[0,1] neg_hi:[0,1]
	v_sub_f32_e32 v151, v180, v151
	v_add_f32_e32 v151, v154, v151
	v_add_f32_e32 v151, v151, v155
	v_add_f32_e32 v151, v172, v151
	v_cndmask_b32_e32 v151, v167, v151, vcc
	v_cmp_ngt_f32_e32 vcc, -1.0, v156
	s_nop 1
	v_cndmask_b32_e32 v151, v168, v151, vcc
	v_cmp_neq_f32_e32 vcc, -1.0, v156
	s_nop 1
	v_cndmask_b32_e32 v151, v169, v151, vcc
	v_cmp_lt_f32_e64 vcc, |v156|, s71
	s_nop 1
	v_cndmask_b32_e32 v151, v151, v156, vcc
;     __device__ __forceinline__ void operator()(const f32x4 (&acc)[2][2][4][2], const Unit& u, int wr, int wc, int fr, int fq) const {
;     ...
;                     for (int m = 0; m < 4; ++m) { const int r = row0 + ai * HALF + m * 16;
;                         const f32x4 v0 = acc[ai][0][m][0], v1 = acc[ai][0][m][1]; float* dp = DT + (size_t)r * 32 + c0;
; #pragma unroll
;                         for (int i = 0; i < 4; ++i) { float x0 = v0[i] + dt_bias[c0 + i], x1 = v1[i] + dt_bias[c0 + 4 + i];
;                             dp[i] = x0 > 20.f ? x0 : log1pf(__expf(x0)); dp[4 + i] = x1 > 20.f ? x1 : log1pf(__expf(x1)); }
.LBB0_881:
	s_or_b64 exec, exec, s[24:25]
	v_lshlrev_b64 v[154:155], 7, v[152:153]
	v_lshl_add_u64 v[154:155], v[138:139], 0, v[154:155]
	v_add_co_u32_e32 v172, vcc, 0x5000, v154
	s_waitcnt vmcnt(0)
	v_add_f32_e32 v136, v24, v136
	v_addc_co_u32_e32 v173, vcc, 0, v155, vcc
	v_cmp_nlt_f32_e32 vcc, s67, v136
	global_store_dword v[172:173], v151, off
	s_and_saveexec_b64 s[24:25], vcc
	s_cbranch_execz .LBB0_883
	v_mul_f32_e32 v136, 0x3fb8aa3b, v136
	v_exp_f32_e32 v136, v136
	s_nop 0
	v_add_f32_e32 v151, 1.0, v136
	v_frexp_mant_f32_e32 v174, v151
	v_cvt_f64_f32_e32 v[172:173], v151
	v_add_f32_e32 v156, -1.0, v151
	v_frexp_exp_i32_f64_e32 v172, v[172:173]
	v_cmp_gt_f32_e32 vcc, s68, v174
	v_sub_f32_e32 v175, v156, v151
	v_sub_f32_e32 v156, v136, v156
	v_subbrev_co_u32_e32 v180, vcc, 0, v172, vcc
	v_add_f32_e32 v175, 1.0, v175
	v_sub_u32_e32 v172, 0, v180
	v_add_f32_e32 v156, v156, v175
	v_ldexp_f32 v151, v151, v172
	v_ldexp_f32 v156, v156, v172
	v_add_f32_e32 v172, -1.0, v151
	v_add_f32_e32 v173, 1.0, v172
	v_sub_f32_e32 v173, v151, v173
	v_add_f32_e32 v174, v156, v173
	v_add_f32_e32 v173, 1.0, v151
	v_add_f32_e32 v175, -1.0, v173
	v_sub_f32_e32 v151, v151, v175
	v_add_f32_e32 v151, v156, v151
	v_add_f32_e32 v156, v173, v151
	v_rcp_f32_e32 v181, v156
	v_sub_f32_e32 v173, v156, v173
	v_sub_f32_e32 v151, v151, v173
	v_add_f32_e32 v173, v172, v174
	v_sub_f32_e32 v172, v173, v172
	v_mul_f32_e32 v183, v173, v181
	v_sub_f32_e32 v182, v174, v172
	v_mul_f32_e32 v174, v156, v183
	v_fma_f32 v176, v183, v156, -v174
	v_fmac_f32_e32 v176, v183, v151
	v_add_f32_e32 v172, v174, v176
	v_sub_f32_e32 v175, v173, v172
	v_pk_add_f32 v[178:179], v[172:173], v[174:175] neg_lo:[0,1] neg_hi:[0,1]
	v_mov_b32_e32 v177, v172
	v_pk_add_f32 v[172:173], v[178:179], v[176:177] neg_lo:[0,1] neg_hi:[0,1]
	v_cmp_neq_f32_e32 vcc, s70, v136
	v_add_f32_e32 v173, v182, v173
	v_add_f32_e32 v172, v172, v173
	v_add_f32_e32 v173, v175, v172
	v_mul_f32_e32 v182, v181, v173
	v_mul_f32_e32 v174, v156, v182
	v_fma_f32 v176, v182, v156, -v174
	v_fmac_f32_e32 v176, v182, v151
	v_sub_f32_e32 v151, v175, v173
	v_add_f32_e32 v151, v172, v151
	v_add_f32_e32 v172, v174, v176
	v_sub_f32_e32 v175, v173, v172
	v_pk_add_f32 v[178:179], v[172:173], v[174:175] neg_lo:[0,1] neg_hi:[0,1]
	v_mov_b32_e32 v177, v172
	v_pk_add_f32 v[172:173], v[178:179], v[176:177] neg_lo:[0,1] neg_hi:[0,1]
	v_add_f32_e32 v156, v183, v182
	v_add_f32_e32 v151, v151, v173
	v_add_f32_e32 v151, v172, v151
	v_add_f32_e32 v151, v175, v151
	v_sub_f32_e32 v172, v156, v183
	v_mul_f32_e32 v151, v181, v151
	v_sub_f32_e32 v172, v182, v172
	v_add_f32_e32 v173, v172, v151
	v_add_f32_e32 v174, v156, v173
	v_cvt_f32_i32_e32 v172, v180
	v_mul_f32_e32 v176, v174, v174
	v_fmamk_f32 v151, v176, 0x3e9b6dac, v166
	v_sub_f32_e32 v156, v174, v156
	v_fmaak_f32 v151, v176, v151, 0x3f2aaada
	v_sub_f32_e32 v156, v173, v156
	v_mul_f32_e32 v173, v174, v176
	v_pk_mul_f32 v[176:177], v[172:173], v[150:151]
	v_ldexp_f32 v175, v174, 1
	v_fma_f32 v174, v172, s69, -v176
	v_fmac_f32_e32 v174, 0xb102e308, v172
	v_pk_add_f32 v[172:173], v[176:177], v[174:175]
	v_ldexp_f32 v156, v156, 1
	v_sub_f32_e32 v151, v173, v175
	v_sub_f32_e32 v151, v177, v151
	v_add_f32_e32 v179, v156, v151
	v_mov_b32_e32 v178, v176
	v_pk_add_f32 v[176:177], v[172:173], v[176:177] neg_lo:[0,1] neg_hi:[0,1]
	v_pk_add_f32 v[180:181], v[172:173], v[178:179]
	v_mov_b32_e32 v175, v172
	v_mov_b32_e32 v177, v181
	v_pk_add_f32 v[182:183], v[174:175], v[176:177] neg_lo:[0,1] neg_hi:[0,1]
	v_pk_add_f32 v[174:175], v[174:175], v[176:177]
	v_mov_b32_e32 v178, v179
	v_pk_add_f32 v[176:177], v[174:175], v[172:173] op_sel:[1,0] op_sel_hi:[0,1] neg_lo:[0,1] neg_hi:[0,1]
	v_pk_add_f32 v[184:185], v[180:181], v[176:177] op_sel_hi:[1,0] neg_lo:[0,1] neg_hi:[0,1]
	v_mov_b32_e32 v180, v181
	v_mov_b32_e32 v181, v175
	v_pk_mov_b32 v[176:177], v[172:173], v[176:177] op_sel:[1,0]
	v_mov_b32_e32 v179, v172
	v_pk_add_f32 v[176:177], v[180:181], v[176:177] neg_lo:[0,1] neg_hi:[0,1]
	v_mov_b32_e32 v184, v182
	v_pk_add_f32 v[172:173], v[178:179], v[176:177] neg_lo:[0,1] neg_hi:[0,1]
	v_mov_b32_e32 v183, v175
	v_pk_add_f32 v[176:177], v[184:185], v[172:173]
	s_nop 0
	v_pk_add_f32 v[178:179], v[176:177], v[176:177] op_sel:[0,1] op_sel_hi:[1,0]
	s_nop 0
	v_pk_add_f32 v[174:175], v[174:175], v[178:179] op_sel:[1,0] op_sel_hi:[0,1]
	v_mov_b32_e32 v177, v174
	v_pk_add_f32 v[180:181], v[176:177], v[182:183] neg_lo:[0,1] neg_hi:[0,1]
	v_mov_b32_e32 v173, v178
	v_sub_f32_e32 v151, v176, v180
	v_pk_add_f32 v[172:173], v[172:173], v[180:181] neg_lo:[0,1] neg_hi:[0,1]
	v_sub_f32_e32 v151, v182, v151
	v_add_f32_e32 v151, v172, v151
	v_add_f32_e32 v151, v151, v173
	v_add_f32_e32 v151, v174, v151
	v_cndmask_b32_e32 v151, v167, v151, vcc
	v_cmp_ngt_f32_e32 vcc, -1.0, v136
	s_nop 1
	v_cndmask_b32_e32 v151, v168, v151, vcc
	v_cmp_neq_f32_e32 vcc, -1.0, v136
	s_nop 1
	v_cndmask_b32_e32 v151, v169, v151, vcc
	v_cmp_lt_f32_e64 vcc, |v136|, s71
	s_nop 1
	v_cndmask_b32_e32 v136, v151, v136, vcc
;     __device__ __forceinline__ void operator()(const f32x4 (&acc)[2][2][4][2], const Unit& u, int wr, int wc, int fr, int fq) const {
;     ...
;                         for (int i = 0; i < 4; ++i) { float x0 = v0[i] + dt_bias[c0 + i], x1 = v1[i] + dt_bias[c0 + 4 + i];
;                             dp[i] = x0 > 20.f ? x0 : log1pf(__expf(x0)); dp[4 + i] = x1 > 20.f ? x1 : log1pf(__expf(x1)); }
.LBB0_883:
	s_or_b64 exec, exec, s[24:25]
	s_mov_b64 s[24:25], 0x5000
	v_lshl_add_u64 v[154:155], v[154:155], 0, s[24:25]
	global_store_dword v[154:155], v136, off offset:16
	global_load_dword v151, v[140:141], off offset:4
	s_nop 0
	global_load_dword v136, v[140:141], off offset:20
	s_waitcnt vmcnt(0)
	v_add_f32_e32 v151, v29, v151
	v_cmp_nlt_f32_e32 vcc, s67, v151
	s_and_saveexec_b64 s[24:25], vcc
	s_cbranch_execz .LBB0_885
	v_mul_f32_e32 v151, 0x3fb8aa3b, v151
	v_exp_f32_e32 v156, v151
	s_nop 0
	v_add_f32_e32 v151, 1.0, v156
	v_frexp_mant_f32_e32 v175, v151
	v_cvt_f64_f32_e32 v[172:173], v151
	v_add_f32_e32 v174, -1.0, v151
	v_frexp_exp_i32_f64_e32 v172, v[172:173]
	v_cmp_gt_f32_e32 vcc, s68, v175
	v_sub_f32_e32 v176, v174, v151
	v_sub_f32_e32 v174, v156, v174
	v_subbrev_co_u32_e32 v180, vcc, 0, v172, vcc
	v_add_f32_e32 v176, 1.0, v176
	v_sub_u32_e32 v172, 0, v180
	v_add_f32_e32 v174, v174, v176
	v_ldexp_f32 v151, v151, v172
	v_ldexp_f32 v172, v174, v172
	v_add_f32_e32 v174, -1.0, v151
	v_add_f32_e32 v173, 1.0, v174
	v_sub_f32_e32 v173, v151, v173
	v_add_f32_e32 v175, v172, v173
	v_add_f32_e32 v173, 1.0, v151
	v_add_f32_e32 v176, -1.0, v173
	v_sub_f32_e32 v151, v151, v176
	v_add_f32_e32 v151, v172, v151
	v_add_f32_e32 v181, v173, v151
	v_rcp_f32_e32 v182, v181
	v_sub_f32_e32 v172, v181, v173
	v_add_f32_e32 v173, v174, v175
	v_sub_f32_e32 v151, v151, v172
	v_mul_f32_e32 v184, v173, v182
	v_sub_f32_e32 v172, v173, v174
	v_mul_f32_e32 v174, v181, v184
	v_fma_f32 v176, v184, v181, -v174
	v_fmac_f32_e32 v176, v184, v151
	v_sub_f32_e32 v183, v175, v172
	v_add_f32_e32 v172, v174, v176
	v_sub_f32_e32 v175, v173, v172
	v_pk_add_f32 v[178:179], v[172:173], v[174:175] neg_lo:[0,1] neg_hi:[0,1]
	v_mov_b32_e32 v177, v172
	v_pk_add_f32 v[172:173], v[178:179], v[176:177] neg_lo:[0,1] neg_hi:[0,1]
	v_cmp_neq_f32_e32 vcc, s70, v156
	v_add_f32_e32 v173, v183, v173
	v_add_f32_e32 v172, v172, v173
	v_add_f32_e32 v173, v175, v172
	v_mul_f32_e32 v183, v182, v173
	v_mul_f32_e32 v174, v181, v183
	v_fma_f32 v176, v183, v181, -v174
	v_fmac_f32_e32 v176, v183, v151
	v_sub_f32_e32 v151, v175, v173
	v_add_f32_e32 v151, v172, v151
	v_add_f32_e32 v172, v174, v176
	v_sub_f32_e32 v175, v173, v172
	v_pk_add_f32 v[178:179], v[172:173], v[174:175] neg_lo:[0,1] neg_hi:[0,1]
	v_mov_b32_e32 v177, v172
	v_pk_add_f32 v[172:173], v[178:179], v[176:177] neg_lo:[0,1] neg_hi:[0,1]
	s_nop 0
	v_add_f32_e32 v151, v151, v173
	v_add_f32_e32 v151, v172, v151
	v_add_f32_e32 v173, v184, v183
	v_add_f32_e32 v151, v175, v151
	v_sub_f32_e32 v172, v173, v184
	v_mul_f32_e32 v151, v182, v151
	v_sub_f32_e32 v172, v183, v172
	v_add_f32_e32 v174, v172, v151
	v_add_f32_e32 v176, v173, v174
	v_cvt_f32_i32_e32 v172, v180
	v_mul_f32_e32 v177, v176, v176
	v_sub_f32_e32 v173, v176, v173
	v_fmamk_f32 v151, v177, 0x3e9b6dac, v166
	v_sub_f32_e32 v173, v174, v173
	v_fmaak_f32 v151, v177, v151, 0x3f2aaada
	v_ldexp_f32 v178, v173, 1
	v_mul_f32_e32 v173, v176, v177
	v_ldexp_f32 v175, v176, 1
	v_pk_mul_f32 v[176:177], v[172:173], v[150:151]
	s_nop 0
	v_fma_f32 v174, v172, s69, -v176
	v_fmac_f32_e32 v174, 0xb102e308, v172
	v_pk_add_f32 v[172:173], v[176:177], v[174:175]
	s_nop 0
	v_sub_f32_e32 v151, v173, v175
	v_sub_f32_e32 v151, v177, v151
	v_add_f32_e32 v179, v178, v151
	v_mov_b32_e32 v178, v176
	v_pk_add_f32 v[176:177], v[172:173], v[176:177] neg_lo:[0,1] neg_hi:[0,1]
	v_pk_add_f32 v[180:181], v[172:173], v[178:179]
	v_mov_b32_e32 v175, v172
	v_mov_b32_e32 v177, v181
	v_pk_add_f32 v[182:183], v[174:175], v[176:177] neg_lo:[0,1] neg_hi:[0,1]
	v_pk_add_f32 v[174:175], v[174:175], v[176:177]
	v_mov_b32_e32 v178, v179
	v_pk_add_f32 v[176:177], v[174:175], v[172:173] op_sel:[1,0] op_sel_hi:[0,1] neg_lo:[0,1] neg_hi:[0,1]
	v_pk_add_f32 v[184:185], v[180:181], v[176:177] op_sel_hi:[1,0] neg_lo:[0,1] neg_hi:[0,1]
	v_mov_b32_e32 v180, v181
	v_mov_b32_e32 v181, v175
	v_pk_mov_b32 v[176:177], v[172:173], v[176:177] op_sel:[1,0]
	v_mov_b32_e32 v179, v172
	v_pk_add_f32 v[176:177], v[180:181], v[176:177] neg_lo:[0,1] neg_hi:[0,1]
	v_mov_b32_e32 v184, v182
	v_pk_add_f32 v[172:173], v[178:179], v[176:177] neg_lo:[0,1] neg_hi:[0,1]
	v_mov_b32_e32 v183, v175
	v_pk_add_f32 v[176:177], v[184:185], v[172:173]
	s_nop 0
	v_pk_add_f32 v[178:179], v[176:177], v[176:177] op_sel:[0,1] op_sel_hi:[1,0]
	s_nop 0
	v_pk_add_f32 v[174:175], v[174:175], v[178:179] op_sel:[1,0] op_sel_hi:[0,1]
	v_mov_b32_e32 v177, v174
	v_pk_add_f32 v[180:181], v[176:177], v[182:183] neg_lo:[0,1] neg_hi:[0,1]
	v_mov_b32_e32 v173, v178
	v_sub_f32_e32 v151, v176, v180
	v_pk_add_f32 v[172:173], v[172:173], v[180:181] neg_lo:[0,1] neg_hi:[0,1]
	v_sub_f32_e32 v151, v182, v151
	v_add_f32_e32 v151, v172, v151
	v_add_f32_e32 v151, v151, v173
	v_add_f32_e32 v151, v174, v151
	v_cndmask_b32_e32 v151, v167, v151, vcc
	v_cmp_ngt_f32_e32 vcc, -1.0, v156
	s_nop 1
	v_cndmask_b32_e32 v151, v168, v151, vcc
	v_cmp_neq_f32_e32 vcc, -1.0, v156
	s_nop 1
	v_cndmask_b32_e32 v151, v169, v151, vcc
	v_cmp_lt_f32_e64 vcc, |v156|, s71
	s_nop 1
	v_cndmask_b32_e32 v151, v151, v156, vcc
;     __device__ __forceinline__ void operator()(const f32x4 (&acc)[2][2][4][2], const Unit& u, int wr, int wc, int fr, int fq) const {
;     ...
;                         for (int i = 0; i < 4; ++i) { float x0 = v0[i] + dt_bias[c0 + i], x1 = v1[i] + dt_bias[c0 + 4 + i];
;                             dp[i] = x0 > 20.f ? x0 : log1pf(__expf(x0)); dp[4 + i] = x1 > 20.f ? x1 : log1pf(__expf(x1)); }
.LBB0_885:
	s_or_b64 exec, exec, s[24:25]
	v_add_f32_e32 v136, v25, v136
	v_cmp_nlt_f32_e32 vcc, s67, v136
	global_store_dword v[154:155], v151, off offset:4
	s_and_saveexec_b64 s[24:25], vcc
	s_cbranch_execz .LBB0_887
	v_mul_f32_e32 v136, 0x3fb8aa3b, v136
	v_exp_f32_e32 v136, v136
	s_nop 0
	v_add_f32_e32 v151, 1.0, v136
	v_frexp_mant_f32_e32 v174, v151
	v_cvt_f64_f32_e32 v[172:173], v151
	v_add_f32_e32 v156, -1.0, v151
	v_frexp_exp_i32_f64_e32 v172, v[172:173]
	v_cmp_gt_f32_e32 vcc, s68, v174
	v_sub_f32_e32 v175, v156, v151
	v_sub_f32_e32 v156, v136, v156
	v_subbrev_co_u32_e32 v180, vcc, 0, v172, vcc
	v_add_f32_e32 v175, 1.0, v175
	v_sub_u32_e32 v172, 0, v180
	v_add_f32_e32 v156, v156, v175
	v_ldexp_f32 v151, v151, v172
	v_ldexp_f32 v156, v156, v172
	v_add_f32_e32 v172, -1.0, v151
	v_add_f32_e32 v173, 1.0, v172
	v_sub_f32_e32 v173, v151, v173
	v_add_f32_e32 v174, v156, v173
	v_add_f32_e32 v173, 1.0, v151
	v_add_f32_e32 v175, -1.0, v173
	v_sub_f32_e32 v151, v151, v175
	v_add_f32_e32 v151, v156, v151
	v_add_f32_e32 v156, v173, v151
	v_rcp_f32_e32 v181, v156
	v_sub_f32_e32 v173, v156, v173
	v_sub_f32_e32 v151, v151, v173
	v_add_f32_e32 v173, v172, v174
	v_sub_f32_e32 v172, v173, v172
	v_mul_f32_e32 v183, v173, v181
	v_sub_f32_e32 v182, v174, v172
	v_mul_f32_e32 v174, v156, v183
	v_fma_f32 v176, v183, v156, -v174
	v_fmac_f32_e32 v176, v183, v151
	v_add_f32_e32 v172, v174, v176
	v_sub_f32_e32 v175, v173, v172
	v_pk_add_f32 v[178:179], v[172:173], v[174:175] neg_lo:[0,1] neg_hi:[0,1]
	v_mov_b32_e32 v177, v172
	v_pk_add_f32 v[172:173], v[178:179], v[176:177] neg_lo:[0,1] neg_hi:[0,1]
	v_cmp_neq_f32_e32 vcc, s70, v136
	v_add_f32_e32 v173, v182, v173
	v_add_f32_e32 v172, v172, v173
	v_add_f32_e32 v173, v175, v172
	v_mul_f32_e32 v182, v181, v173
	v_mul_f32_e32 v174, v156, v182
	v_fma_f32 v176, v182, v156, -v174
	v_fmac_f32_e32 v176, v182, v151
	v_sub_f32_e32 v151, v175, v173
	v_add_f32_e32 v151, v172, v151
	v_add_f32_e32 v172, v174, v176
	v_sub_f32_e32 v175, v173, v172
	v_pk_add_f32 v[178:179], v[172:173], v[174:175] neg_lo:[0,1] neg_hi:[0,1]
	v_mov_b32_e32 v177, v172
	v_pk_add_f32 v[172:173], v[178:179], v[176:177] neg_lo:[0,1] neg_hi:[0,1]
	v_add_f32_e32 v156, v183, v182
	v_add_f32_e32 v151, v151, v173
	v_add_f32_e32 v151, v172, v151
	v_add_f32_e32 v151, v175, v151
	v_sub_f32_e32 v172, v156, v183
	v_mul_f32_e32 v151, v181, v151
	v_sub_f32_e32 v172, v182, v172
	v_add_f32_e32 v173, v172, v151
	v_add_f32_e32 v174, v156, v173
	v_cvt_f32_i32_e32 v172, v180
	v_mul_f32_e32 v176, v174, v174
	v_fmamk_f32 v151, v176, 0x3e9b6dac, v166
	v_sub_f32_e32 v156, v174, v156
	v_fmaak_f32 v151, v176, v151, 0x3f2aaada
	v_sub_f32_e32 v156, v173, v156
	v_mul_f32_e32 v173, v174, v176
	v_pk_mul_f32 v[176:177], v[172:173], v[150:151]
	v_ldexp_f32 v175, v174, 1
	v_fma_f32 v174, v172, s69, -v176
	v_fmac_f32_e32 v174, 0xb102e308, v172
	v_pk_add_f32 v[172:173], v[176:177], v[174:175]
	v_ldexp_f32 v156, v156, 1
	v_sub_f32_e32 v151, v173, v175
	v_sub_f32_e32 v151, v177, v151
	v_add_f32_e32 v179, v156, v151
	v_mov_b32_e32 v178, v176
	v_pk_add_f32 v[176:177], v[172:173], v[176:177] neg_lo:[0,1] neg_hi:[0,1]
	v_pk_add_f32 v[180:181], v[172:173], v[178:179]
	v_mov_b32_e32 v175, v172
	v_mov_b32_e32 v177, v181
	v_pk_add_f32 v[182:183], v[174:175], v[176:177] neg_lo:[0,1] neg_hi:[0,1]
	v_pk_add_f32 v[174:175], v[174:175], v[176:177]
	v_mov_b32_e32 v178, v179
	v_pk_add_f32 v[176:177], v[174:175], v[172:173] op_sel:[1,0] op_sel_hi:[0,1] neg_lo:[0,1] neg_hi:[0,1]
	v_pk_add_f32 v[184:185], v[180:181], v[176:177] op_sel_hi:[1,0] neg_lo:[0,1] neg_hi:[0,1]
	v_mov_b32_e32 v180, v181
	v_mov_b32_e32 v181, v175
	v_pk_mov_b32 v[176:177], v[172:173], v[176:177] op_sel:[1,0]
	v_mov_b32_e32 v179, v172
	v_pk_add_f32 v[176:177], v[180:181], v[176:177] neg_lo:[0,1] neg_hi:[0,1]
	v_mov_b32_e32 v184, v182
	v_pk_add_f32 v[172:173], v[178:179], v[176:177] neg_lo:[0,1] neg_hi:[0,1]
	v_mov_b32_e32 v183, v175
	v_pk_add_f32 v[176:177], v[184:185], v[172:173]
	s_nop 0
	v_pk_add_f32 v[178:179], v[176:177], v[176:177] op_sel:[0,1] op_sel_hi:[1,0]
	s_nop 0
	v_pk_add_f32 v[174:175], v[174:175], v[178:179] op_sel:[1,0] op_sel_hi:[0,1]
	v_mov_b32_e32 v177, v174
	v_pk_add_f32 v[180:181], v[176:177], v[182:183] neg_lo:[0,1] neg_hi:[0,1]
	v_mov_b32_e32 v173, v178
	v_sub_f32_e32 v151, v176, v180
	v_pk_add_f32 v[172:173], v[172:173], v[180:181] neg_lo:[0,1] neg_hi:[0,1]
	v_sub_f32_e32 v151, v182, v151
	v_add_f32_e32 v151, v172, v151
	v_add_f32_e32 v151, v151, v173
	v_add_f32_e32 v151, v174, v151
	v_cndmask_b32_e32 v151, v167, v151, vcc
	v_cmp_ngt_f32_e32 vcc, -1.0, v136
	s_nop 1
	v_cndmask_b32_e32 v151, v168, v151, vcc
	v_cmp_neq_f32_e32 vcc, -1.0, v136
	s_nop 1
	v_cndmask_b32_e32 v151, v169, v151, vcc
	v_cmp_lt_f32_e64 vcc, |v136|, s71
	s_nop 1
	v_cndmask_b32_e32 v136, v151, v136, vcc
;     __device__ __forceinline__ void operator()(const f32x4 (&acc)[2][2][4][2], const Unit& u, int wr, int wc, int fr, int fq) const {
;     ...
;                         for (int i = 0; i < 4; ++i) { float x0 = v0[i] + dt_bias[c0 + i], x1 = v1[i] + dt_bias[c0 + 4 + i];
;                             dp[i] = x0 > 20.f ? x0 : log1pf(__expf(x0)); dp[4 + i] = x1 > 20.f ? x1 : log1pf(__expf(x1)); }
.LBB0_887:
	s_or_b64 exec, exec, s[24:25]
	global_store_dword v[154:155], v136, off offset:20
	global_load_dword v136, v[140:141], off offset:8
	s_waitcnt vmcnt(0)
	v_add_f32_e32 v151, v30, v136
	global_load_dword v136, v[140:141], off offset:24
	v_cmp_nlt_f32_e32 vcc, s67, v151
	s_and_saveexec_b64 s[24:25], vcc
	s_cbranch_execz .LBB0_889
	v_mul_f32_e32 v151, 0x3fb8aa3b, v151
	v_exp_f32_e32 v156, v151
	s_nop 0
	v_add_f32_e32 v151, 1.0, v156
	v_frexp_mant_f32_e32 v175, v151
	v_cvt_f64_f32_e32 v[172:173], v151
	v_add_f32_e32 v174, -1.0, v151
	v_frexp_exp_i32_f64_e32 v172, v[172:173]
	v_cmp_gt_f32_e32 vcc, s68, v175
	v_sub_f32_e32 v176, v174, v151
	v_sub_f32_e32 v174, v156, v174
	v_subbrev_co_u32_e32 v180, vcc, 0, v172, vcc
	v_add_f32_e32 v176, 1.0, v176
	v_sub_u32_e32 v172, 0, v180
	v_add_f32_e32 v174, v174, v176
	v_ldexp_f32 v151, v151, v172
	v_ldexp_f32 v172, v174, v172
	v_add_f32_e32 v174, -1.0, v151
	v_add_f32_e32 v173, 1.0, v174
	v_sub_f32_e32 v173, v151, v173
	v_add_f32_e32 v175, v172, v173
	v_add_f32_e32 v173, 1.0, v151
	v_add_f32_e32 v176, -1.0, v173
	v_sub_f32_e32 v151, v151, v176
	v_add_f32_e32 v151, v172, v151
	v_add_f32_e32 v181, v173, v151
	v_rcp_f32_e32 v182, v181
	v_sub_f32_e32 v172, v181, v173
	v_add_f32_e32 v173, v174, v175
	v_sub_f32_e32 v151, v151, v172
	v_mul_f32_e32 v184, v173, v182
	v_sub_f32_e32 v172, v173, v174
	v_mul_f32_e32 v174, v181, v184
	v_fma_f32 v176, v184, v181, -v174
	v_fmac_f32_e32 v176, v184, v151
	v_sub_f32_e32 v183, v175, v172
	v_add_f32_e32 v172, v174, v176
	v_sub_f32_e32 v175, v173, v172
	v_pk_add_f32 v[178:179], v[172:173], v[174:175] neg_lo:[0,1] neg_hi:[0,1]
	v_mov_b32_e32 v177, v172
	v_pk_add_f32 v[172:173], v[178:179], v[176:177] neg_lo:[0,1] neg_hi:[0,1]
	v_cmp_neq_f32_e32 vcc, s70, v156
	v_add_f32_e32 v173, v183, v173
	v_add_f32_e32 v172, v172, v173
	v_add_f32_e32 v173, v175, v172
	v_mul_f32_e32 v183, v182, v173
	v_mul_f32_e32 v174, v181, v183
	v_fma_f32 v176, v183, v181, -v174
	v_fmac_f32_e32 v176, v183, v151
	v_sub_f32_e32 v151, v175, v173
	v_add_f32_e32 v151, v172, v151
	v_add_f32_e32 v172, v174, v176
	v_sub_f32_e32 v175, v173, v172
	v_pk_add_f32 v[178:179], v[172:173], v[174:175] neg_lo:[0,1] neg_hi:[0,1]
	v_mov_b32_e32 v177, v172
	v_pk_add_f32 v[172:173], v[178:179], v[176:177] neg_lo:[0,1] neg_hi:[0,1]
	s_nop 0
	v_add_f32_e32 v151, v151, v173
	v_add_f32_e32 v151, v172, v151
	v_add_f32_e32 v173, v184, v183
	v_add_f32_e32 v151, v175, v151
	v_sub_f32_e32 v172, v173, v184
	v_mul_f32_e32 v151, v182, v151
	v_sub_f32_e32 v172, v183, v172
	v_add_f32_e32 v174, v172, v151
	v_add_f32_e32 v176, v173, v174
	v_cvt_f32_i32_e32 v172, v180
	v_mul_f32_e32 v177, v176, v176
	v_sub_f32_e32 v173, v176, v173
	v_fmamk_f32 v151, v177, 0x3e9b6dac, v166
	v_sub_f32_e32 v173, v174, v173
	v_fmaak_f32 v151, v177, v151, 0x3f2aaada
	v_ldexp_f32 v178, v173, 1
	v_mul_f32_e32 v173, v176, v177
	v_ldexp_f32 v175, v176, 1
	v_pk_mul_f32 v[176:177], v[172:173], v[150:151]
	s_nop 0
	v_fma_f32 v174, v172, s69, -v176
	v_fmac_f32_e32 v174, 0xb102e308, v172
	v_pk_add_f32 v[172:173], v[176:177], v[174:175]
	s_nop 0
	v_sub_f32_e32 v151, v173, v175
	v_sub_f32_e32 v151, v177, v151
	v_add_f32_e32 v179, v178, v151
	v_mov_b32_e32 v178, v176
	v_pk_add_f32 v[176:177], v[172:173], v[176:177] neg_lo:[0,1] neg_hi:[0,1]
	v_pk_add_f32 v[180:181], v[172:173], v[178:179]
	v_mov_b32_e32 v175, v172
	v_mov_b32_e32 v177, v181
	v_pk_add_f32 v[182:183], v[174:175], v[176:177] neg_lo:[0,1] neg_hi:[0,1]
	v_pk_add_f32 v[174:175], v[174:175], v[176:177]
	v_mov_b32_e32 v178, v179
	v_pk_add_f32 v[176:177], v[174:175], v[172:173] op_sel:[1,0] op_sel_hi:[0,1] neg_lo:[0,1] neg_hi:[0,1]
	v_pk_add_f32 v[184:185], v[180:181], v[176:177] op_sel_hi:[1,0] neg_lo:[0,1] neg_hi:[0,1]
	v_mov_b32_e32 v180, v181
	v_mov_b32_e32 v181, v175
	v_pk_mov_b32 v[176:177], v[172:173], v[176:177] op_sel:[1,0]
	v_mov_b32_e32 v179, v172
	v_pk_add_f32 v[176:177], v[180:181], v[176:177] neg_lo:[0,1] neg_hi:[0,1]
	v_mov_b32_e32 v184, v182
	v_pk_add_f32 v[172:173], v[178:179], v[176:177] neg_lo:[0,1] neg_hi:[0,1]
	v_mov_b32_e32 v183, v175
	v_pk_add_f32 v[176:177], v[184:185], v[172:173]
	s_nop 0
	v_pk_add_f32 v[178:179], v[176:177], v[176:177] op_sel:[0,1] op_sel_hi:[1,0]
	s_nop 0
	v_pk_add_f32 v[174:175], v[174:175], v[178:179] op_sel:[1,0] op_sel_hi:[0,1]
	v_mov_b32_e32 v177, v174
	v_pk_add_f32 v[180:181], v[176:177], v[182:183] neg_lo:[0,1] neg_hi:[0,1]
	v_mov_b32_e32 v173, v178
	v_sub_f32_e32 v151, v176, v180
	v_pk_add_f32 v[172:173], v[172:173], v[180:181] neg_lo:[0,1] neg_hi:[0,1]
	v_sub_f32_e32 v151, v182, v151
	v_add_f32_e32 v151, v172, v151
	v_add_f32_e32 v151, v151, v173
	v_add_f32_e32 v151, v174, v151
	v_cndmask_b32_e32 v151, v167, v151, vcc
	v_cmp_ngt_f32_e32 vcc, -1.0, v156
	s_nop 1
	v_cndmask_b32_e32 v151, v168, v151, vcc
	v_cmp_neq_f32_e32 vcc, -1.0, v156
	s_nop 1
	v_cndmask_b32_e32 v151, v169, v151, vcc
	v_cmp_lt_f32_e64 vcc, |v156|, s71
	s_nop 1
	v_cndmask_b32_e32 v151, v151, v156, vcc
;     __device__ __forceinline__ void operator()(const f32x4 (&acc)[2][2][4][2], const Unit& u, int wr, int wc, int fr, int fq) const {
;     ...
;                         for (int i = 0; i < 4; ++i) { float x0 = v0[i] + dt_bias[c0 + i], x1 = v1[i] + dt_bias[c0 + 4 + i];
;                             dp[i] = x0 > 20.f ? x0 : log1pf(__expf(x0)); dp[4 + i] = x1 > 20.f ? x1 : log1pf(__expf(x1)); }
.LBB0_889:
	s_or_b64 exec, exec, s[24:25]
	s_waitcnt vmcnt(0)
	v_add_f32_e32 v136, v26, v136
	v_cmp_nlt_f32_e32 vcc, s67, v136
	global_store_dword v[154:155], v151, off offset:8
	s_and_saveexec_b64 s[24:25], vcc
	s_cbranch_execz .LBB0_891
	v_mul_f32_e32 v136, 0x3fb8aa3b, v136
	v_exp_f32_e32 v136, v136
	s_nop 0
	v_add_f32_e32 v151, 1.0, v136
	v_frexp_mant_f32_e32 v174, v151
	v_cvt_f64_f32_e32 v[172:173], v151
	v_add_f32_e32 v156, -1.0, v151
	v_frexp_exp_i32_f64_e32 v172, v[172:173]
	v_cmp_gt_f32_e32 vcc, s68, v174
	v_sub_f32_e32 v175, v156, v151
	v_sub_f32_e32 v156, v136, v156
	v_subbrev_co_u32_e32 v180, vcc, 0, v172, vcc
	v_add_f32_e32 v175, 1.0, v175
	v_sub_u32_e32 v172, 0, v180
	v_add_f32_e32 v156, v156, v175
	v_ldexp_f32 v151, v151, v172
	v_ldexp_f32 v156, v156, v172
	v_add_f32_e32 v172, -1.0, v151
	v_add_f32_e32 v173, 1.0, v172
	v_sub_f32_e32 v173, v151, v173
	v_add_f32_e32 v174, v156, v173
	v_add_f32_e32 v173, 1.0, v151
	v_add_f32_e32 v175, -1.0, v173
	v_sub_f32_e32 v151, v151, v175
	v_add_f32_e32 v151, v156, v151
	v_add_f32_e32 v156, v173, v151
	v_rcp_f32_e32 v181, v156
	v_sub_f32_e32 v173, v156, v173
	v_sub_f32_e32 v151, v151, v173
	v_add_f32_e32 v173, v172, v174
	v_sub_f32_e32 v172, v173, v172
	v_mul_f32_e32 v183, v173, v181
	v_sub_f32_e32 v182, v174, v172
	v_mul_f32_e32 v174, v156, v183
	v_fma_f32 v176, v183, v156, -v174
	v_fmac_f32_e32 v176, v183, v151
	v_add_f32_e32 v172, v174, v176
	v_sub_f32_e32 v175, v173, v172
	v_pk_add_f32 v[178:179], v[172:173], v[174:175] neg_lo:[0,1] neg_hi:[0,1]
	v_mov_b32_e32 v177, v172
	v_pk_add_f32 v[172:173], v[178:179], v[176:177] neg_lo:[0,1] neg_hi:[0,1]
	v_cmp_neq_f32_e32 vcc, s70, v136
	v_add_f32_e32 v173, v182, v173
	v_add_f32_e32 v172, v172, v173
	v_add_f32_e32 v173, v175, v172
	v_mul_f32_e32 v182, v181, v173
	v_mul_f32_e32 v174, v156, v182
	v_fma_f32 v176, v182, v156, -v174
	v_fmac_f32_e32 v176, v182, v151
	v_sub_f32_e32 v151, v175, v173
	v_add_f32_e32 v151, v172, v151
	v_add_f32_e32 v172, v174, v176
	v_sub_f32_e32 v175, v173, v172
	v_pk_add_f32 v[178:179], v[172:173], v[174:175] neg_lo:[0,1] neg_hi:[0,1]
	v_mov_b32_e32 v177, v172
	v_pk_add_f32 v[172:173], v[178:179], v[176:177] neg_lo:[0,1] neg_hi:[0,1]
	v_add_f32_e32 v156, v183, v182
	v_add_f32_e32 v151, v151, v173
	v_add_f32_e32 v151, v172, v151
	v_add_f32_e32 v151, v175, v151
	v_sub_f32_e32 v172, v156, v183
	v_mul_f32_e32 v151, v181, v151
	v_sub_f32_e32 v172, v182, v172
	v_add_f32_e32 v173, v172, v151
	v_add_f32_e32 v174, v156, v173
	v_cvt_f32_i32_e32 v172, v180
	v_mul_f32_e32 v176, v174, v174
	v_fmamk_f32 v151, v176, 0x3e9b6dac, v166
	v_sub_f32_e32 v156, v174, v156
	v_fmaak_f32 v151, v176, v151, 0x3f2aaada
	v_sub_f32_e32 v156, v173, v156
	v_mul_f32_e32 v173, v174, v176
	v_pk_mul_f32 v[176:177], v[172:173], v[150:151]
	v_ldexp_f32 v175, v174, 1
	v_fma_f32 v174, v172, s69, -v176
	v_fmac_f32_e32 v174, 0xb102e308, v172
	v_pk_add_f32 v[172:173], v[176:177], v[174:175]
	v_ldexp_f32 v156, v156, 1
	v_sub_f32_e32 v151, v173, v175
	v_sub_f32_e32 v151, v177, v151
	v_add_f32_e32 v179, v156, v151
	v_mov_b32_e32 v178, v176
	v_pk_add_f32 v[176:177], v[172:173], v[176:177] neg_lo:[0,1] neg_hi:[0,1]
	v_pk_add_f32 v[180:181], v[172:173], v[178:179]
	v_mov_b32_e32 v175, v172
	v_mov_b32_e32 v177, v181
	v_pk_add_f32 v[182:183], v[174:175], v[176:177] neg_lo:[0,1] neg_hi:[0,1]
	v_pk_add_f32 v[174:175], v[174:175], v[176:177]
	v_mov_b32_e32 v178, v179
	v_pk_add_f32 v[176:177], v[174:175], v[172:173] op_sel:[1,0] op_sel_hi:[0,1] neg_lo:[0,1] neg_hi:[0,1]
	v_pk_add_f32 v[184:185], v[180:181], v[176:177] op_sel_hi:[1,0] neg_lo:[0,1] neg_hi:[0,1]
	v_mov_b32_e32 v180, v181
	v_mov_b32_e32 v181, v175
	v_pk_mov_b32 v[176:177], v[172:173], v[176:177] op_sel:[1,0]
	v_mov_b32_e32 v179, v172
	v_pk_add_f32 v[176:177], v[180:181], v[176:177] neg_lo:[0,1] neg_hi:[0,1]
	v_mov_b32_e32 v184, v182
	v_pk_add_f32 v[172:173], v[178:179], v[176:177] neg_lo:[0,1] neg_hi:[0,1]
	v_mov_b32_e32 v183, v175
	v_pk_add_f32 v[176:177], v[184:185], v[172:173]
	s_nop 0
	v_pk_add_f32 v[178:179], v[176:177], v[176:177] op_sel:[0,1] op_sel_hi:[1,0]
	s_nop 0
	v_pk_add_f32 v[174:175], v[174:175], v[178:179] op_sel:[1,0] op_sel_hi:[0,1]
	v_mov_b32_e32 v177, v174
	v_pk_add_f32 v[180:181], v[176:177], v[182:183] neg_lo:[0,1] neg_hi:[0,1]
	v_mov_b32_e32 v173, v178
	v_sub_f32_e32 v151, v176, v180
	v_pk_add_f32 v[172:173], v[172:173], v[180:181] neg_lo:[0,1] neg_hi:[0,1]
	v_sub_f32_e32 v151, v182, v151
	v_add_f32_e32 v151, v172, v151
	v_add_f32_e32 v151, v151, v173
	v_add_f32_e32 v151, v174, v151
	v_cndmask_b32_e32 v151, v167, v151, vcc
	v_cmp_ngt_f32_e32 vcc, -1.0, v136
	s_nop 1
	v_cndmask_b32_e32 v151, v168, v151, vcc
	v_cmp_neq_f32_e32 vcc, -1.0, v136
	s_nop 1
	v_cndmask_b32_e32 v151, v169, v151, vcc
	v_cmp_lt_f32_e64 vcc, |v136|, s71
	s_nop 1
	v_cndmask_b32_e32 v136, v151, v136, vcc
;     __device__ __forceinline__ void operator()(const f32x4 (&acc)[2][2][4][2], const Unit& u, int wr, int wc, int fr, int fq) const {
;     ...
;                         for (int i = 0; i < 4; ++i) { float x0 = v0[i] + dt_bias[c0 + i], x1 = v1[i] + dt_bias[c0 + 4 + i];
;                             dp[i] = x0 > 20.f ? x0 : log1pf(__expf(x0)); dp[4 + i] = x1 > 20.f ? x1 : log1pf(__expf(x1)); }
.LBB0_891:
	s_or_b64 exec, exec, s[24:25]
	global_store_dword v[154:155], v136, off offset:24
	global_load_dword v136, v[140:141], off offset:12
	s_waitcnt vmcnt(0)
	v_add_f32_e32 v151, v31, v136
	global_load_dword v136, v[140:141], off offset:28
	v_cmp_nlt_f32_e32 vcc, s67, v151
	s_and_saveexec_b64 s[24:25], vcc
	s_cbranch_execz .LBB0_893
	v_mul_f32_e32 v151, 0x3fb8aa3b, v151
	v_exp_f32_e32 v156, v151
	s_nop 0
	v_add_f32_e32 v151, 1.0, v156
	v_frexp_mant_f32_e32 v175, v151
	v_cvt_f64_f32_e32 v[172:173], v151
	v_add_f32_e32 v174, -1.0, v151
	v_frexp_exp_i32_f64_e32 v172, v[172:173]
	v_cmp_gt_f32_e32 vcc, s68, v175
	v_sub_f32_e32 v176, v174, v151
	v_sub_f32_e32 v174, v156, v174
	v_subbrev_co_u32_e32 v180, vcc, 0, v172, vcc
	v_add_f32_e32 v176, 1.0, v176
	v_sub_u32_e32 v172, 0, v180
	v_add_f32_e32 v174, v174, v176
	v_ldexp_f32 v151, v151, v172
	v_ldexp_f32 v172, v174, v172
	v_add_f32_e32 v174, -1.0, v151
	v_add_f32_e32 v173, 1.0, v174
	v_sub_f32_e32 v173, v151, v173
	v_add_f32_e32 v175, v172, v173
	v_add_f32_e32 v173, 1.0, v151
	v_add_f32_e32 v176, -1.0, v173
	v_sub_f32_e32 v151, v151, v176
	v_add_f32_e32 v151, v172, v151
	v_add_f32_e32 v181, v173, v151
	v_rcp_f32_e32 v182, v181
	v_sub_f32_e32 v172, v181, v173
	v_add_f32_e32 v173, v174, v175
	v_sub_f32_e32 v151, v151, v172
	v_mul_f32_e32 v184, v173, v182
	v_sub_f32_e32 v172, v173, v174
	v_mul_f32_e32 v174, v181, v184
	v_fma_f32 v176, v184, v181, -v174
	v_fmac_f32_e32 v176, v184, v151
	v_sub_f32_e32 v183, v175, v172
	v_add_f32_e32 v172, v174, v176
	v_sub_f32_e32 v175, v173, v172
	v_pk_add_f32 v[178:179], v[172:173], v[174:175] neg_lo:[0,1] neg_hi:[0,1]
	v_mov_b32_e32 v177, v172
	v_pk_add_f32 v[172:173], v[178:179], v[176:177] neg_lo:[0,1] neg_hi:[0,1]
	v_cmp_neq_f32_e32 vcc, s70, v156
	v_add_f32_e32 v173, v183, v173
	v_add_f32_e32 v172, v172, v173
	v_add_f32_e32 v173, v175, v172
	v_mul_f32_e32 v183, v182, v173
	v_mul_f32_e32 v174, v181, v183
	v_fma_f32 v176, v183, v181, -v174
	v_fmac_f32_e32 v176, v183, v151
	v_sub_f32_e32 v151, v175, v173
	v_add_f32_e32 v151, v172, v151
	v_add_f32_e32 v172, v174, v176
	v_sub_f32_e32 v175, v173, v172
	v_pk_add_f32 v[178:179], v[172:173], v[174:175] neg_lo:[0,1] neg_hi:[0,1]
	v_mov_b32_e32 v177, v172
	v_pk_add_f32 v[172:173], v[178:179], v[176:177] neg_lo:[0,1] neg_hi:[0,1]
	s_nop 0
	v_add_f32_e32 v151, v151, v173
	v_add_f32_e32 v151, v172, v151
	v_add_f32_e32 v173, v184, v183
	v_add_f32_e32 v151, v175, v151
	v_sub_f32_e32 v172, v173, v184
	v_mul_f32_e32 v151, v182, v151
	v_sub_f32_e32 v172, v183, v172
	v_add_f32_e32 v174, v172, v151
	v_add_f32_e32 v176, v173, v174
	v_cvt_f32_i32_e32 v172, v180
	v_mul_f32_e32 v177, v176, v176
	v_sub_f32_e32 v173, v176, v173
	v_fmamk_f32 v151, v177, 0x3e9b6dac, v166
	v_sub_f32_e32 v173, v174, v173
	v_fmaak_f32 v151, v177, v151, 0x3f2aaada
	v_ldexp_f32 v178, v173, 1
	v_mul_f32_e32 v173, v176, v177
	v_ldexp_f32 v175, v176, 1
	v_pk_mul_f32 v[176:177], v[172:173], v[150:151]
	s_nop 0
	v_fma_f32 v174, v172, s69, -v176
	v_fmac_f32_e32 v174, 0xb102e308, v172
	v_pk_add_f32 v[172:173], v[176:177], v[174:175]
	s_nop 0
	v_sub_f32_e32 v151, v173, v175
	v_sub_f32_e32 v151, v177, v151
	v_add_f32_e32 v179, v178, v151
	v_mov_b32_e32 v178, v176
	v_pk_add_f32 v[176:177], v[172:173], v[176:177] neg_lo:[0,1] neg_hi:[0,1]
	v_pk_add_f32 v[180:181], v[172:173], v[178:179]
	v_mov_b32_e32 v175, v172
	v_mov_b32_e32 v177, v181
	v_pk_add_f32 v[182:183], v[174:175], v[176:177] neg_lo:[0,1] neg_hi:[0,1]
	v_pk_add_f32 v[174:175], v[174:175], v[176:177]
	v_mov_b32_e32 v178, v179
	v_pk_add_f32 v[176:177], v[174:175], v[172:173] op_sel:[1,0] op_sel_hi:[0,1] neg_lo:[0,1] neg_hi:[0,1]
	v_pk_add_f32 v[184:185], v[180:181], v[176:177] op_sel_hi:[1,0] neg_lo:[0,1] neg_hi:[0,1]
	v_mov_b32_e32 v180, v181
	v_mov_b32_e32 v181, v175
	v_pk_mov_b32 v[176:177], v[172:173], v[176:177] op_sel:[1,0]
	v_mov_b32_e32 v179, v172
	v_pk_add_f32 v[176:177], v[180:181], v[176:177] neg_lo:[0,1] neg_hi:[0,1]
	v_mov_b32_e32 v184, v182
	v_pk_add_f32 v[172:173], v[178:179], v[176:177] neg_lo:[0,1] neg_hi:[0,1]
	v_mov_b32_e32 v183, v175
	v_pk_add_f32 v[176:177], v[184:185], v[172:173]
	s_nop 0
	v_pk_add_f32 v[178:179], v[176:177], v[176:177] op_sel:[0,1] op_sel_hi:[1,0]
	s_nop 0
	v_pk_add_f32 v[174:175], v[174:175], v[178:179] op_sel:[1,0] op_sel_hi:[0,1]
	v_mov_b32_e32 v177, v174
	v_pk_add_f32 v[180:181], v[176:177], v[182:183] neg_lo:[0,1] neg_hi:[0,1]
	v_mov_b32_e32 v173, v178
	v_sub_f32_e32 v151, v176, v180
	v_pk_add_f32 v[172:173], v[172:173], v[180:181] neg_lo:[0,1] neg_hi:[0,1]
	v_sub_f32_e32 v151, v182, v151
	v_add_f32_e32 v151, v172, v151
	v_add_f32_e32 v151, v151, v173
	v_add_f32_e32 v151, v174, v151
	v_cndmask_b32_e32 v151, v167, v151, vcc
	v_cmp_ngt_f32_e32 vcc, -1.0, v156
	s_nop 1
	v_cndmask_b32_e32 v151, v168, v151, vcc
	v_cmp_neq_f32_e32 vcc, -1.0, v156
	s_nop 1
	v_cndmask_b32_e32 v151, v169, v151, vcc
	v_cmp_lt_f32_e64 vcc, |v156|, s71
	s_nop 1
	v_cndmask_b32_e32 v151, v151, v156, vcc
;     __device__ __forceinline__ void operator()(const f32x4 (&acc)[2][2][4][2], const Unit& u, int wr, int wc, int fr, int fq) const {
;     ...
;                         for (int i = 0; i < 4; ++i) { float x0 = v0[i] + dt_bias[c0 + i], x1 = v1[i] + dt_bias[c0 + 4 + i];
;                             dp[i] = x0 > 20.f ? x0 : log1pf(__expf(x0)); dp[4 + i] = x1 > 20.f ? x1 : log1pf(__expf(x1)); }
.LBB0_893:
	s_or_b64 exec, exec, s[24:25]
	s_waitcnt vmcnt(0)
	v_add_f32_e32 v136, v27, v136
	v_cmp_nlt_f32_e32 vcc, s67, v136
	global_store_dword v[154:155], v151, off offset:12
	s_and_saveexec_b64 s[24:25], vcc
	s_cbranch_execz .LBB0_895
	v_mul_f32_e32 v136, 0x3fb8aa3b, v136
	v_exp_f32_e32 v136, v136
	s_nop 0
	v_add_f32_e32 v151, 1.0, v136
	v_frexp_mant_f32_e32 v174, v151
	v_cvt_f64_f32_e32 v[172:173], v151
	v_add_f32_e32 v156, -1.0, v151
	v_frexp_exp_i32_f64_e32 v172, v[172:173]
	v_cmp_gt_f32_e32 vcc, s68, v174
	v_sub_f32_e32 v175, v156, v151
	v_sub_f32_e32 v156, v136, v156
	v_subbrev_co_u32_e32 v180, vcc, 0, v172, vcc
	v_add_f32_e32 v175, 1.0, v175
	v_sub_u32_e32 v172, 0, v180
	v_add_f32_e32 v156, v156, v175
	v_ldexp_f32 v151, v151, v172
	v_ldexp_f32 v156, v156, v172
	v_add_f32_e32 v172, -1.0, v151
	v_add_f32_e32 v173, 1.0, v172
	v_sub_f32_e32 v173, v151, v173
	v_add_f32_e32 v174, v156, v173
	v_add_f32_e32 v173, 1.0, v151
	v_add_f32_e32 v175, -1.0, v173
	v_sub_f32_e32 v151, v151, v175
	v_add_f32_e32 v151, v156, v151
	v_add_f32_e32 v156, v173, v151
	v_rcp_f32_e32 v181, v156
	v_sub_f32_e32 v173, v156, v173
	v_sub_f32_e32 v151, v151, v173
	v_add_f32_e32 v173, v172, v174
	v_sub_f32_e32 v172, v173, v172
	v_mul_f32_e32 v183, v173, v181
	v_sub_f32_e32 v182, v174, v172
	v_mul_f32_e32 v174, v156, v183
	v_fma_f32 v176, v183, v156, -v174
	v_fmac_f32_e32 v176, v183, v151
	v_add_f32_e32 v172, v174, v176
	v_sub_f32_e32 v175, v173, v172
	v_pk_add_f32 v[178:179], v[172:173], v[174:175] neg_lo:[0,1] neg_hi:[0,1]
	v_mov_b32_e32 v177, v172
	v_pk_add_f32 v[172:173], v[178:179], v[176:177] neg_lo:[0,1] neg_hi:[0,1]
	v_cmp_neq_f32_e32 vcc, s70, v136
	v_add_f32_e32 v173, v182, v173
	v_add_f32_e32 v172, v172, v173
	v_add_f32_e32 v173, v175, v172
	v_mul_f32_e32 v182, v181, v173
	v_mul_f32_e32 v174, v156, v182
	v_fma_f32 v176, v182, v156, -v174
	v_fmac_f32_e32 v176, v182, v151
	v_sub_f32_e32 v151, v175, v173
	v_add_f32_e32 v151, v172, v151
	v_add_f32_e32 v172, v174, v176
	v_sub_f32_e32 v175, v173, v172
	v_pk_add_f32 v[178:179], v[172:173], v[174:175] neg_lo:[0,1] neg_hi:[0,1]
	v_mov_b32_e32 v177, v172
	v_pk_add_f32 v[172:173], v[178:179], v[176:177] neg_lo:[0,1] neg_hi:[0,1]
	v_add_f32_e32 v156, v183, v182
	v_add_f32_e32 v151, v151, v173
	v_add_f32_e32 v151, v172, v151
	v_add_f32_e32 v151, v175, v151
	v_sub_f32_e32 v172, v156, v183
	v_mul_f32_e32 v151, v181, v151
	v_sub_f32_e32 v172, v182, v172
	v_add_f32_e32 v173, v172, v151
	v_add_f32_e32 v174, v156, v173
	v_cvt_f32_i32_e32 v172, v180
	v_mul_f32_e32 v176, v174, v174
	v_fmamk_f32 v151, v176, 0x3e9b6dac, v166
	v_sub_f32_e32 v156, v174, v156
	v_fmaak_f32 v151, v176, v151, 0x3f2aaada
	v_sub_f32_e32 v156, v173, v156
	v_mul_f32_e32 v173, v174, v176
	v_pk_mul_f32 v[176:177], v[172:173], v[150:151]
	v_ldexp_f32 v175, v174, 1
	v_fma_f32 v174, v172, s69, -v176
	v_fmac_f32_e32 v174, 0xb102e308, v172
	v_pk_add_f32 v[172:173], v[176:177], v[174:175]
	v_ldexp_f32 v156, v156, 1
	v_sub_f32_e32 v151, v173, v175
	v_sub_f32_e32 v151, v177, v151
	v_add_f32_e32 v179, v156, v151
	v_mov_b32_e32 v178, v176
	v_pk_add_f32 v[176:177], v[172:173], v[176:177] neg_lo:[0,1] neg_hi:[0,1]
	v_pk_add_f32 v[180:181], v[172:173], v[178:179]
	v_mov_b32_e32 v175, v172
	v_mov_b32_e32 v177, v181
	v_pk_add_f32 v[182:183], v[174:175], v[176:177] neg_lo:[0,1] neg_hi:[0,1]
	v_pk_add_f32 v[174:175], v[174:175], v[176:177]
	v_mov_b32_e32 v178, v179
	v_pk_add_f32 v[176:177], v[174:175], v[172:173] op_sel:[1,0] op_sel_hi:[0,1] neg_lo:[0,1] neg_hi:[0,1]
	v_pk_add_f32 v[184:185], v[180:181], v[176:177] op_sel_hi:[1,0] neg_lo:[0,1] neg_hi:[0,1]
	v_mov_b32_e32 v180, v181
	v_mov_b32_e32 v181, v175
	v_pk_mov_b32 v[176:177], v[172:173], v[176:177] op_sel:[1,0]
	v_mov_b32_e32 v179, v172
	v_pk_add_f32 v[176:177], v[180:181], v[176:177] neg_lo:[0,1] neg_hi:[0,1]
	v_mov_b32_e32 v184, v182
	v_pk_add_f32 v[172:173], v[178:179], v[176:177] neg_lo:[0,1] neg_hi:[0,1]
	v_mov_b32_e32 v183, v175
	v_pk_add_f32 v[176:177], v[184:185], v[172:173]
	s_nop 0
	v_pk_add_f32 v[178:179], v[176:177], v[176:177] op_sel:[0,1] op_sel_hi:[1,0]
	s_nop 0
	v_pk_add_f32 v[174:175], v[174:175], v[178:179] op_sel:[1,0] op_sel_hi:[0,1]
	v_mov_b32_e32 v177, v174
	v_pk_add_f32 v[180:181], v[176:177], v[182:183] neg_lo:[0,1] neg_hi:[0,1]
	v_mov_b32_e32 v173, v178
	v_sub_f32_e32 v151, v176, v180
	v_pk_add_f32 v[172:173], v[172:173], v[180:181] neg_lo:[0,1] neg_hi:[0,1]
	v_sub_f32_e32 v151, v182, v151
	v_add_f32_e32 v151, v172, v151
	v_add_f32_e32 v151, v151, v173
	v_add_f32_e32 v151, v174, v151
	v_cndmask_b32_e32 v151, v167, v151, vcc
	v_cmp_ngt_f32_e32 vcc, -1.0, v136
	s_nop 1
	v_cndmask_b32_e32 v151, v168, v151, vcc
	v_cmp_neq_f32_e32 vcc, -1.0, v136
	s_nop 1
	v_cndmask_b32_e32 v151, v169, v151, vcc
	v_cmp_lt_f32_e64 vcc, |v136|, s71
	s_nop 1
	v_cndmask_b32_e32 v136, v151, v136, vcc
;     __device__ __forceinline__ void operator()(const f32x4 (&acc)[2][2][4][2], const Unit& u, int wr, int wc, int fr, int fq) const {
;     ...
;                         for (int i = 0; i < 4; ++i) { float x0 = v0[i] + dt_bias[c0 + i], x1 = v1[i] + dt_bias[c0 + 4 + i];
;                             dp[i] = x0 > 20.f ? x0 : log1pf(__expf(x0)); dp[4 + i] = x1 > 20.f ? x1 : log1pf(__expf(x1)); }
.LBB0_895:
	s_or_b64 exec, exec, s[24:25]
	global_store_dword v[154:155], v136, off offset:28
	global_load_dword v136, v[140:141], off
	s_waitcnt vmcnt(0)
	v_add_f32_e32 v151, v12, v136
	global_load_dword v136, v[140:141], off offset:16
	v_cmp_nlt_f32_e32 vcc, s67, v151
	s_and_saveexec_b64 s[24:25], vcc
	s_cbranch_execz .LBB0_897
	v_mul_f32_e32 v151, 0x3fb8aa3b, v151
	v_exp_f32_e32 v156, v151
	s_nop 0
	v_add_f32_e32 v151, 1.0, v156
	v_frexp_mant_f32_e32 v173, v151
	v_cvt_f64_f32_e32 v[154:155], v151
	v_add_f32_e32 v172, -1.0, v151
	v_frexp_exp_i32_f64_e32 v154, v[154:155]
	v_cmp_gt_f32_e32 vcc, s68, v173
	v_sub_f32_e32 v174, v172, v151
	v_sub_f32_e32 v172, v156, v172
	v_subbrev_co_u32_e32 v178, vcc, 0, v154, vcc
	v_add_f32_e32 v174, 1.0, v174
	v_sub_u32_e32 v154, 0, v178
	v_add_f32_e32 v172, v172, v174
	v_ldexp_f32 v151, v151, v154
	v_ldexp_f32 v154, v172, v154
	v_add_f32_e32 v172, -1.0, v151
	v_add_f32_e32 v155, 1.0, v172
	v_sub_f32_e32 v155, v151, v155
	v_add_f32_e32 v173, v154, v155
	v_add_f32_e32 v155, 1.0, v151
	v_add_f32_e32 v174, -1.0, v155
	v_sub_f32_e32 v151, v151, v174
	v_add_f32_e32 v151, v154, v151
	v_add_f32_e32 v179, v155, v151
	v_rcp_f32_e32 v180, v179
	v_sub_f32_e32 v154, v179, v155
	v_add_f32_e32 v155, v172, v173
	v_sub_f32_e32 v151, v151, v154
	v_mul_f32_e32 v182, v155, v180
	v_sub_f32_e32 v154, v155, v172
	v_mul_f32_e32 v172, v179, v182
	v_fma_f32 v174, v182, v179, -v172
	v_fmac_f32_e32 v174, v182, v151
	v_sub_f32_e32 v181, v173, v154
	v_add_f32_e32 v154, v172, v174
	v_sub_f32_e32 v173, v155, v154
	v_pk_add_f32 v[176:177], v[154:155], v[172:173] neg_lo:[0,1] neg_hi:[0,1]
	v_mov_b32_e32 v175, v154
	v_pk_add_f32 v[154:155], v[176:177], v[174:175] neg_lo:[0,1] neg_hi:[0,1]
	v_cmp_neq_f32_e32 vcc, s70, v156
	v_add_f32_e32 v155, v181, v155
	v_add_f32_e32 v154, v154, v155
	v_add_f32_e32 v155, v173, v154
	v_mul_f32_e32 v181, v180, v155
	v_mul_f32_e32 v172, v179, v181
	v_fma_f32 v174, v181, v179, -v172
	v_fmac_f32_e32 v174, v181, v151
	v_sub_f32_e32 v151, v173, v155
	v_add_f32_e32 v151, v154, v151
	v_add_f32_e32 v154, v172, v174
	v_sub_f32_e32 v173, v155, v154
	v_pk_add_f32 v[176:177], v[154:155], v[172:173] neg_lo:[0,1] neg_hi:[0,1]
	v_mov_b32_e32 v175, v154
	v_pk_add_f32 v[154:155], v[176:177], v[174:175] neg_lo:[0,1] neg_hi:[0,1]
	s_nop 0
	v_add_f32_e32 v151, v151, v155
	v_add_f32_e32 v151, v154, v151
	v_add_f32_e32 v155, v182, v181
	v_add_f32_e32 v151, v173, v151
	v_sub_f32_e32 v154, v155, v182
	v_mul_f32_e32 v151, v180, v151
	v_sub_f32_e32 v154, v181, v154
	v_add_f32_e32 v172, v154, v151
	v_add_f32_e32 v174, v155, v172
	v_cvt_f32_i32_e32 v154, v178
	v_mul_f32_e32 v175, v174, v174
	v_sub_f32_e32 v155, v174, v155
	v_fmamk_f32 v151, v175, 0x3e9b6dac, v166
	v_sub_f32_e32 v155, v172, v155
	v_fmaak_f32 v151, v175, v151, 0x3f2aaada
	v_ldexp_f32 v176, v155, 1
	v_mul_f32_e32 v155, v174, v175
	v_ldexp_f32 v173, v174, 1
	v_pk_mul_f32 v[174:175], v[154:155], v[150:151]
	s_nop 0
	v_fma_f32 v172, v154, s69, -v174
	v_fmac_f32_e32 v172, 0xb102e308, v154
	v_pk_add_f32 v[154:155], v[174:175], v[172:173]
	s_nop 0
	v_sub_f32_e32 v151, v155, v173
	v_sub_f32_e32 v151, v175, v151
	v_add_f32_e32 v177, v176, v151
	v_mov_b32_e32 v176, v174
	v_pk_add_f32 v[174:175], v[154:155], v[174:175] neg_lo:[0,1] neg_hi:[0,1]
	v_pk_add_f32 v[178:179], v[154:155], v[176:177]
	v_mov_b32_e32 v173, v154
	v_mov_b32_e32 v175, v179
	v_pk_add_f32 v[180:181], v[172:173], v[174:175] neg_lo:[0,1] neg_hi:[0,1]
	v_pk_add_f32 v[172:173], v[172:173], v[174:175]
	v_mov_b32_e32 v176, v177
	v_pk_add_f32 v[174:175], v[172:173], v[154:155] op_sel:[1,0] op_sel_hi:[0,1] neg_lo:[0,1] neg_hi:[0,1]
	v_pk_add_f32 v[182:183], v[178:179], v[174:175] op_sel_hi:[1,0] neg_lo:[0,1] neg_hi:[0,1]
	v_mov_b32_e32 v178, v179
	v_mov_b32_e32 v179, v173
	v_pk_mov_b32 v[174:175], v[154:155], v[174:175] op_sel:[1,0]
	v_mov_b32_e32 v177, v154
	v_pk_add_f32 v[174:175], v[178:179], v[174:175] neg_lo:[0,1] neg_hi:[0,1]
	v_mov_b32_e32 v182, v180
	v_pk_add_f32 v[154:155], v[176:177], v[174:175] neg_lo:[0,1] neg_hi:[0,1]
	v_mov_b32_e32 v181, v173
	v_pk_add_f32 v[174:175], v[182:183], v[154:155]
	s_nop 0
	v_pk_add_f32 v[176:177], v[174:175], v[174:175] op_sel:[0,1] op_sel_hi:[1,0]
	s_nop 0
	v_pk_add_f32 v[172:173], v[172:173], v[176:177] op_sel:[1,0] op_sel_hi:[0,1]
	v_mov_b32_e32 v175, v172
	v_pk_add_f32 v[178:179], v[174:175], v[180:181] neg_lo:[0,1] neg_hi:[0,1]
	v_mov_b32_e32 v155, v176
	v_sub_f32_e32 v151, v174, v178
	v_pk_add_f32 v[154:155], v[154:155], v[178:179] neg_lo:[0,1] neg_hi:[0,1]
	v_sub_f32_e32 v151, v180, v151
	v_add_f32_e32 v151, v154, v151
	v_add_f32_e32 v151, v151, v155
	v_add_f32_e32 v151, v172, v151
	v_cndmask_b32_e32 v151, v167, v151, vcc
	v_cmp_ngt_f32_e32 vcc, -1.0, v156
	s_nop 1
	v_cndmask_b32_e32 v151, v168, v151, vcc
	v_cmp_neq_f32_e32 vcc, -1.0, v156
	s_nop 1
	v_cndmask_b32_e32 v151, v169, v151, vcc
	v_cmp_lt_f32_e64 vcc, |v156|, s71
	s_nop 1
	v_cndmask_b32_e32 v151, v151, v156, vcc
;     __device__ __forceinline__ void operator()(const f32x4 (&acc)[2][2][4][2], const Unit& u, int wr, int wc, int fr, int fq) const {
;     ...
;                     for (int m = 0; m < 4; ++m) { const int r = row0 + ai * HALF + m * 16;
;                         const f32x4 v0 = acc[ai][0][m][0], v1 = acc[ai][0][m][1]; float* dp = DT + (size_t)r * 32 + c0;
; #pragma unroll
;                         for (int i = 0; i < 4; ++i) { float x0 = v0[i] + dt_bias[c0 + i], x1 = v1[i] + dt_bias[c0 + 4 + i];
;                             dp[i] = x0 > 20.f ? x0 : log1pf(__expf(x0)); dp[4 + i] = x1 > 20.f ? x1 : log1pf(__expf(x1)); }
.LBB0_897:
	s_or_b64 exec, exec, s[24:25]
	v_lshlrev_b64 v[154:155], 7, v[152:153]
	v_lshl_add_u64 v[154:155], v[138:139], 0, v[154:155]
	v_add_co_u32_e32 v172, vcc, 0x5000, v154
	s_waitcnt vmcnt(0)
	v_add_f32_e32 v136, v8, v136
	v_addc_co_u32_e32 v173, vcc, 0, v155, vcc
	v_cmp_nlt_f32_e32 vcc, s67, v136
	global_store_dword v[172:173], v151, off offset:2048
	s_and_saveexec_b64 s[24:25], vcc
	s_cbranch_execz .LBB0_899
	v_mul_f32_e32 v136, 0x3fb8aa3b, v136
	v_exp_f32_e32 v136, v136
	s_nop 0
	v_add_f32_e32 v151, 1.0, v136
	v_frexp_mant_f32_e32 v156, v151
	v_cvt_f64_f32_e32 v[172:173], v151
	v_add_f32_e32 v153, -1.0, v151
	v_frexp_exp_i32_f64_e32 v172, v[172:173]
	v_cmp_gt_f32_e32 vcc, s68, v156
	v_sub_f32_e32 v174, v153, v151
	v_sub_f32_e32 v153, v136, v153
	v_subbrev_co_u32_e32 v156, vcc, 0, v172, vcc
	v_add_f32_e32 v174, 1.0, v174
	v_sub_u32_e32 v172, 0, v156
	v_add_f32_e32 v153, v153, v174
	v_ldexp_f32 v151, v151, v172
	v_ldexp_f32 v153, v153, v172
	v_add_f32_e32 v172, -1.0, v151
	v_add_f32_e32 v173, 1.0, v172
	v_sub_f32_e32 v173, v151, v173
	v_add_f32_e32 v174, v153, v173
	v_add_f32_e32 v173, 1.0, v151
	v_add_f32_e32 v175, -1.0, v173
	v_sub_f32_e32 v151, v151, v175
	v_add_f32_e32 v151, v153, v151
	v_add_f32_e32 v153, v173, v151
	v_rcp_f32_e32 v180, v153
	v_sub_f32_e32 v173, v153, v173
	v_sub_f32_e32 v151, v151, v173
	v_add_f32_e32 v173, v172, v174
	v_sub_f32_e32 v172, v173, v172
	v_mul_f32_e32 v182, v173, v180
	v_sub_f32_e32 v181, v174, v172
	v_mul_f32_e32 v174, v153, v182
	v_fma_f32 v176, v182, v153, -v174
	v_fmac_f32_e32 v176, v182, v151
	v_add_f32_e32 v172, v174, v176
	v_sub_f32_e32 v175, v173, v172
	v_pk_add_f32 v[178:179], v[172:173], v[174:175] neg_lo:[0,1] neg_hi:[0,1]
	v_mov_b32_e32 v177, v172
	v_pk_add_f32 v[172:173], v[178:179], v[176:177] neg_lo:[0,1] neg_hi:[0,1]
	v_cmp_neq_f32_e32 vcc, s70, v136
	v_add_f32_e32 v173, v181, v173
	v_add_f32_e32 v172, v172, v173
	v_add_f32_e32 v173, v175, v172
	v_mul_f32_e32 v181, v180, v173
	v_mul_f32_e32 v174, v153, v181
	v_fma_f32 v176, v181, v153, -v174
	v_fmac_f32_e32 v176, v181, v151
	v_sub_f32_e32 v151, v175, v173
	v_add_f32_e32 v151, v172, v151
	v_add_f32_e32 v172, v174, v176
	v_sub_f32_e32 v175, v173, v172
	v_pk_add_f32 v[178:179], v[172:173], v[174:175] neg_lo:[0,1] neg_hi:[0,1]
	v_mov_b32_e32 v177, v172
	v_pk_add_f32 v[172:173], v[178:179], v[176:177] neg_lo:[0,1] neg_hi:[0,1]
	v_add_f32_e32 v153, v182, v181
	v_add_f32_e32 v151, v151, v173
	v_add_f32_e32 v151, v172, v151
	v_add_f32_e32 v151, v175, v151
	v_sub_f32_e32 v172, v153, v182
	v_mul_f32_e32 v151, v180, v151
	v_sub_f32_e32 v172, v181, v172
	v_add_f32_e32 v173, v172, v151
	v_add_f32_e32 v174, v153, v173
	v_cvt_f32_i32_e32 v172, v156
	v_mul_f32_e32 v176, v174, v174
	v_fmamk_f32 v151, v176, 0x3e9b6dac, v166
	v_sub_f32_e32 v153, v174, v153
	v_fmaak_f32 v151, v176, v151, 0x3f2aaada
	v_sub_f32_e32 v153, v173, v153
	v_mul_f32_e32 v173, v174, v176
	v_pk_mul_f32 v[176:177], v[172:173], v[150:151]
	v_ldexp_f32 v175, v174, 1
	v_fma_f32 v174, v172, s69, -v176
	v_fmac_f32_e32 v174, 0xb102e308, v172
	v_pk_add_f32 v[172:173], v[176:177], v[174:175]
	v_ldexp_f32 v153, v153, 1
	v_sub_f32_e32 v151, v173, v175
	v_sub_f32_e32 v151, v177, v151
	v_add_f32_e32 v179, v153, v151
	v_mov_b32_e32 v178, v176
	v_pk_add_f32 v[176:177], v[172:173], v[176:177] neg_lo:[0,1] neg_hi:[0,1]
	v_pk_add_f32 v[180:181], v[172:173], v[178:179]
	v_mov_b32_e32 v175, v172
	v_mov_b32_e32 v177, v181
	v_pk_add_f32 v[182:183], v[174:175], v[176:177] neg_lo:[0,1] neg_hi:[0,1]
	v_pk_add_f32 v[174:175], v[174:175], v[176:177]
	v_mov_b32_e32 v178, v179
	v_pk_add_f32 v[176:177], v[174:175], v[172:173] op_sel:[1,0] op_sel_hi:[0,1] neg_lo:[0,1] neg_hi:[0,1]
	v_pk_add_f32 v[184:185], v[180:181], v[176:177] op_sel_hi:[1,0] neg_lo:[0,1] neg_hi:[0,1]
	v_mov_b32_e32 v180, v181
	v_mov_b32_e32 v181, v175
	v_pk_mov_b32 v[176:177], v[172:173], v[176:177] op_sel:[1,0]
	v_mov_b32_e32 v179, v172
	v_pk_add_f32 v[176:177], v[180:181], v[176:177] neg_lo:[0,1] neg_hi:[0,1]
	v_mov_b32_e32 v184, v182
	v_pk_add_f32 v[172:173], v[178:179], v[176:177] neg_lo:[0,1] neg_hi:[0,1]
	v_mov_b32_e32 v183, v175
	v_pk_add_f32 v[176:177], v[184:185], v[172:173]
	s_nop 0
	v_pk_add_f32 v[178:179], v[176:177], v[176:177] op_sel:[0,1] op_sel_hi:[1,0]
	s_nop 0
	v_pk_add_f32 v[174:175], v[174:175], v[178:179] op_sel:[1,0] op_sel_hi:[0,1]
	v_mov_b32_e32 v177, v174
	v_pk_add_f32 v[180:181], v[176:177], v[182:183] neg_lo:[0,1] neg_hi:[0,1]
	v_mov_b32_e32 v173, v178
	v_sub_f32_e32 v151, v176, v180
	v_pk_add_f32 v[172:173], v[172:173], v[180:181] neg_lo:[0,1] neg_hi:[0,1]
	v_sub_f32_e32 v151, v182, v151
	v_add_f32_e32 v151, v172, v151
	v_add_f32_e32 v151, v151, v173
	v_add_f32_e32 v151, v174, v151
	v_cndmask_b32_e32 v151, v167, v151, vcc
	v_cmp_ngt_f32_e32 vcc, -1.0, v136
	s_nop 1
	v_cndmask_b32_e32 v151, v168, v151, vcc
	v_cmp_neq_f32_e32 vcc, -1.0, v136
	s_nop 1
	v_cndmask_b32_e32 v151, v169, v151, vcc
	v_cmp_lt_f32_e64 vcc, |v136|, s71
	s_nop 1
	v_cndmask_b32_e32 v136, v151, v136, vcc
;     __device__ __forceinline__ void operator()(const f32x4 (&acc)[2][2][4][2], const Unit& u, int wr, int wc, int fr, int fq) const {
;     ...
;                         for (int i = 0; i < 4; ++i) { float x0 = v0[i] + dt_bias[c0 + i], x1 = v1[i] + dt_bias[c0 + 4 + i];
;                             dp[i] = x0 > 20.f ? x0 : log1pf(__expf(x0)); dp[4 + i] = x1 > 20.f ? x1 : log1pf(__expf(x1)); }
.LBB0_899:
	s_or_b64 exec, exec, s[24:25]
	s_mov_b64 s[24:25], 0x5800
	v_lshl_add_u64 v[154:155], v[154:155], 0, s[24:25]
	global_store_dword v[154:155], v136, off offset:16
	global_load_dword v151, v[140:141], off offset:4
	s_nop 0
	global_load_dword v136, v[140:141], off offset:20
	s_waitcnt vmcnt(0)
	v_add_f32_e32 v151, v13, v151
	v_cmp_nlt_f32_e32 vcc, s67, v151
	s_and_saveexec_b64 s[24:25], vcc
	s_cbranch_execz .LBB0_901
	v_mul_f32_e32 v151, 0x3fb8aa3b, v151
	v_exp_f32_e32 v153, v151
	s_nop 0
	v_add_f32_e32 v151, 1.0, v153
	v_frexp_mant_f32_e32 v174, v151
	v_cvt_f64_f32_e32 v[172:173], v151
	v_add_f32_e32 v156, -1.0, v151
	v_frexp_exp_i32_f64_e32 v172, v[172:173]
	v_cmp_gt_f32_e32 vcc, s68, v174
	v_sub_f32_e32 v175, v156, v151
	v_sub_f32_e32 v156, v153, v156
	v_subbrev_co_u32_e32 v180, vcc, 0, v172, vcc
	v_add_f32_e32 v175, 1.0, v175
	v_sub_u32_e32 v172, 0, v180
	v_add_f32_e32 v156, v156, v175
	v_ldexp_f32 v151, v151, v172
	v_ldexp_f32 v156, v156, v172
	v_add_f32_e32 v172, -1.0, v151
	v_add_f32_e32 v173, 1.0, v172
	v_sub_f32_e32 v173, v151, v173
	v_add_f32_e32 v174, v156, v173
	v_add_f32_e32 v173, 1.0, v151
	v_add_f32_e32 v175, -1.0, v173
	v_sub_f32_e32 v151, v151, v175
	v_add_f32_e32 v151, v156, v151
	v_add_f32_e32 v156, v173, v151
	v_rcp_f32_e32 v181, v156
	v_sub_f32_e32 v173, v156, v173
	v_sub_f32_e32 v151, v151, v173
	v_add_f32_e32 v173, v172, v174
	v_sub_f32_e32 v172, v173, v172
	v_mul_f32_e32 v183, v173, v181
	v_sub_f32_e32 v182, v174, v172
	v_mul_f32_e32 v174, v156, v183
	v_fma_f32 v176, v183, v156, -v174
	v_fmac_f32_e32 v176, v183, v151
	v_add_f32_e32 v172, v174, v176
	v_sub_f32_e32 v175, v173, v172
	v_pk_add_f32 v[178:179], v[172:173], v[174:175] neg_lo:[0,1] neg_hi:[0,1]
	v_mov_b32_e32 v177, v172
	v_pk_add_f32 v[172:173], v[178:179], v[176:177] neg_lo:[0,1] neg_hi:[0,1]
	v_cmp_neq_f32_e32 vcc, s70, v153
	v_add_f32_e32 v173, v182, v173
	v_add_f32_e32 v172, v172, v173
	v_add_f32_e32 v173, v175, v172
	v_mul_f32_e32 v182, v181, v173
	v_mul_f32_e32 v174, v156, v182
	v_fma_f32 v176, v182, v156, -v174
	v_fmac_f32_e32 v176, v182, v151
	v_sub_f32_e32 v151, v175, v173
	v_add_f32_e32 v151, v172, v151
	v_add_f32_e32 v172, v174, v176
	v_sub_f32_e32 v175, v173, v172
	v_pk_add_f32 v[178:179], v[172:173], v[174:175] neg_lo:[0,1] neg_hi:[0,1]
	v_mov_b32_e32 v177, v172
	v_pk_add_f32 v[172:173], v[178:179], v[176:177] neg_lo:[0,1] neg_hi:[0,1]
	v_add_f32_e32 v156, v183, v182
	v_add_f32_e32 v151, v151, v173
	v_add_f32_e32 v151, v172, v151
	v_add_f32_e32 v151, v175, v151
	v_sub_f32_e32 v172, v156, v183
	v_mul_f32_e32 v151, v181, v151
	v_sub_f32_e32 v172, v182, v172
	v_add_f32_e32 v173, v172, v151
	v_add_f32_e32 v174, v156, v173
	v_cvt_f32_i32_e32 v172, v180
	v_mul_f32_e32 v176, v174, v174
	v_fmamk_f32 v151, v176, 0x3e9b6dac, v166
	v_sub_f32_e32 v156, v174, v156
	v_fmaak_f32 v151, v176, v151, 0x3f2aaada
	v_sub_f32_e32 v156, v173, v156
	v_mul_f32_e32 v173, v174, v176
	v_pk_mul_f32 v[176:177], v[172:173], v[150:151]
	v_ldexp_f32 v175, v174, 1
	v_fma_f32 v174, v172, s69, -v176
	v_fmac_f32_e32 v174, 0xb102e308, v172
	v_pk_add_f32 v[172:173], v[176:177], v[174:175]
	v_ldexp_f32 v156, v156, 1
	v_sub_f32_e32 v151, v173, v175
	v_sub_f32_e32 v151, v177, v151
	v_add_f32_e32 v179, v156, v151
	v_mov_b32_e32 v178, v176
	v_pk_add_f32 v[176:177], v[172:173], v[176:177] neg_lo:[0,1] neg_hi:[0,1]
	v_pk_add_f32 v[180:181], v[172:173], v[178:179]
	v_mov_b32_e32 v175, v172
	v_mov_b32_e32 v177, v181
	v_pk_add_f32 v[182:183], v[174:175], v[176:177] neg_lo:[0,1] neg_hi:[0,1]
	v_pk_add_f32 v[174:175], v[174:175], v[176:177]
	v_mov_b32_e32 v178, v179
	v_pk_add_f32 v[176:177], v[174:175], v[172:173] op_sel:[1,0] op_sel_hi:[0,1] neg_lo:[0,1] neg_hi:[0,1]
	v_pk_add_f32 v[184:185], v[180:181], v[176:177] op_sel_hi:[1,0] neg_lo:[0,1] neg_hi:[0,1]
	v_mov_b32_e32 v180, v181
	v_mov_b32_e32 v181, v175
	v_pk_mov_b32 v[176:177], v[172:173], v[176:177] op_sel:[1,0]
	v_mov_b32_e32 v179, v172
	v_pk_add_f32 v[176:177], v[180:181], v[176:177] neg_lo:[0,1] neg_hi:[0,1]
	v_mov_b32_e32 v184, v182
	v_pk_add_f32 v[172:173], v[178:179], v[176:177] neg_lo:[0,1] neg_hi:[0,1]
	v_mov_b32_e32 v183, v175
	v_pk_add_f32 v[176:177], v[184:185], v[172:173]
	s_nop 0
	v_pk_add_f32 v[178:179], v[176:177], v[176:177] op_sel:[0,1] op_sel_hi:[1,0]
	s_nop 0
	v_pk_add_f32 v[174:175], v[174:175], v[178:179] op_sel:[1,0] op_sel_hi:[0,1]
	v_mov_b32_e32 v177, v174
	v_pk_add_f32 v[180:181], v[176:177], v[182:183] neg_lo:[0,1] neg_hi:[0,1]
	v_mov_b32_e32 v173, v178
	v_sub_f32_e32 v151, v176, v180
	v_pk_add_f32 v[172:173], v[172:173], v[180:181] neg_lo:[0,1] neg_hi:[0,1]
	v_sub_f32_e32 v151, v182, v151
	v_add_f32_e32 v151, v172, v151
	v_add_f32_e32 v151, v151, v173
	v_add_f32_e32 v151, v174, v151
	v_cndmask_b32_e32 v151, v167, v151, vcc
	v_cmp_ngt_f32_e32 vcc, -1.0, v153
	s_nop 1
	v_cndmask_b32_e32 v151, v168, v151, vcc
	v_cmp_neq_f32_e32 vcc, -1.0, v153
	s_nop 1
	v_cndmask_b32_e32 v151, v169, v151, vcc
	v_cmp_lt_f32_e64 vcc, |v153|, s71
	s_nop 1
	v_cndmask_b32_e32 v151, v151, v153, vcc
;     __device__ __forceinline__ void operator()(const f32x4 (&acc)[2][2][4][2], const Unit& u, int wr, int wc, int fr, int fq) const {
;     ...
;                         for (int i = 0; i < 4; ++i) { float x0 = v0[i] + dt_bias[c0 + i], x1 = v1[i] + dt_bias[c0 + 4 + i];
;                             dp[i] = x0 > 20.f ? x0 : log1pf(__expf(x0)); dp[4 + i] = x1 > 20.f ? x1 : log1pf(__expf(x1)); }
.LBB0_901:
	s_or_b64 exec, exec, s[24:25]
	v_add_f32_e32 v136, v9, v136
	v_cmp_nlt_f32_e32 vcc, s67, v136
	global_store_dword v[154:155], v151, off offset:4
	s_and_saveexec_b64 s[24:25], vcc
	s_cbranch_execz .LBB0_903
	v_mul_f32_e32 v136, 0x3fb8aa3b, v136
	v_exp_f32_e32 v136, v136
	s_nop 0
	v_add_f32_e32 v151, 1.0, v136
	v_frexp_mant_f32_e32 v156, v151
	v_cvt_f64_f32_e32 v[172:173], v151
	v_add_f32_e32 v153, -1.0, v151
	v_frexp_exp_i32_f64_e32 v172, v[172:173]
	v_cmp_gt_f32_e32 vcc, s68, v156
	v_sub_f32_e32 v174, v153, v151
	v_sub_f32_e32 v153, v136, v153
	v_subbrev_co_u32_e32 v156, vcc, 0, v172, vcc
	v_add_f32_e32 v174, 1.0, v174
	v_sub_u32_e32 v172, 0, v156
	v_add_f32_e32 v153, v153, v174
	v_ldexp_f32 v151, v151, v172
	v_ldexp_f32 v153, v153, v172
	v_add_f32_e32 v172, -1.0, v151
	v_add_f32_e32 v173, 1.0, v172
	v_sub_f32_e32 v173, v151, v173
	v_add_f32_e32 v174, v153, v173
	v_add_f32_e32 v173, 1.0, v151
	v_add_f32_e32 v175, -1.0, v173
	v_sub_f32_e32 v151, v151, v175
	v_add_f32_e32 v151, v153, v151
	v_add_f32_e32 v153, v173, v151
	v_rcp_f32_e32 v180, v153
	v_sub_f32_e32 v173, v153, v173
	v_sub_f32_e32 v151, v151, v173
	v_add_f32_e32 v173, v172, v174
	v_sub_f32_e32 v172, v173, v172
	v_mul_f32_e32 v182, v173, v180
	v_sub_f32_e32 v181, v174, v172
	v_mul_f32_e32 v174, v153, v182
	v_fma_f32 v176, v182, v153, -v174
	v_fmac_f32_e32 v176, v182, v151
	v_add_f32_e32 v172, v174, v176
	v_sub_f32_e32 v175, v173, v172
	v_pk_add_f32 v[178:179], v[172:173], v[174:175] neg_lo:[0,1] neg_hi:[0,1]
	v_mov_b32_e32 v177, v172
	v_pk_add_f32 v[172:173], v[178:179], v[176:177] neg_lo:[0,1] neg_hi:[0,1]
	v_cmp_neq_f32_e32 vcc, s70, v136
	v_add_f32_e32 v173, v181, v173
	v_add_f32_e32 v172, v172, v173
	v_add_f32_e32 v173, v175, v172
	v_mul_f32_e32 v181, v180, v173
	v_mul_f32_e32 v174, v153, v181
	v_fma_f32 v176, v181, v153, -v174
	v_fmac_f32_e32 v176, v181, v151
	v_sub_f32_e32 v151, v175, v173
	v_add_f32_e32 v151, v172, v151
	v_add_f32_e32 v172, v174, v176
	v_sub_f32_e32 v175, v173, v172
	v_pk_add_f32 v[178:179], v[172:173], v[174:175] neg_lo:[0,1] neg_hi:[0,1]
	v_mov_b32_e32 v177, v172
	v_pk_add_f32 v[172:173], v[178:179], v[176:177] neg_lo:[0,1] neg_hi:[0,1]
	v_add_f32_e32 v153, v182, v181
	v_add_f32_e32 v151, v151, v173
	v_add_f32_e32 v151, v172, v151
	v_add_f32_e32 v151, v175, v151
	v_sub_f32_e32 v172, v153, v182
	v_mul_f32_e32 v151, v180, v151
	v_sub_f32_e32 v172, v181, v172
	v_add_f32_e32 v173, v172, v151
	v_add_f32_e32 v174, v153, v173
	v_cvt_f32_i32_e32 v172, v156
	v_mul_f32_e32 v176, v174, v174
	v_fmamk_f32 v151, v176, 0x3e9b6dac, v166
	v_sub_f32_e32 v153, v174, v153
	v_fmaak_f32 v151, v176, v151, 0x3f2aaada
	v_sub_f32_e32 v153, v173, v153
	v_mul_f32_e32 v173, v174, v176
	v_pk_mul_f32 v[176:177], v[172:173], v[150:151]
	v_ldexp_f32 v175, v174, 1
	v_fma_f32 v174, v172, s69, -v176
	v_fmac_f32_e32 v174, 0xb102e308, v172
	v_pk_add_f32 v[172:173], v[176:177], v[174:175]
	v_ldexp_f32 v153, v153, 1
	v_sub_f32_e32 v151, v173, v175
	v_sub_f32_e32 v151, v177, v151
	v_add_f32_e32 v179, v153, v151
	v_mov_b32_e32 v178, v176
	v_pk_add_f32 v[176:177], v[172:173], v[176:177] neg_lo:[0,1] neg_hi:[0,1]
	v_pk_add_f32 v[180:181], v[172:173], v[178:179]
	v_mov_b32_e32 v175, v172
	v_mov_b32_e32 v177, v181
	v_pk_add_f32 v[182:183], v[174:175], v[176:177] neg_lo:[0,1] neg_hi:[0,1]
	v_pk_add_f32 v[174:175], v[174:175], v[176:177]
	v_mov_b32_e32 v178, v179
	v_pk_add_f32 v[176:177], v[174:175], v[172:173] op_sel:[1,0] op_sel_hi:[0,1] neg_lo:[0,1] neg_hi:[0,1]
	v_pk_add_f32 v[184:185], v[180:181], v[176:177] op_sel_hi:[1,0] neg_lo:[0,1] neg_hi:[0,1]
	v_mov_b32_e32 v180, v181
	v_mov_b32_e32 v181, v175
	v_pk_mov_b32 v[176:177], v[172:173], v[176:177] op_sel:[1,0]
	v_mov_b32_e32 v179, v172
	v_pk_add_f32 v[176:177], v[180:181], v[176:177] neg_lo:[0,1] neg_hi:[0,1]
	v_mov_b32_e32 v184, v182
	v_pk_add_f32 v[172:173], v[178:179], v[176:177] neg_lo:[0,1] neg_hi:[0,1]
	v_mov_b32_e32 v183, v175
	v_pk_add_f32 v[176:177], v[184:185], v[172:173]
	s_nop 0
	v_pk_add_f32 v[178:179], v[176:177], v[176:177] op_sel:[0,1] op_sel_hi:[1,0]
	s_nop 0
	v_pk_add_f32 v[174:175], v[174:175], v[178:179] op_sel:[1,0] op_sel_hi:[0,1]
	v_mov_b32_e32 v177, v174
	v_pk_add_f32 v[180:181], v[176:177], v[182:183] neg_lo:[0,1] neg_hi:[0,1]
	v_mov_b32_e32 v173, v178
	v_sub_f32_e32 v151, v176, v180
	v_pk_add_f32 v[172:173], v[172:173], v[180:181] neg_lo:[0,1] neg_hi:[0,1]
	v_sub_f32_e32 v151, v182, v151
	v_add_f32_e32 v151, v172, v151
	v_add_f32_e32 v151, v151, v173
	v_add_f32_e32 v151, v174, v151
	v_cndmask_b32_e32 v151, v167, v151, vcc
	v_cmp_ngt_f32_e32 vcc, -1.0, v136
	s_nop 1
	v_cndmask_b32_e32 v151, v168, v151, vcc
	v_cmp_neq_f32_e32 vcc, -1.0, v136
	s_nop 1
	v_cndmask_b32_e32 v151, v169, v151, vcc
	v_cmp_lt_f32_e64 vcc, |v136|, s71
	s_nop 1
	v_cndmask_b32_e32 v136, v151, v136, vcc
;     __device__ __forceinline__ void operator()(const f32x4 (&acc)[2][2][4][2], const Unit& u, int wr, int wc, int fr, int fq) const {
;     ...
;                         for (int i = 0; i < 4; ++i) { float x0 = v0[i] + dt_bias[c0 + i], x1 = v1[i] + dt_bias[c0 + 4 + i];
;                             dp[i] = x0 > 20.f ? x0 : log1pf(__expf(x0)); dp[4 + i] = x1 > 20.f ? x1 : log1pf(__expf(x1)); }
.LBB0_903:
	s_or_b64 exec, exec, s[24:25]
	global_store_dword v[154:155], v136, off offset:20
	global_load_dword v136, v[140:141], off offset:8
	s_waitcnt vmcnt(0)
	v_add_f32_e32 v151, v14, v136
	global_load_dword v136, v[140:141], off offset:24
	v_cmp_nlt_f32_e32 vcc, s67, v151
	s_and_saveexec_b64 s[24:25], vcc
	s_cbranch_execz .LBB0_905
	v_mul_f32_e32 v151, 0x3fb8aa3b, v151
	v_exp_f32_e32 v153, v151
	s_nop 0
	v_add_f32_e32 v151, 1.0, v153
	v_frexp_mant_f32_e32 v174, v151
	v_cvt_f64_f32_e32 v[172:173], v151
	v_add_f32_e32 v156, -1.0, v151
	v_frexp_exp_i32_f64_e32 v172, v[172:173]
	v_cmp_gt_f32_e32 vcc, s68, v174
	v_sub_f32_e32 v175, v156, v151
	v_sub_f32_e32 v156, v153, v156
	v_subbrev_co_u32_e32 v180, vcc, 0, v172, vcc
	v_add_f32_e32 v175, 1.0, v175
	v_sub_u32_e32 v172, 0, v180
	v_add_f32_e32 v156, v156, v175
	v_ldexp_f32 v151, v151, v172
	v_ldexp_f32 v156, v156, v172
	v_add_f32_e32 v172, -1.0, v151
	v_add_f32_e32 v173, 1.0, v172
	v_sub_f32_e32 v173, v151, v173
	v_add_f32_e32 v174, v156, v173
	v_add_f32_e32 v173, 1.0, v151
	v_add_f32_e32 v175, -1.0, v173
	v_sub_f32_e32 v151, v151, v175
	v_add_f32_e32 v151, v156, v151
	v_add_f32_e32 v156, v173, v151
	v_rcp_f32_e32 v181, v156
	v_sub_f32_e32 v173, v156, v173
	v_sub_f32_e32 v151, v151, v173
	v_add_f32_e32 v173, v172, v174
	v_sub_f32_e32 v172, v173, v172
	v_mul_f32_e32 v183, v173, v181
	v_sub_f32_e32 v182, v174, v172
	v_mul_f32_e32 v174, v156, v183
	v_fma_f32 v176, v183, v156, -v174
	v_fmac_f32_e32 v176, v183, v151
	v_add_f32_e32 v172, v174, v176
	v_sub_f32_e32 v175, v173, v172
	v_pk_add_f32 v[178:179], v[172:173], v[174:175] neg_lo:[0,1] neg_hi:[0,1]
	v_mov_b32_e32 v177, v172
	v_pk_add_f32 v[172:173], v[178:179], v[176:177] neg_lo:[0,1] neg_hi:[0,1]
	v_cmp_neq_f32_e32 vcc, s70, v153
	v_add_f32_e32 v173, v182, v173
	v_add_f32_e32 v172, v172, v173
	v_add_f32_e32 v173, v175, v172
	v_mul_f32_e32 v182, v181, v173
	v_mul_f32_e32 v174, v156, v182
	v_fma_f32 v176, v182, v156, -v174
	v_fmac_f32_e32 v176, v182, v151
	v_sub_f32_e32 v151, v175, v173
	v_add_f32_e32 v151, v172, v151
	v_add_f32_e32 v172, v174, v176
	v_sub_f32_e32 v175, v173, v172
	v_pk_add_f32 v[178:179], v[172:173], v[174:175] neg_lo:[0,1] neg_hi:[0,1]
	v_mov_b32_e32 v177, v172
	v_pk_add_f32 v[172:173], v[178:179], v[176:177] neg_lo:[0,1] neg_hi:[0,1]
	v_add_f32_e32 v156, v183, v182
	v_add_f32_e32 v151, v151, v173
	v_add_f32_e32 v151, v172, v151
	v_add_f32_e32 v151, v175, v151
	v_sub_f32_e32 v172, v156, v183
	v_mul_f32_e32 v151, v181, v151
	v_sub_f32_e32 v172, v182, v172
	v_add_f32_e32 v173, v172, v151
	v_add_f32_e32 v174, v156, v173
	v_cvt_f32_i32_e32 v172, v180
	v_mul_f32_e32 v176, v174, v174
	v_fmamk_f32 v151, v176, 0x3e9b6dac, v166
	v_sub_f32_e32 v156, v174, v156
	v_fmaak_f32 v151, v176, v151, 0x3f2aaada
	v_sub_f32_e32 v156, v173, v156
	v_mul_f32_e32 v173, v174, v176
	v_pk_mul_f32 v[176:177], v[172:173], v[150:151]
	v_ldexp_f32 v175, v174, 1
	v_fma_f32 v174, v172, s69, -v176
	v_fmac_f32_e32 v174, 0xb102e308, v172
	v_pk_add_f32 v[172:173], v[176:177], v[174:175]
	v_ldexp_f32 v156, v156, 1
	v_sub_f32_e32 v151, v173, v175
	v_sub_f32_e32 v151, v177, v151
	v_add_f32_e32 v179, v156, v151
	v_mov_b32_e32 v178, v176
	v_pk_add_f32 v[176:177], v[172:173], v[176:177] neg_lo:[0,1] neg_hi:[0,1]
	v_pk_add_f32 v[180:181], v[172:173], v[178:179]
	v_mov_b32_e32 v175, v172
	v_mov_b32_e32 v177, v181
	v_pk_add_f32 v[182:183], v[174:175], v[176:177] neg_lo:[0,1] neg_hi:[0,1]
	v_pk_add_f32 v[174:175], v[174:175], v[176:177]
	v_mov_b32_e32 v178, v179
	v_pk_add_f32 v[176:177], v[174:175], v[172:173] op_sel:[1,0] op_sel_hi:[0,1] neg_lo:[0,1] neg_hi:[0,1]
	v_pk_add_f32 v[184:185], v[180:181], v[176:177] op_sel_hi:[1,0] neg_lo:[0,1] neg_hi:[0,1]
	v_mov_b32_e32 v180, v181
	v_mov_b32_e32 v181, v175
	v_pk_mov_b32 v[176:177], v[172:173], v[176:177] op_sel:[1,0]
	v_mov_b32_e32 v179, v172
	v_pk_add_f32 v[176:177], v[180:181], v[176:177] neg_lo:[0,1] neg_hi:[0,1]
	v_mov_b32_e32 v184, v182
	v_pk_add_f32 v[172:173], v[178:179], v[176:177] neg_lo:[0,1] neg_hi:[0,1]
	v_mov_b32_e32 v183, v175
	v_pk_add_f32 v[176:177], v[184:185], v[172:173]
	s_nop 0
	v_pk_add_f32 v[178:179], v[176:177], v[176:177] op_sel:[0,1] op_sel_hi:[1,0]
	s_nop 0
	v_pk_add_f32 v[174:175], v[174:175], v[178:179] op_sel:[1,0] op_sel_hi:[0,1]
	v_mov_b32_e32 v177, v174
	v_pk_add_f32 v[180:181], v[176:177], v[182:183] neg_lo:[0,1] neg_hi:[0,1]
	v_mov_b32_e32 v173, v178
	v_sub_f32_e32 v151, v176, v180
	v_pk_add_f32 v[172:173], v[172:173], v[180:181] neg_lo:[0,1] neg_hi:[0,1]
	v_sub_f32_e32 v151, v182, v151
	v_add_f32_e32 v151, v172, v151
	v_add_f32_e32 v151, v151, v173
	v_add_f32_e32 v151, v174, v151
	v_cndmask_b32_e32 v151, v167, v151, vcc
	v_cmp_ngt_f32_e32 vcc, -1.0, v153
	s_nop 1
	v_cndmask_b32_e32 v151, v168, v151, vcc
	v_cmp_neq_f32_e32 vcc, -1.0, v153
	s_nop 1
	v_cndmask_b32_e32 v151, v169, v151, vcc
	v_cmp_lt_f32_e64 vcc, |v153|, s71
	s_nop 1
	v_cndmask_b32_e32 v151, v151, v153, vcc
;     __device__ __forceinline__ void operator()(const f32x4 (&acc)[2][2][4][2], const Unit& u, int wr, int wc, int fr, int fq) const {
;     ...
;                         for (int i = 0; i < 4; ++i) { float x0 = v0[i] + dt_bias[c0 + i], x1 = v1[i] + dt_bias[c0 + 4 + i];
;                             dp[i] = x0 > 20.f ? x0 : log1pf(__expf(x0)); dp[4 + i] = x1 > 20.f ? x1 : log1pf(__expf(x1)); }
.LBB0_905:
	s_or_b64 exec, exec, s[24:25]
	s_waitcnt vmcnt(0)
	v_add_f32_e32 v136, v10, v136
	v_cmp_nlt_f32_e32 vcc, s67, v136
	global_store_dword v[154:155], v151, off offset:8
	s_and_saveexec_b64 s[24:25], vcc
	s_cbranch_execz .LBB0_907
	v_mul_f32_e32 v136, 0x3fb8aa3b, v136
	v_exp_f32_e32 v136, v136
	s_nop 0
	v_add_f32_e32 v151, 1.0, v136
	v_frexp_mant_f32_e32 v156, v151
	v_cvt_f64_f32_e32 v[172:173], v151
	v_add_f32_e32 v153, -1.0, v151
	v_frexp_exp_i32_f64_e32 v172, v[172:173]
	v_cmp_gt_f32_e32 vcc, s68, v156
	v_sub_f32_e32 v174, v153, v151
	v_sub_f32_e32 v153, v136, v153
	v_subbrev_co_u32_e32 v156, vcc, 0, v172, vcc
	v_add_f32_e32 v174, 1.0, v174
	v_sub_u32_e32 v172, 0, v156
	v_add_f32_e32 v153, v153, v174
	v_ldexp_f32 v151, v151, v172
	v_ldexp_f32 v153, v153, v172
	v_add_f32_e32 v172, -1.0, v151
	v_add_f32_e32 v173, 1.0, v172
	v_sub_f32_e32 v173, v151, v173
	v_add_f32_e32 v174, v153, v173
	v_add_f32_e32 v173, 1.0, v151
	v_add_f32_e32 v175, -1.0, v173
	v_sub_f32_e32 v151, v151, v175
	v_add_f32_e32 v151, v153, v151
	v_add_f32_e32 v153, v173, v151
	v_rcp_f32_e32 v180, v153
	v_sub_f32_e32 v173, v153, v173
	v_sub_f32_e32 v151, v151, v173
	v_add_f32_e32 v173, v172, v174
	v_sub_f32_e32 v172, v173, v172
	v_mul_f32_e32 v182, v173, v180
	v_sub_f32_e32 v181, v174, v172
	v_mul_f32_e32 v174, v153, v182
	v_fma_f32 v176, v182, v153, -v174
	v_fmac_f32_e32 v176, v182, v151
	v_add_f32_e32 v172, v174, v176
	v_sub_f32_e32 v175, v173, v172
	v_pk_add_f32 v[178:179], v[172:173], v[174:175] neg_lo:[0,1] neg_hi:[0,1]
	v_mov_b32_e32 v177, v172
	v_pk_add_f32 v[172:173], v[178:179], v[176:177] neg_lo:[0,1] neg_hi:[0,1]
	v_cmp_neq_f32_e32 vcc, s70, v136
	v_add_f32_e32 v173, v181, v173
	v_add_f32_e32 v172, v172, v173
	v_add_f32_e32 v173, v175, v172
	v_mul_f32_e32 v181, v180, v173
	v_mul_f32_e32 v174, v153, v181
	v_fma_f32 v176, v181, v153, -v174
	v_fmac_f32_e32 v176, v181, v151
	v_sub_f32_e32 v151, v175, v173
	v_add_f32_e32 v151, v172, v151
	v_add_f32_e32 v172, v174, v176
	v_sub_f32_e32 v175, v173, v172
	v_pk_add_f32 v[178:179], v[172:173], v[174:175] neg_lo:[0,1] neg_hi:[0,1]
	v_mov_b32_e32 v177, v172
	v_pk_add_f32 v[172:173], v[178:179], v[176:177] neg_lo:[0,1] neg_hi:[0,1]
	v_add_f32_e32 v153, v182, v181
	v_add_f32_e32 v151, v151, v173
	v_add_f32_e32 v151, v172, v151
	v_add_f32_e32 v151, v175, v151
	v_sub_f32_e32 v172, v153, v182
	v_mul_f32_e32 v151, v180, v151
	v_sub_f32_e32 v172, v181, v172
	v_add_f32_e32 v173, v172, v151
	v_add_f32_e32 v174, v153, v173
	v_cvt_f32_i32_e32 v172, v156
	v_mul_f32_e32 v176, v174, v174
	v_fmamk_f32 v151, v176, 0x3e9b6dac, v166
	v_sub_f32_e32 v153, v174, v153
	v_fmaak_f32 v151, v176, v151, 0x3f2aaada
	v_sub_f32_e32 v153, v173, v153
	v_mul_f32_e32 v173, v174, v176
	v_pk_mul_f32 v[176:177], v[172:173], v[150:151]
	v_ldexp_f32 v175, v174, 1
	v_fma_f32 v174, v172, s69, -v176
	v_fmac_f32_e32 v174, 0xb102e308, v172
	v_pk_add_f32 v[172:173], v[176:177], v[174:175]
	v_ldexp_f32 v153, v153, 1
	v_sub_f32_e32 v151, v173, v175
	v_sub_f32_e32 v151, v177, v151
	v_add_f32_e32 v179, v153, v151
	v_mov_b32_e32 v178, v176
	v_pk_add_f32 v[176:177], v[172:173], v[176:177] neg_lo:[0,1] neg_hi:[0,1]
	v_pk_add_f32 v[180:181], v[172:173], v[178:179]
	v_mov_b32_e32 v175, v172
	v_mov_b32_e32 v177, v181
	v_pk_add_f32 v[182:183], v[174:175], v[176:177] neg_lo:[0,1] neg_hi:[0,1]
	v_pk_add_f32 v[174:175], v[174:175], v[176:177]
	v_mov_b32_e32 v178, v179
	v_pk_add_f32 v[176:177], v[174:175], v[172:173] op_sel:[1,0] op_sel_hi:[0,1] neg_lo:[0,1] neg_hi:[0,1]
	v_pk_add_f32 v[184:185], v[180:181], v[176:177] op_sel_hi:[1,0] neg_lo:[0,1] neg_hi:[0,1]
	v_mov_b32_e32 v180, v181
	v_mov_b32_e32 v181, v175
	v_pk_mov_b32 v[176:177], v[172:173], v[176:177] op_sel:[1,0]
	v_mov_b32_e32 v179, v172
	v_pk_add_f32 v[176:177], v[180:181], v[176:177] neg_lo:[0,1] neg_hi:[0,1]
	v_mov_b32_e32 v184, v182
	v_pk_add_f32 v[172:173], v[178:179], v[176:177] neg_lo:[0,1] neg_hi:[0,1]
	v_mov_b32_e32 v183, v175
	v_pk_add_f32 v[176:177], v[184:185], v[172:173]
	s_nop 0
	v_pk_add_f32 v[178:179], v[176:177], v[176:177] op_sel:[0,1] op_sel_hi:[1,0]
	s_nop 0
	v_pk_add_f32 v[174:175], v[174:175], v[178:179] op_sel:[1,0] op_sel_hi:[0,1]
	v_mov_b32_e32 v177, v174
	v_pk_add_f32 v[180:181], v[176:177], v[182:183] neg_lo:[0,1] neg_hi:[0,1]
	v_mov_b32_e32 v173, v178
	v_sub_f32_e32 v151, v176, v180
	v_pk_add_f32 v[172:173], v[172:173], v[180:181] neg_lo:[0,1] neg_hi:[0,1]
	v_sub_f32_e32 v151, v182, v151
	v_add_f32_e32 v151, v172, v151
	v_add_f32_e32 v151, v151, v173
	v_add_f32_e32 v151, v174, v151
	v_cndmask_b32_e32 v151, v167, v151, vcc
	v_cmp_ngt_f32_e32 vcc, -1.0, v136
	s_nop 1
	v_cndmask_b32_e32 v151, v168, v151, vcc
	v_cmp_neq_f32_e32 vcc, -1.0, v136
	s_nop 1
	v_cndmask_b32_e32 v151, v169, v151, vcc
	v_cmp_lt_f32_e64 vcc, |v136|, s71
	s_nop 1
	v_cndmask_b32_e32 v136, v151, v136, vcc
;     __device__ __forceinline__ void operator()(const f32x4 (&acc)[2][2][4][2], const Unit& u, int wr, int wc, int fr, int fq) const {
;     ...
;                         for (int i = 0; i < 4; ++i) { float x0 = v0[i] + dt_bias[c0 + i], x1 = v1[i] + dt_bias[c0 + 4 + i];
;                             dp[i] = x0 > 20.f ? x0 : log1pf(__expf(x0)); dp[4 + i] = x1 > 20.f ? x1 : log1pf(__expf(x1)); }
.LBB0_907:
	s_or_b64 exec, exec, s[24:25]
	global_store_dword v[154:155], v136, off offset:24
	global_load_dword v136, v[140:141], off offset:12
	s_waitcnt vmcnt(0)
	v_add_f32_e32 v151, v15, v136
	global_load_dword v136, v[140:141], off offset:28
	v_cmp_nlt_f32_e32 vcc, s67, v151
	s_and_saveexec_b64 s[24:25], vcc
	s_cbranch_execz .LBB0_909
	v_mul_f32_e32 v151, 0x3fb8aa3b, v151
	v_exp_f32_e32 v153, v151
	s_nop 0
	v_add_f32_e32 v151, 1.0, v153
	v_frexp_mant_f32_e32 v174, v151
	v_cvt_f64_f32_e32 v[172:173], v151
	v_add_f32_e32 v156, -1.0, v151
	v_frexp_exp_i32_f64_e32 v172, v[172:173]
	v_cmp_gt_f32_e32 vcc, s68, v174
	v_sub_f32_e32 v175, v156, v151
	v_sub_f32_e32 v156, v153, v156
	v_subbrev_co_u32_e32 v180, vcc, 0, v172, vcc
	v_add_f32_e32 v175, 1.0, v175
	v_sub_u32_e32 v172, 0, v180
	v_add_f32_e32 v156, v156, v175
	v_ldexp_f32 v151, v151, v172
	v_ldexp_f32 v156, v156, v172
	v_add_f32_e32 v172, -1.0, v151
	v_add_f32_e32 v173, 1.0, v172
	v_sub_f32_e32 v173, v151, v173
	v_add_f32_e32 v174, v156, v173
	v_add_f32_e32 v173, 1.0, v151
	v_add_f32_e32 v175, -1.0, v173
	v_sub_f32_e32 v151, v151, v175
	v_add_f32_e32 v151, v156, v151
	v_add_f32_e32 v156, v173, v151
	v_rcp_f32_e32 v181, v156
	v_sub_f32_e32 v173, v156, v173
	v_sub_f32_e32 v151, v151, v173
	v_add_f32_e32 v173, v172, v174
	v_sub_f32_e32 v172, v173, v172
	v_mul_f32_e32 v183, v173, v181
	v_sub_f32_e32 v182, v174, v172
	v_mul_f32_e32 v174, v156, v183
	v_fma_f32 v176, v183, v156, -v174
	v_fmac_f32_e32 v176, v183, v151
	v_add_f32_e32 v172, v174, v176
	v_sub_f32_e32 v175, v173, v172
	v_pk_add_f32 v[178:179], v[172:173], v[174:175] neg_lo:[0,1] neg_hi:[0,1]
	v_mov_b32_e32 v177, v172
	v_pk_add_f32 v[172:173], v[178:179], v[176:177] neg_lo:[0,1] neg_hi:[0,1]
	v_cmp_neq_f32_e32 vcc, s70, v153
	v_add_f32_e32 v173, v182, v173
	v_add_f32_e32 v172, v172, v173
	v_add_f32_e32 v173, v175, v172
	v_mul_f32_e32 v182, v181, v173
	v_mul_f32_e32 v174, v156, v182
	v_fma_f32 v176, v182, v156, -v174
	v_fmac_f32_e32 v176, v182, v151
	v_sub_f32_e32 v151, v175, v173
	v_add_f32_e32 v151, v172, v151
	v_add_f32_e32 v172, v174, v176
	v_sub_f32_e32 v175, v173, v172
	v_pk_add_f32 v[178:179], v[172:173], v[174:175] neg_lo:[0,1] neg_hi:[0,1]
	v_mov_b32_e32 v177, v172
	v_pk_add_f32 v[172:173], v[178:179], v[176:177] neg_lo:[0,1] neg_hi:[0,1]
	v_add_f32_e32 v156, v183, v182
	v_add_f32_e32 v151, v151, v173
	v_add_f32_e32 v151, v172, v151
	v_add_f32_e32 v151, v175, v151
	v_sub_f32_e32 v172, v156, v183
	v_mul_f32_e32 v151, v181, v151
	v_sub_f32_e32 v172, v182, v172
	v_add_f32_e32 v173, v172, v151
	v_add_f32_e32 v174, v156, v173
	v_cvt_f32_i32_e32 v172, v180
	v_mul_f32_e32 v176, v174, v174
	v_fmamk_f32 v151, v176, 0x3e9b6dac, v166
	v_sub_f32_e32 v156, v174, v156
	v_fmaak_f32 v151, v176, v151, 0x3f2aaada
	v_sub_f32_e32 v156, v173, v156
	v_mul_f32_e32 v173, v174, v176
	v_pk_mul_f32 v[176:177], v[172:173], v[150:151]
	v_ldexp_f32 v175, v174, 1
	v_fma_f32 v174, v172, s69, -v176
	v_fmac_f32_e32 v174, 0xb102e308, v172
	v_pk_add_f32 v[172:173], v[176:177], v[174:175]
	v_ldexp_f32 v156, v156, 1
	v_sub_f32_e32 v151, v173, v175
	v_sub_f32_e32 v151, v177, v151
	v_add_f32_e32 v179, v156, v151
	v_mov_b32_e32 v178, v176
	v_pk_add_f32 v[176:177], v[172:173], v[176:177] neg_lo:[0,1] neg_hi:[0,1]
	v_pk_add_f32 v[180:181], v[172:173], v[178:179]
	v_mov_b32_e32 v175, v172
	v_mov_b32_e32 v177, v181
	v_pk_add_f32 v[182:183], v[174:175], v[176:177] neg_lo:[0,1] neg_hi:[0,1]
	v_pk_add_f32 v[174:175], v[174:175], v[176:177]
	v_mov_b32_e32 v178, v179
	v_pk_add_f32 v[176:177], v[174:175], v[172:173] op_sel:[1,0] op_sel_hi:[0,1] neg_lo:[0,1] neg_hi:[0,1]
	v_pk_add_f32 v[184:185], v[180:181], v[176:177] op_sel_hi:[1,0] neg_lo:[0,1] neg_hi:[0,1]
	v_mov_b32_e32 v180, v181
	v_mov_b32_e32 v181, v175
	v_pk_mov_b32 v[176:177], v[172:173], v[176:177] op_sel:[1,0]
	v_mov_b32_e32 v179, v172
	v_pk_add_f32 v[176:177], v[180:181], v[176:177] neg_lo:[0,1] neg_hi:[0,1]
	v_mov_b32_e32 v184, v182
	v_pk_add_f32 v[172:173], v[178:179], v[176:177] neg_lo:[0,1] neg_hi:[0,1]
	v_mov_b32_e32 v183, v175
	v_pk_add_f32 v[176:177], v[184:185], v[172:173]
	s_nop 0
	v_pk_add_f32 v[178:179], v[176:177], v[176:177] op_sel:[0,1] op_sel_hi:[1,0]
	s_nop 0
	v_pk_add_f32 v[174:175], v[174:175], v[178:179] op_sel:[1,0] op_sel_hi:[0,1]
	v_mov_b32_e32 v177, v174
	v_pk_add_f32 v[180:181], v[176:177], v[182:183] neg_lo:[0,1] neg_hi:[0,1]
	v_mov_b32_e32 v173, v178
	v_sub_f32_e32 v151, v176, v180
	v_pk_add_f32 v[172:173], v[172:173], v[180:181] neg_lo:[0,1] neg_hi:[0,1]
	v_sub_f32_e32 v151, v182, v151
	v_add_f32_e32 v151, v172, v151
	v_add_f32_e32 v151, v151, v173
	v_add_f32_e32 v151, v174, v151
	v_cndmask_b32_e32 v151, v167, v151, vcc
	v_cmp_ngt_f32_e32 vcc, -1.0, v153
	s_nop 1
	v_cndmask_b32_e32 v151, v168, v151, vcc
	v_cmp_neq_f32_e32 vcc, -1.0, v153
	s_nop 1
	v_cndmask_b32_e32 v151, v169, v151, vcc
	v_cmp_lt_f32_e64 vcc, |v153|, s71
	s_nop 1
	v_cndmask_b32_e32 v151, v151, v153, vcc
;     __device__ __forceinline__ void operator()(const f32x4 (&acc)[2][2][4][2], const Unit& u, int wr, int wc, int fr, int fq) const {
;     ...
;                         for (int i = 0; i < 4; ++i) { float x0 = v0[i] + dt_bias[c0 + i], x1 = v1[i] + dt_bias[c0 + 4 + i];
;                             dp[i] = x0 > 20.f ? x0 : log1pf(__expf(x0)); dp[4 + i] = x1 > 20.f ? x1 : log1pf(__expf(x1)); }
;                         __builtin_amdgcn_sched_barrier(0); }
.LBB0_909:
	s_or_b64 exec, exec, s[24:25]
	s_waitcnt vmcnt(0)
	v_add_f32_e32 v136, v11, v136
	v_cmp_nlt_f32_e32 vcc, s67, v136
	global_store_dword v[154:155], v151, off offset:12
	s_and_saveexec_b64 s[24:25], vcc
	s_cbranch_execz .LBB0_911
	v_mul_f32_e32 v136, 0x3fb8aa3b, v136
	v_exp_f32_e32 v136, v136
	s_nop 0
	v_add_f32_e32 v151, 1.0, v136
	v_frexp_mant_f32_e32 v156, v151
	v_cvt_f64_f32_e32 v[172:173], v151
	v_add_f32_e32 v153, -1.0, v151
	v_frexp_exp_i32_f64_e32 v172, v[172:173]
	v_cmp_gt_f32_e32 vcc, s68, v156
	v_sub_f32_e32 v174, v153, v151
	v_sub_f32_e32 v153, v136, v153
	v_subbrev_co_u32_e32 v156, vcc, 0, v172, vcc
	v_add_f32_e32 v174, 1.0, v174
	v_sub_u32_e32 v172, 0, v156
	v_add_f32_e32 v153, v153, v174
	v_ldexp_f32 v151, v151, v172
	v_ldexp_f32 v153, v153, v172
	v_add_f32_e32 v172, -1.0, v151
	v_add_f32_e32 v173, 1.0, v172
	v_sub_f32_e32 v173, v151, v173
	v_add_f32_e32 v174, v153, v173
	v_add_f32_e32 v173, 1.0, v151
	v_add_f32_e32 v175, -1.0, v173
	v_sub_f32_e32 v151, v151, v175
	v_add_f32_e32 v151, v153, v151
	v_add_f32_e32 v153, v173, v151
	v_rcp_f32_e32 v180, v153
	v_sub_f32_e32 v173, v153, v173
	v_sub_f32_e32 v151, v151, v173
	v_add_f32_e32 v173, v172, v174
	v_sub_f32_e32 v172, v173, v172
	v_mul_f32_e32 v182, v173, v180
	v_sub_f32_e32 v181, v174, v172
	v_mul_f32_e32 v174, v153, v182
	v_fma_f32 v176, v182, v153, -v174
	v_fmac_f32_e32 v176, v182, v151
	v_add_f32_e32 v172, v174, v176
	v_sub_f32_e32 v175, v173, v172
	v_pk_add_f32 v[178:179], v[172:173], v[174:175] neg_lo:[0,1] neg_hi:[0,1]
	v_mov_b32_e32 v177, v172
	v_pk_add_f32 v[172:173], v[178:179], v[176:177] neg_lo:[0,1] neg_hi:[0,1]
	v_cmp_neq_f32_e32 vcc, s70, v136
	v_add_f32_e32 v173, v181, v173
	v_add_f32_e32 v172, v172, v173
	v_add_f32_e32 v173, v175, v172
	v_mul_f32_e32 v181, v180, v173
	v_mul_f32_e32 v174, v153, v181
	v_fma_f32 v176, v181, v153, -v174
	v_fmac_f32_e32 v176, v181, v151
	v_sub_f32_e32 v151, v175, v173
	v_add_f32_e32 v151, v172, v151
	v_add_f32_e32 v172, v174, v176
	v_sub_f32_e32 v175, v173, v172
	v_pk_add_f32 v[178:179], v[172:173], v[174:175] neg_lo:[0,1] neg_hi:[0,1]
	v_mov_b32_e32 v177, v172
	v_pk_add_f32 v[172:173], v[178:179], v[176:177] neg_lo:[0,1] neg_hi:[0,1]
	v_add_f32_e32 v153, v182, v181
	v_add_f32_e32 v151, v151, v173
	v_add_f32_e32 v151, v172, v151
	v_add_f32_e32 v151, v175, v151
	v_sub_f32_e32 v172, v153, v182
	v_mul_f32_e32 v151, v180, v151
	v_sub_f32_e32 v172, v181, v172
	v_add_f32_e32 v173, v172, v151
	v_add_f32_e32 v174, v153, v173
	v_cvt_f32_i32_e32 v172, v156
	v_mul_f32_e32 v176, v174, v174
	v_fmamk_f32 v151, v176, 0x3e9b6dac, v166
	v_sub_f32_e32 v153, v174, v153
	v_fmaak_f32 v151, v176, v151, 0x3f2aaada
	v_sub_f32_e32 v153, v173, v153
	v_mul_f32_e32 v173, v174, v176
	v_pk_mul_f32 v[176:177], v[172:173], v[150:151]
	v_ldexp_f32 v175, v174, 1
	v_fma_f32 v174, v172, s69, -v176
	v_fmac_f32_e32 v174, 0xb102e308, v172
	v_pk_add_f32 v[172:173], v[176:177], v[174:175]
	v_ldexp_f32 v153, v153, 1
	v_sub_f32_e32 v151, v173, v175
	v_sub_f32_e32 v151, v177, v151
	v_add_f32_e32 v179, v153, v151
	v_mov_b32_e32 v178, v176
	v_pk_add_f32 v[176:177], v[172:173], v[176:177] neg_lo:[0,1] neg_hi:[0,1]
	v_pk_add_f32 v[180:181], v[172:173], v[178:179]
	v_mov_b32_e32 v175, v172
	v_mov_b32_e32 v177, v181
	v_pk_add_f32 v[182:183], v[174:175], v[176:177] neg_lo:[0,1] neg_hi:[0,1]
	v_pk_add_f32 v[174:175], v[174:175], v[176:177]
	v_mov_b32_e32 v178, v179
	v_pk_add_f32 v[176:177], v[174:175], v[172:173] op_sel:[1,0] op_sel_hi:[0,1] neg_lo:[0,1] neg_hi:[0,1]
	v_pk_add_f32 v[184:185], v[180:181], v[176:177] op_sel_hi:[1,0] neg_lo:[0,1] neg_hi:[0,1]
	v_mov_b32_e32 v180, v181
	v_mov_b32_e32 v181, v175
	v_pk_mov_b32 v[176:177], v[172:173], v[176:177] op_sel:[1,0]
	v_mov_b32_e32 v179, v172
	v_pk_add_f32 v[176:177], v[180:181], v[176:177] neg_lo:[0,1] neg_hi:[0,1]
	v_mov_b32_e32 v184, v182
	v_pk_add_f32 v[172:173], v[178:179], v[176:177] neg_lo:[0,1] neg_hi:[0,1]
	v_mov_b32_e32 v183, v175
	v_pk_add_f32 v[176:177], v[184:185], v[172:173]
	s_nop 0
	v_pk_add_f32 v[178:179], v[176:177], v[176:177] op_sel:[0,1] op_sel_hi:[1,0]
	s_nop 0
	v_pk_add_f32 v[174:175], v[174:175], v[178:179] op_sel:[1,0] op_sel_hi:[0,1]
	v_mov_b32_e32 v177, v174
	v_pk_add_f32 v[180:181], v[176:177], v[182:183] neg_lo:[0,1] neg_hi:[0,1]
	v_mov_b32_e32 v173, v178
	v_sub_f32_e32 v151, v176, v180
	v_pk_add_f32 v[172:173], v[172:173], v[180:181] neg_lo:[0,1] neg_hi:[0,1]
	v_sub_f32_e32 v151, v182, v151
	v_add_f32_e32 v151, v172, v151
	v_add_f32_e32 v151, v151, v173
	v_add_f32_e32 v151, v174, v151
	v_cndmask_b32_e32 v151, v167, v151, vcc
	v_cmp_ngt_f32_e32 vcc, -1.0, v136
	s_nop 1
	v_cndmask_b32_e32 v151, v168, v151, vcc
	v_cmp_neq_f32_e32 vcc, -1.0, v136
	s_nop 1
	v_cndmask_b32_e32 v151, v169, v151, vcc
	v_cmp_lt_f32_e64 vcc, |v136|, s71
	s_nop 1
	v_cndmask_b32_e32 v136, v151, v136, vcc
.LBB0_911:
	s_or_b64 exec, exec, s[24:25]
	global_store_dword v[154:155], v136, off offset:28
	s_cbranch_execnz .LBB0_633
	s_branch .LBB0_644

; __device__ __forceinline__ unsigned cvt_pk_bf16(float lo, float hi) { unsigned r; asm volatile("v_cvt_pk_bf16_f32 %0, %1, %2" : "=v"(r) : "v"(lo), "v"(hi)); return r; }
;     __device__ __forceinline__ void operator()(const f32x4 (&acc)[2][2][4][2], const Unit& u, int wr, int wc, int fr, int fq) const {
;         const int row0 = u.pm * BM + wr * 64 + fr, col0 = u.pn * BM + wc * 32 + 8 * fq;
; #pragma unroll
;         for (int ai = 0; ai < 2; ++ai)
; #pragma unroll
;             for (int m = 0; m < 4; ++m) { bf16_t* rowp = O + (size_t)(row0 + ai * HALF + m * 16) * ldc + col0;
; #pragma unroll
;                 for (int bj = 0; bj < 2; ++bj) { const f32x4 v0 = acc[ai][bj][m][0], v1 = acc[ai][bj][m][1];
;                     u32x4 w; w.x = cvt_pk_bf16(v0[0], v0[1]); w.y = cvt_pk_bf16(v0[2], v0[3]); w.z = cvt_pk_bf16(v1[0], v1[1]); w.w = cvt_pk_bf16(v1[2], v1[3]);
;                     *(u32x4*)(rowp + bj * HALF) = w; } }
.LBB0_1536:
	v_lshl_add_u32 v154, s38, 8, v147
	v_lshl_or_b32 v144, s56, 8, v149
	v_ashrrev_i32_e32 v155, 31, v154
	v_ashrrev_i32_e32 v145, 31, v144
	v_lshlrev_b64 v[156:157], 12, v[154:155]
	v_lshl_add_u64 v[156:157], s[8:9], 0, v[156:157]
	v_lshlrev_b64 v[158:159], 1, v[144:145]
	v_lshl_add_u64 v[144:145], v[156:157], 0, v[158:159]
	v_cvt_pk_bf16_f32 v124, v124, v125
	v_cvt_pk_bf16_f32 v125, v126, v127
	v_cvt_pk_bf16_f32 v126, v120, v121
	v_cvt_pk_bf16_f32 v127, v122, v123
	global_store_dwordx4 v[144:145], v[124:127], off
	v_cvt_pk_bf16_f32 v112, v112, v113
	v_cvt_pk_bf16_f32 v113, v114, v115
	v_cvt_pk_bf16_f32 v114, v104, v105
	v_or_b32_e32 v104, 16, v154
	v_ashrrev_i32_e32 v105, 31, v104
	v_lshlrev_b64 v[104:105], 12, v[104:105]
	v_lshl_add_u64 v[104:105], s[8:9], 0, v[104:105]
	v_cvt_pk_bf16_f32 v115, v106, v107
	global_store_dwordx4 v[144:145], v[112:115], off offset:256
	s_mov_b32 s29, 0x80000
	s_mov_b64 s[44:45], 0x80000
	v_lshl_add_u64 v[112:113], v[104:105], 0, v[158:159]
	v_cvt_pk_bf16_f32 v104, v116, v117
	v_cvt_pk_bf16_f32 v105, v118, v119
	v_cvt_pk_bf16_f32 v106, v108, v109
	v_cvt_pk_bf16_f32 v107, v110, v111
	global_store_dwordx4 v[112:113], v[104:107], off
	v_cvt_pk_bf16_f32 v96, v96, v97
	v_cvt_pk_bf16_f32 v97, v98, v99
	v_cvt_pk_bf16_f32 v98, v88, v89
	v_or_b32_e32 v88, 32, v154
	v_ashrrev_i32_e32 v89, 31, v88
	v_lshlrev_b64 v[88:89], 12, v[88:89]
	v_lshl_add_u64 v[88:89], s[8:9], 0, v[88:89]
	v_cvt_pk_bf16_f32 v99, v90, v91
	global_store_dwordx4 v[112:113], v[96:99], off offset:256
	s_nop 1
	v_lshl_add_u64 v[96:97], v[88:89], 0, v[158:159]
	v_cvt_pk_bf16_f32 v88, v100, v101
	v_cvt_pk_bf16_f32 v89, v102, v103
	v_cvt_pk_bf16_f32 v90, v92, v93
	v_cvt_pk_bf16_f32 v91, v94, v95
	global_store_dwordx4 v[96:97], v[88:91], off
	v_cvt_pk_bf16_f32 v80, v80, v81
	v_cvt_pk_bf16_f32 v81, v82, v83
	v_cvt_pk_bf16_f32 v82, v72, v73
	v_or_b32_e32 v72, 48, v154
	v_ashrrev_i32_e32 v73, 31, v72
	v_lshlrev_b64 v[72:73], 12, v[72:73]
	v_lshl_add_u64 v[72:73], s[8:9], 0, v[72:73]
	v_cvt_pk_bf16_f32 v83, v74, v75
	global_store_dwordx4 v[96:97], v[80:83], off offset:256
	s_nop 1
	v_lshl_add_u64 v[80:81], v[72:73], 0, v[158:159]
	v_cvt_pk_bf16_f32 v72, v84, v85
	v_cvt_pk_bf16_f32 v73, v86, v87
	v_cvt_pk_bf16_f32 v74, v76, v77
	v_cvt_pk_bf16_f32 v75, v78, v79
	global_store_dwordx4 v[80:81], v[72:75], off
	v_cvt_pk_bf16_f32 v68, v68, v69
	v_cvt_pk_bf16_f32 v69, v70, v71
	v_cvt_pk_bf16_f32 v70, v64, v65
	v_cvt_pk_bf16_f32 v71, v66, v67
	global_store_dwordx4 v[80:81], v[68:71], off offset:256
	v_cvt_pk_bf16_f32 v60, v60, v61
	v_cvt_pk_bf16_f32 v61, v62, v63
	v_cvt_pk_bf16_f32 v62, v56, v57
	v_add_co_u32_e32 v56, vcc, s29, v144
	v_lshl_add_u64 v[64:65], v[144:145], 0, s[44:45]
	s_nop 0
	v_addc_co_u32_e32 v57, vcc, 0, v145, vcc
	s_mov_b32 s29, 0x90000
	v_cvt_pk_bf16_f32 v63, v58, v59
	global_store_dwordx4 v[56:57], v[60:63], off
	v_cvt_pk_bf16_f32 v48, v48, v49
	v_cvt_pk_bf16_f32 v49, v50, v51
	v_cvt_pk_bf16_f32 v50, v40, v41
	v_cvt_pk_bf16_f32 v51, v42, v43
	global_store_dwordx4 v[64:65], v[48:51], off offset:256
	s_mov_b64 s[44:45], 0x90000
	v_cvt_pk_bf16_f32 v40, v52, v53
	v_cvt_pk_bf16_f32 v41, v54, v55
	v_cvt_pk_bf16_f32 v42, v44, v45
	v_add_co_u32_e32 v44, vcc, s29, v144
	v_lshl_add_u64 v[48:49], v[144:145], 0, s[44:45]
	s_nop 0
	v_addc_co_u32_e32 v45, vcc, 0, v145, vcc
	s_mov_b32 s29, 0xa0000
	v_cvt_pk_bf16_f32 v43, v46, v47
	global_store_dwordx4 v[44:45], v[40:43], off
	v_cvt_pk_bf16_f32 v32, v32, v33
	v_cvt_pk_bf16_f32 v33, v34, v35
	v_cvt_pk_bf16_f32 v34, v24, v25
	v_cvt_pk_bf16_f32 v35, v26, v27
	global_store_dwordx4 v[48:49], v[32:35], off offset:256
	s_mov_b64 s[44:45], 0xa0000
	v_cvt_pk_bf16_f32 v24, v36, v37
	v_cvt_pk_bf16_f32 v25, v38, v39
	v_cvt_pk_bf16_f32 v26, v28, v29
	v_add_co_u32_e32 v28, vcc, s29, v144
	v_lshl_add_u64 v[32:33], v[144:145], 0, s[44:45]
	s_nop 0
	v_addc_co_u32_e32 v29, vcc, 0, v145, vcc
	s_mov_b32 s29, 0xb0000
	v_cvt_pk_bf16_f32 v27, v30, v31
	global_store_dwordx4 v[28:29], v[24:27], off
	v_cvt_pk_bf16_f32 v16, v16, v17
	v_cvt_pk_bf16_f32 v17, v18, v19
	v_cvt_pk_bf16_f32 v18, v8, v9
	v_cvt_pk_bf16_f32 v19, v10, v11
	global_store_dwordx4 v[32:33], v[16:19], off offset:256
	v_cvt_pk_bf16_f32 v8, v20, v21
	v_cvt_pk_bf16_f32 v9, v22, v23
	v_cvt_pk_bf16_f32 v10, v12, v13
	v_add_co_u32_e32 v12, vcc, s29, v144
	s_mov_b64 s[44:45], 0xb0000
	s_nop 0
	v_addc_co_u32_e32 v13, vcc, 0, v145, vcc
	v_lshl_add_u64 v[16:17], v[144:145], 0, s[44:45]
	s_andn2_b64 vcc, exec, s[36:37]
	s_mov_b64 s[36:37], -1
	v_cvt_pk_bf16_f32 v11, v14, v15
	global_store_dwordx4 v[12:13], v[8:11], off
	v_cvt_pk_bf16_f32 v4, v4, v5
	v_cvt_pk_bf16_f32 v5, v6, v7
	v_cvt_pk_bf16_f32 v6, v0, v1
	v_cvt_pk_bf16_f32 v7, v2, v3
	global_store_dwordx4 v[16:17], v[4:7], off offset:256
	s_cbranch_vccnz .LBB0_1525
	s_andn2_b64 vcc, exec, s[4:5]
	s_cbranch_vccnz .LBB0_1524
	s_barrier
	s_branch .LBB0_1524

; #define LAS __attribute__((address_space(3)))
; #define LDS_WAIT() asm volatile("s_waitcnt lgkmcnt(0)" ::: "memory")
; __device__ __forceinline__ void transpose_item(const float* W, int K, int N, bf16_t* WT, int drow0, int k0, int n0, LAS float* scr, int lane) {
; #pragma unroll
;     for (int i = 0; i < 32; ++i) { const int kk = 2 * i + (lane >> 5); scr[kk * 33 + (lane & 31)] = __builtin_nontemporal_load(&W[(size_t)(k0 + kk) * N + n0 + (lane & 31)]); }
;     LDS_WAIT();
; __device__ __forceinline__ void convert_ffn_dyn(const float* Wg, const float* Wu, const float* Wd, bf16_t* GU, bf16_t* DN, LAS unsigned char* lds, unsigned* ctr, int max_batches, int tid, int wave, int lane) {
;     ...
;         if (tid == 0) MISC[0] = (int)atomicAdd(ctr, 1u);
;         __syncthreads();
;         const int b = __builtin_amdgcn_readfirstlane(MISC[0]);
;         __syncthreads();
;         if (b >= NB) break;
;         const int it = b * 8 + wave;
;         if (it < 2 * I1) { const int up = it >= I1, r = it - up * I1, kb = r / (FF / 32), nb = r % (FF / 32), n0 = nb * 32;
;             transpose_item(up ? Wu : Wg, DM, FF, GU, 256 * (n0 >> 7) + up * 128 + (n0 & 127), kb * 64, n0, scr, lane); }
;         else { const int r = it - 2 * I1, kb = r / (DM / 32), nb = r % (DM / 32); transpose_item(Wd, FF, DM, DN, nb * 32, kb * 64, nb * 32, scr, lane); }
.LBB0_1545:
	s_or_b64 exec, exec, s[6:7]
	s_waitcnt vmcnt(0) lgkmcnt(0)
	s_barrier
	ds_read_b32 v8, v48
	s_mov_b64 s[6:7], -1
	s_waitcnt lgkmcnt(0)
	s_barrier
	v_readfirstlane_b32 s0, v8
	s_cmpk_gt_i32 s0, 0x83f
	s_cbranch_scc1 .LBB0_1542
	s_lshl_b32 s23, s0, 3
	s_add_i32 s23, s23, s10
	s_cmpk_gt_i32 s23, 0x2bff
	s_cbranch_scc0 .LBB0_1548
	s_and_b32 s0, s23, 0x7fffffc0
	s_add_i32 s6, s0, 0xffffd400
	s_lshl_b32 s0, s23, 5
	s_and_b32 s24, s0, 0x7e0
	s_lshl_b32 s0, s24, 2
	v_or_b32_e32 v58, s6, v10
	v_mov_b32_e32 v59, v1
	v_lshl_add_u64 v[8:9], v[2:3], 0, s[0:1]
	v_lshlrev_b64 v[58:59], 13, v[58:59]
	v_lshl_add_u64 v[58:59], v[8:9], 0, v[58:59]
	global_load_dword v60, v[58:59], off nt
	v_or_b32_e32 v58, s6, v11
	v_mov_b32_e32 v59, v1
	v_lshlrev_b64 v[58:59], 13, v[58:59]
	v_lshl_add_u64 v[58:59], v[8:9], 0, v[58:59]
	global_load_dword v58, v[58:59], off nt
	v_mov_b32_e32 v59, v1
	s_mov_b32 s7, s1
	s_waitcnt vmcnt(0)
	ds_write2_b32 v49, v60, v58 offset1:66
	v_or_b32_e32 v58, s6, v12
	v_lshlrev_b64 v[58:59], 13, v[58:59]
	v_lshl_add_u64 v[58:59], v[8:9], 0, v[58:59]
	global_load_dword v60, v[58:59], off nt
	v_or_b32_e32 v58, s6, v13
	v_mov_b32_e32 v59, v1
	v_lshlrev_b64 v[58:59], 13, v[58:59]
	v_lshl_add_u64 v[58:59], v[8:9], 0, v[58:59]
	global_load_dword v58, v[58:59], off nt
	v_mov_b32_e32 v59, v1
	s_waitcnt vmcnt(0)
	ds_write2_b32 v49, v60, v58 offset0:132 offset1:198
	v_or_b32_e32 v58, s6, v14
	v_lshlrev_b64 v[58:59], 13, v[58:59]
	v_lshl_add_u64 v[58:59], v[8:9], 0, v[58:59]
	global_load_dword v60, v[58:59], off nt
	v_or_b32_e32 v58, s6, v15
	v_mov_b32_e32 v59, v1
	v_lshlrev_b64 v[58:59], 13, v[58:59]
	v_lshl_add_u64 v[58:59], v[8:9], 0, v[58:59]
	global_load_dword v58, v[58:59], off nt
	v_mov_b32_e32 v59, v1
	s_waitcnt vmcnt(0)
	ds_write2_b32 v52, v60, v58 offset0:8 offset1:74
	v_or_b32_e32 v58, s6, v16
	v_lshlrev_b64 v[58:59], 13, v[58:59]
	v_lshl_add_u64 v[58:59], v[8:9], 0, v[58:59]
	global_load_dword v60, v[58:59], off nt
	v_or_b32_e32 v58, s6, v17
	v_mov_b32_e32 v59, v1
	v_lshlrev_b64 v[58:59], 13, v[58:59]
	v_lshl_add_u64 v[58:59], v[8:9], 0, v[58:59]
	global_load_dword v58, v[58:59], off nt
	v_mov_b32_e32 v59, v1
	s_waitcnt vmcnt(0)
	ds_write2_b32 v50, v60, v58 offset1:66
	v_or_b32_e32 v58, s6, v18
	v_lshlrev_b64 v[58:59], 13, v[58:59]
	v_lshl_add_u64 v[58:59], v[8:9], 0, v[58:59]
	global_load_dword v60, v[58:59], off nt
	v_or_b32_e32 v58, s6, v19
	v_mov_b32_e32 v59, v1
	v_lshlrev_b64 v[58:59], 13, v[58:59]
	v_lshl_add_u64 v[58:59], v[8:9], 0, v[58:59]
	global_load_dword v58, v[58:59], off nt
	v_mov_b32_e32 v59, v1
	s_waitcnt vmcnt(0)
	ds_write2_b32 v50, v60, v58 offset0:132 offset1:198
	v_or_b32_e32 v58, s6, v20
	v_lshlrev_b64 v[58:59], 13, v[58:59]
	v_lshl_add_u64 v[58:59], v[8:9], 0, v[58:59]
	global_load_dword v60, v[58:59], off nt
	v_or_b32_e32 v58, s6, v21
	v_mov_b32_e32 v59, v1
	v_lshlrev_b64 v[58:59], 13, v[58:59]
	v_lshl_add_u64 v[58:59], v[8:9], 0, v[58:59]
	global_load_dword v58, v[58:59], off nt
	v_mov_b32_e32 v59, v1
	s_waitcnt vmcnt(0)
	ds_write2_b32 v53, v60, v58 offset0:8 offset1:74
	v_or_b32_e32 v58, s6, v22
	v_lshlrev_b64 v[58:59], 13, v[58:59]
	v_lshl_add_u64 v[58:59], v[8:9], 0, v[58:59]
	global_load_dword v60, v[58:59], off nt
	v_or_b32_e32 v58, s6, v23
	v_mov_b32_e32 v59, v1
	v_lshlrev_b64 v[58:59], 13, v[58:59]
	v_lshl_add_u64 v[58:59], v[8:9], 0, v[58:59]
	global_load_dword v58, v[58:59], off nt
	v_mov_b32_e32 v59, v1
	s_waitcnt vmcnt(0)
	ds_write2_b32 v51, v60, v58 offset1:66
	v_or_b32_e32 v58, s6, v24
	v_lshlrev_b64 v[58:59], 13, v[58:59]
	v_lshl_add_u64 v[58:59], v[8:9], 0, v[58:59]
	global_load_dword v60, v[58:59], off nt
	v_or_b32_e32 v58, s6, v25
	v_mov_b32_e32 v59, v1
	v_lshlrev_b64 v[58:59], 13, v[58:59]
	v_lshl_add_u64 v[58:59], v[8:9], 0, v[58:59]
	global_load_dword v58, v[58:59], off nt
	v_mov_b32_e32 v59, v1
	s_waitcnt vmcnt(0)
	ds_write2_b32 v51, v60, v58 offset0:132 offset1:198
	v_or_b32_e32 v58, s6, v26
	v_lshlrev_b64 v[58:59], 13, v[58:59]
	v_lshl_add_u64 v[58:59], v[8:9], 0, v[58:59]
	global_load_dword v60, v[58:59], off nt
	v_or_b32_e32 v58, s6, v27
	v_mov_b32_e32 v59, v1
	v_lshlrev_b64 v[58:59], 13, v[58:59]
	v_lshl_add_u64 v[58:59], v[8:9], 0, v[58:59]
	global_load_dword v58, v[58:59], off nt
	v_mov_b32_e32 v59, v1
	s_waitcnt vmcnt(0)
	ds_write2_b32 v54, v60, v58 offset0:8 offset1:74
	v_or_b32_e32 v58, s6, v28
	v_lshlrev_b64 v[58:59], 13, v[58:59]
	v_lshl_add_u64 v[58:59], v[8:9], 0, v[58:59]
	global_load_dword v60, v[58:59], off nt
	v_or_b32_e32 v58, s6, v29
	v_mov_b32_e32 v59, v1
	v_lshlrev_b64 v[58:59], 13, v[58:59]
	v_lshl_add_u64 v[58:59], v[8:9], 0, v[58:59]
	global_load_dword v58, v[58:59], off nt
	v_mov_b32_e32 v59, v1
	s_waitcnt vmcnt(0)
	ds_write2_b32 v54, v60, v58 offset0:140 offset1:206
	v_or_b32_e32 v58, s6, v30
	v_lshlrev_b64 v[58:59], 13, v[58:59]
	v_lshl_add_u64 v[58:59], v[8:9], 0, v[58:59]
	global_load_dword v60, v[58:59], off nt
	v_or_b32_e32 v58, s6, v31
	v_mov_b32_e32 v59, v1
	v_lshlrev_b64 v[58:59], 13, v[58:59]
	v_lshl_add_u64 v[58:59], v[8:9], 0, v[58:59]
	global_load_dword v58, v[58:59], off nt
	v_mov_b32_e32 v59, v1
	s_waitcnt vmcnt(0)
	ds_write2_b32 v55, v60, v58 offset0:16 offset1:82
	v_or_b32_e32 v58, s6, v32
	v_lshlrev_b64 v[58:59], 13, v[58:59]
	v_lshl_add_u64 v[58:59], v[8:9], 0, v[58:59]
	global_load_dword v60, v[58:59], off nt
	v_or_b32_e32 v58, s6, v33
	v_mov_b32_e32 v59, v1
	v_lshlrev_b64 v[58:59], 13, v[58:59]
	v_lshl_add_u64 v[58:59], v[8:9], 0, v[58:59]
	global_load_dword v58, v[58:59], off nt
	v_mov_b32_e32 v59, v1
	s_waitcnt vmcnt(0)
; #define LAS __attribute__((address_space(3)))
; __device__ __forceinline__ unsigned pk2(float lo, float hi) { return f2bf(lo) | (f2bf(hi) << 16); }
; #define LDS_WAIT() asm volatile("s_waitcnt lgkmcnt(0)" ::: "memory")
; __device__ __forceinline__ void transpose_item(const float* W, int K, int N, bf16_t* WT, int drow0, int k0, int n0, LAS float* scr, int lane) {
; #pragma unroll
;     for (int i = 0; i < 32; ++i) { const int kk = 2 * i + (lane >> 5); scr[kk * 33 + (lane & 31)] = __builtin_nontemporal_load(&W[(size_t)(k0 + kk) * N + n0 + (lane & 31)]); }
;     LDS_WAIT();
;     const int c = lane & 7;
; #pragma unroll
;     for (int j = 0; j < 4; ++j) { const int n = (lane >> 3) + 8 * j; const LAS float* s = scr + (8 * c) * 33 + n;
;         u32x4 o; o.x = pk2(s[0 * 33], s[1 * 33]); o.y = pk2(s[2 * 33], s[3 * 33]); o.z = pk2(s[4 * 33], s[5 * 33]); o.w = pk2(s[6 * 33], s[7 * 33]);
;         *(u32x4*)(WT + (size_t)(drow0 + n) * K + k0 + 8 * c) = o; }
;     LDS_WAIT();
	ds_write2_b32 v55, v60, v58 offset0:148 offset1:214
	v_or_b32_e32 v58, s6, v34
	v_lshlrev_b64 v[58:59], 13, v[58:59]
	v_lshl_add_u64 v[58:59], v[8:9], 0, v[58:59]
	global_load_dword v60, v[58:59], off nt
	v_or_b32_e32 v58, s6, v35
	v_mov_b32_e32 v59, v1
	v_lshlrev_b64 v[58:59], 13, v[58:59]
	v_lshl_add_u64 v[58:59], v[8:9], 0, v[58:59]
	global_load_dword v58, v[58:59], off nt
	v_mov_b32_e32 v59, v1
	s_waitcnt vmcnt(0)
	ds_write2_b32 v56, v60, v58 offset0:24 offset1:90
	v_or_b32_e32 v58, s6, v36
	v_lshlrev_b64 v[58:59], 13, v[58:59]
	v_lshl_add_u64 v[58:59], v[8:9], 0, v[58:59]
	global_load_dword v60, v[58:59], off nt
	v_or_b32_e32 v58, s6, v37
	v_mov_b32_e32 v59, v1
	v_lshlrev_b64 v[58:59], 13, v[58:59]
	v_lshl_add_u64 v[58:59], v[8:9], 0, v[58:59]
	global_load_dword v58, v[58:59], off nt
	v_mov_b32_e32 v59, v1
	s_waitcnt vmcnt(0)
	ds_write2_b32 v56, v60, v58 offset0:156 offset1:222
	v_or_b32_e32 v58, s6, v38
	v_lshlrev_b64 v[58:59], 13, v[58:59]
	v_lshl_add_u64 v[58:59], v[8:9], 0, v[58:59]
	global_load_dword v60, v[58:59], off nt
	v_or_b32_e32 v58, s6, v39
	v_mov_b32_e32 v59, v1
	v_lshlrev_b64 v[58:59], 13, v[58:59]
	v_lshl_add_u64 v[58:59], v[8:9], 0, v[58:59]
	global_load_dword v58, v[58:59], off nt
	v_mov_b32_e32 v59, v1
	s_waitcnt vmcnt(0)
	ds_write2_b32 v57, v60, v58 offset0:32 offset1:98
	v_or_b32_e32 v58, s6, v40
	v_lshlrev_b64 v[58:59], 13, v[58:59]
	v_lshl_add_u64 v[58:59], v[8:9], 0, v[58:59]
	global_load_dword v60, v[58:59], off nt
	v_or_b32_e32 v58, s6, v41
	v_mov_b32_e32 v59, v1
	v_lshlrev_b64 v[58:59], 13, v[58:59]
	v_lshl_add_u64 v[8:9], v[8:9], 0, v[58:59]
	global_load_dword v8, v[8:9], off nt
	s_waitcnt vmcnt(0)
	ds_write2_b32 v57, v60, v8 offset0:164 offset1:230
	s_waitcnt lgkmcnt(0)
	ds_read_b32 v58, v43
	ds_read_b32 v59, v43 offset:132
	v_lshl_add_u64 v[8:9], s[6:7], 1, v[4:5]
	s_mov_b64 s[6:7], 0
	s_waitcnt lgkmcnt(1)
	v_bfe_u32 v60, v58, 16, 1
	v_add3_u32 v58, v58, v60, s11
	s_waitcnt lgkmcnt(0)
	v_bfe_u32 v60, v59, 16, 1
	v_lshrrev_b32_e32 v58, 16, v58
	v_add3_u32 v59, v59, v60, s11
	v_and_or_b32 v58, v59, s20, v58
	ds_read_b32 v59, v43 offset:264
	ds_read_b32 v60, v43 offset:396
	s_waitcnt lgkmcnt(1)
	v_bfe_u32 v61, v59, 16, 1
	v_add3_u32 v59, v59, v61, s11
	s_waitcnt lgkmcnt(0)
	v_bfe_u32 v61, v60, 16, 1
	v_lshrrev_b32_e32 v59, 16, v59
	v_add3_u32 v60, v60, v61, s11
	v_and_or_b32 v59, v60, s20, v59
	ds_read_b32 v60, v43 offset:528
	ds_read_b32 v61, v43 offset:660
	s_waitcnt lgkmcnt(1)
	v_bfe_u32 v62, v60, 16, 1
	v_add3_u32 v60, v60, v62, s11
	s_waitcnt lgkmcnt(0)
	v_bfe_u32 v62, v61, 16, 1
	v_lshrrev_b32_e32 v60, 16, v60
	v_add3_u32 v61, v61, v62, s11
	v_and_or_b32 v60, v61, s20, v60
	ds_read_b32 v61, v43 offset:792
	ds_read_b32 v62, v43 offset:924
	s_waitcnt lgkmcnt(1)
	v_bfe_u32 v63, v61, 16, 1
	v_add3_u32 v61, v61, v63, s11
	s_waitcnt lgkmcnt(0)
	v_bfe_u32 v63, v62, 16, 1
	v_lshrrev_b32_e32 v61, 16, v61
	v_add3_u32 v62, v62, v63, s11
	v_and_or_b32 v61, v62, s20, v61
	v_or_b32_e32 v62, s24, v42
	v_mul_u32_u24_e32 v62, 0x1600, v62
	v_lshlrev_b32_e32 v62, 1, v62
	v_mov_b32_e32 v63, v1
	v_lshl_add_u64 v[62:63], v[8:9], 0, v[62:63]
	global_store_dwordx4 v[62:63], v[58:61], off
	ds_read_b32 v58, v43 offset:32
	ds_read_b32 v59, v43 offset:164
	s_waitcnt lgkmcnt(0)
	v_bfe_u32 v60, v58, 16, 1
	v_add3_u32 v58, v58, v60, s11
	v_bfe_u32 v60, v59, 16, 1
	v_lshrrev_b32_e32 v58, 16, v58
	v_add3_u32 v59, v59, v60, s11
	v_and_or_b32 v58, v59, s20, v58
	ds_read_b32 v59, v43 offset:296
	ds_read_b32 v60, v43 offset:428
	s_waitcnt lgkmcnt(0)
	v_bfe_u32 v61, v59, 16, 1
	v_add3_u32 v59, v59, v61, s11
	v_bfe_u32 v61, v60, 16, 1
	v_lshrrev_b32_e32 v59, 16, v59
	v_add3_u32 v60, v60, v61, s11
	v_and_or_b32 v59, v60, s20, v59
	ds_read_b32 v60, v43 offset:560
	ds_read_b32 v61, v43 offset:692
	s_waitcnt lgkmcnt(0)
	v_bfe_u32 v62, v60, 16, 1
	v_add3_u32 v60, v60, v62, s11
	v_bfe_u32 v62, v61, 16, 1
	v_lshrrev_b32_e32 v60, 16, v60
	v_add3_u32 v61, v61, v62, s11
	v_and_or_b32 v60, v61, s20, v60
	ds_read_b32 v61, v43 offset:824
	ds_read_b32 v62, v43 offset:956
	s_waitcnt lgkmcnt(0)
	v_bfe_u32 v63, v61, 16, 1
	v_add3_u32 v61, v61, v63, s11
	v_bfe_u32 v63, v62, 16, 1
	v_lshrrev_b32_e32 v61, 16, v61
	v_add3_u32 v62, v62, v63, s11
	v_and_or_b32 v61, v62, s20, v61
	v_or_b32_e32 v62, s24, v44
	v_mul_u32_u24_e32 v62, 0x1600, v62
	v_lshlrev_b32_e32 v62, 1, v62
	v_mov_b32_e32 v63, v1
	v_lshl_add_u64 v[62:63], v[8:9], 0, v[62:63]
	global_store_dwordx4 v[62:63], v[58:61], off
	ds_read_b32 v58, v43 offset:64
	ds_read_b32 v59, v43 offset:196
	s_waitcnt lgkmcnt(0)
	v_bfe_u32 v60, v58, 16, 1
	v_add3_u32 v58, v58, v60, s11
	v_bfe_u32 v60, v59, 16, 1
	v_lshrrev_b32_e32 v58, 16, v58
	v_add3_u32 v59, v59, v60, s11
	v_and_or_b32 v58, v59, s20, v58
	ds_read_b32 v59, v43 offset:328
	ds_read_b32 v60, v43 offset:460
	s_waitcnt lgkmcnt(0)
	v_bfe_u32 v61, v59, 16, 1
	v_add3_u32 v59, v59, v61, s11
	v_bfe_u32 v61, v60, 16, 1
	v_lshrrev_b32_e32 v59, 16, v59
	v_add3_u32 v60, v60, v61, s11
	v_and_or_b32 v59, v60, s20, v59
	ds_read_b32 v60, v43 offset:592
	ds_read_b32 v61, v43 offset:724
	s_waitcnt lgkmcnt(0)
	v_bfe_u32 v62, v60, 16, 1
	v_add3_u32 v60, v60, v62, s11
	v_bfe_u32 v62, v61, 16, 1
	v_lshrrev_b32_e32 v60, 16, v60
	v_add3_u32 v61, v61, v62, s11
	v_and_or_b32 v60, v61, s20, v60
	ds_read_b32 v61, v43 offset:856
	ds_read_b32 v62, v43 offset:988
	s_waitcnt lgkmcnt(0)
	v_bfe_u32 v63, v61, 16, 1
	v_add3_u32 v61, v61, v63, s11
	v_bfe_u32 v63, v62, 16, 1
	v_lshrrev_b32_e32 v61, 16, v61
	v_add3_u32 v62, v62, v63, s11
	v_and_or_b32 v61, v62, s20, v61
	v_or_b32_e32 v62, s24, v45
	v_mul_u32_u24_e32 v62, 0x1600, v62
	v_lshlrev_b32_e32 v62, 1, v62
	v_mov_b32_e32 v63, v1
	v_lshl_add_u64 v[62:63], v[8:9], 0, v[62:63]
	global_store_dwordx4 v[62:63], v[58:61], off
	ds_read_b32 v58, v43 offset:96
	ds_read_b32 v59, v43 offset:228
	s_waitcnt lgkmcnt(0)
	v_bfe_u32 v60, v58, 16, 1
	v_add3_u32 v58, v58, v60, s11
	v_bfe_u32 v60, v59, 16, 1
	v_lshrrev_b32_e32 v58, 16, v58
	v_add3_u32 v59, v59, v60, s11
	v_and_or_b32 v58, v59, s20, v58
	ds_read_b32 v59, v43 offset:360
	ds_read_b32 v60, v43 offset:492
	s_waitcnt lgkmcnt(0)
	v_bfe_u32 v61, v59, 16, 1
	v_add3_u32 v59, v59, v61, s11
	v_bfe_u32 v61, v60, 16, 1
	v_lshrrev_b32_e32 v59, 16, v59
	v_add3_u32 v60, v60, v61, s11
	v_and_or_b32 v59, v60, s20, v59
	ds_read_b32 v60, v43 offset:624
	ds_read_b32 v61, v43 offset:756
	s_waitcnt lgkmcnt(0)
	v_bfe_u32 v62, v60, 16, 1
	v_add3_u32 v60, v60, v62, s11
	v_bfe_u32 v62, v61, 16, 1
	v_lshrrev_b32_e32 v60, 16, v60
	v_add3_u32 v61, v61, v62, s11
	v_and_or_b32 v60, v61, s20, v60
	ds_read_b32 v61, v43 offset:888
	ds_read_b32 v62, v43 offset:1020
	s_waitcnt lgkmcnt(0)
	v_bfe_u32 v63, v61, 16, 1
	v_add3_u32 v61, v61, v63, s11
	v_bfe_u32 v63, v62, 16, 1
	v_lshrrev_b32_e32 v61, 16, v61
	v_add3_u32 v62, v62, v63, s11
	v_and_or_b32 v61, v62, s20, v61
	v_or_b32_e32 v62, s24, v46
	v_mul_u32_u24_e32 v62, 0x1600, v62
	v_lshlrev_b32_e32 v62, 1, v62
	v_mov_b32_e32 v63, v1
	v_lshl_add_u64 v[8:9], v[8:9], 0, v[62:63]
	global_store_dwordx4 v[8:9], v[58:61], off
	s_waitcnt lgkmcnt(0)
; #define LAS __attribute__((address_space(3)))
; #define LDS_WAIT() asm volatile("s_waitcnt lgkmcnt(0)" ::: "memory")
; __device__ __forceinline__ void transpose_item(const float* W, int K, int N, bf16_t* WT, int drow0, int k0, int n0, LAS float* scr, int lane) {
; #pragma unroll
;     for (int i = 0; i < 32; ++i) { const int kk = 2 * i + (lane >> 5); scr[kk * 33 + (lane & 31)] = __builtin_nontemporal_load(&W[(size_t)(k0 + kk) * N + n0 + (lane & 31)]); }
;     LDS_WAIT();
; __device__ __forceinline__ void convert_ffn_dyn(const float* Wg, const float* Wu, const float* Wd, bf16_t* GU, bf16_t* DN, LAS unsigned char* lds, unsigned* ctr, int max_batches, int tid, int wave, int lane) {
;     ...
;         if (it < 2 * I1) { const int up = it >= I1, r = it - up * I1, kb = r / (FF / 32), nb = r % (FF / 32), n0 = nb * 32;
;             transpose_item(up ? Wu : Wg, DM, FF, GU, 256 * (n0 >> 7) + up * 128 + (n0 & 127), kb * 64, n0, scr, lane); }
.LBB0_1548:
	s_andn2_b64 vcc, exec, s[6:7]
	s_cbranch_vccnz .LBB0_1541
	v_readlane_b32 s40, v252, 32
	v_readlane_b32 s44, v252, 36
	v_readlane_b32 s45, v252, 37
	v_readlane_b32 s46, v252, 38
	v_readlane_b32 s47, v252, 39
	v_readlane_b32 s48, v252, 40
	v_readlane_b32 s49, v252, 41
	v_readlane_b32 s50, v252, 42
	v_readlane_b32 s51, v252, 43
	s_cmpk_gt_i32 s23, 0x15ff
	v_readlane_b32 s52, v252, 44
	v_readlane_b32 s53, v252, 45
	v_readlane_b32 s54, v252, 46
	v_readlane_b32 s55, v252, 47
	s_mov_b64 s[44:45], s[48:49]
	s_cselect_b32 s0, 0xffffea00, 0
	s_mov_b64 s[46:47], s[50:51]
	s_mov_b64 s[48:49], s[52:53]
	s_cselect_b32 s7, s48, s46
	s_cselect_b32 s26, s49, s47
	s_cselect_b32 s6, 0x80, 0
	s_add_i32 s0, s0, s23
	s_mul_hi_i32 s23, s0, 0x2e8ba2e9
	s_lshr_b32 s24, s23, 31
	s_ashr_i32 s23, s23, 5
	s_add_i32 s23, s23, s24
	s_mul_i32 s24, s23, 0xb0
	s_sub_i32 s0, s0, s24
	s_lshl_b32 s24, s0, 5
	s_lshl_b32 s0, s0, 6
	s_and_b32 s0, s0, 0xffffff00
	s_or_b32 s0, s0, s6
	s_and_b32 s6, s24, 0x60
	s_ashr_i32 s25, s24, 31
	s_or_b32 s0, s0, s6
	s_lshl_b32 s6, s23, 6
	s_lshl_b64 s[24:25], s[24:25], 2
	s_add_u32 s24, s7, s24
	s_addc_u32 s25, s26, s25
	v_lshl_add_u64 v[8:9], s[24:25], 0, v[0:1]
	v_or_b32_e32 v58, s6, v10
	v_mad_i64_i32 v[58:59], s[24:25], v58, s21, v[8:9]
	global_load_dword v60, v[58:59], off nt
	v_or_b32_e32 v58, s6, v11
	v_mad_i64_i32 v[58:59], s[24:25], v58, s21, v[8:9]
	global_load_dword v58, v[58:59], off nt
	s_ashr_i32 s7, s6, 31
	v_readlane_b32 s41, v252, 33
	v_readlane_b32 s42, v252, 34
	v_readlane_b32 s43, v252, 35
	s_mov_b64 s[50:51], s[54:55]
	s_waitcnt vmcnt(0)
	ds_write2_b32 v49, v60, v58 offset1:66
	v_or_b32_e32 v58, s6, v12
	v_mad_i64_i32 v[58:59], s[24:25], v58, s21, v[8:9]
	global_load_dword v60, v[58:59], off nt
	v_or_b32_e32 v58, s6, v13
	v_mad_i64_i32 v[58:59], s[24:25], v58, s21, v[8:9]
	global_load_dword v58, v[58:59], off nt
	s_waitcnt vmcnt(0)
	ds_write2_b32 v49, v60, v58 offset0:132 offset1:198
	v_or_b32_e32 v58, s6, v14
	v_mad_i64_i32 v[58:59], s[24:25], v58, s21, v[8:9]
	global_load_dword v60, v[58:59], off nt
	v_or_b32_e32 v58, s6, v15
	v_mad_i64_i32 v[58:59], s[24:25], v58, s21, v[8:9]
	global_load_dword v58, v[58:59], off nt
	s_waitcnt vmcnt(0)
	ds_write2_b32 v52, v60, v58 offset0:8 offset1:74
	v_or_b32_e32 v58, s6, v16
	v_mad_i64_i32 v[58:59], s[24:25], v58, s21, v[8:9]
	global_load_dword v60, v[58:59], off nt
	v_or_b32_e32 v58, s6, v17
	v_mad_i64_i32 v[58:59], s[24:25], v58, s21, v[8:9]
	global_load_dword v58, v[58:59], off nt
	s_waitcnt vmcnt(0)
	ds_write2_b32 v50, v60, v58 offset1:66
	v_or_b32_e32 v58, s6, v18
	v_mad_i64_i32 v[58:59], s[24:25], v58, s21, v[8:9]
	global_load_dword v60, v[58:59], off nt
	v_or_b32_e32 v58, s6, v19
	v_mad_i64_i32 v[58:59], s[24:25], v58, s21, v[8:9]
	global_load_dword v58, v[58:59], off nt
	s_waitcnt vmcnt(0)
	ds_write2_b32 v50, v60, v58 offset0:132 offset1:198
	v_or_b32_e32 v58, s6, v20
	v_mad_i64_i32 v[58:59], s[24:25], v58, s21, v[8:9]
	global_load_dword v60, v[58:59], off nt
	v_or_b32_e32 v58, s6, v21
	v_mad_i64_i32 v[58:59], s[24:25], v58, s21, v[8:9]
	global_load_dword v58, v[58:59], off nt
	s_waitcnt vmcnt(0)
	ds_write2_b32 v53, v60, v58 offset0:8 offset1:74
	v_or_b32_e32 v58, s6, v22
	v_mad_i64_i32 v[58:59], s[24:25], v58, s21, v[8:9]
	global_load_dword v60, v[58:59], off nt
	v_or_b32_e32 v58, s6, v23
	v_mad_i64_i32 v[58:59], s[24:25], v58, s21, v[8:9]
	global_load_dword v58, v[58:59], off nt
	s_waitcnt vmcnt(0)
	ds_write2_b32 v51, v60, v58 offset1:66
	v_or_b32_e32 v58, s6, v24
	v_mad_i64_i32 v[58:59], s[24:25], v58, s21, v[8:9]
	global_load_dword v60, v[58:59], off nt
	v_or_b32_e32 v58, s6, v25
	v_mad_i64_i32 v[58:59], s[24:25], v58, s21, v[8:9]
	global_load_dword v58, v[58:59], off nt
	s_waitcnt vmcnt(0)
	ds_write2_b32 v51, v60, v58 offset0:132 offset1:198
	v_or_b32_e32 v58, s6, v26
	v_mad_i64_i32 v[58:59], s[24:25], v58, s21, v[8:9]
	global_load_dword v60, v[58:59], off nt
	v_or_b32_e32 v58, s6, v27
	v_mad_i64_i32 v[58:59], s[24:25], v58, s21, v[8:9]
	global_load_dword v58, v[58:59], off nt
	s_waitcnt vmcnt(0)
	ds_write2_b32 v54, v60, v58 offset0:8 offset1:74
	v_or_b32_e32 v58, s6, v28
	v_mad_i64_i32 v[58:59], s[24:25], v58, s21, v[8:9]
	global_load_dword v60, v[58:59], off nt
	v_or_b32_e32 v58, s6, v29
	v_mad_i64_i32 v[58:59], s[24:25], v58, s21, v[8:9]
	global_load_dword v58, v[58:59], off nt
	s_waitcnt vmcnt(0)
	ds_write2_b32 v54, v60, v58 offset0:140 offset1:206
	v_or_b32_e32 v58, s6, v30
	v_mad_i64_i32 v[58:59], s[24:25], v58, s21, v[8:9]
	global_load_dword v60, v[58:59], off nt
	v_or_b32_e32 v58, s6, v31
	v_mad_i64_i32 v[58:59], s[24:25], v58, s21, v[8:9]
	global_load_dword v58, v[58:59], off nt
	s_waitcnt vmcnt(0)
	ds_write2_b32 v55, v60, v58 offset0:16 offset1:82
	v_or_b32_e32 v58, s6, v32
	v_mad_i64_i32 v[58:59], s[24:25], v58, s21, v[8:9]
	global_load_dword v60, v[58:59], off nt
	v_or_b32_e32 v58, s6, v33
	v_mad_i64_i32 v[58:59], s[24:25], v58, s21, v[8:9]
	global_load_dword v58, v[58:59], off nt
	s_waitcnt vmcnt(0)
	ds_write2_b32 v55, v60, v58 offset0:148 offset1:214
	v_or_b32_e32 v58, s6, v34
	v_mad_i64_i32 v[58:59], s[24:25], v58, s21, v[8:9]
	global_load_dword v60, v[58:59], off nt
	v_or_b32_e32 v58, s6, v35
	v_mad_i64_i32 v[58:59], s[24:25], v58, s21, v[8:9]
	global_load_dword v58, v[58:59], off nt
	s_waitcnt vmcnt(0)
	ds_write2_b32 v56, v60, v58 offset0:24 offset1:90
	v_or_b32_e32 v58, s6, v36
	v_mad_i64_i32 v[58:59], s[24:25], v58, s21, v[8:9]
	global_load_dword v60, v[58:59], off nt
	v_or_b32_e32 v58, s6, v37
	v_mad_i64_i32 v[58:59], s[24:25], v58, s21, v[8:9]
	global_load_dword v58, v[58:59], off nt
	s_waitcnt vmcnt(0)
; #define LAS __attribute__((address_space(3)))
; __device__ __forceinline__ unsigned pk2(float lo, float hi) { return f2bf(lo) | (f2bf(hi) << 16); }
; #define LDS_WAIT() asm volatile("s_waitcnt lgkmcnt(0)" ::: "memory")
; __device__ __forceinline__ void transpose_item(const float* W, int K, int N, bf16_t* WT, int drow0, int k0, int n0, LAS float* scr, int lane) {
; #pragma unroll
;     for (int i = 0; i < 32; ++i) { const int kk = 2 * i + (lane >> 5); scr[kk * 33 + (lane & 31)] = __builtin_nontemporal_load(&W[(size_t)(k0 + kk) * N + n0 + (lane & 31)]); }
;     LDS_WAIT();
;     const int c = lane & 7;
; #pragma unroll
;     for (int j = 0; j < 4; ++j) { const int n = (lane >> 3) + 8 * j; const LAS float* s = scr + (8 * c) * 33 + n;
;         u32x4 o; o.x = pk2(s[0 * 33], s[1 * 33]); o.y = pk2(s[2 * 33], s[3 * 33]); o.z = pk2(s[4 * 33], s[5 * 33]); o.w = pk2(s[6 * 33], s[7 * 33]);
;         *(u32x4*)(WT + (size_t)(drow0 + n) * K + k0 + 8 * c) = o; }
;     LDS_WAIT();
	ds_write2_b32 v56, v60, v58 offset0:156 offset1:222
	v_or_b32_e32 v58, s6, v38
	v_mad_i64_i32 v[58:59], s[24:25], v58, s21, v[8:9]
	global_load_dword v60, v[58:59], off nt
	v_or_b32_e32 v58, s6, v39
	v_mad_i64_i32 v[58:59], s[24:25], v58, s21, v[8:9]
	global_load_dword v58, v[58:59], off nt
	s_waitcnt vmcnt(0)
	ds_write2_b32 v57, v60, v58 offset0:32 offset1:98
	v_or_b32_e32 v58, s6, v40
	v_mad_i64_i32 v[58:59], s[24:25], v58, s21, v[8:9]
	global_load_dword v58, v[58:59], off nt
	v_or_b32_e32 v59, s6, v41
	v_mad_i64_i32 v[8:9], s[24:25], v59, s21, v[8:9]
	global_load_dword v8, v[8:9], off nt
	s_waitcnt vmcnt(0)
	ds_write2_b32 v57, v58, v8 offset0:164 offset1:230
	s_waitcnt lgkmcnt(0)
	ds_read_b32 v58, v43
	ds_read_b32 v59, v43 offset:132
	v_lshl_add_u64 v[8:9], s[6:7], 1, v[6:7]
	s_waitcnt lgkmcnt(0)
	v_bfe_u32 v60, v58, 16, 1
	v_add3_u32 v58, v58, v60, s11
	v_bfe_u32 v60, v59, 16, 1
	v_lshrrev_b32_e32 v58, 16, v58
	v_add3_u32 v59, v59, v60, s11
	v_and_or_b32 v58, v59, s20, v58
	ds_read_b32 v59, v43 offset:264
	ds_read_b32 v60, v43 offset:396
	s_waitcnt lgkmcnt(1)
	v_bfe_u32 v61, v59, 16, 1
	v_add3_u32 v59, v59, v61, s11
	s_waitcnt lgkmcnt(0)
	v_bfe_u32 v61, v60, 16, 1
	v_lshrrev_b32_e32 v59, 16, v59
	v_add3_u32 v60, v60, v61, s11
	v_and_or_b32 v59, v60, s20, v59
	ds_read_b32 v60, v43 offset:528
	ds_read_b32 v61, v43 offset:660
	s_waitcnt lgkmcnt(1)
	v_bfe_u32 v62, v60, 16, 1
	v_add3_u32 v60, v60, v62, s11
	s_waitcnt lgkmcnt(0)
	v_bfe_u32 v62, v61, 16, 1
	v_lshrrev_b32_e32 v60, 16, v60
	v_add3_u32 v61, v61, v62, s11
	v_and_or_b32 v60, v61, s20, v60
	ds_read_b32 v61, v43 offset:792
	ds_read_b32 v62, v43 offset:924
	s_waitcnt lgkmcnt(1)
	v_bfe_u32 v63, v61, 16, 1
	v_add3_u32 v61, v61, v63, s11
	s_waitcnt lgkmcnt(0)
	v_bfe_u32 v63, v62, 16, 1
	v_lshrrev_b32_e32 v61, 16, v61
	v_add3_u32 v62, v62, v63, s11
	v_and_or_b32 v61, v62, s20, v61
	v_or_b32_e32 v62, s0, v42
	v_ashrrev_i32_e32 v63, 31, v62
	v_lshlrev_b64 v[62:63], 12, v[62:63]
	v_lshl_add_u64 v[62:63], v[8:9], 0, v[62:63]
	global_store_dwordx4 v[62:63], v[58:61], off
	ds_read_b32 v58, v43 offset:32
	ds_read_b32 v59, v43 offset:164
	s_waitcnt lgkmcnt(0)
	v_bfe_u32 v60, v58, 16, 1
	v_add3_u32 v58, v58, v60, s11
	v_bfe_u32 v60, v59, 16, 1
	v_lshrrev_b32_e32 v58, 16, v58
	v_add3_u32 v59, v59, v60, s11
	v_and_or_b32 v58, v59, s20, v58
	ds_read_b32 v59, v43 offset:296
	ds_read_b32 v60, v43 offset:428
	s_waitcnt lgkmcnt(0)
	v_bfe_u32 v61, v59, 16, 1
	v_add3_u32 v59, v59, v61, s11
	v_bfe_u32 v61, v60, 16, 1
	v_lshrrev_b32_e32 v59, 16, v59
	v_add3_u32 v60, v60, v61, s11
	v_and_or_b32 v59, v60, s20, v59
	ds_read_b32 v60, v43 offset:560
	ds_read_b32 v61, v43 offset:692
	s_waitcnt lgkmcnt(0)
	v_bfe_u32 v62, v60, 16, 1
	v_add3_u32 v60, v60, v62, s11
	v_bfe_u32 v62, v61, 16, 1
	v_lshrrev_b32_e32 v60, 16, v60
	v_add3_u32 v61, v61, v62, s11
	v_and_or_b32 v60, v61, s20, v60
	ds_read_b32 v61, v43 offset:824
	ds_read_b32 v62, v43 offset:956
	s_waitcnt lgkmcnt(0)
	v_bfe_u32 v63, v61, 16, 1
	v_add3_u32 v61, v61, v63, s11
	v_bfe_u32 v63, v62, 16, 1
	v_lshrrev_b32_e32 v61, 16, v61
	v_add3_u32 v62, v62, v63, s11
	v_and_or_b32 v61, v62, s20, v61
	v_or_b32_e32 v62, s0, v44
	v_ashrrev_i32_e32 v63, 31, v62
	v_lshlrev_b64 v[62:63], 12, v[62:63]
	v_lshl_add_u64 v[62:63], v[8:9], 0, v[62:63]
	global_store_dwordx4 v[62:63], v[58:61], off
	ds_read_b32 v58, v43 offset:64
	ds_read_b32 v59, v43 offset:196
	s_waitcnt lgkmcnt(0)
	v_bfe_u32 v60, v58, 16, 1
	v_add3_u32 v58, v58, v60, s11
	v_bfe_u32 v60, v59, 16, 1
	v_lshrrev_b32_e32 v58, 16, v58
	v_add3_u32 v59, v59, v60, s11
	v_and_or_b32 v58, v59, s20, v58
	ds_read_b32 v59, v43 offset:328
	ds_read_b32 v60, v43 offset:460
	s_waitcnt lgkmcnt(0)
	v_bfe_u32 v61, v59, 16, 1
	v_add3_u32 v59, v59, v61, s11
	v_bfe_u32 v61, v60, 16, 1
	v_lshrrev_b32_e32 v59, 16, v59
	v_add3_u32 v60, v60, v61, s11
	v_and_or_b32 v59, v60, s20, v59
	ds_read_b32 v60, v43 offset:592
	ds_read_b32 v61, v43 offset:724
	s_waitcnt lgkmcnt(0)
	v_bfe_u32 v62, v60, 16, 1
	v_add3_u32 v60, v60, v62, s11
	v_bfe_u32 v62, v61, 16, 1
	v_lshrrev_b32_e32 v60, 16, v60
	v_add3_u32 v61, v61, v62, s11
	v_and_or_b32 v60, v61, s20, v60
	ds_read_b32 v61, v43 offset:856
	ds_read_b32 v62, v43 offset:988
	s_waitcnt lgkmcnt(0)
	v_bfe_u32 v63, v61, 16, 1
	v_add3_u32 v61, v61, v63, s11
	v_bfe_u32 v63, v62, 16, 1
	v_lshrrev_b32_e32 v61, 16, v61
	v_add3_u32 v62, v62, v63, s11
	v_and_or_b32 v61, v62, s20, v61
	v_or_b32_e32 v62, s0, v45
	v_ashrrev_i32_e32 v63, 31, v62
	v_lshlrev_b64 v[62:63], 12, v[62:63]
	v_lshl_add_u64 v[62:63], v[8:9], 0, v[62:63]
	global_store_dwordx4 v[62:63], v[58:61], off
	ds_read_b32 v58, v43 offset:96
	ds_read_b32 v59, v43 offset:228
	s_waitcnt lgkmcnt(0)
	v_bfe_u32 v60, v58, 16, 1
	v_add3_u32 v58, v58, v60, s11
	v_bfe_u32 v60, v59, 16, 1
	v_lshrrev_b32_e32 v58, 16, v58
	v_add3_u32 v59, v59, v60, s11
	v_and_or_b32 v58, v59, s20, v58
	ds_read_b32 v59, v43 offset:360
	ds_read_b32 v60, v43 offset:492
	s_waitcnt lgkmcnt(0)
	v_bfe_u32 v61, v59, 16, 1
	v_add3_u32 v59, v59, v61, s11
	v_bfe_u32 v61, v60, 16, 1
	v_lshrrev_b32_e32 v59, 16, v59
	v_add3_u32 v60, v60, v61, s11
	v_and_or_b32 v59, v60, s20, v59
	ds_read_b32 v60, v43 offset:624
	ds_read_b32 v61, v43 offset:756
	s_waitcnt lgkmcnt(0)
	v_bfe_u32 v62, v60, 16, 1
	v_add3_u32 v60, v60, v62, s11
	v_bfe_u32 v62, v61, 16, 1
	v_lshrrev_b32_e32 v60, 16, v60
	v_add3_u32 v61, v61, v62, s11
	v_and_or_b32 v60, v61, s20, v60
	ds_read_b32 v61, v43 offset:888
	ds_read_b32 v62, v43 offset:1020
	s_waitcnt lgkmcnt(0)
	v_bfe_u32 v63, v61, 16, 1
	v_add3_u32 v61, v61, v63, s11
	v_bfe_u32 v63, v62, 16, 1
	v_lshrrev_b32_e32 v61, 16, v61
	v_add3_u32 v62, v62, v63, s11
	v_and_or_b32 v61, v62, s20, v61
	v_or_b32_e32 v62, s0, v46
	v_ashrrev_i32_e32 v63, 31, v62
	v_lshlrev_b64 v[62:63], 12, v[62:63]
	v_lshl_add_u64 v[8:9], v[8:9], 0, v[62:63]
	global_store_dwordx4 v[8:9], v[58:61], off
	s_waitcnt lgkmcnt(0)
	s_branch .LBB0_1541

; #define LAS __attribute__((address_space(3)))
; #define LDS_WAIT() asm volatile("s_waitcnt lgkmcnt(0)" ::: "memory")
; __device__ __forceinline__ void transpose_item(const float* W, int K, int N, bf16_t* WT, int drow0, int k0, int n0, LAS float* scr, int lane) {
; #pragma unroll
;     for (int i = 0; i < 32; ++i) { const int kk = 2 * i + (lane >> 5); scr[kk * 33 + (lane & 31)] = __builtin_nontemporal_load(&W[(size_t)(k0 + kk) * N + n0 + (lane & 31)]); }
;     LDS_WAIT();
; __device__ __forceinline__ void convert_ffn_dyn(const float* Wg, const float* Wu, const float* Wd, bf16_t* GU, bf16_t* DN, LAS unsigned char* lds, unsigned* ctr, int max_batches, int tid, int wave, int lane) {
;     ...
;         if (tid == 0) MISC[0] = (int)atomicAdd(ctr, 1u);
;         __syncthreads();
;         const int b = __builtin_amdgcn_readfirstlane(MISC[0]);
;         __syncthreads();
;         if (b >= NB) break;
;         const int it = b * 8 + wave;
;         if (it < 2 * I1) { const int up = it >= I1, r = it - up * I1, kb = r / (FF / 32), nb = r % (FF / 32), n0 = nb * 32;
;             transpose_item(up ? Wu : Wg, DM, FF, GU, 256 * (n0 >> 7) + up * 128 + (n0 & 127), kb * 64, n0, scr, lane); }
;         else { const int r = it - 2 * I1, kb = r / (DM / 32), nb = r % (DM / 32); transpose_item(Wd, FF, DM, DN, nb * 32, kb * 64, nb * 32, scr, lane); }
.LBB0_1610:
	s_or_b64 exec, exec, s[8:9]
	s_waitcnt lgkmcnt(0)
	s_barrier
	ds_read_b32 v8, v48
	s_mov_b64 s[8:9], -1
	s_waitcnt lgkmcnt(0)
	s_barrier
	v_readfirstlane_b32 s4, v8
	s_cmpk_gt_i32 s4, 0x83f
	s_cbranch_scc1 .LBB0_1607
	s_lshl_b32 s26, s4, 3
	s_add_i32 s26, s26, s11
	s_cmpk_gt_i32 s26, 0x2bff
	v_add_u32_e32 v57, 0x800, v51
	v_add_u32_e32 v56, 0xc00, v51
	v_add_u32_e32 v55, 0x1000, v51
	s_cbranch_scc0 .LBB0_1613
	s_and_b32 s4, s26, 0x7fffffc0
	s_add_i32 s8, s4, 0xffffd400
	s_lshl_b32 s4, s26, 5
	s_and_b32 s27, s4, 0x7e0
	s_lshl_b32 s4, s27, 2
	v_or_b32_e32 v58, s8, v10
	v_mov_b32_e32 v59, v1
	v_lshl_add_u64 v[8:9], v[2:3], 0, s[4:5]
	v_lshlrev_b64 v[58:59], 13, v[58:59]
	v_lshl_add_u64 v[58:59], v[8:9], 0, v[58:59]
	global_load_dword v60, v[58:59], off nt
	v_or_b32_e32 v58, s8, v11
	v_mov_b32_e32 v59, v1
	v_lshlrev_b64 v[58:59], 13, v[58:59]
	v_lshl_add_u64 v[58:59], v[8:9], 0, v[58:59]
	global_load_dword v58, v[58:59], off nt
	v_mov_b32_e32 v59, v1
	s_mov_b32 s9, s5
	s_waitcnt vmcnt(0)
	ds_write2_b32 v49, v60, v58 offset1:66
	v_or_b32_e32 v58, s8, v12
	v_lshlrev_b64 v[58:59], 13, v[58:59]
	v_lshl_add_u64 v[58:59], v[8:9], 0, v[58:59]
	global_load_dword v60, v[58:59], off nt
	v_or_b32_e32 v58, s8, v13
	v_mov_b32_e32 v59, v1
	v_lshlrev_b64 v[58:59], 13, v[58:59]
	v_lshl_add_u64 v[58:59], v[8:9], 0, v[58:59]
	global_load_dword v58, v[58:59], off nt
	v_mov_b32_e32 v59, v1
	s_waitcnt vmcnt(0)
	ds_write2_b32 v49, v60, v58 offset0:132 offset1:198
	v_or_b32_e32 v58, s8, v14
	v_lshlrev_b64 v[58:59], 13, v[58:59]
	v_lshl_add_u64 v[58:59], v[8:9], 0, v[58:59]
	global_load_dword v60, v[58:59], off nt
	v_or_b32_e32 v58, s8, v15
	v_mov_b32_e32 v59, v1
	v_lshlrev_b64 v[58:59], 13, v[58:59]
	v_lshl_add_u64 v[58:59], v[8:9], 0, v[58:59]
	global_load_dword v58, v[58:59], off nt
	v_mov_b32_e32 v59, v1
	s_waitcnt vmcnt(0)
	ds_write2_b32 v52, v60, v58 offset0:8 offset1:74
	v_or_b32_e32 v58, s8, v16
	v_lshlrev_b64 v[58:59], 13, v[58:59]
	v_lshl_add_u64 v[58:59], v[8:9], 0, v[58:59]
	global_load_dword v60, v[58:59], off nt
	v_or_b32_e32 v58, s8, v17
	v_mov_b32_e32 v59, v1
	v_lshlrev_b64 v[58:59], 13, v[58:59]
	v_lshl_add_u64 v[58:59], v[8:9], 0, v[58:59]
	global_load_dword v58, v[58:59], off nt
	v_mov_b32_e32 v59, v1
	s_waitcnt vmcnt(0)
	ds_write2_b32 v50, v60, v58 offset1:66
	v_or_b32_e32 v58, s8, v18
	v_lshlrev_b64 v[58:59], 13, v[58:59]
	v_lshl_add_u64 v[58:59], v[8:9], 0, v[58:59]
	global_load_dword v60, v[58:59], off nt
	v_or_b32_e32 v58, s8, v19
	v_mov_b32_e32 v59, v1
	v_lshlrev_b64 v[58:59], 13, v[58:59]
	v_lshl_add_u64 v[58:59], v[8:9], 0, v[58:59]
	global_load_dword v58, v[58:59], off nt
	v_mov_b32_e32 v59, v1
	s_waitcnt vmcnt(0)
	ds_write2_b32 v50, v60, v58 offset0:132 offset1:198
	v_or_b32_e32 v58, s8, v20
	v_lshlrev_b64 v[58:59], 13, v[58:59]
	v_lshl_add_u64 v[58:59], v[8:9], 0, v[58:59]
	global_load_dword v60, v[58:59], off nt
	v_or_b32_e32 v58, s8, v21
	v_mov_b32_e32 v59, v1
	v_lshlrev_b64 v[58:59], 13, v[58:59]
	v_lshl_add_u64 v[58:59], v[8:9], 0, v[58:59]
	global_load_dword v58, v[58:59], off nt
	v_mov_b32_e32 v59, v1
	s_waitcnt vmcnt(0)
	ds_write2_b32 v53, v60, v58 offset0:8 offset1:74
	v_or_b32_e32 v58, s8, v22
	v_lshlrev_b64 v[58:59], 13, v[58:59]
	v_lshl_add_u64 v[58:59], v[8:9], 0, v[58:59]
	global_load_dword v60, v[58:59], off nt
	v_or_b32_e32 v58, s8, v23
	v_mov_b32_e32 v59, v1
	v_lshlrev_b64 v[58:59], 13, v[58:59]
	v_lshl_add_u64 v[58:59], v[8:9], 0, v[58:59]
	global_load_dword v58, v[58:59], off nt
	v_mov_b32_e32 v59, v1
	s_waitcnt vmcnt(0)
	ds_write2_b32 v51, v60, v58 offset1:66
	v_or_b32_e32 v58, s8, v24
	v_lshlrev_b64 v[58:59], 13, v[58:59]
	v_lshl_add_u64 v[58:59], v[8:9], 0, v[58:59]
	global_load_dword v60, v[58:59], off nt
	v_or_b32_e32 v58, s8, v25
	v_mov_b32_e32 v59, v1
	v_lshlrev_b64 v[58:59], 13, v[58:59]
	v_lshl_add_u64 v[58:59], v[8:9], 0, v[58:59]
	global_load_dword v58, v[58:59], off nt
	v_mov_b32_e32 v59, v1
	s_waitcnt vmcnt(0)
	ds_write2_b32 v51, v60, v58 offset0:132 offset1:198
	v_or_b32_e32 v58, s8, v26
	v_lshlrev_b64 v[58:59], 13, v[58:59]
	v_lshl_add_u64 v[58:59], v[8:9], 0, v[58:59]
	global_load_dword v60, v[58:59], off nt
	v_or_b32_e32 v58, s8, v27
	v_mov_b32_e32 v59, v1
	v_lshlrev_b64 v[58:59], 13, v[58:59]
	v_lshl_add_u64 v[58:59], v[8:9], 0, v[58:59]
	global_load_dword v58, v[58:59], off nt
	v_mov_b32_e32 v59, v1
	s_waitcnt vmcnt(0)
	ds_write2_b32 v54, v60, v58 offset0:8 offset1:74
	v_or_b32_e32 v58, s8, v28
	v_lshlrev_b64 v[58:59], 13, v[58:59]
	v_lshl_add_u64 v[58:59], v[8:9], 0, v[58:59]
	global_load_dword v60, v[58:59], off nt
	v_or_b32_e32 v58, s8, v29
	v_mov_b32_e32 v59, v1
	v_lshlrev_b64 v[58:59], 13, v[58:59]
	v_lshl_add_u64 v[58:59], v[8:9], 0, v[58:59]
	global_load_dword v58, v[58:59], off nt
	v_mov_b32_e32 v59, v1
	s_waitcnt vmcnt(0)
	ds_write2_b32 v54, v60, v58 offset0:140 offset1:206
	v_or_b32_e32 v58, s8, v30
	v_lshlrev_b64 v[58:59], 13, v[58:59]
	v_lshl_add_u64 v[58:59], v[8:9], 0, v[58:59]
	global_load_dword v60, v[58:59], off nt
	v_or_b32_e32 v58, s8, v31
	v_mov_b32_e32 v59, v1
	v_lshlrev_b64 v[58:59], 13, v[58:59]
	v_lshl_add_u64 v[58:59], v[8:9], 0, v[58:59]
	global_load_dword v58, v[58:59], off nt
	v_mov_b32_e32 v59, v1
	s_waitcnt vmcnt(0)
	ds_write2_b32 v57, v60, v58 offset0:16 offset1:82
	v_or_b32_e32 v58, s8, v32
	v_lshlrev_b64 v[58:59], 13, v[58:59]
	v_lshl_add_u64 v[58:59], v[8:9], 0, v[58:59]
	global_load_dword v60, v[58:59], off nt
	v_or_b32_e32 v58, s8, v33
	v_mov_b32_e32 v59, v1
	v_lshlrev_b64 v[58:59], 13, v[58:59]
	v_lshl_add_u64 v[58:59], v[8:9], 0, v[58:59]
	global_load_dword v58, v[58:59], off nt
	v_mov_b32_e32 v59, v1
	s_waitcnt vmcnt(0)
; #define LAS __attribute__((address_space(3)))
; __device__ __forceinline__ unsigned pk2(float lo, float hi) { return f2bf(lo) | (f2bf(hi) << 16); }
; #define LDS_WAIT() asm volatile("s_waitcnt lgkmcnt(0)" ::: "memory")
; __device__ __forceinline__ void transpose_item(const float* W, int K, int N, bf16_t* WT, int drow0, int k0, int n0, LAS float* scr, int lane) {
; #pragma unroll
;     for (int i = 0; i < 32; ++i) { const int kk = 2 * i + (lane >> 5); scr[kk * 33 + (lane & 31)] = __builtin_nontemporal_load(&W[(size_t)(k0 + kk) * N + n0 + (lane & 31)]); }
;     LDS_WAIT();
;     const int c = lane & 7;
; #pragma unroll
;     for (int j = 0; j < 4; ++j) { const int n = (lane >> 3) + 8 * j; const LAS float* s = scr + (8 * c) * 33 + n;
;         u32x4 o; o.x = pk2(s[0 * 33], s[1 * 33]); o.y = pk2(s[2 * 33], s[3 * 33]); o.z = pk2(s[4 * 33], s[5 * 33]); o.w = pk2(s[6 * 33], s[7 * 33]);
;         *(u32x4*)(WT + (size_t)(drow0 + n) * K + k0 + 8 * c) = o; }
;     LDS_WAIT();
	ds_write2_b32 v57, v60, v58 offset0:148 offset1:214
	v_or_b32_e32 v58, s8, v34
	v_lshlrev_b64 v[58:59], 13, v[58:59]
	v_lshl_add_u64 v[58:59], v[8:9], 0, v[58:59]
	global_load_dword v60, v[58:59], off nt
	v_or_b32_e32 v58, s8, v35
	v_mov_b32_e32 v59, v1
	v_lshlrev_b64 v[58:59], 13, v[58:59]
	v_lshl_add_u64 v[58:59], v[8:9], 0, v[58:59]
	global_load_dword v58, v[58:59], off nt
	v_mov_b32_e32 v59, v1
	s_waitcnt vmcnt(0)
	ds_write2_b32 v56, v60, v58 offset0:24 offset1:90
	v_or_b32_e32 v58, s8, v36
	v_lshlrev_b64 v[58:59], 13, v[58:59]
	v_lshl_add_u64 v[58:59], v[8:9], 0, v[58:59]
	global_load_dword v60, v[58:59], off nt
	v_or_b32_e32 v58, s8, v37
	v_mov_b32_e32 v59, v1
	v_lshlrev_b64 v[58:59], 13, v[58:59]
	v_lshl_add_u64 v[58:59], v[8:9], 0, v[58:59]
	global_load_dword v58, v[58:59], off nt
	v_mov_b32_e32 v59, v1
	s_waitcnt vmcnt(0)
	ds_write2_b32 v56, v60, v58 offset0:156 offset1:222
	v_or_b32_e32 v58, s8, v38
	v_lshlrev_b64 v[58:59], 13, v[58:59]
	v_lshl_add_u64 v[58:59], v[8:9], 0, v[58:59]
	global_load_dword v60, v[58:59], off nt
	v_or_b32_e32 v58, s8, v39
	v_mov_b32_e32 v59, v1
	v_lshlrev_b64 v[58:59], 13, v[58:59]
	v_lshl_add_u64 v[58:59], v[8:9], 0, v[58:59]
	global_load_dword v58, v[58:59], off nt
	v_mov_b32_e32 v59, v1
	s_waitcnt vmcnt(0)
	ds_write2_b32 v55, v60, v58 offset0:32 offset1:98
	v_or_b32_e32 v58, s8, v40
	v_lshlrev_b64 v[58:59], 13, v[58:59]
	v_lshl_add_u64 v[58:59], v[8:9], 0, v[58:59]
	global_load_dword v60, v[58:59], off nt
	v_or_b32_e32 v58, s8, v41
	v_mov_b32_e32 v59, v1
	v_lshlrev_b64 v[58:59], 13, v[58:59]
	v_lshl_add_u64 v[8:9], v[8:9], 0, v[58:59]
	global_load_dword v8, v[8:9], off nt
	s_waitcnt vmcnt(0)
	ds_write2_b32 v55, v60, v8 offset0:164 offset1:230
	s_waitcnt lgkmcnt(0)
	ds_read_b32 v58, v43
	ds_read_b32 v59, v43 offset:132
	v_lshl_add_u64 v[8:9], s[8:9], 1, v[4:5]
	s_mov_b64 s[8:9], 0
	s_waitcnt lgkmcnt(1)
	v_bfe_u32 v60, v58, 16, 1
	v_add3_u32 v58, v58, v60, s23
	s_waitcnt lgkmcnt(0)
	v_bfe_u32 v60, v59, 16, 1
	v_lshrrev_b32_e32 v58, 16, v58
	v_add3_u32 v59, v59, v60, s23
	v_and_or_b32 v58, v59, s24, v58
	ds_read_b32 v59, v43 offset:264
	ds_read_b32 v60, v43 offset:396
	s_waitcnt lgkmcnt(1)
	v_bfe_u32 v61, v59, 16, 1
	v_add3_u32 v59, v59, v61, s23
	s_waitcnt lgkmcnt(0)
	v_bfe_u32 v61, v60, 16, 1
	v_lshrrev_b32_e32 v59, 16, v59
	v_add3_u32 v60, v60, v61, s23
	v_and_or_b32 v59, v60, s24, v59
	ds_read_b32 v60, v43 offset:528
	ds_read_b32 v61, v43 offset:660
	s_waitcnt lgkmcnt(1)
	v_bfe_u32 v62, v60, 16, 1
	v_add3_u32 v60, v60, v62, s23
	s_waitcnt lgkmcnt(0)
	v_bfe_u32 v62, v61, 16, 1
	v_lshrrev_b32_e32 v60, 16, v60
	v_add3_u32 v61, v61, v62, s23
	v_and_or_b32 v60, v61, s24, v60
	ds_read_b32 v61, v43 offset:792
	ds_read_b32 v62, v43 offset:924
	s_waitcnt lgkmcnt(1)
	v_bfe_u32 v63, v61, 16, 1
	v_add3_u32 v61, v61, v63, s23
	s_waitcnt lgkmcnt(0)
	v_bfe_u32 v63, v62, 16, 1
	v_lshrrev_b32_e32 v61, 16, v61
	v_add3_u32 v62, v62, v63, s23
	v_and_or_b32 v61, v62, s24, v61
	v_or_b32_e32 v62, s27, v42
	v_mul_u32_u24_e32 v62, 0x1600, v62
	v_lshlrev_b32_e32 v62, 1, v62
	v_mov_b32_e32 v63, v1
	v_lshl_add_u64 v[62:63], v[8:9], 0, v[62:63]
	global_store_dwordx4 v[62:63], v[58:61], off
	ds_read_b32 v58, v43 offset:32
	ds_read_b32 v59, v43 offset:164
	s_waitcnt lgkmcnt(0)
	v_bfe_u32 v60, v58, 16, 1
	v_add3_u32 v58, v58, v60, s23
	v_bfe_u32 v60, v59, 16, 1
	v_lshrrev_b32_e32 v58, 16, v58
	v_add3_u32 v59, v59, v60, s23
	v_and_or_b32 v58, v59, s24, v58
	ds_read_b32 v59, v43 offset:296
	ds_read_b32 v60, v43 offset:428
	s_waitcnt lgkmcnt(0)
	v_bfe_u32 v61, v59, 16, 1
	v_add3_u32 v59, v59, v61, s23
	v_bfe_u32 v61, v60, 16, 1
	v_lshrrev_b32_e32 v59, 16, v59
	v_add3_u32 v60, v60, v61, s23
	v_and_or_b32 v59, v60, s24, v59
	ds_read_b32 v60, v43 offset:560
	ds_read_b32 v61, v43 offset:692
	s_waitcnt lgkmcnt(0)
	v_bfe_u32 v62, v60, 16, 1
	v_add3_u32 v60, v60, v62, s23
	v_bfe_u32 v62, v61, 16, 1
	v_lshrrev_b32_e32 v60, 16, v60
	v_add3_u32 v61, v61, v62, s23
	v_and_or_b32 v60, v61, s24, v60
	ds_read_b32 v61, v43 offset:824
	ds_read_b32 v62, v43 offset:956
	s_waitcnt lgkmcnt(0)
	v_bfe_u32 v63, v61, 16, 1
	v_add3_u32 v61, v61, v63, s23
	v_bfe_u32 v63, v62, 16, 1
	v_lshrrev_b32_e32 v61, 16, v61
	v_add3_u32 v62, v62, v63, s23
	v_and_or_b32 v61, v62, s24, v61
	v_or_b32_e32 v62, s27, v44
	v_mul_u32_u24_e32 v62, 0x1600, v62
	v_lshlrev_b32_e32 v62, 1, v62
	v_mov_b32_e32 v63, v1
	v_lshl_add_u64 v[62:63], v[8:9], 0, v[62:63]
	global_store_dwordx4 v[62:63], v[58:61], off
	ds_read_b32 v58, v43 offset:64
	ds_read_b32 v59, v43 offset:196
	s_waitcnt lgkmcnt(0)
	v_bfe_u32 v60, v58, 16, 1
	v_add3_u32 v58, v58, v60, s23
	v_bfe_u32 v60, v59, 16, 1
	v_lshrrev_b32_e32 v58, 16, v58
	v_add3_u32 v59, v59, v60, s23
	v_and_or_b32 v58, v59, s24, v58
	ds_read_b32 v59, v43 offset:328
	ds_read_b32 v60, v43 offset:460
	s_waitcnt lgkmcnt(0)
	v_bfe_u32 v61, v59, 16, 1
	v_add3_u32 v59, v59, v61, s23
	v_bfe_u32 v61, v60, 16, 1
	v_lshrrev_b32_e32 v59, 16, v59
	v_add3_u32 v60, v60, v61, s23
	v_and_or_b32 v59, v60, s24, v59
	ds_read_b32 v60, v43 offset:592
	ds_read_b32 v61, v43 offset:724
	s_waitcnt lgkmcnt(0)
	v_bfe_u32 v62, v60, 16, 1
	v_add3_u32 v60, v60, v62, s23
	v_bfe_u32 v62, v61, 16, 1
	v_lshrrev_b32_e32 v60, 16, v60
	v_add3_u32 v61, v61, v62, s23
	v_and_or_b32 v60, v61, s24, v60
	ds_read_b32 v61, v43 offset:856
	ds_read_b32 v62, v43 offset:988
	s_waitcnt lgkmcnt(0)
	v_bfe_u32 v63, v61, 16, 1
	v_add3_u32 v61, v61, v63, s23
	v_bfe_u32 v63, v62, 16, 1
	v_lshrrev_b32_e32 v61, 16, v61
	v_add3_u32 v62, v62, v63, s23
	v_and_or_b32 v61, v62, s24, v61
	v_or_b32_e32 v62, s27, v45
	v_mul_u32_u24_e32 v62, 0x1600, v62
	v_lshlrev_b32_e32 v62, 1, v62
	v_mov_b32_e32 v63, v1
	v_lshl_add_u64 v[62:63], v[8:9], 0, v[62:63]
	global_store_dwordx4 v[62:63], v[58:61], off
	ds_read_b32 v58, v43 offset:96
	ds_read_b32 v59, v43 offset:228
	s_waitcnt lgkmcnt(0)
	v_bfe_u32 v60, v58, 16, 1
	v_add3_u32 v58, v58, v60, s23
	v_bfe_u32 v60, v59, 16, 1
	v_lshrrev_b32_e32 v58, 16, v58
	v_add3_u32 v59, v59, v60, s23
	v_and_or_b32 v58, v59, s24, v58
	ds_read_b32 v59, v43 offset:360
	ds_read_b32 v60, v43 offset:492
	s_waitcnt lgkmcnt(0)
	v_bfe_u32 v61, v59, 16, 1
	v_add3_u32 v59, v59, v61, s23
	v_bfe_u32 v61, v60, 16, 1
	v_lshrrev_b32_e32 v59, 16, v59
	v_add3_u32 v60, v60, v61, s23
	v_and_or_b32 v59, v60, s24, v59
	ds_read_b32 v60, v43 offset:624
	ds_read_b32 v61, v43 offset:756
	s_waitcnt lgkmcnt(0)
	v_bfe_u32 v62, v60, 16, 1
	v_add3_u32 v60, v60, v62, s23
	v_bfe_u32 v62, v61, 16, 1
	v_lshrrev_b32_e32 v60, 16, v60
	v_add3_u32 v61, v61, v62, s23
	v_and_or_b32 v60, v61, s24, v60
	ds_read_b32 v61, v43 offset:888
	ds_read_b32 v62, v43 offset:1020
	s_waitcnt lgkmcnt(0)
	v_bfe_u32 v63, v61, 16, 1
	v_add3_u32 v61, v61, v63, s23
	v_bfe_u32 v63, v62, 16, 1
	v_lshrrev_b32_e32 v61, 16, v61
	v_add3_u32 v62, v62, v63, s23
	v_and_or_b32 v61, v62, s24, v61
	v_or_b32_e32 v62, s27, v46
	v_mul_u32_u24_e32 v62, 0x1600, v62
	v_lshlrev_b32_e32 v62, 1, v62
	v_mov_b32_e32 v63, v1
	v_lshl_add_u64 v[8:9], v[8:9], 0, v[62:63]
	global_store_dwordx4 v[8:9], v[58:61], off
	s_waitcnt lgkmcnt(0)
; #define LAS __attribute__((address_space(3)))
; #define LDS_WAIT() asm volatile("s_waitcnt lgkmcnt(0)" ::: "memory")
; __device__ __forceinline__ void transpose_item(const float* W, int K, int N, bf16_t* WT, int drow0, int k0, int n0, LAS float* scr, int lane) {
; #pragma unroll
;     for (int i = 0; i < 32; ++i) { const int kk = 2 * i + (lane >> 5); scr[kk * 33 + (lane & 31)] = __builtin_nontemporal_load(&W[(size_t)(k0 + kk) * N + n0 + (lane & 31)]); }
;     LDS_WAIT();
; __device__ __forceinline__ void convert_ffn_dyn(const float* Wg, const float* Wu, const float* Wd, bf16_t* GU, bf16_t* DN, LAS unsigned char* lds, unsigned* ctr, int max_batches, int tid, int wave, int lane) {
;     ...
;         if (it < 2 * I1) { const int up = it >= I1, r = it - up * I1, kb = r / (FF / 32), nb = r % (FF / 32), n0 = nb * 32;
;             transpose_item(up ? Wu : Wg, DM, FF, GU, 256 * (n0 >> 7) + up * 128 + (n0 & 127), kb * 64, n0, scr, lane); }
.LBB0_1613:
	s_andn2_b64 vcc, exec, s[8:9]
	s_cbranch_vccnz .LBB0_1606
	v_readlane_b32 s40, v252, 32
	v_readlane_b32 s44, v252, 36
	v_readlane_b32 s45, v252, 37
	v_readlane_b32 s46, v252, 38
	v_readlane_b32 s47, v252, 39
	v_readlane_b32 s48, v252, 40
	v_readlane_b32 s49, v252, 41
	s_cmpk_gt_i32 s26, 0x15ff
	v_readlane_b32 s50, v252, 42
	v_readlane_b32 s51, v252, 43
	v_readlane_b32 s52, v252, 44
	v_readlane_b32 s53, v252, 45
	s_mov_b64 s[44:45], s[48:49]
	s_cselect_b32 s4, 0xffffea00, 0
	s_mov_b64 s[46:47], s[50:51]
	s_mov_b64 s[48:49], s[52:53]
	s_cselect_b32 s9, s48, s46
	s_cselect_b32 s28, s49, s47
	s_cselect_b32 s8, 0x80, 0
	s_add_i32 s4, s4, s26
	s_mul_hi_i32 s26, s4, 0x2e8ba2e9
	s_lshr_b32 s27, s26, 31
	s_ashr_i32 s26, s26, 5
	s_add_i32 s27, s26, s27
	s_mul_i32 s26, s27, 0xb0
	s_sub_i32 s4, s4, s26
	s_lshl_b32 s26, s4, 5
	s_lshl_b32 s4, s4, 6
	s_and_b32 s4, s4, 0xffffff00
	s_or_b32 s4, s4, s8
	s_and_b32 s8, s26, 0x60
	s_or_b32 s4, s4, s8
	s_lshl_b32 s8, s27, 6
	s_ashr_i32 s27, s26, 31
	s_lshl_b64 s[26:27], s[26:27], 2
	s_add_u32 s26, s9, s26
	s_addc_u32 s27, s28, s27
	v_lshl_add_u64 v[8:9], s[26:27], 0, v[0:1]
	v_or_b32_e32 v58, s8, v10
	v_mad_i64_i32 v[58:59], s[26:27], v58, s25, v[8:9]
	global_load_dword v60, v[58:59], off nt
	v_or_b32_e32 v58, s8, v11
	v_mad_i64_i32 v[58:59], s[26:27], v58, s25, v[8:9]
	global_load_dword v58, v[58:59], off nt
	s_ashr_i32 s9, s8, 31
	v_readlane_b32 s41, v252, 33
	v_readlane_b32 s42, v252, 34
	v_readlane_b32 s43, v252, 35
	v_readlane_b32 s54, v252, 46
	v_readlane_b32 s55, v252, 47
	s_waitcnt vmcnt(0)
	ds_write2_b32 v49, v60, v58 offset1:66
	v_or_b32_e32 v58, s8, v12
	v_mad_i64_i32 v[58:59], s[26:27], v58, s25, v[8:9]
	global_load_dword v60, v[58:59], off nt
	v_or_b32_e32 v58, s8, v13
	v_mad_i64_i32 v[58:59], s[26:27], v58, s25, v[8:9]
	global_load_dword v58, v[58:59], off nt
	s_waitcnt vmcnt(0)
	ds_write2_b32 v49, v60, v58 offset0:132 offset1:198
	v_or_b32_e32 v58, s8, v14
	v_mad_i64_i32 v[58:59], s[26:27], v58, s25, v[8:9]
	global_load_dword v60, v[58:59], off nt
	v_or_b32_e32 v58, s8, v15
	v_mad_i64_i32 v[58:59], s[26:27], v58, s25, v[8:9]
	global_load_dword v58, v[58:59], off nt
	s_waitcnt vmcnt(0)
	ds_write2_b32 v52, v60, v58 offset0:8 offset1:74
	v_or_b32_e32 v58, s8, v16
	v_mad_i64_i32 v[58:59], s[26:27], v58, s25, v[8:9]
	global_load_dword v60, v[58:59], off nt
	v_or_b32_e32 v58, s8, v17
	v_mad_i64_i32 v[58:59], s[26:27], v58, s25, v[8:9]
	global_load_dword v58, v[58:59], off nt
	s_waitcnt vmcnt(0)
	ds_write2_b32 v50, v60, v58 offset1:66
	v_or_b32_e32 v58, s8, v18
	v_mad_i64_i32 v[58:59], s[26:27], v58, s25, v[8:9]
	global_load_dword v60, v[58:59], off nt
	v_or_b32_e32 v58, s8, v19
	v_mad_i64_i32 v[58:59], s[26:27], v58, s25, v[8:9]
	global_load_dword v58, v[58:59], off nt
	s_waitcnt vmcnt(0)
	ds_write2_b32 v50, v60, v58 offset0:132 offset1:198
	v_or_b32_e32 v58, s8, v20
	v_mad_i64_i32 v[58:59], s[26:27], v58, s25, v[8:9]
	global_load_dword v60, v[58:59], off nt
	v_or_b32_e32 v58, s8, v21
	v_mad_i64_i32 v[58:59], s[26:27], v58, s25, v[8:9]
	global_load_dword v58, v[58:59], off nt
	s_waitcnt vmcnt(0)
	ds_write2_b32 v53, v60, v58 offset0:8 offset1:74
	v_or_b32_e32 v58, s8, v22
	v_mad_i64_i32 v[58:59], s[26:27], v58, s25, v[8:9]
	global_load_dword v60, v[58:59], off nt
	v_or_b32_e32 v58, s8, v23
	v_mad_i64_i32 v[58:59], s[26:27], v58, s25, v[8:9]
	global_load_dword v58, v[58:59], off nt
	s_waitcnt vmcnt(0)
	ds_write2_b32 v51, v60, v58 offset1:66
	v_or_b32_e32 v58, s8, v24
	v_mad_i64_i32 v[58:59], s[26:27], v58, s25, v[8:9]
	global_load_dword v60, v[58:59], off nt
	v_or_b32_e32 v58, s8, v25
	v_mad_i64_i32 v[58:59], s[26:27], v58, s25, v[8:9]
	global_load_dword v58, v[58:59], off nt
	s_waitcnt vmcnt(0)
	ds_write2_b32 v51, v60, v58 offset0:132 offset1:198
	v_or_b32_e32 v58, s8, v26
	v_mad_i64_i32 v[58:59], s[26:27], v58, s25, v[8:9]
	global_load_dword v60, v[58:59], off nt
	v_or_b32_e32 v58, s8, v27
	v_mad_i64_i32 v[58:59], s[26:27], v58, s25, v[8:9]
	global_load_dword v58, v[58:59], off nt
	s_waitcnt vmcnt(0)
	ds_write2_b32 v54, v60, v58 offset0:8 offset1:74
	v_or_b32_e32 v58, s8, v28
	v_mad_i64_i32 v[58:59], s[26:27], v58, s25, v[8:9]
	global_load_dword v60, v[58:59], off nt
	v_or_b32_e32 v58, s8, v29
	v_mad_i64_i32 v[58:59], s[26:27], v58, s25, v[8:9]
	global_load_dword v58, v[58:59], off nt
	s_waitcnt vmcnt(0)
	ds_write2_b32 v54, v60, v58 offset0:140 offset1:206
	v_or_b32_e32 v58, s8, v30
	v_mad_i64_i32 v[58:59], s[26:27], v58, s25, v[8:9]
	global_load_dword v60, v[58:59], off nt
	v_or_b32_e32 v58, s8, v31
	v_mad_i64_i32 v[58:59], s[26:27], v58, s25, v[8:9]
	global_load_dword v58, v[58:59], off nt
	s_waitcnt vmcnt(0)
	ds_write2_b32 v57, v60, v58 offset0:16 offset1:82
	v_or_b32_e32 v58, s8, v32
	v_mad_i64_i32 v[58:59], s[26:27], v58, s25, v[8:9]
	global_load_dword v60, v[58:59], off nt
	v_or_b32_e32 v58, s8, v33
	v_mad_i64_i32 v[58:59], s[26:27], v58, s25, v[8:9]
	global_load_dword v58, v[58:59], off nt
	s_waitcnt vmcnt(0)
	ds_write2_b32 v57, v60, v58 offset0:148 offset1:214
	v_or_b32_e32 v57, s8, v34
	v_mad_i64_i32 v[58:59], s[26:27], v57, s25, v[8:9]
	global_load_dword v57, v[58:59], off nt
	v_or_b32_e32 v58, s8, v35
	v_mad_i64_i32 v[58:59], s[26:27], v58, s25, v[8:9]
	global_load_dword v58, v[58:59], off nt
	s_waitcnt vmcnt(0)
	ds_write2_b32 v56, v57, v58 offset0:24 offset1:90
	v_or_b32_e32 v57, s8, v36
	v_mad_i64_i32 v[58:59], s[26:27], v57, s25, v[8:9]
	global_load_dword v57, v[58:59], off nt
	v_or_b32_e32 v58, s8, v37
	v_mad_i64_i32 v[58:59], s[26:27], v58, s25, v[8:9]
	global_load_dword v58, v[58:59], off nt
	s_waitcnt vmcnt(0)
; #define LAS __attribute__((address_space(3)))
; __device__ __forceinline__ unsigned pk2(float lo, float hi) { return f2bf(lo) | (f2bf(hi) << 16); }
; #define LDS_WAIT() asm volatile("s_waitcnt lgkmcnt(0)" ::: "memory")
; __device__ __forceinline__ void transpose_item(const float* W, int K, int N, bf16_t* WT, int drow0, int k0, int n0, LAS float* scr, int lane) {
; #pragma unroll
;     for (int i = 0; i < 32; ++i) { const int kk = 2 * i + (lane >> 5); scr[kk * 33 + (lane & 31)] = __builtin_nontemporal_load(&W[(size_t)(k0 + kk) * N + n0 + (lane & 31)]); }
;     LDS_WAIT();
;     const int c = lane & 7;
; #pragma unroll
;     for (int j = 0; j < 4; ++j) { const int n = (lane >> 3) + 8 * j; const LAS float* s = scr + (8 * c) * 33 + n;
;         u32x4 o; o.x = pk2(s[0 * 33], s[1 * 33]); o.y = pk2(s[2 * 33], s[3 * 33]); o.z = pk2(s[4 * 33], s[5 * 33]); o.w = pk2(s[6 * 33], s[7 * 33]);
;         *(u32x4*)(WT + (size_t)(drow0 + n) * K + k0 + 8 * c) = o; }
;     LDS_WAIT();
	ds_write2_b32 v56, v57, v58 offset0:156 offset1:222
	v_or_b32_e32 v56, s8, v38
	v_mad_i64_i32 v[56:57], s[26:27], v56, s25, v[8:9]
	global_load_dword v58, v[56:57], off nt
	v_or_b32_e32 v56, s8, v39
	v_mad_i64_i32 v[56:57], s[26:27], v56, s25, v[8:9]
	global_load_dword v56, v[56:57], off nt
	s_waitcnt vmcnt(0)
	ds_write2_b32 v55, v58, v56 offset0:32 offset1:98
	v_or_b32_e32 v56, s8, v40
	v_mad_i64_i32 v[56:57], s[26:27], v56, s25, v[8:9]
	global_load_dword v56, v[56:57], off nt
	v_or_b32_e32 v57, s8, v41
	v_mad_i64_i32 v[8:9], s[26:27], v57, s25, v[8:9]
	global_load_dword v8, v[8:9], off nt
	s_waitcnt vmcnt(0)
	ds_write2_b32 v55, v56, v8 offset0:164 offset1:230
	s_waitcnt lgkmcnt(0)
	ds_read_b32 v55, v43
	ds_read_b32 v56, v43 offset:132
	v_lshl_add_u64 v[8:9], s[8:9], 1, v[6:7]
	s_waitcnt lgkmcnt(0)
	v_bfe_u32 v57, v55, 16, 1
	v_add3_u32 v55, v55, v57, s23
	v_bfe_u32 v57, v56, 16, 1
	v_lshrrev_b32_e32 v55, 16, v55
	v_add3_u32 v56, v56, v57, s23
	v_and_or_b32 v56, v56, s24, v55
	ds_read_b32 v55, v43 offset:264
	ds_read_b32 v57, v43 offset:396
	s_waitcnt lgkmcnt(1)
	v_bfe_u32 v58, v55, 16, 1
	v_add3_u32 v55, v55, v58, s23
	s_waitcnt lgkmcnt(0)
	v_bfe_u32 v58, v57, 16, 1
	v_lshrrev_b32_e32 v55, 16, v55
	v_add3_u32 v57, v57, v58, s23
	v_and_or_b32 v57, v57, s24, v55
	ds_read_b32 v55, v43 offset:528
	ds_read_b32 v58, v43 offset:660
	s_waitcnt lgkmcnt(1)
	v_bfe_u32 v59, v55, 16, 1
	v_add3_u32 v55, v55, v59, s23
	s_waitcnt lgkmcnt(0)
	v_bfe_u32 v59, v58, 16, 1
	v_lshrrev_b32_e32 v55, 16, v55
	v_add3_u32 v58, v58, v59, s23
	v_and_or_b32 v58, v58, s24, v55
	ds_read_b32 v55, v43 offset:792
	ds_read_b32 v59, v43 offset:924
	s_waitcnt lgkmcnt(1)
	v_bfe_u32 v60, v55, 16, 1
	v_add3_u32 v55, v55, v60, s23
	s_waitcnt lgkmcnt(0)
	v_bfe_u32 v60, v59, 16, 1
	v_add3_u32 v59, v59, v60, s23
	v_or_b32_e32 v60, s4, v42
	v_ashrrev_i32_e32 v61, 31, v60
	v_lshrrev_b32_e32 v55, 16, v55
	v_lshlrev_b64 v[60:61], 12, v[60:61]
	v_and_or_b32 v59, v59, s24, v55
	v_lshl_add_u64 v[60:61], v[8:9], 0, v[60:61]
	global_store_dwordx4 v[60:61], v[56:59], off
	ds_read_b32 v55, v43 offset:32
	ds_read_b32 v56, v43 offset:164
	s_waitcnt lgkmcnt(0)
	v_bfe_u32 v57, v55, 16, 1
	v_add3_u32 v55, v55, v57, s23
	v_bfe_u32 v57, v56, 16, 1
	v_lshrrev_b32_e32 v55, 16, v55
	v_add3_u32 v56, v56, v57, s23
	v_and_or_b32 v56, v56, s24, v55
	ds_read_b32 v55, v43 offset:296
	ds_read_b32 v57, v43 offset:428
	s_waitcnt lgkmcnt(0)
	v_bfe_u32 v58, v55, 16, 1
	v_add3_u32 v55, v55, v58, s23
	v_bfe_u32 v58, v57, 16, 1
	v_lshrrev_b32_e32 v55, 16, v55
	v_add3_u32 v57, v57, v58, s23
	v_and_or_b32 v57, v57, s24, v55
	ds_read_b32 v55, v43 offset:560
	ds_read_b32 v58, v43 offset:692
	s_waitcnt lgkmcnt(0)
	v_bfe_u32 v59, v55, 16, 1
	v_add3_u32 v55, v55, v59, s23
	v_bfe_u32 v59, v58, 16, 1
	v_lshrrev_b32_e32 v55, 16, v55
	v_add3_u32 v58, v58, v59, s23
	v_and_or_b32 v58, v58, s24, v55
	ds_read_b32 v55, v43 offset:824
	ds_read_b32 v59, v43 offset:956
	s_waitcnt lgkmcnt(0)
	v_bfe_u32 v60, v55, 16, 1
	v_add3_u32 v55, v55, v60, s23
	v_bfe_u32 v60, v59, 16, 1
	v_add3_u32 v59, v59, v60, s23
	v_or_b32_e32 v60, s4, v44
	v_ashrrev_i32_e32 v61, 31, v60
	v_lshrrev_b32_e32 v55, 16, v55
	v_lshlrev_b64 v[60:61], 12, v[60:61]
	v_and_or_b32 v59, v59, s24, v55
	v_lshl_add_u64 v[60:61], v[8:9], 0, v[60:61]
	global_store_dwordx4 v[60:61], v[56:59], off
	ds_read_b32 v55, v43 offset:64
	ds_read_b32 v56, v43 offset:196
	s_waitcnt lgkmcnt(0)
	v_bfe_u32 v57, v55, 16, 1
	v_add3_u32 v55, v55, v57, s23
	v_bfe_u32 v57, v56, 16, 1
	v_lshrrev_b32_e32 v55, 16, v55
	v_add3_u32 v56, v56, v57, s23
	v_and_or_b32 v56, v56, s24, v55
	ds_read_b32 v55, v43 offset:328
	ds_read_b32 v57, v43 offset:460
	s_waitcnt lgkmcnt(0)
	v_bfe_u32 v58, v55, 16, 1
	v_add3_u32 v55, v55, v58, s23
	v_bfe_u32 v58, v57, 16, 1
	v_lshrrev_b32_e32 v55, 16, v55
	v_add3_u32 v57, v57, v58, s23
	v_and_or_b32 v57, v57, s24, v55
	ds_read_b32 v55, v43 offset:592
	ds_read_b32 v58, v43 offset:724
	s_waitcnt lgkmcnt(0)
	v_bfe_u32 v59, v55, 16, 1
	v_add3_u32 v55, v55, v59, s23
	v_bfe_u32 v59, v58, 16, 1
	v_lshrrev_b32_e32 v55, 16, v55
	v_add3_u32 v58, v58, v59, s23
	v_and_or_b32 v58, v58, s24, v55
	ds_read_b32 v55, v43 offset:856
	ds_read_b32 v59, v43 offset:988
	s_waitcnt lgkmcnt(0)
	v_bfe_u32 v60, v55, 16, 1
	v_add3_u32 v55, v55, v60, s23
	v_bfe_u32 v60, v59, 16, 1
	v_add3_u32 v59, v59, v60, s23
	v_or_b32_e32 v60, s4, v45
	v_ashrrev_i32_e32 v61, 31, v60
	v_lshrrev_b32_e32 v55, 16, v55
	v_lshlrev_b64 v[60:61], 12, v[60:61]
	v_and_or_b32 v59, v59, s24, v55
	v_lshl_add_u64 v[60:61], v[8:9], 0, v[60:61]
	global_store_dwordx4 v[60:61], v[56:59], off
	ds_read_b32 v55, v43 offset:96
	ds_read_b32 v56, v43 offset:228
	s_waitcnt lgkmcnt(0)
	v_bfe_u32 v57, v55, 16, 1
	v_add3_u32 v55, v55, v57, s23
	v_bfe_u32 v57, v56, 16, 1
	v_lshrrev_b32_e32 v55, 16, v55
	v_add3_u32 v56, v56, v57, s23
	v_and_or_b32 v56, v56, s24, v55
	ds_read_b32 v55, v43 offset:360
	ds_read_b32 v57, v43 offset:492
	s_waitcnt lgkmcnt(0)
	v_bfe_u32 v58, v55, 16, 1
	v_add3_u32 v55, v55, v58, s23
	v_bfe_u32 v58, v57, 16, 1
	v_lshrrev_b32_e32 v55, 16, v55
	v_add3_u32 v57, v57, v58, s23
	v_and_or_b32 v57, v57, s24, v55
	ds_read_b32 v55, v43 offset:624
	ds_read_b32 v58, v43 offset:756
	s_waitcnt lgkmcnt(0)
	v_bfe_u32 v59, v55, 16, 1
	v_add3_u32 v55, v55, v59, s23
	v_bfe_u32 v59, v58, 16, 1
	v_lshrrev_b32_e32 v55, 16, v55
	v_add3_u32 v58, v58, v59, s23
	v_and_or_b32 v58, v58, s24, v55
	ds_read_b32 v55, v43 offset:888
	ds_read_b32 v59, v43 offset:1020
	s_waitcnt lgkmcnt(0)
	v_bfe_u32 v60, v55, 16, 1
	v_add3_u32 v55, v55, v60, s23
	v_bfe_u32 v60, v59, 16, 1
	v_add3_u32 v59, v59, v60, s23
	v_or_b32_e32 v60, s4, v46
	v_ashrrev_i32_e32 v61, 31, v60
	v_lshrrev_b32_e32 v55, 16, v55
	v_lshlrev_b64 v[60:61], 12, v[60:61]
	v_and_or_b32 v59, v59, s24, v55
	v_lshl_add_u64 v[8:9], v[8:9], 0, v[60:61]
	global_store_dwordx4 v[8:9], v[56:59], off
	s_waitcnt lgkmcnt(0)
	s_branch .LBB0_1606

; template <int MODE>
; __device__ __forceinline__ void row_finish(const Params& p, int r, int lane, const float* gpost, const float* gnext, bf16_t* U, float coef, f32x4 (&h)[8], const u32x2 (&dw)[8]) {
;     ...
;     if (MODE >= 1) {
;         f32x4 d[8]; float ss = 0.f;
; #pragma unroll
;         for (int j = 0; j < 8; ++j) { const u32x2 w = dw[j]; d[j] = (f32x4){bflo(w.x), bfhi(w.x), bflo(w.y), bfhi(w.y)};
;             ss += (d[j].x * d[j].x + d[j].y * d[j].y) + (d[j].z * d[j].z + d[j].w * d[j].w); }
;         ss = wave_sum(ss);
;         const float rs = rsqrtf(ss * (1.f / DM) + EPS) * coef;
;         f32x4* hd = (f32x4*)hrow(p, r);
; #pragma unroll
;         for (int j = 0; j < 8; ++j) { const f32x4 g = ((const f32x4*)gpost)[lane + 64 * j]; h[j] = h[j] + d[j] * g * rs; __builtin_nontemporal_store(h[j], &hd[lane + 64 * j]); }
.LBB0_1626:
	s_andn2_b64 vcc, exec, s[24:25]
	v_mov_b32_e32 v95, v202
	v_mov_b32_e32 v94, v201
	v_mov_b32_e32 v93, v200
	v_mov_b32_e32 v92, v199
	v_mov_b32_e32 v91, v198
	v_mov_b32_e32 v90, v197
	v_mov_b32_e32 v89, v196
	v_mov_b32_e32 v88, v195
	v_mov_b32_e32 v87, v194
	v_mov_b32_e32 v86, v193
	v_mov_b32_e32 v85, v192
	v_mov_b32_e32 v84, v191
	v_mov_b32_e32 v83, v190
	v_mov_b32_e32 v82, v189
	v_mov_b32_e32 v81, v188
	v_mov_b32_e32 v80, v187
	v_mov_b32_e32 v79, v186
	v_mov_b32_e32 v78, v185
	v_mov_b32_e32 v77, v184
	v_mov_b32_e32 v76, v183
	v_mov_b32_e32 v75, v182
	v_mov_b32_e32 v74, v181
	v_mov_b32_e32 v73, v180
	v_mov_b32_e32 v72, v179
	v_mov_b32_e32 v71, v178
	v_mov_b32_e32 v70, v177
	v_mov_b32_e32 v69, v176
	v_mov_b32_e32 v68, v175
	v_mov_b32_e32 v67, v174
	v_mov_b32_e32 v66, v173
	v_mov_b32_e32 v65, v172
	v_mov_b32_e32 v64, v171
	s_cbranch_vccnz .LBB0_1628
	s_waitcnt lgkmcnt(0)
	v_and_b32_e32 v167, 0xffff0000, v148
	v_and_b32_e32 v166, 0xffff0000, v150
	v_and_b32_e32 v169, 0xffff0000, v149
	v_and_b32_e32 v168, 0xffff0000, v151
	v_lshlrev_b32_e32 v71, 16, v148
	v_lshlrev_b32_e32 v70, 16, v150
	v_lshlrev_b32_e32 v69, 16, v149
	v_lshlrev_b32_e32 v68, 16, v151
	v_pk_mul_f32 v[64:65], v[166:167], v[166:167]
	v_pk_mul_f32 v[66:67], v[168:169], v[168:169]
	v_pk_fma_f32 v[64:65], v[70:71], v[70:71], v[64:65]
	v_pk_fma_f32 v[66:67], v[68:69], v[68:69], v[66:67]
	v_and_b32_e32 v73, 0xffff0000, v153
	v_pk_add_f32 v[64:65], v[64:65], v[66:67]
	v_and_b32_e32 v72, 0xffff0000, v152
	v_pk_add_f32 v[64:65], v[64:65], v[64:65] op_sel_hi:[0,1]
	v_lshlrev_b32_e32 v75, 16, v153
	v_lshlrev_b32_e32 v74, 16, v152
	v_pk_mul_f32 v[66:67], v[72:73], v[72:73]
	v_lshlrev_b32_e32 v76, 16, v154
	v_and_b32_e32 v77, 0xffff0000, v154
	v_lshlrev_b32_e32 v78, 16, v155
	v_lshlrev_b32_e32 v80, 16, v156
	v_pk_fma_f32 v[66:67], v[74:75], v[74:75], v[66:67]
	v_mul_f32_e32 v81, v76, v76
	v_mul_f32_e32 v85, v77, v77
	v_and_b32_e32 v79, 0xffff0000, v155
	v_mul_f32_e32 v64, v78, v78
	v_mov_b32_e32 v84, v80
	v_pk_add_f32 v[66:67], v[66:67], v[66:67] op_sel_hi:[0,1]
	v_pk_fma_f32 v[86:87], v[78:79], v[78:79], v[64:65] op_sel_hi:[1,1,0]
	v_and_b32_e32 v204, 0xffff0000, v156
	v_lshlrev_b32_e32 v82, 16, v157
	v_and_b32_e32 v83, 0xffff0000, v157
	v_pk_add_f32 v[84:85], v[80:81], v[84:85]
	v_mul_f32_e32 v86, v204, v204
	v_mul_f32_e32 v66, v82, v82
	v_mul_f32_e32 v64, v83, v83
	v_mul_f32_e32 v88, v80, v80
	v_mov_b32_e32 v89, v85
	v_pk_add_f32 v[84:85], v[88:89], v[86:87]
	v_pk_add_f32 v[64:65], v[66:67], v[64:65]
	v_and_b32_e32 v87, 0xffff0000, v159
	v_pk_add_f32 v[64:65], v[84:85], v[64:65]
	v_and_b32_e32 v86, 0xffff0000, v158
	v_pk_add_f32 v[64:65], v[64:65], v[64:65] op_sel_hi:[0,1]
	v_lshlrev_b32_e32 v85, 16, v159
	v_lshlrev_b32_e32 v84, 16, v158
	v_pk_mul_f32 v[66:67], v[86:87], v[86:87]
	v_lshlrev_b32_e32 v88, 16, v160
	v_and_b32_e32 v89, 0xffff0000, v160
	v_lshlrev_b32_e32 v90, 16, v161
	v_lshlrev_b32_e32 v92, 16, v162
	v_pk_fma_f32 v[66:67], v[84:85], v[84:85], v[66:67]
	v_mul_f32_e32 v93, v88, v88
	v_mul_f32_e32 v207, v89, v89
	v_and_b32_e32 v91, 0xffff0000, v161
	v_mul_f32_e32 v64, v90, v90
	v_mov_b32_e32 v206, v92
	v_pk_add_f32 v[66:67], v[66:67], v[66:67] op_sel_hi:[0,1]
	v_pk_fma_f32 v[208:209], v[90:91], v[90:91], v[64:65] op_sel_hi:[1,1,0]
	v_and_b32_e32 v203, 0xffff0000, v162
	v_lshlrev_b32_e32 v94, 16, v163
	v_and_b32_e32 v95, 0xffff0000, v163
	v_pk_add_f32 v[206:207], v[92:93], v[206:207]
	v_mul_f32_e32 v208, v203, v203
	v_mul_f32_e32 v66, v94, v94
	v_mul_f32_e32 v64, v95, v95
	v_mul_f32_e32 v210, v92, v92
	v_mov_b32_e32 v211, v207
	v_pk_add_f32 v[206:207], v[210:211], v[208:209]
	v_pk_add_f32 v[64:65], v[66:67], v[64:65]
	s_ashr_i32 s7, s6, 31
	v_pk_add_f32 v[64:65], v[206:207], v[64:65]
	v_mov_b32_e32 v206, v71
	v_add_f32_e32 v64, v64, v65
	ds_bpermute_b32 v65, v97, v64
	v_mov_b32_e32 v207, v167
	s_lshl_b64 s[24:25], s[6:7], 13
	s_add_u32 s24, s14, s24
	s_addc_u32 s25, s15, s25
	s_waitcnt lgkmcnt(0)
	v_add_f32_e32 v64, v64, v65
	ds_bpermute_b32 v65, v99, v64
	v_lshlrev_b32_e32 v81, 4, v96
	v_mov_b32_e32 v71, v166
	v_mov_b32_e32 v93, v203
	s_waitcnt lgkmcnt(0)
	v_add_f32_e32 v64, v64, v65
	ds_bpermute_b32 v65, v101, v64
	s_waitcnt lgkmcnt(0)
	v_add_f32_e32 v64, v64, v65
	ds_bpermute_b32 v65, v103, v64
	s_waitcnt lgkmcnt(0)
	v_add_f32_e32 v64, v64, v65
	ds_bpermute_b32 v65, v105, v64
	s_waitcnt lgkmcnt(0)
	v_add_f32_e32 v64, v64, v65
	ds_bpermute_b32 v65, v165, v64
	s_waitcnt lgkmcnt(0)
	v_add_f32_e32 v64, v64, v65
	v_fmamk_f32 v64, v64, 0x3a000000, v170
	v_cmp_gt_f32_e32 vcc, s23, v64
	v_mul_f32_e32 v65, 0x4b800000, v64
	s_nop 0
	v_cndmask_b32_e32 v64, v64, v65, vcc
	v_rsq_f32_e32 v64, v64
	s_nop 0
	v_mul_f32_e32 v65, 0x45800000, v64
	v_cndmask_b32_e32 v164, v64, v65, vcc
	global_load_dwordx4 v[64:67], v[106:107], off
	s_waitcnt vmcnt(0)
	v_pk_mul_f32 v[64:65], v[206:207], v[64:65]
	v_mov_b32_e32 v206, v69
	v_mov_b32_e32 v207, v169
	v_pk_mul_f32 v[66:67], v[206:207], v[66:67]
	v_pk_fma_f32 v[64:65], v[64:65], v[164:165], v[44:45] op_sel_hi:[1,0,1]
	v_pk_fma_f32 v[66:67], v[66:67], v[164:165], v[46:47] op_sel_hi:[1,0,1]
	global_store_dwordx4 v81, v[64:67], s[24:25] nt
	global_load_dwordx4 v[44:47], v[106:107], off offset:1024
	v_mov_b32_e32 v69, v168
	s_waitcnt vmcnt(0)
	v_pk_mul_f32 v[44:45], v[70:71], v[44:45]
	v_pk_mul_f32 v[46:47], v[68:69], v[46:47]
	v_pk_fma_f32 v[68:69], v[44:45], v[164:165], v[60:61] op_sel_hi:[1,0,1]
	v_pk_fma_f32 v[70:71], v[46:47], v[164:165], v[62:63] op_sel_hi:[1,0,1]
	global_store_dwordx4 v81, v[68:71], s[24:25] offset:1024 nt
	global_load_dwordx4 v[44:47], v[106:107], off offset:2048
	v_mov_b32_e32 v60, v74
	v_mov_b32_e32 v61, v72
	v_mov_b32_e32 v72, v75
	s_waitcnt vmcnt(0)
; template <int MODE>
; __device__ __forceinline__ void row_finish(const Params& p, int r, int lane, const float* gpost, const float* gnext, bf16_t* U, float coef, f32x4 (&h)[8], const u32x2 (&dw)[8]) {
;     ...
;         for (int j = 0; j < 8; ++j) { const f32x4 g = ((const f32x4*)gpost)[lane + 64 * j]; h[j] = h[j] + d[j] * g * rs; __builtin_nontemporal_store(h[j], &hd[lane + 64 * j]); }
;     }
;     if (MODE != 3) {
;         float s2 = 0.f;
; #pragma unroll
;         for (int j = 0; j < 8; ++j) s2 += (h[j].x * h[j].x + h[j].y * h[j].y) + (h[j].z * h[j].z + h[j].w * h[j].w);
;         s2 = wave_sum(s2);
;         const float rs2 = rsqrtf(s2 * (1.f / DM) + EPS);
	v_pk_mul_f32 v[44:45], v[44:45], v[60:61]
	v_pk_mul_f32 v[46:47], v[46:47], v[72:73]
	v_pk_fma_f32 v[72:73], v[44:45], v[164:165], v[56:57] op_sel_hi:[1,0,1]
	v_pk_fma_f32 v[74:75], v[46:47], v[164:165], v[58:59] op_sel_hi:[1,0,1]
	global_store_dwordx4 v81, v[72:75], s[24:25] offset:2048 nt
	global_load_dwordx4 v[44:47], v[106:107], off offset:3072
	s_waitcnt vmcnt(0)
	v_pk_mul_f32 v[46:47], v[78:79], v[46:47]
	v_pk_mul_f32 v[44:45], v[76:77], v[44:45]
	v_pk_fma_f32 v[78:79], v[46:47], v[164:165], v[54:55] op_sel_hi:[1,0,1]
	v_pk_fma_f32 v[76:77], v[44:45], v[164:165], v[52:53] op_sel_hi:[1,0,1]
	global_store_dwordx4 v81, v[76:79], s[24:25] offset:3072 nt
	global_load_dwordx4 v[44:47], v[108:109], off
	v_mov_b32_e32 v81, v204
	s_waitcnt vmcnt(0)
	v_pk_mul_f32 v[44:45], v[80:81], v[44:45]
	v_pk_mul_f32 v[46:47], v[82:83], v[46:47]
	v_pk_fma_f32 v[80:81], v[44:45], v[164:165], v[48:49] op_sel_hi:[1,0,1]
	v_pk_fma_f32 v[82:83], v[46:47], v[164:165], v[50:51] op_sel_hi:[1,0,1]
	v_lshlrev_b32_e32 v44, 4, v98
	global_store_dwordx4 v44, v[80:83], s[24:25] nt
	global_load_dwordx4 v[44:47], v[110:111], off
	v_mov_b32_e32 v48, v84
	v_mov_b32_e32 v49, v86
	v_mov_b32_e32 v86, v85
	s_waitcnt vmcnt(0)
	v_pk_mul_f32 v[44:45], v[44:45], v[48:49]
	v_pk_mul_f32 v[46:47], v[46:47], v[86:87]
	v_pk_fma_f32 v[84:85], v[164:165], v[44:45], v[40:41] op_sel_hi:[0,1,1]
	v_pk_fma_f32 v[86:87], v[164:165], v[46:47], v[42:43] op_sel_hi:[0,1,1]
	v_lshlrev_b32_e32 v40, 4, v100
	global_store_dwordx4 v40, v[84:87], s[24:25] nt
	global_load_dwordx4 v[40:43], v[112:113], off
	s_waitcnt vmcnt(0)
	v_pk_mul_f32 v[42:43], v[90:91], v[42:43]
	v_pk_mul_f32 v[40:41], v[88:89], v[40:41]
	v_pk_fma_f32 v[90:91], v[164:165], v[42:43], v[38:39] op_sel_hi:[0,1,1]
	v_pk_fma_f32 v[88:89], v[164:165], v[40:41], v[36:37] op_sel_hi:[0,1,1]
	v_lshlrev_b32_e32 v36, 4, v102
	global_store_dwordx4 v36, v[88:91], s[24:25] nt
	global_load_dwordx4 v[36:39], v[114:115], off
	s_waitcnt vmcnt(0)
	v_pk_mul_f32 v[36:37], v[92:93], v[36:37]
	v_pk_mul_f32 v[38:39], v[94:95], v[38:39]
	v_pk_fma_f32 v[92:93], v[164:165], v[36:37], v[32:33] op_sel_hi:[0,1,1]
	v_pk_fma_f32 v[94:95], v[164:165], v[38:39], v[34:35] op_sel_hi:[0,1,1]
	v_lshlrev_b32_e32 v32, 4, v104
	v_mov_b32_e32 v34, v65
	v_mov_b32_e32 v35, v69
	global_store_dwordx4 v32, v[92:95], s[24:25] nt
	v_mov_b32_e32 v32, v64
	v_mov_b32_e32 v33, v68
	v_pk_mul_f32 v[34:35], v[34:35], v[34:35]
	v_mov_b32_e32 v36, v67
	v_mov_b32_e32 v37, v71
	v_pk_fma_f32 v[32:33], v[32:33], v[32:33], v[34:35]
	v_mov_b32_e32 v34, v66
	v_mov_b32_e32 v35, v70
	v_pk_mul_f32 v[36:37], v[36:37], v[36:37]
	s_lshl_b64 s[24:25], s[6:7], 12
	v_pk_fma_f32 v[34:35], v[34:35], v[34:35], v[36:37]
	v_pk_mul_f32 v[36:37], v[74:75], v[74:75]
	v_pk_add_f32 v[32:33], v[32:33], v[34:35]
	v_pk_mul_f32 v[34:35], v[72:73], v[72:73]
	v_pk_add_f32 v[32:33], v[32:33], v[32:33] op_sel_hi:[0,1]
	v_pk_mov_b32 v[38:39], v[34:35], v[36:37] op_sel:[1,0]
	v_mov_b32_e32 v35, v37
	v_mul_f32_e32 v32, v76, v76
	v_pk_add_f32 v[34:35], v[38:39], v[34:35]
	v_pk_fma_f32 v[36:37], v[76:77], v[76:77], v[32:33] op_sel_hi:[1,1,0]
	v_mul_f32_e32 v32, v78, v78
	v_pk_add_f32 v[34:35], v[34:35], v[34:35] op_sel_hi:[0,1]
	v_pk_fma_f32 v[38:39], v[78:79], v[78:79], v[32:33] op_sel_hi:[1,1,0]
	v_mul_f32_e32 v36, v80, v80
	v_mul_f32_e32 v38, v81, v81
	v_mul_f32_e32 v34, v82, v82
	v_mul_f32_e32 v32, v83, v83
	v_pk_add_f32 v[36:37], v[36:37], v[38:39]
	v_pk_add_f32 v[32:33], v[34:35], v[32:33]
	v_pk_mul_f32 v[34:35], v[84:85], v[84:85]
	v_pk_add_f32 v[32:33], v[36:37], v[32:33]
	v_pk_mul_f32 v[36:37], v[86:87], v[86:87]
	v_pk_add_f32 v[32:33], v[32:33], v[32:33] op_sel_hi:[0,1]
	v_pk_mov_b32 v[38:39], v[34:35], v[36:37] op_sel:[1,0]
	v_mov_b32_e32 v35, v37
	v_mul_f32_e32 v32, v88, v88
	v_pk_add_f32 v[34:35], v[38:39], v[34:35]
	v_pk_fma_f32 v[36:37], v[88:89], v[88:89], v[32:33] op_sel_hi:[1,1,0]
	v_mul_f32_e32 v32, v90, v90
	v_pk_add_f32 v[34:35], v[34:35], v[34:35] op_sel_hi:[0,1]
	v_pk_fma_f32 v[38:39], v[90:91], v[90:91], v[32:33] op_sel_hi:[1,1,0]
	v_mul_f32_e32 v36, v92, v92
	v_mul_f32_e32 v38, v93, v93
	v_mul_f32_e32 v34, v94, v94
	v_mul_f32_e32 v32, v95, v95
	v_pk_add_f32 v[36:37], v[36:37], v[38:39]
	v_pk_add_f32 v[32:33], v[34:35], v[32:33]
	s_nop 0
	v_pk_add_f32 v[32:33], v[36:37], v[32:33]
	global_load_dwordx4 v[34:37], v[116:117], off
	v_add_f32_e32 v32, v32, v33
	ds_bpermute_b32 v33, v97, v32
	s_waitcnt lgkmcnt(0)
	v_add_f32_e32 v32, v32, v33
	ds_bpermute_b32 v33, v99, v32
	s_waitcnt lgkmcnt(0)
	v_add_f32_e32 v32, v32, v33
	ds_bpermute_b32 v33, v101, v32
	s_waitcnt lgkmcnt(0)
	v_add_f32_e32 v32, v32, v33
	ds_bpermute_b32 v33, v103, v32
	s_waitcnt lgkmcnt(0)
	v_add_f32_e32 v32, v32, v33
	ds_bpermute_b32 v33, v105, v32
	s_waitcnt lgkmcnt(0)
	v_add_f32_e32 v32, v32, v33
	ds_bpermute_b32 v33, v165, v32
	s_waitcnt lgkmcnt(0)
	v_add_f32_e32 v32, v32, v33
	v_fmamk_f32 v32, v32, 0x3a000000, v170
	v_cmp_gt_f32_e32 vcc, s23, v32
	v_mul_f32_e32 v33, 0x4b800000, v32
	s_waitcnt vmcnt(0)
; __device__ __forceinline__ unsigned pk2(float lo, float hi) { return f2bf(lo) | (f2bf(hi) << 16); }
; template <int MODE>
; __device__ __forceinline__ void row_finish(const Params& p, int r, int lane, const float* gpost, const float* gnext, bf16_t* U, float coef, f32x4 (&h)[8], const u32x2 (&dw)[8]) {
;     ...
;         u32x2* up = (u32x2*)(U + (size_t)r * DM);
; #pragma unroll
;         for (int j = 0; j < 8; ++j) { const f32x4 g = ((const f32x4*)gnext)[lane + 64 * j]; const f32x4 v = h[j] * g * rs2;
;             u32x2 w; w.x = pk2(v.x, v.y); w.y = pk2(v.z, v.w); up[lane + 64 * j] = w; }
;     }
	v_pk_mul_f32 v[34:35], v[64:65], v[34:35]
	v_cndmask_b32_e32 v32, v32, v33, vcc
	v_rsq_f32_e32 v32, v32
	v_pk_mul_f32 v[36:37], v[66:67], v[36:37]
	v_mul_f32_e32 v33, 0x45800000, v32
	v_cndmask_b32_e32 v32, v32, v33, vcc
	v_pk_mul_f32 v[34:35], v[34:35], v[32:33] op_sel_hi:[1,0]
	v_pk_mul_f32 v[38:39], v[36:37], v[32:33] op_sel_hi:[1,0]
	v_bfe_u32 v33, v34, 16, 1
	v_add3_u32 v33, v34, v33, s20
	v_bfe_u32 v34, v35, 16, 1
	v_lshrrev_b32_e32 v33, 16, v33
	v_add3_u32 v34, v35, v34, s20
	v_and_or_b32 v36, v34, s21, v33
	v_bfe_u32 v33, v38, 16, 1
	v_add3_u32 v33, v38, v33, s20
	v_bfe_u32 v34, v39, 16, 1
	v_lshrrev_b32_e32 v33, 16, v33
	v_add3_u32 v34, v39, v34, s20
	v_and_or_b32 v37, v34, s21, v33
	v_lshl_add_u64 v[34:35], v[130:131], 0, s[24:25]
	global_store_dwordx2 v[34:35], v[36:37], off
	global_load_dwordx4 v[36:39], v[116:117], off offset:1024
	s_waitcnt vmcnt(0)
	v_pk_mul_f32 v[36:37], v[68:69], v[36:37]
	v_pk_mul_f32 v[38:39], v[70:71], v[38:39]
	v_pk_mul_f32 v[36:37], v[36:37], v[32:33] op_sel_hi:[1,0]
	v_pk_mul_f32 v[38:39], v[38:39], v[32:33] op_sel_hi:[1,0]
	v_bfe_u32 v33, v36, 16, 1
	v_add3_u32 v33, v36, v33, s20
	v_bfe_u32 v36, v37, 16, 1
	v_lshrrev_b32_e32 v33, 16, v33
	v_add3_u32 v36, v37, v36, s20
	v_and_or_b32 v36, v36, s21, v33
	v_bfe_u32 v33, v38, 16, 1
	v_add3_u32 v33, v38, v33, s20
	v_bfe_u32 v37, v39, 16, 1
	v_lshrrev_b32_e32 v33, 16, v33
	v_add3_u32 v37, v39, v37, s20
	v_and_or_b32 v37, v37, s21, v33
	global_store_dwordx2 v[34:35], v[36:37], off offset:512
	global_load_dwordx4 v[36:39], v[116:117], off offset:2048
	s_waitcnt vmcnt(0)
	v_pk_mul_f32 v[36:37], v[72:73], v[36:37]
	v_pk_mul_f32 v[38:39], v[74:75], v[38:39]
	v_pk_mul_f32 v[36:37], v[36:37], v[32:33] op_sel_hi:[1,0]
	v_pk_mul_f32 v[38:39], v[38:39], v[32:33] op_sel_hi:[1,0]
	v_bfe_u32 v33, v36, 16, 1
	v_add3_u32 v33, v36, v33, s20
	v_bfe_u32 v36, v37, 16, 1
	v_lshrrev_b32_e32 v33, 16, v33
	v_add3_u32 v36, v37, v36, s20
	v_and_or_b32 v36, v36, s21, v33
	v_bfe_u32 v33, v38, 16, 1
	v_add3_u32 v33, v38, v33, s20
	v_bfe_u32 v37, v39, 16, 1
	v_lshrrev_b32_e32 v33, 16, v33
	v_add3_u32 v37, v39, v37, s20
	v_and_or_b32 v37, v37, s21, v33
	global_store_dwordx2 v[34:35], v[36:37], off offset:1024
	global_load_dwordx4 v[36:39], v[116:117], off offset:3072
	s_waitcnt vmcnt(0)
	v_pk_mul_f32 v[36:37], v[76:77], v[36:37]
	v_pk_mul_f32 v[38:39], v[78:79], v[38:39]
	v_pk_mul_f32 v[36:37], v[36:37], v[32:33] op_sel_hi:[1,0]
	v_pk_mul_f32 v[38:39], v[38:39], v[32:33] op_sel_hi:[1,0]
	v_bfe_u32 v33, v36, 16, 1
	v_add3_u32 v33, v36, v33, s20
	v_bfe_u32 v36, v37, 16, 1
	v_lshrrev_b32_e32 v33, 16, v33
	v_add3_u32 v36, v37, v36, s20
	v_and_or_b32 v36, v36, s21, v33
	v_bfe_u32 v33, v38, 16, 1
	v_add3_u32 v33, v38, v33, s20
	v_bfe_u32 v37, v39, 16, 1
	v_lshrrev_b32_e32 v33, 16, v33
	v_add3_u32 v37, v39, v37, s20
	v_and_or_b32 v37, v37, s21, v33
	global_store_dwordx2 v[34:35], v[36:37], off offset:1536
	global_load_dwordx4 v[36:39], v[118:119], off
	s_waitcnt vmcnt(0)
	v_pk_mul_f32 v[36:37], v[80:81], v[36:37]
	v_pk_mul_f32 v[38:39], v[82:83], v[38:39]
	v_pk_mul_f32 v[36:37], v[36:37], v[32:33] op_sel_hi:[1,0]
	v_pk_mul_f32 v[38:39], v[38:39], v[32:33] op_sel_hi:[1,0]
	v_bfe_u32 v33, v36, 16, 1
	v_add3_u32 v33, v36, v33, s20
	v_bfe_u32 v36, v37, 16, 1
	v_lshrrev_b32_e32 v33, 16, v33
	v_add3_u32 v36, v37, v36, s20
	v_and_or_b32 v36, v36, s21, v33
	v_bfe_u32 v33, v38, 16, 1
	v_add3_u32 v33, v38, v33, s20
	v_bfe_u32 v37, v39, 16, 1
	v_lshrrev_b32_e32 v33, 16, v33
	v_add3_u32 v37, v39, v37, s20
	v_and_or_b32 v37, v37, s21, v33
	global_store_dwordx2 v[34:35], v[36:37], off offset:2048
	global_load_dwordx4 v[36:39], v[120:121], off
	s_waitcnt vmcnt(0)
	v_pk_mul_f32 v[36:37], v[84:85], v[36:37]
	v_pk_mul_f32 v[38:39], v[86:87], v[38:39]
	v_pk_mul_f32 v[36:37], v[36:37], v[32:33] op_sel_hi:[1,0]
	v_pk_mul_f32 v[38:39], v[38:39], v[32:33] op_sel_hi:[1,0]
	v_bfe_u32 v33, v36, 16, 1
	v_add3_u32 v33, v36, v33, s20
	v_bfe_u32 v36, v37, 16, 1
	v_lshrrev_b32_e32 v33, 16, v33
	v_add3_u32 v36, v37, v36, s20
	v_and_or_b32 v36, v36, s21, v33
	v_bfe_u32 v33, v38, 16, 1
	v_add3_u32 v33, v38, v33, s20
	v_bfe_u32 v37, v39, 16, 1
	v_lshrrev_b32_e32 v33, 16, v33
	v_add3_u32 v37, v39, v37, s20
	v_and_or_b32 v37, v37, s21, v33
	global_store_dwordx2 v[34:35], v[36:37], off offset:2560
	global_load_dwordx4 v[36:39], v[122:123], off
	s_waitcnt vmcnt(0)
	v_pk_mul_f32 v[36:37], v[88:89], v[36:37]
	v_pk_mul_f32 v[38:39], v[90:91], v[38:39]
	v_pk_mul_f32 v[36:37], v[36:37], v[32:33] op_sel_hi:[1,0]
	v_pk_mul_f32 v[38:39], v[38:39], v[32:33] op_sel_hi:[1,0]
	v_bfe_u32 v33, v36, 16, 1
	v_add3_u32 v33, v36, v33, s20
	v_bfe_u32 v36, v37, 16, 1
	v_lshrrev_b32_e32 v33, 16, v33
	v_add3_u32 v36, v37, v36, s20
	v_and_or_b32 v36, v36, s21, v33
	v_bfe_u32 v33, v38, 16, 1
	v_add3_u32 v33, v38, v33, s20
	v_bfe_u32 v37, v39, 16, 1
	v_lshrrev_b32_e32 v33, 16, v33
	v_add3_u32 v37, v39, v37, s20
	v_and_or_b32 v37, v37, s21, v33
	global_store_dwordx2 v[34:35], v[36:37], off offset:3072
	global_load_dwordx4 v[36:39], v[124:125], off
	s_waitcnt vmcnt(0)
	v_pk_mul_f32 v[36:37], v[92:93], v[36:37]
	v_pk_mul_f32 v[38:39], v[94:95], v[38:39]
	s_nop 0
	v_pk_mul_f32 v[38:39], v[38:39], v[32:33] op_sel_hi:[1,0]
	v_pk_mul_f32 v[32:33], v[36:37], v[32:33] op_sel_hi:[1,0]
	s_nop 0
	v_bfe_u32 v36, v32, 16, 1
	v_add3_u32 v32, v32, v36, s20
	v_bfe_u32 v36, v33, 16, 1
	v_lshrrev_b32_e32 v32, 16, v32
	v_add3_u32 v33, v33, v36, s20
	v_and_or_b32 v32, v33, s21, v32
	v_bfe_u32 v33, v38, 16, 1
	v_add3_u32 v33, v38, v33, s20
	v_bfe_u32 v36, v39, 16, 1
	v_lshrrev_b32_e32 v33, 16, v33
	v_add3_u32 v36, v39, v36, s20
	v_and_or_b32 v33, v36, s21, v33
	global_store_dwordx2 v[34:35], v[32:33], off offset:3584

; template <int MODE>
; __device__ __forceinline__ void row_finish(const Params& p, int r, int lane, const float* gpost, const float* gnext, bf16_t* U, float coef, f32x4 (&h)[8], const u32x2 (&dw)[8]) {
;     if (r >= ROWSP) return;
;     if (r >= ROWS) { if (MODE != 3) { u32x4* up = (u32x4*)(U + (size_t)r * DM);
; #pragma unroll
;             for (int j = 0; j < 4; ++j) up[lane + 64 * j] = (u32x4){0u, 0u, 0u, 0u}; } return; }
;     if (MODE >= 2 && r >= NTOKR) return;
;     if (MODE >= 1) {
;         f32x4 d[8]; float ss = 0.f;
; #pragma unroll
;         for (int j = 0; j < 8; ++j) { const u32x2 w = dw[j]; d[j] = (f32x4){bflo(w.x), bfhi(w.x), bflo(w.y), bfhi(w.y)};
;             ss += (d[j].x * d[j].x + d[j].y * d[j].y) + (d[j].z * d[j].z + d[j].w * d[j].w); }
;         ss = wave_sum(ss);
;         const float rs = rsqrtf(ss * (1.f / DM) + EPS) * coef;
;         f32x4* hd = (f32x4*)hrow(p, r);
; #pragma unroll
;         for (int j = 0; j < 8; ++j) { const f32x4 g = ((const f32x4*)gpost)[lane + 64 * j]; h[j] = h[j] + d[j] * g * rs; __builtin_nontemporal_store(h[j], &hd[lane + 64 * j]); }
.LBB0_1629:
	s_mov_b32 s7, s4
	s_lshl_b64 s[6:7], s[6:7], 12
	v_lshl_add_u64 v[32:33], v[126:127], 0, s[6:7]
	s_mov_b32 s6, s4
	s_mov_b32 s7, s4
	s_mov_b32 s5, s4
	v_mov_b64_e32 v[36:37], s[6:7]
	v_mov_b64_e32 v[34:35], s[4:5]
	global_store_dwordx4 v[32:33], v[34:37], off
	global_store_dwordx4 v[32:33], v[34:37], off offset:1024
	global_store_dwordx4 v[32:33], v[34:37], off offset:2048
	global_store_dwordx4 v[32:33], v[34:37], off offset:3072
	v_mov_b32_e32 v44, v171
	v_mov_b32_e32 v45, v172
	v_mov_b32_e32 v46, v173
	v_mov_b32_e32 v47, v174
	v_mov_b32_e32 v60, v175
	v_mov_b32_e32 v61, v176
	v_mov_b32_e32 v62, v177
	v_mov_b32_e32 v63, v178
	v_mov_b32_e32 v56, v179
	v_mov_b32_e32 v57, v180
	v_mov_b32_e32 v58, v181
	v_mov_b32_e32 v59, v182
	v_mov_b32_e32 v52, v183
	v_mov_b32_e32 v53, v184
	v_mov_b32_e32 v54, v185
	v_mov_b32_e32 v55, v186
	v_mov_b32_e32 v48, v187
	v_mov_b32_e32 v49, v188
	v_mov_b32_e32 v50, v189
	v_mov_b32_e32 v51, v190
	v_mov_b32_e32 v40, v191
	v_mov_b32_e32 v41, v192
	v_mov_b32_e32 v42, v193
	v_mov_b32_e32 v43, v194
	v_mov_b32_e32 v36, v195
	v_mov_b32_e32 v37, v196
	v_mov_b32_e32 v38, v197
	v_mov_b32_e32 v39, v198
	v_mov_b32_e32 v32, v199
	v_mov_b32_e32 v33, v200
	v_mov_b32_e32 v34, v201
	v_mov_b32_e32 v35, v202
	s_cmp_gt_i32 s0, 0x80ff
	s_cbranch_scc1 .LBB0_1618
.LBB0_1630:
	s_cmp_lt_i32 s0, 0x8090
	s_mov_b64 s[6:7], -1
	s_cbranch_scc0 .LBB0_1634
	s_waitcnt vmcnt(0)
	v_mov_b64_e32 v[66:67], v[14:15]
	v_mov_b64_e32 v[70:71], v[10:11]
	v_mov_b64_e32 v[74:75], v[6:7]
	v_mov_b64_e32 v[78:79], v[2:3]
	v_mov_b64_e32 v[82:83], v[22:23]
	v_mov_b64_e32 v[86:87], v[18:19]
	v_mov_b64_e32 v[90:91], v[30:31]
	v_mov_b64_e32 v[94:95], v[26:27]
	s_andn2_b64 vcc, exec, s[8:9]
	v_mov_b64_e32 v[64:65], v[12:13]
	v_mov_b64_e32 v[68:69], v[8:9]
	v_mov_b64_e32 v[72:73], v[4:5]
	v_mov_b64_e32 v[76:77], v[0:1]
	v_mov_b64_e32 v[80:81], v[20:21]
	v_mov_b64_e32 v[84:85], v[16:17]
	v_mov_b64_e32 v[88:89], v[28:29]
	v_mov_b64_e32 v[92:93], v[24:25]
	s_cbranch_vccnz .LBB0_1633
	s_waitcnt lgkmcnt(0)
	v_and_b32_e32 v71, 0xffff0000, v132
	v_and_b32_e32 v70, 0xffff0000, v134
	v_and_b32_e32 v169, 0xffff0000, v133
	v_and_b32_e32 v168, 0xffff0000, v135
	v_lshlrev_b32_e32 v69, 16, v132
	v_lshlrev_b32_e32 v68, 16, v134
	v_lshlrev_b32_e32 v167, 16, v133
	v_lshlrev_b32_e32 v166, 16, v135
	v_pk_mul_f32 v[64:65], v[70:71], v[70:71]
	v_pk_mul_f32 v[66:67], v[168:169], v[168:169]
	v_pk_fma_f32 v[64:65], v[68:69], v[68:69], v[64:65]
	v_pk_fma_f32 v[66:67], v[166:167], v[166:167], v[66:67]
	v_and_b32_e32 v75, 0xffff0000, v137
	v_pk_add_f32 v[64:65], v[64:65], v[66:67]
	v_and_b32_e32 v74, 0xffff0000, v136
	v_pk_add_f32 v[64:65], v[64:65], v[64:65] op_sel_hi:[0,1]
	v_lshlrev_b32_e32 v73, 16, v137
	v_lshlrev_b32_e32 v72, 16, v136
	v_pk_mul_f32 v[66:67], v[74:75], v[74:75]
	v_lshlrev_b32_e32 v76, 16, v138
	v_and_b32_e32 v77, 0xffff0000, v138
	v_lshlrev_b32_e32 v78, 16, v139
	v_lshlrev_b32_e32 v80, 16, v140
	v_pk_fma_f32 v[66:67], v[72:73], v[72:73], v[66:67]
	v_mul_f32_e32 v81, v76, v76
	v_mul_f32_e32 v85, v77, v77
	v_and_b32_e32 v79, 0xffff0000, v139
	v_mul_f32_e32 v64, v78, v78
	v_mov_b32_e32 v84, v80
	v_pk_add_f32 v[66:67], v[66:67], v[66:67] op_sel_hi:[0,1]
	v_pk_fma_f32 v[86:87], v[78:79], v[78:79], v[64:65] op_sel_hi:[1,1,0]
	v_and_b32_e32 v178, 0xffff0000, v140
	v_lshlrev_b32_e32 v82, 16, v141
	v_and_b32_e32 v83, 0xffff0000, v141
	v_pk_add_f32 v[84:85], v[80:81], v[84:85]
	v_mul_f32_e32 v86, v178, v178
	v_mul_f32_e32 v66, v82, v82
	v_mul_f32_e32 v64, v83, v83
	v_mul_f32_e32 v88, v80, v80
	v_mov_b32_e32 v89, v85
	v_pk_add_f32 v[84:85], v[88:89], v[86:87]
	v_pk_add_f32 v[64:65], v[66:67], v[64:65]
	v_and_b32_e32 v87, 0xffff0000, v143
	v_pk_add_f32 v[64:65], v[84:85], v[64:65]
	v_and_b32_e32 v86, 0xffff0000, v142
	v_pk_add_f32 v[64:65], v[64:65], v[64:65] op_sel_hi:[0,1]
	v_lshlrev_b32_e32 v85, 16, v143
	v_lshlrev_b32_e32 v84, 16, v142
	v_pk_mul_f32 v[66:67], v[86:87], v[86:87]
	v_lshlrev_b32_e32 v88, 16, v144
	v_and_b32_e32 v89, 0xffff0000, v144
	v_lshlrev_b32_e32 v90, 16, v145
	v_lshlrev_b32_e32 v92, 16, v146
	v_pk_fma_f32 v[66:67], v[84:85], v[84:85], v[66:67]
	v_mul_f32_e32 v93, v88, v88
	v_mul_f32_e32 v173, v89, v89
	v_and_b32_e32 v91, 0xffff0000, v145
	v_mul_f32_e32 v64, v90, v90
	v_mov_b32_e32 v172, v92
	v_pk_add_f32 v[66:67], v[66:67], v[66:67] op_sel_hi:[0,1]
	v_pk_fma_f32 v[174:175], v[90:91], v[90:91], v[64:65] op_sel_hi:[1,1,0]
	v_and_b32_e32 v171, 0xffff0000, v146
	v_lshlrev_b32_e32 v94, 16, v147
	v_and_b32_e32 v95, 0xffff0000, v147
	v_pk_add_f32 v[172:173], v[92:93], v[172:173]
	v_mul_f32_e32 v174, v171, v171
	v_mul_f32_e32 v66, v94, v94
	v_mul_f32_e32 v64, v95, v95
	v_mul_f32_e32 v176, v92, v92
	v_mov_b32_e32 v177, v173
	v_pk_add_f32 v[172:173], v[176:177], v[174:175]
	v_pk_add_f32 v[64:65], v[66:67], v[64:65]
	s_ashr_i32 s1, s0, 31
	v_pk_add_f32 v[64:65], v[172:173], v[64:65]
	v_mov_b32_e32 v172, v69
	v_add_f32_e32 v64, v64, v65
	ds_bpermute_b32 v65, v97, v64
	v_mov_b32_e32 v173, v71
	s_lshl_b64 s[6:7], s[0:1], 13
	s_add_u32 s6, s14, s6
	s_addc_u32 s7, s15, s7
	s_waitcnt lgkmcnt(0)
	v_add_f32_e32 v64, v64, v65
	ds_bpermute_b32 v65, v99, v64
	v_lshlrev_b32_e32 v81, 4, v96
	v_mov_b32_e32 v69, v70
	v_lshlrev_b32_e32 v93, 4, v98
	s_waitcnt lgkmcnt(0)
	v_add_f32_e32 v64, v64, v65
	ds_bpermute_b32 v65, v101, v64
	s_waitcnt lgkmcnt(0)
	v_add_f32_e32 v64, v64, v65
	ds_bpermute_b32 v65, v103, v64
	s_waitcnt lgkmcnt(0)
	v_add_f32_e32 v64, v64, v65
	ds_bpermute_b32 v65, v105, v64
	s_waitcnt lgkmcnt(0)
	v_add_f32_e32 v64, v64, v65
	ds_bpermute_b32 v65, v165, v64
	s_waitcnt lgkmcnt(0)
; template <int MODE>
; __device__ __forceinline__ void row_finish(const Params& p, int r, int lane, const float* gpost, const float* gnext, bf16_t* U, float coef, f32x4 (&h)[8], const u32x2 (&dw)[8]) {
;     ...
;         for (int j = 0; j < 8; ++j) { const u32x2 w = dw[j]; d[j] = (f32x4){bflo(w.x), bfhi(w.x), bflo(w.y), bfhi(w.y)};
;             ss += (d[j].x * d[j].x + d[j].y * d[j].y) + (d[j].z * d[j].z + d[j].w * d[j].w); }
;         ss = wave_sum(ss);
;         const float rs = rsqrtf(ss * (1.f / DM) + EPS) * coef;
;         f32x4* hd = (f32x4*)hrow(p, r);
; #pragma unroll
;         for (int j = 0; j < 8; ++j) { const f32x4 g = ((const f32x4*)gpost)[lane + 64 * j]; h[j] = h[j] + d[j] * g * rs; __builtin_nontemporal_store(h[j], &hd[lane + 64 * j]); }
;     }
;     if (MODE != 3) {
;         float s2 = 0.f;
; #pragma unroll
;         for (int j = 0; j < 8; ++j) s2 += (h[j].x * h[j].x + h[j].y * h[j].y) + (h[j].z * h[j].z + h[j].w * h[j].w);
;         s2 = wave_sum(s2);
;         const float rs2 = rsqrtf(s2 * (1.f / DM) + EPS);
	v_add_f32_e32 v64, v64, v65
	v_fmamk_f32 v64, v64, 0x3a000000, v170
	v_cmp_gt_f32_e32 vcc, s23, v64
	v_mul_f32_e32 v65, 0x4b800000, v64
	s_nop 0
	v_cndmask_b32_e32 v64, v64, v65, vcc
	v_rsq_f32_e32 v64, v64
	s_nop 0
	v_mul_f32_e32 v65, 0x45800000, v64
	v_cndmask_b32_e32 v164, v64, v65, vcc
	global_load_dwordx4 v[64:67], v[106:107], off
	s_waitcnt vmcnt(0)
	v_pk_mul_f32 v[64:65], v[172:173], v[64:65]
	v_mov_b32_e32 v172, v167
	v_mov_b32_e32 v173, v169
	v_pk_mul_f32 v[66:67], v[172:173], v[66:67]
	v_pk_fma_f32 v[64:65], v[64:65], v[164:165], v[12:13] op_sel_hi:[1,0,1]
	v_pk_fma_f32 v[66:67], v[66:67], v[164:165], v[14:15] op_sel_hi:[1,0,1]
	global_store_dwordx4 v81, v[64:67], s[6:7] nt
	global_load_dwordx4 v[172:175], v[106:107], off offset:1024
	v_mov_b32_e32 v167, v168
	s_waitcnt vmcnt(0)
	v_pk_mul_f32 v[166:167], v[166:167], v[174:175]
	v_pk_mul_f32 v[68:69], v[68:69], v[172:173]
	v_pk_fma_f32 v[70:71], v[166:167], v[164:165], v[10:11] op_sel_hi:[1,0,1]
	v_pk_fma_f32 v[68:69], v[68:69], v[164:165], v[8:9] op_sel_hi:[1,0,1]
	global_store_dwordx4 v81, v[68:71], s[6:7] offset:1024 nt
	global_load_dwordx4 v[166:169], v[106:107], off offset:2048
	v_mov_b32_e32 v172, v73
	v_mov_b32_e32 v173, v75
	v_mov_b32_e32 v73, v74
	s_waitcnt vmcnt(0)
	v_pk_mul_f32 v[168:169], v[168:169], v[172:173]
	v_pk_mul_f32 v[72:73], v[166:167], v[72:73]
	v_pk_fma_f32 v[74:75], v[168:169], v[164:165], v[6:7] op_sel_hi:[1,0,1]
	v_pk_fma_f32 v[72:73], v[72:73], v[164:165], v[4:5] op_sel_hi:[1,0,1]
	global_store_dwordx4 v81, v[72:75], s[6:7] offset:2048 nt
	global_load_dwordx4 v[166:169], v[106:107], off offset:3072
	v_mov_b32_e32 v172, v85
	v_mov_b32_e32 v173, v87
	v_mov_b32_e32 v85, v86
	s_waitcnt vmcnt(0)
	v_pk_mul_f32 v[78:79], v[78:79], v[168:169]
	v_pk_mul_f32 v[76:77], v[76:77], v[166:167]
	v_pk_fma_f32 v[78:79], v[78:79], v[164:165], v[2:3] op_sel_hi:[1,0,1]
	v_pk_fma_f32 v[76:77], v[76:77], v[164:165], v[0:1] op_sel_hi:[1,0,1]
	global_store_dwordx4 v81, v[76:79], s[6:7] offset:3072 nt
	global_load_dwordx4 v[166:169], v[108:109], off
	v_mov_b32_e32 v81, v178
	s_waitcnt vmcnt(0)
	v_pk_mul_f32 v[80:81], v[80:81], v[166:167]
	v_pk_mul_f32 v[82:83], v[82:83], v[168:169]
	v_pk_fma_f32 v[80:81], v[80:81], v[164:165], v[20:21] op_sel_hi:[1,0,1]
	v_pk_fma_f32 v[82:83], v[82:83], v[164:165], v[22:23] op_sel_hi:[1,0,1]
	global_store_dwordx4 v93, v[80:83], s[6:7] nt
	global_load_dwordx4 v[166:169], v[110:111], off
	v_lshlrev_b32_e32 v93, 4, v100
	s_waitcnt vmcnt(0)
	v_pk_mul_f32 v[168:169], v[168:169], v[172:173]
	v_pk_mul_f32 v[84:85], v[166:167], v[84:85]
	v_pk_fma_f32 v[86:87], v[164:165], v[168:169], v[18:19] op_sel_hi:[0,1,1]
	v_pk_fma_f32 v[84:85], v[164:165], v[84:85], v[16:17] op_sel_hi:[0,1,1]
	global_store_dwordx4 v93, v[84:87], s[6:7] nt
	global_load_dwordx4 v[166:169], v[112:113], off
	v_lshlrev_b32_e32 v93, 4, v102
	v_mov_b32_e32 v172, v67
	v_mov_b32_e32 v173, v71
	v_pk_mul_f32 v[172:173], v[172:173], v[172:173]
	s_waitcnt vmcnt(0)
	v_pk_mul_f32 v[90:91], v[90:91], v[168:169]
	v_pk_mul_f32 v[88:89], v[88:89], v[166:167]
	v_pk_fma_f32 v[90:91], v[164:165], v[90:91], v[30:31] op_sel_hi:[0,1,1]
	v_pk_fma_f32 v[88:89], v[164:165], v[88:89], v[28:29] op_sel_hi:[0,1,1]
	global_store_dwordx4 v93, v[88:91], s[6:7] nt
	global_load_dwordx4 v[166:169], v[114:115], off
	v_mov_b32_e32 v93, v171
	s_waitcnt vmcnt(0)
	v_pk_mul_f32 v[94:95], v[94:95], v[168:169]
	v_mov_b32_e32 v168, v65
	v_mov_b32_e32 v169, v69
	v_pk_mul_f32 v[92:93], v[92:93], v[166:167]
	v_mov_b32_e32 v166, v64
	v_mov_b32_e32 v167, v68
	v_pk_mul_f32 v[168:169], v[168:169], v[168:169]
	v_pk_fma_f32 v[94:95], v[164:165], v[94:95], v[26:27] op_sel_hi:[0,1,1]
	v_pk_fma_f32 v[166:167], v[166:167], v[166:167], v[168:169]
	v_mov_b32_e32 v168, v66
	v_mov_b32_e32 v169, v70
	v_pk_fma_f32 v[168:169], v[168:169], v[168:169], v[172:173]
	v_pk_fma_f32 v[92:93], v[164:165], v[92:93], v[24:25] op_sel_hi:[0,1,1]
	v_lshlrev_b32_e32 v164, 4, v104
	v_pk_add_f32 v[166:167], v[166:167], v[168:169]
	v_pk_mul_f32 v[168:169], v[72:73], v[72:73]
	v_pk_mul_f32 v[172:173], v[74:75], v[74:75]
	global_store_dwordx4 v164, v[92:95], s[6:7] nt
	v_pk_mov_b32 v[174:175], v[168:169], v[172:173] op_sel:[1,0]
	v_mov_b32_e32 v169, v173
	v_mul_f32_e32 v164, v76, v76
	v_pk_add_f32 v[168:169], v[174:175], v[168:169]
	v_pk_fma_f32 v[172:173], v[76:77], v[76:77], v[164:165] op_sel_hi:[1,1,0]
	v_mul_f32_e32 v164, v78, v78
	v_pk_add_f32 v[166:167], v[166:167], v[166:167] op_sel_hi:[0,1]
	v_pk_add_f32 v[168:169], v[168:169], v[168:169] op_sel_hi:[0,1]
	v_pk_fma_f32 v[174:175], v[78:79], v[78:79], v[164:165] op_sel_hi:[1,1,0]
	v_mul_f32_e32 v172, v80, v80
	v_mul_f32_e32 v174, v81, v81
	v_mul_f32_e32 v168, v82, v82
	v_mul_f32_e32 v166, v83, v83
	v_pk_add_f32 v[172:173], v[172:173], v[174:175]
	v_pk_add_f32 v[166:167], v[168:169], v[166:167]
	v_pk_mul_f32 v[168:169], v[84:85], v[84:85]
	v_pk_add_f32 v[166:167], v[172:173], v[166:167]
	v_pk_mul_f32 v[172:173], v[86:87], v[86:87]
	v_mul_f32_e32 v164, v88, v88
	v_pk_mov_b32 v[174:175], v[168:169], v[172:173] op_sel:[1,0]
	v_mov_b32_e32 v169, v173
	v_pk_add_f32 v[168:169], v[174:175], v[168:169]
	v_pk_fma_f32 v[172:173], v[88:89], v[88:89], v[164:165] op_sel_hi:[1,1,0]
	v_mul_f32_e32 v164, v90, v90
	v_pk_add_f32 v[166:167], v[166:167], v[166:167] op_sel_hi:[0,1]
	v_pk_add_f32 v[168:169], v[168:169], v[168:169] op_sel_hi:[0,1]
	v_pk_fma_f32 v[174:175], v[90:91], v[90:91], v[164:165] op_sel_hi:[1,1,0]
	v_mul_f32_e32 v172, v92, v92
	v_mul_f32_e32 v174, v93, v93
	v_mul_f32_e32 v168, v94, v94
	v_mul_f32_e32 v166, v95, v95
	v_pk_add_f32 v[172:173], v[172:173], v[174:175]
	v_pk_add_f32 v[166:167], v[168:169], v[166:167]
	s_lshl_b64 s[6:7], s[0:1], 12
	v_pk_add_f32 v[166:167], v[172:173], v[166:167]
	s_nop 0
	v_add_f32_e32 v164, v166, v167
	ds_bpermute_b32 v166, v97, v164
	s_waitcnt lgkmcnt(0)
; __device__ __forceinline__ unsigned pk2(float lo, float hi) { return f2bf(lo) | (f2bf(hi) << 16); }
; template <int MODE>
; __device__ __forceinline__ void row_finish(const Params& p, int r, int lane, const float* gpost, const float* gnext, bf16_t* U, float coef, f32x4 (&h)[8], const u32x2 (&dw)[8]) {
;     ...
;         s2 = wave_sum(s2);
;         const float rs2 = rsqrtf(s2 * (1.f / DM) + EPS);
;         u32x2* up = (u32x2*)(U + (size_t)r * DM);
; #pragma unroll
;         for (int j = 0; j < 8; ++j) { const f32x4 g = ((const f32x4*)gnext)[lane + 64 * j]; const f32x4 v = h[j] * g * rs2;
;             u32x2 w; w.x = pk2(v.x, v.y); w.y = pk2(v.z, v.w); up[lane + 64 * j] = w; }
;     }
	v_add_f32_e32 v164, v164, v166
	ds_bpermute_b32 v166, v99, v164
	s_waitcnt lgkmcnt(0)
	v_add_f32_e32 v164, v164, v166
	ds_bpermute_b32 v166, v101, v164
	s_waitcnt lgkmcnt(0)
	v_add_f32_e32 v164, v164, v166
	ds_bpermute_b32 v166, v103, v164
	s_waitcnt lgkmcnt(0)
	v_add_f32_e32 v164, v164, v166
	ds_bpermute_b32 v166, v105, v164
	s_waitcnt lgkmcnt(0)
	v_add_f32_e32 v164, v164, v166
	ds_bpermute_b32 v166, v165, v164
	s_waitcnt lgkmcnt(0)
	v_add_f32_e32 v164, v164, v166
	v_fmamk_f32 v164, v164, 0x3a000000, v170
	v_cmp_gt_f32_e32 vcc, s23, v164
	v_mul_f32_e32 v166, 0x4b800000, v164
	s_nop 0
	v_cndmask_b32_e32 v164, v164, v166, vcc
	v_rsq_f32_e32 v164, v164
	s_nop 0
	v_mul_f32_e32 v166, 0x45800000, v164
	v_cndmask_b32_e32 v164, v164, v166, vcc
	global_load_dwordx4 v[166:169], v[116:117], off
	s_waitcnt vmcnt(0)
	v_pk_mul_f32 v[166:167], v[64:65], v[166:167]
	v_pk_mul_f32 v[168:169], v[66:67], v[168:169]
	v_pk_mul_f32 v[166:167], v[166:167], v[164:165] op_sel_hi:[1,0]
	v_pk_mul_f32 v[172:173], v[168:169], v[164:165] op_sel_hi:[1,0]
	v_bfe_u32 v168, v166, 16, 1
	v_add3_u32 v166, v166, v168, s20
	v_bfe_u32 v168, v167, 16, 1
	v_lshrrev_b32_e32 v166, 16, v166
	v_add3_u32 v167, v167, v168, s20
	v_and_or_b32 v168, v167, s21, v166
	v_bfe_u32 v166, v172, 16, 1
	v_add3_u32 v166, v172, v166, s20
	v_bfe_u32 v167, v173, 16, 1
	v_lshrrev_b32_e32 v166, 16, v166
	v_add3_u32 v167, v173, v167, s20
	v_and_or_b32 v169, v167, s21, v166
	v_lshl_add_u64 v[166:167], v[130:131], 0, s[6:7]
	global_store_dwordx2 v[166:167], v[168:169], off
	global_load_dwordx4 v[172:175], v[116:117], off offset:1024
	s_waitcnt vmcnt(0)
	v_pk_mul_f32 v[168:169], v[68:69], v[172:173]
	s_nop 0
	v_pk_mul_f32 v[168:169], v[168:169], v[164:165] op_sel_hi:[1,0]
	v_pk_mul_f32 v[172:173], v[70:71], v[174:175]
	v_bfe_u32 v171, v168, 16, 1
	v_add3_u32 v168, v168, v171, s20
	v_bfe_u32 v171, v169, 16, 1
	v_pk_mul_f32 v[172:173], v[172:173], v[164:165] op_sel_hi:[1,0]
	v_lshrrev_b32_e32 v168, 16, v168
	v_add3_u32 v169, v169, v171, s20
	v_and_or_b32 v168, v169, s21, v168
	v_bfe_u32 v169, v172, 16, 1
	v_add3_u32 v169, v172, v169, s20
	v_bfe_u32 v171, v173, 16, 1
	v_lshrrev_b32_e32 v169, 16, v169
	v_add3_u32 v171, v173, v171, s20
	v_and_or_b32 v169, v171, s21, v169
	global_store_dwordx2 v[166:167], v[168:169], off offset:512
	global_load_dwordx4 v[172:175], v[116:117], off offset:2048
	s_waitcnt vmcnt(0)
	v_pk_mul_f32 v[168:169], v[72:73], v[172:173]
	s_nop 0
	v_pk_mul_f32 v[168:169], v[168:169], v[164:165] op_sel_hi:[1,0]
	v_pk_mul_f32 v[172:173], v[74:75], v[174:175]
	v_bfe_u32 v171, v168, 16, 1
	v_add3_u32 v168, v168, v171, s20
	v_bfe_u32 v171, v169, 16, 1
	v_pk_mul_f32 v[172:173], v[172:173], v[164:165] op_sel_hi:[1,0]
	v_lshrrev_b32_e32 v168, 16, v168
	v_add3_u32 v169, v169, v171, s20
	v_and_or_b32 v168, v169, s21, v168
	v_bfe_u32 v169, v172, 16, 1
	v_add3_u32 v169, v172, v169, s20
	v_bfe_u32 v171, v173, 16, 1
	v_lshrrev_b32_e32 v169, 16, v169
	v_add3_u32 v171, v173, v171, s20
	v_and_or_b32 v169, v171, s21, v169
	global_store_dwordx2 v[166:167], v[168:169], off offset:1024
	global_load_dwordx4 v[172:175], v[116:117], off offset:3072
	s_waitcnt vmcnt(0)
	v_pk_mul_f32 v[168:169], v[76:77], v[172:173]
	s_nop 0
	v_pk_mul_f32 v[168:169], v[168:169], v[164:165] op_sel_hi:[1,0]
	v_pk_mul_f32 v[172:173], v[78:79], v[174:175]
	v_bfe_u32 v171, v168, 16, 1
	v_add3_u32 v168, v168, v171, s20
	v_bfe_u32 v171, v169, 16, 1
	v_pk_mul_f32 v[172:173], v[172:173], v[164:165] op_sel_hi:[1,0]
	v_lshrrev_b32_e32 v168, 16, v168
	v_add3_u32 v169, v169, v171, s20
	v_and_or_b32 v168, v169, s21, v168
	v_bfe_u32 v169, v172, 16, 1
	v_add3_u32 v169, v172, v169, s20
	v_bfe_u32 v171, v173, 16, 1
	v_lshrrev_b32_e32 v169, 16, v169
	v_add3_u32 v171, v173, v171, s20
	v_and_or_b32 v169, v171, s21, v169
	global_store_dwordx2 v[166:167], v[168:169], off offset:1536
	global_load_dwordx4 v[172:175], v[118:119], off
	s_waitcnt vmcnt(0)
	v_pk_mul_f32 v[168:169], v[80:81], v[172:173]
	s_nop 0
	v_pk_mul_f32 v[168:169], v[168:169], v[164:165] op_sel_hi:[1,0]
	v_pk_mul_f32 v[172:173], v[82:83], v[174:175]
	v_bfe_u32 v171, v168, 16, 1
	v_add3_u32 v168, v168, v171, s20
	v_bfe_u32 v171, v169, 16, 1
	v_pk_mul_f32 v[172:173], v[172:173], v[164:165] op_sel_hi:[1,0]
	v_lshrrev_b32_e32 v168, 16, v168
	v_add3_u32 v169, v169, v171, s20
	v_and_or_b32 v168, v169, s21, v168
	v_bfe_u32 v169, v172, 16, 1
	v_add3_u32 v169, v172, v169, s20
	v_bfe_u32 v171, v173, 16, 1
	v_lshrrev_b32_e32 v169, 16, v169
	v_add3_u32 v171, v173, v171, s20
	v_and_or_b32 v169, v171, s21, v169
	global_store_dwordx2 v[166:167], v[168:169], off offset:2048
	global_load_dwordx4 v[172:175], v[120:121], off
	s_waitcnt vmcnt(0)
	v_pk_mul_f32 v[168:169], v[84:85], v[172:173]
	s_nop 0
	v_pk_mul_f32 v[168:169], v[168:169], v[164:165] op_sel_hi:[1,0]
	v_pk_mul_f32 v[172:173], v[86:87], v[174:175]
	v_bfe_u32 v171, v168, 16, 1
	v_add3_u32 v168, v168, v171, s20
	v_bfe_u32 v171, v169, 16, 1
	v_pk_mul_f32 v[172:173], v[172:173], v[164:165] op_sel_hi:[1,0]
	v_lshrrev_b32_e32 v168, 16, v168
	v_add3_u32 v169, v169, v171, s20
	v_and_or_b32 v168, v169, s21, v168
	v_bfe_u32 v169, v172, 16, 1
	v_add3_u32 v169, v172, v169, s20
	v_bfe_u32 v171, v173, 16, 1
	v_lshrrev_b32_e32 v169, 16, v169
	v_add3_u32 v171, v173, v171, s20
	v_and_or_b32 v169, v171, s21, v169
	global_store_dwordx2 v[166:167], v[168:169], off offset:2560
	global_load_dwordx4 v[172:175], v[122:123], off
	s_waitcnt vmcnt(0)
	v_pk_mul_f32 v[168:169], v[88:89], v[172:173]
	s_nop 0
	v_pk_mul_f32 v[168:169], v[168:169], v[164:165] op_sel_hi:[1,0]
	v_pk_mul_f32 v[172:173], v[90:91], v[174:175]
	v_bfe_u32 v171, v168, 16, 1
	v_add3_u32 v168, v168, v171, s20
	v_bfe_u32 v171, v169, 16, 1
	v_pk_mul_f32 v[172:173], v[172:173], v[164:165] op_sel_hi:[1,0]
	v_lshrrev_b32_e32 v168, 16, v168
	v_add3_u32 v169, v169, v171, s20
	v_and_or_b32 v168, v169, s21, v168
	v_bfe_u32 v169, v172, 16, 1
	v_add3_u32 v169, v172, v169, s20
	v_bfe_u32 v171, v173, 16, 1
	v_lshrrev_b32_e32 v169, 16, v169
	v_add3_u32 v171, v173, v171, s20
	v_and_or_b32 v169, v171, s21, v169
	global_store_dwordx2 v[166:167], v[168:169], off offset:3072
	global_load_dwordx4 v[172:175], v[124:125], off
	s_waitcnt vmcnt(0)
	v_pk_mul_f32 v[168:169], v[92:93], v[172:173]
	v_pk_mul_f32 v[172:173], v[94:95], v[174:175]
	v_pk_mul_f32 v[168:169], v[168:169], v[164:165] op_sel_hi:[1,0]
	v_pk_mul_f32 v[172:173], v[172:173], v[164:165] op_sel_hi:[1,0]
	v_bfe_u32 v164, v168, 16, 1
	v_add3_u32 v164, v168, v164, s20
	v_bfe_u32 v168, v169, 16, 1
	v_lshrrev_b32_e32 v164, 16, v164
	v_add3_u32 v168, v169, v168, s20
	v_and_or_b32 v168, v168, s21, v164
	v_bfe_u32 v164, v172, 16, 1
	v_add3_u32 v164, v172, v164, s20
	v_bfe_u32 v169, v173, 16, 1
	v_lshrrev_b32_e32 v164, 16, v164
	v_add3_u32 v169, v173, v169, s20
	v_and_or_b32 v169, v169, s21, v164
	global_store_dwordx2 v[166:167], v[168:169], off offset:3584

; template <int MODE>
; __device__ __forceinline__ void row_finish(const Params& p, int r, int lane, const float* gpost, const float* gnext, bf16_t* U, float coef, f32x4 (&h)[8], const u32x2 (&dw)[8]) {
;     ...
;     if (r >= ROWS) { if (MODE != 3) { u32x4* up = (u32x4*)(U + (size_t)r * DM);
; #pragma unroll
;             for (int j = 0; j < 4; ++j) up[lane + 64 * j] = (u32x4){0u, 0u, 0u, 0u}; } return; }
.LBB0_1634:
	s_andn2_b64 vcc, exec, s[6:7]
	s_cbranch_vccnz .LBB0_1617
	s_mov_b32 s1, s4
	s_lshl_b64 s[6:7], s[0:1], 12
	v_lshl_add_u64 v[64:65], v[126:127], 0, s[6:7]
	s_mov_b32 s6, s4
	s_mov_b32 s7, s4
	s_mov_b32 s5, s4
	v_mov_b64_e32 v[68:69], s[6:7]
	v_mov_b64_e32 v[66:67], s[4:5]
	global_store_dwordx4 v[64:65], v[66:69], off
	global_store_dwordx4 v[64:65], v[66:69], off offset:1024
	global_store_dwordx4 v[64:65], v[66:69], off offset:2048
	global_store_dwordx4 v[64:65], v[66:69], off offset:3072
	s_waitcnt vmcnt(0)
	v_mov_b64_e32 v[70:71], v[10:11]
	v_mov_b64_e32 v[74:75], v[6:7]
	v_mov_b64_e32 v[66:67], v[14:15]
	v_mov_b64_e32 v[78:79], v[2:3]
	v_mov_b64_e32 v[82:83], v[22:23]
	v_mov_b64_e32 v[86:87], v[18:19]
	v_mov_b64_e32 v[90:91], v[30:31]
	v_mov_b64_e32 v[94:95], v[26:27]
	v_mov_b64_e32 v[64:65], v[12:13]
	v_mov_b64_e32 v[68:69], v[8:9]
	v_mov_b64_e32 v[72:73], v[4:5]
	v_mov_b64_e32 v[76:77], v[0:1]
	v_mov_b64_e32 v[80:81], v[20:21]
	v_mov_b64_e32 v[84:85], v[16:17]
	v_mov_b64_e32 v[88:89], v[28:29]
	v_mov_b64_e32 v[92:93], v[24:25]
	s_branch .LBB0_1617

; __device__ __forceinline__ unsigned cvt_pk_bf16(float lo, float hi) { unsigned r; asm volatile("v_cvt_pk_bf16_f32 %0, %1, %2" : "=v"(r) : "v"(lo), "v"(hi)); return r; }
;     __device__ __forceinline__ void operator()(const f32x4 (&acc)[2][2][4][2], const Unit& u, int wr, int wc, int fr, int fq) const {
;         const int row0 = u.pm * BM + wr * 64 + fr, col0 = u.pn * BM + wc * 32 + 8 * fq;
; #pragma unroll
;         for (int ai = 0; ai < 2; ++ai)
; #pragma unroll
;             for (int m = 0; m < 4; ++m) { bf16_t* rowp = O + (size_t)(row0 + ai * HALF + m * 16) * ldc + col0;
; #pragma unroll
;                 for (int bj = 0; bj < 2; ++bj) { const f32x4 v0 = acc[ai][bj][m][0], v1 = acc[ai][bj][m][1];
;                     u32x4 w; w.x = cvt_pk_bf16(v0[0], v0[1]); w.y = cvt_pk_bf16(v0[2], v0[3]); w.z = cvt_pk_bf16(v1[0], v1[1]); w.w = cvt_pk_bf16(v1[2], v1[3]);
;                     *(u32x4*)(rowp + bj * HALF) = w; } }
.LBB0_1807:
	v_lshl_add_u32 v154, s87, 8, v150
	v_lshl_or_b32 v148, s86, 8, v152
	v_ashrrev_i32_e32 v155, 31, v154
	v_ashrrev_i32_e32 v149, 31, v148
	v_lshlrev_b64 v[156:157], 12, v[154:155]
	v_lshl_add_u64 v[156:157], s[24:25], 0, v[156:157]
	v_lshlrev_b64 v[162:163], 1, v[148:149]
	v_lshl_add_u64 v[148:149], v[156:157], 0, v[162:163]
	v_cvt_pk_bf16_f32 v124, v124, v125
	v_cvt_pk_bf16_f32 v125, v126, v127
	v_cvt_pk_bf16_f32 v126, v120, v121
	v_cvt_pk_bf16_f32 v127, v122, v123
	global_store_dwordx4 v[148:149], v[124:127], off
	v_cvt_pk_bf16_f32 v112, v112, v113
	v_cvt_pk_bf16_f32 v113, v114, v115
	v_cvt_pk_bf16_f32 v114, v104, v105
	v_or_b32_e32 v104, 16, v154
	v_ashrrev_i32_e32 v105, 31, v104
	v_lshlrev_b64 v[104:105], 12, v[104:105]
	v_lshl_add_u64 v[104:105], s[24:25], 0, v[104:105]
	v_cvt_pk_bf16_f32 v115, v106, v107
	global_store_dwordx4 v[148:149], v[112:115], off offset:256
	s_mov_b64 s[56:57], 0x80000
	s_nop 0
	v_lshl_add_u64 v[112:113], v[104:105], 0, v[162:163]
	v_cvt_pk_bf16_f32 v104, v116, v117
	v_cvt_pk_bf16_f32 v105, v118, v119
	v_cvt_pk_bf16_f32 v106, v108, v109
	v_cvt_pk_bf16_f32 v107, v110, v111
	global_store_dwordx4 v[112:113], v[104:107], off
	v_cvt_pk_bf16_f32 v96, v96, v97
	v_cvt_pk_bf16_f32 v97, v98, v99
	v_cvt_pk_bf16_f32 v98, v88, v89
	v_or_b32_e32 v88, 32, v154
	v_ashrrev_i32_e32 v89, 31, v88
	v_lshlrev_b64 v[88:89], 12, v[88:89]
	v_lshl_add_u64 v[88:89], s[24:25], 0, v[88:89]
	v_cvt_pk_bf16_f32 v99, v90, v91
	global_store_dwordx4 v[112:113], v[96:99], off offset:256
	s_nop 1
	v_lshl_add_u64 v[96:97], v[88:89], 0, v[162:163]
	v_cvt_pk_bf16_f32 v88, v100, v101
	v_cvt_pk_bf16_f32 v89, v102, v103
	v_cvt_pk_bf16_f32 v90, v92, v93
	v_cvt_pk_bf16_f32 v91, v94, v95
	global_store_dwordx4 v[96:97], v[88:91], off
	v_cvt_pk_bf16_f32 v80, v80, v81
	v_cvt_pk_bf16_f32 v81, v82, v83
	v_cvt_pk_bf16_f32 v82, v72, v73
	v_or_b32_e32 v72, 48, v154
	v_ashrrev_i32_e32 v73, 31, v72
	v_lshlrev_b64 v[72:73], 12, v[72:73]
	v_lshl_add_u64 v[72:73], s[24:25], 0, v[72:73]
	v_cvt_pk_bf16_f32 v83, v74, v75
	global_store_dwordx4 v[96:97], v[80:83], off offset:256
	s_nop 1
	v_lshl_add_u64 v[80:81], v[72:73], 0, v[162:163]
	v_cvt_pk_bf16_f32 v72, v84, v85
	v_cvt_pk_bf16_f32 v73, v86, v87
	v_cvt_pk_bf16_f32 v74, v76, v77
	v_cvt_pk_bf16_f32 v75, v78, v79
	global_store_dwordx4 v[80:81], v[72:75], off
	v_cvt_pk_bf16_f32 v68, v68, v69
	v_cvt_pk_bf16_f32 v69, v70, v71
	v_cvt_pk_bf16_f32 v70, v64, v65
	v_lshl_add_u64 v[64:65], v[148:149], 0, s[56:57]
	s_mov_b32 s56, 0x80000
	v_cvt_pk_bf16_f32 v71, v66, v67
	global_store_dwordx4 v[80:81], v[68:71], off offset:256
	v_cvt_pk_bf16_f32 v60, v60, v61
	v_cvt_pk_bf16_f32 v61, v62, v63
	v_cvt_pk_bf16_f32 v62, v56, v57
	v_add_co_u32_e32 v56, vcc, s56, v148
	v_cvt_pk_bf16_f32 v63, v58, v59
	s_mov_b64 s[56:57], 0x90000
	s_nop 0
	v_addc_co_u32_e32 v57, vcc, 0, v149, vcc
	global_store_dwordx4 v[56:57], v[60:63], off
	v_cvt_pk_bf16_f32 v48, v48, v49
	v_cvt_pk_bf16_f32 v49, v50, v51
	v_cvt_pk_bf16_f32 v50, v40, v41
	v_cvt_pk_bf16_f32 v51, v42, v43
	global_store_dwordx4 v[64:65], v[48:51], off offset:256
	v_cvt_pk_bf16_f32 v40, v52, v53
	v_cvt_pk_bf16_f32 v41, v54, v55
	v_cvt_pk_bf16_f32 v42, v44, v45
	v_cvt_pk_bf16_f32 v43, v46, v47
	s_nop 1
	v_lshl_add_u64 v[48:49], v[148:149], 0, s[56:57]
	s_mov_b32 s56, 0x90000
	v_add_co_u32_e32 v44, vcc, s56, v148
	s_mov_b64 s[56:57], 0xa0000
	s_nop 0
	v_addc_co_u32_e32 v45, vcc, 0, v149, vcc
	global_store_dwordx4 v[44:45], v[40:43], off
	v_cvt_pk_bf16_f32 v32, v32, v33
	v_cvt_pk_bf16_f32 v33, v34, v35
	v_cvt_pk_bf16_f32 v34, v24, v25
	v_cvt_pk_bf16_f32 v35, v26, v27
	global_store_dwordx4 v[48:49], v[32:35], off offset:256
	v_cvt_pk_bf16_f32 v24, v36, v37
	v_cvt_pk_bf16_f32 v25, v38, v39
	v_cvt_pk_bf16_f32 v26, v28, v29
	v_cvt_pk_bf16_f32 v27, v30, v31
	s_nop 1
	v_lshl_add_u64 v[32:33], v[148:149], 0, s[56:57]
	s_mov_b32 s56, 0xa0000
	v_add_co_u32_e32 v28, vcc, s56, v148
	s_mov_b64 s[56:57], 0xb0000
	s_nop 0
	v_addc_co_u32_e32 v29, vcc, 0, v149, vcc
	global_store_dwordx4 v[28:29], v[24:27], off
	v_cvt_pk_bf16_f32 v16, v16, v17
	v_cvt_pk_bf16_f32 v17, v18, v19
	v_cvt_pk_bf16_f32 v18, v8, v9
	v_cvt_pk_bf16_f32 v19, v10, v11
	global_store_dwordx4 v[32:33], v[16:19], off offset:256
	v_cvt_pk_bf16_f32 v8, v20, v21
	v_cvt_pk_bf16_f32 v9, v22, v23
	v_cvt_pk_bf16_f32 v10, v12, v13
	v_cvt_pk_bf16_f32 v11, v14, v15
	s_nop 1
	v_lshl_add_u64 v[16:17], v[148:149], 0, s[56:57]
	s_mov_b32 s56, 0xb0000
	v_add_co_u32_e32 v12, vcc, s56, v148
	s_nop 1
	v_addc_co_u32_e32 v13, vcc, 0, v149, vcc
	s_and_b64 vcc, exec, s[38:39]
	s_mov_b64 s[38:39], -1
	global_store_dwordx4 v[12:13], v[8:11], off
	v_cvt_pk_bf16_f32 v4, v4, v5
	v_cvt_pk_bf16_f32 v5, v6, v7
	v_cvt_pk_bf16_f32 v6, v0, v1
	v_cvt_pk_bf16_f32 v7, v2, v3
	global_store_dwordx4 v[16:17], v[4:7], off offset:256
	s_cbranch_vccnz .LBB0_1792
	s_andn2_b64 vcc, exec, s[50:51]
	s_cbranch_vccnz .LBB0_1791
	s_barrier
	s_branch .LBB0_1791
